# GEMM MFMA issue order: A fragment shared by consecutive pairs (a0b0,a0b1,a1b0,a1b1,..) instead of the B fragment
# speedup vs baseline: 1.0094x; 1.0094x over previous
; #define PG8_STAGE(bufoff, gbase, voff) do { _Pragma("unroll") for (int _i = 0; _i < 2; ++_i) \
;         __builtin_amdgcn_global_load_lds((const unsigned*)((const char*)(gbase) + (voff)[_i]), (PG8_LAS unsigned*)(lds + (bufoff) + ldsw + _i * 8192), 16, 0, 0); } while (0)
; #define PG8_LDA(dst, b, h) do { _Pragma("unroll") for (int m = 0; m < 4; ++m) _Pragma("unroll") for (int k = 0; k < 2; ++k) dst[m][k] = *(const PG8_LAS bf16x8*)(lds + PG8_SA(b, h) + aoff + m * 2048 + k * 1024); } while (0)
; #define PG8_LDB(dst, b, h) do { _Pragma("unroll") for (int n = 0; n < 2; ++n) _Pragma("unroll") for (int k = 0; k < 2; ++k) dst[n][k] = *(const PG8_LAS bf16x8*)(lds + PG8_SB(b, h) + boff + n * 2048 + k * 1024); } while (0)
; #define PG8_WAIT_V(n) asm volatile("s_waitcnt vmcnt(" #n ")" ::: "memory")
; #define PG8_WAIT_L(n) asm volatile("s_waitcnt lgkmcnt(" #n ")" ::: "memory")
; #define PG8_BAR __builtin_amdgcn_s_barrier()
; #define PG8_SCHED __builtin_amdgcn_sched_barrier(0)
; template <class Epi, class Sched, bool ALIGN_EPI = false, bool SP2 = false>
; __device__ __forceinline__ void gemm_phase(PG8_LAS unsigned char* lds, const Gemm g, const Sched& S, const Epi& E) {
;     ...
;         const bool has_next = S.next(ui + 1, nxt);
;         const char* nA = has_next ? (const char*)g.A + (size_t)nxt.pm * tstep : cA; const char* nB = has_next ? (const char*)g.Bt + (size_t)nxt.pn * tstep : cB;
;         for (int t = 0; t < nt; t += 2) {
;             const bool last = (t == nt - 2);
;             const char* a1 = cA + (size_t)(t + 1) * kstep;
;             const char* a2 = last ? nA : cA + (size_t)(t + 2) * kstep; const char* b2 = last ? nB : cB + (size_t)(t + 2) * kstep;
;             const char* a3 = a2 + kstep; const char* b3 = b2 + kstep;
;             if (last && has_next) S.a_ready(nxt);
;             if constexpr (SP2) {
;             PG8_LDB(B0, 0, 0); PG8_LDB(B1, 0, 1); PG8_SCHED; PG8_LDA(At, 0, 0); PG8_STAGE(PG8_SA(1, 1), a1 + hstep, voffA);
;             PG8_WAIT_V(8); PG8_WAIT_L(0); PG8_BAR; PG8_MMA(0, 0, At, B0); PG8_MMA(0, 1, At, B1); PG8_BAR; PG8_SCHED;
;             PG8_LDA(At, 0, 1); PG8_STAGE(PG8_SB(0, 0), b2, voffB); PG8_STAGE(PG8_SB(0, 1), b2 + hstep, voffB); PG8_STAGE(PG8_SA(0, 0), a2, voffA);
;             PG8_WAIT_V(8); PG8_WAIT_L(0); PG8_BAR; PG8_MMA(1, 0, At, B0); PG8_MMA(1, 1, At, B1); PG8_BAR; PG8_SCHED;
.LBB0_190:
	s_ashr_i32 s27, s26, 31
	s_lshl_b64 s[14:15], s[26:27], 19
	s_add_u32 s28, s22, s14
	s_addc_u32 s29, s23, s15
	s_and_b64 s[14:15], s[0:1], exec
	s_cselect_b32 s27, s29, s49
	s_cselect_b32 s67, s28, s48
	s_ashr_i32 s25, s24, 31
	s_lshl_b64 s[14:15], s[24:25], 19
	s_add_u32 s40, s94, s14
	s_addc_u32 s41, s96, s15
	s_and_b64 s[14:15], s[0:1], exec
	s_cselect_b32 s25, s41, s51
	s_cselect_b32 s86, s40, s50
	s_add_u32 s48, s48, 0x40080
	s_addc_u32 s49, s49, 0
	s_add_u32 s87, s50, 0x100
	s_addc_u32 s88, s51, 0
	s_mov_b32 s89, -2
	ds_read_b128 v[144:147], v155
	ds_read_b128 v[148:151], v155 offset:1024
	ds_read_b128 v[160:163], v155 offset:2048
	ds_read_b128 v[168:171], v155 offset:3072
	ds_read_b128 v[172:175], v156
	ds_read_b128 v[176:179], v156 offset:1024
	ds_read_b128 v[182:185], v156 offset:2048
	ds_read_b128 v[186:189], v156 offset:3072
	s_add_u32 s3, s48, 0xfffc0080
	s_addc_u32 s14, s49, -1
	s_cmp_eq_u32 s89, 12
	s_cselect_b32 s55, s27, s14
	s_cselect_b32 s54, s67, s3
	s_cselect_b32 s51, s25, s88
	s_cselect_b32 s50, s86, s87
	v_lshl_add_u64 v[164:165], s[48:49], 0, v[136:137]
	s_add_i32 m0, s45, 0xc000
	ds_read_b128 v[190:193], v157
	ds_read_b128 v[194:197], v157 offset:1024
	ds_read_b128 v[198:201], v157 offset:2048
	ds_read_b128 v[208:211], v157 offset:3072
	ds_read_b128 v[212:215], v157 offset:4096
	ds_read_b128 v[216:219], v157 offset:5120
	ds_read_b128 v[220:223], v157 offset:6144
	ds_read_b128 v[224:227], v157 offset:7168
	global_load_lds_dwordx4 v[164:165], off
	v_lshl_add_u64 v[164:165], s[48:49], 0, v[138:139]
	s_add_i32 m0, s45, 0xe000
	s_nop 0
	global_load_lds_dwordx4 v[164:165], off
	s_waitcnt vmcnt(8)
	s_waitcnt lgkmcnt(0)
	s_barrier
	s_setprio 1
	s_waitcnt lgkmcnt(0)
	v_mfma_f32_16x16x32_bf16 v[124:127], v[144:147], v[190:193], 0
	v_mfma_f32_16x16x32_bf16 v[108:111], v[144:147], v[198:201], 0
	v_mfma_f32_16x16x32_bf16 v[120:123], v[160:163], v[190:193], 0
	v_mfma_f32_16x16x32_bf16 v[104:107], v[160:163], v[198:201], 0
	v_mfma_f32_16x16x32_bf16 v[92:95], v[144:147], v[212:215], 0
	v_mfma_f32_16x16x32_bf16 v[76:79], v[144:147], v[220:223], 0
	v_mfma_f32_16x16x32_bf16 v[88:91], v[160:163], v[212:215], 0
	v_mfma_f32_16x16x32_bf16 v[72:75], v[160:163], v[220:223], 0
	v_mfma_f32_16x16x32_bf16 v[124:127], v[148:151], v[194:197], v[124:127]
	v_mfma_f32_16x16x32_bf16 v[108:111], v[148:151], v[208:211], v[108:111]
	v_mfma_f32_16x16x32_bf16 v[120:123], v[168:171], v[194:197], v[120:123]
	v_mfma_f32_16x16x32_bf16 v[104:107], v[168:171], v[208:211], v[104:107]
	v_mfma_f32_16x16x32_bf16 v[92:95], v[148:151], v[216:219], v[92:95]
	v_mfma_f32_16x16x32_bf16 v[76:79], v[148:151], v[224:227], v[76:79]
	v_mfma_f32_16x16x32_bf16 v[88:91], v[168:171], v[216:219], v[88:91]
	v_mfma_f32_16x16x32_bf16 v[72:75], v[168:171], v[224:227], v[72:75]
	s_setprio 0
	s_setprio 1
	v_mfma_f32_16x16x32_bf16 v[116:119], v[172:175], v[190:193], 0
	v_mfma_f32_16x16x32_bf16 v[100:103], v[172:175], v[198:201], 0
	v_mfma_f32_16x16x32_bf16 v[112:115], v[182:185], v[190:193], 0
	v_mfma_f32_16x16x32_bf16 v[96:99], v[182:185], v[198:201], 0
	v_mfma_f32_16x16x32_bf16 v[84:87], v[172:175], v[212:215], 0
	v_mfma_f32_16x16x32_bf16 v[68:71], v[172:175], v[220:223], 0
	v_mfma_f32_16x16x32_bf16 v[80:83], v[182:185], v[212:215], 0
	v_mfma_f32_16x16x32_bf16 v[64:67], v[182:185], v[220:223], 0
	v_mfma_f32_16x16x32_bf16 v[116:119], v[176:179], v[194:197], v[116:119]
	v_mfma_f32_16x16x32_bf16 v[100:103], v[176:179], v[208:211], v[100:103]
	v_mfma_f32_16x16x32_bf16 v[112:115], v[186:189], v[194:197], v[112:115]
	v_mfma_f32_16x16x32_bf16 v[96:99], v[186:189], v[208:211], v[96:99]
	v_mfma_f32_16x16x32_bf16 v[84:87], v[176:179], v[216:219], v[84:87]
	v_mfma_f32_16x16x32_bf16 v[68:71], v[176:179], v[224:227], v[68:71]
	v_mfma_f32_16x16x32_bf16 v[80:83], v[186:189], v[216:219], v[80:83]
	v_mfma_f32_16x16x32_bf16 v[64:67], v[186:189], v[224:227], v[64:67]
	s_setprio 0
	s_barrier
	s_add_i32 s3, s63, s43
	v_lshl_add_u64 v[164:165], s[50:51], 0, v[132:133]
	s_mov_b32 m0, s3
	ds_read_b128 v[190:193], v157 offset:16384
	ds_read_b128 v[194:197], v157 offset:17408
	ds_read_b128 v[198:201], v157 offset:18432
	ds_read_b128 v[208:211], v157 offset:19456
	ds_read_b128 v[212:215], v157 offset:20480
	ds_read_b128 v[216:219], v157 offset:21504
	ds_read_b128 v[220:223], v157 offset:22528
	ds_read_b128 v[224:227], v157 offset:23552
	global_load_lds_dwordx4 v[164:165], off
	s_add_i32 m0, s3, 0x2000
	s_add_u32 s14, s50, 0x40000
	v_lshl_add_u64 v[202:203], s[50:51], 0, v[128:129]
	s_addc_u32 s15, s51, 0
	s_add_i32 s3, s64, s43
	global_load_lds_dwordx4 v[202:203], off
	v_lshl_add_u64 v[228:229], s[14:15], 0, v[132:133]
	s_mov_b32 m0, s3
	global_load_lds_dwordx4 v[228:229], off
	v_lshl_add_u64 v[228:229], s[14:15], 0, v[128:129]
	s_add_i32 m0, s3, 0x2000
	s_nop 0
	global_load_lds_dwordx4 v[228:229], off
	s_waitcnt vmcnt(6)
	s_waitcnt lgkmcnt(0)
	s_barrier
; #define PG8_STAGE(bufoff, gbase, voff) do { _Pragma("unroll") for (int _i = 0; _i < 2; ++_i) \
;         __builtin_amdgcn_global_load_lds((const unsigned*)((const char*)(gbase) + (voff)[_i]), (PG8_LAS unsigned*)(lds + (bufoff) + ldsw + _i * 8192), 16, 0, 0); } while (0)
; #define PG8_LDA(dst, b, h) do { _Pragma("unroll") for (int m = 0; m < 4; ++m) _Pragma("unroll") for (int k = 0; k < 2; ++k) dst[m][k] = *(const PG8_LAS bf16x8*)(lds + PG8_SA(b, h) + aoff + m * 2048 + k * 1024); } while (0)
; #define PG8_LDB(dst, b, h) do { _Pragma("unroll") for (int n = 0; n < 2; ++n) _Pragma("unroll") for (int k = 0; k < 2; ++k) dst[n][k] = *(const PG8_LAS bf16x8*)(lds + PG8_SB(b, h) + boff + n * 2048 + k * 1024); } while (0)
; #define PG8_MMA(ai, bj, At, Bt) do { __builtin_amdgcn_s_setprio(1); _Pragma("unroll") for (int m = 0; m < 4; ++m) _Pragma("unroll") for (int n = 0; n < 2; ++n) _Pragma("unroll") for (int k = 0; k < 2; ++k) \
;         acc[ai][bj][m][n] = __builtin_amdgcn_mfma_f32_16x16x32_bf16(Bt[n][k], At[m][k], acc[ai][bj][m][n], 0, 0, 0); __builtin_amdgcn_s_setprio(0); } while (0)
; #define PG8_WAIT_V(n) asm volatile("s_waitcnt vmcnt(" #n ")" ::: "memory")
; #define PG8_WAIT_L(n) asm volatile("s_waitcnt lgkmcnt(" #n ")" ::: "memory")
; #define PG8_BAR __builtin_amdgcn_s_barrier()
; #define PG8_SCHED __builtin_amdgcn_sched_barrier(0)
; template <class Epi, class Sched, bool ALIGN_EPI = false, bool SP2 = false>
; __device__ __forceinline__ void gemm_phase(PG8_LAS unsigned char* lds, const Gemm g, const Sched& S, const Epi& E) {
;     ...
;             PG8_WAIT_V(8); PG8_WAIT_L(0); PG8_BAR; PG8_MMA(1, 0, At, B0); PG8_MMA(1, 1, At, B1); PG8_BAR; PG8_SCHED;
;             PG8_LDB(B0, 1, 0); PG8_LDB(B1, 1, 1); PG8_SCHED; PG8_LDA(At, 1, 0); PG8_STAGE(PG8_SA(0, 1), a2 + hstep, voffA);
;             PG8_WAIT_V(8); PG8_WAIT_L(0); PG8_BAR; PG8_MMA(0, 0, At, B0); PG8_MMA(0, 1, At, B1); PG8_BAR; PG8_SCHED;
	s_setprio 1
	s_waitcnt lgkmcnt(0)
	v_mfma_f32_16x16x32_bf16 v[60:63], v[144:147], v[190:193], 0
	v_mfma_f32_16x16x32_bf16 v[44:47], v[144:147], v[198:201], 0
	v_mfma_f32_16x16x32_bf16 v[56:59], v[160:163], v[190:193], 0
	v_mfma_f32_16x16x32_bf16 v[40:43], v[160:163], v[198:201], 0
	v_mfma_f32_16x16x32_bf16 v[28:31], v[144:147], v[212:215], 0
	v_mfma_f32_16x16x32_bf16 v[12:15], v[144:147], v[220:223], 0
	v_mfma_f32_16x16x32_bf16 v[24:27], v[160:163], v[212:215], 0
	v_mfma_f32_16x16x32_bf16 v[8:11], v[160:163], v[220:223], 0
	v_mfma_f32_16x16x32_bf16 v[60:63], v[148:151], v[194:197], v[60:63]
	v_mfma_f32_16x16x32_bf16 v[44:47], v[148:151], v[208:211], v[44:47]
	v_mfma_f32_16x16x32_bf16 v[56:59], v[168:171], v[194:197], v[56:59]
	v_mfma_f32_16x16x32_bf16 v[40:43], v[168:171], v[208:211], v[40:43]
	v_mfma_f32_16x16x32_bf16 v[28:31], v[148:151], v[216:219], v[28:31]
	v_mfma_f32_16x16x32_bf16 v[12:15], v[148:151], v[224:227], v[12:15]
	v_lshl_add_u64 v[228:229], s[54:55], 0, v[134:135]
	s_mov_b32 m0, s45
	s_nop 0
	global_load_lds_dwordx4 v[228:229], off
	v_mfma_f32_16x16x32_bf16 v[24:27], v[168:171], v[216:219], v[24:27]
	v_mfma_f32_16x16x32_bf16 v[8:11], v[168:171], v[224:227], v[8:11]
	s_setprio 0
	s_setprio 1
	v_mfma_f32_16x16x32_bf16 v[52:55], v[172:175], v[190:193], 0
	v_mfma_f32_16x16x32_bf16 v[36:39], v[172:175], v[198:201], 0
	v_mfma_f32_16x16x32_bf16 v[48:51], v[182:185], v[190:193], 0
	v_mfma_f32_16x16x32_bf16 v[32:35], v[182:185], v[198:201], 0
	v_mfma_f32_16x16x32_bf16 v[20:23], v[172:175], v[212:215], 0
	v_mfma_f32_16x16x32_bf16 v[4:7], v[172:175], v[220:223], 0
	v_mfma_f32_16x16x32_bf16 v[16:19], v[182:185], v[212:215], 0
	v_mfma_f32_16x16x32_bf16 v[0:3], v[182:185], v[220:223], 0
	v_mfma_f32_16x16x32_bf16 v[52:55], v[176:179], v[194:197], v[52:55]
	v_mfma_f32_16x16x32_bf16 v[36:39], v[176:179], v[208:211], v[36:39]
	v_mfma_f32_16x16x32_bf16 v[48:51], v[186:189], v[194:197], v[48:51]
	v_mfma_f32_16x16x32_bf16 v[32:35], v[186:189], v[208:211], v[32:35]
	v_mfma_f32_16x16x32_bf16 v[20:23], v[176:179], v[216:219], v[20:23]
	v_mfma_f32_16x16x32_bf16 v[4:7], v[176:179], v[224:227], v[4:7]
	v_lshl_add_u64 v[230:231], s[54:55], 0, v[130:131]
	s_mov_b32 m0, s57
	s_nop 0
	global_load_lds_dwordx4 v[230:231], off
	v_mfma_f32_16x16x32_bf16 v[16:19], v[186:189], v[216:219], v[16:19]
	v_mfma_f32_16x16x32_bf16 v[0:3], v[186:189], v[224:227], v[0:3]
	s_setprio 0
	s_barrier
	s_add_i32 s3, 0, 0x18000
	v_add_u32_e32 v159, s3, v153
	s_add_i32 s33, 0, 0x1c000
	ds_read_b128 v[144:147], v159
	ds_read_b128 v[148:151], v159 offset:1024
	ds_read_b128 v[160:163], v159 offset:2048
	ds_read_b128 v[168:171], v159 offset:3072
	v_add_u32_e32 v159, s33, v153
	ds_read_b128 v[172:175], v159
	ds_read_b128 v[176:179], v159 offset:1024
	ds_read_b128 v[182:185], v159 offset:2048
	ds_read_b128 v[186:189], v159 offset:3072
	s_add_u32 s14, s54, 0x40000
	s_addc_u32 s15, s55, 0
	s_mov_b32 m0, s58
	v_lshl_add_u64 v[232:233], s[14:15], 0, v[134:135]
	ds_read_b128 v[190:193], v157 offset:32768
	ds_read_b128 v[194:197], v157 offset:33792
	ds_read_b128 v[198:201], v157 offset:34816
	ds_read_b128 v[208:211], v157 offset:35840
	ds_read_b128 v[212:215], v157 offset:36864
	ds_read_b128 v[216:219], v157 offset:37888
	ds_read_b128 v[220:223], v157 offset:38912
	ds_read_b128 v[224:227], v157 offset:39936
	global_load_lds_dwordx4 v[232:233], off
	v_lshl_add_u64 v[232:233], s[14:15], 0, v[130:131]
	s_mov_b32 m0, s59
	s_nop 0
	global_load_lds_dwordx4 v[232:233], off
	s_waitcnt vmcnt(8)
	s_waitcnt lgkmcnt(0)
	s_barrier
	s_setprio 1
	s_waitcnt lgkmcnt(0)
	v_mfma_f32_16x16x32_bf16 v[124:127], v[144:147], v[190:193], v[124:127]
	v_mfma_f32_16x16x32_bf16 v[108:111], v[144:147], v[198:201], v[108:111]
	v_mfma_f32_16x16x32_bf16 v[120:123], v[160:163], v[190:193], v[120:123]
	v_mfma_f32_16x16x32_bf16 v[104:107], v[160:163], v[198:201], v[104:107]
	v_mfma_f32_16x16x32_bf16 v[92:95], v[144:147], v[212:215], v[92:95]
	v_mfma_f32_16x16x32_bf16 v[76:79], v[144:147], v[220:223], v[76:79]
	v_mfma_f32_16x16x32_bf16 v[88:91], v[160:163], v[212:215], v[88:91]
	v_mfma_f32_16x16x32_bf16 v[72:75], v[160:163], v[220:223], v[72:75]
	v_mfma_f32_16x16x32_bf16 v[124:127], v[148:151], v[194:197], v[124:127]
	v_mfma_f32_16x16x32_bf16 v[108:111], v[148:151], v[208:211], v[108:111]
	v_mfma_f32_16x16x32_bf16 v[120:123], v[168:171], v[194:197], v[120:123]
	v_mfma_f32_16x16x32_bf16 v[104:107], v[168:171], v[208:211], v[104:107]
	v_mfma_f32_16x16x32_bf16 v[92:95], v[148:151], v[216:219], v[92:95]
	v_mfma_f32_16x16x32_bf16 v[76:79], v[148:151], v[224:227], v[76:79]
	v_mfma_f32_16x16x32_bf16 v[88:91], v[168:171], v[216:219], v[88:91]
	v_mfma_f32_16x16x32_bf16 v[72:75], v[168:171], v[224:227], v[72:75]
	s_setprio 0
	s_setprio 1
	v_mfma_f32_16x16x32_bf16 v[116:119], v[172:175], v[190:193], v[116:119]
	v_mfma_f32_16x16x32_bf16 v[100:103], v[172:175], v[198:201], v[100:103]
	v_mfma_f32_16x16x32_bf16 v[112:115], v[182:185], v[190:193], v[112:115]
	v_mfma_f32_16x16x32_bf16 v[96:99], v[182:185], v[198:201], v[96:99]
	v_mfma_f32_16x16x32_bf16 v[84:87], v[172:175], v[212:215], v[84:87]
	v_mfma_f32_16x16x32_bf16 v[68:71], v[172:175], v[220:223], v[68:71]
	v_mfma_f32_16x16x32_bf16 v[80:83], v[182:185], v[212:215], v[80:83]
	v_mfma_f32_16x16x32_bf16 v[64:67], v[182:185], v[220:223], v[64:67]
	v_mfma_f32_16x16x32_bf16 v[116:119], v[176:179], v[194:197], v[116:119]
	v_mfma_f32_16x16x32_bf16 v[100:103], v[176:179], v[208:211], v[100:103]
	v_mfma_f32_16x16x32_bf16 v[112:115], v[186:189], v[194:197], v[112:115]
	v_mfma_f32_16x16x32_bf16 v[96:99], v[186:189], v[208:211], v[96:99]
	v_mfma_f32_16x16x32_bf16 v[84:87], v[176:179], v[216:219], v[84:87]
	v_mfma_f32_16x16x32_bf16 v[68:71], v[176:179], v[224:227], v[68:71]
	v_mfma_f32_16x16x32_bf16 v[80:83], v[186:189], v[216:219], v[80:83]
	v_mfma_f32_16x16x32_bf16 v[64:67], v[186:189], v[224:227], v[64:67]
	s_setprio 0
	s_barrier
; #define PG8_STAGE(bufoff, gbase, voff) do { _Pragma("unroll") for (int _i = 0; _i < 2; ++_i) \
;         __builtin_amdgcn_global_load_lds((const unsigned*)((const char*)(gbase) + (voff)[_i]), (PG8_LAS unsigned*)(lds + (bufoff) + ldsw + _i * 8192), 16, 0, 0); } while (0)
; #define PG8_LDA(dst, b, h) do { _Pragma("unroll") for (int m = 0; m < 4; ++m) _Pragma("unroll") for (int k = 0; k < 2; ++k) dst[m][k] = *(const PG8_LAS bf16x8*)(lds + PG8_SA(b, h) + aoff + m * 2048 + k * 1024); } while (0)
; #define PG8_LDB(dst, b, h) do { _Pragma("unroll") for (int n = 0; n < 2; ++n) _Pragma("unroll") for (int k = 0; k < 2; ++k) dst[n][k] = *(const PG8_LAS bf16x8*)(lds + PG8_SB(b, h) + boff + n * 2048 + k * 1024); } while (0)
; #define PG8_MMA(ai, bj, At, Bt) do { __builtin_amdgcn_s_setprio(1); _Pragma("unroll") for (int m = 0; m < 4; ++m) _Pragma("unroll") for (int n = 0; n < 2; ++n) _Pragma("unroll") for (int k = 0; k < 2; ++k) \
;         acc[ai][bj][m][n] = __builtin_amdgcn_mfma_f32_16x16x32_bf16(Bt[n][k], At[m][k], acc[ai][bj][m][n], 0, 0, 0); __builtin_amdgcn_s_setprio(0); } while (0)
; #define PG8_WAIT_V(n) asm volatile("s_waitcnt vmcnt(" #n ")" ::: "memory")
; #define PG8_WAIT_L(n) asm volatile("s_waitcnt lgkmcnt(" #n ")" ::: "memory")
; #define PG8_BAR __builtin_amdgcn_s_barrier()
; #define PG8_SCHED __builtin_amdgcn_sched_barrier(0)
; template <class Epi, class Sched, bool ALIGN_EPI = false, bool SP2 = false>
; __device__ __forceinline__ void gemm_phase(PG8_LAS unsigned char* lds, const Gemm g, const Sched& S, const Epi& E) {
;     ...
;             PG8_LDB(B0, 0, 0); PG8_LDB(B1, 0, 1); PG8_SCHED; PG8_LDA(At, 0, 0); PG8_STAGE(PG8_SA(1, 1), a1 + hstep, voffA);
;             PG8_WAIT_V(8); PG8_WAIT_L(0); PG8_BAR; PG8_MMA(0, 0, At, B0); PG8_MMA(0, 1, At, B1); PG8_BAR; PG8_SCHED;
;     ...
;             PG8_LDA(At, 1, 1); PG8_STAGE(PG8_SB(1, 0), b3, voffB); PG8_STAGE(PG8_SB(1, 1), b3 + hstep, voffB); PG8_STAGE(PG8_SA(1, 0), a3, voffA);
;             PG8_WAIT_V(8); PG8_WAIT_L(0); PG8_BAR; PG8_MMA(1, 0, At, B0); PG8_MMA(1, 1, At, B1); PG8_BAR; PG8_SCHED;
	s_add_i32 s3, s3, s43
	v_lshl_add_u64 v[164:165], v[164:165], 0, s[10:11]
	s_mov_b32 m0, s3
	ds_read_b128 v[190:193], v157 offset:49152
	ds_read_b128 v[194:197], v157 offset:50176
	ds_read_b128 v[198:201], v157 offset:51200
	ds_read_b128 v[208:211], v157 offset:52224
	ds_read_b128 v[212:215], v157 offset:53248
	ds_read_b128 v[216:219], v157 offset:54272
	ds_read_b128 v[220:223], v157 offset:55296
	ds_read_b128 v[224:227], v157 offset:56320
	global_load_lds_dwordx4 v[164:165], off
	s_add_i32 m0, s3, 0x2000
	s_add_u32 s14, s50, 0x40080
	v_lshl_add_u64 v[164:165], v[202:203], 0, s[10:11]
	s_addc_u32 s15, s51, 0
	s_add_i32 s3, s33, s43
	global_load_lds_dwordx4 v[164:165], off
	v_lshl_add_u64 v[164:165], s[14:15], 0, v[132:133]
	s_mov_b32 m0, s3
	s_nop 0
	global_load_lds_dwordx4 v[164:165], off
	v_lshl_add_u64 v[164:165], s[14:15], 0, v[128:129]
	s_add_i32 m0, s3, 0x2000
	s_nop 0
	global_load_lds_dwordx4 v[164:165], off
	s_waitcnt vmcnt(6)
	s_waitcnt lgkmcnt(0)
	s_barrier
	s_setprio 1
	s_waitcnt lgkmcnt(0)
	v_mfma_f32_16x16x32_bf16 v[60:63], v[144:147], v[190:193], v[60:63]
	v_mfma_f32_16x16x32_bf16 v[44:47], v[144:147], v[198:201], v[44:47]
	v_mfma_f32_16x16x32_bf16 v[56:59], v[160:163], v[190:193], v[56:59]
	v_mfma_f32_16x16x32_bf16 v[40:43], v[160:163], v[198:201], v[40:43]
	v_mfma_f32_16x16x32_bf16 v[28:31], v[144:147], v[212:215], v[28:31]
	v_mfma_f32_16x16x32_bf16 v[12:15], v[144:147], v[220:223], v[12:15]
	v_mfma_f32_16x16x32_bf16 v[24:27], v[160:163], v[212:215], v[24:27]
	v_mfma_f32_16x16x32_bf16 v[8:11], v[160:163], v[220:223], v[8:11]
	v_mfma_f32_16x16x32_bf16 v[60:63], v[148:151], v[194:197], v[60:63]
	v_mfma_f32_16x16x32_bf16 v[44:47], v[148:151], v[208:211], v[44:47]
	v_mfma_f32_16x16x32_bf16 v[56:59], v[168:171], v[194:197], v[56:59]
	v_mfma_f32_16x16x32_bf16 v[40:43], v[168:171], v[208:211], v[40:43]
	v_mfma_f32_16x16x32_bf16 v[28:31], v[148:151], v[216:219], v[28:31]
	v_mfma_f32_16x16x32_bf16 v[12:15], v[148:151], v[224:227], v[12:15]
	v_lshl_add_u64 v[164:165], v[228:229], 0, s[10:11]
	s_mov_b32 m0, s61
	s_nop 0
	global_load_lds_dwordx4 v[164:165], off
	v_mfma_f32_16x16x32_bf16 v[24:27], v[168:171], v[216:219], v[24:27]
	v_mfma_f32_16x16x32_bf16 v[8:11], v[168:171], v[224:227], v[8:11]
	s_setprio 0
	s_setprio 1
	v_mfma_f32_16x16x32_bf16 v[52:55], v[172:175], v[190:193], v[52:55]
	v_mfma_f32_16x16x32_bf16 v[36:39], v[172:175], v[198:201], v[36:39]
	v_mfma_f32_16x16x32_bf16 v[48:51], v[182:185], v[190:193], v[48:51]
	v_mfma_f32_16x16x32_bf16 v[32:35], v[182:185], v[198:201], v[32:35]
	v_mfma_f32_16x16x32_bf16 v[20:23], v[172:175], v[212:215], v[20:23]
	v_mfma_f32_16x16x32_bf16 v[4:7], v[172:175], v[220:223], v[4:7]
	v_mfma_f32_16x16x32_bf16 v[16:19], v[182:185], v[212:215], v[16:19]
	v_mfma_f32_16x16x32_bf16 v[0:3], v[182:185], v[220:223], v[0:3]
	v_mfma_f32_16x16x32_bf16 v[52:55], v[176:179], v[194:197], v[52:55]
	v_mfma_f32_16x16x32_bf16 v[36:39], v[176:179], v[208:211], v[36:39]
	v_mfma_f32_16x16x32_bf16 v[48:51], v[186:189], v[194:197], v[48:51]
	v_mfma_f32_16x16x32_bf16 v[32:35], v[186:189], v[208:211], v[32:35]
	v_mfma_f32_16x16x32_bf16 v[20:23], v[176:179], v[216:219], v[20:23]
	v_mfma_f32_16x16x32_bf16 v[4:7], v[176:179], v[224:227], v[4:7]
	v_lshl_add_u64 v[164:165], v[230:231], 0, s[10:11]
	s_mov_b32 m0, s62
	s_nop 0
	global_load_lds_dwordx4 v[164:165], off
	v_mfma_f32_16x16x32_bf16 v[16:19], v[186:189], v[216:219], v[16:19]
	v_mfma_f32_16x16x32_bf16 v[0:3], v[186:189], v[224:227], v[0:3]
	s_setprio 0
	s_barrier
	s_add_i32 s89, s89, 2
	s_add_u32 s48, s48, 0x100
	s_addc_u32 s49, s49, 0
	s_add_u32 s87, s87, 0x100
	s_addc_u32 s88, s88, 0
.LBB0_191:
	ds_read_b128 v[144:147], v155
	ds_read_b128 v[148:151], v155 offset:1024
	ds_read_b128 v[160:163], v155 offset:2048
	ds_read_b128 v[168:171], v155 offset:3072
	ds_read_b128 v[172:175], v156
	ds_read_b128 v[176:179], v156 offset:1024
	ds_read_b128 v[182:185], v156 offset:2048
	ds_read_b128 v[186:189], v156 offset:3072
	s_add_u32 s3, s48, 0xfffc0080
	s_addc_u32 s14, s49, -1
	s_cmp_eq_u32 s89, 12
	s_cselect_b32 s55, s27, s14
	s_cselect_b32 s54, s67, s3
	s_cselect_b32 s51, s25, s88
	s_cselect_b32 s50, s86, s87
	v_lshl_add_u64 v[164:165], s[48:49], 0, v[136:137]
	s_add_i32 m0, s45, 0xc000
	ds_read_b128 v[190:193], v157
	ds_read_b128 v[194:197], v157 offset:1024
	ds_read_b128 v[198:201], v157 offset:2048
	ds_read_b128 v[208:211], v157 offset:3072
	ds_read_b128 v[212:215], v157 offset:4096
	ds_read_b128 v[216:219], v157 offset:5120
	ds_read_b128 v[220:223], v157 offset:6144
	ds_read_b128 v[224:227], v157 offset:7168
	global_load_lds_dwordx4 v[164:165], off
	v_lshl_add_u64 v[164:165], s[48:49], 0, v[138:139]
	s_add_i32 m0, s45, 0xe000
	s_nop 0
	global_load_lds_dwordx4 v[164:165], off
	s_waitcnt vmcnt(8)
	s_waitcnt lgkmcnt(0)
	s_barrier
; #define PG8_STAGE(bufoff, gbase, voff) do { _Pragma("unroll") for (int _i = 0; _i < 2; ++_i) \
;         __builtin_amdgcn_global_load_lds((const unsigned*)((const char*)(gbase) + (voff)[_i]), (PG8_LAS unsigned*)(lds + (bufoff) + ldsw + _i * 8192), 16, 0, 0); } while (0)
; #define PG8_LDA(dst, b, h) do { _Pragma("unroll") for (int m = 0; m < 4; ++m) _Pragma("unroll") for (int k = 0; k < 2; ++k) dst[m][k] = *(const PG8_LAS bf16x8*)(lds + PG8_SA(b, h) + aoff + m * 2048 + k * 1024); } while (0)
; #define PG8_MMA(ai, bj, At, Bt) do { __builtin_amdgcn_s_setprio(1); _Pragma("unroll") for (int m = 0; m < 4; ++m) _Pragma("unroll") for (int n = 0; n < 2; ++n) _Pragma("unroll") for (int k = 0; k < 2; ++k) \
;         acc[ai][bj][m][n] = __builtin_amdgcn_mfma_f32_16x16x32_bf16(Bt[n][k], At[m][k], acc[ai][bj][m][n], 0, 0, 0); __builtin_amdgcn_s_setprio(0); } while (0)
; #define PG8_WAIT_V(n) asm volatile("s_waitcnt vmcnt(" #n ")" ::: "memory")
; #define PG8_WAIT_L(n) asm volatile("s_waitcnt lgkmcnt(" #n ")" ::: "memory")
; #define PG8_BAR __builtin_amdgcn_s_barrier()
; #define PG8_SCHED __builtin_amdgcn_sched_barrier(0)
; template <class Epi, class Sched, bool ALIGN_EPI = false, bool SP2 = false>
; __device__ __forceinline__ void gemm_phase(PG8_LAS unsigned char* lds, const Gemm g, const Sched& S, const Epi& E) {
;     ...
;             PG8_WAIT_V(8); PG8_WAIT_L(0); PG8_BAR; PG8_MMA(0, 0, At, B0); PG8_MMA(0, 1, At, B1); PG8_BAR; PG8_SCHED;
;             PG8_LDA(At, 0, 1); PG8_STAGE(PG8_SB(0, 0), b2, voffB); PG8_STAGE(PG8_SB(0, 1), b2 + hstep, voffB); PG8_STAGE(PG8_SA(0, 0), a2, voffA);
;             PG8_WAIT_V(8); PG8_WAIT_L(0); PG8_BAR; PG8_MMA(1, 0, At, B0); PG8_MMA(1, 1, At, B1); PG8_BAR; PG8_SCHED;
	s_setprio 1
	s_waitcnt lgkmcnt(0)
	v_mfma_f32_16x16x32_bf16 v[124:127], v[144:147], v[190:193], v[124:127]
	v_mfma_f32_16x16x32_bf16 v[108:111], v[144:147], v[198:201], v[108:111]
	v_mfma_f32_16x16x32_bf16 v[120:123], v[160:163], v[190:193], v[120:123]
	v_mfma_f32_16x16x32_bf16 v[104:107], v[160:163], v[198:201], v[104:107]
	v_mfma_f32_16x16x32_bf16 v[92:95], v[144:147], v[212:215], v[92:95]
	v_mfma_f32_16x16x32_bf16 v[76:79], v[144:147], v[220:223], v[76:79]
	v_mfma_f32_16x16x32_bf16 v[88:91], v[160:163], v[212:215], v[88:91]
	v_mfma_f32_16x16x32_bf16 v[72:75], v[160:163], v[220:223], v[72:75]
	v_mfma_f32_16x16x32_bf16 v[124:127], v[148:151], v[194:197], v[124:127]
	v_mfma_f32_16x16x32_bf16 v[108:111], v[148:151], v[208:211], v[108:111]
	v_mfma_f32_16x16x32_bf16 v[120:123], v[168:171], v[194:197], v[120:123]
	v_mfma_f32_16x16x32_bf16 v[104:107], v[168:171], v[208:211], v[104:107]
	v_mfma_f32_16x16x32_bf16 v[92:95], v[148:151], v[216:219], v[92:95]
	v_mfma_f32_16x16x32_bf16 v[76:79], v[148:151], v[224:227], v[76:79]
	v_mfma_f32_16x16x32_bf16 v[88:91], v[168:171], v[216:219], v[88:91]
	v_mfma_f32_16x16x32_bf16 v[72:75], v[168:171], v[224:227], v[72:75]
	s_setprio 0
	s_setprio 1
	v_mfma_f32_16x16x32_bf16 v[116:119], v[172:175], v[190:193], v[116:119]
	v_mfma_f32_16x16x32_bf16 v[100:103], v[172:175], v[198:201], v[100:103]
	v_mfma_f32_16x16x32_bf16 v[112:115], v[182:185], v[190:193], v[112:115]
	v_mfma_f32_16x16x32_bf16 v[96:99], v[182:185], v[198:201], v[96:99]
	v_mfma_f32_16x16x32_bf16 v[84:87], v[172:175], v[212:215], v[84:87]
	v_mfma_f32_16x16x32_bf16 v[68:71], v[172:175], v[220:223], v[68:71]
	v_mfma_f32_16x16x32_bf16 v[80:83], v[182:185], v[212:215], v[80:83]
	v_mfma_f32_16x16x32_bf16 v[64:67], v[182:185], v[220:223], v[64:67]
	v_mfma_f32_16x16x32_bf16 v[116:119], v[176:179], v[194:197], v[116:119]
	v_mfma_f32_16x16x32_bf16 v[100:103], v[176:179], v[208:211], v[100:103]
	v_mfma_f32_16x16x32_bf16 v[112:115], v[186:189], v[194:197], v[112:115]
	v_mfma_f32_16x16x32_bf16 v[96:99], v[186:189], v[208:211], v[96:99]
	v_mfma_f32_16x16x32_bf16 v[84:87], v[176:179], v[216:219], v[84:87]
	v_mfma_f32_16x16x32_bf16 v[68:71], v[176:179], v[224:227], v[68:71]
	v_mfma_f32_16x16x32_bf16 v[80:83], v[186:189], v[216:219], v[80:83]
	v_mfma_f32_16x16x32_bf16 v[64:67], v[186:189], v[224:227], v[64:67]
	s_setprio 0
	s_barrier
	s_add_i32 s3, s63, s43
	v_lshl_add_u64 v[164:165], s[50:51], 0, v[132:133]
	s_mov_b32 m0, s3
	ds_read_b128 v[190:193], v157 offset:16384
	ds_read_b128 v[194:197], v157 offset:17408
	ds_read_b128 v[198:201], v157 offset:18432
	ds_read_b128 v[208:211], v157 offset:19456
	ds_read_b128 v[212:215], v157 offset:20480
	ds_read_b128 v[216:219], v157 offset:21504
	ds_read_b128 v[220:223], v157 offset:22528
	ds_read_b128 v[224:227], v157 offset:23552
	global_load_lds_dwordx4 v[164:165], off
	s_add_i32 m0, s3, 0x2000
	s_add_u32 s14, s50, 0x40000
	v_lshl_add_u64 v[202:203], s[50:51], 0, v[128:129]
	s_addc_u32 s15, s51, 0
	s_add_i32 s3, s64, s43
	global_load_lds_dwordx4 v[202:203], off
	v_lshl_add_u64 v[228:229], s[14:15], 0, v[132:133]
	s_mov_b32 m0, s3
	global_load_lds_dwordx4 v[228:229], off
	v_lshl_add_u64 v[228:229], s[14:15], 0, v[128:129]
	s_add_i32 m0, s3, 0x2000
	s_nop 0
	global_load_lds_dwordx4 v[228:229], off
	s_waitcnt vmcnt(6)
	s_waitcnt lgkmcnt(0)
	s_barrier
	s_setprio 1
	s_waitcnt lgkmcnt(0)
	v_mfma_f32_16x16x32_bf16 v[60:63], v[144:147], v[190:193], v[60:63]
	v_mfma_f32_16x16x32_bf16 v[44:47], v[144:147], v[198:201], v[44:47]
	v_mfma_f32_16x16x32_bf16 v[56:59], v[160:163], v[190:193], v[56:59]
	v_mfma_f32_16x16x32_bf16 v[40:43], v[160:163], v[198:201], v[40:43]
	v_mfma_f32_16x16x32_bf16 v[28:31], v[144:147], v[212:215], v[28:31]
	v_mfma_f32_16x16x32_bf16 v[12:15], v[144:147], v[220:223], v[12:15]
	v_mfma_f32_16x16x32_bf16 v[24:27], v[160:163], v[212:215], v[24:27]
	v_mfma_f32_16x16x32_bf16 v[8:11], v[160:163], v[220:223], v[8:11]
	v_mfma_f32_16x16x32_bf16 v[60:63], v[148:151], v[194:197], v[60:63]
	v_mfma_f32_16x16x32_bf16 v[44:47], v[148:151], v[208:211], v[44:47]
	v_mfma_f32_16x16x32_bf16 v[56:59], v[168:171], v[194:197], v[56:59]
	v_mfma_f32_16x16x32_bf16 v[40:43], v[168:171], v[208:211], v[40:43]
	v_mfma_f32_16x16x32_bf16 v[28:31], v[148:151], v[216:219], v[28:31]
	v_mfma_f32_16x16x32_bf16 v[12:15], v[148:151], v[224:227], v[12:15]
	v_lshl_add_u64 v[228:229], s[54:55], 0, v[134:135]
	s_mov_b32 m0, s45
	s_nop 0
	global_load_lds_dwordx4 v[228:229], off
	v_mfma_f32_16x16x32_bf16 v[24:27], v[168:171], v[216:219], v[24:27]
	v_mfma_f32_16x16x32_bf16 v[8:11], v[168:171], v[224:227], v[8:11]
	s_setprio 0
	s_setprio 1
	v_mfma_f32_16x16x32_bf16 v[52:55], v[172:175], v[190:193], v[52:55]
	v_mfma_f32_16x16x32_bf16 v[36:39], v[172:175], v[198:201], v[36:39]
	v_mfma_f32_16x16x32_bf16 v[48:51], v[182:185], v[190:193], v[48:51]
	v_mfma_f32_16x16x32_bf16 v[32:35], v[182:185], v[198:201], v[32:35]
	v_mfma_f32_16x16x32_bf16 v[20:23], v[172:175], v[212:215], v[20:23]
	v_mfma_f32_16x16x32_bf16 v[4:7], v[172:175], v[220:223], v[4:7]
	v_mfma_f32_16x16x32_bf16 v[16:19], v[182:185], v[212:215], v[16:19]
	v_mfma_f32_16x16x32_bf16 v[0:3], v[182:185], v[220:223], v[0:3]
	v_mfma_f32_16x16x32_bf16 v[52:55], v[176:179], v[194:197], v[52:55]
	v_mfma_f32_16x16x32_bf16 v[36:39], v[176:179], v[208:211], v[36:39]
	v_mfma_f32_16x16x32_bf16 v[48:51], v[186:189], v[194:197], v[48:51]
	v_mfma_f32_16x16x32_bf16 v[32:35], v[186:189], v[208:211], v[32:35]
	v_mfma_f32_16x16x32_bf16 v[20:23], v[176:179], v[216:219], v[20:23]
	v_mfma_f32_16x16x32_bf16 v[4:7], v[176:179], v[224:227], v[4:7]
	v_lshl_add_u64 v[230:231], s[54:55], 0, v[130:131]
	s_mov_b32 m0, s57
	s_nop 0
	global_load_lds_dwordx4 v[230:231], off
	v_mfma_f32_16x16x32_bf16 v[16:19], v[186:189], v[216:219], v[16:19]
	v_mfma_f32_16x16x32_bf16 v[0:3], v[186:189], v[224:227], v[0:3]
	s_setprio 0
	s_barrier
; #define PG8_STAGE(bufoff, gbase, voff) do { _Pragma("unroll") for (int _i = 0; _i < 2; ++_i) \
;         __builtin_amdgcn_global_load_lds((const unsigned*)((const char*)(gbase) + (voff)[_i]), (PG8_LAS unsigned*)(lds + (bufoff) + ldsw + _i * 8192), 16, 0, 0); } while (0)
; #define PG8_LDA(dst, b, h) do { _Pragma("unroll") for (int m = 0; m < 4; ++m) _Pragma("unroll") for (int k = 0; k < 2; ++k) dst[m][k] = *(const PG8_LAS bf16x8*)(lds + PG8_SA(b, h) + aoff + m * 2048 + k * 1024); } while (0)
; #define PG8_LDB(dst, b, h) do { _Pragma("unroll") for (int n = 0; n < 2; ++n) _Pragma("unroll") for (int k = 0; k < 2; ++k) dst[n][k] = *(const PG8_LAS bf16x8*)(lds + PG8_SB(b, h) + boff + n * 2048 + k * 1024); } while (0)
; #define PG8_MMA(ai, bj, At, Bt) do { __builtin_amdgcn_s_setprio(1); _Pragma("unroll") for (int m = 0; m < 4; ++m) _Pragma("unroll") for (int n = 0; n < 2; ++n) _Pragma("unroll") for (int k = 0; k < 2; ++k) \
;         acc[ai][bj][m][n] = __builtin_amdgcn_mfma_f32_16x16x32_bf16(Bt[n][k], At[m][k], acc[ai][bj][m][n], 0, 0, 0); __builtin_amdgcn_s_setprio(0); } while (0)
; #define PG8_WAIT_V(n) asm volatile("s_waitcnt vmcnt(" #n ")" ::: "memory")
; #define PG8_WAIT_L(n) asm volatile("s_waitcnt lgkmcnt(" #n ")" ::: "memory")
; #define PG8_BAR __builtin_amdgcn_s_barrier()
; #define PG8_SCHED __builtin_amdgcn_sched_barrier(0)
; template <class Epi, class Sched, bool ALIGN_EPI = false, bool SP2 = false>
; __device__ __forceinline__ void gemm_phase(PG8_LAS unsigned char* lds, const Gemm g, const Sched& S, const Epi& E) {
;     ...
;             PG8_LDB(B0, 1, 0); PG8_LDB(B1, 1, 1); PG8_SCHED; PG8_LDA(At, 1, 0); PG8_STAGE(PG8_SA(0, 1), a2 + hstep, voffA);
;             PG8_WAIT_V(8); PG8_WAIT_L(0); PG8_BAR; PG8_MMA(0, 0, At, B0); PG8_MMA(0, 1, At, B1); PG8_BAR; PG8_SCHED;
	s_add_i32 s3, 0, 0x18000
	v_add_u32_e32 v159, s3, v153
	s_add_i32 s33, 0, 0x1c000
	ds_read_b128 v[144:147], v159
	ds_read_b128 v[148:151], v159 offset:1024
	ds_read_b128 v[160:163], v159 offset:2048
	ds_read_b128 v[168:171], v159 offset:3072
	v_add_u32_e32 v159, s33, v153
	ds_read_b128 v[172:175], v159
	ds_read_b128 v[176:179], v159 offset:1024
	ds_read_b128 v[182:185], v159 offset:2048
	ds_read_b128 v[186:189], v159 offset:3072
	s_add_u32 s14, s54, 0x40000
	s_addc_u32 s15, s55, 0
	s_mov_b32 m0, s58
	v_lshl_add_u64 v[232:233], s[14:15], 0, v[134:135]
	ds_read_b128 v[190:193], v157 offset:32768
	ds_read_b128 v[194:197], v157 offset:33792
	ds_read_b128 v[198:201], v157 offset:34816
	ds_read_b128 v[208:211], v157 offset:35840
	ds_read_b128 v[212:215], v157 offset:36864
	ds_read_b128 v[216:219], v157 offset:37888
	ds_read_b128 v[220:223], v157 offset:38912
	ds_read_b128 v[224:227], v157 offset:39936
	global_load_lds_dwordx4 v[232:233], off
	v_lshl_add_u64 v[232:233], s[14:15], 0, v[130:131]
	s_mov_b32 m0, s59
	s_nop 0
	global_load_lds_dwordx4 v[232:233], off
	s_waitcnt vmcnt(8)
	s_waitcnt lgkmcnt(0)
	s_barrier
	s_setprio 1
	s_waitcnt lgkmcnt(0)
	v_mfma_f32_16x16x32_bf16 v[124:127], v[144:147], v[190:193], v[124:127]
	v_mfma_f32_16x16x32_bf16 v[108:111], v[144:147], v[198:201], v[108:111]
	v_mfma_f32_16x16x32_bf16 v[120:123], v[160:163], v[190:193], v[120:123]
	v_mfma_f32_16x16x32_bf16 v[104:107], v[160:163], v[198:201], v[104:107]
	v_mfma_f32_16x16x32_bf16 v[92:95], v[144:147], v[212:215], v[92:95]
	v_mfma_f32_16x16x32_bf16 v[76:79], v[144:147], v[220:223], v[76:79]
	v_mfma_f32_16x16x32_bf16 v[88:91], v[160:163], v[212:215], v[88:91]
	v_mfma_f32_16x16x32_bf16 v[72:75], v[160:163], v[220:223], v[72:75]
	v_mfma_f32_16x16x32_bf16 v[124:127], v[148:151], v[194:197], v[124:127]
	v_mfma_f32_16x16x32_bf16 v[108:111], v[148:151], v[208:211], v[108:111]
	v_mfma_f32_16x16x32_bf16 v[120:123], v[168:171], v[194:197], v[120:123]
	v_mfma_f32_16x16x32_bf16 v[104:107], v[168:171], v[208:211], v[104:107]
	v_mfma_f32_16x16x32_bf16 v[92:95], v[148:151], v[216:219], v[92:95]
	v_mfma_f32_16x16x32_bf16 v[76:79], v[148:151], v[224:227], v[76:79]
	v_mfma_f32_16x16x32_bf16 v[88:91], v[168:171], v[216:219], v[88:91]
	v_mfma_f32_16x16x32_bf16 v[72:75], v[168:171], v[224:227], v[72:75]
	s_setprio 0
	s_setprio 1
	v_mfma_f32_16x16x32_bf16 v[116:119], v[172:175], v[190:193], v[116:119]
	v_mfma_f32_16x16x32_bf16 v[100:103], v[172:175], v[198:201], v[100:103]
	v_mfma_f32_16x16x32_bf16 v[112:115], v[182:185], v[190:193], v[112:115]
	v_mfma_f32_16x16x32_bf16 v[96:99], v[182:185], v[198:201], v[96:99]
	v_mfma_f32_16x16x32_bf16 v[84:87], v[172:175], v[212:215], v[84:87]
	v_mfma_f32_16x16x32_bf16 v[68:71], v[172:175], v[220:223], v[68:71]
	v_mfma_f32_16x16x32_bf16 v[80:83], v[182:185], v[212:215], v[80:83]
	v_mfma_f32_16x16x32_bf16 v[64:67], v[182:185], v[220:223], v[64:67]
	v_mfma_f32_16x16x32_bf16 v[116:119], v[176:179], v[194:197], v[116:119]
	v_mfma_f32_16x16x32_bf16 v[100:103], v[176:179], v[208:211], v[100:103]
	v_mfma_f32_16x16x32_bf16 v[112:115], v[186:189], v[194:197], v[112:115]
	v_mfma_f32_16x16x32_bf16 v[96:99], v[186:189], v[208:211], v[96:99]
	v_mfma_f32_16x16x32_bf16 v[84:87], v[176:179], v[216:219], v[84:87]
	v_mfma_f32_16x16x32_bf16 v[68:71], v[176:179], v[224:227], v[68:71]
	v_mfma_f32_16x16x32_bf16 v[80:83], v[186:189], v[216:219], v[80:83]
	v_mfma_f32_16x16x32_bf16 v[64:67], v[186:189], v[224:227], v[64:67]
	s_setprio 0
	s_barrier
; #define PG8_STAGE(bufoff, gbase, voff) do { _Pragma("unroll") for (int _i = 0; _i < 2; ++_i) \
;         __builtin_amdgcn_global_load_lds((const unsigned*)((const char*)(gbase) + (voff)[_i]), (PG8_LAS unsigned*)(lds + (bufoff) + ldsw + _i * 8192), 16, 0, 0); } while (0)
; #define PG8_LDA(dst, b, h) do { _Pragma("unroll") for (int m = 0; m < 4; ++m) _Pragma("unroll") for (int k = 0; k < 2; ++k) dst[m][k] = *(const PG8_LAS bf16x8*)(lds + PG8_SA(b, h) + aoff + m * 2048 + k * 1024); } while (0)
; #define PG8_MMA(ai, bj, At, Bt) do { __builtin_amdgcn_s_setprio(1); _Pragma("unroll") for (int m = 0; m < 4; ++m) _Pragma("unroll") for (int n = 0; n < 2; ++n) _Pragma("unroll") for (int k = 0; k < 2; ++k) \
;         acc[ai][bj][m][n] = __builtin_amdgcn_mfma_f32_16x16x32_bf16(Bt[n][k], At[m][k], acc[ai][bj][m][n], 0, 0, 0); __builtin_amdgcn_s_setprio(0); } while (0)
; #define PG8_WAIT_V(n) asm volatile("s_waitcnt vmcnt(" #n ")" ::: "memory")
; #define PG8_WAIT_L(n) asm volatile("s_waitcnt lgkmcnt(" #n ")" ::: "memory")
; #define PG8_BAR __builtin_amdgcn_s_barrier()
; #define PG8_SCHED __builtin_amdgcn_sched_barrier(0)
; __device__ __forceinline__ float row_rs(const float* ssp, int row) { const unsigned long long v = ((const unsigned long long*)ssp)[row];
;     return __builtin_amdgcn_rsqf((float)v * (1.0f / 4294967296.0f) * (1.0f / 1024.0f) + RMS_EPS); }
; template <class Epi, class Sched, bool ALIGN_EPI = false, bool SP2 = false>
; __device__ __forceinline__ void gemm_phase(PG8_LAS unsigned char* lds, const Gemm g, const Sched& S, const Epi& E) {
;     ...
;             PG8_LDA(At, 1, 1); PG8_STAGE(PG8_SB(1, 0), b3, voffB); PG8_STAGE(PG8_SB(1, 1), b3 + hstep, voffB); PG8_STAGE(PG8_SA(1, 0), a3, voffA);
;             PG8_WAIT_V(8); PG8_WAIT_L(0); PG8_BAR; PG8_MMA(1, 0, At, B0); PG8_MMA(1, 1, At, B1); PG8_BAR; PG8_SCHED;
	s_add_i32 s3, s3, s43
	v_lshl_add_u64 v[164:165], v[164:165], 0, s[10:11]
	s_mov_b32 m0, s3
	ds_read_b128 v[190:193], v157 offset:49152
	ds_read_b128 v[194:197], v157 offset:50176
	ds_read_b128 v[198:201], v157 offset:51200
	ds_read_b128 v[208:211], v157 offset:52224
	ds_read_b128 v[212:215], v157 offset:53248
	ds_read_b128 v[216:219], v157 offset:54272
	ds_read_b128 v[220:223], v157 offset:55296
	ds_read_b128 v[224:227], v157 offset:56320
	global_load_lds_dwordx4 v[164:165], off
	s_add_i32 m0, s3, 0x2000
	s_add_u32 s14, s50, 0x40080
	v_lshl_add_u64 v[164:165], v[202:203], 0, s[10:11]
	s_addc_u32 s15, s51, 0
	s_add_i32 s3, s33, s43
	global_load_lds_dwordx4 v[164:165], off
	v_lshl_add_u64 v[164:165], s[14:15], 0, v[132:133]
	s_mov_b32 m0, s3
	s_nop 0
	global_load_lds_dwordx4 v[164:165], off
	v_lshl_add_u64 v[164:165], s[14:15], 0, v[128:129]
	s_add_i32 m0, s3, 0x2000
	s_nop 0
	global_load_lds_dwordx4 v[164:165], off
	s_waitcnt vmcnt(6)
	s_waitcnt lgkmcnt(0)
	s_barrier
	s_setprio 1
	s_waitcnt lgkmcnt(0)
	v_mfma_f32_16x16x32_bf16 v[60:63], v[144:147], v[190:193], v[60:63]
	v_mfma_f32_16x16x32_bf16 v[44:47], v[144:147], v[198:201], v[44:47]
	v_mfma_f32_16x16x32_bf16 v[56:59], v[160:163], v[190:193], v[56:59]
	v_mfma_f32_16x16x32_bf16 v[40:43], v[160:163], v[198:201], v[40:43]
	v_mfma_f32_16x16x32_bf16 v[28:31], v[144:147], v[212:215], v[28:31]
	v_mfma_f32_16x16x32_bf16 v[12:15], v[144:147], v[220:223], v[12:15]
	v_mfma_f32_16x16x32_bf16 v[24:27], v[160:163], v[212:215], v[24:27]
	v_mfma_f32_16x16x32_bf16 v[8:11], v[160:163], v[220:223], v[8:11]
	v_mfma_f32_16x16x32_bf16 v[60:63], v[148:151], v[194:197], v[60:63]
	v_mfma_f32_16x16x32_bf16 v[44:47], v[148:151], v[208:211], v[44:47]
	v_mfma_f32_16x16x32_bf16 v[56:59], v[168:171], v[194:197], v[56:59]
	v_mfma_f32_16x16x32_bf16 v[40:43], v[168:171], v[208:211], v[40:43]
	v_mfma_f32_16x16x32_bf16 v[28:31], v[148:151], v[216:219], v[28:31]
	v_mfma_f32_16x16x32_bf16 v[12:15], v[148:151], v[224:227], v[12:15]
	v_lshl_add_u64 v[164:165], v[228:229], 0, s[10:11]
	s_mov_b32 m0, s61
	s_nop 0
	global_load_lds_dwordx4 v[164:165], off
	v_mfma_f32_16x16x32_bf16 v[24:27], v[168:171], v[216:219], v[24:27]
	v_mfma_f32_16x16x32_bf16 v[8:11], v[168:171], v[224:227], v[8:11]
	s_setprio 0
	s_setprio 1
	v_mfma_f32_16x16x32_bf16 v[52:55], v[172:175], v[190:193], v[52:55]
	v_mfma_f32_16x16x32_bf16 v[36:39], v[172:175], v[198:201], v[36:39]
	v_mfma_f32_16x16x32_bf16 v[48:51], v[182:185], v[190:193], v[48:51]
	v_mfma_f32_16x16x32_bf16 v[32:35], v[182:185], v[198:201], v[32:35]
	v_mfma_f32_16x16x32_bf16 v[20:23], v[172:175], v[212:215], v[20:23]
	v_mfma_f32_16x16x32_bf16 v[4:7], v[172:175], v[220:223], v[4:7]
	v_mfma_f32_16x16x32_bf16 v[16:19], v[182:185], v[212:215], v[16:19]
	v_mfma_f32_16x16x32_bf16 v[0:3], v[182:185], v[220:223], v[0:3]
	v_mfma_f32_16x16x32_bf16 v[52:55], v[176:179], v[194:197], v[52:55]
	v_mfma_f32_16x16x32_bf16 v[36:39], v[176:179], v[208:211], v[36:39]
	v_mfma_f32_16x16x32_bf16 v[48:51], v[186:189], v[194:197], v[48:51]
	v_mfma_f32_16x16x32_bf16 v[32:35], v[186:189], v[208:211], v[32:35]
	v_mfma_f32_16x16x32_bf16 v[20:23], v[176:179], v[216:219], v[20:23]
	v_mfma_f32_16x16x32_bf16 v[4:7], v[176:179], v[224:227], v[4:7]
	v_lshl_add_u64 v[164:165], v[230:231], 0, s[10:11]
	s_mov_b32 m0, s62
	s_nop 0
	global_load_lds_dwordx4 v[164:165], off
	v_mfma_f32_16x16x32_bf16 v[16:19], v[186:189], v[216:219], v[16:19]
	v_mfma_f32_16x16x32_bf16 v[0:3], v[186:189], v[224:227], v[0:3]
	s_setprio 0
	s_barrier
	s_add_i32 s89, s89, 2
	s_add_u32 s48, s48, 0x100
	s_addc_u32 s49, s49, 0
	s_add_u32 s87, s87, 0x100
	s_addc_u32 s88, s88, 0
	s_cmp_gt_u32 s89, 13
	s_cbranch_scc0 .LBB0_191
	v_lshl_add_u32 v144, s44, 8, v152
	v_ashrrev_i32_e32 v145, 31, v144
	v_lshl_add_u64 v[150:151], v[144:145], 3, s[6:7]
	global_load_dwordx2 v[182:183], v[150:151], off
	global_load_dwordx2 v[184:185], v[150:151], off offset:128
	global_load_dwordx2 v[186:187], v[150:151], off offset:256
	global_load_dwordx2 v[188:189], v[150:151], off offset:384
	global_load_dwordx2 v[190:191], v[150:151], off offset:1024
	global_load_dwordx2 v[192:193], v[150:151], off offset:1152
	global_load_dwordx2 v[194:195], v[150:151], off offset:1280
	global_load_dwordx2 v[196:197], v[150:151], off offset:1408
	s_and_b64 vcc, exec, s[16:17]
	s_cbranch_vccz .LBB0_194
	s_barrier

; #define PG8_STAGE(bufoff, gbase, voff) do { _Pragma("unroll") for (int _i = 0; _i < 2; ++_i) \
;         __builtin_amdgcn_global_load_lds((const unsigned*)((const char*)(gbase) + (voff)[_i]), (PG8_LAS unsigned*)(lds + (bufoff) + ldsw + _i * 8192), 16, 0, 0); } while (0)
; #define PG8_LDA(dst, b, h) do { _Pragma("unroll") for (int m = 0; m < 4; ++m) _Pragma("unroll") for (int k = 0; k < 2; ++k) dst[m][k] = *(const PG8_LAS bf16x8*)(lds + PG8_SA(b, h) + aoff + m * 2048 + k * 1024); } while (0)
; #define PG8_LDB(dst, b, h) do { _Pragma("unroll") for (int n = 0; n < 2; ++n) _Pragma("unroll") for (int k = 0; k < 2; ++k) dst[n][k] = *(const PG8_LAS bf16x8*)(lds + PG8_SB(b, h) + boff + n * 2048 + k * 1024); } while (0)
; #define PG8_MMA(ai, bj, At, Bt) do { __builtin_amdgcn_s_setprio(1); _Pragma("unroll") for (int m = 0; m < 4; ++m) _Pragma("unroll") for (int n = 0; n < 2; ++n) _Pragma("unroll") for (int k = 0; k < 2; ++k) \
;         acc[ai][bj][m][n] = __builtin_amdgcn_mfma_f32_16x16x32_bf16(Bt[n][k], At[m][k], acc[ai][bj][m][n], 0, 0, 0); __builtin_amdgcn_s_setprio(0); } while (0)
; #define PG8_BAR __builtin_amdgcn_s_barrier()
; template <class Epi, class Sched, bool ALIGN_EPI = false, bool SP2 = false>
; __device__ __forceinline__ void gemm_phase(PG8_LAS unsigned char* lds, const Gemm g, const Sched& S, const Epi& E) {
;     ...
;         const bool has_next = S.next(ui + 1, nxt);
;         const char* nA = has_next ? (const char*)g.A + (size_t)nxt.pm * tstep : cA; const char* nB = has_next ? (const char*)g.Bt + (size_t)nxt.pn * tstep : cB;
;         for (int t = 0; t < nt; t += 2) {
;             const bool last = (t == nt - 2);
;             const char* a1 = cA + (size_t)(t + 1) * kstep;
;             const char* a2 = last ? nA : cA + (size_t)(t + 2) * kstep; const char* b2 = last ? nB : cB + (size_t)(t + 2) * kstep;
;             const char* a3 = a2 + kstep; const char* b3 = b2 + kstep;
;             if (last && has_next) S.a_ready(nxt);
;             if constexpr (SP2) {
;             PG8_LDB(B0, 0, 0); PG8_LDB(B1, 0, 1); PG8_SCHED; PG8_LDA(At, 0, 0); PG8_STAGE(PG8_SA(1, 1), a1 + hstep, voffA);
;             PG8_WAIT_V(8); PG8_WAIT_L(0); PG8_BAR; PG8_MMA(0, 0, At, B0); PG8_MMA(0, 1, At, B1); PG8_BAR; PG8_SCHED;
;             PG8_LDA(At, 0, 1); PG8_STAGE(PG8_SB(0, 0), b2, voffB); PG8_STAGE(PG8_SB(0, 1), b2 + hstep, voffB); PG8_STAGE(PG8_SA(0, 0), a2, voffA);
.LBB0_268:
	s_add_u32 s91, s50, 0x100
	s_addc_u32 s92, s51, 0
	s_mov_b32 s93, -2
	s_waitcnt lgkmcnt(0)
	ds_read_b128 v[128:131], v165
	ds_read_b128 v[132:135], v165 offset:1024
	ds_read_b128 v[152:155], v165 offset:2048
	ds_read_b128 v[156:159], v165 offset:3072
	ds_read_b128 v[172:175], v168
	ds_read_b128 v[176:179], v168 offset:1024
	ds_read_b128 v[182:185], v168 offset:2048
	ds_read_b128 v[186:189], v168 offset:3072
	s_add_u32 s50, s10, 0x100
	s_addc_u32 s51, s11, 0
	s_cmp_eq_u32 s93, 40
	s_cselect_b32 s57, s1, s51
	s_cselect_b32 s56, s0, s50
	s_cselect_b32 s55, s49, s92
	s_cselect_b32 s54, s48, s91
	v_lshl_add_u64 v[160:161], s[10:11], 0, v[144:145]
	s_add_i32 m0, s58, 0xc000
	ds_read_b128 v[190:193], v169
	ds_read_b128 v[194:197], v169 offset:1024
	ds_read_b128 v[198:201], v169 offset:2048
	ds_read_b128 v[208:211], v169 offset:3072
	ds_read_b128 v[212:215], v169 offset:4096
	ds_read_b128 v[216:219], v169 offset:5120
	ds_read_b128 v[220:223], v169 offset:6144
	ds_read_b128 v[224:227], v169 offset:7168
	global_load_lds_dwordx4 v[160:161], off
	v_lshl_add_u64 v[160:161], s[10:11], 0, v[146:147]
	s_add_i32 m0, s58, 0xe000
	s_nop 0
	global_load_lds_dwordx4 v[160:161], off
	s_waitcnt vmcnt(8)
	s_waitcnt lgkmcnt(0)
	s_barrier
	s_setprio 1
	s_waitcnt lgkmcnt(0)
	v_mfma_f32_16x16x32_bf16 v[124:127], v[128:131], v[190:193], 0
	v_mfma_f32_16x16x32_bf16 v[108:111], v[128:131], v[198:201], 0
	v_mfma_f32_16x16x32_bf16 v[120:123], v[152:155], v[190:193], 0
	v_mfma_f32_16x16x32_bf16 v[104:107], v[152:155], v[198:201], 0
	v_mfma_f32_16x16x32_bf16 v[92:95], v[128:131], v[212:215], 0
	v_mfma_f32_16x16x32_bf16 v[76:79], v[128:131], v[220:223], 0
	v_mfma_f32_16x16x32_bf16 v[88:91], v[152:155], v[212:215], 0
	v_mfma_f32_16x16x32_bf16 v[72:75], v[152:155], v[220:223], 0
	v_mfma_f32_16x16x32_bf16 v[124:127], v[132:135], v[194:197], v[124:127]
	v_mfma_f32_16x16x32_bf16 v[108:111], v[132:135], v[208:211], v[108:111]
	v_mfma_f32_16x16x32_bf16 v[120:123], v[156:159], v[194:197], v[120:123]
	v_mfma_f32_16x16x32_bf16 v[104:107], v[156:159], v[208:211], v[104:107]
	v_mfma_f32_16x16x32_bf16 v[92:95], v[132:135], v[216:219], v[92:95]
	v_mfma_f32_16x16x32_bf16 v[76:79], v[132:135], v[224:227], v[76:79]
	v_mfma_f32_16x16x32_bf16 v[88:91], v[156:159], v[216:219], v[88:91]
	v_mfma_f32_16x16x32_bf16 v[72:75], v[156:159], v[224:227], v[72:75]
	s_setprio 0
	s_setprio 1
	v_mfma_f32_16x16x32_bf16 v[116:119], v[172:175], v[190:193], 0
	v_mfma_f32_16x16x32_bf16 v[100:103], v[172:175], v[198:201], 0
	v_mfma_f32_16x16x32_bf16 v[112:115], v[182:185], v[190:193], 0
	v_mfma_f32_16x16x32_bf16 v[96:99], v[182:185], v[198:201], 0
	v_mfma_f32_16x16x32_bf16 v[84:87], v[172:175], v[212:215], 0
	v_mfma_f32_16x16x32_bf16 v[68:71], v[172:175], v[220:223], 0
	v_mfma_f32_16x16x32_bf16 v[80:83], v[182:185], v[212:215], 0
	v_mfma_f32_16x16x32_bf16 v[64:67], v[182:185], v[220:223], 0
	v_mfma_f32_16x16x32_bf16 v[116:119], v[176:179], v[194:197], v[116:119]
	v_mfma_f32_16x16x32_bf16 v[100:103], v[176:179], v[208:211], v[100:103]
	v_mfma_f32_16x16x32_bf16 v[112:115], v[186:189], v[194:197], v[112:115]
	v_mfma_f32_16x16x32_bf16 v[96:99], v[186:189], v[208:211], v[96:99]
	v_mfma_f32_16x16x32_bf16 v[84:87], v[176:179], v[216:219], v[84:87]
	v_mfma_f32_16x16x32_bf16 v[68:71], v[176:179], v[224:227], v[68:71]
	v_mfma_f32_16x16x32_bf16 v[80:83], v[186:189], v[216:219], v[80:83]
	v_mfma_f32_16x16x32_bf16 v[64:67], v[186:189], v[224:227], v[64:67]
	s_setprio 0
	s_barrier
	s_add_i32 s3, s65, s43
	v_lshl_add_u64 v[160:161], s[54:55], 0, v[138:139]
	s_mov_b32 m0, s3
	ds_read_b128 v[190:193], v169 offset:16384
	ds_read_b128 v[194:197], v169 offset:17408
	ds_read_b128 v[198:201], v169 offset:18432
	ds_read_b128 v[208:211], v169 offset:19456
	ds_read_b128 v[212:215], v169 offset:20480
	ds_read_b128 v[216:219], v169 offset:21504
	ds_read_b128 v[220:223], v169 offset:22528
	ds_read_b128 v[224:227], v169 offset:23552
	global_load_lds_dwordx4 v[160:161], off
	s_add_i32 m0, s3, 0x2000
	s_add_u32 s10, s54, 0xb0000
	v_lshl_add_u64 v[202:203], s[54:55], 0, v[142:143]
	s_addc_u32 s11, s55, 0
	s_add_i32 s3, s66, s43
	global_load_lds_dwordx4 v[202:203], off
	v_lshl_add_u64 v[228:229], s[10:11], 0, v[138:139]
	s_mov_b32 m0, s3
	global_load_lds_dwordx4 v[228:229], off
	v_lshl_add_u64 v[228:229], s[10:11], 0, v[142:143]
	s_add_i32 m0, s3, 0x2000
	s_nop 0
	global_load_lds_dwordx4 v[228:229], off
	s_waitcnt vmcnt(6)
	s_waitcnt lgkmcnt(0)
	s_barrier
; #define PG8_STAGE(bufoff, gbase, voff) do { _Pragma("unroll") for (int _i = 0; _i < 2; ++_i) \
;         __builtin_amdgcn_global_load_lds((const unsigned*)((const char*)(gbase) + (voff)[_i]), (PG8_LAS unsigned*)(lds + (bufoff) + ldsw + _i * 8192), 16, 0, 0); } while (0)
; #define PG8_LDA(dst, b, h) do { _Pragma("unroll") for (int m = 0; m < 4; ++m) _Pragma("unroll") for (int k = 0; k < 2; ++k) dst[m][k] = *(const PG8_LAS bf16x8*)(lds + PG8_SA(b, h) + aoff + m * 2048 + k * 1024); } while (0)
; #define PG8_LDB(dst, b, h) do { _Pragma("unroll") for (int n = 0; n < 2; ++n) _Pragma("unroll") for (int k = 0; k < 2; ++k) dst[n][k] = *(const PG8_LAS bf16x8*)(lds + PG8_SB(b, h) + boff + n * 2048 + k * 1024); } while (0)
; #define PG8_MMA(ai, bj, At, Bt) do { __builtin_amdgcn_s_setprio(1); _Pragma("unroll") for (int m = 0; m < 4; ++m) _Pragma("unroll") for (int n = 0; n < 2; ++n) _Pragma("unroll") for (int k = 0; k < 2; ++k) \
;         acc[ai][bj][m][n] = __builtin_amdgcn_mfma_f32_16x16x32_bf16(Bt[n][k], At[m][k], acc[ai][bj][m][n], 0, 0, 0); __builtin_amdgcn_s_setprio(0); } while (0)
; #define PG8_WAIT_V(n) asm volatile("s_waitcnt vmcnt(" #n ")" ::: "memory")
; #define PG8_WAIT_L(n) asm volatile("s_waitcnt lgkmcnt(" #n ")" ::: "memory")
; #define PG8_BAR __builtin_amdgcn_s_barrier()
; #define PG8_SCHED __builtin_amdgcn_sched_barrier(0)
; template <class Epi, class Sched, bool ALIGN_EPI = false, bool SP2 = false>
; __device__ __forceinline__ void gemm_phase(PG8_LAS unsigned char* lds, const Gemm g, const Sched& S, const Epi& E) {
;     ...
;             PG8_LDA(At, 0, 1); PG8_STAGE(PG8_SB(0, 0), b2, voffB); PG8_STAGE(PG8_SB(0, 1), b2 + hstep, voffB); PG8_STAGE(PG8_SA(0, 0), a2, voffA);
;             PG8_WAIT_V(8); PG8_WAIT_L(0); PG8_BAR; PG8_MMA(1, 0, At, B0); PG8_MMA(1, 1, At, B1); PG8_BAR; PG8_SCHED;
;             PG8_LDB(B0, 1, 0); PG8_LDB(B1, 1, 1); PG8_SCHED; PG8_LDA(At, 1, 0); PG8_STAGE(PG8_SA(0, 1), a2 + hstep, voffA);
;             PG8_WAIT_V(8); PG8_WAIT_L(0); PG8_BAR; PG8_MMA(0, 0, At, B0); PG8_MMA(0, 1, At, B1); PG8_BAR; PG8_SCHED;
	s_setprio 1
	s_waitcnt lgkmcnt(0)
	v_mfma_f32_16x16x32_bf16 v[60:63], v[128:131], v[190:193], 0
	v_mfma_f32_16x16x32_bf16 v[44:47], v[128:131], v[198:201], 0
	v_mfma_f32_16x16x32_bf16 v[56:59], v[152:155], v[190:193], 0
	v_mfma_f32_16x16x32_bf16 v[40:43], v[152:155], v[198:201], 0
	v_mfma_f32_16x16x32_bf16 v[28:31], v[128:131], v[212:215], 0
	v_mfma_f32_16x16x32_bf16 v[12:15], v[128:131], v[220:223], 0
	v_mfma_f32_16x16x32_bf16 v[24:27], v[152:155], v[212:215], 0
	v_mfma_f32_16x16x32_bf16 v[8:11], v[152:155], v[220:223], 0
	v_mfma_f32_16x16x32_bf16 v[60:63], v[132:135], v[194:197], v[60:63]
	v_mfma_f32_16x16x32_bf16 v[44:47], v[132:135], v[208:211], v[44:47]
	v_mfma_f32_16x16x32_bf16 v[56:59], v[156:159], v[194:197], v[56:59]
	v_mfma_f32_16x16x32_bf16 v[40:43], v[156:159], v[208:211], v[40:43]
	v_mfma_f32_16x16x32_bf16 v[28:31], v[132:135], v[216:219], v[28:31]
	v_mfma_f32_16x16x32_bf16 v[12:15], v[132:135], v[224:227], v[12:15]
	v_lshl_add_u64 v[228:229], s[56:57], 0, v[136:137]
	s_mov_b32 m0, s58
	s_nop 0
	global_load_lds_dwordx4 v[228:229], off
	v_mfma_f32_16x16x32_bf16 v[24:27], v[156:159], v[216:219], v[24:27]
	v_mfma_f32_16x16x32_bf16 v[8:11], v[156:159], v[224:227], v[8:11]
	s_setprio 0
	s_setprio 1
	v_mfma_f32_16x16x32_bf16 v[52:55], v[172:175], v[190:193], 0
	v_mfma_f32_16x16x32_bf16 v[36:39], v[172:175], v[198:201], 0
	v_mfma_f32_16x16x32_bf16 v[48:51], v[182:185], v[190:193], 0
	v_mfma_f32_16x16x32_bf16 v[32:35], v[182:185], v[198:201], 0
	v_mfma_f32_16x16x32_bf16 v[20:23], v[172:175], v[212:215], 0
	v_mfma_f32_16x16x32_bf16 v[4:7], v[172:175], v[220:223], 0
	v_mfma_f32_16x16x32_bf16 v[16:19], v[182:185], v[212:215], 0
	v_mfma_f32_16x16x32_bf16 v[0:3], v[182:185], v[220:223], 0
	v_mfma_f32_16x16x32_bf16 v[52:55], v[176:179], v[194:197], v[52:55]
	v_mfma_f32_16x16x32_bf16 v[36:39], v[176:179], v[208:211], v[36:39]
	v_mfma_f32_16x16x32_bf16 v[48:51], v[186:189], v[194:197], v[48:51]
	v_mfma_f32_16x16x32_bf16 v[32:35], v[186:189], v[208:211], v[32:35]
	v_mfma_f32_16x16x32_bf16 v[20:23], v[176:179], v[216:219], v[20:23]
	v_mfma_f32_16x16x32_bf16 v[4:7], v[176:179], v[224:227], v[4:7]
	v_lshl_add_u64 v[230:231], s[56:57], 0, v[140:141]
	s_mov_b32 m0, s59
	s_nop 0
	global_load_lds_dwordx4 v[230:231], off
	v_mfma_f32_16x16x32_bf16 v[16:19], v[186:189], v[216:219], v[16:19]
	v_mfma_f32_16x16x32_bf16 v[0:3], v[186:189], v[224:227], v[0:3]
	s_setprio 0
	s_barrier
	s_add_i32 s3, 0, 0x18000
	s_add_i32 s14, 0, 0x1c000
	v_add_u32_e32 v156, s3, v163
	v_add_u32_e32 v171, s14, v163
	ds_read_b128 v[128:131], v156
	ds_read_b128 v[132:135], v156 offset:1024
	ds_read_b128 v[152:155], v156 offset:2048
	ds_read_b128 v[156:159], v156 offset:3072
	ds_read_b128 v[172:175], v171
	ds_read_b128 v[176:179], v171 offset:1024
	ds_read_b128 v[182:185], v171 offset:2048
	ds_read_b128 v[186:189], v171 offset:3072
	s_add_u32 s10, s56, 0xb0000
	s_addc_u32 s11, s57, 0
	s_mov_b32 m0, s60
	v_lshl_add_u64 v[232:233], s[10:11], 0, v[136:137]
	ds_read_b128 v[190:193], v169 offset:32768
	ds_read_b128 v[194:197], v169 offset:33792
	ds_read_b128 v[198:201], v169 offset:34816
	ds_read_b128 v[208:211], v169 offset:35840
	ds_read_b128 v[212:215], v169 offset:36864
	ds_read_b128 v[216:219], v169 offset:37888
	ds_read_b128 v[220:223], v169 offset:38912
	ds_read_b128 v[224:227], v169 offset:39936
	global_load_lds_dwordx4 v[232:233], off
	v_lshl_add_u64 v[232:233], s[10:11], 0, v[140:141]
	s_mov_b32 m0, s61
	s_nop 0
	global_load_lds_dwordx4 v[232:233], off
	s_waitcnt vmcnt(8)
	s_waitcnt lgkmcnt(0)
	s_barrier
	s_setprio 1
	s_waitcnt lgkmcnt(0)
	v_mfma_f32_16x16x32_bf16 v[124:127], v[128:131], v[190:193], v[124:127]
	v_mfma_f32_16x16x32_bf16 v[108:111], v[128:131], v[198:201], v[108:111]
	v_mfma_f32_16x16x32_bf16 v[120:123], v[152:155], v[190:193], v[120:123]
	v_mfma_f32_16x16x32_bf16 v[104:107], v[152:155], v[198:201], v[104:107]
	v_mfma_f32_16x16x32_bf16 v[92:95], v[128:131], v[212:215], v[92:95]
	v_mfma_f32_16x16x32_bf16 v[76:79], v[128:131], v[220:223], v[76:79]
	v_mfma_f32_16x16x32_bf16 v[88:91], v[152:155], v[212:215], v[88:91]
	v_mfma_f32_16x16x32_bf16 v[72:75], v[152:155], v[220:223], v[72:75]
	v_mfma_f32_16x16x32_bf16 v[124:127], v[132:135], v[194:197], v[124:127]
	v_mfma_f32_16x16x32_bf16 v[108:111], v[132:135], v[208:211], v[108:111]
	v_mfma_f32_16x16x32_bf16 v[120:123], v[156:159], v[194:197], v[120:123]
	v_mfma_f32_16x16x32_bf16 v[104:107], v[156:159], v[208:211], v[104:107]
	v_mfma_f32_16x16x32_bf16 v[92:95], v[132:135], v[216:219], v[92:95]
	v_mfma_f32_16x16x32_bf16 v[76:79], v[132:135], v[224:227], v[76:79]
	v_mfma_f32_16x16x32_bf16 v[88:91], v[156:159], v[216:219], v[88:91]
	v_mfma_f32_16x16x32_bf16 v[72:75], v[156:159], v[224:227], v[72:75]
	s_setprio 0
	s_setprio 1
	v_mfma_f32_16x16x32_bf16 v[116:119], v[172:175], v[190:193], v[116:119]
	v_mfma_f32_16x16x32_bf16 v[100:103], v[172:175], v[198:201], v[100:103]
	v_mfma_f32_16x16x32_bf16 v[112:115], v[182:185], v[190:193], v[112:115]
	v_mfma_f32_16x16x32_bf16 v[96:99], v[182:185], v[198:201], v[96:99]
	v_mfma_f32_16x16x32_bf16 v[84:87], v[172:175], v[212:215], v[84:87]
	v_mfma_f32_16x16x32_bf16 v[68:71], v[172:175], v[220:223], v[68:71]
	v_mfma_f32_16x16x32_bf16 v[80:83], v[182:185], v[212:215], v[80:83]
	v_mfma_f32_16x16x32_bf16 v[64:67], v[182:185], v[220:223], v[64:67]
	v_mfma_f32_16x16x32_bf16 v[116:119], v[176:179], v[194:197], v[116:119]
	v_mfma_f32_16x16x32_bf16 v[100:103], v[176:179], v[208:211], v[100:103]
	v_mfma_f32_16x16x32_bf16 v[112:115], v[186:189], v[194:197], v[112:115]
	v_mfma_f32_16x16x32_bf16 v[96:99], v[186:189], v[208:211], v[96:99]
	v_mfma_f32_16x16x32_bf16 v[84:87], v[176:179], v[216:219], v[84:87]
	v_mfma_f32_16x16x32_bf16 v[68:71], v[176:179], v[224:227], v[68:71]
	v_mfma_f32_16x16x32_bf16 v[80:83], v[186:189], v[216:219], v[80:83]
	v_mfma_f32_16x16x32_bf16 v[64:67], v[186:189], v[224:227], v[64:67]
	s_setprio 0
	s_barrier
; #define PG8_STAGE(bufoff, gbase, voff) do { _Pragma("unroll") for (int _i = 0; _i < 2; ++_i) \
;         __builtin_amdgcn_global_load_lds((const unsigned*)((const char*)(gbase) + (voff)[_i]), (PG8_LAS unsigned*)(lds + (bufoff) + ldsw + _i * 8192), 16, 0, 0); } while (0)
; #define PG8_LDA(dst, b, h) do { _Pragma("unroll") for (int m = 0; m < 4; ++m) _Pragma("unroll") for (int k = 0; k < 2; ++k) dst[m][k] = *(const PG8_LAS bf16x8*)(lds + PG8_SA(b, h) + aoff + m * 2048 + k * 1024); } while (0)
; #define PG8_LDB(dst, b, h) do { _Pragma("unroll") for (int n = 0; n < 2; ++n) _Pragma("unroll") for (int k = 0; k < 2; ++k) dst[n][k] = *(const PG8_LAS bf16x8*)(lds + PG8_SB(b, h) + boff + n * 2048 + k * 1024); } while (0)
; #define PG8_MMA(ai, bj, At, Bt) do { __builtin_amdgcn_s_setprio(1); _Pragma("unroll") for (int m = 0; m < 4; ++m) _Pragma("unroll") for (int n = 0; n < 2; ++n) _Pragma("unroll") for (int k = 0; k < 2; ++k) \
;         acc[ai][bj][m][n] = __builtin_amdgcn_mfma_f32_16x16x32_bf16(Bt[n][k], At[m][k], acc[ai][bj][m][n], 0, 0, 0); __builtin_amdgcn_s_setprio(0); } while (0)
; #define PG8_WAIT_V(n) asm volatile("s_waitcnt vmcnt(" #n ")" ::: "memory")
; template <class Epi, class Sched, bool ALIGN_EPI = false, bool SP2 = false>
; __device__ __forceinline__ void gemm_phase(PG8_LAS unsigned char* lds, const Gemm g, const Sched& S, const Epi& E) {
;     ...
;             PG8_LDB(B0, 0, 0); PG8_LDB(B1, 0, 1); PG8_SCHED; PG8_LDA(At, 0, 0); PG8_STAGE(PG8_SA(1, 1), a1 + hstep, voffA);
;             PG8_WAIT_V(8); PG8_WAIT_L(0); PG8_BAR; PG8_MMA(0, 0, At, B0); PG8_MMA(0, 1, At, B1); PG8_BAR; PG8_SCHED;
;             PG8_LDA(At, 0, 1); PG8_STAGE(PG8_SB(0, 0), b2, voffB); PG8_STAGE(PG8_SB(0, 1), b2 + hstep, voffB); PG8_STAGE(PG8_SA(0, 0), a2, voffA);
;             PG8_WAIT_V(8); PG8_WAIT_L(0); PG8_BAR; PG8_MMA(1, 0, At, B0); PG8_MMA(1, 1, At, B1); PG8_BAR; PG8_SCHED;
;             PG8_LDB(B0, 1, 0); PG8_LDB(B1, 1, 1); PG8_SCHED; PG8_LDA(At, 1, 0); PG8_STAGE(PG8_SA(0, 1), a2 + hstep, voffA);
;             PG8_WAIT_V(8); PG8_WAIT_L(0); PG8_BAR; PG8_MMA(0, 0, At, B0); PG8_MMA(0, 1, At, B1); PG8_BAR; PG8_SCHED;
;             PG8_LDA(At, 1, 1); PG8_STAGE(PG8_SB(1, 0), b3, voffB); PG8_STAGE(PG8_SB(1, 1), b3 + hstep, voffB); PG8_STAGE(PG8_SA(1, 0), a3, voffA);
;             PG8_WAIT_V(8); PG8_WAIT_L(0); PG8_BAR; PG8_MMA(1, 0, At, B0); PG8_MMA(1, 1, At, B1); PG8_BAR; PG8_SCHED;
	s_add_i32 s3, s3, s43
	v_lshl_add_u64 v[160:161], v[160:161], 0, s[40:41]
	s_mov_b32 m0, s3
	ds_read_b128 v[190:193], v169 offset:49152
	ds_read_b128 v[194:197], v169 offset:50176
	ds_read_b128 v[198:201], v169 offset:51200
	ds_read_b128 v[208:211], v169 offset:52224
	ds_read_b128 v[212:215], v169 offset:53248
	ds_read_b128 v[216:219], v169 offset:54272
	ds_read_b128 v[220:223], v169 offset:55296
	ds_read_b128 v[224:227], v169 offset:56320
	global_load_lds_dwordx4 v[160:161], off
	s_add_i32 m0, s3, 0x2000
	s_add_u32 s10, s54, 0xb0080
	v_lshl_add_u64 v[160:161], v[202:203], 0, s[40:41]
	s_addc_u32 s11, s55, 0
	s_add_i32 s3, s14, s43
	global_load_lds_dwordx4 v[160:161], off
	v_lshl_add_u64 v[160:161], s[10:11], 0, v[138:139]
	s_mov_b32 m0, s3
	s_nop 0
	global_load_lds_dwordx4 v[160:161], off
	v_lshl_add_u64 v[160:161], s[10:11], 0, v[142:143]
	s_add_i32 m0, s3, 0x2000
	s_nop 0
	global_load_lds_dwordx4 v[160:161], off
	s_waitcnt vmcnt(6)
	s_waitcnt lgkmcnt(0)
	s_barrier
	s_setprio 1
	s_waitcnt lgkmcnt(0)
	v_mfma_f32_16x16x32_bf16 v[60:63], v[128:131], v[190:193], v[60:63]
	v_mfma_f32_16x16x32_bf16 v[44:47], v[128:131], v[198:201], v[44:47]
	v_mfma_f32_16x16x32_bf16 v[56:59], v[152:155], v[190:193], v[56:59]
	v_mfma_f32_16x16x32_bf16 v[40:43], v[152:155], v[198:201], v[40:43]
	v_mfma_f32_16x16x32_bf16 v[28:31], v[128:131], v[212:215], v[28:31]
	v_mfma_f32_16x16x32_bf16 v[12:15], v[128:131], v[220:223], v[12:15]
	v_mfma_f32_16x16x32_bf16 v[24:27], v[152:155], v[212:215], v[24:27]
	v_mfma_f32_16x16x32_bf16 v[8:11], v[152:155], v[220:223], v[8:11]
	v_mfma_f32_16x16x32_bf16 v[60:63], v[132:135], v[194:197], v[60:63]
	v_mfma_f32_16x16x32_bf16 v[44:47], v[132:135], v[208:211], v[44:47]
	v_mfma_f32_16x16x32_bf16 v[56:59], v[156:159], v[194:197], v[56:59]
	v_mfma_f32_16x16x32_bf16 v[40:43], v[156:159], v[208:211], v[40:43]
	v_mfma_f32_16x16x32_bf16 v[28:31], v[132:135], v[216:219], v[28:31]
	v_mfma_f32_16x16x32_bf16 v[12:15], v[132:135], v[224:227], v[12:15]
	v_lshl_add_u64 v[160:161], v[228:229], 0, s[40:41]
	s_mov_b32 m0, s63
	s_nop 0
	global_load_lds_dwordx4 v[160:161], off
	v_mfma_f32_16x16x32_bf16 v[24:27], v[156:159], v[216:219], v[24:27]
	v_mfma_f32_16x16x32_bf16 v[8:11], v[156:159], v[224:227], v[8:11]
	s_setprio 0
	s_setprio 1
	v_mfma_f32_16x16x32_bf16 v[52:55], v[172:175], v[190:193], v[52:55]
	v_mfma_f32_16x16x32_bf16 v[36:39], v[172:175], v[198:201], v[36:39]
	v_mfma_f32_16x16x32_bf16 v[48:51], v[182:185], v[190:193], v[48:51]
	v_mfma_f32_16x16x32_bf16 v[32:35], v[182:185], v[198:201], v[32:35]
	v_mfma_f32_16x16x32_bf16 v[20:23], v[172:175], v[212:215], v[20:23]
	v_mfma_f32_16x16x32_bf16 v[4:7], v[172:175], v[220:223], v[4:7]
	v_mfma_f32_16x16x32_bf16 v[16:19], v[182:185], v[212:215], v[16:19]
	v_mfma_f32_16x16x32_bf16 v[0:3], v[182:185], v[220:223], v[0:3]
	v_mfma_f32_16x16x32_bf16 v[52:55], v[176:179], v[194:197], v[52:55]
	v_mfma_f32_16x16x32_bf16 v[36:39], v[176:179], v[208:211], v[36:39]
	v_mfma_f32_16x16x32_bf16 v[48:51], v[186:189], v[194:197], v[48:51]
	v_mfma_f32_16x16x32_bf16 v[32:35], v[186:189], v[208:211], v[32:35]
	v_mfma_f32_16x16x32_bf16 v[20:23], v[176:179], v[216:219], v[20:23]
	v_mfma_f32_16x16x32_bf16 v[4:7], v[176:179], v[224:227], v[4:7]
	v_lshl_add_u64 v[160:161], v[230:231], 0, s[40:41]
	s_mov_b32 m0, s64
	s_nop 0
	global_load_lds_dwordx4 v[160:161], off
	v_mfma_f32_16x16x32_bf16 v[16:19], v[186:189], v[216:219], v[16:19]
	v_mfma_f32_16x16x32_bf16 v[0:3], v[186:189], v[224:227], v[0:3]
	s_setprio 0
	s_barrier
	s_add_i32 s93, s93, 2
	s_add_u32 s91, s91, 0x100
	s_addc_u32 s92, s92, 0
	s_mov_b64 s[10:11], s[50:51]
.LBB0_269:
	ds_read_b128 v[128:131], v165
	ds_read_b128 v[132:135], v165 offset:1024
	ds_read_b128 v[152:155], v165 offset:2048
	ds_read_b128 v[156:159], v165 offset:3072
	ds_read_b128 v[172:175], v168
	ds_read_b128 v[176:179], v168 offset:1024
	ds_read_b128 v[182:185], v168 offset:2048
	ds_read_b128 v[186:189], v168 offset:3072
	s_add_u32 s50, s10, 0x100
	s_addc_u32 s51, s11, 0
	s_cmp_eq_u32 s93, 40
	s_cselect_b32 s57, s1, s51
	s_cselect_b32 s56, s0, s50
	s_cselect_b32 s55, s49, s92
	s_cselect_b32 s54, s48, s91
	v_lshl_add_u64 v[160:161], s[10:11], 0, v[144:145]
	s_add_i32 m0, s58, 0xc000
	ds_read_b128 v[190:193], v169
	ds_read_b128 v[194:197], v169 offset:1024
	ds_read_b128 v[198:201], v169 offset:2048
	ds_read_b128 v[208:211], v169 offset:3072
	ds_read_b128 v[212:215], v169 offset:4096
	ds_read_b128 v[216:219], v169 offset:5120
	ds_read_b128 v[220:223], v169 offset:6144
	ds_read_b128 v[224:227], v169 offset:7168
	global_load_lds_dwordx4 v[160:161], off
	v_lshl_add_u64 v[160:161], s[10:11], 0, v[146:147]
	s_add_i32 m0, s58, 0xe000
	s_nop 0
	global_load_lds_dwordx4 v[160:161], off
	s_waitcnt vmcnt(8)
	s_waitcnt lgkmcnt(0)
	s_barrier
; #define PG8_STAGE(bufoff, gbase, voff) do { _Pragma("unroll") for (int _i = 0; _i < 2; ++_i) \
;         __builtin_amdgcn_global_load_lds((const unsigned*)((const char*)(gbase) + (voff)[_i]), (PG8_LAS unsigned*)(lds + (bufoff) + ldsw + _i * 8192), 16, 0, 0); } while (0)
; #define PG8_LDA(dst, b, h) do { _Pragma("unroll") for (int m = 0; m < 4; ++m) _Pragma("unroll") for (int k = 0; k < 2; ++k) dst[m][k] = *(const PG8_LAS bf16x8*)(lds + PG8_SA(b, h) + aoff + m * 2048 + k * 1024); } while (0)
; #define PG8_LDB(dst, b, h) do { _Pragma("unroll") for (int n = 0; n < 2; ++n) _Pragma("unroll") for (int k = 0; k < 2; ++k) dst[n][k] = *(const PG8_LAS bf16x8*)(lds + PG8_SB(b, h) + boff + n * 2048 + k * 1024); } while (0)
; #define PG8_MMA(ai, bj, At, Bt) do { __builtin_amdgcn_s_setprio(1); _Pragma("unroll") for (int m = 0; m < 4; ++m) _Pragma("unroll") for (int n = 0; n < 2; ++n) _Pragma("unroll") for (int k = 0; k < 2; ++k) \
;         acc[ai][bj][m][n] = __builtin_amdgcn_mfma_f32_16x16x32_bf16(Bt[n][k], At[m][k], acc[ai][bj][m][n], 0, 0, 0); __builtin_amdgcn_s_setprio(0); } while (0)
; #define PG8_WAIT_V(n) asm volatile("s_waitcnt vmcnt(" #n ")" ::: "memory")
; #define PG8_WAIT_L(n) asm volatile("s_waitcnt lgkmcnt(" #n ")" ::: "memory")
; #define PG8_BAR __builtin_amdgcn_s_barrier()
; #define PG8_SCHED __builtin_amdgcn_sched_barrier(0)
; template <class Epi, class Sched, bool ALIGN_EPI = false, bool SP2 = false>
; __device__ __forceinline__ void gemm_phase(PG8_LAS unsigned char* lds, const Gemm g, const Sched& S, const Epi& E) {
;     ...
;             PG8_LDB(B0, 0, 0); PG8_LDB(B1, 0, 1); PG8_SCHED; PG8_LDA(At, 0, 0); PG8_STAGE(PG8_SA(1, 1), a1 + hstep, voffA);
;             PG8_WAIT_V(8); PG8_WAIT_L(0); PG8_BAR; PG8_MMA(0, 0, At, B0); PG8_MMA(0, 1, At, B1); PG8_BAR; PG8_SCHED;
;             PG8_LDA(At, 0, 1); PG8_STAGE(PG8_SB(0, 0), b2, voffB); PG8_STAGE(PG8_SB(0, 1), b2 + hstep, voffB); PG8_STAGE(PG8_SA(0, 0), a2, voffA);
;             PG8_WAIT_V(8); PG8_WAIT_L(0); PG8_BAR; PG8_MMA(1, 0, At, B0); PG8_MMA(1, 1, At, B1); PG8_BAR; PG8_SCHED;
	s_setprio 1
	s_waitcnt lgkmcnt(0)
	v_mfma_f32_16x16x32_bf16 v[124:127], v[128:131], v[190:193], v[124:127]
	v_mfma_f32_16x16x32_bf16 v[108:111], v[128:131], v[198:201], v[108:111]
	v_mfma_f32_16x16x32_bf16 v[120:123], v[152:155], v[190:193], v[120:123]
	v_mfma_f32_16x16x32_bf16 v[104:107], v[152:155], v[198:201], v[104:107]
	v_mfma_f32_16x16x32_bf16 v[92:95], v[128:131], v[212:215], v[92:95]
	v_mfma_f32_16x16x32_bf16 v[76:79], v[128:131], v[220:223], v[76:79]
	v_mfma_f32_16x16x32_bf16 v[88:91], v[152:155], v[212:215], v[88:91]
	v_mfma_f32_16x16x32_bf16 v[72:75], v[152:155], v[220:223], v[72:75]
	v_mfma_f32_16x16x32_bf16 v[124:127], v[132:135], v[194:197], v[124:127]
	v_mfma_f32_16x16x32_bf16 v[108:111], v[132:135], v[208:211], v[108:111]
	v_mfma_f32_16x16x32_bf16 v[120:123], v[156:159], v[194:197], v[120:123]
	v_mfma_f32_16x16x32_bf16 v[104:107], v[156:159], v[208:211], v[104:107]
	v_mfma_f32_16x16x32_bf16 v[92:95], v[132:135], v[216:219], v[92:95]
	v_mfma_f32_16x16x32_bf16 v[76:79], v[132:135], v[224:227], v[76:79]
	v_mfma_f32_16x16x32_bf16 v[88:91], v[156:159], v[216:219], v[88:91]
	v_mfma_f32_16x16x32_bf16 v[72:75], v[156:159], v[224:227], v[72:75]
	s_setprio 0
	s_setprio 1
	v_mfma_f32_16x16x32_bf16 v[116:119], v[172:175], v[190:193], v[116:119]
	v_mfma_f32_16x16x32_bf16 v[100:103], v[172:175], v[198:201], v[100:103]
	v_mfma_f32_16x16x32_bf16 v[112:115], v[182:185], v[190:193], v[112:115]
	v_mfma_f32_16x16x32_bf16 v[96:99], v[182:185], v[198:201], v[96:99]
	v_mfma_f32_16x16x32_bf16 v[84:87], v[172:175], v[212:215], v[84:87]
	v_mfma_f32_16x16x32_bf16 v[68:71], v[172:175], v[220:223], v[68:71]
	v_mfma_f32_16x16x32_bf16 v[80:83], v[182:185], v[212:215], v[80:83]
	v_mfma_f32_16x16x32_bf16 v[64:67], v[182:185], v[220:223], v[64:67]
	v_mfma_f32_16x16x32_bf16 v[116:119], v[176:179], v[194:197], v[116:119]
	v_mfma_f32_16x16x32_bf16 v[100:103], v[176:179], v[208:211], v[100:103]
	v_mfma_f32_16x16x32_bf16 v[112:115], v[186:189], v[194:197], v[112:115]
	v_mfma_f32_16x16x32_bf16 v[96:99], v[186:189], v[208:211], v[96:99]
	v_mfma_f32_16x16x32_bf16 v[84:87], v[176:179], v[216:219], v[84:87]
	v_mfma_f32_16x16x32_bf16 v[68:71], v[176:179], v[224:227], v[68:71]
	v_mfma_f32_16x16x32_bf16 v[80:83], v[186:189], v[216:219], v[80:83]
	v_mfma_f32_16x16x32_bf16 v[64:67], v[186:189], v[224:227], v[64:67]
	s_setprio 0
	s_barrier
	s_add_i32 s3, s65, s43
	v_lshl_add_u64 v[160:161], s[54:55], 0, v[138:139]
	s_mov_b32 m0, s3
	ds_read_b128 v[190:193], v169 offset:16384
	ds_read_b128 v[194:197], v169 offset:17408
	ds_read_b128 v[198:201], v169 offset:18432
	ds_read_b128 v[208:211], v169 offset:19456
	ds_read_b128 v[212:215], v169 offset:20480
	ds_read_b128 v[216:219], v169 offset:21504
	ds_read_b128 v[220:223], v169 offset:22528
	ds_read_b128 v[224:227], v169 offset:23552
	global_load_lds_dwordx4 v[160:161], off
	s_add_i32 m0, s3, 0x2000
	s_add_u32 s10, s54, 0xb0000
	v_lshl_add_u64 v[202:203], s[54:55], 0, v[142:143]
	s_addc_u32 s11, s55, 0
	s_add_i32 s3, s66, s43
	global_load_lds_dwordx4 v[202:203], off
	v_lshl_add_u64 v[228:229], s[10:11], 0, v[138:139]
	s_mov_b32 m0, s3
	global_load_lds_dwordx4 v[228:229], off
	v_lshl_add_u64 v[228:229], s[10:11], 0, v[142:143]
	s_add_i32 m0, s3, 0x2000
	s_nop 0
	global_load_lds_dwordx4 v[228:229], off
	s_waitcnt vmcnt(6)
	s_waitcnt lgkmcnt(0)
	s_barrier
	s_setprio 1
	s_waitcnt lgkmcnt(0)
	v_mfma_f32_16x16x32_bf16 v[60:63], v[128:131], v[190:193], v[60:63]
	v_mfma_f32_16x16x32_bf16 v[44:47], v[128:131], v[198:201], v[44:47]
	v_mfma_f32_16x16x32_bf16 v[56:59], v[152:155], v[190:193], v[56:59]
	v_mfma_f32_16x16x32_bf16 v[40:43], v[152:155], v[198:201], v[40:43]
	v_mfma_f32_16x16x32_bf16 v[28:31], v[128:131], v[212:215], v[28:31]
	v_mfma_f32_16x16x32_bf16 v[12:15], v[128:131], v[220:223], v[12:15]
	v_mfma_f32_16x16x32_bf16 v[24:27], v[152:155], v[212:215], v[24:27]
	v_mfma_f32_16x16x32_bf16 v[8:11], v[152:155], v[220:223], v[8:11]
	v_mfma_f32_16x16x32_bf16 v[60:63], v[132:135], v[194:197], v[60:63]
	v_mfma_f32_16x16x32_bf16 v[44:47], v[132:135], v[208:211], v[44:47]
	v_mfma_f32_16x16x32_bf16 v[56:59], v[156:159], v[194:197], v[56:59]
	v_mfma_f32_16x16x32_bf16 v[40:43], v[156:159], v[208:211], v[40:43]
	v_mfma_f32_16x16x32_bf16 v[28:31], v[132:135], v[216:219], v[28:31]
	v_mfma_f32_16x16x32_bf16 v[12:15], v[132:135], v[224:227], v[12:15]
	v_lshl_add_u64 v[228:229], s[56:57], 0, v[136:137]
	s_mov_b32 m0, s58
	s_nop 0
	global_load_lds_dwordx4 v[228:229], off
	v_mfma_f32_16x16x32_bf16 v[24:27], v[156:159], v[216:219], v[24:27]
	v_mfma_f32_16x16x32_bf16 v[8:11], v[156:159], v[224:227], v[8:11]
	s_setprio 0
	s_setprio 1
	v_mfma_f32_16x16x32_bf16 v[52:55], v[172:175], v[190:193], v[52:55]
	v_mfma_f32_16x16x32_bf16 v[36:39], v[172:175], v[198:201], v[36:39]
	v_mfma_f32_16x16x32_bf16 v[48:51], v[182:185], v[190:193], v[48:51]
	v_mfma_f32_16x16x32_bf16 v[32:35], v[182:185], v[198:201], v[32:35]
	v_mfma_f32_16x16x32_bf16 v[20:23], v[172:175], v[212:215], v[20:23]
	v_mfma_f32_16x16x32_bf16 v[4:7], v[172:175], v[220:223], v[4:7]
	v_mfma_f32_16x16x32_bf16 v[16:19], v[182:185], v[212:215], v[16:19]
	v_mfma_f32_16x16x32_bf16 v[0:3], v[182:185], v[220:223], v[0:3]
	v_mfma_f32_16x16x32_bf16 v[52:55], v[176:179], v[194:197], v[52:55]
	v_mfma_f32_16x16x32_bf16 v[36:39], v[176:179], v[208:211], v[36:39]
	v_mfma_f32_16x16x32_bf16 v[48:51], v[186:189], v[194:197], v[48:51]
	v_mfma_f32_16x16x32_bf16 v[32:35], v[186:189], v[208:211], v[32:35]
	v_mfma_f32_16x16x32_bf16 v[20:23], v[176:179], v[216:219], v[20:23]
	v_mfma_f32_16x16x32_bf16 v[4:7], v[176:179], v[224:227], v[4:7]
	v_lshl_add_u64 v[230:231], s[56:57], 0, v[140:141]
	s_mov_b32 m0, s59
	s_nop 0
	global_load_lds_dwordx4 v[230:231], off
	v_mfma_f32_16x16x32_bf16 v[16:19], v[186:189], v[216:219], v[16:19]
	v_mfma_f32_16x16x32_bf16 v[0:3], v[186:189], v[224:227], v[0:3]
	s_setprio 0
	s_barrier
; #define PG8_STAGE(bufoff, gbase, voff) do { _Pragma("unroll") for (int _i = 0; _i < 2; ++_i) \
;         __builtin_amdgcn_global_load_lds((const unsigned*)((const char*)(gbase) + (voff)[_i]), (PG8_LAS unsigned*)(lds + (bufoff) + ldsw + _i * 8192), 16, 0, 0); } while (0)
; #define PG8_LDA(dst, b, h) do { _Pragma("unroll") for (int m = 0; m < 4; ++m) _Pragma("unroll") for (int k = 0; k < 2; ++k) dst[m][k] = *(const PG8_LAS bf16x8*)(lds + PG8_SA(b, h) + aoff + m * 2048 + k * 1024); } while (0)
; #define PG8_LDB(dst, b, h) do { _Pragma("unroll") for (int n = 0; n < 2; ++n) _Pragma("unroll") for (int k = 0; k < 2; ++k) dst[n][k] = *(const PG8_LAS bf16x8*)(lds + PG8_SB(b, h) + boff + n * 2048 + k * 1024); } while (0)
; #define PG8_MMA(ai, bj, At, Bt) do { __builtin_amdgcn_s_setprio(1); _Pragma("unroll") for (int m = 0; m < 4; ++m) _Pragma("unroll") for (int n = 0; n < 2; ++n) _Pragma("unroll") for (int k = 0; k < 2; ++k) \
;         acc[ai][bj][m][n] = __builtin_amdgcn_mfma_f32_16x16x32_bf16(Bt[n][k], At[m][k], acc[ai][bj][m][n], 0, 0, 0); __builtin_amdgcn_s_setprio(0); } while (0)
; #define PG8_WAIT_V(n) asm volatile("s_waitcnt vmcnt(" #n ")" ::: "memory")
; #define PG8_WAIT_L(n) asm volatile("s_waitcnt lgkmcnt(" #n ")" ::: "memory")
; #define PG8_BAR __builtin_amdgcn_s_barrier()
; #define PG8_SCHED __builtin_amdgcn_sched_barrier(0)
; template <class Epi, class Sched, bool ALIGN_EPI = false, bool SP2 = false>
; __device__ __forceinline__ void gemm_phase(PG8_LAS unsigned char* lds, const Gemm g, const Sched& S, const Epi& E) {
;     ...
;             PG8_LDB(B0, 1, 0); PG8_LDB(B1, 1, 1); PG8_SCHED; PG8_LDA(At, 1, 0); PG8_STAGE(PG8_SA(0, 1), a2 + hstep, voffA);
;             PG8_WAIT_V(8); PG8_WAIT_L(0); PG8_BAR; PG8_MMA(0, 0, At, B0); PG8_MMA(0, 1, At, B1); PG8_BAR; PG8_SCHED;
	s_add_i32 s3, 0, 0x18000
	s_add_i32 s14, 0, 0x1c000
	v_add_u32_e32 v156, s3, v163
	v_add_u32_e32 v171, s14, v163
	ds_read_b128 v[128:131], v156
	ds_read_b128 v[132:135], v156 offset:1024
	ds_read_b128 v[152:155], v156 offset:2048
	ds_read_b128 v[156:159], v156 offset:3072
	ds_read_b128 v[172:175], v171
	ds_read_b128 v[176:179], v171 offset:1024
	ds_read_b128 v[182:185], v171 offset:2048
	ds_read_b128 v[186:189], v171 offset:3072
	s_add_u32 s10, s56, 0xb0000
	s_addc_u32 s11, s57, 0
	s_mov_b32 m0, s60
	v_lshl_add_u64 v[232:233], s[10:11], 0, v[136:137]
	ds_read_b128 v[190:193], v169 offset:32768
	ds_read_b128 v[194:197], v169 offset:33792
	ds_read_b128 v[198:201], v169 offset:34816
	ds_read_b128 v[208:211], v169 offset:35840
	ds_read_b128 v[212:215], v169 offset:36864
	ds_read_b128 v[216:219], v169 offset:37888
	ds_read_b128 v[220:223], v169 offset:38912
	ds_read_b128 v[224:227], v169 offset:39936
	global_load_lds_dwordx4 v[232:233], off
	v_lshl_add_u64 v[232:233], s[10:11], 0, v[140:141]
	s_mov_b32 m0, s61
	s_nop 0
	global_load_lds_dwordx4 v[232:233], off
	s_waitcnt vmcnt(8)
	s_waitcnt lgkmcnt(0)
	s_barrier
	s_setprio 1
	s_waitcnt lgkmcnt(0)
	v_mfma_f32_16x16x32_bf16 v[124:127], v[128:131], v[190:193], v[124:127]
	v_mfma_f32_16x16x32_bf16 v[108:111], v[128:131], v[198:201], v[108:111]
	v_mfma_f32_16x16x32_bf16 v[120:123], v[152:155], v[190:193], v[120:123]
	v_mfma_f32_16x16x32_bf16 v[104:107], v[152:155], v[198:201], v[104:107]
	v_mfma_f32_16x16x32_bf16 v[92:95], v[128:131], v[212:215], v[92:95]
	v_mfma_f32_16x16x32_bf16 v[76:79], v[128:131], v[220:223], v[76:79]
	v_mfma_f32_16x16x32_bf16 v[88:91], v[152:155], v[212:215], v[88:91]
	v_mfma_f32_16x16x32_bf16 v[72:75], v[152:155], v[220:223], v[72:75]
	v_mfma_f32_16x16x32_bf16 v[124:127], v[132:135], v[194:197], v[124:127]
	v_mfma_f32_16x16x32_bf16 v[108:111], v[132:135], v[208:211], v[108:111]
	v_mfma_f32_16x16x32_bf16 v[120:123], v[156:159], v[194:197], v[120:123]
	v_mfma_f32_16x16x32_bf16 v[104:107], v[156:159], v[208:211], v[104:107]
	v_mfma_f32_16x16x32_bf16 v[92:95], v[132:135], v[216:219], v[92:95]
	v_mfma_f32_16x16x32_bf16 v[76:79], v[132:135], v[224:227], v[76:79]
	v_mfma_f32_16x16x32_bf16 v[88:91], v[156:159], v[216:219], v[88:91]
	v_mfma_f32_16x16x32_bf16 v[72:75], v[156:159], v[224:227], v[72:75]
	s_setprio 0
	s_setprio 1
	v_mfma_f32_16x16x32_bf16 v[116:119], v[172:175], v[190:193], v[116:119]
	v_mfma_f32_16x16x32_bf16 v[100:103], v[172:175], v[198:201], v[100:103]
	v_mfma_f32_16x16x32_bf16 v[112:115], v[182:185], v[190:193], v[112:115]
	v_mfma_f32_16x16x32_bf16 v[96:99], v[182:185], v[198:201], v[96:99]
	v_mfma_f32_16x16x32_bf16 v[84:87], v[172:175], v[212:215], v[84:87]
	v_mfma_f32_16x16x32_bf16 v[68:71], v[172:175], v[220:223], v[68:71]
	v_mfma_f32_16x16x32_bf16 v[80:83], v[182:185], v[212:215], v[80:83]
	v_mfma_f32_16x16x32_bf16 v[64:67], v[182:185], v[220:223], v[64:67]
	v_mfma_f32_16x16x32_bf16 v[116:119], v[176:179], v[194:197], v[116:119]
	v_mfma_f32_16x16x32_bf16 v[100:103], v[176:179], v[208:211], v[100:103]
	v_mfma_f32_16x16x32_bf16 v[112:115], v[186:189], v[194:197], v[112:115]
	v_mfma_f32_16x16x32_bf16 v[96:99], v[186:189], v[208:211], v[96:99]
	v_mfma_f32_16x16x32_bf16 v[84:87], v[176:179], v[216:219], v[84:87]
	v_mfma_f32_16x16x32_bf16 v[68:71], v[176:179], v[224:227], v[68:71]
	v_mfma_f32_16x16x32_bf16 v[80:83], v[186:189], v[216:219], v[80:83]
	v_mfma_f32_16x16x32_bf16 v[64:67], v[186:189], v[224:227], v[64:67]
	s_setprio 0
	s_barrier
; #define PG8_STAGE(bufoff, gbase, voff) do { _Pragma("unroll") for (int _i = 0; _i < 2; ++_i) \
;         __builtin_amdgcn_global_load_lds((const unsigned*)((const char*)(gbase) + (voff)[_i]), (PG8_LAS unsigned*)(lds + (bufoff) + ldsw + _i * 8192), 16, 0, 0); } while (0)
; #define PG8_LDA(dst, b, h) do { _Pragma("unroll") for (int m = 0; m < 4; ++m) _Pragma("unroll") for (int k = 0; k < 2; ++k) dst[m][k] = *(const PG8_LAS bf16x8*)(lds + PG8_SA(b, h) + aoff + m * 2048 + k * 1024); } while (0)
; #define PG8_MMA(ai, bj, At, Bt) do { __builtin_amdgcn_s_setprio(1); _Pragma("unroll") for (int m = 0; m < 4; ++m) _Pragma("unroll") for (int n = 0; n < 2; ++n) _Pragma("unroll") for (int k = 0; k < 2; ++k) \
;         acc[ai][bj][m][n] = __builtin_amdgcn_mfma_f32_16x16x32_bf16(Bt[n][k], At[m][k], acc[ai][bj][m][n], 0, 0, 0); __builtin_amdgcn_s_setprio(0); } while (0)
; #define PG8_WAIT_V(n) asm volatile("s_waitcnt vmcnt(" #n ")" ::: "memory")
; #define PG8_WAIT_L(n) asm volatile("s_waitcnt lgkmcnt(" #n ")" ::: "memory")
; #define PG8_BAR __builtin_amdgcn_s_barrier()
; #define PG8_SCHED __builtin_amdgcn_sched_barrier(0)
; template <class Epi, class Sched, bool ALIGN_EPI = false, bool SP2 = false>
; __device__ __forceinline__ void gemm_phase(PG8_LAS unsigned char* lds, const Gemm g, const Sched& S, const Epi& E) {
;     ...
;             PG8_LDA(At, 1, 1); PG8_STAGE(PG8_SB(1, 0), b3, voffB); PG8_STAGE(PG8_SB(1, 1), b3 + hstep, voffB); PG8_STAGE(PG8_SA(1, 0), a3, voffA);
;             PG8_WAIT_V(8); PG8_WAIT_L(0); PG8_BAR; PG8_MMA(1, 0, At, B0); PG8_MMA(1, 1, At, B1); PG8_BAR; PG8_SCHED;
;     ...
;         if constexpr (ALIGN_EPI) { if (wr == 0) PG8_BAR; }
	s_add_i32 s3, s3, s43
	v_lshl_add_u64 v[160:161], v[160:161], 0, s[40:41]
	s_mov_b32 m0, s3
	ds_read_b128 v[190:193], v169 offset:49152
	ds_read_b128 v[194:197], v169 offset:50176
	ds_read_b128 v[198:201], v169 offset:51200
	ds_read_b128 v[208:211], v169 offset:52224
	ds_read_b128 v[212:215], v169 offset:53248
	ds_read_b128 v[216:219], v169 offset:54272
	ds_read_b128 v[220:223], v169 offset:55296
	ds_read_b128 v[224:227], v169 offset:56320
	global_load_lds_dwordx4 v[160:161], off
	s_add_i32 m0, s3, 0x2000
	s_add_u32 s10, s54, 0xb0080
	v_lshl_add_u64 v[160:161], v[202:203], 0, s[40:41]
	s_addc_u32 s11, s55, 0
	s_add_i32 s3, s14, s43
	global_load_lds_dwordx4 v[160:161], off
	v_lshl_add_u64 v[160:161], s[10:11], 0, v[138:139]
	s_mov_b32 m0, s3
	s_nop 0
	global_load_lds_dwordx4 v[160:161], off
	v_lshl_add_u64 v[160:161], s[10:11], 0, v[142:143]
	s_add_i32 m0, s3, 0x2000
	s_nop 0
	global_load_lds_dwordx4 v[160:161], off
	s_waitcnt vmcnt(6)
	s_waitcnt lgkmcnt(0)
	s_barrier
	s_setprio 1
	s_waitcnt lgkmcnt(0)
	v_mfma_f32_16x16x32_bf16 v[60:63], v[128:131], v[190:193], v[60:63]
	v_mfma_f32_16x16x32_bf16 v[44:47], v[128:131], v[198:201], v[44:47]
	v_mfma_f32_16x16x32_bf16 v[56:59], v[152:155], v[190:193], v[56:59]
	v_mfma_f32_16x16x32_bf16 v[40:43], v[152:155], v[198:201], v[40:43]
	v_mfma_f32_16x16x32_bf16 v[28:31], v[128:131], v[212:215], v[28:31]
	v_mfma_f32_16x16x32_bf16 v[12:15], v[128:131], v[220:223], v[12:15]
	v_mfma_f32_16x16x32_bf16 v[24:27], v[152:155], v[212:215], v[24:27]
	v_mfma_f32_16x16x32_bf16 v[8:11], v[152:155], v[220:223], v[8:11]
	v_mfma_f32_16x16x32_bf16 v[60:63], v[132:135], v[194:197], v[60:63]
	v_mfma_f32_16x16x32_bf16 v[44:47], v[132:135], v[208:211], v[44:47]
	v_mfma_f32_16x16x32_bf16 v[56:59], v[156:159], v[194:197], v[56:59]
	v_mfma_f32_16x16x32_bf16 v[40:43], v[156:159], v[208:211], v[40:43]
	v_mfma_f32_16x16x32_bf16 v[28:31], v[132:135], v[216:219], v[28:31]
	v_mfma_f32_16x16x32_bf16 v[12:15], v[132:135], v[224:227], v[12:15]
	v_lshl_add_u64 v[160:161], v[228:229], 0, s[40:41]
	s_mov_b32 m0, s63
	s_nop 0
	global_load_lds_dwordx4 v[160:161], off
	v_mfma_f32_16x16x32_bf16 v[24:27], v[156:159], v[216:219], v[24:27]
	v_mfma_f32_16x16x32_bf16 v[8:11], v[156:159], v[224:227], v[8:11]
	s_setprio 0
	s_setprio 1
	v_mfma_f32_16x16x32_bf16 v[52:55], v[172:175], v[190:193], v[52:55]
	v_mfma_f32_16x16x32_bf16 v[36:39], v[172:175], v[198:201], v[36:39]
	v_mfma_f32_16x16x32_bf16 v[48:51], v[182:185], v[190:193], v[48:51]
	v_mfma_f32_16x16x32_bf16 v[32:35], v[182:185], v[198:201], v[32:35]
	v_mfma_f32_16x16x32_bf16 v[20:23], v[172:175], v[212:215], v[20:23]
	v_mfma_f32_16x16x32_bf16 v[4:7], v[172:175], v[220:223], v[4:7]
	v_mfma_f32_16x16x32_bf16 v[16:19], v[182:185], v[212:215], v[16:19]
	v_mfma_f32_16x16x32_bf16 v[0:3], v[182:185], v[220:223], v[0:3]
	v_mfma_f32_16x16x32_bf16 v[52:55], v[176:179], v[194:197], v[52:55]
	v_mfma_f32_16x16x32_bf16 v[36:39], v[176:179], v[208:211], v[36:39]
	v_mfma_f32_16x16x32_bf16 v[48:51], v[186:189], v[194:197], v[48:51]
	v_mfma_f32_16x16x32_bf16 v[32:35], v[186:189], v[208:211], v[32:35]
	v_mfma_f32_16x16x32_bf16 v[20:23], v[176:179], v[216:219], v[20:23]
	v_mfma_f32_16x16x32_bf16 v[4:7], v[176:179], v[224:227], v[4:7]
	v_lshl_add_u64 v[160:161], v[230:231], 0, s[40:41]
	s_mov_b32 m0, s64
	s_nop 0
	global_load_lds_dwordx4 v[160:161], off
	v_mfma_f32_16x16x32_bf16 v[16:19], v[186:189], v[216:219], v[16:19]
	v_mfma_f32_16x16x32_bf16 v[0:3], v[186:189], v[224:227], v[0:3]
	s_setprio 0
	s_barrier
	s_add_i32 s93, s93, 2
	s_add_u32 s91, s91, 0x100
	s_addc_u32 s92, s92, 0
	s_cmp_gt_u32 s93, 41
	s_mov_b64 s[10:11], s[50:51]
	s_cbranch_scc0 .LBB0_269
	s_and_b64 vcc, exec, s[44:45]
	s_cbranch_vccz .LBB0_272
	s_barrier

; #define PG8_STAGE(bufoff, gbase, voff) do { _Pragma("unroll") for (int _i = 0; _i < 2; ++_i) \
;         __builtin_amdgcn_global_load_lds((const unsigned*)((const char*)(gbase) + (voff)[_i]), (PG8_LAS unsigned*)(lds + (bufoff) + ldsw + _i * 8192), 16, 0, 0); } while (0)
; #define PG8_LDA(dst, b, h) do { _Pragma("unroll") for (int m = 0; m < 4; ++m) _Pragma("unroll") for (int k = 0; k < 2; ++k) dst[m][k] = *(const PG8_LAS bf16x8*)(lds + PG8_SA(b, h) + aoff + m * 2048 + k * 1024); } while (0)
; #define PG8_LDB(dst, b, h) do { _Pragma("unroll") for (int n = 0; n < 2; ++n) _Pragma("unroll") for (int k = 0; k < 2; ++k) dst[n][k] = *(const PG8_LAS bf16x8*)(lds + PG8_SB(b, h) + boff + n * 2048 + k * 1024); } while (0)
; #define PG8_MMA(ai, bj, At, Bt) do { __builtin_amdgcn_s_setprio(1); _Pragma("unroll") for (int m = 0; m < 4; ++m) _Pragma("unroll") for (int n = 0; n < 2; ++n) _Pragma("unroll") for (int k = 0; k < 2; ++k) \
;         acc[ai][bj][m][n] = __builtin_amdgcn_mfma_f32_16x16x32_bf16(Bt[n][k], At[m][k], acc[ai][bj][m][n], 0, 0, 0); __builtin_amdgcn_s_setprio(0); } while (0)
; #define PG8_BAR __builtin_amdgcn_s_barrier()
; template <class Epi, class Sched, bool ALIGN_EPI = false, bool SP2 = false>
; __device__ __forceinline__ void gemm_phase(PG8_LAS unsigned char* lds, const Gemm g, const Sched& S, const Epi& E) {
;     ...
;         const bool has_next = S.next(ui + 1, nxt);
;         const char* nA = has_next ? (const char*)g.A + (size_t)nxt.pm * tstep : cA; const char* nB = has_next ? (const char*)g.Bt + (size_t)nxt.pn * tstep : cB;
;         for (int t = 0; t < nt; t += 2) {
;             const bool last = (t == nt - 2);
;             const char* a1 = cA + (size_t)(t + 1) * kstep;
;             const char* a2 = last ? nA : cA + (size_t)(t + 2) * kstep; const char* b2 = last ? nB : cB + (size_t)(t + 2) * kstep;
;             const char* a3 = a2 + kstep; const char* b3 = b2 + kstep;
;             if (last && has_next) S.a_ready(nxt);
;             if constexpr (SP2) {
;             PG8_LDB(B0, 0, 0); PG8_LDB(B1, 0, 1); PG8_SCHED; PG8_LDA(At, 0, 0); PG8_STAGE(PG8_SA(1, 1), a1 + hstep, voffA);
;             PG8_WAIT_V(8); PG8_WAIT_L(0); PG8_BAR; PG8_MMA(0, 0, At, B0); PG8_MMA(0, 1, At, B1); PG8_BAR; PG8_SCHED;
;             PG8_LDA(At, 0, 1); PG8_STAGE(PG8_SB(0, 0), b2, voffB); PG8_STAGE(PG8_SB(0, 1), b2 + hstep, voffB); PG8_STAGE(PG8_SA(0, 0), a2, voffA);
.LBB0_416:
	s_ashr_i32 s45, s44, 31
	s_lshl_b64 s[14:15], s[44:45], 19
	s_add_u32 s48, s22, s14
	s_addc_u32 s49, s23, s15
	s_and_b64 s[14:15], s[6:7], exec
	s_cselect_b32 s45, s49, s55
	s_cselect_b32 s89, s48, s54
	s_ashr_i32 s41, s40, 31
	s_lshl_b64 s[14:15], s[40:41], 19
	s_add_u32 s50, s84, s14
	s_addc_u32 s51, s85, s15
	s_and_b64 s[14:15], s[6:7], exec
	s_cselect_b32 s41, s51, s57
	s_cselect_b32 s90, s50, s56
	s_add_u32 s54, s54, 0x40080
	s_addc_u32 s55, s55, 0
	s_add_u32 s91, s56, 0x100
	s_addc_u32 s92, s57, 0
	s_mov_b32 s93, -2
	ds_read_b128 v[154:157], v169
	ds_read_b128 v[158:161], v169 offset:1024
	ds_read_b128 v[162:165], v169 offset:2048
	ds_read_b128 v[174:177], v169 offset:3072
	ds_read_b128 v[182:185], v170
	ds_read_b128 v[186:189], v170 offset:1024
	ds_read_b128 v[190:193], v170 offset:2048
	ds_read_b128 v[194:197], v170 offset:3072
	s_add_u32 s3, s54, 0xfffc0080
	s_addc_u32 s14, s55, -1
	s_cmp_eq_u32 s93, 12
	s_cselect_b32 s59, s45, s14
	s_cselect_b32 s58, s89, s3
	s_cselect_b32 s57, s41, s92
	s_cselect_b32 s56, s90, s91
	v_lshl_add_u64 v[178:179], s[54:55], 0, v[146:147]
	s_add_i32 m0, s60, 0xc000
	ds_read_b128 v[198:201], v171
	ds_read_b128 v[208:211], v171 offset:1024
	ds_read_b128 v[212:215], v171 offset:2048
	ds_read_b128 v[216:219], v171 offset:3072
	ds_read_b128 v[220:223], v171 offset:4096
	ds_read_b128 v[224:227], v171 offset:5120
	ds_read_b128 v[228:231], v171 offset:6144
	ds_read_b128 v[232:235], v171 offset:7168
	global_load_lds_dwordx4 v[178:179], off
	v_lshl_add_u64 v[178:179], s[54:55], 0, v[148:149]
	s_add_i32 m0, s60, 0xe000
	s_nop 0
	global_load_lds_dwordx4 v[178:179], off
	s_waitcnt vmcnt(8)
	s_waitcnt lgkmcnt(0)
	s_barrier
	s_setprio 1
	s_waitcnt lgkmcnt(0)
	v_mfma_f32_16x16x32_bf16 v[124:127], v[154:157], v[198:201], 0
	v_mfma_f32_16x16x32_bf16 v[116:119], v[154:157], v[212:215], 0
	v_mfma_f32_16x16x32_bf16 v[120:123], v[162:165], v[198:201], 0
	v_mfma_f32_16x16x32_bf16 v[112:115], v[162:165], v[212:215], 0
	v_mfma_f32_16x16x32_bf16 v[108:111], v[154:157], v[220:223], 0
	v_mfma_f32_16x16x32_bf16 v[100:103], v[154:157], v[228:231], 0
	v_mfma_f32_16x16x32_bf16 v[104:107], v[162:165], v[220:223], 0
	v_mfma_f32_16x16x32_bf16 v[96:99], v[162:165], v[228:231], 0
	v_mfma_f32_16x16x32_bf16 v[124:127], v[158:161], v[208:211], v[124:127]
	v_mfma_f32_16x16x32_bf16 v[116:119], v[158:161], v[216:219], v[116:119]
	v_mfma_f32_16x16x32_bf16 v[120:123], v[174:177], v[208:211], v[120:123]
	v_mfma_f32_16x16x32_bf16 v[112:115], v[174:177], v[216:219], v[112:115]
	v_mfma_f32_16x16x32_bf16 v[108:111], v[158:161], v[224:227], v[108:111]
	v_mfma_f32_16x16x32_bf16 v[100:103], v[158:161], v[232:235], v[100:103]
	v_mfma_f32_16x16x32_bf16 v[104:107], v[174:177], v[224:227], v[104:107]
	v_mfma_f32_16x16x32_bf16 v[96:99], v[174:177], v[232:235], v[96:99]
	s_setprio 0
	s_setprio 1
	v_mfma_f32_16x16x32_bf16 v[68:71], v[182:185], v[198:201], 0
	v_mfma_f32_16x16x32_bf16 v[52:55], v[182:185], v[212:215], 0
	v_mfma_f32_16x16x32_bf16 v[64:67], v[190:193], v[198:201], 0
	v_mfma_f32_16x16x32_bf16 v[48:51], v[190:193], v[212:215], 0
	v_mfma_f32_16x16x32_bf16 v[44:47], v[182:185], v[220:223], 0
	v_mfma_f32_16x16x32_bf16 v[36:39], v[182:185], v[228:231], 0
	v_mfma_f32_16x16x32_bf16 v[40:43], v[190:193], v[220:223], 0
	v_mfma_f32_16x16x32_bf16 v[32:35], v[190:193], v[228:231], 0
	v_mfma_f32_16x16x32_bf16 v[68:71], v[186:189], v[208:211], v[68:71]
	v_mfma_f32_16x16x32_bf16 v[52:55], v[186:189], v[216:219], v[52:55]
	v_mfma_f32_16x16x32_bf16 v[64:67], v[194:197], v[208:211], v[64:67]
	v_mfma_f32_16x16x32_bf16 v[48:51], v[194:197], v[216:219], v[48:51]
	v_mfma_f32_16x16x32_bf16 v[44:47], v[186:189], v[224:227], v[44:47]
	v_mfma_f32_16x16x32_bf16 v[36:39], v[186:189], v[232:235], v[36:39]
	v_mfma_f32_16x16x32_bf16 v[40:43], v[194:197], v[224:227], v[40:43]
	v_mfma_f32_16x16x32_bf16 v[32:35], v[194:197], v[232:235], v[32:35]
	s_setprio 0
	s_barrier
	s_add_i32 s3, s86, s34
	v_lshl_add_u64 v[178:179], s[56:57], 0, v[132:133]
	s_mov_b32 m0, s3
	ds_read_b128 v[198:201], v171 offset:16384
	ds_read_b128 v[208:211], v171 offset:17408
	ds_read_b128 v[212:215], v171 offset:18432
	ds_read_b128 v[216:219], v171 offset:19456
	ds_read_b128 v[220:223], v171 offset:20480
	ds_read_b128 v[224:227], v171 offset:21504
	ds_read_b128 v[228:231], v171 offset:22528
	ds_read_b128 v[232:235], v171 offset:23552
	global_load_lds_dwordx4 v[178:179], off
	s_add_i32 m0, s3, 0x2000
	s_add_u32 s14, s56, 0x40000
	v_lshl_add_u64 v[202:203], s[56:57], 0, v[128:129]
	s_addc_u32 s15, s57, 0
	s_add_i32 s3, s87, s34
	global_load_lds_dwordx4 v[202:203], off
	v_lshl_add_u64 v[236:237], s[14:15], 0, v[132:133]
	s_mov_b32 m0, s3
	global_load_lds_dwordx4 v[236:237], off
	v_lshl_add_u64 v[236:237], s[14:15], 0, v[128:129]
	s_add_i32 m0, s3, 0x2000
	s_nop 0
	global_load_lds_dwordx4 v[236:237], off
	s_waitcnt vmcnt(6)
	s_waitcnt lgkmcnt(0)
	s_barrier
; #define PG8_STAGE(bufoff, gbase, voff) do { _Pragma("unroll") for (int _i = 0; _i < 2; ++_i) \
;         __builtin_amdgcn_global_load_lds((const unsigned*)((const char*)(gbase) + (voff)[_i]), (PG8_LAS unsigned*)(lds + (bufoff) + ldsw + _i * 8192), 16, 0, 0); } while (0)
; #define PG8_LDA(dst, b, h) do { _Pragma("unroll") for (int m = 0; m < 4; ++m) _Pragma("unroll") for (int k = 0; k < 2; ++k) dst[m][k] = *(const PG8_LAS bf16x8*)(lds + PG8_SA(b, h) + aoff + m * 2048 + k * 1024); } while (0)
; #define PG8_LDB(dst, b, h) do { _Pragma("unroll") for (int n = 0; n < 2; ++n) _Pragma("unroll") for (int k = 0; k < 2; ++k) dst[n][k] = *(const PG8_LAS bf16x8*)(lds + PG8_SB(b, h) + boff + n * 2048 + k * 1024); } while (0)
; #define PG8_MMA(ai, bj, At, Bt) do { __builtin_amdgcn_s_setprio(1); _Pragma("unroll") for (int m = 0; m < 4; ++m) _Pragma("unroll") for (int n = 0; n < 2; ++n) _Pragma("unroll") for (int k = 0; k < 2; ++k) \
;         acc[ai][bj][m][n] = __builtin_amdgcn_mfma_f32_16x16x32_bf16(Bt[n][k], At[m][k], acc[ai][bj][m][n], 0, 0, 0); __builtin_amdgcn_s_setprio(0); } while (0)
; #define PG8_WAIT_V(n) asm volatile("s_waitcnt vmcnt(" #n ")" ::: "memory")
; #define PG8_WAIT_L(n) asm volatile("s_waitcnt lgkmcnt(" #n ")" ::: "memory")
; #define PG8_BAR __builtin_amdgcn_s_barrier()
; #define PG8_SCHED __builtin_amdgcn_sched_barrier(0)
; template <class Epi, class Sched, bool ALIGN_EPI = false, bool SP2 = false>
; __device__ __forceinline__ void gemm_phase(PG8_LAS unsigned char* lds, const Gemm g, const Sched& S, const Epi& E) {
;     ...
;             PG8_LDA(At, 0, 1); PG8_STAGE(PG8_SB(0, 0), b2, voffB); PG8_STAGE(PG8_SB(0, 1), b2 + hstep, voffB); PG8_STAGE(PG8_SA(0, 0), a2, voffA);
;             PG8_WAIT_V(8); PG8_WAIT_L(0); PG8_BAR; PG8_MMA(1, 0, At, B0); PG8_MMA(1, 1, At, B1); PG8_BAR; PG8_SCHED;
;             PG8_LDB(B0, 1, 0); PG8_LDB(B1, 1, 1); PG8_SCHED; PG8_LDA(At, 1, 0); PG8_STAGE(PG8_SA(0, 1), a2 + hstep, voffA);
;             PG8_WAIT_V(8); PG8_WAIT_L(0); PG8_BAR; PG8_MMA(0, 0, At, B0); PG8_MMA(0, 1, At, B1); PG8_BAR; PG8_SCHED;
	s_setprio 1
	s_waitcnt lgkmcnt(0)
	v_mfma_f32_16x16x32_bf16 v[92:95], v[154:157], v[198:201], 0
	v_mfma_f32_16x16x32_bf16 v[84:87], v[154:157], v[212:215], 0
	v_mfma_f32_16x16x32_bf16 v[88:91], v[162:165], v[198:201], 0
	v_mfma_f32_16x16x32_bf16 v[80:83], v[162:165], v[212:215], 0
	v_mfma_f32_16x16x32_bf16 v[76:79], v[154:157], v[220:223], 0
	v_mfma_f32_16x16x32_bf16 v[60:63], v[154:157], v[228:231], 0
	v_mfma_f32_16x16x32_bf16 v[72:75], v[162:165], v[220:223], 0
	v_mfma_f32_16x16x32_bf16 v[56:59], v[162:165], v[228:231], 0
	v_mfma_f32_16x16x32_bf16 v[92:95], v[158:161], v[208:211], v[92:95]
	v_mfma_f32_16x16x32_bf16 v[84:87], v[158:161], v[216:219], v[84:87]
	v_mfma_f32_16x16x32_bf16 v[88:91], v[174:177], v[208:211], v[88:91]
	v_mfma_f32_16x16x32_bf16 v[80:83], v[174:177], v[216:219], v[80:83]
	v_mfma_f32_16x16x32_bf16 v[76:79], v[158:161], v[224:227], v[76:79]
	v_mfma_f32_16x16x32_bf16 v[60:63], v[158:161], v[232:235], v[60:63]
	v_lshl_add_u64 v[236:237], s[58:59], 0, v[134:135]
	s_mov_b32 m0, s60
	s_nop 0
	global_load_lds_dwordx4 v[236:237], off
	v_mfma_f32_16x16x32_bf16 v[72:75], v[174:177], v[224:227], v[72:75]
	v_mfma_f32_16x16x32_bf16 v[56:59], v[174:177], v[232:235], v[56:59]
	s_setprio 0
	s_setprio 1
	v_mfma_f32_16x16x32_bf16 v[28:31], v[182:185], v[198:201], 0
	v_mfma_f32_16x16x32_bf16 v[20:23], v[182:185], v[212:215], 0
	v_mfma_f32_16x16x32_bf16 v[24:27], v[190:193], v[198:201], 0
	v_mfma_f32_16x16x32_bf16 v[16:19], v[190:193], v[212:215], 0
	v_mfma_f32_16x16x32_bf16 v[12:15], v[182:185], v[220:223], 0
	v_mfma_f32_16x16x32_bf16 v[4:7], v[182:185], v[228:231], 0
	v_mfma_f32_16x16x32_bf16 v[8:11], v[190:193], v[220:223], 0
	v_mfma_f32_16x16x32_bf16 v[0:3], v[190:193], v[228:231], 0
	v_mfma_f32_16x16x32_bf16 v[28:31], v[186:189], v[208:211], v[28:31]
	v_mfma_f32_16x16x32_bf16 v[20:23], v[186:189], v[216:219], v[20:23]
	v_mfma_f32_16x16x32_bf16 v[24:27], v[194:197], v[208:211], v[24:27]
	v_mfma_f32_16x16x32_bf16 v[16:19], v[194:197], v[216:219], v[16:19]
	v_mfma_f32_16x16x32_bf16 v[12:15], v[186:189], v[224:227], v[12:15]
	v_mfma_f32_16x16x32_bf16 v[4:7], v[186:189], v[232:235], v[4:7]
	v_lshl_add_u64 v[238:239], s[58:59], 0, v[130:131]
	s_mov_b32 m0, s61
	s_nop 0
	global_load_lds_dwordx4 v[238:239], off
	v_mfma_f32_16x16x32_bf16 v[8:11], v[194:197], v[224:227], v[8:11]
	v_mfma_f32_16x16x32_bf16 v[0:3], v[194:197], v[232:235], v[0:3]
	s_setprio 0
	s_barrier
	s_add_i32 s3, 0, 0x18000
	v_add_u32_e32 v136, s3, v143
	s_add_i32 s33, 0, 0x1c000
	ds_read_b128 v[154:157], v136
	ds_read_b128 v[158:161], v136 offset:1024
	ds_read_b128 v[162:165], v136 offset:2048
	ds_read_b128 v[174:177], v136 offset:3072
	v_add_u32_e32 v136, s33, v143
	ds_read_b128 v[182:185], v136
	ds_read_b128 v[186:189], v136 offset:1024
	ds_read_b128 v[190:193], v136 offset:2048
	ds_read_b128 v[194:197], v136 offset:3072
	s_add_u32 s14, s58, 0x40000
	s_addc_u32 s15, s59, 0
	s_mov_b32 m0, s62
	v_lshl_add_u64 v[240:241], s[14:15], 0, v[134:135]
	ds_read_b128 v[198:201], v171 offset:32768
	ds_read_b128 v[208:211], v171 offset:33792
	ds_read_b128 v[212:215], v171 offset:34816
	ds_read_b128 v[216:219], v171 offset:35840
	ds_read_b128 v[220:223], v171 offset:36864
	ds_read_b128 v[224:227], v171 offset:37888
	ds_read_b128 v[228:231], v171 offset:38912
	ds_read_b128 v[232:235], v171 offset:39936
	global_load_lds_dwordx4 v[240:241], off
	v_lshl_add_u64 v[240:241], s[14:15], 0, v[130:131]
	s_mov_b32 m0, s63
	s_nop 0
	global_load_lds_dwordx4 v[240:241], off
	s_waitcnt vmcnt(8)
	s_waitcnt lgkmcnt(0)
	s_barrier
	s_setprio 1
	s_waitcnt lgkmcnt(0)
	v_mfma_f32_16x16x32_bf16 v[124:127], v[154:157], v[198:201], v[124:127]
	v_mfma_f32_16x16x32_bf16 v[116:119], v[154:157], v[212:215], v[116:119]
	v_mfma_f32_16x16x32_bf16 v[120:123], v[162:165], v[198:201], v[120:123]
	v_mfma_f32_16x16x32_bf16 v[112:115], v[162:165], v[212:215], v[112:115]
	v_mfma_f32_16x16x32_bf16 v[108:111], v[154:157], v[220:223], v[108:111]
	v_mfma_f32_16x16x32_bf16 v[100:103], v[154:157], v[228:231], v[100:103]
	v_mfma_f32_16x16x32_bf16 v[104:107], v[162:165], v[220:223], v[104:107]
	v_mfma_f32_16x16x32_bf16 v[96:99], v[162:165], v[228:231], v[96:99]
	v_mfma_f32_16x16x32_bf16 v[124:127], v[158:161], v[208:211], v[124:127]
	v_mfma_f32_16x16x32_bf16 v[116:119], v[158:161], v[216:219], v[116:119]
	v_mfma_f32_16x16x32_bf16 v[120:123], v[174:177], v[208:211], v[120:123]
	v_mfma_f32_16x16x32_bf16 v[112:115], v[174:177], v[216:219], v[112:115]
	v_mfma_f32_16x16x32_bf16 v[108:111], v[158:161], v[224:227], v[108:111]
	v_mfma_f32_16x16x32_bf16 v[100:103], v[158:161], v[232:235], v[100:103]
	v_mfma_f32_16x16x32_bf16 v[104:107], v[174:177], v[224:227], v[104:107]
	v_mfma_f32_16x16x32_bf16 v[96:99], v[174:177], v[232:235], v[96:99]
	s_setprio 0
	s_setprio 1
	v_mfma_f32_16x16x32_bf16 v[68:71], v[182:185], v[198:201], v[68:71]
	v_mfma_f32_16x16x32_bf16 v[52:55], v[182:185], v[212:215], v[52:55]
	v_mfma_f32_16x16x32_bf16 v[64:67], v[190:193], v[198:201], v[64:67]
	v_mfma_f32_16x16x32_bf16 v[48:51], v[190:193], v[212:215], v[48:51]
	v_mfma_f32_16x16x32_bf16 v[44:47], v[182:185], v[220:223], v[44:47]
	v_mfma_f32_16x16x32_bf16 v[36:39], v[182:185], v[228:231], v[36:39]
	v_mfma_f32_16x16x32_bf16 v[40:43], v[190:193], v[220:223], v[40:43]
	v_mfma_f32_16x16x32_bf16 v[32:35], v[190:193], v[228:231], v[32:35]
	v_mfma_f32_16x16x32_bf16 v[68:71], v[186:189], v[208:211], v[68:71]
	v_mfma_f32_16x16x32_bf16 v[52:55], v[186:189], v[216:219], v[52:55]
	v_mfma_f32_16x16x32_bf16 v[64:67], v[194:197], v[208:211], v[64:67]
	v_mfma_f32_16x16x32_bf16 v[48:51], v[194:197], v[216:219], v[48:51]
	v_mfma_f32_16x16x32_bf16 v[44:47], v[186:189], v[224:227], v[44:47]
	v_mfma_f32_16x16x32_bf16 v[36:39], v[186:189], v[232:235], v[36:39]
	v_mfma_f32_16x16x32_bf16 v[40:43], v[194:197], v[224:227], v[40:43]
	v_mfma_f32_16x16x32_bf16 v[32:35], v[194:197], v[232:235], v[32:35]
	s_setprio 0
	s_barrier
; #define PG8_STAGE(bufoff, gbase, voff) do { _Pragma("unroll") for (int _i = 0; _i < 2; ++_i) \
;         __builtin_amdgcn_global_load_lds((const unsigned*)((const char*)(gbase) + (voff)[_i]), (PG8_LAS unsigned*)(lds + (bufoff) + ldsw + _i * 8192), 16, 0, 0); } while (0)
; #define PG8_LDA(dst, b, h) do { _Pragma("unroll") for (int m = 0; m < 4; ++m) _Pragma("unroll") for (int k = 0; k < 2; ++k) dst[m][k] = *(const PG8_LAS bf16x8*)(lds + PG8_SA(b, h) + aoff + m * 2048 + k * 1024); } while (0)
; #define PG8_LDB(dst, b, h) do { _Pragma("unroll") for (int n = 0; n < 2; ++n) _Pragma("unroll") for (int k = 0; k < 2; ++k) dst[n][k] = *(const PG8_LAS bf16x8*)(lds + PG8_SB(b, h) + boff + n * 2048 + k * 1024); } while (0)
; #define PG8_MMA(ai, bj, At, Bt) do { __builtin_amdgcn_s_setprio(1); _Pragma("unroll") for (int m = 0; m < 4; ++m) _Pragma("unroll") for (int n = 0; n < 2; ++n) _Pragma("unroll") for (int k = 0; k < 2; ++k) \
;         acc[ai][bj][m][n] = __builtin_amdgcn_mfma_f32_16x16x32_bf16(Bt[n][k], At[m][k], acc[ai][bj][m][n], 0, 0, 0); __builtin_amdgcn_s_setprio(0); } while (0)
; #define PG8_WAIT_V(n) asm volatile("s_waitcnt vmcnt(" #n ")" ::: "memory")
; template <class Epi, class Sched, bool ALIGN_EPI = false, bool SP2 = false>
; __device__ __forceinline__ void gemm_phase(PG8_LAS unsigned char* lds, const Gemm g, const Sched& S, const Epi& E) {
;     ...
;             PG8_LDB(B0, 0, 0); PG8_LDB(B1, 0, 1); PG8_SCHED; PG8_LDA(At, 0, 0); PG8_STAGE(PG8_SA(1, 1), a1 + hstep, voffA);
;             PG8_WAIT_V(8); PG8_WAIT_L(0); PG8_BAR; PG8_MMA(0, 0, At, B0); PG8_MMA(0, 1, At, B1); PG8_BAR; PG8_SCHED;
;             PG8_LDA(At, 0, 1); PG8_STAGE(PG8_SB(0, 0), b2, voffB); PG8_STAGE(PG8_SB(0, 1), b2 + hstep, voffB); PG8_STAGE(PG8_SA(0, 0), a2, voffA);
;             PG8_WAIT_V(8); PG8_WAIT_L(0); PG8_BAR; PG8_MMA(1, 0, At, B0); PG8_MMA(1, 1, At, B1); PG8_BAR; PG8_SCHED;
;             PG8_LDB(B0, 1, 0); PG8_LDB(B1, 1, 1); PG8_SCHED; PG8_LDA(At, 1, 0); PG8_STAGE(PG8_SA(0, 1), a2 + hstep, voffA);
;             PG8_WAIT_V(8); PG8_WAIT_L(0); PG8_BAR; PG8_MMA(0, 0, At, B0); PG8_MMA(0, 1, At, B1); PG8_BAR; PG8_SCHED;
;             PG8_LDA(At, 1, 1); PG8_STAGE(PG8_SB(1, 0), b3, voffB); PG8_STAGE(PG8_SB(1, 1), b3 + hstep, voffB); PG8_STAGE(PG8_SA(1, 0), a3, voffA);
;             PG8_WAIT_V(8); PG8_WAIT_L(0); PG8_BAR; PG8_MMA(1, 0, At, B0); PG8_MMA(1, 1, At, B1); PG8_BAR; PG8_SCHED;
	s_add_i32 s3, s3, s34
	v_lshl_add_u64 v[178:179], v[178:179], 0, s[8:9]
	s_mov_b32 m0, s3
	ds_read_b128 v[198:201], v171 offset:49152
	ds_read_b128 v[208:211], v171 offset:50176
	ds_read_b128 v[212:215], v171 offset:51200
	ds_read_b128 v[216:219], v171 offset:52224
	ds_read_b128 v[220:223], v171 offset:53248
	ds_read_b128 v[224:227], v171 offset:54272
	ds_read_b128 v[228:231], v171 offset:55296
	ds_read_b128 v[232:235], v171 offset:56320
	global_load_lds_dwordx4 v[178:179], off
	s_add_i32 m0, s3, 0x2000
	s_add_u32 s14, s56, 0x40080
	v_lshl_add_u64 v[178:179], v[202:203], 0, s[8:9]
	s_addc_u32 s15, s57, 0
	s_add_i32 s3, s33, s34
	global_load_lds_dwordx4 v[178:179], off
	v_lshl_add_u64 v[178:179], s[14:15], 0, v[132:133]
	s_mov_b32 m0, s3
	s_nop 0
	global_load_lds_dwordx4 v[178:179], off
	v_lshl_add_u64 v[178:179], s[14:15], 0, v[128:129]
	s_add_i32 m0, s3, 0x2000
	s_nop 0
	global_load_lds_dwordx4 v[178:179], off
	s_waitcnt vmcnt(6)
	s_waitcnt lgkmcnt(0)
	s_barrier
	s_setprio 1
	s_waitcnt lgkmcnt(0)
	v_mfma_f32_16x16x32_bf16 v[92:95], v[154:157], v[198:201], v[92:95]
	v_mfma_f32_16x16x32_bf16 v[84:87], v[154:157], v[212:215], v[84:87]
	v_mfma_f32_16x16x32_bf16 v[88:91], v[162:165], v[198:201], v[88:91]
	v_mfma_f32_16x16x32_bf16 v[80:83], v[162:165], v[212:215], v[80:83]
	v_mfma_f32_16x16x32_bf16 v[76:79], v[154:157], v[220:223], v[76:79]
	v_mfma_f32_16x16x32_bf16 v[60:63], v[154:157], v[228:231], v[60:63]
	v_mfma_f32_16x16x32_bf16 v[72:75], v[162:165], v[220:223], v[72:75]
	v_mfma_f32_16x16x32_bf16 v[56:59], v[162:165], v[228:231], v[56:59]
	v_mfma_f32_16x16x32_bf16 v[92:95], v[158:161], v[208:211], v[92:95]
	v_mfma_f32_16x16x32_bf16 v[84:87], v[158:161], v[216:219], v[84:87]
	v_mfma_f32_16x16x32_bf16 v[88:91], v[174:177], v[208:211], v[88:91]
	v_mfma_f32_16x16x32_bf16 v[80:83], v[174:177], v[216:219], v[80:83]
	v_mfma_f32_16x16x32_bf16 v[76:79], v[158:161], v[224:227], v[76:79]
	v_mfma_f32_16x16x32_bf16 v[60:63], v[158:161], v[232:235], v[60:63]
	v_lshl_add_u64 v[178:179], v[236:237], 0, s[8:9]
	s_mov_b32 m0, s66
	s_nop 0
	global_load_lds_dwordx4 v[178:179], off
	v_mfma_f32_16x16x32_bf16 v[72:75], v[174:177], v[224:227], v[72:75]
	v_mfma_f32_16x16x32_bf16 v[56:59], v[174:177], v[232:235], v[56:59]
	s_setprio 0
	s_setprio 1
	v_mfma_f32_16x16x32_bf16 v[28:31], v[182:185], v[198:201], v[28:31]
	v_mfma_f32_16x16x32_bf16 v[20:23], v[182:185], v[212:215], v[20:23]
	v_mfma_f32_16x16x32_bf16 v[24:27], v[190:193], v[198:201], v[24:27]
	v_mfma_f32_16x16x32_bf16 v[16:19], v[190:193], v[212:215], v[16:19]
	v_mfma_f32_16x16x32_bf16 v[12:15], v[182:185], v[220:223], v[12:15]
	v_mfma_f32_16x16x32_bf16 v[4:7], v[182:185], v[228:231], v[4:7]
	v_mfma_f32_16x16x32_bf16 v[8:11], v[190:193], v[220:223], v[8:11]
	v_mfma_f32_16x16x32_bf16 v[0:3], v[190:193], v[228:231], v[0:3]
	v_mfma_f32_16x16x32_bf16 v[28:31], v[186:189], v[208:211], v[28:31]
	v_mfma_f32_16x16x32_bf16 v[20:23], v[186:189], v[216:219], v[20:23]
	v_mfma_f32_16x16x32_bf16 v[24:27], v[194:197], v[208:211], v[24:27]
	v_mfma_f32_16x16x32_bf16 v[16:19], v[194:197], v[216:219], v[16:19]
	v_mfma_f32_16x16x32_bf16 v[12:15], v[186:189], v[224:227], v[12:15]
	v_mfma_f32_16x16x32_bf16 v[4:7], v[186:189], v[232:235], v[4:7]
	v_lshl_add_u64 v[178:179], v[238:239], 0, s[8:9]
	s_mov_b32 m0, s67
	s_nop 0
	global_load_lds_dwordx4 v[178:179], off
	v_mfma_f32_16x16x32_bf16 v[8:11], v[194:197], v[224:227], v[8:11]
	v_mfma_f32_16x16x32_bf16 v[0:3], v[194:197], v[232:235], v[0:3]
	s_setprio 0
	s_barrier
	s_add_i32 s93, s93, 2
	s_add_u32 s54, s54, 0x100
	s_addc_u32 s55, s55, 0
	s_add_u32 s91, s91, 0x100
	s_addc_u32 s92, s92, 0
.LBB0_417:
	ds_read_b128 v[154:157], v169
	ds_read_b128 v[158:161], v169 offset:1024
	ds_read_b128 v[162:165], v169 offset:2048
	ds_read_b128 v[174:177], v169 offset:3072
	ds_read_b128 v[182:185], v170
	ds_read_b128 v[186:189], v170 offset:1024
	ds_read_b128 v[190:193], v170 offset:2048
	ds_read_b128 v[194:197], v170 offset:3072
	s_add_u32 s3, s54, 0xfffc0080
	s_addc_u32 s14, s55, -1
	s_cmp_eq_u32 s93, 12
	s_cselect_b32 s59, s45, s14
	s_cselect_b32 s58, s89, s3
	s_cselect_b32 s57, s41, s92
	s_cselect_b32 s56, s90, s91
	v_lshl_add_u64 v[178:179], s[54:55], 0, v[146:147]
	s_add_i32 m0, s60, 0xc000
	ds_read_b128 v[198:201], v171
	ds_read_b128 v[208:211], v171 offset:1024
	ds_read_b128 v[212:215], v171 offset:2048
	ds_read_b128 v[216:219], v171 offset:3072
	ds_read_b128 v[220:223], v171 offset:4096
	ds_read_b128 v[224:227], v171 offset:5120
	ds_read_b128 v[228:231], v171 offset:6144
	ds_read_b128 v[232:235], v171 offset:7168
	global_load_lds_dwordx4 v[178:179], off
	v_lshl_add_u64 v[178:179], s[54:55], 0, v[148:149]
	s_add_i32 m0, s60, 0xe000
	s_nop 0
	global_load_lds_dwordx4 v[178:179], off
	s_waitcnt vmcnt(8)
	s_waitcnt lgkmcnt(0)
	s_barrier
; #define PG8_STAGE(bufoff, gbase, voff) do { _Pragma("unroll") for (int _i = 0; _i < 2; ++_i) \
;         __builtin_amdgcn_global_load_lds((const unsigned*)((const char*)(gbase) + (voff)[_i]), (PG8_LAS unsigned*)(lds + (bufoff) + ldsw + _i * 8192), 16, 0, 0); } while (0)
; #define PG8_LDA(dst, b, h) do { _Pragma("unroll") for (int m = 0; m < 4; ++m) _Pragma("unroll") for (int k = 0; k < 2; ++k) dst[m][k] = *(const PG8_LAS bf16x8*)(lds + PG8_SA(b, h) + aoff + m * 2048 + k * 1024); } while (0)
; #define PG8_LDB(dst, b, h) do { _Pragma("unroll") for (int n = 0; n < 2; ++n) _Pragma("unroll") for (int k = 0; k < 2; ++k) dst[n][k] = *(const PG8_LAS bf16x8*)(lds + PG8_SB(b, h) + boff + n * 2048 + k * 1024); } while (0)
; #define PG8_MMA(ai, bj, At, Bt) do { __builtin_amdgcn_s_setprio(1); _Pragma("unroll") for (int m = 0; m < 4; ++m) _Pragma("unroll") for (int n = 0; n < 2; ++n) _Pragma("unroll") for (int k = 0; k < 2; ++k) \
;         acc[ai][bj][m][n] = __builtin_amdgcn_mfma_f32_16x16x32_bf16(Bt[n][k], At[m][k], acc[ai][bj][m][n], 0, 0, 0); __builtin_amdgcn_s_setprio(0); } while (0)
; #define PG8_WAIT_V(n) asm volatile("s_waitcnt vmcnt(" #n ")" ::: "memory")
; #define PG8_WAIT_L(n) asm volatile("s_waitcnt lgkmcnt(" #n ")" ::: "memory")
; #define PG8_BAR __builtin_amdgcn_s_barrier()
; #define PG8_SCHED __builtin_amdgcn_sched_barrier(0)
; template <class Epi, class Sched, bool ALIGN_EPI = false, bool SP2 = false>
; __device__ __forceinline__ void gemm_phase(PG8_LAS unsigned char* lds, const Gemm g, const Sched& S, const Epi& E) {
;     ...
;             PG8_LDB(B0, 0, 0); PG8_LDB(B1, 0, 1); PG8_SCHED; PG8_LDA(At, 0, 0); PG8_STAGE(PG8_SA(1, 1), a1 + hstep, voffA);
;             PG8_WAIT_V(8); PG8_WAIT_L(0); PG8_BAR; PG8_MMA(0, 0, At, B0); PG8_MMA(0, 1, At, B1); PG8_BAR; PG8_SCHED;
;             PG8_LDA(At, 0, 1); PG8_STAGE(PG8_SB(0, 0), b2, voffB); PG8_STAGE(PG8_SB(0, 1), b2 + hstep, voffB); PG8_STAGE(PG8_SA(0, 0), a2, voffA);
;             PG8_WAIT_V(8); PG8_WAIT_L(0); PG8_BAR; PG8_MMA(1, 0, At, B0); PG8_MMA(1, 1, At, B1); PG8_BAR; PG8_SCHED;
	s_setprio 1
	s_waitcnt lgkmcnt(0)
	v_mfma_f32_16x16x32_bf16 v[124:127], v[154:157], v[198:201], v[124:127]
	v_mfma_f32_16x16x32_bf16 v[116:119], v[154:157], v[212:215], v[116:119]
	v_mfma_f32_16x16x32_bf16 v[120:123], v[162:165], v[198:201], v[120:123]
	v_mfma_f32_16x16x32_bf16 v[112:115], v[162:165], v[212:215], v[112:115]
	v_mfma_f32_16x16x32_bf16 v[108:111], v[154:157], v[220:223], v[108:111]
	v_mfma_f32_16x16x32_bf16 v[100:103], v[154:157], v[228:231], v[100:103]
	v_mfma_f32_16x16x32_bf16 v[104:107], v[162:165], v[220:223], v[104:107]
	v_mfma_f32_16x16x32_bf16 v[96:99], v[162:165], v[228:231], v[96:99]
	v_mfma_f32_16x16x32_bf16 v[124:127], v[158:161], v[208:211], v[124:127]
	v_mfma_f32_16x16x32_bf16 v[116:119], v[158:161], v[216:219], v[116:119]
	v_mfma_f32_16x16x32_bf16 v[120:123], v[174:177], v[208:211], v[120:123]
	v_mfma_f32_16x16x32_bf16 v[112:115], v[174:177], v[216:219], v[112:115]
	v_mfma_f32_16x16x32_bf16 v[108:111], v[158:161], v[224:227], v[108:111]
	v_mfma_f32_16x16x32_bf16 v[100:103], v[158:161], v[232:235], v[100:103]
	v_mfma_f32_16x16x32_bf16 v[104:107], v[174:177], v[224:227], v[104:107]
	v_mfma_f32_16x16x32_bf16 v[96:99], v[174:177], v[232:235], v[96:99]
	s_setprio 0
	s_setprio 1
	v_mfma_f32_16x16x32_bf16 v[68:71], v[182:185], v[198:201], v[68:71]
	v_mfma_f32_16x16x32_bf16 v[52:55], v[182:185], v[212:215], v[52:55]
	v_mfma_f32_16x16x32_bf16 v[64:67], v[190:193], v[198:201], v[64:67]
	v_mfma_f32_16x16x32_bf16 v[48:51], v[190:193], v[212:215], v[48:51]
	v_mfma_f32_16x16x32_bf16 v[44:47], v[182:185], v[220:223], v[44:47]
	v_mfma_f32_16x16x32_bf16 v[36:39], v[182:185], v[228:231], v[36:39]
	v_mfma_f32_16x16x32_bf16 v[40:43], v[190:193], v[220:223], v[40:43]
	v_mfma_f32_16x16x32_bf16 v[32:35], v[190:193], v[228:231], v[32:35]
	v_mfma_f32_16x16x32_bf16 v[68:71], v[186:189], v[208:211], v[68:71]
	v_mfma_f32_16x16x32_bf16 v[52:55], v[186:189], v[216:219], v[52:55]
	v_mfma_f32_16x16x32_bf16 v[64:67], v[194:197], v[208:211], v[64:67]
	v_mfma_f32_16x16x32_bf16 v[48:51], v[194:197], v[216:219], v[48:51]
	v_mfma_f32_16x16x32_bf16 v[44:47], v[186:189], v[224:227], v[44:47]
	v_mfma_f32_16x16x32_bf16 v[36:39], v[186:189], v[232:235], v[36:39]
	v_mfma_f32_16x16x32_bf16 v[40:43], v[194:197], v[224:227], v[40:43]
	v_mfma_f32_16x16x32_bf16 v[32:35], v[194:197], v[232:235], v[32:35]
	s_setprio 0
	s_barrier
	s_add_i32 s3, s86, s34
	v_lshl_add_u64 v[178:179], s[56:57], 0, v[132:133]
	s_mov_b32 m0, s3
	ds_read_b128 v[198:201], v171 offset:16384
	ds_read_b128 v[208:211], v171 offset:17408
	ds_read_b128 v[212:215], v171 offset:18432
	ds_read_b128 v[216:219], v171 offset:19456
	ds_read_b128 v[220:223], v171 offset:20480
	ds_read_b128 v[224:227], v171 offset:21504
	ds_read_b128 v[228:231], v171 offset:22528
	ds_read_b128 v[232:235], v171 offset:23552
	global_load_lds_dwordx4 v[178:179], off
	s_add_i32 m0, s3, 0x2000
	s_add_u32 s14, s56, 0x40000
	v_lshl_add_u64 v[202:203], s[56:57], 0, v[128:129]
	s_addc_u32 s15, s57, 0
	s_add_i32 s3, s87, s34
	global_load_lds_dwordx4 v[202:203], off
	v_lshl_add_u64 v[236:237], s[14:15], 0, v[132:133]
	s_mov_b32 m0, s3
	global_load_lds_dwordx4 v[236:237], off
	v_lshl_add_u64 v[236:237], s[14:15], 0, v[128:129]
	s_add_i32 m0, s3, 0x2000
	s_nop 0
	global_load_lds_dwordx4 v[236:237], off
	s_waitcnt vmcnt(6)
	s_waitcnt lgkmcnt(0)
	s_barrier
	s_setprio 1
	s_waitcnt lgkmcnt(0)
	v_mfma_f32_16x16x32_bf16 v[92:95], v[154:157], v[198:201], v[92:95]
	v_mfma_f32_16x16x32_bf16 v[84:87], v[154:157], v[212:215], v[84:87]
	v_mfma_f32_16x16x32_bf16 v[88:91], v[162:165], v[198:201], v[88:91]
	v_mfma_f32_16x16x32_bf16 v[80:83], v[162:165], v[212:215], v[80:83]
	v_mfma_f32_16x16x32_bf16 v[76:79], v[154:157], v[220:223], v[76:79]
	v_mfma_f32_16x16x32_bf16 v[60:63], v[154:157], v[228:231], v[60:63]
	v_mfma_f32_16x16x32_bf16 v[72:75], v[162:165], v[220:223], v[72:75]
	v_mfma_f32_16x16x32_bf16 v[56:59], v[162:165], v[228:231], v[56:59]
	v_mfma_f32_16x16x32_bf16 v[92:95], v[158:161], v[208:211], v[92:95]
	v_mfma_f32_16x16x32_bf16 v[84:87], v[158:161], v[216:219], v[84:87]
	v_mfma_f32_16x16x32_bf16 v[88:91], v[174:177], v[208:211], v[88:91]
	v_mfma_f32_16x16x32_bf16 v[80:83], v[174:177], v[216:219], v[80:83]
	v_mfma_f32_16x16x32_bf16 v[76:79], v[158:161], v[224:227], v[76:79]
	v_mfma_f32_16x16x32_bf16 v[60:63], v[158:161], v[232:235], v[60:63]
	v_lshl_add_u64 v[236:237], s[58:59], 0, v[134:135]
	s_mov_b32 m0, s60
	s_nop 0
	global_load_lds_dwordx4 v[236:237], off
	v_mfma_f32_16x16x32_bf16 v[72:75], v[174:177], v[224:227], v[72:75]
	v_mfma_f32_16x16x32_bf16 v[56:59], v[174:177], v[232:235], v[56:59]
	s_setprio 0
	s_setprio 1
	v_mfma_f32_16x16x32_bf16 v[28:31], v[182:185], v[198:201], v[28:31]
	v_mfma_f32_16x16x32_bf16 v[20:23], v[182:185], v[212:215], v[20:23]
	v_mfma_f32_16x16x32_bf16 v[24:27], v[190:193], v[198:201], v[24:27]
	v_mfma_f32_16x16x32_bf16 v[16:19], v[190:193], v[212:215], v[16:19]
	v_mfma_f32_16x16x32_bf16 v[12:15], v[182:185], v[220:223], v[12:15]
	v_mfma_f32_16x16x32_bf16 v[4:7], v[182:185], v[228:231], v[4:7]
	v_mfma_f32_16x16x32_bf16 v[8:11], v[190:193], v[220:223], v[8:11]
	v_mfma_f32_16x16x32_bf16 v[0:3], v[190:193], v[228:231], v[0:3]
	v_mfma_f32_16x16x32_bf16 v[28:31], v[186:189], v[208:211], v[28:31]
	v_mfma_f32_16x16x32_bf16 v[20:23], v[186:189], v[216:219], v[20:23]
	v_mfma_f32_16x16x32_bf16 v[24:27], v[194:197], v[208:211], v[24:27]
	v_mfma_f32_16x16x32_bf16 v[16:19], v[194:197], v[216:219], v[16:19]
	v_mfma_f32_16x16x32_bf16 v[12:15], v[186:189], v[224:227], v[12:15]
	v_mfma_f32_16x16x32_bf16 v[4:7], v[186:189], v[232:235], v[4:7]
	v_lshl_add_u64 v[238:239], s[58:59], 0, v[130:131]
	s_mov_b32 m0, s61
	s_nop 0
	global_load_lds_dwordx4 v[238:239], off
	v_mfma_f32_16x16x32_bf16 v[8:11], v[194:197], v[224:227], v[8:11]
	v_mfma_f32_16x16x32_bf16 v[0:3], v[194:197], v[232:235], v[0:3]
	s_setprio 0
	s_barrier
; #define PG8_STAGE(bufoff, gbase, voff) do { _Pragma("unroll") for (int _i = 0; _i < 2; ++_i) \
;         __builtin_amdgcn_global_load_lds((const unsigned*)((const char*)(gbase) + (voff)[_i]), (PG8_LAS unsigned*)(lds + (bufoff) + ldsw + _i * 8192), 16, 0, 0); } while (0)
; #define PG8_LDA(dst, b, h) do { _Pragma("unroll") for (int m = 0; m < 4; ++m) _Pragma("unroll") for (int k = 0; k < 2; ++k) dst[m][k] = *(const PG8_LAS bf16x8*)(lds + PG8_SA(b, h) + aoff + m * 2048 + k * 1024); } while (0)
; #define PG8_LDB(dst, b, h) do { _Pragma("unroll") for (int n = 0; n < 2; ++n) _Pragma("unroll") for (int k = 0; k < 2; ++k) dst[n][k] = *(const PG8_LAS bf16x8*)(lds + PG8_SB(b, h) + boff + n * 2048 + k * 1024); } while (0)
; #define PG8_MMA(ai, bj, At, Bt) do { __builtin_amdgcn_s_setprio(1); _Pragma("unroll") for (int m = 0; m < 4; ++m) _Pragma("unroll") for (int n = 0; n < 2; ++n) _Pragma("unroll") for (int k = 0; k < 2; ++k) \
;         acc[ai][bj][m][n] = __builtin_amdgcn_mfma_f32_16x16x32_bf16(Bt[n][k], At[m][k], acc[ai][bj][m][n], 0, 0, 0); __builtin_amdgcn_s_setprio(0); } while (0)
; #define PG8_WAIT_V(n) asm volatile("s_waitcnt vmcnt(" #n ")" ::: "memory")
; #define PG8_WAIT_L(n) asm volatile("s_waitcnt lgkmcnt(" #n ")" ::: "memory")
; #define PG8_BAR __builtin_amdgcn_s_barrier()
; #define PG8_SCHED __builtin_amdgcn_sched_barrier(0)
; template <class Epi, class Sched, bool ALIGN_EPI = false, bool SP2 = false>
; __device__ __forceinline__ void gemm_phase(PG8_LAS unsigned char* lds, const Gemm g, const Sched& S, const Epi& E) {
;     ...
;             PG8_LDB(B0, 1, 0); PG8_LDB(B1, 1, 1); PG8_SCHED; PG8_LDA(At, 1, 0); PG8_STAGE(PG8_SA(0, 1), a2 + hstep, voffA);
;             PG8_WAIT_V(8); PG8_WAIT_L(0); PG8_BAR; PG8_MMA(0, 0, At, B0); PG8_MMA(0, 1, At, B1); PG8_BAR; PG8_SCHED;
	s_add_i32 s3, 0, 0x18000
	v_add_u32_e32 v136, s3, v143
	s_add_i32 s33, 0, 0x1c000
	ds_read_b128 v[154:157], v136
	ds_read_b128 v[158:161], v136 offset:1024
	ds_read_b128 v[162:165], v136 offset:2048
	ds_read_b128 v[174:177], v136 offset:3072
	v_add_u32_e32 v136, s33, v143
	ds_read_b128 v[182:185], v136
	ds_read_b128 v[186:189], v136 offset:1024
	ds_read_b128 v[190:193], v136 offset:2048
	ds_read_b128 v[194:197], v136 offset:3072
	s_add_u32 s14, s58, 0x40000
	s_addc_u32 s15, s59, 0
	s_mov_b32 m0, s62
	v_lshl_add_u64 v[240:241], s[14:15], 0, v[134:135]
	ds_read_b128 v[198:201], v171 offset:32768
	ds_read_b128 v[208:211], v171 offset:33792
	ds_read_b128 v[212:215], v171 offset:34816
	ds_read_b128 v[216:219], v171 offset:35840
	ds_read_b128 v[220:223], v171 offset:36864
	ds_read_b128 v[224:227], v171 offset:37888
	ds_read_b128 v[228:231], v171 offset:38912
	ds_read_b128 v[232:235], v171 offset:39936
	global_load_lds_dwordx4 v[240:241], off
	v_lshl_add_u64 v[240:241], s[14:15], 0, v[130:131]
	s_mov_b32 m0, s63
	s_nop 0
	global_load_lds_dwordx4 v[240:241], off
	s_waitcnt vmcnt(8)
	s_waitcnt lgkmcnt(0)
	s_barrier
	s_setprio 1
	s_waitcnt lgkmcnt(0)
	v_mfma_f32_16x16x32_bf16 v[124:127], v[154:157], v[198:201], v[124:127]
	v_mfma_f32_16x16x32_bf16 v[116:119], v[154:157], v[212:215], v[116:119]
	v_mfma_f32_16x16x32_bf16 v[120:123], v[162:165], v[198:201], v[120:123]
	v_mfma_f32_16x16x32_bf16 v[112:115], v[162:165], v[212:215], v[112:115]
	v_mfma_f32_16x16x32_bf16 v[108:111], v[154:157], v[220:223], v[108:111]
	v_mfma_f32_16x16x32_bf16 v[100:103], v[154:157], v[228:231], v[100:103]
	v_mfma_f32_16x16x32_bf16 v[104:107], v[162:165], v[220:223], v[104:107]
	v_mfma_f32_16x16x32_bf16 v[96:99], v[162:165], v[228:231], v[96:99]
	v_mfma_f32_16x16x32_bf16 v[124:127], v[158:161], v[208:211], v[124:127]
	v_mfma_f32_16x16x32_bf16 v[116:119], v[158:161], v[216:219], v[116:119]
	v_mfma_f32_16x16x32_bf16 v[120:123], v[174:177], v[208:211], v[120:123]
	v_mfma_f32_16x16x32_bf16 v[112:115], v[174:177], v[216:219], v[112:115]
	v_mfma_f32_16x16x32_bf16 v[108:111], v[158:161], v[224:227], v[108:111]
	v_mfma_f32_16x16x32_bf16 v[100:103], v[158:161], v[232:235], v[100:103]
	v_mfma_f32_16x16x32_bf16 v[104:107], v[174:177], v[224:227], v[104:107]
	v_mfma_f32_16x16x32_bf16 v[96:99], v[174:177], v[232:235], v[96:99]
	s_setprio 0
	s_setprio 1
	v_mfma_f32_16x16x32_bf16 v[68:71], v[182:185], v[198:201], v[68:71]
	v_mfma_f32_16x16x32_bf16 v[52:55], v[182:185], v[212:215], v[52:55]
	v_mfma_f32_16x16x32_bf16 v[64:67], v[190:193], v[198:201], v[64:67]
	v_mfma_f32_16x16x32_bf16 v[48:51], v[190:193], v[212:215], v[48:51]
	v_mfma_f32_16x16x32_bf16 v[44:47], v[182:185], v[220:223], v[44:47]
	v_mfma_f32_16x16x32_bf16 v[36:39], v[182:185], v[228:231], v[36:39]
	v_mfma_f32_16x16x32_bf16 v[40:43], v[190:193], v[220:223], v[40:43]
	v_mfma_f32_16x16x32_bf16 v[32:35], v[190:193], v[228:231], v[32:35]
	v_mfma_f32_16x16x32_bf16 v[68:71], v[186:189], v[208:211], v[68:71]
	v_mfma_f32_16x16x32_bf16 v[52:55], v[186:189], v[216:219], v[52:55]
	v_mfma_f32_16x16x32_bf16 v[64:67], v[194:197], v[208:211], v[64:67]
	v_mfma_f32_16x16x32_bf16 v[48:51], v[194:197], v[216:219], v[48:51]
	v_mfma_f32_16x16x32_bf16 v[44:47], v[186:189], v[224:227], v[44:47]
	v_mfma_f32_16x16x32_bf16 v[36:39], v[186:189], v[232:235], v[36:39]
	v_mfma_f32_16x16x32_bf16 v[40:43], v[194:197], v[224:227], v[40:43]
	v_mfma_f32_16x16x32_bf16 v[32:35], v[194:197], v[232:235], v[32:35]
	s_setprio 0
	s_barrier
; #define PG8_STAGE(bufoff, gbase, voff) do { _Pragma("unroll") for (int _i = 0; _i < 2; ++_i) \
;         __builtin_amdgcn_global_load_lds((const unsigned*)((const char*)(gbase) + (voff)[_i]), (PG8_LAS unsigned*)(lds + (bufoff) + ldsw + _i * 8192), 16, 0, 0); } while (0)
; #define PG8_LDA(dst, b, h) do { _Pragma("unroll") for (int m = 0; m < 4; ++m) _Pragma("unroll") for (int k = 0; k < 2; ++k) dst[m][k] = *(const PG8_LAS bf16x8*)(lds + PG8_SA(b, h) + aoff + m * 2048 + k * 1024); } while (0)
; #define PG8_MMA(ai, bj, At, Bt) do { __builtin_amdgcn_s_setprio(1); _Pragma("unroll") for (int m = 0; m < 4; ++m) _Pragma("unroll") for (int n = 0; n < 2; ++n) _Pragma("unroll") for (int k = 0; k < 2; ++k) \
;         acc[ai][bj][m][n] = __builtin_amdgcn_mfma_f32_16x16x32_bf16(Bt[n][k], At[m][k], acc[ai][bj][m][n], 0, 0, 0); __builtin_amdgcn_s_setprio(0); } while (0)
; #define PG8_WAIT_V(n) asm volatile("s_waitcnt vmcnt(" #n ")" ::: "memory")
; #define PG8_WAIT_L(n) asm volatile("s_waitcnt lgkmcnt(" #n ")" ::: "memory")
; #define PG8_BAR __builtin_amdgcn_s_barrier()
; #define PG8_SCHED __builtin_amdgcn_sched_barrier(0)
; template <class Epi, class Sched, bool ALIGN_EPI = false, bool SP2 = false>
; __device__ __forceinline__ void gemm_phase(PG8_LAS unsigned char* lds, const Gemm g, const Sched& S, const Epi& E) {
;     ...
;             PG8_LDA(At, 1, 1); PG8_STAGE(PG8_SB(1, 0), b3, voffB); PG8_STAGE(PG8_SB(1, 1), b3 + hstep, voffB); PG8_STAGE(PG8_SA(1, 0), a3, voffA);
;             PG8_WAIT_V(8); PG8_WAIT_L(0); PG8_BAR; PG8_MMA(1, 0, At, B0); PG8_MMA(1, 1, At, B1); PG8_BAR; PG8_SCHED;
;     ...
;         if constexpr (ALIGN_EPI) { if (wr == 0) PG8_BAR; }
	s_add_i32 s3, s3, s34
	v_lshl_add_u64 v[178:179], v[178:179], 0, s[8:9]
	s_mov_b32 m0, s3
	ds_read_b128 v[198:201], v171 offset:49152
	ds_read_b128 v[208:211], v171 offset:50176
	ds_read_b128 v[212:215], v171 offset:51200
	ds_read_b128 v[216:219], v171 offset:52224
	ds_read_b128 v[220:223], v171 offset:53248
	ds_read_b128 v[224:227], v171 offset:54272
	ds_read_b128 v[228:231], v171 offset:55296
	ds_read_b128 v[232:235], v171 offset:56320
	global_load_lds_dwordx4 v[178:179], off
	s_add_i32 m0, s3, 0x2000
	s_add_u32 s14, s56, 0x40080
	v_lshl_add_u64 v[178:179], v[202:203], 0, s[8:9]
	s_addc_u32 s15, s57, 0
	s_add_i32 s3, s33, s34
	global_load_lds_dwordx4 v[178:179], off
	v_lshl_add_u64 v[178:179], s[14:15], 0, v[132:133]
	s_mov_b32 m0, s3
	s_nop 0
	global_load_lds_dwordx4 v[178:179], off
	v_lshl_add_u64 v[178:179], s[14:15], 0, v[128:129]
	s_add_i32 m0, s3, 0x2000
	s_nop 0
	global_load_lds_dwordx4 v[178:179], off
	s_waitcnt vmcnt(6)
	s_waitcnt lgkmcnt(0)
	s_barrier
	s_setprio 1
	s_waitcnt lgkmcnt(0)
	v_mfma_f32_16x16x32_bf16 v[92:95], v[154:157], v[198:201], v[92:95]
	v_mfma_f32_16x16x32_bf16 v[84:87], v[154:157], v[212:215], v[84:87]
	v_mfma_f32_16x16x32_bf16 v[88:91], v[162:165], v[198:201], v[88:91]
	v_mfma_f32_16x16x32_bf16 v[80:83], v[162:165], v[212:215], v[80:83]
	v_mfma_f32_16x16x32_bf16 v[76:79], v[154:157], v[220:223], v[76:79]
	v_mfma_f32_16x16x32_bf16 v[60:63], v[154:157], v[228:231], v[60:63]
	v_mfma_f32_16x16x32_bf16 v[72:75], v[162:165], v[220:223], v[72:75]
	v_mfma_f32_16x16x32_bf16 v[56:59], v[162:165], v[228:231], v[56:59]
	v_mfma_f32_16x16x32_bf16 v[92:95], v[158:161], v[208:211], v[92:95]
	v_mfma_f32_16x16x32_bf16 v[84:87], v[158:161], v[216:219], v[84:87]
	v_mfma_f32_16x16x32_bf16 v[88:91], v[174:177], v[208:211], v[88:91]
	v_mfma_f32_16x16x32_bf16 v[80:83], v[174:177], v[216:219], v[80:83]
	v_mfma_f32_16x16x32_bf16 v[76:79], v[158:161], v[224:227], v[76:79]
	v_mfma_f32_16x16x32_bf16 v[60:63], v[158:161], v[232:235], v[60:63]
	v_lshl_add_u64 v[178:179], v[236:237], 0, s[8:9]
	s_mov_b32 m0, s66
	s_nop 0
	global_load_lds_dwordx4 v[178:179], off
	v_mfma_f32_16x16x32_bf16 v[72:75], v[174:177], v[224:227], v[72:75]
	v_mfma_f32_16x16x32_bf16 v[56:59], v[174:177], v[232:235], v[56:59]
	s_setprio 0
	s_setprio 1
	v_mfma_f32_16x16x32_bf16 v[28:31], v[182:185], v[198:201], v[28:31]
	v_mfma_f32_16x16x32_bf16 v[20:23], v[182:185], v[212:215], v[20:23]
	v_mfma_f32_16x16x32_bf16 v[24:27], v[190:193], v[198:201], v[24:27]
	v_mfma_f32_16x16x32_bf16 v[16:19], v[190:193], v[212:215], v[16:19]
	v_mfma_f32_16x16x32_bf16 v[12:15], v[182:185], v[220:223], v[12:15]
	v_mfma_f32_16x16x32_bf16 v[4:7], v[182:185], v[228:231], v[4:7]
	v_mfma_f32_16x16x32_bf16 v[8:11], v[190:193], v[220:223], v[8:11]
	v_mfma_f32_16x16x32_bf16 v[0:3], v[190:193], v[228:231], v[0:3]
	v_mfma_f32_16x16x32_bf16 v[28:31], v[186:189], v[208:211], v[28:31]
	v_mfma_f32_16x16x32_bf16 v[20:23], v[186:189], v[216:219], v[20:23]
	v_mfma_f32_16x16x32_bf16 v[24:27], v[194:197], v[208:211], v[24:27]
	v_mfma_f32_16x16x32_bf16 v[16:19], v[194:197], v[216:219], v[16:19]
	v_mfma_f32_16x16x32_bf16 v[12:15], v[186:189], v[224:227], v[12:15]
	v_mfma_f32_16x16x32_bf16 v[4:7], v[186:189], v[232:235], v[4:7]
	v_lshl_add_u64 v[178:179], v[238:239], 0, s[8:9]
	s_mov_b32 m0, s67
	s_nop 0
	global_load_lds_dwordx4 v[178:179], off
	v_mfma_f32_16x16x32_bf16 v[8:11], v[194:197], v[224:227], v[8:11]
	v_mfma_f32_16x16x32_bf16 v[0:3], v[194:197], v[232:235], v[0:3]
	s_setprio 0
	s_barrier
	s_add_i32 s93, s93, 2
	s_add_u32 s54, s54, 0x100
	s_addc_u32 s55, s55, 0
	s_add_u32 s91, s91, 0x100
	s_addc_u32 s92, s92, 0
	s_cmp_gt_u32 s93, 13
	s_cbranch_scc0 .LBB0_417
	s_and_b64 vcc, exec, s[10:11]
	s_cbranch_vccz .LBB0_420
	s_barrier

; #define PG8_STAGE(bufoff, gbase, voff) do { _Pragma("unroll") for (int _i = 0; _i < 2; ++_i) \
;         __builtin_amdgcn_global_load_lds((const unsigned*)((const char*)(gbase) + (voff)[_i]), (PG8_LAS unsigned*)(lds + (bufoff) + ldsw + _i * 8192), 16, 0, 0); } while (0)
; #define PG8_LDA(dst, b, h) do { _Pragma("unroll") for (int m = 0; m < 4; ++m) _Pragma("unroll") for (int k = 0; k < 2; ++k) dst[m][k] = *(const PG8_LAS bf16x8*)(lds + PG8_SA(b, h) + aoff + m * 2048 + k * 1024); } while (0)
; #define PG8_LDB(dst, b, h) do { _Pragma("unroll") for (int n = 0; n < 2; ++n) _Pragma("unroll") for (int k = 0; k < 2; ++k) dst[n][k] = *(const PG8_LAS bf16x8*)(lds + PG8_SB(b, h) + boff + n * 2048 + k * 1024); } while (0)
; #define PG8_MMA(ai, bj, At, Bt) do { __builtin_amdgcn_s_setprio(1); _Pragma("unroll") for (int m = 0; m < 4; ++m) _Pragma("unroll") for (int n = 0; n < 2; ++n) _Pragma("unroll") for (int k = 0; k < 2; ++k) \
;         acc[ai][bj][m][n] = __builtin_amdgcn_mfma_f32_16x16x32_bf16(Bt[n][k], At[m][k], acc[ai][bj][m][n], 0, 0, 0); __builtin_amdgcn_s_setprio(0); } while (0)
; #define PG8_BAR __builtin_amdgcn_s_barrier()
; template <class Epi, class Sched, bool ALIGN_EPI = false, bool SP2 = false>
; __device__ __forceinline__ void gemm_phase(PG8_LAS unsigned char* lds, const Gemm g, const Sched& S, const Epi& E) {
;     ...
;         const bool has_next = S.next(ui + 1, nxt);
;         const char* nA = has_next ? (const char*)g.A + (size_t)nxt.pm * tstep : cA; const char* nB = has_next ? (const char*)g.Bt + (size_t)nxt.pn * tstep : cB;
;         for (int t = 0; t < nt; t += 2) {
;             const bool last = (t == nt - 2);
;             const char* a1 = cA + (size_t)(t + 1) * kstep;
;             const char* a2 = last ? nA : cA + (size_t)(t + 2) * kstep; const char* b2 = last ? nB : cB + (size_t)(t + 2) * kstep;
;             const char* a3 = a2 + kstep; const char* b3 = b2 + kstep;
;             if (last && has_next) S.a_ready(nxt);
;             if constexpr (SP2) {
;             PG8_LDB(B0, 0, 0); PG8_LDB(B1, 0, 1); PG8_SCHED; PG8_LDA(At, 0, 0); PG8_STAGE(PG8_SA(1, 1), a1 + hstep, voffA);
;             PG8_WAIT_V(8); PG8_WAIT_L(0); PG8_BAR; PG8_MMA(0, 0, At, B0); PG8_MMA(0, 1, At, B1); PG8_BAR; PG8_SCHED;
;             PG8_LDA(At, 0, 1); PG8_STAGE(PG8_SB(0, 0), b2, voffB); PG8_STAGE(PG8_SB(0, 1), b2 + hstep, voffB); PG8_STAGE(PG8_SA(0, 0), a2, voffA);
.LBB0_458:
	s_ashr_i32 s49, s48, 31
	s_lshl_b64 s[14:15], s[48:49], 19
	s_add_u32 s50, s34, s14
	s_addc_u32 s51, s43, s15
	s_and_b64 s[14:15], s[40:41], exec
	s_cselect_b32 s49, s51, s59
	s_cselect_b32 s55, s50, s58
	s_ashr_i32 s45, s44, 31
	s_lshl_b64 s[14:15], s[44:45], 19
	v_readlane_b32 s3, v250, 13
	s_add_u32 s52, s3, s14
	v_readlane_b32 s3, v250, 14
	s_addc_u32 s53, s3, s15
	s_and_b64 s[14:15], s[40:41], exec
	s_cselect_b32 s45, s53, s61
	s_cselect_b32 s57, s52, s60
	s_add_u32 s58, s58, 0x40080
	s_addc_u32 s59, s59, 0
	s_add_u32 s96, s60, 0x100
	s_addc_u32 s97, s61, 0
	s_mov_b32 vcc_lo, -2
	ds_read_b128 v[170:173], v165
	ds_read_b128 v[174:177], v165 offset:1024
	ds_read_b128 v[182:185], v165 offset:2048
	ds_read_b128 v[186:189], v165 offset:3072
	ds_read_b128 v[190:193], v168
	ds_read_b128 v[194:197], v168 offset:1024
	ds_read_b128 v[198:201], v168 offset:2048
	ds_read_b128 v[208:211], v168 offset:3072
	s_add_u32 s3, s58, 0xfffc0080
	s_addc_u32 s14, s59, -1
	s_cmp_eq_u32 vcc_lo, 12
	s_cselect_b32 s63, s49, s14
	s_cselect_b32 s62, s55, s3
	s_cselect_b32 s61, s45, s97
	s_cselect_b32 s60, s57, s96
	v_lshl_add_u64 v[178:179], s[58:59], 0, v[160:161]
	s_add_i32 m0, s85, 0xc000
	ds_read_b128 v[212:215], v164
	ds_read_b128 v[216:219], v164 offset:1024
	ds_read_b128 v[220:223], v164 offset:2048
	ds_read_b128 v[224:227], v164 offset:3072
	ds_read_b128 v[228:231], v164 offset:4096
	ds_read_b128 v[232:235], v164 offset:5120
	ds_read_b128 v[236:239], v164 offset:6144
	ds_read_b128 v[240:243], v164 offset:7168
	global_load_lds_dwordx4 v[178:179], off
	v_lshl_add_u64 v[178:179], s[58:59], 0, v[162:163]
	s_add_i32 m0, s85, 0xe000
	s_nop 0
	global_load_lds_dwordx4 v[178:179], off
	s_waitcnt vmcnt(8)
	s_waitcnt lgkmcnt(0)
	s_barrier
	s_setprio 1
	s_waitcnt lgkmcnt(0)
	v_mfma_f32_16x16x32_bf16 v[124:127], v[170:173], v[212:215], 0
	v_mfma_f32_16x16x32_bf16 v[116:119], v[170:173], v[220:223], 0
	v_mfma_f32_16x16x32_bf16 v[120:123], v[182:185], v[212:215], 0
	v_mfma_f32_16x16x32_bf16 v[112:115], v[182:185], v[220:223], 0
	v_mfma_f32_16x16x32_bf16 v[108:111], v[170:173], v[228:231], 0
	v_mfma_f32_16x16x32_bf16 v[100:103], v[170:173], v[236:239], 0
	v_mfma_f32_16x16x32_bf16 v[104:107], v[182:185], v[228:231], 0
	v_mfma_f32_16x16x32_bf16 v[96:99], v[182:185], v[236:239], 0
	v_mfma_f32_16x16x32_bf16 v[124:127], v[174:177], v[216:219], v[124:127]
	v_mfma_f32_16x16x32_bf16 v[116:119], v[174:177], v[224:227], v[116:119]
	v_mfma_f32_16x16x32_bf16 v[120:123], v[186:189], v[216:219], v[120:123]
	v_mfma_f32_16x16x32_bf16 v[112:115], v[186:189], v[224:227], v[112:115]
	v_mfma_f32_16x16x32_bf16 v[108:111], v[174:177], v[232:235], v[108:111]
	v_mfma_f32_16x16x32_bf16 v[100:103], v[174:177], v[240:243], v[100:103]
	v_mfma_f32_16x16x32_bf16 v[104:107], v[186:189], v[232:235], v[104:107]
	v_mfma_f32_16x16x32_bf16 v[96:99], v[186:189], v[240:243], v[96:99]
	s_setprio 0
	s_setprio 1
	v_mfma_f32_16x16x32_bf16 v[60:63], v[190:193], v[212:215], 0
	v_mfma_f32_16x16x32_bf16 v[52:55], v[190:193], v[220:223], 0
	v_mfma_f32_16x16x32_bf16 v[56:59], v[198:201], v[212:215], 0
	v_mfma_f32_16x16x32_bf16 v[48:51], v[198:201], v[220:223], 0
	v_mfma_f32_16x16x32_bf16 v[44:47], v[190:193], v[228:231], 0
	v_mfma_f32_16x16x32_bf16 v[36:39], v[190:193], v[236:239], 0
	v_mfma_f32_16x16x32_bf16 v[40:43], v[198:201], v[228:231], 0
	v_mfma_f32_16x16x32_bf16 v[32:35], v[198:201], v[236:239], 0
	v_mfma_f32_16x16x32_bf16 v[60:63], v[194:197], v[216:219], v[60:63]
	v_mfma_f32_16x16x32_bf16 v[52:55], v[194:197], v[224:227], v[52:55]
	v_mfma_f32_16x16x32_bf16 v[56:59], v[208:211], v[216:219], v[56:59]
	v_mfma_f32_16x16x32_bf16 v[48:51], v[208:211], v[224:227], v[48:51]
	v_mfma_f32_16x16x32_bf16 v[44:47], v[194:197], v[232:235], v[44:47]
	v_mfma_f32_16x16x32_bf16 v[36:39], v[194:197], v[240:243], v[36:39]
	v_mfma_f32_16x16x32_bf16 v[40:43], v[208:211], v[232:235], v[40:43]
	v_mfma_f32_16x16x32_bf16 v[32:35], v[208:211], v[240:243], v[32:35]
	s_setprio 0
	s_barrier
	s_add_i32 s3, s94, s84
	v_lshl_add_u64 v[178:179], s[60:61], 0, v[130:131]
	s_mov_b32 m0, s3
	ds_read_b128 v[212:215], v164 offset:16384
	ds_read_b128 v[216:219], v164 offset:17408
	ds_read_b128 v[220:223], v164 offset:18432
	ds_read_b128 v[224:227], v164 offset:19456
	ds_read_b128 v[228:231], v164 offset:20480
	ds_read_b128 v[232:235], v164 offset:21504
	ds_read_b128 v[236:239], v164 offset:22528
	ds_read_b128 v[240:243], v164 offset:23552
	global_load_lds_dwordx4 v[178:179], off
	s_add_i32 m0, s3, 0x2000
	s_add_u32 s14, s60, 0x40000
	v_lshl_add_u64 v[202:203], s[60:61], 0, v[134:135]
	s_addc_u32 s15, s61, 0
	s_add_i32 s3, s95, s84
	global_load_lds_dwordx4 v[202:203], off
	v_lshl_add_u64 v[244:245], s[14:15], 0, v[130:131]
	s_mov_b32 m0, s3
	global_load_lds_dwordx4 v[244:245], off
	v_lshl_add_u64 v[244:245], s[14:15], 0, v[134:135]
	s_add_i32 m0, s3, 0x2000
	s_nop 0
	global_load_lds_dwordx4 v[244:245], off
	s_waitcnt vmcnt(6)
	s_waitcnt lgkmcnt(0)
	s_barrier
; #define PG8_STAGE(bufoff, gbase, voff) do { _Pragma("unroll") for (int _i = 0; _i < 2; ++_i) \
;         __builtin_amdgcn_global_load_lds((const unsigned*)((const char*)(gbase) + (voff)[_i]), (PG8_LAS unsigned*)(lds + (bufoff) + ldsw + _i * 8192), 16, 0, 0); } while (0)
; #define PG8_LDA(dst, b, h) do { _Pragma("unroll") for (int m = 0; m < 4; ++m) _Pragma("unroll") for (int k = 0; k < 2; ++k) dst[m][k] = *(const PG8_LAS bf16x8*)(lds + PG8_SA(b, h) + aoff + m * 2048 + k * 1024); } while (0)
; #define PG8_LDB(dst, b, h) do { _Pragma("unroll") for (int n = 0; n < 2; ++n) _Pragma("unroll") for (int k = 0; k < 2; ++k) dst[n][k] = *(const PG8_LAS bf16x8*)(lds + PG8_SB(b, h) + boff + n * 2048 + k * 1024); } while (0)
; #define PG8_MMA(ai, bj, At, Bt) do { __builtin_amdgcn_s_setprio(1); _Pragma("unroll") for (int m = 0; m < 4; ++m) _Pragma("unroll") for (int n = 0; n < 2; ++n) _Pragma("unroll") for (int k = 0; k < 2; ++k) \
;         acc[ai][bj][m][n] = __builtin_amdgcn_mfma_f32_16x16x32_bf16(Bt[n][k], At[m][k], acc[ai][bj][m][n], 0, 0, 0); __builtin_amdgcn_s_setprio(0); } while (0)
; #define PG8_WAIT_V(n) asm volatile("s_waitcnt vmcnt(" #n ")" ::: "memory")
; #define PG8_WAIT_L(n) asm volatile("s_waitcnt lgkmcnt(" #n ")" ::: "memory")
; #define PG8_BAR __builtin_amdgcn_s_barrier()
; #define PG8_SCHED __builtin_amdgcn_sched_barrier(0)
; template <class Epi, class Sched, bool ALIGN_EPI = false, bool SP2 = false>
; __device__ __forceinline__ void gemm_phase(PG8_LAS unsigned char* lds, const Gemm g, const Sched& S, const Epi& E) {
;     ...
;             PG8_LDA(At, 0, 1); PG8_STAGE(PG8_SB(0, 0), b2, voffB); PG8_STAGE(PG8_SB(0, 1), b2 + hstep, voffB); PG8_STAGE(PG8_SA(0, 0), a2, voffA);
;             PG8_WAIT_V(8); PG8_WAIT_L(0); PG8_BAR; PG8_MMA(1, 0, At, B0); PG8_MMA(1, 1, At, B1); PG8_BAR; PG8_SCHED;
;             PG8_LDB(B0, 1, 0); PG8_LDB(B1, 1, 1); PG8_SCHED; PG8_LDA(At, 1, 0); PG8_STAGE(PG8_SA(0, 1), a2 + hstep, voffA);
;             PG8_WAIT_V(8); PG8_WAIT_L(0); PG8_BAR; PG8_MMA(0, 0, At, B0); PG8_MMA(0, 1, At, B1); PG8_BAR; PG8_SCHED;
	s_setprio 1
	s_waitcnt lgkmcnt(0)
	v_mfma_f32_16x16x32_bf16 v[92:95], v[170:173], v[212:215], 0
	v_mfma_f32_16x16x32_bf16 v[84:87], v[170:173], v[220:223], 0
	v_mfma_f32_16x16x32_bf16 v[88:91], v[182:185], v[212:215], 0
	v_mfma_f32_16x16x32_bf16 v[80:83], v[182:185], v[220:223], 0
	v_mfma_f32_16x16x32_bf16 v[76:79], v[170:173], v[228:231], 0
	v_mfma_f32_16x16x32_bf16 v[68:71], v[170:173], v[236:239], 0
	v_mfma_f32_16x16x32_bf16 v[72:75], v[182:185], v[228:231], 0
	v_mfma_f32_16x16x32_bf16 v[64:67], v[182:185], v[236:239], 0
	v_mfma_f32_16x16x32_bf16 v[92:95], v[174:177], v[216:219], v[92:95]
	v_mfma_f32_16x16x32_bf16 v[84:87], v[174:177], v[224:227], v[84:87]
	v_mfma_f32_16x16x32_bf16 v[88:91], v[186:189], v[216:219], v[88:91]
	v_mfma_f32_16x16x32_bf16 v[80:83], v[186:189], v[224:227], v[80:83]
	v_mfma_f32_16x16x32_bf16 v[76:79], v[174:177], v[232:235], v[76:79]
	v_mfma_f32_16x16x32_bf16 v[68:71], v[174:177], v[240:243], v[68:71]
	v_lshl_add_u64 v[244:245], s[62:63], 0, v[128:129]
	s_mov_b32 m0, s85
	s_nop 0
	global_load_lds_dwordx4 v[244:245], off
	v_mfma_f32_16x16x32_bf16 v[72:75], v[186:189], v[232:235], v[72:75]
	v_mfma_f32_16x16x32_bf16 v[64:67], v[186:189], v[240:243], v[64:67]
	s_setprio 0
	s_setprio 1
	v_mfma_f32_16x16x32_bf16 v[28:31], v[190:193], v[212:215], 0
	v_mfma_f32_16x16x32_bf16 v[20:23], v[190:193], v[220:223], 0
	v_mfma_f32_16x16x32_bf16 v[24:27], v[198:201], v[212:215], 0
	v_mfma_f32_16x16x32_bf16 v[16:19], v[198:201], v[220:223], 0
	v_mfma_f32_16x16x32_bf16 v[12:15], v[190:193], v[228:231], 0
	v_mfma_f32_16x16x32_bf16 v[4:7], v[190:193], v[236:239], 0
	v_mfma_f32_16x16x32_bf16 v[8:11], v[198:201], v[228:231], 0
	v_mfma_f32_16x16x32_bf16 v[0:3], v[198:201], v[236:239], 0
	v_mfma_f32_16x16x32_bf16 v[28:31], v[194:197], v[216:219], v[28:31]
	v_mfma_f32_16x16x32_bf16 v[20:23], v[194:197], v[224:227], v[20:23]
	v_mfma_f32_16x16x32_bf16 v[24:27], v[208:211], v[216:219], v[24:27]
	v_mfma_f32_16x16x32_bf16 v[16:19], v[208:211], v[224:227], v[16:19]
	v_mfma_f32_16x16x32_bf16 v[12:15], v[194:197], v[232:235], v[12:15]
	v_mfma_f32_16x16x32_bf16 v[4:7], v[194:197], v[240:243], v[4:7]
	v_lshl_add_u64 v[246:247], s[62:63], 0, v[132:133]
	s_mov_b32 m0, s86
	s_nop 0
	global_load_lds_dwordx4 v[246:247], off
	v_mfma_f32_16x16x32_bf16 v[8:11], v[208:211], v[232:235], v[8:11]
	v_mfma_f32_16x16x32_bf16 v[0:3], v[208:211], v[240:243], v[0:3]
	s_setprio 0
	s_barrier
	s_add_i32 s3, 0, 0x18000
	v_add_u32_e32 v136, s3, v141
	s_add_i32 s33, 0, 0x1c000
	ds_read_b128 v[170:173], v136
	ds_read_b128 v[174:177], v136 offset:1024
	ds_read_b128 v[182:185], v136 offset:2048
	ds_read_b128 v[186:189], v136 offset:3072
	v_add_u32_e32 v136, s33, v141
	ds_read_b128 v[190:193], v136
	ds_read_b128 v[194:197], v136 offset:1024
	ds_read_b128 v[198:201], v136 offset:2048
	ds_read_b128 v[208:211], v136 offset:3072
	s_add_u32 s14, s62, 0x40000
	s_addc_u32 s15, s63, 0
	s_mov_b32 m0, s87
	v_lshl_add_u64 v[248:249], s[14:15], 0, v[128:129]
	ds_read_b128 v[212:215], v164 offset:32768
	ds_read_b128 v[216:219], v164 offset:33792
	ds_read_b128 v[220:223], v164 offset:34816
	ds_read_b128 v[224:227], v164 offset:35840
	ds_read_b128 v[228:231], v164 offset:36864
	ds_read_b128 v[232:235], v164 offset:37888
	ds_read_b128 v[236:239], v164 offset:38912
	ds_read_b128 v[240:243], v164 offset:39936
	global_load_lds_dwordx4 v[248:249], off
	v_lshl_add_u64 v[248:249], s[14:15], 0, v[132:133]
	s_mov_b32 m0, s88
	s_nop 0
	global_load_lds_dwordx4 v[248:249], off
	s_waitcnt vmcnt(8)
	s_waitcnt lgkmcnt(0)
	s_barrier
	s_setprio 1
	s_waitcnt lgkmcnt(0)
	v_mfma_f32_16x16x32_bf16 v[124:127], v[170:173], v[212:215], v[124:127]
	v_mfma_f32_16x16x32_bf16 v[116:119], v[170:173], v[220:223], v[116:119]
	v_mfma_f32_16x16x32_bf16 v[120:123], v[182:185], v[212:215], v[120:123]
	v_mfma_f32_16x16x32_bf16 v[112:115], v[182:185], v[220:223], v[112:115]
	v_mfma_f32_16x16x32_bf16 v[108:111], v[170:173], v[228:231], v[108:111]
	v_mfma_f32_16x16x32_bf16 v[100:103], v[170:173], v[236:239], v[100:103]
	v_mfma_f32_16x16x32_bf16 v[104:107], v[182:185], v[228:231], v[104:107]
	v_mfma_f32_16x16x32_bf16 v[96:99], v[182:185], v[236:239], v[96:99]
	v_mfma_f32_16x16x32_bf16 v[124:127], v[174:177], v[216:219], v[124:127]
	v_mfma_f32_16x16x32_bf16 v[116:119], v[174:177], v[224:227], v[116:119]
	v_mfma_f32_16x16x32_bf16 v[120:123], v[186:189], v[216:219], v[120:123]
	v_mfma_f32_16x16x32_bf16 v[112:115], v[186:189], v[224:227], v[112:115]
	v_mfma_f32_16x16x32_bf16 v[108:111], v[174:177], v[232:235], v[108:111]
	v_mfma_f32_16x16x32_bf16 v[100:103], v[174:177], v[240:243], v[100:103]
	v_mfma_f32_16x16x32_bf16 v[104:107], v[186:189], v[232:235], v[104:107]
	v_mfma_f32_16x16x32_bf16 v[96:99], v[186:189], v[240:243], v[96:99]
	s_setprio 0
	s_setprio 1
	v_mfma_f32_16x16x32_bf16 v[60:63], v[190:193], v[212:215], v[60:63]
	v_mfma_f32_16x16x32_bf16 v[52:55], v[190:193], v[220:223], v[52:55]
	v_mfma_f32_16x16x32_bf16 v[56:59], v[198:201], v[212:215], v[56:59]
	v_mfma_f32_16x16x32_bf16 v[48:51], v[198:201], v[220:223], v[48:51]
	v_mfma_f32_16x16x32_bf16 v[44:47], v[190:193], v[228:231], v[44:47]
	v_mfma_f32_16x16x32_bf16 v[36:39], v[190:193], v[236:239], v[36:39]
	v_mfma_f32_16x16x32_bf16 v[40:43], v[198:201], v[228:231], v[40:43]
	v_mfma_f32_16x16x32_bf16 v[32:35], v[198:201], v[236:239], v[32:35]
	v_mfma_f32_16x16x32_bf16 v[60:63], v[194:197], v[216:219], v[60:63]
	v_mfma_f32_16x16x32_bf16 v[52:55], v[194:197], v[224:227], v[52:55]
	v_mfma_f32_16x16x32_bf16 v[56:59], v[208:211], v[216:219], v[56:59]
	v_mfma_f32_16x16x32_bf16 v[48:51], v[208:211], v[224:227], v[48:51]
	v_mfma_f32_16x16x32_bf16 v[44:47], v[194:197], v[232:235], v[44:47]
	v_mfma_f32_16x16x32_bf16 v[36:39], v[194:197], v[240:243], v[36:39]
	v_mfma_f32_16x16x32_bf16 v[40:43], v[208:211], v[232:235], v[40:43]
	v_mfma_f32_16x16x32_bf16 v[32:35], v[208:211], v[240:243], v[32:35]
	s_setprio 0
	s_barrier
; #define PG8_STAGE(bufoff, gbase, voff) do { _Pragma("unroll") for (int _i = 0; _i < 2; ++_i) \
;         __builtin_amdgcn_global_load_lds((const unsigned*)((const char*)(gbase) + (voff)[_i]), (PG8_LAS unsigned*)(lds + (bufoff) + ldsw + _i * 8192), 16, 0, 0); } while (0)
; #define PG8_LDA(dst, b, h) do { _Pragma("unroll") for (int m = 0; m < 4; ++m) _Pragma("unroll") for (int k = 0; k < 2; ++k) dst[m][k] = *(const PG8_LAS bf16x8*)(lds + PG8_SA(b, h) + aoff + m * 2048 + k * 1024); } while (0)
; #define PG8_LDB(dst, b, h) do { _Pragma("unroll") for (int n = 0; n < 2; ++n) _Pragma("unroll") for (int k = 0; k < 2; ++k) dst[n][k] = *(const PG8_LAS bf16x8*)(lds + PG8_SB(b, h) + boff + n * 2048 + k * 1024); } while (0)
; #define PG8_MMA(ai, bj, At, Bt) do { __builtin_amdgcn_s_setprio(1); _Pragma("unroll") for (int m = 0; m < 4; ++m) _Pragma("unroll") for (int n = 0; n < 2; ++n) _Pragma("unroll") for (int k = 0; k < 2; ++k) \
;         acc[ai][bj][m][n] = __builtin_amdgcn_mfma_f32_16x16x32_bf16(Bt[n][k], At[m][k], acc[ai][bj][m][n], 0, 0, 0); __builtin_amdgcn_s_setprio(0); } while (0)
; #define PG8_WAIT_V(n) asm volatile("s_waitcnt vmcnt(" #n ")" ::: "memory")
; template <class Epi, class Sched, bool ALIGN_EPI = false, bool SP2 = false>
; __device__ __forceinline__ void gemm_phase(PG8_LAS unsigned char* lds, const Gemm g, const Sched& S, const Epi& E) {
;     ...
;             PG8_LDB(B0, 0, 0); PG8_LDB(B1, 0, 1); PG8_SCHED; PG8_LDA(At, 0, 0); PG8_STAGE(PG8_SA(1, 1), a1 + hstep, voffA);
;             PG8_WAIT_V(8); PG8_WAIT_L(0); PG8_BAR; PG8_MMA(0, 0, At, B0); PG8_MMA(0, 1, At, B1); PG8_BAR; PG8_SCHED;
;             PG8_LDA(At, 0, 1); PG8_STAGE(PG8_SB(0, 0), b2, voffB); PG8_STAGE(PG8_SB(0, 1), b2 + hstep, voffB); PG8_STAGE(PG8_SA(0, 0), a2, voffA);
;             PG8_WAIT_V(8); PG8_WAIT_L(0); PG8_BAR; PG8_MMA(1, 0, At, B0); PG8_MMA(1, 1, At, B1); PG8_BAR; PG8_SCHED;
;             PG8_LDB(B0, 1, 0); PG8_LDB(B1, 1, 1); PG8_SCHED; PG8_LDA(At, 1, 0); PG8_STAGE(PG8_SA(0, 1), a2 + hstep, voffA);
;             PG8_WAIT_V(8); PG8_WAIT_L(0); PG8_BAR; PG8_MMA(0, 0, At, B0); PG8_MMA(0, 1, At, B1); PG8_BAR; PG8_SCHED;
;             PG8_LDA(At, 1, 1); PG8_STAGE(PG8_SB(1, 0), b3, voffB); PG8_STAGE(PG8_SB(1, 1), b3 + hstep, voffB); PG8_STAGE(PG8_SA(1, 0), a3, voffA);
;             PG8_WAIT_V(8); PG8_WAIT_L(0); PG8_BAR; PG8_MMA(1, 0, At, B0); PG8_MMA(1, 1, At, B1); PG8_BAR; PG8_SCHED;
	s_add_i32 s3, s3, s84
	v_lshl_add_u64 v[178:179], v[178:179], 0, s[8:9]
	s_mov_b32 m0, s3
	ds_read_b128 v[212:215], v164 offset:49152
	ds_read_b128 v[216:219], v164 offset:50176
	ds_read_b128 v[220:223], v164 offset:51200
	ds_read_b128 v[224:227], v164 offset:52224
	ds_read_b128 v[228:231], v164 offset:53248
	ds_read_b128 v[232:235], v164 offset:54272
	ds_read_b128 v[236:239], v164 offset:55296
	ds_read_b128 v[240:243], v164 offset:56320
	global_load_lds_dwordx4 v[178:179], off
	s_add_i32 m0, s3, 0x2000
	s_add_u32 s14, s60, 0x40080
	v_lshl_add_u64 v[178:179], v[202:203], 0, s[8:9]
	s_addc_u32 s15, s61, 0
	s_add_i32 s3, s33, s84
	global_load_lds_dwordx4 v[178:179], off
	v_lshl_add_u64 v[178:179], s[14:15], 0, v[130:131]
	s_mov_b32 m0, s3
	s_nop 0
	global_load_lds_dwordx4 v[178:179], off
	v_lshl_add_u64 v[178:179], s[14:15], 0, v[134:135]
	s_add_i32 m0, s3, 0x2000
	s_nop 0
	global_load_lds_dwordx4 v[178:179], off
	s_waitcnt vmcnt(6)
	s_waitcnt lgkmcnt(0)
	s_barrier
	s_setprio 1
	s_waitcnt lgkmcnt(0)
	v_mfma_f32_16x16x32_bf16 v[92:95], v[170:173], v[212:215], v[92:95]
	v_mfma_f32_16x16x32_bf16 v[84:87], v[170:173], v[220:223], v[84:87]
	v_mfma_f32_16x16x32_bf16 v[88:91], v[182:185], v[212:215], v[88:91]
	v_mfma_f32_16x16x32_bf16 v[80:83], v[182:185], v[220:223], v[80:83]
	v_mfma_f32_16x16x32_bf16 v[76:79], v[170:173], v[228:231], v[76:79]
	v_mfma_f32_16x16x32_bf16 v[68:71], v[170:173], v[236:239], v[68:71]
	v_mfma_f32_16x16x32_bf16 v[72:75], v[182:185], v[228:231], v[72:75]
	v_mfma_f32_16x16x32_bf16 v[64:67], v[182:185], v[236:239], v[64:67]
	v_mfma_f32_16x16x32_bf16 v[92:95], v[174:177], v[216:219], v[92:95]
	v_mfma_f32_16x16x32_bf16 v[84:87], v[174:177], v[224:227], v[84:87]
	v_mfma_f32_16x16x32_bf16 v[88:91], v[186:189], v[216:219], v[88:91]
	v_mfma_f32_16x16x32_bf16 v[80:83], v[186:189], v[224:227], v[80:83]
	v_mfma_f32_16x16x32_bf16 v[76:79], v[174:177], v[232:235], v[76:79]
	v_mfma_f32_16x16x32_bf16 v[68:71], v[174:177], v[240:243], v[68:71]
	v_lshl_add_u64 v[178:179], v[244:245], 0, s[8:9]
	s_mov_b32 m0, s90
	s_nop 0
	global_load_lds_dwordx4 v[178:179], off
	v_mfma_f32_16x16x32_bf16 v[72:75], v[186:189], v[232:235], v[72:75]
	v_mfma_f32_16x16x32_bf16 v[64:67], v[186:189], v[240:243], v[64:67]
	s_setprio 0
	s_setprio 1
	v_mfma_f32_16x16x32_bf16 v[28:31], v[190:193], v[212:215], v[28:31]
	v_mfma_f32_16x16x32_bf16 v[20:23], v[190:193], v[220:223], v[20:23]
	v_mfma_f32_16x16x32_bf16 v[24:27], v[198:201], v[212:215], v[24:27]
	v_mfma_f32_16x16x32_bf16 v[16:19], v[198:201], v[220:223], v[16:19]
	v_mfma_f32_16x16x32_bf16 v[12:15], v[190:193], v[228:231], v[12:15]
	v_mfma_f32_16x16x32_bf16 v[4:7], v[190:193], v[236:239], v[4:7]
	v_mfma_f32_16x16x32_bf16 v[8:11], v[198:201], v[228:231], v[8:11]
	v_mfma_f32_16x16x32_bf16 v[0:3], v[198:201], v[236:239], v[0:3]
	v_mfma_f32_16x16x32_bf16 v[28:31], v[194:197], v[216:219], v[28:31]
	v_mfma_f32_16x16x32_bf16 v[20:23], v[194:197], v[224:227], v[20:23]
	v_mfma_f32_16x16x32_bf16 v[24:27], v[208:211], v[216:219], v[24:27]
	v_mfma_f32_16x16x32_bf16 v[16:19], v[208:211], v[224:227], v[16:19]
	v_mfma_f32_16x16x32_bf16 v[12:15], v[194:197], v[232:235], v[12:15]
	v_mfma_f32_16x16x32_bf16 v[4:7], v[194:197], v[240:243], v[4:7]
	v_lshl_add_u64 v[178:179], v[246:247], 0, s[8:9]
	s_mov_b32 m0, s91
	s_nop 0
	global_load_lds_dwordx4 v[178:179], off
	v_mfma_f32_16x16x32_bf16 v[8:11], v[208:211], v[232:235], v[8:11]
	v_mfma_f32_16x16x32_bf16 v[0:3], v[208:211], v[240:243], v[0:3]
	s_setprio 0
	s_barrier
	s_add_i32 vcc_lo, vcc_lo, 2
	s_add_u32 s58, s58, 0x100
	s_addc_u32 s59, s59, 0
	s_add_u32 s96, s96, 0x100
	s_addc_u32 s97, s97, 0
.LBB0_459:
	ds_read_b128 v[170:173], v165
	ds_read_b128 v[174:177], v165 offset:1024
	ds_read_b128 v[182:185], v165 offset:2048
	ds_read_b128 v[186:189], v165 offset:3072
	ds_read_b128 v[190:193], v168
	ds_read_b128 v[194:197], v168 offset:1024
	ds_read_b128 v[198:201], v168 offset:2048
	ds_read_b128 v[208:211], v168 offset:3072
	s_add_u32 s3, s58, 0xfffc0080
	s_addc_u32 s14, s59, -1
	s_cmp_eq_u32 vcc_lo, 12
	s_cselect_b32 s63, s49, s14
	s_cselect_b32 s62, s55, s3
	s_cselect_b32 s61, s45, s97
	s_cselect_b32 s60, s57, s96
	v_lshl_add_u64 v[178:179], s[58:59], 0, v[160:161]
	s_add_i32 m0, s85, 0xc000
	ds_read_b128 v[212:215], v164
	ds_read_b128 v[216:219], v164 offset:1024
	ds_read_b128 v[220:223], v164 offset:2048
	ds_read_b128 v[224:227], v164 offset:3072
	ds_read_b128 v[228:231], v164 offset:4096
	ds_read_b128 v[232:235], v164 offset:5120
	ds_read_b128 v[236:239], v164 offset:6144
	ds_read_b128 v[240:243], v164 offset:7168
	global_load_lds_dwordx4 v[178:179], off
	v_lshl_add_u64 v[178:179], s[58:59], 0, v[162:163]
	s_add_i32 m0, s85, 0xe000
	s_nop 0
	global_load_lds_dwordx4 v[178:179], off
	s_waitcnt vmcnt(8)
	s_waitcnt lgkmcnt(0)
	s_barrier
; #define PG8_STAGE(bufoff, gbase, voff) do { _Pragma("unroll") for (int _i = 0; _i < 2; ++_i) \
;         __builtin_amdgcn_global_load_lds((const unsigned*)((const char*)(gbase) + (voff)[_i]), (PG8_LAS unsigned*)(lds + (bufoff) + ldsw + _i * 8192), 16, 0, 0); } while (0)
; #define PG8_LDA(dst, b, h) do { _Pragma("unroll") for (int m = 0; m < 4; ++m) _Pragma("unroll") for (int k = 0; k < 2; ++k) dst[m][k] = *(const PG8_LAS bf16x8*)(lds + PG8_SA(b, h) + aoff + m * 2048 + k * 1024); } while (0)
; #define PG8_LDB(dst, b, h) do { _Pragma("unroll") for (int n = 0; n < 2; ++n) _Pragma("unroll") for (int k = 0; k < 2; ++k) dst[n][k] = *(const PG8_LAS bf16x8*)(lds + PG8_SB(b, h) + boff + n * 2048 + k * 1024); } while (0)
; #define PG8_MMA(ai, bj, At, Bt) do { __builtin_amdgcn_s_setprio(1); _Pragma("unroll") for (int m = 0; m < 4; ++m) _Pragma("unroll") for (int n = 0; n < 2; ++n) _Pragma("unroll") for (int k = 0; k < 2; ++k) \
;         acc[ai][bj][m][n] = __builtin_amdgcn_mfma_f32_16x16x32_bf16(Bt[n][k], At[m][k], acc[ai][bj][m][n], 0, 0, 0); __builtin_amdgcn_s_setprio(0); } while (0)
; #define PG8_WAIT_V(n) asm volatile("s_waitcnt vmcnt(" #n ")" ::: "memory")
; #define PG8_WAIT_L(n) asm volatile("s_waitcnt lgkmcnt(" #n ")" ::: "memory")
; #define PG8_BAR __builtin_amdgcn_s_barrier()
; #define PG8_SCHED __builtin_amdgcn_sched_barrier(0)
; template <class Epi, class Sched, bool ALIGN_EPI = false, bool SP2 = false>
; __device__ __forceinline__ void gemm_phase(PG8_LAS unsigned char* lds, const Gemm g, const Sched& S, const Epi& E) {
;     ...
;             PG8_LDB(B0, 0, 0); PG8_LDB(B1, 0, 1); PG8_SCHED; PG8_LDA(At, 0, 0); PG8_STAGE(PG8_SA(1, 1), a1 + hstep, voffA);
;             PG8_WAIT_V(8); PG8_WAIT_L(0); PG8_BAR; PG8_MMA(0, 0, At, B0); PG8_MMA(0, 1, At, B1); PG8_BAR; PG8_SCHED;
;             PG8_LDA(At, 0, 1); PG8_STAGE(PG8_SB(0, 0), b2, voffB); PG8_STAGE(PG8_SB(0, 1), b2 + hstep, voffB); PG8_STAGE(PG8_SA(0, 0), a2, voffA);
;             PG8_WAIT_V(8); PG8_WAIT_L(0); PG8_BAR; PG8_MMA(1, 0, At, B0); PG8_MMA(1, 1, At, B1); PG8_BAR; PG8_SCHED;
	s_setprio 1
	s_waitcnt lgkmcnt(0)
	v_mfma_f32_16x16x32_bf16 v[124:127], v[170:173], v[212:215], v[124:127]
	v_mfma_f32_16x16x32_bf16 v[116:119], v[170:173], v[220:223], v[116:119]
	v_mfma_f32_16x16x32_bf16 v[120:123], v[182:185], v[212:215], v[120:123]
	v_mfma_f32_16x16x32_bf16 v[112:115], v[182:185], v[220:223], v[112:115]
	v_mfma_f32_16x16x32_bf16 v[108:111], v[170:173], v[228:231], v[108:111]
	v_mfma_f32_16x16x32_bf16 v[100:103], v[170:173], v[236:239], v[100:103]
	v_mfma_f32_16x16x32_bf16 v[104:107], v[182:185], v[228:231], v[104:107]
	v_mfma_f32_16x16x32_bf16 v[96:99], v[182:185], v[236:239], v[96:99]
	v_mfma_f32_16x16x32_bf16 v[124:127], v[174:177], v[216:219], v[124:127]
	v_mfma_f32_16x16x32_bf16 v[116:119], v[174:177], v[224:227], v[116:119]
	v_mfma_f32_16x16x32_bf16 v[120:123], v[186:189], v[216:219], v[120:123]
	v_mfma_f32_16x16x32_bf16 v[112:115], v[186:189], v[224:227], v[112:115]
	v_mfma_f32_16x16x32_bf16 v[108:111], v[174:177], v[232:235], v[108:111]
	v_mfma_f32_16x16x32_bf16 v[100:103], v[174:177], v[240:243], v[100:103]
	v_mfma_f32_16x16x32_bf16 v[104:107], v[186:189], v[232:235], v[104:107]
	v_mfma_f32_16x16x32_bf16 v[96:99], v[186:189], v[240:243], v[96:99]
	s_setprio 0
	s_setprio 1
	v_mfma_f32_16x16x32_bf16 v[60:63], v[190:193], v[212:215], v[60:63]
	v_mfma_f32_16x16x32_bf16 v[52:55], v[190:193], v[220:223], v[52:55]
	v_mfma_f32_16x16x32_bf16 v[56:59], v[198:201], v[212:215], v[56:59]
	v_mfma_f32_16x16x32_bf16 v[48:51], v[198:201], v[220:223], v[48:51]
	v_mfma_f32_16x16x32_bf16 v[44:47], v[190:193], v[228:231], v[44:47]
	v_mfma_f32_16x16x32_bf16 v[36:39], v[190:193], v[236:239], v[36:39]
	v_mfma_f32_16x16x32_bf16 v[40:43], v[198:201], v[228:231], v[40:43]
	v_mfma_f32_16x16x32_bf16 v[32:35], v[198:201], v[236:239], v[32:35]
	v_mfma_f32_16x16x32_bf16 v[60:63], v[194:197], v[216:219], v[60:63]
	v_mfma_f32_16x16x32_bf16 v[52:55], v[194:197], v[224:227], v[52:55]
	v_mfma_f32_16x16x32_bf16 v[56:59], v[208:211], v[216:219], v[56:59]
	v_mfma_f32_16x16x32_bf16 v[48:51], v[208:211], v[224:227], v[48:51]
	v_mfma_f32_16x16x32_bf16 v[44:47], v[194:197], v[232:235], v[44:47]
	v_mfma_f32_16x16x32_bf16 v[36:39], v[194:197], v[240:243], v[36:39]
	v_mfma_f32_16x16x32_bf16 v[40:43], v[208:211], v[232:235], v[40:43]
	v_mfma_f32_16x16x32_bf16 v[32:35], v[208:211], v[240:243], v[32:35]
	s_setprio 0
	s_barrier
	s_add_i32 s3, s94, s84
	v_lshl_add_u64 v[178:179], s[60:61], 0, v[130:131]
	s_mov_b32 m0, s3
	ds_read_b128 v[212:215], v164 offset:16384
	ds_read_b128 v[216:219], v164 offset:17408
	ds_read_b128 v[220:223], v164 offset:18432
	ds_read_b128 v[224:227], v164 offset:19456
	ds_read_b128 v[228:231], v164 offset:20480
	ds_read_b128 v[232:235], v164 offset:21504
	ds_read_b128 v[236:239], v164 offset:22528
	ds_read_b128 v[240:243], v164 offset:23552
	global_load_lds_dwordx4 v[178:179], off
	s_add_i32 m0, s3, 0x2000
	s_add_u32 s14, s60, 0x40000
	v_lshl_add_u64 v[202:203], s[60:61], 0, v[134:135]
	s_addc_u32 s15, s61, 0
	s_add_i32 s3, s95, s84
	global_load_lds_dwordx4 v[202:203], off
	v_lshl_add_u64 v[244:245], s[14:15], 0, v[130:131]
	s_mov_b32 m0, s3
	global_load_lds_dwordx4 v[244:245], off
	v_lshl_add_u64 v[244:245], s[14:15], 0, v[134:135]
	s_add_i32 m0, s3, 0x2000
	s_nop 0
	global_load_lds_dwordx4 v[244:245], off
	s_waitcnt vmcnt(6)
	s_waitcnt lgkmcnt(0)
	s_barrier
	s_setprio 1
	s_waitcnt lgkmcnt(0)
	v_mfma_f32_16x16x32_bf16 v[92:95], v[170:173], v[212:215], v[92:95]
	v_mfma_f32_16x16x32_bf16 v[84:87], v[170:173], v[220:223], v[84:87]
	v_mfma_f32_16x16x32_bf16 v[88:91], v[182:185], v[212:215], v[88:91]
	v_mfma_f32_16x16x32_bf16 v[80:83], v[182:185], v[220:223], v[80:83]
	v_mfma_f32_16x16x32_bf16 v[76:79], v[170:173], v[228:231], v[76:79]
	v_mfma_f32_16x16x32_bf16 v[68:71], v[170:173], v[236:239], v[68:71]
	v_mfma_f32_16x16x32_bf16 v[72:75], v[182:185], v[228:231], v[72:75]
	v_mfma_f32_16x16x32_bf16 v[64:67], v[182:185], v[236:239], v[64:67]
	v_mfma_f32_16x16x32_bf16 v[92:95], v[174:177], v[216:219], v[92:95]
	v_mfma_f32_16x16x32_bf16 v[84:87], v[174:177], v[224:227], v[84:87]
	v_mfma_f32_16x16x32_bf16 v[88:91], v[186:189], v[216:219], v[88:91]
	v_mfma_f32_16x16x32_bf16 v[80:83], v[186:189], v[224:227], v[80:83]
	v_mfma_f32_16x16x32_bf16 v[76:79], v[174:177], v[232:235], v[76:79]
	v_mfma_f32_16x16x32_bf16 v[68:71], v[174:177], v[240:243], v[68:71]
	v_lshl_add_u64 v[244:245], s[62:63], 0, v[128:129]
	s_mov_b32 m0, s85
	s_nop 0
	global_load_lds_dwordx4 v[244:245], off
	v_mfma_f32_16x16x32_bf16 v[72:75], v[186:189], v[232:235], v[72:75]
	v_mfma_f32_16x16x32_bf16 v[64:67], v[186:189], v[240:243], v[64:67]
	s_setprio 0
	s_setprio 1
	v_mfma_f32_16x16x32_bf16 v[28:31], v[190:193], v[212:215], v[28:31]
	v_mfma_f32_16x16x32_bf16 v[20:23], v[190:193], v[220:223], v[20:23]
	v_mfma_f32_16x16x32_bf16 v[24:27], v[198:201], v[212:215], v[24:27]
	v_mfma_f32_16x16x32_bf16 v[16:19], v[198:201], v[220:223], v[16:19]
	v_mfma_f32_16x16x32_bf16 v[12:15], v[190:193], v[228:231], v[12:15]
	v_mfma_f32_16x16x32_bf16 v[4:7], v[190:193], v[236:239], v[4:7]
	v_mfma_f32_16x16x32_bf16 v[8:11], v[198:201], v[228:231], v[8:11]
	v_mfma_f32_16x16x32_bf16 v[0:3], v[198:201], v[236:239], v[0:3]
	v_mfma_f32_16x16x32_bf16 v[28:31], v[194:197], v[216:219], v[28:31]
	v_mfma_f32_16x16x32_bf16 v[20:23], v[194:197], v[224:227], v[20:23]
	v_mfma_f32_16x16x32_bf16 v[24:27], v[208:211], v[216:219], v[24:27]
	v_mfma_f32_16x16x32_bf16 v[16:19], v[208:211], v[224:227], v[16:19]
	v_mfma_f32_16x16x32_bf16 v[12:15], v[194:197], v[232:235], v[12:15]
	v_mfma_f32_16x16x32_bf16 v[4:7], v[194:197], v[240:243], v[4:7]
	v_lshl_add_u64 v[246:247], s[62:63], 0, v[132:133]
	s_mov_b32 m0, s86
	s_nop 0
	global_load_lds_dwordx4 v[246:247], off
	v_mfma_f32_16x16x32_bf16 v[8:11], v[208:211], v[232:235], v[8:11]
	v_mfma_f32_16x16x32_bf16 v[0:3], v[208:211], v[240:243], v[0:3]
	s_setprio 0
	s_barrier
; #define PG8_STAGE(bufoff, gbase, voff) do { _Pragma("unroll") for (int _i = 0; _i < 2; ++_i) \
;         __builtin_amdgcn_global_load_lds((const unsigned*)((const char*)(gbase) + (voff)[_i]), (PG8_LAS unsigned*)(lds + (bufoff) + ldsw + _i * 8192), 16, 0, 0); } while (0)
; #define PG8_LDA(dst, b, h) do { _Pragma("unroll") for (int m = 0; m < 4; ++m) _Pragma("unroll") for (int k = 0; k < 2; ++k) dst[m][k] = *(const PG8_LAS bf16x8*)(lds + PG8_SA(b, h) + aoff + m * 2048 + k * 1024); } while (0)
; #define PG8_LDB(dst, b, h) do { _Pragma("unroll") for (int n = 0; n < 2; ++n) _Pragma("unroll") for (int k = 0; k < 2; ++k) dst[n][k] = *(const PG8_LAS bf16x8*)(lds + PG8_SB(b, h) + boff + n * 2048 + k * 1024); } while (0)
; #define PG8_MMA(ai, bj, At, Bt) do { __builtin_amdgcn_s_setprio(1); _Pragma("unroll") for (int m = 0; m < 4; ++m) _Pragma("unroll") for (int n = 0; n < 2; ++n) _Pragma("unroll") for (int k = 0; k < 2; ++k) \
;         acc[ai][bj][m][n] = __builtin_amdgcn_mfma_f32_16x16x32_bf16(Bt[n][k], At[m][k], acc[ai][bj][m][n], 0, 0, 0); __builtin_amdgcn_s_setprio(0); } while (0)
; #define PG8_WAIT_V(n) asm volatile("s_waitcnt vmcnt(" #n ")" ::: "memory")
; #define PG8_WAIT_L(n) asm volatile("s_waitcnt lgkmcnt(" #n ")" ::: "memory")
; #define PG8_BAR __builtin_amdgcn_s_barrier()
; #define PG8_SCHED __builtin_amdgcn_sched_barrier(0)
; template <class Epi, class Sched, bool ALIGN_EPI = false, bool SP2 = false>
; __device__ __forceinline__ void gemm_phase(PG8_LAS unsigned char* lds, const Gemm g, const Sched& S, const Epi& E) {
;     ...
;             PG8_LDB(B0, 1, 0); PG8_LDB(B1, 1, 1); PG8_SCHED; PG8_LDA(At, 1, 0); PG8_STAGE(PG8_SA(0, 1), a2 + hstep, voffA);
;             PG8_WAIT_V(8); PG8_WAIT_L(0); PG8_BAR; PG8_MMA(0, 0, At, B0); PG8_MMA(0, 1, At, B1); PG8_BAR; PG8_SCHED;
	s_add_i32 s3, 0, 0x18000
	v_add_u32_e32 v136, s3, v141
	s_add_i32 s33, 0, 0x1c000
	ds_read_b128 v[170:173], v136
	ds_read_b128 v[174:177], v136 offset:1024
	ds_read_b128 v[182:185], v136 offset:2048
	ds_read_b128 v[186:189], v136 offset:3072
	v_add_u32_e32 v136, s33, v141
	ds_read_b128 v[190:193], v136
	ds_read_b128 v[194:197], v136 offset:1024
	ds_read_b128 v[198:201], v136 offset:2048
	ds_read_b128 v[208:211], v136 offset:3072
	s_add_u32 s14, s62, 0x40000
	s_addc_u32 s15, s63, 0
	s_mov_b32 m0, s87
	v_lshl_add_u64 v[248:249], s[14:15], 0, v[128:129]
	ds_read_b128 v[212:215], v164 offset:32768
	ds_read_b128 v[216:219], v164 offset:33792
	ds_read_b128 v[220:223], v164 offset:34816
	ds_read_b128 v[224:227], v164 offset:35840
	ds_read_b128 v[228:231], v164 offset:36864
	ds_read_b128 v[232:235], v164 offset:37888
	ds_read_b128 v[236:239], v164 offset:38912
	ds_read_b128 v[240:243], v164 offset:39936
	global_load_lds_dwordx4 v[248:249], off
	v_lshl_add_u64 v[248:249], s[14:15], 0, v[132:133]
	s_mov_b32 m0, s88
	s_nop 0
	global_load_lds_dwordx4 v[248:249], off
	s_waitcnt vmcnt(8)
	s_waitcnt lgkmcnt(0)
	s_barrier
	s_setprio 1
	s_waitcnt lgkmcnt(0)
	v_mfma_f32_16x16x32_bf16 v[124:127], v[170:173], v[212:215], v[124:127]
	v_mfma_f32_16x16x32_bf16 v[116:119], v[170:173], v[220:223], v[116:119]
	v_mfma_f32_16x16x32_bf16 v[120:123], v[182:185], v[212:215], v[120:123]
	v_mfma_f32_16x16x32_bf16 v[112:115], v[182:185], v[220:223], v[112:115]
	v_mfma_f32_16x16x32_bf16 v[108:111], v[170:173], v[228:231], v[108:111]
	v_mfma_f32_16x16x32_bf16 v[100:103], v[170:173], v[236:239], v[100:103]
	v_mfma_f32_16x16x32_bf16 v[104:107], v[182:185], v[228:231], v[104:107]
	v_mfma_f32_16x16x32_bf16 v[96:99], v[182:185], v[236:239], v[96:99]
	v_mfma_f32_16x16x32_bf16 v[124:127], v[174:177], v[216:219], v[124:127]
	v_mfma_f32_16x16x32_bf16 v[116:119], v[174:177], v[224:227], v[116:119]
	v_mfma_f32_16x16x32_bf16 v[120:123], v[186:189], v[216:219], v[120:123]
	v_mfma_f32_16x16x32_bf16 v[112:115], v[186:189], v[224:227], v[112:115]
	v_mfma_f32_16x16x32_bf16 v[108:111], v[174:177], v[232:235], v[108:111]
	v_mfma_f32_16x16x32_bf16 v[100:103], v[174:177], v[240:243], v[100:103]
	v_mfma_f32_16x16x32_bf16 v[104:107], v[186:189], v[232:235], v[104:107]
	v_mfma_f32_16x16x32_bf16 v[96:99], v[186:189], v[240:243], v[96:99]
	s_setprio 0
	s_setprio 1
	v_mfma_f32_16x16x32_bf16 v[60:63], v[190:193], v[212:215], v[60:63]
	v_mfma_f32_16x16x32_bf16 v[52:55], v[190:193], v[220:223], v[52:55]
	v_mfma_f32_16x16x32_bf16 v[56:59], v[198:201], v[212:215], v[56:59]
	v_mfma_f32_16x16x32_bf16 v[48:51], v[198:201], v[220:223], v[48:51]
	v_mfma_f32_16x16x32_bf16 v[44:47], v[190:193], v[228:231], v[44:47]
	v_mfma_f32_16x16x32_bf16 v[36:39], v[190:193], v[236:239], v[36:39]
	v_mfma_f32_16x16x32_bf16 v[40:43], v[198:201], v[228:231], v[40:43]
	v_mfma_f32_16x16x32_bf16 v[32:35], v[198:201], v[236:239], v[32:35]
	v_mfma_f32_16x16x32_bf16 v[60:63], v[194:197], v[216:219], v[60:63]
	v_mfma_f32_16x16x32_bf16 v[52:55], v[194:197], v[224:227], v[52:55]
	v_mfma_f32_16x16x32_bf16 v[56:59], v[208:211], v[216:219], v[56:59]
	v_mfma_f32_16x16x32_bf16 v[48:51], v[208:211], v[224:227], v[48:51]
	v_mfma_f32_16x16x32_bf16 v[44:47], v[194:197], v[232:235], v[44:47]
	v_mfma_f32_16x16x32_bf16 v[36:39], v[194:197], v[240:243], v[36:39]
	v_mfma_f32_16x16x32_bf16 v[40:43], v[208:211], v[232:235], v[40:43]
	v_mfma_f32_16x16x32_bf16 v[32:35], v[208:211], v[240:243], v[32:35]
	s_setprio 0
	s_barrier
; #define PG8_STAGE(bufoff, gbase, voff) do { _Pragma("unroll") for (int _i = 0; _i < 2; ++_i) \
;         __builtin_amdgcn_global_load_lds((const unsigned*)((const char*)(gbase) + (voff)[_i]), (PG8_LAS unsigned*)(lds + (bufoff) + ldsw + _i * 8192), 16, 0, 0); } while (0)
; #define PG8_LDA(dst, b, h) do { _Pragma("unroll") for (int m = 0; m < 4; ++m) _Pragma("unroll") for (int k = 0; k < 2; ++k) dst[m][k] = *(const PG8_LAS bf16x8*)(lds + PG8_SA(b, h) + aoff + m * 2048 + k * 1024); } while (0)
; #define PG8_MMA(ai, bj, At, Bt) do { __builtin_amdgcn_s_setprio(1); _Pragma("unroll") for (int m = 0; m < 4; ++m) _Pragma("unroll") for (int n = 0; n < 2; ++n) _Pragma("unroll") for (int k = 0; k < 2; ++k) \
;         acc[ai][bj][m][n] = __builtin_amdgcn_mfma_f32_16x16x32_bf16(Bt[n][k], At[m][k], acc[ai][bj][m][n], 0, 0, 0); __builtin_amdgcn_s_setprio(0); } while (0)
; #define PG8_WAIT_V(n) asm volatile("s_waitcnt vmcnt(" #n ")" ::: "memory")
; #define PG8_WAIT_L(n) asm volatile("s_waitcnt lgkmcnt(" #n ")" ::: "memory")
; #define PG8_BAR __builtin_amdgcn_s_barrier()
; #define PG8_SCHED __builtin_amdgcn_sched_barrier(0)
; template <class Epi, class Sched, bool ALIGN_EPI = false, bool SP2 = false>
; __device__ __forceinline__ void gemm_phase(PG8_LAS unsigned char* lds, const Gemm g, const Sched& S, const Epi& E) {
;     ...
;             PG8_LDA(At, 1, 1); PG8_STAGE(PG8_SB(1, 0), b3, voffB); PG8_STAGE(PG8_SB(1, 1), b3 + hstep, voffB); PG8_STAGE(PG8_SA(1, 0), a3, voffA);
;             PG8_WAIT_V(8); PG8_WAIT_L(0); PG8_BAR; PG8_MMA(1, 0, At, B0); PG8_MMA(1, 1, At, B1); PG8_BAR; PG8_SCHED;
;     ...
;         if constexpr (ALIGN_EPI) { if (wr == 0) PG8_BAR; }
	s_add_i32 s3, s3, s84
	v_lshl_add_u64 v[178:179], v[178:179], 0, s[8:9]
	s_mov_b32 m0, s3
	ds_read_b128 v[212:215], v164 offset:49152
	ds_read_b128 v[216:219], v164 offset:50176
	ds_read_b128 v[220:223], v164 offset:51200
	ds_read_b128 v[224:227], v164 offset:52224
	ds_read_b128 v[228:231], v164 offset:53248
	ds_read_b128 v[232:235], v164 offset:54272
	ds_read_b128 v[236:239], v164 offset:55296
	ds_read_b128 v[240:243], v164 offset:56320
	global_load_lds_dwordx4 v[178:179], off
	s_add_i32 m0, s3, 0x2000
	s_add_u32 s14, s60, 0x40080
	v_lshl_add_u64 v[178:179], v[202:203], 0, s[8:9]
	s_addc_u32 s15, s61, 0
	s_add_i32 s3, s33, s84
	global_load_lds_dwordx4 v[178:179], off
	v_lshl_add_u64 v[178:179], s[14:15], 0, v[130:131]
	s_mov_b32 m0, s3
	s_nop 0
	global_load_lds_dwordx4 v[178:179], off
	v_lshl_add_u64 v[178:179], s[14:15], 0, v[134:135]
	s_add_i32 m0, s3, 0x2000
	s_nop 0
	global_load_lds_dwordx4 v[178:179], off
	s_waitcnt vmcnt(6)
	s_waitcnt lgkmcnt(0)
	s_barrier
	s_setprio 1
	s_waitcnt lgkmcnt(0)
	v_mfma_f32_16x16x32_bf16 v[92:95], v[170:173], v[212:215], v[92:95]
	v_mfma_f32_16x16x32_bf16 v[84:87], v[170:173], v[220:223], v[84:87]
	v_mfma_f32_16x16x32_bf16 v[88:91], v[182:185], v[212:215], v[88:91]
	v_mfma_f32_16x16x32_bf16 v[80:83], v[182:185], v[220:223], v[80:83]
	v_mfma_f32_16x16x32_bf16 v[76:79], v[170:173], v[228:231], v[76:79]
	v_mfma_f32_16x16x32_bf16 v[68:71], v[170:173], v[236:239], v[68:71]
	v_mfma_f32_16x16x32_bf16 v[72:75], v[182:185], v[228:231], v[72:75]
	v_mfma_f32_16x16x32_bf16 v[64:67], v[182:185], v[236:239], v[64:67]
	v_mfma_f32_16x16x32_bf16 v[92:95], v[174:177], v[216:219], v[92:95]
	v_mfma_f32_16x16x32_bf16 v[84:87], v[174:177], v[224:227], v[84:87]
	v_mfma_f32_16x16x32_bf16 v[88:91], v[186:189], v[216:219], v[88:91]
	v_mfma_f32_16x16x32_bf16 v[80:83], v[186:189], v[224:227], v[80:83]
	v_mfma_f32_16x16x32_bf16 v[76:79], v[174:177], v[232:235], v[76:79]
	v_mfma_f32_16x16x32_bf16 v[68:71], v[174:177], v[240:243], v[68:71]
	v_lshl_add_u64 v[178:179], v[244:245], 0, s[8:9]
	s_mov_b32 m0, s90
	s_nop 0
	global_load_lds_dwordx4 v[178:179], off
	v_mfma_f32_16x16x32_bf16 v[72:75], v[186:189], v[232:235], v[72:75]
	v_mfma_f32_16x16x32_bf16 v[64:67], v[186:189], v[240:243], v[64:67]
	s_setprio 0
	s_setprio 1
	v_mfma_f32_16x16x32_bf16 v[28:31], v[190:193], v[212:215], v[28:31]
	v_mfma_f32_16x16x32_bf16 v[20:23], v[190:193], v[220:223], v[20:23]
	v_mfma_f32_16x16x32_bf16 v[24:27], v[198:201], v[212:215], v[24:27]
	v_mfma_f32_16x16x32_bf16 v[16:19], v[198:201], v[220:223], v[16:19]
	v_mfma_f32_16x16x32_bf16 v[12:15], v[190:193], v[228:231], v[12:15]
	v_mfma_f32_16x16x32_bf16 v[4:7], v[190:193], v[236:239], v[4:7]
	v_mfma_f32_16x16x32_bf16 v[8:11], v[198:201], v[228:231], v[8:11]
	v_mfma_f32_16x16x32_bf16 v[0:3], v[198:201], v[236:239], v[0:3]
	v_mfma_f32_16x16x32_bf16 v[28:31], v[194:197], v[216:219], v[28:31]
	v_mfma_f32_16x16x32_bf16 v[20:23], v[194:197], v[224:227], v[20:23]
	v_mfma_f32_16x16x32_bf16 v[24:27], v[208:211], v[216:219], v[24:27]
	v_mfma_f32_16x16x32_bf16 v[16:19], v[208:211], v[224:227], v[16:19]
	v_mfma_f32_16x16x32_bf16 v[12:15], v[194:197], v[232:235], v[12:15]
	v_mfma_f32_16x16x32_bf16 v[4:7], v[194:197], v[240:243], v[4:7]
	v_lshl_add_u64 v[178:179], v[246:247], 0, s[8:9]
	s_mov_b32 m0, s91
	s_nop 0
	global_load_lds_dwordx4 v[178:179], off
	v_mfma_f32_16x16x32_bf16 v[8:11], v[208:211], v[232:235], v[8:11]
	v_mfma_f32_16x16x32_bf16 v[0:3], v[208:211], v[240:243], v[0:3]
	s_setprio 0
	s_barrier
	s_add_i32 vcc_lo, vcc_lo, 2
	s_add_u32 s58, s58, 0x100
	s_addc_u32 s59, s59, 0
	s_add_u32 s96, s96, 0x100
	s_addc_u32 s97, s97, 0
	s_cmp_gt_u32 vcc_lo, 13
	s_cbranch_scc0 .LBB0_459
	s_and_b64 vcc, exec, s[10:11]
	s_cbranch_vccz .LBB0_462
	s_barrier

; #define PG8_STAGE(bufoff, gbase, voff) do { _Pragma("unroll") for (int _i = 0; _i < 2; ++_i) \
;         __builtin_amdgcn_global_load_lds((const unsigned*)((const char*)(gbase) + (voff)[_i]), (PG8_LAS unsigned*)(lds + (bufoff) + ldsw + _i * 8192), 16, 0, 0); } while (0)
; #define PG8_LDA(dst, b, h) do { _Pragma("unroll") for (int m = 0; m < 4; ++m) _Pragma("unroll") for (int k = 0; k < 2; ++k) dst[m][k] = *(const PG8_LAS bf16x8*)(lds + PG8_SA(b, h) + aoff + m * 2048 + k * 1024); } while (0)
; #define PG8_LDB(dst, b, h) do { _Pragma("unroll") for (int n = 0; n < 2; ++n) _Pragma("unroll") for (int k = 0; k < 2; ++k) dst[n][k] = *(const PG8_LAS bf16x8*)(lds + PG8_SB(b, h) + boff + n * 2048 + k * 1024); } while (0)
; #define PG8_MMA(ai, bj, At, Bt) do { __builtin_amdgcn_s_setprio(1); _Pragma("unroll") for (int m = 0; m < 4; ++m) _Pragma("unroll") for (int n = 0; n < 2; ++n) _Pragma("unroll") for (int k = 0; k < 2; ++k) \
;         acc[ai][bj][m][n] = __builtin_amdgcn_mfma_f32_16x16x32_bf16(Bt[n][k], At[m][k], acc[ai][bj][m][n], 0, 0, 0); __builtin_amdgcn_s_setprio(0); } while (0)
; #define PG8_WAIT_V(n) asm volatile("s_waitcnt vmcnt(" #n ")" ::: "memory")
; #define PG8_WAIT_L(n) asm volatile("s_waitcnt lgkmcnt(" #n ")" ::: "memory")
; #define PG8_BAR __builtin_amdgcn_s_barrier()
; #define PG8_SCHED __builtin_amdgcn_sched_barrier(0)
; template <class Epi, class Sched, bool ALIGN_EPI = false, bool SP2 = false>
; __device__ __forceinline__ void gemm_phase(PG8_LAS unsigned char* lds, const Gemm g, const Sched& S, const Epi& E) {
;     ...
;             PG8_LDB(B0, 0, 0); PG8_LDB(B1, 0, 1); PG8_SCHED; PG8_LDA(At, 0, 0); PG8_STAGE(PG8_SA(1, 1), a1 + hstep, voffA);
;             PG8_WAIT_V(8); PG8_WAIT_L(0); PG8_BAR; PG8_MMA(0, 0, At, B0); PG8_MMA(0, 1, At, B1); PG8_BAR; PG8_SCHED;
;             PG8_LDA(At, 0, 1); PG8_STAGE(PG8_SB(0, 0), b2, voffB); PG8_STAGE(PG8_SB(0, 1), b2 + hstep, voffB); PG8_STAGE(PG8_SA(0, 0), a2, voffA);
;             PG8_WAIT_V(8); PG8_WAIT_L(0); PG8_BAR; PG8_MMA(1, 0, At, B0); PG8_MMA(1, 1, At, B1); PG8_BAR; PG8_SCHED;
.LBB0_495:
	ds_read_b128 v[170:173], v165
	ds_read_b128 v[174:177], v165 offset:1024
	ds_read_b128 v[182:185], v165 offset:2048
	ds_read_b128 v[186:189], v165 offset:3072
	ds_read_b128 v[190:193], v168
	ds_read_b128 v[194:197], v168 offset:1024
	ds_read_b128 v[198:201], v168 offset:2048
	ds_read_b128 v[208:211], v168 offset:3072
	s_add_u32 s3, s60, 0xfffc0080
	s_addc_u32 s14, s61, -1
	s_cmp_eq_u32 s97, 12
	s_cselect_b32 s65, s49, s14
	s_cselect_b32 s64, s57, s3
	s_cselect_b32 s63, s45, s96
	s_cselect_b32 s62, s94, s95
	v_lshl_add_u64 v[178:179], s[60:61], 0, v[160:161]
	s_add_i32 m0, s59, 0xc000
	ds_read_b128 v[212:215], v164
	ds_read_b128 v[216:219], v164 offset:1024
	ds_read_b128 v[220:223], v164 offset:2048
	ds_read_b128 v[224:227], v164 offset:3072
	ds_read_b128 v[228:231], v164 offset:4096
	ds_read_b128 v[232:235], v164 offset:5120
	ds_read_b128 v[236:239], v164 offset:6144
	ds_read_b128 v[240:243], v164 offset:7168
	global_load_lds_dwordx4 v[178:179], off
	v_lshl_add_u64 v[178:179], s[60:61], 0, v[162:163]
	s_add_i32 m0, s59, 0xe000
	s_nop 0
	global_load_lds_dwordx4 v[178:179], off
	s_waitcnt vmcnt(8)
	s_waitcnt lgkmcnt(0)
	s_barrier
	s_setprio 1
	s_waitcnt lgkmcnt(0)
	v_mfma_f32_16x16x32_bf16 v[124:127], v[170:173], v[212:215], v[124:127]
	v_mfma_f32_16x16x32_bf16 v[116:119], v[170:173], v[220:223], v[116:119]
	v_mfma_f32_16x16x32_bf16 v[120:123], v[182:185], v[212:215], v[120:123]
	v_mfma_f32_16x16x32_bf16 v[112:115], v[182:185], v[220:223], v[112:115]
	v_mfma_f32_16x16x32_bf16 v[108:111], v[170:173], v[228:231], v[108:111]
	v_mfma_f32_16x16x32_bf16 v[100:103], v[170:173], v[236:239], v[100:103]
	v_mfma_f32_16x16x32_bf16 v[104:107], v[182:185], v[228:231], v[104:107]
	v_mfma_f32_16x16x32_bf16 v[96:99], v[182:185], v[236:239], v[96:99]
	v_mfma_f32_16x16x32_bf16 v[124:127], v[174:177], v[216:219], v[124:127]
	v_mfma_f32_16x16x32_bf16 v[116:119], v[174:177], v[224:227], v[116:119]
	v_mfma_f32_16x16x32_bf16 v[120:123], v[186:189], v[216:219], v[120:123]
	v_mfma_f32_16x16x32_bf16 v[112:115], v[186:189], v[224:227], v[112:115]
	v_mfma_f32_16x16x32_bf16 v[108:111], v[174:177], v[232:235], v[108:111]
	v_mfma_f32_16x16x32_bf16 v[100:103], v[174:177], v[240:243], v[100:103]
	v_mfma_f32_16x16x32_bf16 v[104:107], v[186:189], v[232:235], v[104:107]
	v_mfma_f32_16x16x32_bf16 v[96:99], v[186:189], v[240:243], v[96:99]
	s_setprio 0
	s_setprio 1
	v_mfma_f32_16x16x32_bf16 v[60:63], v[190:193], v[212:215], v[60:63]
	v_mfma_f32_16x16x32_bf16 v[52:55], v[190:193], v[220:223], v[52:55]
	v_mfma_f32_16x16x32_bf16 v[56:59], v[198:201], v[212:215], v[56:59]
	v_mfma_f32_16x16x32_bf16 v[48:51], v[198:201], v[220:223], v[48:51]
	v_mfma_f32_16x16x32_bf16 v[44:47], v[190:193], v[228:231], v[44:47]
	v_mfma_f32_16x16x32_bf16 v[36:39], v[190:193], v[236:239], v[36:39]
	v_mfma_f32_16x16x32_bf16 v[40:43], v[198:201], v[228:231], v[40:43]
	v_mfma_f32_16x16x32_bf16 v[32:35], v[198:201], v[236:239], v[32:35]
	v_mfma_f32_16x16x32_bf16 v[60:63], v[194:197], v[216:219], v[60:63]
	v_mfma_f32_16x16x32_bf16 v[52:55], v[194:197], v[224:227], v[52:55]
	v_mfma_f32_16x16x32_bf16 v[56:59], v[208:211], v[216:219], v[56:59]
	v_mfma_f32_16x16x32_bf16 v[48:51], v[208:211], v[224:227], v[48:51]
	v_mfma_f32_16x16x32_bf16 v[44:47], v[194:197], v[232:235], v[44:47]
	v_mfma_f32_16x16x32_bf16 v[36:39], v[194:197], v[240:243], v[36:39]
	v_mfma_f32_16x16x32_bf16 v[40:43], v[208:211], v[232:235], v[40:43]
	v_mfma_f32_16x16x32_bf16 v[32:35], v[208:211], v[240:243], v[32:35]
	s_setprio 0
	s_barrier
	s_add_i32 s3, s92, s75
	v_lshl_add_u64 v[178:179], s[62:63], 0, v[130:131]
	s_mov_b32 m0, s3
	ds_read_b128 v[212:215], v164 offset:16384
	ds_read_b128 v[216:219], v164 offset:17408
	ds_read_b128 v[220:223], v164 offset:18432
	ds_read_b128 v[224:227], v164 offset:19456
	ds_read_b128 v[228:231], v164 offset:20480
	ds_read_b128 v[232:235], v164 offset:21504
	ds_read_b128 v[236:239], v164 offset:22528
	ds_read_b128 v[240:243], v164 offset:23552
	global_load_lds_dwordx4 v[178:179], off
	s_add_i32 m0, s3, 0x2000
	s_add_u32 s14, s62, 0x40000
	v_lshl_add_u64 v[202:203], s[62:63], 0, v[134:135]
	s_addc_u32 s15, s63, 0
	s_add_i32 s3, s93, s75
	global_load_lds_dwordx4 v[202:203], off
	v_lshl_add_u64 v[244:245], s[14:15], 0, v[130:131]
	s_mov_b32 m0, s3
	global_load_lds_dwordx4 v[244:245], off
	v_lshl_add_u64 v[244:245], s[14:15], 0, v[134:135]
	s_add_i32 m0, s3, 0x2000
	s_nop 0
	global_load_lds_dwordx4 v[244:245], off
	s_waitcnt vmcnt(6)
	s_waitcnt lgkmcnt(0)
	s_barrier
; #define PG8_STAGE(bufoff, gbase, voff) do { _Pragma("unroll") for (int _i = 0; _i < 2; ++_i) \
;         __builtin_amdgcn_global_load_lds((const unsigned*)((const char*)(gbase) + (voff)[_i]), (PG8_LAS unsigned*)(lds + (bufoff) + ldsw + _i * 8192), 16, 0, 0); } while (0)
; #define PG8_LDA(dst, b, h) do { _Pragma("unroll") for (int m = 0; m < 4; ++m) _Pragma("unroll") for (int k = 0; k < 2; ++k) dst[m][k] = *(const PG8_LAS bf16x8*)(lds + PG8_SA(b, h) + aoff + m * 2048 + k * 1024); } while (0)
; #define PG8_LDB(dst, b, h) do { _Pragma("unroll") for (int n = 0; n < 2; ++n) _Pragma("unroll") for (int k = 0; k < 2; ++k) dst[n][k] = *(const PG8_LAS bf16x8*)(lds + PG8_SB(b, h) + boff + n * 2048 + k * 1024); } while (0)
; #define PG8_MMA(ai, bj, At, Bt) do { __builtin_amdgcn_s_setprio(1); _Pragma("unroll") for (int m = 0; m < 4; ++m) _Pragma("unroll") for (int n = 0; n < 2; ++n) _Pragma("unroll") for (int k = 0; k < 2; ++k) \
;         acc[ai][bj][m][n] = __builtin_amdgcn_mfma_f32_16x16x32_bf16(Bt[n][k], At[m][k], acc[ai][bj][m][n], 0, 0, 0); __builtin_amdgcn_s_setprio(0); } while (0)
; #define PG8_WAIT_V(n) asm volatile("s_waitcnt vmcnt(" #n ")" ::: "memory")
; #define PG8_WAIT_L(n) asm volatile("s_waitcnt lgkmcnt(" #n ")" ::: "memory")
; #define PG8_BAR __builtin_amdgcn_s_barrier()
; #define PG8_SCHED __builtin_amdgcn_sched_barrier(0)
; template <class Epi, class Sched, bool ALIGN_EPI = false, bool SP2 = false>
; __device__ __forceinline__ void gemm_phase(PG8_LAS unsigned char* lds, const Gemm g, const Sched& S, const Epi& E) {
;     ...
;             PG8_WAIT_V(8); PG8_WAIT_L(0); PG8_BAR; PG8_MMA(1, 0, At, B0); PG8_MMA(1, 1, At, B1); PG8_BAR; PG8_SCHED;
;             PG8_LDB(B0, 1, 0); PG8_LDB(B1, 1, 1); PG8_SCHED; PG8_LDA(At, 1, 0); PG8_STAGE(PG8_SA(0, 1), a2 + hstep, voffA);
;             PG8_WAIT_V(8); PG8_WAIT_L(0); PG8_BAR; PG8_MMA(0, 0, At, B0); PG8_MMA(0, 1, At, B1); PG8_BAR; PG8_SCHED;
	s_setprio 1
	s_waitcnt lgkmcnt(0)
	v_mfma_f32_16x16x32_bf16 v[92:95], v[170:173], v[212:215], v[92:95]
	v_mfma_f32_16x16x32_bf16 v[84:87], v[170:173], v[220:223], v[84:87]
	v_mfma_f32_16x16x32_bf16 v[88:91], v[182:185], v[212:215], v[88:91]
	v_mfma_f32_16x16x32_bf16 v[80:83], v[182:185], v[220:223], v[80:83]
	v_mfma_f32_16x16x32_bf16 v[76:79], v[170:173], v[228:231], v[76:79]
	v_mfma_f32_16x16x32_bf16 v[68:71], v[170:173], v[236:239], v[68:71]
	v_mfma_f32_16x16x32_bf16 v[72:75], v[182:185], v[228:231], v[72:75]
	v_mfma_f32_16x16x32_bf16 v[64:67], v[182:185], v[236:239], v[64:67]
	v_mfma_f32_16x16x32_bf16 v[92:95], v[174:177], v[216:219], v[92:95]
	v_mfma_f32_16x16x32_bf16 v[84:87], v[174:177], v[224:227], v[84:87]
	v_mfma_f32_16x16x32_bf16 v[88:91], v[186:189], v[216:219], v[88:91]
	v_mfma_f32_16x16x32_bf16 v[80:83], v[186:189], v[224:227], v[80:83]
	v_mfma_f32_16x16x32_bf16 v[76:79], v[174:177], v[232:235], v[76:79]
	v_mfma_f32_16x16x32_bf16 v[68:71], v[174:177], v[240:243], v[68:71]
	v_lshl_add_u64 v[244:245], s[64:65], 0, v[128:129]
	s_mov_b32 m0, s59
	s_nop 0
	global_load_lds_dwordx4 v[244:245], off
	v_mfma_f32_16x16x32_bf16 v[72:75], v[186:189], v[232:235], v[72:75]
	v_mfma_f32_16x16x32_bf16 v[64:67], v[186:189], v[240:243], v[64:67]
	s_setprio 0
	s_setprio 1
	v_mfma_f32_16x16x32_bf16 v[28:31], v[190:193], v[212:215], v[28:31]
	v_mfma_f32_16x16x32_bf16 v[20:23], v[190:193], v[220:223], v[20:23]
	v_mfma_f32_16x16x32_bf16 v[24:27], v[198:201], v[212:215], v[24:27]
	v_mfma_f32_16x16x32_bf16 v[16:19], v[198:201], v[220:223], v[16:19]
	v_mfma_f32_16x16x32_bf16 v[12:15], v[190:193], v[228:231], v[12:15]
	v_mfma_f32_16x16x32_bf16 v[4:7], v[190:193], v[236:239], v[4:7]
	v_mfma_f32_16x16x32_bf16 v[8:11], v[198:201], v[228:231], v[8:11]
	v_mfma_f32_16x16x32_bf16 v[0:3], v[198:201], v[236:239], v[0:3]
	v_mfma_f32_16x16x32_bf16 v[28:31], v[194:197], v[216:219], v[28:31]
	v_mfma_f32_16x16x32_bf16 v[20:23], v[194:197], v[224:227], v[20:23]
	v_mfma_f32_16x16x32_bf16 v[24:27], v[208:211], v[216:219], v[24:27]
	v_mfma_f32_16x16x32_bf16 v[16:19], v[208:211], v[224:227], v[16:19]
	v_mfma_f32_16x16x32_bf16 v[12:15], v[194:197], v[232:235], v[12:15]
	v_mfma_f32_16x16x32_bf16 v[4:7], v[194:197], v[240:243], v[4:7]
	v_lshl_add_u64 v[246:247], s[64:65], 0, v[132:133]
	s_mov_b32 m0, s84
	s_nop 0
	global_load_lds_dwordx4 v[246:247], off
	v_mfma_f32_16x16x32_bf16 v[8:11], v[208:211], v[232:235], v[8:11]
	v_mfma_f32_16x16x32_bf16 v[0:3], v[208:211], v[240:243], v[0:3]
	s_setprio 0
	s_barrier
	s_add_i32 s3, 0, 0x18000
	v_add_u32_e32 v136, s3, v141
	s_add_i32 s33, 0, 0x1c000
	ds_read_b128 v[170:173], v136
	ds_read_b128 v[174:177], v136 offset:1024
	ds_read_b128 v[182:185], v136 offset:2048
	ds_read_b128 v[186:189], v136 offset:3072
	v_add_u32_e32 v136, s33, v141
	ds_read_b128 v[190:193], v136
	ds_read_b128 v[194:197], v136 offset:1024
	ds_read_b128 v[198:201], v136 offset:2048
	ds_read_b128 v[208:211], v136 offset:3072
	s_add_u32 s14, s64, 0x40000
	s_addc_u32 s15, s65, 0
	s_mov_b32 m0, s85
	v_lshl_add_u64 v[248:249], s[14:15], 0, v[128:129]
	ds_read_b128 v[212:215], v164 offset:32768
	ds_read_b128 v[216:219], v164 offset:33792
	ds_read_b128 v[220:223], v164 offset:34816
	ds_read_b128 v[224:227], v164 offset:35840
	ds_read_b128 v[228:231], v164 offset:36864
	ds_read_b128 v[232:235], v164 offset:37888
	ds_read_b128 v[236:239], v164 offset:38912
	ds_read_b128 v[240:243], v164 offset:39936
	global_load_lds_dwordx4 v[248:249], off
	v_lshl_add_u64 v[248:249], s[14:15], 0, v[132:133]
	s_mov_b32 m0, s86
	s_nop 0
	global_load_lds_dwordx4 v[248:249], off
	s_waitcnt vmcnt(8)
	s_waitcnt lgkmcnt(0)
	s_barrier
	s_setprio 1
	s_waitcnt lgkmcnt(0)
	v_mfma_f32_16x16x32_bf16 v[124:127], v[170:173], v[212:215], v[124:127]
	v_mfma_f32_16x16x32_bf16 v[116:119], v[170:173], v[220:223], v[116:119]
	v_mfma_f32_16x16x32_bf16 v[120:123], v[182:185], v[212:215], v[120:123]
	v_mfma_f32_16x16x32_bf16 v[112:115], v[182:185], v[220:223], v[112:115]
	v_mfma_f32_16x16x32_bf16 v[108:111], v[170:173], v[228:231], v[108:111]
	v_mfma_f32_16x16x32_bf16 v[100:103], v[170:173], v[236:239], v[100:103]
	v_mfma_f32_16x16x32_bf16 v[104:107], v[182:185], v[228:231], v[104:107]
	v_mfma_f32_16x16x32_bf16 v[96:99], v[182:185], v[236:239], v[96:99]
	v_mfma_f32_16x16x32_bf16 v[124:127], v[174:177], v[216:219], v[124:127]
	v_mfma_f32_16x16x32_bf16 v[116:119], v[174:177], v[224:227], v[116:119]
	v_mfma_f32_16x16x32_bf16 v[120:123], v[186:189], v[216:219], v[120:123]
	v_mfma_f32_16x16x32_bf16 v[112:115], v[186:189], v[224:227], v[112:115]
	v_mfma_f32_16x16x32_bf16 v[108:111], v[174:177], v[232:235], v[108:111]
	v_mfma_f32_16x16x32_bf16 v[100:103], v[174:177], v[240:243], v[100:103]
	v_mfma_f32_16x16x32_bf16 v[104:107], v[186:189], v[232:235], v[104:107]
	v_mfma_f32_16x16x32_bf16 v[96:99], v[186:189], v[240:243], v[96:99]
	s_setprio 0
	s_setprio 1
	v_mfma_f32_16x16x32_bf16 v[60:63], v[190:193], v[212:215], v[60:63]
	v_mfma_f32_16x16x32_bf16 v[52:55], v[190:193], v[220:223], v[52:55]
	v_mfma_f32_16x16x32_bf16 v[56:59], v[198:201], v[212:215], v[56:59]
	v_mfma_f32_16x16x32_bf16 v[48:51], v[198:201], v[220:223], v[48:51]
	v_mfma_f32_16x16x32_bf16 v[44:47], v[190:193], v[228:231], v[44:47]
	v_mfma_f32_16x16x32_bf16 v[36:39], v[190:193], v[236:239], v[36:39]
	v_mfma_f32_16x16x32_bf16 v[40:43], v[198:201], v[228:231], v[40:43]
	v_mfma_f32_16x16x32_bf16 v[32:35], v[198:201], v[236:239], v[32:35]
	v_mfma_f32_16x16x32_bf16 v[60:63], v[194:197], v[216:219], v[60:63]
	v_mfma_f32_16x16x32_bf16 v[52:55], v[194:197], v[224:227], v[52:55]
	v_mfma_f32_16x16x32_bf16 v[56:59], v[208:211], v[216:219], v[56:59]
	v_mfma_f32_16x16x32_bf16 v[48:51], v[208:211], v[224:227], v[48:51]
	v_mfma_f32_16x16x32_bf16 v[44:47], v[194:197], v[232:235], v[44:47]
	v_mfma_f32_16x16x32_bf16 v[36:39], v[194:197], v[240:243], v[36:39]
	v_mfma_f32_16x16x32_bf16 v[40:43], v[208:211], v[232:235], v[40:43]
	v_mfma_f32_16x16x32_bf16 v[32:35], v[208:211], v[240:243], v[32:35]
	s_setprio 0
	s_barrier
; #define PG8_STAGE(bufoff, gbase, voff) do { _Pragma("unroll") for (int _i = 0; _i < 2; ++_i) \
;         __builtin_amdgcn_global_load_lds((const unsigned*)((const char*)(gbase) + (voff)[_i]), (PG8_LAS unsigned*)(lds + (bufoff) + ldsw + _i * 8192), 16, 0, 0); } while (0)
; #define PG8_LDA(dst, b, h) do { _Pragma("unroll") for (int m = 0; m < 4; ++m) _Pragma("unroll") for (int k = 0; k < 2; ++k) dst[m][k] = *(const PG8_LAS bf16x8*)(lds + PG8_SA(b, h) + aoff + m * 2048 + k * 1024); } while (0)
; #define PG8_MMA(ai, bj, At, Bt) do { __builtin_amdgcn_s_setprio(1); _Pragma("unroll") for (int m = 0; m < 4; ++m) _Pragma("unroll") for (int n = 0; n < 2; ++n) _Pragma("unroll") for (int k = 0; k < 2; ++k) \
;         acc[ai][bj][m][n] = __builtin_amdgcn_mfma_f32_16x16x32_bf16(Bt[n][k], At[m][k], acc[ai][bj][m][n], 0, 0, 0); __builtin_amdgcn_s_setprio(0); } while (0)
; #define PG8_WAIT_V(n) asm volatile("s_waitcnt vmcnt(" #n ")" ::: "memory")
; #define PG8_WAIT_L(n) asm volatile("s_waitcnt lgkmcnt(" #n ")" ::: "memory")
; #define PG8_BAR __builtin_amdgcn_s_barrier()
; #define PG8_SCHED __builtin_amdgcn_sched_barrier(0)
; template <class Epi, class Sched, bool ALIGN_EPI = false, bool SP2 = false>
; __device__ __forceinline__ void gemm_phase(PG8_LAS unsigned char* lds, const Gemm g, const Sched& S, const Epi& E) {
;     ...
;             PG8_LDA(At, 1, 1); PG8_STAGE(PG8_SB(1, 0), b3, voffB); PG8_STAGE(PG8_SB(1, 1), b3 + hstep, voffB); PG8_STAGE(PG8_SA(1, 0), a3, voffA);
;             PG8_WAIT_V(8); PG8_WAIT_L(0); PG8_BAR; PG8_MMA(1, 0, At, B0); PG8_MMA(1, 1, At, B1); PG8_BAR; PG8_SCHED;
	s_add_i32 s3, s3, s75
	v_lshl_add_u64 v[178:179], v[178:179], 0, s[10:11]
	s_mov_b32 m0, s3
	ds_read_b128 v[212:215], v164 offset:49152
	ds_read_b128 v[216:219], v164 offset:50176
	ds_read_b128 v[220:223], v164 offset:51200
	ds_read_b128 v[224:227], v164 offset:52224
	ds_read_b128 v[228:231], v164 offset:53248
	ds_read_b128 v[232:235], v164 offset:54272
	ds_read_b128 v[236:239], v164 offset:55296
	ds_read_b128 v[240:243], v164 offset:56320
	global_load_lds_dwordx4 v[178:179], off
	s_add_i32 m0, s3, 0x2000
	s_add_u32 s14, s62, 0x40080
	v_lshl_add_u64 v[178:179], v[202:203], 0, s[10:11]
	s_addc_u32 s15, s63, 0
	s_add_i32 s3, s33, s75
	global_load_lds_dwordx4 v[178:179], off
	v_lshl_add_u64 v[178:179], s[14:15], 0, v[130:131]
	s_mov_b32 m0, s3
	s_nop 0
	global_load_lds_dwordx4 v[178:179], off
	v_lshl_add_u64 v[178:179], s[14:15], 0, v[134:135]
	s_add_i32 m0, s3, 0x2000
	s_nop 0
	global_load_lds_dwordx4 v[178:179], off
	s_waitcnt vmcnt(6)
	s_waitcnt lgkmcnt(0)
	s_barrier
	s_setprio 1
	s_waitcnt lgkmcnt(0)
	v_mfma_f32_16x16x32_bf16 v[92:95], v[170:173], v[212:215], v[92:95]
	v_mfma_f32_16x16x32_bf16 v[84:87], v[170:173], v[220:223], v[84:87]
	v_mfma_f32_16x16x32_bf16 v[88:91], v[182:185], v[212:215], v[88:91]
	v_mfma_f32_16x16x32_bf16 v[80:83], v[182:185], v[220:223], v[80:83]
	v_mfma_f32_16x16x32_bf16 v[76:79], v[170:173], v[228:231], v[76:79]
	v_mfma_f32_16x16x32_bf16 v[68:71], v[170:173], v[236:239], v[68:71]
	v_mfma_f32_16x16x32_bf16 v[72:75], v[182:185], v[228:231], v[72:75]
	v_mfma_f32_16x16x32_bf16 v[64:67], v[182:185], v[236:239], v[64:67]
	v_mfma_f32_16x16x32_bf16 v[92:95], v[174:177], v[216:219], v[92:95]
	v_mfma_f32_16x16x32_bf16 v[84:87], v[174:177], v[224:227], v[84:87]
	v_mfma_f32_16x16x32_bf16 v[88:91], v[186:189], v[216:219], v[88:91]
	v_mfma_f32_16x16x32_bf16 v[80:83], v[186:189], v[224:227], v[80:83]
	v_mfma_f32_16x16x32_bf16 v[76:79], v[174:177], v[232:235], v[76:79]
	v_mfma_f32_16x16x32_bf16 v[68:71], v[174:177], v[240:243], v[68:71]
	v_lshl_add_u64 v[178:179], v[244:245], 0, s[10:11]
	s_mov_b32 m0, s88
	s_nop 0
	global_load_lds_dwordx4 v[178:179], off
	v_mfma_f32_16x16x32_bf16 v[72:75], v[186:189], v[232:235], v[72:75]
	v_mfma_f32_16x16x32_bf16 v[64:67], v[186:189], v[240:243], v[64:67]
	s_setprio 0
	s_setprio 1
	v_mfma_f32_16x16x32_bf16 v[28:31], v[190:193], v[212:215], v[28:31]
	v_mfma_f32_16x16x32_bf16 v[20:23], v[190:193], v[220:223], v[20:23]
	v_mfma_f32_16x16x32_bf16 v[24:27], v[198:201], v[212:215], v[24:27]
	v_mfma_f32_16x16x32_bf16 v[16:19], v[198:201], v[220:223], v[16:19]
	v_mfma_f32_16x16x32_bf16 v[12:15], v[190:193], v[228:231], v[12:15]
	v_mfma_f32_16x16x32_bf16 v[4:7], v[190:193], v[236:239], v[4:7]
	v_mfma_f32_16x16x32_bf16 v[8:11], v[198:201], v[228:231], v[8:11]
	v_mfma_f32_16x16x32_bf16 v[0:3], v[198:201], v[236:239], v[0:3]
	v_mfma_f32_16x16x32_bf16 v[28:31], v[194:197], v[216:219], v[28:31]
	v_mfma_f32_16x16x32_bf16 v[20:23], v[194:197], v[224:227], v[20:23]
	v_mfma_f32_16x16x32_bf16 v[24:27], v[208:211], v[216:219], v[24:27]
	v_mfma_f32_16x16x32_bf16 v[16:19], v[208:211], v[224:227], v[16:19]
	v_mfma_f32_16x16x32_bf16 v[12:15], v[194:197], v[232:235], v[12:15]
	v_mfma_f32_16x16x32_bf16 v[4:7], v[194:197], v[240:243], v[4:7]
	v_lshl_add_u64 v[178:179], v[246:247], 0, s[10:11]
	s_mov_b32 m0, s89
	s_nop 0
	global_load_lds_dwordx4 v[178:179], off
	v_mfma_f32_16x16x32_bf16 v[8:11], v[208:211], v[232:235], v[8:11]
	v_mfma_f32_16x16x32_bf16 v[0:3], v[208:211], v[240:243], v[0:3]
	s_setprio 0
	s_barrier
	s_add_i32 s97, s97, 2
	s_add_u32 s60, s60, 0x100
	s_addc_u32 s61, s61, 0
	s_add_u32 s95, s95, 0x100
	s_addc_u32 s96, s96, 0
	s_cmp_lt_u32 s97, 14
	s_cbranch_scc1 .LBB0_495
	s_andn2_b64 vcc, exec, s[40:41]
	s_cbranch_vccnz .LBB0_498
	s_barrier

; #define PG8_STAGE(bufoff, gbase, voff) do { _Pragma("unroll") for (int _i = 0; _i < 2; ++_i) \
;         __builtin_amdgcn_global_load_lds((const unsigned*)((const char*)(gbase) + (voff)[_i]), (PG8_LAS unsigned*)(lds + (bufoff) + ldsw + _i * 8192), 16, 0, 0); } while (0)
; #define PG8_LDA(dst, b, h) do { _Pragma("unroll") for (int m = 0; m < 4; ++m) _Pragma("unroll") for (int k = 0; k < 2; ++k) dst[m][k] = *(const PG8_LAS bf16x8*)(lds + PG8_SA(b, h) + aoff + m * 2048 + k * 1024); } while (0)
; #define PG8_LDB(dst, b, h) do { _Pragma("unroll") for (int n = 0; n < 2; ++n) _Pragma("unroll") for (int k = 0; k < 2; ++k) dst[n][k] = *(const PG8_LAS bf16x8*)(lds + PG8_SB(b, h) + boff + n * 2048 + k * 1024); } while (0)
; #define PG8_MMA(ai, bj, At, Bt) do { __builtin_amdgcn_s_setprio(1); _Pragma("unroll") for (int m = 0; m < 4; ++m) _Pragma("unroll") for (int n = 0; n < 2; ++n) _Pragma("unroll") for (int k = 0; k < 2; ++k) \
;         acc[ai][bj][m][n] = __builtin_amdgcn_mfma_f32_16x16x32_bf16(Bt[n][k], At[m][k], acc[ai][bj][m][n], 0, 0, 0); __builtin_amdgcn_s_setprio(0); } while (0)
; #define PG8_BAR __builtin_amdgcn_s_barrier()
; template <class Epi, class Sched, bool ALIGN_EPI = false, bool SP2 = false>
; __device__ __forceinline__ void gemm_phase(PG8_LAS unsigned char* lds, const Gemm g, const Sched& S, const Epi& E) {
;     ...
;         const bool has_next = S.next(ui + 1, nxt);
;         const char* nA = has_next ? (const char*)g.A + (size_t)nxt.pm * tstep : cA; const char* nB = has_next ? (const char*)g.Bt + (size_t)nxt.pn * tstep : cB;
;         for (int t = 0; t < nt; t += 2) {
;             const bool last = (t == nt - 2);
;             const char* a1 = cA + (size_t)(t + 1) * kstep;
;             const char* a2 = last ? nA : cA + (size_t)(t + 2) * kstep; const char* b2 = last ? nB : cB + (size_t)(t + 2) * kstep;
;             const char* a3 = a2 + kstep; const char* b3 = b2 + kstep;
;             if (last && has_next) S.a_ready(nxt);
;             if constexpr (SP2) {
;             PG8_LDB(B0, 0, 0); PG8_LDB(B1, 0, 1); PG8_SCHED; PG8_LDA(At, 0, 0); PG8_STAGE(PG8_SA(1, 1), a1 + hstep, voffA);
;             PG8_WAIT_V(8); PG8_WAIT_L(0); PG8_BAR; PG8_MMA(0, 0, At, B0); PG8_MMA(0, 1, At, B1); PG8_BAR; PG8_SCHED;
;             PG8_LDA(At, 0, 1); PG8_STAGE(PG8_SB(0, 0), b2, voffB); PG8_STAGE(PG8_SB(0, 1), b2 + hstep, voffB); PG8_STAGE(PG8_SA(0, 0), a2, voffA);
.LBB0_649:
	s_ashr_i32 s51, s50, 31
	s_lshl_b64 s[14:15], s[50:51], 19
	s_add_u32 s52, s40, s14
	s_addc_u32 s53, s41, s15
	s_and_b64 s[14:15], s[8:9], exec
	s_cselect_b32 s51, s53, s61
	s_cselect_b32 s57, s52, s60
	s_ashr_i32 s49, s48, 31
	s_lshl_b64 s[14:15], s[48:49], 19
	s_add_u32 s54, s82, s14
	s_addc_u32 s55, s83, s15
	s_and_b64 s[14:15], s[8:9], exec
	s_cselect_b32 s49, s55, s63
	s_cselect_b32 s89, s54, s62
	s_add_u32 s60, s60, 0x40080
	s_addc_u32 s61, s61, 0
	s_add_u32 s90, s62, 0x100
	s_addc_u32 s91, s63, 0
	s_mov_b32 s92, -2
	s_waitcnt lgkmcnt(0)
	s_waitcnt vmcnt(0)
	ds_read_b128 v[148:151], v155
	ds_read_b128 v[160:163], v155 offset:1024
	ds_read_b128 v[164:167], v155 offset:2048
	ds_read_b128 v[168:171], v155 offset:3072
	ds_read_b128 v[172:175], v156
	ds_read_b128 v[176:179], v156 offset:1024
	ds_read_b128 v[182:185], v156 offset:2048
	ds_read_b128 v[186:189], v156 offset:3072
	s_add_u32 s3, s60, 0xfffc0080
	s_addc_u32 s14, s61, -1
	s_cmp_eq_u32 s92, 12
	s_cselect_b32 s65, s51, s14
	s_cselect_b32 s64, s57, s3
	s_cselect_b32 s63, s49, s91
	s_cselect_b32 s62, s89, s90
	v_lshl_add_u64 v[202:203], s[60:61], 0, v[140:141]
	s_add_i32 m0, s43, 0xc000
	ds_read_b128 v[190:193], v157
	ds_read_b128 v[194:197], v157 offset:1024
	ds_read_b128 v[198:201], v157 offset:2048
	ds_read_b128 v[208:211], v157 offset:3072
	ds_read_b128 v[212:215], v157 offset:4096
	ds_read_b128 v[216:219], v157 offset:5120
	ds_read_b128 v[220:223], v157 offset:6144
	ds_read_b128 v[224:227], v157 offset:7168
	global_load_lds_dwordx4 v[202:203], off
	v_lshl_add_u64 v[202:203], s[60:61], 0, v[142:143]
	s_add_i32 m0, s43, 0xe000
	s_nop 0
	global_load_lds_dwordx4 v[202:203], off
	s_waitcnt vmcnt(8)
	s_waitcnt lgkmcnt(0)
	s_barrier
	s_setprio 1
	s_waitcnt lgkmcnt(0)
	v_mfma_f32_16x16x32_bf16 v[124:127], v[148:151], v[190:193], 0
	v_mfma_f32_16x16x32_bf16 v[108:111], v[148:151], v[198:201], 0
	v_mfma_f32_16x16x32_bf16 v[120:123], v[164:167], v[190:193], 0
	v_mfma_f32_16x16x32_bf16 v[104:107], v[164:167], v[198:201], 0
	v_mfma_f32_16x16x32_bf16 v[92:95], v[148:151], v[212:215], 0
	v_mfma_f32_16x16x32_bf16 v[76:79], v[148:151], v[220:223], 0
	v_mfma_f32_16x16x32_bf16 v[88:91], v[164:167], v[212:215], 0
	v_mfma_f32_16x16x32_bf16 v[72:75], v[164:167], v[220:223], 0
	v_mfma_f32_16x16x32_bf16 v[124:127], v[160:163], v[194:197], v[124:127]
	v_mfma_f32_16x16x32_bf16 v[108:111], v[160:163], v[208:211], v[108:111]
	v_mfma_f32_16x16x32_bf16 v[120:123], v[168:171], v[194:197], v[120:123]
	v_mfma_f32_16x16x32_bf16 v[104:107], v[168:171], v[208:211], v[104:107]
	v_mfma_f32_16x16x32_bf16 v[92:95], v[160:163], v[216:219], v[92:95]
	v_mfma_f32_16x16x32_bf16 v[76:79], v[160:163], v[224:227], v[76:79]
	v_mfma_f32_16x16x32_bf16 v[88:91], v[168:171], v[216:219], v[88:91]
	v_mfma_f32_16x16x32_bf16 v[72:75], v[168:171], v[224:227], v[72:75]
	s_setprio 0
	s_setprio 1
	v_mfma_f32_16x16x32_bf16 v[116:119], v[172:175], v[190:193], 0
	v_mfma_f32_16x16x32_bf16 v[100:103], v[172:175], v[198:201], 0
	v_mfma_f32_16x16x32_bf16 v[112:115], v[182:185], v[190:193], 0
	v_mfma_f32_16x16x32_bf16 v[96:99], v[182:185], v[198:201], 0
	v_mfma_f32_16x16x32_bf16 v[84:87], v[172:175], v[212:215], 0
	v_mfma_f32_16x16x32_bf16 v[68:71], v[172:175], v[220:223], 0
	v_mfma_f32_16x16x32_bf16 v[80:83], v[182:185], v[212:215], 0
	v_mfma_f32_16x16x32_bf16 v[64:67], v[182:185], v[220:223], 0
	v_mfma_f32_16x16x32_bf16 v[116:119], v[176:179], v[194:197], v[116:119]
	v_mfma_f32_16x16x32_bf16 v[100:103], v[176:179], v[208:211], v[100:103]
	v_mfma_f32_16x16x32_bf16 v[112:115], v[186:189], v[194:197], v[112:115]
	v_mfma_f32_16x16x32_bf16 v[96:99], v[186:189], v[208:211], v[96:99]
	v_mfma_f32_16x16x32_bf16 v[84:87], v[176:179], v[216:219], v[84:87]
	v_mfma_f32_16x16x32_bf16 v[68:71], v[176:179], v[224:227], v[68:71]
	v_mfma_f32_16x16x32_bf16 v[80:83], v[186:189], v[216:219], v[80:83]
	v_mfma_f32_16x16x32_bf16 v[64:67], v[186:189], v[224:227], v[64:67]
	s_setprio 0
	s_barrier
	s_add_i32 s3, s85, s34
	v_lshl_add_u64 v[202:203], s[62:63], 0, v[134:135]
	s_mov_b32 m0, s3
	ds_read_b128 v[190:193], v157 offset:16384
	ds_read_b128 v[194:197], v157 offset:17408
	ds_read_b128 v[198:201], v157 offset:18432
	ds_read_b128 v[208:211], v157 offset:19456
	ds_read_b128 v[212:215], v157 offset:20480
	ds_read_b128 v[216:219], v157 offset:21504
	ds_read_b128 v[220:223], v157 offset:22528
	ds_read_b128 v[224:227], v157 offset:23552
	global_load_lds_dwordx4 v[202:203], off
	s_add_i32 m0, s3, 0x2000
	s_add_u32 s14, s62, 0x40000
	v_lshl_add_u64 v[228:229], s[62:63], 0, v[138:139]
	s_addc_u32 s15, s63, 0
	s_add_i32 s3, s86, s34
	global_load_lds_dwordx4 v[228:229], off
	v_lshl_add_u64 v[230:231], s[14:15], 0, v[134:135]
	s_mov_b32 m0, s3
	global_load_lds_dwordx4 v[230:231], off
	v_lshl_add_u64 v[230:231], s[14:15], 0, v[138:139]
	s_add_i32 m0, s3, 0x2000
	s_nop 0
	global_load_lds_dwordx4 v[230:231], off
	s_waitcnt vmcnt(6)
	s_waitcnt lgkmcnt(0)
	s_barrier
; #define PG8_STAGE(bufoff, gbase, voff) do { _Pragma("unroll") for (int _i = 0; _i < 2; ++_i) \
;         __builtin_amdgcn_global_load_lds((const unsigned*)((const char*)(gbase) + (voff)[_i]), (PG8_LAS unsigned*)(lds + (bufoff) + ldsw + _i * 8192), 16, 0, 0); } while (0)
; #define PG8_LDA(dst, b, h) do { _Pragma("unroll") for (int m = 0; m < 4; ++m) _Pragma("unroll") for (int k = 0; k < 2; ++k) dst[m][k] = *(const PG8_LAS bf16x8*)(lds + PG8_SA(b, h) + aoff + m * 2048 + k * 1024); } while (0)
; #define PG8_LDB(dst, b, h) do { _Pragma("unroll") for (int n = 0; n < 2; ++n) _Pragma("unroll") for (int k = 0; k < 2; ++k) dst[n][k] = *(const PG8_LAS bf16x8*)(lds + PG8_SB(b, h) + boff + n * 2048 + k * 1024); } while (0)
; #define PG8_MMA(ai, bj, At, Bt) do { __builtin_amdgcn_s_setprio(1); _Pragma("unroll") for (int m = 0; m < 4; ++m) _Pragma("unroll") for (int n = 0; n < 2; ++n) _Pragma("unroll") for (int k = 0; k < 2; ++k) \
;         acc[ai][bj][m][n] = __builtin_amdgcn_mfma_f32_16x16x32_bf16(Bt[n][k], At[m][k], acc[ai][bj][m][n], 0, 0, 0); __builtin_amdgcn_s_setprio(0); } while (0)
; #define PG8_WAIT_V(n) asm volatile("s_waitcnt vmcnt(" #n ")" ::: "memory")
; #define PG8_WAIT_L(n) asm volatile("s_waitcnt lgkmcnt(" #n ")" ::: "memory")
; #define PG8_BAR __builtin_amdgcn_s_barrier()
; #define PG8_SCHED __builtin_amdgcn_sched_barrier(0)
; template <class Epi, class Sched, bool ALIGN_EPI = false, bool SP2 = false>
; __device__ __forceinline__ void gemm_phase(PG8_LAS unsigned char* lds, const Gemm g, const Sched& S, const Epi& E) {
;     ...
;             PG8_WAIT_V(8); PG8_WAIT_L(0); PG8_BAR; PG8_MMA(1, 0, At, B0); PG8_MMA(1, 1, At, B1); PG8_BAR; PG8_SCHED;
;             PG8_LDB(B0, 1, 0); PG8_LDB(B1, 1, 1); PG8_SCHED; PG8_LDA(At, 1, 0); PG8_STAGE(PG8_SA(0, 1), a2 + hstep, voffA);
;             PG8_WAIT_V(8); PG8_WAIT_L(0); PG8_BAR; PG8_MMA(0, 0, At, B0); PG8_MMA(0, 1, At, B1); PG8_BAR; PG8_SCHED;
	s_setprio 1
	s_waitcnt lgkmcnt(0)
	v_mfma_f32_16x16x32_bf16 v[60:63], v[148:151], v[190:193], 0
	v_mfma_f32_16x16x32_bf16 v[44:47], v[148:151], v[198:201], 0
	v_mfma_f32_16x16x32_bf16 v[56:59], v[164:167], v[190:193], 0
	v_mfma_f32_16x16x32_bf16 v[40:43], v[164:167], v[198:201], 0
	v_mfma_f32_16x16x32_bf16 v[28:31], v[148:151], v[212:215], 0
	v_mfma_f32_16x16x32_bf16 v[12:15], v[148:151], v[220:223], 0
	v_mfma_f32_16x16x32_bf16 v[24:27], v[164:167], v[212:215], 0
	v_mfma_f32_16x16x32_bf16 v[8:11], v[164:167], v[220:223], 0
	v_mfma_f32_16x16x32_bf16 v[60:63], v[160:163], v[194:197], v[60:63]
	v_mfma_f32_16x16x32_bf16 v[44:47], v[160:163], v[208:211], v[44:47]
	v_mfma_f32_16x16x32_bf16 v[56:59], v[168:171], v[194:197], v[56:59]
	v_mfma_f32_16x16x32_bf16 v[40:43], v[168:171], v[208:211], v[40:43]
	v_mfma_f32_16x16x32_bf16 v[28:31], v[160:163], v[216:219], v[28:31]
	v_mfma_f32_16x16x32_bf16 v[12:15], v[160:163], v[224:227], v[12:15]
	v_lshl_add_u64 v[230:231], s[64:65], 0, v[132:133]
	s_mov_b32 m0, s43
	s_nop 0
	global_load_lds_dwordx4 v[230:231], off
	v_mfma_f32_16x16x32_bf16 v[24:27], v[168:171], v[216:219], v[24:27]
	v_mfma_f32_16x16x32_bf16 v[8:11], v[168:171], v[224:227], v[8:11]
	s_setprio 0
	s_setprio 1
	v_mfma_f32_16x16x32_bf16 v[52:55], v[172:175], v[190:193], 0
	v_mfma_f32_16x16x32_bf16 v[36:39], v[172:175], v[198:201], 0
	v_mfma_f32_16x16x32_bf16 v[48:51], v[182:185], v[190:193], 0
	v_mfma_f32_16x16x32_bf16 v[32:35], v[182:185], v[198:201], 0
	v_mfma_f32_16x16x32_bf16 v[20:23], v[172:175], v[212:215], 0
	v_mfma_f32_16x16x32_bf16 v[4:7], v[172:175], v[220:223], 0
	v_mfma_f32_16x16x32_bf16 v[16:19], v[182:185], v[212:215], 0
	v_mfma_f32_16x16x32_bf16 v[0:3], v[182:185], v[220:223], 0
	v_mfma_f32_16x16x32_bf16 v[52:55], v[176:179], v[194:197], v[52:55]
	v_mfma_f32_16x16x32_bf16 v[36:39], v[176:179], v[208:211], v[36:39]
	v_mfma_f32_16x16x32_bf16 v[48:51], v[186:189], v[194:197], v[48:51]
	v_mfma_f32_16x16x32_bf16 v[32:35], v[186:189], v[208:211], v[32:35]
	v_mfma_f32_16x16x32_bf16 v[20:23], v[176:179], v[216:219], v[20:23]
	v_mfma_f32_16x16x32_bf16 v[4:7], v[176:179], v[224:227], v[4:7]
	v_lshl_add_u64 v[232:233], s[64:65], 0, v[136:137]
	s_mov_b32 m0, s59
	s_nop 0
	global_load_lds_dwordx4 v[232:233], off
	v_mfma_f32_16x16x32_bf16 v[16:19], v[186:189], v[216:219], v[16:19]
	v_mfma_f32_16x16x32_bf16 v[0:3], v[186:189], v[224:227], v[0:3]
	s_setprio 0
	s_barrier
	s_add_i32 s3, 0, 0x18000
	v_add_u32_e32 v159, s3, v131
	s_add_i32 s33, 0, 0x1c000
	ds_read_b128 v[148:151], v159
	ds_read_b128 v[160:163], v159 offset:1024
	ds_read_b128 v[164:167], v159 offset:2048
	ds_read_b128 v[168:171], v159 offset:3072
	v_add_u32_e32 v159, s33, v131
	ds_read_b128 v[172:175], v159
	ds_read_b128 v[176:179], v159 offset:1024
	ds_read_b128 v[182:185], v159 offset:2048
	ds_read_b128 v[186:189], v159 offset:3072
	s_add_u32 s14, s64, 0x40000
	s_addc_u32 s15, s65, 0
	s_mov_b32 m0, s66
	v_lshl_add_u64 v[234:235], s[14:15], 0, v[132:133]
	ds_read_b128 v[190:193], v157 offset:32768
	ds_read_b128 v[194:197], v157 offset:33792
	ds_read_b128 v[198:201], v157 offset:34816
	ds_read_b128 v[208:211], v157 offset:35840
	ds_read_b128 v[212:215], v157 offset:36864
	ds_read_b128 v[216:219], v157 offset:37888
	ds_read_b128 v[220:223], v157 offset:38912
	ds_read_b128 v[224:227], v157 offset:39936
	global_load_lds_dwordx4 v[234:235], off
	v_lshl_add_u64 v[234:235], s[14:15], 0, v[136:137]
	s_mov_b32 m0, s67
	s_nop 0
	global_load_lds_dwordx4 v[234:235], off
	s_waitcnt vmcnt(8)
	s_waitcnt lgkmcnt(0)
	s_barrier
	s_setprio 1
	s_waitcnt lgkmcnt(0)
	v_mfma_f32_16x16x32_bf16 v[124:127], v[148:151], v[190:193], v[124:127]
	v_mfma_f32_16x16x32_bf16 v[108:111], v[148:151], v[198:201], v[108:111]
	v_mfma_f32_16x16x32_bf16 v[120:123], v[164:167], v[190:193], v[120:123]
	v_mfma_f32_16x16x32_bf16 v[104:107], v[164:167], v[198:201], v[104:107]
	v_mfma_f32_16x16x32_bf16 v[92:95], v[148:151], v[212:215], v[92:95]
	v_mfma_f32_16x16x32_bf16 v[76:79], v[148:151], v[220:223], v[76:79]
	v_mfma_f32_16x16x32_bf16 v[88:91], v[164:167], v[212:215], v[88:91]
	v_mfma_f32_16x16x32_bf16 v[72:75], v[164:167], v[220:223], v[72:75]
	v_mfma_f32_16x16x32_bf16 v[124:127], v[160:163], v[194:197], v[124:127]
	v_mfma_f32_16x16x32_bf16 v[108:111], v[160:163], v[208:211], v[108:111]
	v_mfma_f32_16x16x32_bf16 v[120:123], v[168:171], v[194:197], v[120:123]
	v_mfma_f32_16x16x32_bf16 v[104:107], v[168:171], v[208:211], v[104:107]
	v_mfma_f32_16x16x32_bf16 v[92:95], v[160:163], v[216:219], v[92:95]
	v_mfma_f32_16x16x32_bf16 v[76:79], v[160:163], v[224:227], v[76:79]
	v_mfma_f32_16x16x32_bf16 v[88:91], v[168:171], v[216:219], v[88:91]
	v_mfma_f32_16x16x32_bf16 v[72:75], v[168:171], v[224:227], v[72:75]
	s_setprio 0
	s_setprio 1
	v_mfma_f32_16x16x32_bf16 v[116:119], v[172:175], v[190:193], v[116:119]
	v_mfma_f32_16x16x32_bf16 v[100:103], v[172:175], v[198:201], v[100:103]
	v_mfma_f32_16x16x32_bf16 v[112:115], v[182:185], v[190:193], v[112:115]
	v_mfma_f32_16x16x32_bf16 v[96:99], v[182:185], v[198:201], v[96:99]
	v_mfma_f32_16x16x32_bf16 v[84:87], v[172:175], v[212:215], v[84:87]
	v_mfma_f32_16x16x32_bf16 v[68:71], v[172:175], v[220:223], v[68:71]
	v_mfma_f32_16x16x32_bf16 v[80:83], v[182:185], v[212:215], v[80:83]
	v_mfma_f32_16x16x32_bf16 v[64:67], v[182:185], v[220:223], v[64:67]
	v_mfma_f32_16x16x32_bf16 v[116:119], v[176:179], v[194:197], v[116:119]
	v_mfma_f32_16x16x32_bf16 v[100:103], v[176:179], v[208:211], v[100:103]
	v_mfma_f32_16x16x32_bf16 v[112:115], v[186:189], v[194:197], v[112:115]
	v_mfma_f32_16x16x32_bf16 v[96:99], v[186:189], v[208:211], v[96:99]
	v_mfma_f32_16x16x32_bf16 v[84:87], v[176:179], v[216:219], v[84:87]
	v_mfma_f32_16x16x32_bf16 v[68:71], v[176:179], v[224:227], v[68:71]
	v_mfma_f32_16x16x32_bf16 v[80:83], v[186:189], v[216:219], v[80:83]
	v_mfma_f32_16x16x32_bf16 v[64:67], v[186:189], v[224:227], v[64:67]
	s_setprio 0
	s_barrier
; #define PG8_STAGE(bufoff, gbase, voff) do { _Pragma("unroll") for (int _i = 0; _i < 2; ++_i) \
;         __builtin_amdgcn_global_load_lds((const unsigned*)((const char*)(gbase) + (voff)[_i]), (PG8_LAS unsigned*)(lds + (bufoff) + ldsw + _i * 8192), 16, 0, 0); } while (0)
; #define PG8_LDA(dst, b, h) do { _Pragma("unroll") for (int m = 0; m < 4; ++m) _Pragma("unroll") for (int k = 0; k < 2; ++k) dst[m][k] = *(const PG8_LAS bf16x8*)(lds + PG8_SA(b, h) + aoff + m * 2048 + k * 1024); } while (0)
; #define PG8_LDB(dst, b, h) do { _Pragma("unroll") for (int n = 0; n < 2; ++n) _Pragma("unroll") for (int k = 0; k < 2; ++k) dst[n][k] = *(const PG8_LAS bf16x8*)(lds + PG8_SB(b, h) + boff + n * 2048 + k * 1024); } while (0)
; #define PG8_MMA(ai, bj, At, Bt) do { __builtin_amdgcn_s_setprio(1); _Pragma("unroll") for (int m = 0; m < 4; ++m) _Pragma("unroll") for (int n = 0; n < 2; ++n) _Pragma("unroll") for (int k = 0; k < 2; ++k) \
;         acc[ai][bj][m][n] = __builtin_amdgcn_mfma_f32_16x16x32_bf16(Bt[n][k], At[m][k], acc[ai][bj][m][n], 0, 0, 0); __builtin_amdgcn_s_setprio(0); } while (0)
; #define PG8_WAIT_V(n) asm volatile("s_waitcnt vmcnt(" #n ")" ::: "memory")
; template <class Epi, class Sched, bool ALIGN_EPI = false, bool SP2 = false>
; __device__ __forceinline__ void gemm_phase(PG8_LAS unsigned char* lds, const Gemm g, const Sched& S, const Epi& E) {
;     ...
;             PG8_LDB(B0, 0, 0); PG8_LDB(B1, 0, 1); PG8_SCHED; PG8_LDA(At, 0, 0); PG8_STAGE(PG8_SA(1, 1), a1 + hstep, voffA);
;             PG8_WAIT_V(8); PG8_WAIT_L(0); PG8_BAR; PG8_MMA(0, 0, At, B0); PG8_MMA(0, 1, At, B1); PG8_BAR; PG8_SCHED;
;             PG8_LDA(At, 0, 1); PG8_STAGE(PG8_SB(0, 0), b2, voffB); PG8_STAGE(PG8_SB(0, 1), b2 + hstep, voffB); PG8_STAGE(PG8_SA(0, 0), a2, voffA);
;             PG8_WAIT_V(8); PG8_WAIT_L(0); PG8_BAR; PG8_MMA(1, 0, At, B0); PG8_MMA(1, 1, At, B1); PG8_BAR; PG8_SCHED;
;             PG8_LDB(B0, 1, 0); PG8_LDB(B1, 1, 1); PG8_SCHED; PG8_LDA(At, 1, 0); PG8_STAGE(PG8_SA(0, 1), a2 + hstep, voffA);
;             PG8_WAIT_V(8); PG8_WAIT_L(0); PG8_BAR; PG8_MMA(0, 0, At, B0); PG8_MMA(0, 1, At, B1); PG8_BAR; PG8_SCHED;
;             PG8_LDA(At, 1, 1); PG8_STAGE(PG8_SB(1, 0), b3, voffB); PG8_STAGE(PG8_SB(1, 1), b3 + hstep, voffB); PG8_STAGE(PG8_SA(1, 0), a3, voffA);
;             PG8_WAIT_V(8); PG8_WAIT_L(0); PG8_BAR; PG8_MMA(1, 0, At, B0); PG8_MMA(1, 1, At, B1); PG8_BAR; PG8_SCHED;
	s_add_i32 s3, s3, s34
	v_lshl_add_u64 v[202:203], v[202:203], 0, s[38:39]
	s_mov_b32 m0, s3
	ds_read_b128 v[190:193], v157 offset:49152
	ds_read_b128 v[194:197], v157 offset:50176
	ds_read_b128 v[198:201], v157 offset:51200
	ds_read_b128 v[208:211], v157 offset:52224
	ds_read_b128 v[212:215], v157 offset:53248
	ds_read_b128 v[216:219], v157 offset:54272
	ds_read_b128 v[220:223], v157 offset:55296
	ds_read_b128 v[224:227], v157 offset:56320
	global_load_lds_dwordx4 v[202:203], off
	s_add_i32 m0, s3, 0x2000
	s_add_u32 s14, s62, 0x40080
	v_lshl_add_u64 v[202:203], v[228:229], 0, s[38:39]
	s_addc_u32 s15, s63, 0
	s_add_i32 s3, s33, s34
	global_load_lds_dwordx4 v[202:203], off
	v_lshl_add_u64 v[202:203], s[14:15], 0, v[134:135]
	s_mov_b32 m0, s3
	s_nop 0
	global_load_lds_dwordx4 v[202:203], off
	v_lshl_add_u64 v[202:203], s[14:15], 0, v[138:139]
	s_add_i32 m0, s3, 0x2000
	s_nop 0
	global_load_lds_dwordx4 v[202:203], off
	s_waitcnt vmcnt(6)
	s_waitcnt lgkmcnt(0)
	s_barrier
	s_setprio 1
	s_waitcnt lgkmcnt(0)
	v_mfma_f32_16x16x32_bf16 v[60:63], v[148:151], v[190:193], v[60:63]
	v_mfma_f32_16x16x32_bf16 v[44:47], v[148:151], v[198:201], v[44:47]
	v_mfma_f32_16x16x32_bf16 v[56:59], v[164:167], v[190:193], v[56:59]
	v_mfma_f32_16x16x32_bf16 v[40:43], v[164:167], v[198:201], v[40:43]
	v_mfma_f32_16x16x32_bf16 v[28:31], v[148:151], v[212:215], v[28:31]
	v_mfma_f32_16x16x32_bf16 v[12:15], v[148:151], v[220:223], v[12:15]
	v_mfma_f32_16x16x32_bf16 v[24:27], v[164:167], v[212:215], v[24:27]
	v_mfma_f32_16x16x32_bf16 v[8:11], v[164:167], v[220:223], v[8:11]
	v_mfma_f32_16x16x32_bf16 v[60:63], v[160:163], v[194:197], v[60:63]
	v_mfma_f32_16x16x32_bf16 v[44:47], v[160:163], v[208:211], v[44:47]
	v_mfma_f32_16x16x32_bf16 v[56:59], v[168:171], v[194:197], v[56:59]
	v_mfma_f32_16x16x32_bf16 v[40:43], v[168:171], v[208:211], v[40:43]
	v_mfma_f32_16x16x32_bf16 v[28:31], v[160:163], v[216:219], v[28:31]
	v_mfma_f32_16x16x32_bf16 v[12:15], v[160:163], v[224:227], v[12:15]
	v_lshl_add_u64 v[202:203], v[230:231], 0, s[38:39]
	s_mov_b32 m0, s75
	s_nop 0
	global_load_lds_dwordx4 v[202:203], off
	v_mfma_f32_16x16x32_bf16 v[24:27], v[168:171], v[216:219], v[24:27]
	v_mfma_f32_16x16x32_bf16 v[8:11], v[168:171], v[224:227], v[8:11]
	s_setprio 0
	s_setprio 1
	v_mfma_f32_16x16x32_bf16 v[52:55], v[172:175], v[190:193], v[52:55]
	v_mfma_f32_16x16x32_bf16 v[36:39], v[172:175], v[198:201], v[36:39]
	v_mfma_f32_16x16x32_bf16 v[48:51], v[182:185], v[190:193], v[48:51]
	v_mfma_f32_16x16x32_bf16 v[32:35], v[182:185], v[198:201], v[32:35]
	v_mfma_f32_16x16x32_bf16 v[20:23], v[172:175], v[212:215], v[20:23]
	v_mfma_f32_16x16x32_bf16 v[4:7], v[172:175], v[220:223], v[4:7]
	v_mfma_f32_16x16x32_bf16 v[16:19], v[182:185], v[212:215], v[16:19]
	v_mfma_f32_16x16x32_bf16 v[0:3], v[182:185], v[220:223], v[0:3]
	v_mfma_f32_16x16x32_bf16 v[52:55], v[176:179], v[194:197], v[52:55]
	v_mfma_f32_16x16x32_bf16 v[36:39], v[176:179], v[208:211], v[36:39]
	v_mfma_f32_16x16x32_bf16 v[48:51], v[186:189], v[194:197], v[48:51]
	v_mfma_f32_16x16x32_bf16 v[32:35], v[186:189], v[208:211], v[32:35]
	v_mfma_f32_16x16x32_bf16 v[20:23], v[176:179], v[216:219], v[20:23]
	v_mfma_f32_16x16x32_bf16 v[4:7], v[176:179], v[224:227], v[4:7]
	v_lshl_add_u64 v[202:203], v[232:233], 0, s[38:39]
	s_mov_b32 m0, s84
	s_nop 0
	global_load_lds_dwordx4 v[202:203], off
	v_mfma_f32_16x16x32_bf16 v[16:19], v[186:189], v[216:219], v[16:19]
	v_mfma_f32_16x16x32_bf16 v[0:3], v[186:189], v[224:227], v[0:3]
	s_setprio 0
	s_barrier
	s_add_i32 s92, s92, 2
	s_add_u32 s60, s60, 0x100
	s_addc_u32 s61, s61, 0
	s_add_u32 s90, s90, 0x100
	s_addc_u32 s91, s91, 0
.LBB0_650:
	ds_read_b128 v[148:151], v155
	ds_read_b128 v[160:163], v155 offset:1024
	ds_read_b128 v[164:167], v155 offset:2048
	ds_read_b128 v[168:171], v155 offset:3072
	ds_read_b128 v[172:175], v156
	ds_read_b128 v[176:179], v156 offset:1024
	ds_read_b128 v[182:185], v156 offset:2048
	ds_read_b128 v[186:189], v156 offset:3072
	s_add_u32 s3, s60, 0xfffc0080
	s_addc_u32 s14, s61, -1
	s_cmp_eq_u32 s92, 12
	s_cselect_b32 s65, s51, s14
	s_cselect_b32 s64, s57, s3
	s_cselect_b32 s63, s49, s91
	s_cselect_b32 s62, s89, s90
	v_lshl_add_u64 v[202:203], s[60:61], 0, v[140:141]
	s_add_i32 m0, s43, 0xc000
	ds_read_b128 v[190:193], v157
	ds_read_b128 v[194:197], v157 offset:1024
	ds_read_b128 v[198:201], v157 offset:2048
	ds_read_b128 v[208:211], v157 offset:3072
	ds_read_b128 v[212:215], v157 offset:4096
	ds_read_b128 v[216:219], v157 offset:5120
	ds_read_b128 v[220:223], v157 offset:6144
	ds_read_b128 v[224:227], v157 offset:7168
	global_load_lds_dwordx4 v[202:203], off
	v_lshl_add_u64 v[202:203], s[60:61], 0, v[142:143]
	s_add_i32 m0, s43, 0xe000
	s_nop 0
	global_load_lds_dwordx4 v[202:203], off
	s_waitcnt vmcnt(8)
	s_waitcnt lgkmcnt(0)
	s_barrier
; #define PG8_STAGE(bufoff, gbase, voff) do { _Pragma("unroll") for (int _i = 0; _i < 2; ++_i) \
;         __builtin_amdgcn_global_load_lds((const unsigned*)((const char*)(gbase) + (voff)[_i]), (PG8_LAS unsigned*)(lds + (bufoff) + ldsw + _i * 8192), 16, 0, 0); } while (0)
; #define PG8_LDA(dst, b, h) do { _Pragma("unroll") for (int m = 0; m < 4; ++m) _Pragma("unroll") for (int k = 0; k < 2; ++k) dst[m][k] = *(const PG8_LAS bf16x8*)(lds + PG8_SA(b, h) + aoff + m * 2048 + k * 1024); } while (0)
; #define PG8_MMA(ai, bj, At, Bt) do { __builtin_amdgcn_s_setprio(1); _Pragma("unroll") for (int m = 0; m < 4; ++m) _Pragma("unroll") for (int n = 0; n < 2; ++n) _Pragma("unroll") for (int k = 0; k < 2; ++k) \
;         acc[ai][bj][m][n] = __builtin_amdgcn_mfma_f32_16x16x32_bf16(Bt[n][k], At[m][k], acc[ai][bj][m][n], 0, 0, 0); __builtin_amdgcn_s_setprio(0); } while (0)
; #define PG8_WAIT_V(n) asm volatile("s_waitcnt vmcnt(" #n ")" ::: "memory")
; #define PG8_WAIT_L(n) asm volatile("s_waitcnt lgkmcnt(" #n ")" ::: "memory")
; #define PG8_BAR __builtin_amdgcn_s_barrier()
; #define PG8_SCHED __builtin_amdgcn_sched_barrier(0)
; template <class Epi, class Sched, bool ALIGN_EPI = false, bool SP2 = false>
; __device__ __forceinline__ void gemm_phase(PG8_LAS unsigned char* lds, const Gemm g, const Sched& S, const Epi& E) {
;     ...
;             PG8_WAIT_V(8); PG8_WAIT_L(0); PG8_BAR; PG8_MMA(0, 0, At, B0); PG8_MMA(0, 1, At, B1); PG8_BAR; PG8_SCHED;
;             PG8_LDA(At, 0, 1); PG8_STAGE(PG8_SB(0, 0), b2, voffB); PG8_STAGE(PG8_SB(0, 1), b2 + hstep, voffB); PG8_STAGE(PG8_SA(0, 0), a2, voffA);
;             PG8_WAIT_V(8); PG8_WAIT_L(0); PG8_BAR; PG8_MMA(1, 0, At, B0); PG8_MMA(1, 1, At, B1); PG8_BAR; PG8_SCHED;
	s_setprio 1
	s_waitcnt lgkmcnt(0)
	v_mfma_f32_16x16x32_bf16 v[124:127], v[148:151], v[190:193], v[124:127]
	v_mfma_f32_16x16x32_bf16 v[108:111], v[148:151], v[198:201], v[108:111]
	v_mfma_f32_16x16x32_bf16 v[120:123], v[164:167], v[190:193], v[120:123]
	v_mfma_f32_16x16x32_bf16 v[104:107], v[164:167], v[198:201], v[104:107]
	v_mfma_f32_16x16x32_bf16 v[92:95], v[148:151], v[212:215], v[92:95]
	v_mfma_f32_16x16x32_bf16 v[76:79], v[148:151], v[220:223], v[76:79]
	v_mfma_f32_16x16x32_bf16 v[88:91], v[164:167], v[212:215], v[88:91]
	v_mfma_f32_16x16x32_bf16 v[72:75], v[164:167], v[220:223], v[72:75]
	v_mfma_f32_16x16x32_bf16 v[124:127], v[160:163], v[194:197], v[124:127]
	v_mfma_f32_16x16x32_bf16 v[108:111], v[160:163], v[208:211], v[108:111]
	v_mfma_f32_16x16x32_bf16 v[120:123], v[168:171], v[194:197], v[120:123]
	v_mfma_f32_16x16x32_bf16 v[104:107], v[168:171], v[208:211], v[104:107]
	v_mfma_f32_16x16x32_bf16 v[92:95], v[160:163], v[216:219], v[92:95]
	v_mfma_f32_16x16x32_bf16 v[76:79], v[160:163], v[224:227], v[76:79]
	v_mfma_f32_16x16x32_bf16 v[88:91], v[168:171], v[216:219], v[88:91]
	v_mfma_f32_16x16x32_bf16 v[72:75], v[168:171], v[224:227], v[72:75]
	s_setprio 0
	s_setprio 1
	v_mfma_f32_16x16x32_bf16 v[116:119], v[172:175], v[190:193], v[116:119]
	v_mfma_f32_16x16x32_bf16 v[100:103], v[172:175], v[198:201], v[100:103]
	v_mfma_f32_16x16x32_bf16 v[112:115], v[182:185], v[190:193], v[112:115]
	v_mfma_f32_16x16x32_bf16 v[96:99], v[182:185], v[198:201], v[96:99]
	v_mfma_f32_16x16x32_bf16 v[84:87], v[172:175], v[212:215], v[84:87]
	v_mfma_f32_16x16x32_bf16 v[68:71], v[172:175], v[220:223], v[68:71]
	v_mfma_f32_16x16x32_bf16 v[80:83], v[182:185], v[212:215], v[80:83]
	v_mfma_f32_16x16x32_bf16 v[64:67], v[182:185], v[220:223], v[64:67]
	v_mfma_f32_16x16x32_bf16 v[116:119], v[176:179], v[194:197], v[116:119]
	v_mfma_f32_16x16x32_bf16 v[100:103], v[176:179], v[208:211], v[100:103]
	v_mfma_f32_16x16x32_bf16 v[112:115], v[186:189], v[194:197], v[112:115]
	v_mfma_f32_16x16x32_bf16 v[96:99], v[186:189], v[208:211], v[96:99]
	v_mfma_f32_16x16x32_bf16 v[84:87], v[176:179], v[216:219], v[84:87]
	v_mfma_f32_16x16x32_bf16 v[68:71], v[176:179], v[224:227], v[68:71]
	v_mfma_f32_16x16x32_bf16 v[80:83], v[186:189], v[216:219], v[80:83]
	v_mfma_f32_16x16x32_bf16 v[64:67], v[186:189], v[224:227], v[64:67]
	s_setprio 0
	s_barrier
	s_add_i32 s3, s85, s34
	v_lshl_add_u64 v[202:203], s[62:63], 0, v[134:135]
	s_mov_b32 m0, s3
	ds_read_b128 v[190:193], v157 offset:16384
	ds_read_b128 v[194:197], v157 offset:17408
	ds_read_b128 v[198:201], v157 offset:18432
	ds_read_b128 v[208:211], v157 offset:19456
	ds_read_b128 v[212:215], v157 offset:20480
	ds_read_b128 v[216:219], v157 offset:21504
	ds_read_b128 v[220:223], v157 offset:22528
	ds_read_b128 v[224:227], v157 offset:23552
	global_load_lds_dwordx4 v[202:203], off
	s_add_i32 m0, s3, 0x2000
	s_add_u32 s14, s62, 0x40000
	v_lshl_add_u64 v[228:229], s[62:63], 0, v[138:139]
	s_addc_u32 s15, s63, 0
	s_add_i32 s3, s86, s34
	global_load_lds_dwordx4 v[228:229], off
	v_lshl_add_u64 v[230:231], s[14:15], 0, v[134:135]
	s_mov_b32 m0, s3
	global_load_lds_dwordx4 v[230:231], off
	v_lshl_add_u64 v[230:231], s[14:15], 0, v[138:139]
	s_add_i32 m0, s3, 0x2000
	s_nop 0
	global_load_lds_dwordx4 v[230:231], off
	s_waitcnt vmcnt(6)
	s_waitcnt lgkmcnt(0)
	s_barrier
	s_setprio 1
	s_waitcnt lgkmcnt(0)
	v_mfma_f32_16x16x32_bf16 v[60:63], v[148:151], v[190:193], v[60:63]
	v_mfma_f32_16x16x32_bf16 v[44:47], v[148:151], v[198:201], v[44:47]
	v_mfma_f32_16x16x32_bf16 v[56:59], v[164:167], v[190:193], v[56:59]
	v_mfma_f32_16x16x32_bf16 v[40:43], v[164:167], v[198:201], v[40:43]
	v_mfma_f32_16x16x32_bf16 v[28:31], v[148:151], v[212:215], v[28:31]
	v_mfma_f32_16x16x32_bf16 v[12:15], v[148:151], v[220:223], v[12:15]
	v_mfma_f32_16x16x32_bf16 v[24:27], v[164:167], v[212:215], v[24:27]
	v_mfma_f32_16x16x32_bf16 v[8:11], v[164:167], v[220:223], v[8:11]
	v_mfma_f32_16x16x32_bf16 v[60:63], v[160:163], v[194:197], v[60:63]
	v_mfma_f32_16x16x32_bf16 v[44:47], v[160:163], v[208:211], v[44:47]
	v_mfma_f32_16x16x32_bf16 v[56:59], v[168:171], v[194:197], v[56:59]
	v_mfma_f32_16x16x32_bf16 v[40:43], v[168:171], v[208:211], v[40:43]
	v_mfma_f32_16x16x32_bf16 v[28:31], v[160:163], v[216:219], v[28:31]
	v_mfma_f32_16x16x32_bf16 v[12:15], v[160:163], v[224:227], v[12:15]
	v_lshl_add_u64 v[230:231], s[64:65], 0, v[132:133]
	s_mov_b32 m0, s43
	s_nop 0
	global_load_lds_dwordx4 v[230:231], off
	v_mfma_f32_16x16x32_bf16 v[24:27], v[168:171], v[216:219], v[24:27]
	v_mfma_f32_16x16x32_bf16 v[8:11], v[168:171], v[224:227], v[8:11]
	s_setprio 0
	s_setprio 1
	v_mfma_f32_16x16x32_bf16 v[52:55], v[172:175], v[190:193], v[52:55]
	v_mfma_f32_16x16x32_bf16 v[36:39], v[172:175], v[198:201], v[36:39]
	v_mfma_f32_16x16x32_bf16 v[48:51], v[182:185], v[190:193], v[48:51]
	v_mfma_f32_16x16x32_bf16 v[32:35], v[182:185], v[198:201], v[32:35]
	v_mfma_f32_16x16x32_bf16 v[20:23], v[172:175], v[212:215], v[20:23]
	v_mfma_f32_16x16x32_bf16 v[4:7], v[172:175], v[220:223], v[4:7]
	v_mfma_f32_16x16x32_bf16 v[16:19], v[182:185], v[212:215], v[16:19]
	v_mfma_f32_16x16x32_bf16 v[0:3], v[182:185], v[220:223], v[0:3]
	v_mfma_f32_16x16x32_bf16 v[52:55], v[176:179], v[194:197], v[52:55]
	v_mfma_f32_16x16x32_bf16 v[36:39], v[176:179], v[208:211], v[36:39]
	v_mfma_f32_16x16x32_bf16 v[48:51], v[186:189], v[194:197], v[48:51]
	v_mfma_f32_16x16x32_bf16 v[32:35], v[186:189], v[208:211], v[32:35]
	v_mfma_f32_16x16x32_bf16 v[20:23], v[176:179], v[216:219], v[20:23]
	v_mfma_f32_16x16x32_bf16 v[4:7], v[176:179], v[224:227], v[4:7]
	v_lshl_add_u64 v[232:233], s[64:65], 0, v[136:137]
	s_mov_b32 m0, s59
	s_nop 0
	global_load_lds_dwordx4 v[232:233], off
	v_mfma_f32_16x16x32_bf16 v[16:19], v[186:189], v[216:219], v[16:19]
	v_mfma_f32_16x16x32_bf16 v[0:3], v[186:189], v[224:227], v[0:3]
	s_setprio 0
	s_barrier
; #define PG8_STAGE(bufoff, gbase, voff) do { _Pragma("unroll") for (int _i = 0; _i < 2; ++_i) \
;         __builtin_amdgcn_global_load_lds((const unsigned*)((const char*)(gbase) + (voff)[_i]), (PG8_LAS unsigned*)(lds + (bufoff) + ldsw + _i * 8192), 16, 0, 0); } while (0)
; #define PG8_LDA(dst, b, h) do { _Pragma("unroll") for (int m = 0; m < 4; ++m) _Pragma("unroll") for (int k = 0; k < 2; ++k) dst[m][k] = *(const PG8_LAS bf16x8*)(lds + PG8_SA(b, h) + aoff + m * 2048 + k * 1024); } while (0)
; #define PG8_LDB(dst, b, h) do { _Pragma("unroll") for (int n = 0; n < 2; ++n) _Pragma("unroll") for (int k = 0; k < 2; ++k) dst[n][k] = *(const PG8_LAS bf16x8*)(lds + PG8_SB(b, h) + boff + n * 2048 + k * 1024); } while (0)
; #define PG8_MMA(ai, bj, At, Bt) do { __builtin_amdgcn_s_setprio(1); _Pragma("unroll") for (int m = 0; m < 4; ++m) _Pragma("unroll") for (int n = 0; n < 2; ++n) _Pragma("unroll") for (int k = 0; k < 2; ++k) \
;         acc[ai][bj][m][n] = __builtin_amdgcn_mfma_f32_16x16x32_bf16(Bt[n][k], At[m][k], acc[ai][bj][m][n], 0, 0, 0); __builtin_amdgcn_s_setprio(0); } while (0)
; #define PG8_WAIT_V(n) asm volatile("s_waitcnt vmcnt(" #n ")" ::: "memory")
; #define PG8_WAIT_L(n) asm volatile("s_waitcnt lgkmcnt(" #n ")" ::: "memory")
; #define PG8_BAR __builtin_amdgcn_s_barrier()
; #define PG8_SCHED __builtin_amdgcn_sched_barrier(0)
; template <class Epi, class Sched, bool ALIGN_EPI = false, bool SP2 = false>
; __device__ __forceinline__ void gemm_phase(PG8_LAS unsigned char* lds, const Gemm g, const Sched& S, const Epi& E) {
;     ...
;             PG8_LDB(B0, 1, 0); PG8_LDB(B1, 1, 1); PG8_SCHED; PG8_LDA(At, 1, 0); PG8_STAGE(PG8_SA(0, 1), a2 + hstep, voffA);
;             PG8_WAIT_V(8); PG8_WAIT_L(0); PG8_BAR; PG8_MMA(0, 0, At, B0); PG8_MMA(0, 1, At, B1); PG8_BAR; PG8_SCHED;
	s_add_i32 s3, 0, 0x18000
	v_add_u32_e32 v159, s3, v131
	s_add_i32 s33, 0, 0x1c000
	ds_read_b128 v[148:151], v159
	ds_read_b128 v[160:163], v159 offset:1024
	ds_read_b128 v[164:167], v159 offset:2048
	ds_read_b128 v[168:171], v159 offset:3072
	v_add_u32_e32 v159, s33, v131
	ds_read_b128 v[172:175], v159
	ds_read_b128 v[176:179], v159 offset:1024
	ds_read_b128 v[182:185], v159 offset:2048
	ds_read_b128 v[186:189], v159 offset:3072
	s_add_u32 s14, s64, 0x40000
	s_addc_u32 s15, s65, 0
	s_mov_b32 m0, s66
	v_lshl_add_u64 v[234:235], s[14:15], 0, v[132:133]
	ds_read_b128 v[190:193], v157 offset:32768
	ds_read_b128 v[194:197], v157 offset:33792
	ds_read_b128 v[198:201], v157 offset:34816
	ds_read_b128 v[208:211], v157 offset:35840
	ds_read_b128 v[212:215], v157 offset:36864
	ds_read_b128 v[216:219], v157 offset:37888
	ds_read_b128 v[220:223], v157 offset:38912
	ds_read_b128 v[224:227], v157 offset:39936
	global_load_lds_dwordx4 v[234:235], off
	v_lshl_add_u64 v[234:235], s[14:15], 0, v[136:137]
	s_mov_b32 m0, s67
	s_nop 0
	global_load_lds_dwordx4 v[234:235], off
	s_waitcnt vmcnt(8)
	s_waitcnt lgkmcnt(0)
	s_barrier
	s_setprio 1
	s_waitcnt lgkmcnt(0)
	v_mfma_f32_16x16x32_bf16 v[124:127], v[148:151], v[190:193], v[124:127]
	v_mfma_f32_16x16x32_bf16 v[108:111], v[148:151], v[198:201], v[108:111]
	v_mfma_f32_16x16x32_bf16 v[120:123], v[164:167], v[190:193], v[120:123]
	v_mfma_f32_16x16x32_bf16 v[104:107], v[164:167], v[198:201], v[104:107]
	v_mfma_f32_16x16x32_bf16 v[92:95], v[148:151], v[212:215], v[92:95]
	v_mfma_f32_16x16x32_bf16 v[76:79], v[148:151], v[220:223], v[76:79]
	v_mfma_f32_16x16x32_bf16 v[88:91], v[164:167], v[212:215], v[88:91]
	v_mfma_f32_16x16x32_bf16 v[72:75], v[164:167], v[220:223], v[72:75]
	v_mfma_f32_16x16x32_bf16 v[124:127], v[160:163], v[194:197], v[124:127]
	v_mfma_f32_16x16x32_bf16 v[108:111], v[160:163], v[208:211], v[108:111]
	v_mfma_f32_16x16x32_bf16 v[120:123], v[168:171], v[194:197], v[120:123]
	v_mfma_f32_16x16x32_bf16 v[104:107], v[168:171], v[208:211], v[104:107]
	v_mfma_f32_16x16x32_bf16 v[92:95], v[160:163], v[216:219], v[92:95]
	v_mfma_f32_16x16x32_bf16 v[76:79], v[160:163], v[224:227], v[76:79]
	v_mfma_f32_16x16x32_bf16 v[88:91], v[168:171], v[216:219], v[88:91]
	v_mfma_f32_16x16x32_bf16 v[72:75], v[168:171], v[224:227], v[72:75]
	s_setprio 0
	s_setprio 1
	v_mfma_f32_16x16x32_bf16 v[116:119], v[172:175], v[190:193], v[116:119]
	v_mfma_f32_16x16x32_bf16 v[100:103], v[172:175], v[198:201], v[100:103]
	v_mfma_f32_16x16x32_bf16 v[112:115], v[182:185], v[190:193], v[112:115]
	v_mfma_f32_16x16x32_bf16 v[96:99], v[182:185], v[198:201], v[96:99]
	v_mfma_f32_16x16x32_bf16 v[84:87], v[172:175], v[212:215], v[84:87]
	v_mfma_f32_16x16x32_bf16 v[68:71], v[172:175], v[220:223], v[68:71]
	v_mfma_f32_16x16x32_bf16 v[80:83], v[182:185], v[212:215], v[80:83]
	v_mfma_f32_16x16x32_bf16 v[64:67], v[182:185], v[220:223], v[64:67]
	v_mfma_f32_16x16x32_bf16 v[116:119], v[176:179], v[194:197], v[116:119]
	v_mfma_f32_16x16x32_bf16 v[100:103], v[176:179], v[208:211], v[100:103]
	v_mfma_f32_16x16x32_bf16 v[112:115], v[186:189], v[194:197], v[112:115]
	v_mfma_f32_16x16x32_bf16 v[96:99], v[186:189], v[208:211], v[96:99]
	v_mfma_f32_16x16x32_bf16 v[84:87], v[176:179], v[216:219], v[84:87]
	v_mfma_f32_16x16x32_bf16 v[68:71], v[176:179], v[224:227], v[68:71]
	v_mfma_f32_16x16x32_bf16 v[80:83], v[186:189], v[216:219], v[80:83]
	v_mfma_f32_16x16x32_bf16 v[64:67], v[186:189], v[224:227], v[64:67]
	s_setprio 0
	s_barrier
; #define PG8_STAGE(bufoff, gbase, voff) do { _Pragma("unroll") for (int _i = 0; _i < 2; ++_i) \
;         __builtin_amdgcn_global_load_lds((const unsigned*)((const char*)(gbase) + (voff)[_i]), (PG8_LAS unsigned*)(lds + (bufoff) + ldsw + _i * 8192), 16, 0, 0); } while (0)
; #define PG8_LDA(dst, b, h) do { _Pragma("unroll") for (int m = 0; m < 4; ++m) _Pragma("unroll") for (int k = 0; k < 2; ++k) dst[m][k] = *(const PG8_LAS bf16x8*)(lds + PG8_SA(b, h) + aoff + m * 2048 + k * 1024); } while (0)
; #define PG8_MMA(ai, bj, At, Bt) do { __builtin_amdgcn_s_setprio(1); _Pragma("unroll") for (int m = 0; m < 4; ++m) _Pragma("unroll") for (int n = 0; n < 2; ++n) _Pragma("unroll") for (int k = 0; k < 2; ++k) \
;         acc[ai][bj][m][n] = __builtin_amdgcn_mfma_f32_16x16x32_bf16(Bt[n][k], At[m][k], acc[ai][bj][m][n], 0, 0, 0); __builtin_amdgcn_s_setprio(0); } while (0)
; #define PG8_WAIT_V(n) asm volatile("s_waitcnt vmcnt(" #n ")" ::: "memory")
; #define PG8_WAIT_L(n) asm volatile("s_waitcnt lgkmcnt(" #n ")" ::: "memory")
; #define PG8_BAR __builtin_amdgcn_s_barrier()
; #define PG8_SCHED __builtin_amdgcn_sched_barrier(0)
; template <class Epi, class Sched, bool ALIGN_EPI = false, bool SP2 = false>
; __device__ __forceinline__ void gemm_phase(PG8_LAS unsigned char* lds, const Gemm g, const Sched& S, const Epi& E) {
;     ...
;             PG8_LDA(At, 1, 1); PG8_STAGE(PG8_SB(1, 0), b3, voffB); PG8_STAGE(PG8_SB(1, 1), b3 + hstep, voffB); PG8_STAGE(PG8_SA(1, 0), a3, voffA);
;             PG8_WAIT_V(8); PG8_WAIT_L(0); PG8_BAR; PG8_MMA(1, 0, At, B0); PG8_MMA(1, 1, At, B1); PG8_BAR; PG8_SCHED;
	s_add_i32 s3, s3, s34
	v_lshl_add_u64 v[202:203], v[202:203], 0, s[38:39]
	s_mov_b32 m0, s3
	ds_read_b128 v[190:193], v157 offset:49152
	ds_read_b128 v[194:197], v157 offset:50176
	ds_read_b128 v[198:201], v157 offset:51200
	ds_read_b128 v[208:211], v157 offset:52224
	ds_read_b128 v[212:215], v157 offset:53248
	ds_read_b128 v[216:219], v157 offset:54272
	ds_read_b128 v[220:223], v157 offset:55296
	ds_read_b128 v[224:227], v157 offset:56320
	global_load_lds_dwordx4 v[202:203], off
	s_add_i32 m0, s3, 0x2000
	s_add_u32 s14, s62, 0x40080
	v_lshl_add_u64 v[202:203], v[228:229], 0, s[38:39]
	s_addc_u32 s15, s63, 0
	s_add_i32 s3, s33, s34
	global_load_lds_dwordx4 v[202:203], off
	v_lshl_add_u64 v[202:203], s[14:15], 0, v[134:135]
	s_mov_b32 m0, s3
	s_nop 0
	global_load_lds_dwordx4 v[202:203], off
	v_lshl_add_u64 v[202:203], s[14:15], 0, v[138:139]
	s_add_i32 m0, s3, 0x2000
	s_nop 0
	global_load_lds_dwordx4 v[202:203], off
	s_waitcnt vmcnt(6)
	s_waitcnt lgkmcnt(0)
	s_barrier
	s_setprio 1
	s_waitcnt lgkmcnt(0)
	v_mfma_f32_16x16x32_bf16 v[60:63], v[148:151], v[190:193], v[60:63]
	v_mfma_f32_16x16x32_bf16 v[44:47], v[148:151], v[198:201], v[44:47]
	v_mfma_f32_16x16x32_bf16 v[56:59], v[164:167], v[190:193], v[56:59]
	v_mfma_f32_16x16x32_bf16 v[40:43], v[164:167], v[198:201], v[40:43]
	v_mfma_f32_16x16x32_bf16 v[28:31], v[148:151], v[212:215], v[28:31]
	v_mfma_f32_16x16x32_bf16 v[12:15], v[148:151], v[220:223], v[12:15]
	v_mfma_f32_16x16x32_bf16 v[24:27], v[164:167], v[212:215], v[24:27]
	v_mfma_f32_16x16x32_bf16 v[8:11], v[164:167], v[220:223], v[8:11]
	v_mfma_f32_16x16x32_bf16 v[60:63], v[160:163], v[194:197], v[60:63]
	v_mfma_f32_16x16x32_bf16 v[44:47], v[160:163], v[208:211], v[44:47]
	v_mfma_f32_16x16x32_bf16 v[56:59], v[168:171], v[194:197], v[56:59]
	v_mfma_f32_16x16x32_bf16 v[40:43], v[168:171], v[208:211], v[40:43]
	v_mfma_f32_16x16x32_bf16 v[28:31], v[160:163], v[216:219], v[28:31]
	v_mfma_f32_16x16x32_bf16 v[12:15], v[160:163], v[224:227], v[12:15]
	v_lshl_add_u64 v[202:203], v[230:231], 0, s[38:39]
	s_mov_b32 m0, s75
	s_nop 0
	global_load_lds_dwordx4 v[202:203], off
	v_mfma_f32_16x16x32_bf16 v[24:27], v[168:171], v[216:219], v[24:27]
	v_mfma_f32_16x16x32_bf16 v[8:11], v[168:171], v[224:227], v[8:11]
	s_setprio 0
	s_setprio 1
	v_mfma_f32_16x16x32_bf16 v[52:55], v[172:175], v[190:193], v[52:55]
	v_mfma_f32_16x16x32_bf16 v[36:39], v[172:175], v[198:201], v[36:39]
	v_mfma_f32_16x16x32_bf16 v[48:51], v[182:185], v[190:193], v[48:51]
	v_mfma_f32_16x16x32_bf16 v[32:35], v[182:185], v[198:201], v[32:35]
	v_mfma_f32_16x16x32_bf16 v[20:23], v[172:175], v[212:215], v[20:23]
	v_mfma_f32_16x16x32_bf16 v[4:7], v[172:175], v[220:223], v[4:7]
	v_mfma_f32_16x16x32_bf16 v[16:19], v[182:185], v[212:215], v[16:19]
	v_mfma_f32_16x16x32_bf16 v[0:3], v[182:185], v[220:223], v[0:3]
	v_mfma_f32_16x16x32_bf16 v[52:55], v[176:179], v[194:197], v[52:55]
	v_mfma_f32_16x16x32_bf16 v[36:39], v[176:179], v[208:211], v[36:39]
	v_mfma_f32_16x16x32_bf16 v[48:51], v[186:189], v[194:197], v[48:51]
	v_mfma_f32_16x16x32_bf16 v[32:35], v[186:189], v[208:211], v[32:35]
	v_mfma_f32_16x16x32_bf16 v[20:23], v[176:179], v[216:219], v[20:23]
	v_mfma_f32_16x16x32_bf16 v[4:7], v[176:179], v[224:227], v[4:7]
	v_lshl_add_u64 v[202:203], v[232:233], 0, s[38:39]
	s_mov_b32 m0, s84
	s_nop 0
	global_load_lds_dwordx4 v[202:203], off
	v_mfma_f32_16x16x32_bf16 v[16:19], v[186:189], v[216:219], v[16:19]
	v_mfma_f32_16x16x32_bf16 v[0:3], v[186:189], v[224:227], v[0:3]
	s_setprio 0
	s_barrier
	s_add_i32 s92, s92, 2
	s_add_u32 s60, s60, 0x100
	s_addc_u32 s61, s61, 0
	s_add_u32 s90, s90, 0x100
	s_addc_u32 s91, s91, 0
	s_cmp_gt_u32 s92, 13
	s_cbranch_scc0 .LBB0_650
	s_and_b64 vcc, exec, s[44:45]
	s_cbranch_vccz .LBB0_653
	s_barrier

; #define PG8_STAGE(bufoff, gbase, voff) do { _Pragma("unroll") for (int _i = 0; _i < 2; ++_i) \
;         __builtin_amdgcn_global_load_lds((const unsigned*)((const char*)(gbase) + (voff)[_i]), (PG8_LAS unsigned*)(lds + (bufoff) + ldsw + _i * 8192), 16, 0, 0); } while (0)
; #define PG8_LDA(dst, b, h) do { _Pragma("unroll") for (int m = 0; m < 4; ++m) _Pragma("unroll") for (int k = 0; k < 2; ++k) dst[m][k] = *(const PG8_LAS bf16x8*)(lds + PG8_SA(b, h) + aoff + m * 2048 + k * 1024); } while (0)
; #define PG8_LDB(dst, b, h) do { _Pragma("unroll") for (int n = 0; n < 2; ++n) _Pragma("unroll") for (int k = 0; k < 2; ++k) dst[n][k] = *(const PG8_LAS bf16x8*)(lds + PG8_SB(b, h) + boff + n * 2048 + k * 1024); } while (0)
; #define PG8_MMA(ai, bj, At, Bt) do { __builtin_amdgcn_s_setprio(1); _Pragma("unroll") for (int m = 0; m < 4; ++m) _Pragma("unroll") for (int n = 0; n < 2; ++n) _Pragma("unroll") for (int k = 0; k < 2; ++k) \
;         acc[ai][bj][m][n] = __builtin_amdgcn_mfma_f32_16x16x32_bf16(Bt[n][k], At[m][k], acc[ai][bj][m][n], 0, 0, 0); __builtin_amdgcn_s_setprio(0); } while (0)
; #define PG8_BAR __builtin_amdgcn_s_barrier()
; template <class Epi, class Sched, bool ALIGN_EPI = false, bool SP2 = false>
; __device__ __forceinline__ void gemm_phase(PG8_LAS unsigned char* lds, const Gemm g, const Sched& S, const Epi& E) {
;     ...
;         const bool has_next = S.next(ui + 1, nxt);
;         const char* nA = has_next ? (const char*)g.A + (size_t)nxt.pm * tstep : cA; const char* nB = has_next ? (const char*)g.Bt + (size_t)nxt.pn * tstep : cB;
;         for (int t = 0; t < nt; t += 2) {
;             const bool last = (t == nt - 2);
;             const char* a1 = cA + (size_t)(t + 1) * kstep;
;             const char* a2 = last ? nA : cA + (size_t)(t + 2) * kstep; const char* b2 = last ? nB : cB + (size_t)(t + 2) * kstep;
;             const char* a3 = a2 + kstep; const char* b3 = b2 + kstep;
;             if (last && has_next) S.a_ready(nxt);
;             if constexpr (SP2) {
;             PG8_LDB(B0, 0, 0); PG8_LDB(B1, 0, 1); PG8_SCHED; PG8_LDA(At, 0, 0); PG8_STAGE(PG8_SA(1, 1), a1 + hstep, voffA);
;             PG8_WAIT_V(8); PG8_WAIT_L(0); PG8_BAR; PG8_MMA(0, 0, At, B0); PG8_MMA(0, 1, At, B1); PG8_BAR; PG8_SCHED;
;             PG8_LDA(At, 0, 1); PG8_STAGE(PG8_SB(0, 0), b2, voffB); PG8_STAGE(PG8_SB(0, 1), b2 + hstep, voffB); PG8_STAGE(PG8_SA(0, 0), a2, voffA);
.LBB0_737:
	s_ashr_i32 s51, s50, 31
	s_lshl_b64 s[14:15], s[50:51], 19
	s_add_u32 s52, s22, s14
	s_addc_u32 s53, s23, s15
	s_and_b64 s[14:15], s[8:9], exec
	s_cselect_b32 s51, s53, s57
	s_cselect_b32 s82, s52, s56
	s_ashr_i32 s49, s48, 31
	s_lshl_b64 s[14:15], s[48:49], 19
	v_readlane_b32 s3, v250, 15
	s_add_u32 s54, s3, s14
	v_readlane_b32 s3, v250, 16
	s_addc_u32 s55, s3, s15
	s_and_b64 s[14:15], s[8:9], exec
	s_cselect_b32 s49, s55, s59
	s_cselect_b32 s83, s54, s58
	s_add_u32 s56, s56, 0x40080
	s_addc_u32 s57, s57, 0
	s_add_u32 s84, s58, 0x100
	s_addc_u32 s85, s59, 0
	s_mov_b32 s86, -2
	s_waitcnt vmcnt(0)
	ds_read_b128 v[148:151], v155
	ds_read_b128 v[160:163], v155 offset:1024
	ds_read_b128 v[164:167], v155 offset:2048
	ds_read_b128 v[168:171], v155 offset:3072
	ds_read_b128 v[172:175], v156
	ds_read_b128 v[176:179], v156 offset:1024
	ds_read_b128 v[182:185], v156 offset:2048
	ds_read_b128 v[186:189], v156 offset:3072
	s_add_u32 s3, s56, 0xfffc0080
	s_addc_u32 s14, s57, -1
	s_cmp_eq_u32 s86, 12
	s_cselect_b32 s61, s51, s14
	s_cselect_b32 s60, s82, s3
	s_cselect_b32 s59, s49, s85
	s_cselect_b32 s58, s83, s84
	v_lshl_add_u64 v[202:203], s[56:57], 0, v[140:141]
	s_add_i32 m0, s43, 0xc000
	ds_read_b128 v[190:193], v157
	ds_read_b128 v[194:197], v157 offset:1024
	ds_read_b128 v[198:201], v157 offset:2048
	ds_read_b128 v[208:211], v157 offset:3072
	ds_read_b128 v[212:215], v157 offset:4096
	ds_read_b128 v[216:219], v157 offset:5120
	ds_read_b128 v[220:223], v157 offset:6144
	ds_read_b128 v[224:227], v157 offset:7168
	global_load_lds_dwordx4 v[202:203], off
	v_lshl_add_u64 v[202:203], s[56:57], 0, v[142:143]
	s_add_i32 m0, s43, 0xe000
	s_nop 0
	global_load_lds_dwordx4 v[202:203], off
	s_waitcnt vmcnt(8)
	s_waitcnt lgkmcnt(0)
	s_barrier
	s_setprio 1
	s_waitcnt lgkmcnt(0)
	v_mfma_f32_16x16x32_bf16 v[124:127], v[148:151], v[190:193], 0
	v_mfma_f32_16x16x32_bf16 v[108:111], v[148:151], v[198:201], 0
	v_mfma_f32_16x16x32_bf16 v[120:123], v[164:167], v[190:193], 0
	v_mfma_f32_16x16x32_bf16 v[104:107], v[164:167], v[198:201], 0
	v_mfma_f32_16x16x32_bf16 v[92:95], v[148:151], v[212:215], 0
	v_mfma_f32_16x16x32_bf16 v[76:79], v[148:151], v[220:223], 0
	v_mfma_f32_16x16x32_bf16 v[88:91], v[164:167], v[212:215], 0
	v_mfma_f32_16x16x32_bf16 v[72:75], v[164:167], v[220:223], 0
	v_mfma_f32_16x16x32_bf16 v[124:127], v[160:163], v[194:197], v[124:127]
	v_mfma_f32_16x16x32_bf16 v[108:111], v[160:163], v[208:211], v[108:111]
	v_mfma_f32_16x16x32_bf16 v[120:123], v[168:171], v[194:197], v[120:123]
	v_mfma_f32_16x16x32_bf16 v[104:107], v[168:171], v[208:211], v[104:107]
	v_mfma_f32_16x16x32_bf16 v[92:95], v[160:163], v[216:219], v[92:95]
	v_mfma_f32_16x16x32_bf16 v[76:79], v[160:163], v[224:227], v[76:79]
	v_mfma_f32_16x16x32_bf16 v[88:91], v[168:171], v[216:219], v[88:91]
	v_mfma_f32_16x16x32_bf16 v[72:75], v[168:171], v[224:227], v[72:75]
	s_setprio 0
	s_setprio 1
	v_mfma_f32_16x16x32_bf16 v[116:119], v[172:175], v[190:193], 0
	v_mfma_f32_16x16x32_bf16 v[100:103], v[172:175], v[198:201], 0
	v_mfma_f32_16x16x32_bf16 v[112:115], v[182:185], v[190:193], 0
	v_mfma_f32_16x16x32_bf16 v[96:99], v[182:185], v[198:201], 0
	v_mfma_f32_16x16x32_bf16 v[84:87], v[172:175], v[212:215], 0
	v_mfma_f32_16x16x32_bf16 v[68:71], v[172:175], v[220:223], 0
	v_mfma_f32_16x16x32_bf16 v[80:83], v[182:185], v[212:215], 0
	v_mfma_f32_16x16x32_bf16 v[64:67], v[182:185], v[220:223], 0
	v_mfma_f32_16x16x32_bf16 v[116:119], v[176:179], v[194:197], v[116:119]
	v_mfma_f32_16x16x32_bf16 v[100:103], v[176:179], v[208:211], v[100:103]
	v_mfma_f32_16x16x32_bf16 v[112:115], v[186:189], v[194:197], v[112:115]
	v_mfma_f32_16x16x32_bf16 v[96:99], v[186:189], v[208:211], v[96:99]
	v_mfma_f32_16x16x32_bf16 v[84:87], v[176:179], v[216:219], v[84:87]
	v_mfma_f32_16x16x32_bf16 v[68:71], v[176:179], v[224:227], v[68:71]
	v_mfma_f32_16x16x32_bf16 v[80:83], v[186:189], v[216:219], v[80:83]
	v_mfma_f32_16x16x32_bf16 v[64:67], v[186:189], v[224:227], v[64:67]
	s_setprio 0
	s_barrier
	s_add_i32 s3, s74, s34
	v_lshl_add_u64 v[202:203], s[58:59], 0, v[136:137]
	s_mov_b32 m0, s3
	ds_read_b128 v[190:193], v157 offset:16384
	ds_read_b128 v[194:197], v157 offset:17408
	ds_read_b128 v[198:201], v157 offset:18432
	ds_read_b128 v[208:211], v157 offset:19456
	ds_read_b128 v[212:215], v157 offset:20480
	ds_read_b128 v[216:219], v157 offset:21504
	ds_read_b128 v[220:223], v157 offset:22528
	ds_read_b128 v[224:227], v157 offset:23552
	global_load_lds_dwordx4 v[202:203], off
	s_add_i32 m0, s3, 0x2000
	s_add_u32 s14, s58, 0x40000
	v_lshl_add_u64 v[228:229], s[58:59], 0, v[132:133]
	s_addc_u32 s15, s59, 0
	s_add_i32 s3, s75, s34
	global_load_lds_dwordx4 v[228:229], off
	v_lshl_add_u64 v[230:231], s[14:15], 0, v[136:137]
	s_mov_b32 m0, s3
	global_load_lds_dwordx4 v[230:231], off
	v_lshl_add_u64 v[230:231], s[14:15], 0, v[132:133]
	s_add_i32 m0, s3, 0x2000
	s_nop 0
	global_load_lds_dwordx4 v[230:231], off
	s_waitcnt vmcnt(6)
	s_waitcnt lgkmcnt(0)
	s_barrier
; #define PG8_STAGE(bufoff, gbase, voff) do { _Pragma("unroll") for (int _i = 0; _i < 2; ++_i) \
;         __builtin_amdgcn_global_load_lds((const unsigned*)((const char*)(gbase) + (voff)[_i]), (PG8_LAS unsigned*)(lds + (bufoff) + ldsw + _i * 8192), 16, 0, 0); } while (0)
; #define PG8_LDA(dst, b, h) do { _Pragma("unroll") for (int m = 0; m < 4; ++m) _Pragma("unroll") for (int k = 0; k < 2; ++k) dst[m][k] = *(const PG8_LAS bf16x8*)(lds + PG8_SA(b, h) + aoff + m * 2048 + k * 1024); } while (0)
; #define PG8_LDB(dst, b, h) do { _Pragma("unroll") for (int n = 0; n < 2; ++n) _Pragma("unroll") for (int k = 0; k < 2; ++k) dst[n][k] = *(const PG8_LAS bf16x8*)(lds + PG8_SB(b, h) + boff + n * 2048 + k * 1024); } while (0)
; #define PG8_MMA(ai, bj, At, Bt) do { __builtin_amdgcn_s_setprio(1); _Pragma("unroll") for (int m = 0; m < 4; ++m) _Pragma("unroll") for (int n = 0; n < 2; ++n) _Pragma("unroll") for (int k = 0; k < 2; ++k) \
;         acc[ai][bj][m][n] = __builtin_amdgcn_mfma_f32_16x16x32_bf16(Bt[n][k], At[m][k], acc[ai][bj][m][n], 0, 0, 0); __builtin_amdgcn_s_setprio(0); } while (0)
; #define PG8_WAIT_V(n) asm volatile("s_waitcnt vmcnt(" #n ")" ::: "memory")
; #define PG8_WAIT_L(n) asm volatile("s_waitcnt lgkmcnt(" #n ")" ::: "memory")
; #define PG8_BAR __builtin_amdgcn_s_barrier()
; #define PG8_SCHED __builtin_amdgcn_sched_barrier(0)
; template <class Epi, class Sched, bool ALIGN_EPI = false, bool SP2 = false>
; __device__ __forceinline__ void gemm_phase(PG8_LAS unsigned char* lds, const Gemm g, const Sched& S, const Epi& E) {
;     ...
;             PG8_WAIT_V(8); PG8_WAIT_L(0); PG8_BAR; PG8_MMA(1, 0, At, B0); PG8_MMA(1, 1, At, B1); PG8_BAR; PG8_SCHED;
;             PG8_LDB(B0, 1, 0); PG8_LDB(B1, 1, 1); PG8_SCHED; PG8_LDA(At, 1, 0); PG8_STAGE(PG8_SA(0, 1), a2 + hstep, voffA);
;             PG8_WAIT_V(8); PG8_WAIT_L(0); PG8_BAR; PG8_MMA(0, 0, At, B0); PG8_MMA(0, 1, At, B1); PG8_BAR; PG8_SCHED;
	s_setprio 1
	s_waitcnt lgkmcnt(0)
	v_mfma_f32_16x16x32_bf16 v[60:63], v[148:151], v[190:193], 0
	v_mfma_f32_16x16x32_bf16 v[44:47], v[148:151], v[198:201], 0
	v_mfma_f32_16x16x32_bf16 v[56:59], v[164:167], v[190:193], 0
	v_mfma_f32_16x16x32_bf16 v[40:43], v[164:167], v[198:201], 0
	v_mfma_f32_16x16x32_bf16 v[28:31], v[148:151], v[212:215], 0
	v_mfma_f32_16x16x32_bf16 v[12:15], v[148:151], v[220:223], 0
	v_mfma_f32_16x16x32_bf16 v[24:27], v[164:167], v[212:215], 0
	v_mfma_f32_16x16x32_bf16 v[8:11], v[164:167], v[220:223], 0
	v_mfma_f32_16x16x32_bf16 v[60:63], v[160:163], v[194:197], v[60:63]
	v_mfma_f32_16x16x32_bf16 v[44:47], v[160:163], v[208:211], v[44:47]
	v_mfma_f32_16x16x32_bf16 v[56:59], v[168:171], v[194:197], v[56:59]
	v_mfma_f32_16x16x32_bf16 v[40:43], v[168:171], v[208:211], v[40:43]
	v_mfma_f32_16x16x32_bf16 v[28:31], v[160:163], v[216:219], v[28:31]
	v_mfma_f32_16x16x32_bf16 v[12:15], v[160:163], v[224:227], v[12:15]
	v_lshl_add_u64 v[230:231], s[60:61], 0, v[138:139]
	s_mov_b32 m0, s43
	s_nop 0
	global_load_lds_dwordx4 v[230:231], off
	v_mfma_f32_16x16x32_bf16 v[24:27], v[168:171], v[216:219], v[24:27]
	v_mfma_f32_16x16x32_bf16 v[8:11], v[168:171], v[224:227], v[8:11]
	s_setprio 0
	s_setprio 1
	v_mfma_f32_16x16x32_bf16 v[52:55], v[172:175], v[190:193], 0
	v_mfma_f32_16x16x32_bf16 v[36:39], v[172:175], v[198:201], 0
	v_mfma_f32_16x16x32_bf16 v[48:51], v[182:185], v[190:193], 0
	v_mfma_f32_16x16x32_bf16 v[32:35], v[182:185], v[198:201], 0
	v_mfma_f32_16x16x32_bf16 v[20:23], v[172:175], v[212:215], 0
	v_mfma_f32_16x16x32_bf16 v[4:7], v[172:175], v[220:223], 0
	v_mfma_f32_16x16x32_bf16 v[16:19], v[182:185], v[212:215], 0
	v_mfma_f32_16x16x32_bf16 v[0:3], v[182:185], v[220:223], 0
	v_mfma_f32_16x16x32_bf16 v[52:55], v[176:179], v[194:197], v[52:55]
	v_mfma_f32_16x16x32_bf16 v[36:39], v[176:179], v[208:211], v[36:39]
	v_mfma_f32_16x16x32_bf16 v[48:51], v[186:189], v[194:197], v[48:51]
	v_mfma_f32_16x16x32_bf16 v[32:35], v[186:189], v[208:211], v[32:35]
	v_mfma_f32_16x16x32_bf16 v[20:23], v[176:179], v[216:219], v[20:23]
	v_mfma_f32_16x16x32_bf16 v[4:7], v[176:179], v[224:227], v[4:7]
	v_lshl_add_u64 v[232:233], s[60:61], 0, v[134:135]
	s_mov_b32 m0, s62
	s_nop 0
	global_load_lds_dwordx4 v[232:233], off
	v_mfma_f32_16x16x32_bf16 v[16:19], v[186:189], v[216:219], v[16:19]
	v_mfma_f32_16x16x32_bf16 v[0:3], v[186:189], v[224:227], v[0:3]
	s_setprio 0
	s_barrier
	s_add_i32 s3, 0, 0x18000
	v_add_u32_e32 v159, s3, v131
	s_add_i32 s33, 0, 0x1c000
	ds_read_b128 v[148:151], v159
	ds_read_b128 v[160:163], v159 offset:1024
	ds_read_b128 v[164:167], v159 offset:2048
	ds_read_b128 v[168:171], v159 offset:3072
	v_add_u32_e32 v159, s33, v131
	ds_read_b128 v[172:175], v159
	ds_read_b128 v[176:179], v159 offset:1024
	ds_read_b128 v[182:185], v159 offset:2048
	ds_read_b128 v[186:189], v159 offset:3072
	s_add_u32 s14, s60, 0x40000
	s_addc_u32 s15, s61, 0
	s_mov_b32 m0, s63
	v_lshl_add_u64 v[234:235], s[14:15], 0, v[138:139]
	ds_read_b128 v[190:193], v157 offset:32768
	ds_read_b128 v[194:197], v157 offset:33792
	ds_read_b128 v[198:201], v157 offset:34816
	ds_read_b128 v[208:211], v157 offset:35840
	ds_read_b128 v[212:215], v157 offset:36864
	ds_read_b128 v[216:219], v157 offset:37888
	ds_read_b128 v[220:223], v157 offset:38912
	ds_read_b128 v[224:227], v157 offset:39936
	global_load_lds_dwordx4 v[234:235], off
	v_lshl_add_u64 v[234:235], s[14:15], 0, v[134:135]
	s_mov_b32 m0, s64
	s_nop 0
	global_load_lds_dwordx4 v[234:235], off
	s_waitcnt vmcnt(8)
	s_waitcnt lgkmcnt(0)
	s_barrier
	s_setprio 1
	s_waitcnt lgkmcnt(0)
	v_mfma_f32_16x16x32_bf16 v[124:127], v[148:151], v[190:193], v[124:127]
	v_mfma_f32_16x16x32_bf16 v[108:111], v[148:151], v[198:201], v[108:111]
	v_mfma_f32_16x16x32_bf16 v[120:123], v[164:167], v[190:193], v[120:123]
	v_mfma_f32_16x16x32_bf16 v[104:107], v[164:167], v[198:201], v[104:107]
	v_mfma_f32_16x16x32_bf16 v[92:95], v[148:151], v[212:215], v[92:95]
	v_mfma_f32_16x16x32_bf16 v[76:79], v[148:151], v[220:223], v[76:79]
	v_mfma_f32_16x16x32_bf16 v[88:91], v[164:167], v[212:215], v[88:91]
	v_mfma_f32_16x16x32_bf16 v[72:75], v[164:167], v[220:223], v[72:75]
	v_mfma_f32_16x16x32_bf16 v[124:127], v[160:163], v[194:197], v[124:127]
	v_mfma_f32_16x16x32_bf16 v[108:111], v[160:163], v[208:211], v[108:111]
	v_mfma_f32_16x16x32_bf16 v[120:123], v[168:171], v[194:197], v[120:123]
	v_mfma_f32_16x16x32_bf16 v[104:107], v[168:171], v[208:211], v[104:107]
	v_mfma_f32_16x16x32_bf16 v[92:95], v[160:163], v[216:219], v[92:95]
	v_mfma_f32_16x16x32_bf16 v[76:79], v[160:163], v[224:227], v[76:79]
	v_mfma_f32_16x16x32_bf16 v[88:91], v[168:171], v[216:219], v[88:91]
	v_mfma_f32_16x16x32_bf16 v[72:75], v[168:171], v[224:227], v[72:75]
	s_setprio 0
	s_setprio 1
	v_mfma_f32_16x16x32_bf16 v[116:119], v[172:175], v[190:193], v[116:119]
	v_mfma_f32_16x16x32_bf16 v[100:103], v[172:175], v[198:201], v[100:103]
	v_mfma_f32_16x16x32_bf16 v[112:115], v[182:185], v[190:193], v[112:115]
	v_mfma_f32_16x16x32_bf16 v[96:99], v[182:185], v[198:201], v[96:99]
	v_mfma_f32_16x16x32_bf16 v[84:87], v[172:175], v[212:215], v[84:87]
	v_mfma_f32_16x16x32_bf16 v[68:71], v[172:175], v[220:223], v[68:71]
	v_mfma_f32_16x16x32_bf16 v[80:83], v[182:185], v[212:215], v[80:83]
	v_mfma_f32_16x16x32_bf16 v[64:67], v[182:185], v[220:223], v[64:67]
	v_mfma_f32_16x16x32_bf16 v[116:119], v[176:179], v[194:197], v[116:119]
	v_mfma_f32_16x16x32_bf16 v[100:103], v[176:179], v[208:211], v[100:103]
	v_mfma_f32_16x16x32_bf16 v[112:115], v[186:189], v[194:197], v[112:115]
	v_mfma_f32_16x16x32_bf16 v[96:99], v[186:189], v[208:211], v[96:99]
	v_mfma_f32_16x16x32_bf16 v[84:87], v[176:179], v[216:219], v[84:87]
	v_mfma_f32_16x16x32_bf16 v[68:71], v[176:179], v[224:227], v[68:71]
	v_mfma_f32_16x16x32_bf16 v[80:83], v[186:189], v[216:219], v[80:83]
	v_mfma_f32_16x16x32_bf16 v[64:67], v[186:189], v[224:227], v[64:67]
	s_setprio 0
	s_barrier
; #define PG8_STAGE(bufoff, gbase, voff) do { _Pragma("unroll") for (int _i = 0; _i < 2; ++_i) \
;         __builtin_amdgcn_global_load_lds((const unsigned*)((const char*)(gbase) + (voff)[_i]), (PG8_LAS unsigned*)(lds + (bufoff) + ldsw + _i * 8192), 16, 0, 0); } while (0)
; #define PG8_LDA(dst, b, h) do { _Pragma("unroll") for (int m = 0; m < 4; ++m) _Pragma("unroll") for (int k = 0; k < 2; ++k) dst[m][k] = *(const PG8_LAS bf16x8*)(lds + PG8_SA(b, h) + aoff + m * 2048 + k * 1024); } while (0)
; #define PG8_LDB(dst, b, h) do { _Pragma("unroll") for (int n = 0; n < 2; ++n) _Pragma("unroll") for (int k = 0; k < 2; ++k) dst[n][k] = *(const PG8_LAS bf16x8*)(lds + PG8_SB(b, h) + boff + n * 2048 + k * 1024); } while (0)
; #define PG8_MMA(ai, bj, At, Bt) do { __builtin_amdgcn_s_setprio(1); _Pragma("unroll") for (int m = 0; m < 4; ++m) _Pragma("unroll") for (int n = 0; n < 2; ++n) _Pragma("unroll") for (int k = 0; k < 2; ++k) \
;         acc[ai][bj][m][n] = __builtin_amdgcn_mfma_f32_16x16x32_bf16(Bt[n][k], At[m][k], acc[ai][bj][m][n], 0, 0, 0); __builtin_amdgcn_s_setprio(0); } while (0)
; #define PG8_WAIT_V(n) asm volatile("s_waitcnt vmcnt(" #n ")" ::: "memory")
; template <class Epi, class Sched, bool ALIGN_EPI = false, bool SP2 = false>
; __device__ __forceinline__ void gemm_phase(PG8_LAS unsigned char* lds, const Gemm g, const Sched& S, const Epi& E) {
;     ...
;             PG8_LDB(B0, 0, 0); PG8_LDB(B1, 0, 1); PG8_SCHED; PG8_LDA(At, 0, 0); PG8_STAGE(PG8_SA(1, 1), a1 + hstep, voffA);
;             PG8_WAIT_V(8); PG8_WAIT_L(0); PG8_BAR; PG8_MMA(0, 0, At, B0); PG8_MMA(0, 1, At, B1); PG8_BAR; PG8_SCHED;
;             PG8_LDA(At, 0, 1); PG8_STAGE(PG8_SB(0, 0), b2, voffB); PG8_STAGE(PG8_SB(0, 1), b2 + hstep, voffB); PG8_STAGE(PG8_SA(0, 0), a2, voffA);
;             PG8_WAIT_V(8); PG8_WAIT_L(0); PG8_BAR; PG8_MMA(1, 0, At, B0); PG8_MMA(1, 1, At, B1); PG8_BAR; PG8_SCHED;
;             PG8_LDB(B0, 1, 0); PG8_LDB(B1, 1, 1); PG8_SCHED; PG8_LDA(At, 1, 0); PG8_STAGE(PG8_SA(0, 1), a2 + hstep, voffA);
;             PG8_WAIT_V(8); PG8_WAIT_L(0); PG8_BAR; PG8_MMA(0, 0, At, B0); PG8_MMA(0, 1, At, B1); PG8_BAR; PG8_SCHED;
;             PG8_LDA(At, 1, 1); PG8_STAGE(PG8_SB(1, 0), b3, voffB); PG8_STAGE(PG8_SB(1, 1), b3 + hstep, voffB); PG8_STAGE(PG8_SA(1, 0), a3, voffA);
;             PG8_WAIT_V(8); PG8_WAIT_L(0); PG8_BAR; PG8_MMA(1, 0, At, B0); PG8_MMA(1, 1, At, B1); PG8_BAR; PG8_SCHED;
	s_add_i32 s3, s3, s34
	v_lshl_add_u64 v[202:203], v[202:203], 0, s[38:39]
	s_mov_b32 m0, s3
	ds_read_b128 v[190:193], v157 offset:49152
	ds_read_b128 v[194:197], v157 offset:50176
	ds_read_b128 v[198:201], v157 offset:51200
	ds_read_b128 v[208:211], v157 offset:52224
	ds_read_b128 v[212:215], v157 offset:53248
	ds_read_b128 v[216:219], v157 offset:54272
	ds_read_b128 v[220:223], v157 offset:55296
	ds_read_b128 v[224:227], v157 offset:56320
	global_load_lds_dwordx4 v[202:203], off
	s_add_i32 m0, s3, 0x2000
	s_add_u32 s14, s58, 0x40080
	v_lshl_add_u64 v[202:203], v[228:229], 0, s[38:39]
	s_addc_u32 s15, s59, 0
	s_add_i32 s3, s33, s34
	global_load_lds_dwordx4 v[202:203], off
	v_lshl_add_u64 v[202:203], s[14:15], 0, v[136:137]
	s_mov_b32 m0, s3
	s_nop 0
	global_load_lds_dwordx4 v[202:203], off
	v_lshl_add_u64 v[202:203], s[14:15], 0, v[132:133]
	s_add_i32 m0, s3, 0x2000
	s_nop 0
	global_load_lds_dwordx4 v[202:203], off
	s_waitcnt vmcnt(6)
	s_waitcnt lgkmcnt(0)
	s_barrier
	s_setprio 1
	s_waitcnt lgkmcnt(0)
	v_mfma_f32_16x16x32_bf16 v[60:63], v[148:151], v[190:193], v[60:63]
	v_mfma_f32_16x16x32_bf16 v[44:47], v[148:151], v[198:201], v[44:47]
	v_mfma_f32_16x16x32_bf16 v[56:59], v[164:167], v[190:193], v[56:59]
	v_mfma_f32_16x16x32_bf16 v[40:43], v[164:167], v[198:201], v[40:43]
	v_mfma_f32_16x16x32_bf16 v[28:31], v[148:151], v[212:215], v[28:31]
	v_mfma_f32_16x16x32_bf16 v[12:15], v[148:151], v[220:223], v[12:15]
	v_mfma_f32_16x16x32_bf16 v[24:27], v[164:167], v[212:215], v[24:27]
	v_mfma_f32_16x16x32_bf16 v[8:11], v[164:167], v[220:223], v[8:11]
	v_mfma_f32_16x16x32_bf16 v[60:63], v[160:163], v[194:197], v[60:63]
	v_mfma_f32_16x16x32_bf16 v[44:47], v[160:163], v[208:211], v[44:47]
	v_mfma_f32_16x16x32_bf16 v[56:59], v[168:171], v[194:197], v[56:59]
	v_mfma_f32_16x16x32_bf16 v[40:43], v[168:171], v[208:211], v[40:43]
	v_mfma_f32_16x16x32_bf16 v[28:31], v[160:163], v[216:219], v[28:31]
	v_mfma_f32_16x16x32_bf16 v[12:15], v[160:163], v[224:227], v[12:15]
	v_lshl_add_u64 v[202:203], v[230:231], 0, s[38:39]
	s_mov_b32 m0, s66
	s_nop 0
	global_load_lds_dwordx4 v[202:203], off
	v_mfma_f32_16x16x32_bf16 v[24:27], v[168:171], v[216:219], v[24:27]
	v_mfma_f32_16x16x32_bf16 v[8:11], v[168:171], v[224:227], v[8:11]
	s_setprio 0
	s_setprio 1
	v_mfma_f32_16x16x32_bf16 v[52:55], v[172:175], v[190:193], v[52:55]
	v_mfma_f32_16x16x32_bf16 v[36:39], v[172:175], v[198:201], v[36:39]
	v_mfma_f32_16x16x32_bf16 v[48:51], v[182:185], v[190:193], v[48:51]
	v_mfma_f32_16x16x32_bf16 v[32:35], v[182:185], v[198:201], v[32:35]
	v_mfma_f32_16x16x32_bf16 v[20:23], v[172:175], v[212:215], v[20:23]
	v_mfma_f32_16x16x32_bf16 v[4:7], v[172:175], v[220:223], v[4:7]
	v_mfma_f32_16x16x32_bf16 v[16:19], v[182:185], v[212:215], v[16:19]
	v_mfma_f32_16x16x32_bf16 v[0:3], v[182:185], v[220:223], v[0:3]
	v_mfma_f32_16x16x32_bf16 v[52:55], v[176:179], v[194:197], v[52:55]
	v_mfma_f32_16x16x32_bf16 v[36:39], v[176:179], v[208:211], v[36:39]
	v_mfma_f32_16x16x32_bf16 v[48:51], v[186:189], v[194:197], v[48:51]
	v_mfma_f32_16x16x32_bf16 v[32:35], v[186:189], v[208:211], v[32:35]
	v_mfma_f32_16x16x32_bf16 v[20:23], v[176:179], v[216:219], v[20:23]
	v_mfma_f32_16x16x32_bf16 v[4:7], v[176:179], v[224:227], v[4:7]
	v_lshl_add_u64 v[202:203], v[232:233], 0, s[38:39]
	s_mov_b32 m0, s67
	s_nop 0
	global_load_lds_dwordx4 v[202:203], off
	v_mfma_f32_16x16x32_bf16 v[16:19], v[186:189], v[216:219], v[16:19]
	v_mfma_f32_16x16x32_bf16 v[0:3], v[186:189], v[224:227], v[0:3]
	s_setprio 0
	s_barrier
	s_add_i32 s86, s86, 2
	s_add_u32 s56, s56, 0x100
	s_addc_u32 s57, s57, 0
	s_add_u32 s84, s84, 0x100
	s_addc_u32 s85, s85, 0
.LBB0_738:
	ds_read_b128 v[148:151], v155
	ds_read_b128 v[160:163], v155 offset:1024
	ds_read_b128 v[164:167], v155 offset:2048
	ds_read_b128 v[168:171], v155 offset:3072
	ds_read_b128 v[172:175], v156
	ds_read_b128 v[176:179], v156 offset:1024
	ds_read_b128 v[182:185], v156 offset:2048
	ds_read_b128 v[186:189], v156 offset:3072
	s_add_u32 s3, s56, 0xfffc0080
	s_addc_u32 s14, s57, -1
	s_cmp_eq_u32 s86, 12
	s_cselect_b32 s61, s51, s14
	s_cselect_b32 s60, s82, s3
	s_cselect_b32 s59, s49, s85
	s_cselect_b32 s58, s83, s84
	v_lshl_add_u64 v[202:203], s[56:57], 0, v[140:141]
	s_add_i32 m0, s43, 0xc000
	ds_read_b128 v[190:193], v157
	ds_read_b128 v[194:197], v157 offset:1024
	ds_read_b128 v[198:201], v157 offset:2048
	ds_read_b128 v[208:211], v157 offset:3072
	ds_read_b128 v[212:215], v157 offset:4096
	ds_read_b128 v[216:219], v157 offset:5120
	ds_read_b128 v[220:223], v157 offset:6144
	ds_read_b128 v[224:227], v157 offset:7168
	global_load_lds_dwordx4 v[202:203], off
	v_lshl_add_u64 v[202:203], s[56:57], 0, v[142:143]
	s_add_i32 m0, s43, 0xe000
	s_nop 0
	global_load_lds_dwordx4 v[202:203], off
	s_waitcnt vmcnt(8)
	s_waitcnt lgkmcnt(0)
	s_barrier
; #define PG8_STAGE(bufoff, gbase, voff) do { _Pragma("unroll") for (int _i = 0; _i < 2; ++_i) \
;         __builtin_amdgcn_global_load_lds((const unsigned*)((const char*)(gbase) + (voff)[_i]), (PG8_LAS unsigned*)(lds + (bufoff) + ldsw + _i * 8192), 16, 0, 0); } while (0)
; #define PG8_LDA(dst, b, h) do { _Pragma("unroll") for (int m = 0; m < 4; ++m) _Pragma("unroll") for (int k = 0; k < 2; ++k) dst[m][k] = *(const PG8_LAS bf16x8*)(lds + PG8_SA(b, h) + aoff + m * 2048 + k * 1024); } while (0)
; #define PG8_MMA(ai, bj, At, Bt) do { __builtin_amdgcn_s_setprio(1); _Pragma("unroll") for (int m = 0; m < 4; ++m) _Pragma("unroll") for (int n = 0; n < 2; ++n) _Pragma("unroll") for (int k = 0; k < 2; ++k) \
;         acc[ai][bj][m][n] = __builtin_amdgcn_mfma_f32_16x16x32_bf16(Bt[n][k], At[m][k], acc[ai][bj][m][n], 0, 0, 0); __builtin_amdgcn_s_setprio(0); } while (0)
; #define PG8_WAIT_V(n) asm volatile("s_waitcnt vmcnt(" #n ")" ::: "memory")
; #define PG8_WAIT_L(n) asm volatile("s_waitcnt lgkmcnt(" #n ")" ::: "memory")
; #define PG8_BAR __builtin_amdgcn_s_barrier()
; #define PG8_SCHED __builtin_amdgcn_sched_barrier(0)
; template <class Epi, class Sched, bool ALIGN_EPI = false, bool SP2 = false>
; __device__ __forceinline__ void gemm_phase(PG8_LAS unsigned char* lds, const Gemm g, const Sched& S, const Epi& E) {
;     ...
;             PG8_WAIT_V(8); PG8_WAIT_L(0); PG8_BAR; PG8_MMA(0, 0, At, B0); PG8_MMA(0, 1, At, B1); PG8_BAR; PG8_SCHED;
;             PG8_LDA(At, 0, 1); PG8_STAGE(PG8_SB(0, 0), b2, voffB); PG8_STAGE(PG8_SB(0, 1), b2 + hstep, voffB); PG8_STAGE(PG8_SA(0, 0), a2, voffA);
;             PG8_WAIT_V(8); PG8_WAIT_L(0); PG8_BAR; PG8_MMA(1, 0, At, B0); PG8_MMA(1, 1, At, B1); PG8_BAR; PG8_SCHED;
	s_setprio 1
	s_waitcnt lgkmcnt(0)
	v_mfma_f32_16x16x32_bf16 v[124:127], v[148:151], v[190:193], v[124:127]
	v_mfma_f32_16x16x32_bf16 v[108:111], v[148:151], v[198:201], v[108:111]
	v_mfma_f32_16x16x32_bf16 v[120:123], v[164:167], v[190:193], v[120:123]
	v_mfma_f32_16x16x32_bf16 v[104:107], v[164:167], v[198:201], v[104:107]
	v_mfma_f32_16x16x32_bf16 v[92:95], v[148:151], v[212:215], v[92:95]
	v_mfma_f32_16x16x32_bf16 v[76:79], v[148:151], v[220:223], v[76:79]
	v_mfma_f32_16x16x32_bf16 v[88:91], v[164:167], v[212:215], v[88:91]
	v_mfma_f32_16x16x32_bf16 v[72:75], v[164:167], v[220:223], v[72:75]
	v_mfma_f32_16x16x32_bf16 v[124:127], v[160:163], v[194:197], v[124:127]
	v_mfma_f32_16x16x32_bf16 v[108:111], v[160:163], v[208:211], v[108:111]
	v_mfma_f32_16x16x32_bf16 v[120:123], v[168:171], v[194:197], v[120:123]
	v_mfma_f32_16x16x32_bf16 v[104:107], v[168:171], v[208:211], v[104:107]
	v_mfma_f32_16x16x32_bf16 v[92:95], v[160:163], v[216:219], v[92:95]
	v_mfma_f32_16x16x32_bf16 v[76:79], v[160:163], v[224:227], v[76:79]
	v_mfma_f32_16x16x32_bf16 v[88:91], v[168:171], v[216:219], v[88:91]
	v_mfma_f32_16x16x32_bf16 v[72:75], v[168:171], v[224:227], v[72:75]
	s_setprio 0
	s_setprio 1
	v_mfma_f32_16x16x32_bf16 v[116:119], v[172:175], v[190:193], v[116:119]
	v_mfma_f32_16x16x32_bf16 v[100:103], v[172:175], v[198:201], v[100:103]
	v_mfma_f32_16x16x32_bf16 v[112:115], v[182:185], v[190:193], v[112:115]
	v_mfma_f32_16x16x32_bf16 v[96:99], v[182:185], v[198:201], v[96:99]
	v_mfma_f32_16x16x32_bf16 v[84:87], v[172:175], v[212:215], v[84:87]
	v_mfma_f32_16x16x32_bf16 v[68:71], v[172:175], v[220:223], v[68:71]
	v_mfma_f32_16x16x32_bf16 v[80:83], v[182:185], v[212:215], v[80:83]
	v_mfma_f32_16x16x32_bf16 v[64:67], v[182:185], v[220:223], v[64:67]
	v_mfma_f32_16x16x32_bf16 v[116:119], v[176:179], v[194:197], v[116:119]
	v_mfma_f32_16x16x32_bf16 v[100:103], v[176:179], v[208:211], v[100:103]
	v_mfma_f32_16x16x32_bf16 v[112:115], v[186:189], v[194:197], v[112:115]
	v_mfma_f32_16x16x32_bf16 v[96:99], v[186:189], v[208:211], v[96:99]
	v_mfma_f32_16x16x32_bf16 v[84:87], v[176:179], v[216:219], v[84:87]
	v_mfma_f32_16x16x32_bf16 v[68:71], v[176:179], v[224:227], v[68:71]
	v_mfma_f32_16x16x32_bf16 v[80:83], v[186:189], v[216:219], v[80:83]
	v_mfma_f32_16x16x32_bf16 v[64:67], v[186:189], v[224:227], v[64:67]
	s_setprio 0
	s_barrier
	s_add_i32 s3, s74, s34
	v_lshl_add_u64 v[202:203], s[58:59], 0, v[136:137]
	s_mov_b32 m0, s3
	ds_read_b128 v[190:193], v157 offset:16384
	ds_read_b128 v[194:197], v157 offset:17408
	ds_read_b128 v[198:201], v157 offset:18432
	ds_read_b128 v[208:211], v157 offset:19456
	ds_read_b128 v[212:215], v157 offset:20480
	ds_read_b128 v[216:219], v157 offset:21504
	ds_read_b128 v[220:223], v157 offset:22528
	ds_read_b128 v[224:227], v157 offset:23552
	global_load_lds_dwordx4 v[202:203], off
	s_add_i32 m0, s3, 0x2000
	s_add_u32 s14, s58, 0x40000
	v_lshl_add_u64 v[228:229], s[58:59], 0, v[132:133]
	s_addc_u32 s15, s59, 0
	s_add_i32 s3, s75, s34
	global_load_lds_dwordx4 v[228:229], off
	v_lshl_add_u64 v[230:231], s[14:15], 0, v[136:137]
	s_mov_b32 m0, s3
	global_load_lds_dwordx4 v[230:231], off
	v_lshl_add_u64 v[230:231], s[14:15], 0, v[132:133]
	s_add_i32 m0, s3, 0x2000
	s_nop 0
	global_load_lds_dwordx4 v[230:231], off
	s_waitcnt vmcnt(6)
	s_waitcnt lgkmcnt(0)
	s_barrier
	s_setprio 1
	s_waitcnt lgkmcnt(0)
	v_mfma_f32_16x16x32_bf16 v[60:63], v[148:151], v[190:193], v[60:63]
	v_mfma_f32_16x16x32_bf16 v[44:47], v[148:151], v[198:201], v[44:47]
	v_mfma_f32_16x16x32_bf16 v[56:59], v[164:167], v[190:193], v[56:59]
	v_mfma_f32_16x16x32_bf16 v[40:43], v[164:167], v[198:201], v[40:43]
	v_mfma_f32_16x16x32_bf16 v[28:31], v[148:151], v[212:215], v[28:31]
	v_mfma_f32_16x16x32_bf16 v[12:15], v[148:151], v[220:223], v[12:15]
	v_mfma_f32_16x16x32_bf16 v[24:27], v[164:167], v[212:215], v[24:27]
	v_mfma_f32_16x16x32_bf16 v[8:11], v[164:167], v[220:223], v[8:11]
	v_mfma_f32_16x16x32_bf16 v[60:63], v[160:163], v[194:197], v[60:63]
	v_mfma_f32_16x16x32_bf16 v[44:47], v[160:163], v[208:211], v[44:47]
	v_mfma_f32_16x16x32_bf16 v[56:59], v[168:171], v[194:197], v[56:59]
	v_mfma_f32_16x16x32_bf16 v[40:43], v[168:171], v[208:211], v[40:43]
	v_mfma_f32_16x16x32_bf16 v[28:31], v[160:163], v[216:219], v[28:31]
	v_mfma_f32_16x16x32_bf16 v[12:15], v[160:163], v[224:227], v[12:15]
	v_lshl_add_u64 v[230:231], s[60:61], 0, v[138:139]
	s_mov_b32 m0, s43
	s_nop 0
	global_load_lds_dwordx4 v[230:231], off
	v_mfma_f32_16x16x32_bf16 v[24:27], v[168:171], v[216:219], v[24:27]
	v_mfma_f32_16x16x32_bf16 v[8:11], v[168:171], v[224:227], v[8:11]
	s_setprio 0
	s_setprio 1
	v_mfma_f32_16x16x32_bf16 v[52:55], v[172:175], v[190:193], v[52:55]
	v_mfma_f32_16x16x32_bf16 v[36:39], v[172:175], v[198:201], v[36:39]
	v_mfma_f32_16x16x32_bf16 v[48:51], v[182:185], v[190:193], v[48:51]
	v_mfma_f32_16x16x32_bf16 v[32:35], v[182:185], v[198:201], v[32:35]
	v_mfma_f32_16x16x32_bf16 v[20:23], v[172:175], v[212:215], v[20:23]
	v_mfma_f32_16x16x32_bf16 v[4:7], v[172:175], v[220:223], v[4:7]
	v_mfma_f32_16x16x32_bf16 v[16:19], v[182:185], v[212:215], v[16:19]
	v_mfma_f32_16x16x32_bf16 v[0:3], v[182:185], v[220:223], v[0:3]
	v_mfma_f32_16x16x32_bf16 v[52:55], v[176:179], v[194:197], v[52:55]
	v_mfma_f32_16x16x32_bf16 v[36:39], v[176:179], v[208:211], v[36:39]
	v_mfma_f32_16x16x32_bf16 v[48:51], v[186:189], v[194:197], v[48:51]
	v_mfma_f32_16x16x32_bf16 v[32:35], v[186:189], v[208:211], v[32:35]
	v_mfma_f32_16x16x32_bf16 v[20:23], v[176:179], v[216:219], v[20:23]
	v_mfma_f32_16x16x32_bf16 v[4:7], v[176:179], v[224:227], v[4:7]
	v_lshl_add_u64 v[232:233], s[60:61], 0, v[134:135]
	s_mov_b32 m0, s62
	s_nop 0
	global_load_lds_dwordx4 v[232:233], off
	v_mfma_f32_16x16x32_bf16 v[16:19], v[186:189], v[216:219], v[16:19]
	v_mfma_f32_16x16x32_bf16 v[0:3], v[186:189], v[224:227], v[0:3]
	s_setprio 0
	s_barrier
; #define PG8_STAGE(bufoff, gbase, voff) do { _Pragma("unroll") for (int _i = 0; _i < 2; ++_i) \
;         __builtin_amdgcn_global_load_lds((const unsigned*)((const char*)(gbase) + (voff)[_i]), (PG8_LAS unsigned*)(lds + (bufoff) + ldsw + _i * 8192), 16, 0, 0); } while (0)
; #define PG8_LDA(dst, b, h) do { _Pragma("unroll") for (int m = 0; m < 4; ++m) _Pragma("unroll") for (int k = 0; k < 2; ++k) dst[m][k] = *(const PG8_LAS bf16x8*)(lds + PG8_SA(b, h) + aoff + m * 2048 + k * 1024); } while (0)
; #define PG8_LDB(dst, b, h) do { _Pragma("unroll") for (int n = 0; n < 2; ++n) _Pragma("unroll") for (int k = 0; k < 2; ++k) dst[n][k] = *(const PG8_LAS bf16x8*)(lds + PG8_SB(b, h) + boff + n * 2048 + k * 1024); } while (0)
; #define PG8_MMA(ai, bj, At, Bt) do { __builtin_amdgcn_s_setprio(1); _Pragma("unroll") for (int m = 0; m < 4; ++m) _Pragma("unroll") for (int n = 0; n < 2; ++n) _Pragma("unroll") for (int k = 0; k < 2; ++k) \
;         acc[ai][bj][m][n] = __builtin_amdgcn_mfma_f32_16x16x32_bf16(Bt[n][k], At[m][k], acc[ai][bj][m][n], 0, 0, 0); __builtin_amdgcn_s_setprio(0); } while (0)
; #define PG8_WAIT_V(n) asm volatile("s_waitcnt vmcnt(" #n ")" ::: "memory")
; #define PG8_WAIT_L(n) asm volatile("s_waitcnt lgkmcnt(" #n ")" ::: "memory")
; #define PG8_BAR __builtin_amdgcn_s_barrier()
; #define PG8_SCHED __builtin_amdgcn_sched_barrier(0)
; template <class Epi, class Sched, bool ALIGN_EPI = false, bool SP2 = false>
; __device__ __forceinline__ void gemm_phase(PG8_LAS unsigned char* lds, const Gemm g, const Sched& S, const Epi& E) {
;     ...
;             PG8_LDB(B0, 1, 0); PG8_LDB(B1, 1, 1); PG8_SCHED; PG8_LDA(At, 1, 0); PG8_STAGE(PG8_SA(0, 1), a2 + hstep, voffA);
;             PG8_WAIT_V(8); PG8_WAIT_L(0); PG8_BAR; PG8_MMA(0, 0, At, B0); PG8_MMA(0, 1, At, B1); PG8_BAR; PG8_SCHED;
	s_add_i32 s3, 0, 0x18000
	v_add_u32_e32 v159, s3, v131
	s_add_i32 s33, 0, 0x1c000
	ds_read_b128 v[148:151], v159
	ds_read_b128 v[160:163], v159 offset:1024
	ds_read_b128 v[164:167], v159 offset:2048
	ds_read_b128 v[168:171], v159 offset:3072
	v_add_u32_e32 v159, s33, v131
	ds_read_b128 v[172:175], v159
	ds_read_b128 v[176:179], v159 offset:1024
	ds_read_b128 v[182:185], v159 offset:2048
	ds_read_b128 v[186:189], v159 offset:3072
	s_add_u32 s14, s60, 0x40000
	s_addc_u32 s15, s61, 0
	s_mov_b32 m0, s63
	v_lshl_add_u64 v[234:235], s[14:15], 0, v[138:139]
	ds_read_b128 v[190:193], v157 offset:32768
	ds_read_b128 v[194:197], v157 offset:33792
	ds_read_b128 v[198:201], v157 offset:34816
	ds_read_b128 v[208:211], v157 offset:35840
	ds_read_b128 v[212:215], v157 offset:36864
	ds_read_b128 v[216:219], v157 offset:37888
	ds_read_b128 v[220:223], v157 offset:38912
	ds_read_b128 v[224:227], v157 offset:39936
	global_load_lds_dwordx4 v[234:235], off
	v_lshl_add_u64 v[234:235], s[14:15], 0, v[134:135]
	s_mov_b32 m0, s64
	s_nop 0
	global_load_lds_dwordx4 v[234:235], off
	s_waitcnt vmcnt(8)
	s_waitcnt lgkmcnt(0)
	s_barrier
	s_setprio 1
	s_waitcnt lgkmcnt(0)
	v_mfma_f32_16x16x32_bf16 v[124:127], v[148:151], v[190:193], v[124:127]
	v_mfma_f32_16x16x32_bf16 v[108:111], v[148:151], v[198:201], v[108:111]
	v_mfma_f32_16x16x32_bf16 v[120:123], v[164:167], v[190:193], v[120:123]
	v_mfma_f32_16x16x32_bf16 v[104:107], v[164:167], v[198:201], v[104:107]
	v_mfma_f32_16x16x32_bf16 v[92:95], v[148:151], v[212:215], v[92:95]
	v_mfma_f32_16x16x32_bf16 v[76:79], v[148:151], v[220:223], v[76:79]
	v_mfma_f32_16x16x32_bf16 v[88:91], v[164:167], v[212:215], v[88:91]
	v_mfma_f32_16x16x32_bf16 v[72:75], v[164:167], v[220:223], v[72:75]
	v_mfma_f32_16x16x32_bf16 v[124:127], v[160:163], v[194:197], v[124:127]
	v_mfma_f32_16x16x32_bf16 v[108:111], v[160:163], v[208:211], v[108:111]
	v_mfma_f32_16x16x32_bf16 v[120:123], v[168:171], v[194:197], v[120:123]
	v_mfma_f32_16x16x32_bf16 v[104:107], v[168:171], v[208:211], v[104:107]
	v_mfma_f32_16x16x32_bf16 v[92:95], v[160:163], v[216:219], v[92:95]
	v_mfma_f32_16x16x32_bf16 v[76:79], v[160:163], v[224:227], v[76:79]
	v_mfma_f32_16x16x32_bf16 v[88:91], v[168:171], v[216:219], v[88:91]
	v_mfma_f32_16x16x32_bf16 v[72:75], v[168:171], v[224:227], v[72:75]
	s_setprio 0
	s_setprio 1
	v_mfma_f32_16x16x32_bf16 v[116:119], v[172:175], v[190:193], v[116:119]
	v_mfma_f32_16x16x32_bf16 v[100:103], v[172:175], v[198:201], v[100:103]
	v_mfma_f32_16x16x32_bf16 v[112:115], v[182:185], v[190:193], v[112:115]
	v_mfma_f32_16x16x32_bf16 v[96:99], v[182:185], v[198:201], v[96:99]
	v_mfma_f32_16x16x32_bf16 v[84:87], v[172:175], v[212:215], v[84:87]
	v_mfma_f32_16x16x32_bf16 v[68:71], v[172:175], v[220:223], v[68:71]
	v_mfma_f32_16x16x32_bf16 v[80:83], v[182:185], v[212:215], v[80:83]
	v_mfma_f32_16x16x32_bf16 v[64:67], v[182:185], v[220:223], v[64:67]
	v_mfma_f32_16x16x32_bf16 v[116:119], v[176:179], v[194:197], v[116:119]
	v_mfma_f32_16x16x32_bf16 v[100:103], v[176:179], v[208:211], v[100:103]
	v_mfma_f32_16x16x32_bf16 v[112:115], v[186:189], v[194:197], v[112:115]
	v_mfma_f32_16x16x32_bf16 v[96:99], v[186:189], v[208:211], v[96:99]
	v_mfma_f32_16x16x32_bf16 v[84:87], v[176:179], v[216:219], v[84:87]
	v_mfma_f32_16x16x32_bf16 v[68:71], v[176:179], v[224:227], v[68:71]
	v_mfma_f32_16x16x32_bf16 v[80:83], v[186:189], v[216:219], v[80:83]
	v_mfma_f32_16x16x32_bf16 v[64:67], v[186:189], v[224:227], v[64:67]
	s_setprio 0
	s_barrier
; #define PG8_STAGE(bufoff, gbase, voff) do { _Pragma("unroll") for (int _i = 0; _i < 2; ++_i) \
;         __builtin_amdgcn_global_load_lds((const unsigned*)((const char*)(gbase) + (voff)[_i]), (PG8_LAS unsigned*)(lds + (bufoff) + ldsw + _i * 8192), 16, 0, 0); } while (0)
; #define PG8_LDA(dst, b, h) do { _Pragma("unroll") for (int m = 0; m < 4; ++m) _Pragma("unroll") for (int k = 0; k < 2; ++k) dst[m][k] = *(const PG8_LAS bf16x8*)(lds + PG8_SA(b, h) + aoff + m * 2048 + k * 1024); } while (0)
; #define PG8_MMA(ai, bj, At, Bt) do { __builtin_amdgcn_s_setprio(1); _Pragma("unroll") for (int m = 0; m < 4; ++m) _Pragma("unroll") for (int n = 0; n < 2; ++n) _Pragma("unroll") for (int k = 0; k < 2; ++k) \
;         acc[ai][bj][m][n] = __builtin_amdgcn_mfma_f32_16x16x32_bf16(Bt[n][k], At[m][k], acc[ai][bj][m][n], 0, 0, 0); __builtin_amdgcn_s_setprio(0); } while (0)
; #define PG8_WAIT_V(n) asm volatile("s_waitcnt vmcnt(" #n ")" ::: "memory")
; #define PG8_WAIT_L(n) asm volatile("s_waitcnt lgkmcnt(" #n ")" ::: "memory")
; #define PG8_BAR __builtin_amdgcn_s_barrier()
; #define PG8_SCHED __builtin_amdgcn_sched_barrier(0)
; template <class Epi, class Sched, bool ALIGN_EPI = false, bool SP2 = false>
; __device__ __forceinline__ void gemm_phase(PG8_LAS unsigned char* lds, const Gemm g, const Sched& S, const Epi& E) {
;     ...
;             PG8_LDA(At, 1, 1); PG8_STAGE(PG8_SB(1, 0), b3, voffB); PG8_STAGE(PG8_SB(1, 1), b3 + hstep, voffB); PG8_STAGE(PG8_SA(1, 0), a3, voffA);
;             PG8_WAIT_V(8); PG8_WAIT_L(0); PG8_BAR; PG8_MMA(1, 0, At, B0); PG8_MMA(1, 1, At, B1); PG8_BAR; PG8_SCHED;
	s_add_i32 s3, s3, s34
	v_lshl_add_u64 v[202:203], v[202:203], 0, s[38:39]
	s_mov_b32 m0, s3
	ds_read_b128 v[190:193], v157 offset:49152
	ds_read_b128 v[194:197], v157 offset:50176
	ds_read_b128 v[198:201], v157 offset:51200
	ds_read_b128 v[208:211], v157 offset:52224
	ds_read_b128 v[212:215], v157 offset:53248
	ds_read_b128 v[216:219], v157 offset:54272
	ds_read_b128 v[220:223], v157 offset:55296
	ds_read_b128 v[224:227], v157 offset:56320
	global_load_lds_dwordx4 v[202:203], off
	s_add_i32 m0, s3, 0x2000
	s_add_u32 s14, s58, 0x40080
	v_lshl_add_u64 v[202:203], v[228:229], 0, s[38:39]
	s_addc_u32 s15, s59, 0
	s_add_i32 s3, s33, s34
	global_load_lds_dwordx4 v[202:203], off
	v_lshl_add_u64 v[202:203], s[14:15], 0, v[136:137]
	s_mov_b32 m0, s3
	s_nop 0
	global_load_lds_dwordx4 v[202:203], off
	v_lshl_add_u64 v[202:203], s[14:15], 0, v[132:133]
	s_add_i32 m0, s3, 0x2000
	s_nop 0
	global_load_lds_dwordx4 v[202:203], off
	s_waitcnt vmcnt(6)
	s_waitcnt lgkmcnt(0)
	s_barrier
	s_setprio 1
	s_waitcnt lgkmcnt(0)
	v_mfma_f32_16x16x32_bf16 v[60:63], v[148:151], v[190:193], v[60:63]
	v_mfma_f32_16x16x32_bf16 v[44:47], v[148:151], v[198:201], v[44:47]
	v_mfma_f32_16x16x32_bf16 v[56:59], v[164:167], v[190:193], v[56:59]
	v_mfma_f32_16x16x32_bf16 v[40:43], v[164:167], v[198:201], v[40:43]
	v_mfma_f32_16x16x32_bf16 v[28:31], v[148:151], v[212:215], v[28:31]
	v_mfma_f32_16x16x32_bf16 v[12:15], v[148:151], v[220:223], v[12:15]
	v_mfma_f32_16x16x32_bf16 v[24:27], v[164:167], v[212:215], v[24:27]
	v_mfma_f32_16x16x32_bf16 v[8:11], v[164:167], v[220:223], v[8:11]
	v_mfma_f32_16x16x32_bf16 v[60:63], v[160:163], v[194:197], v[60:63]
	v_mfma_f32_16x16x32_bf16 v[44:47], v[160:163], v[208:211], v[44:47]
	v_mfma_f32_16x16x32_bf16 v[56:59], v[168:171], v[194:197], v[56:59]
	v_mfma_f32_16x16x32_bf16 v[40:43], v[168:171], v[208:211], v[40:43]
	v_mfma_f32_16x16x32_bf16 v[28:31], v[160:163], v[216:219], v[28:31]
	v_mfma_f32_16x16x32_bf16 v[12:15], v[160:163], v[224:227], v[12:15]
	v_lshl_add_u64 v[202:203], v[230:231], 0, s[38:39]
	s_mov_b32 m0, s66
	s_nop 0
	global_load_lds_dwordx4 v[202:203], off
	v_mfma_f32_16x16x32_bf16 v[24:27], v[168:171], v[216:219], v[24:27]
	v_mfma_f32_16x16x32_bf16 v[8:11], v[168:171], v[224:227], v[8:11]
	s_setprio 0
	s_setprio 1
	v_mfma_f32_16x16x32_bf16 v[52:55], v[172:175], v[190:193], v[52:55]
	v_mfma_f32_16x16x32_bf16 v[36:39], v[172:175], v[198:201], v[36:39]
	v_mfma_f32_16x16x32_bf16 v[48:51], v[182:185], v[190:193], v[48:51]
	v_mfma_f32_16x16x32_bf16 v[32:35], v[182:185], v[198:201], v[32:35]
	v_mfma_f32_16x16x32_bf16 v[20:23], v[172:175], v[212:215], v[20:23]
	v_mfma_f32_16x16x32_bf16 v[4:7], v[172:175], v[220:223], v[4:7]
	v_mfma_f32_16x16x32_bf16 v[16:19], v[182:185], v[212:215], v[16:19]
	v_mfma_f32_16x16x32_bf16 v[0:3], v[182:185], v[220:223], v[0:3]
	v_mfma_f32_16x16x32_bf16 v[52:55], v[176:179], v[194:197], v[52:55]
	v_mfma_f32_16x16x32_bf16 v[36:39], v[176:179], v[208:211], v[36:39]
	v_mfma_f32_16x16x32_bf16 v[48:51], v[186:189], v[194:197], v[48:51]
	v_mfma_f32_16x16x32_bf16 v[32:35], v[186:189], v[208:211], v[32:35]
	v_mfma_f32_16x16x32_bf16 v[20:23], v[176:179], v[216:219], v[20:23]
	v_mfma_f32_16x16x32_bf16 v[4:7], v[176:179], v[224:227], v[4:7]
	v_lshl_add_u64 v[202:203], v[232:233], 0, s[38:39]
	s_mov_b32 m0, s67
	s_nop 0
	global_load_lds_dwordx4 v[202:203], off
	v_mfma_f32_16x16x32_bf16 v[16:19], v[186:189], v[216:219], v[16:19]
	v_mfma_f32_16x16x32_bf16 v[0:3], v[186:189], v[224:227], v[0:3]
	s_setprio 0
	s_barrier
	s_add_i32 s86, s86, 2
	s_add_u32 s56, s56, 0x100
	s_addc_u32 s57, s57, 0
	s_add_u32 s84, s84, 0x100
	s_addc_u32 s85, s85, 0
	s_cmp_gt_u32 s86, 13
	s_cbranch_scc0 .LBB0_738
	s_and_b64 vcc, exec, s[44:45]
	s_cbranch_vccz .LBB0_741
	s_barrier

; #define PG8_STAGE(bufoff, gbase, voff) do { _Pragma("unroll") for (int _i = 0; _i < 2; ++_i) \
;         __builtin_amdgcn_global_load_lds((const unsigned*)((const char*)(gbase) + (voff)[_i]), (PG8_LAS unsigned*)(lds + (bufoff) + ldsw + _i * 8192), 16, 0, 0); } while (0)
; #define PG8_LDA(dst, b, h) do { _Pragma("unroll") for (int m = 0; m < 4; ++m) _Pragma("unroll") for (int k = 0; k < 2; ++k) dst[m][k] = *(const PG8_LAS bf16x8*)(lds + PG8_SA(b, h) + aoff + m * 2048 + k * 1024); } while (0)
; #define PG8_LDB(dst, b, h) do { _Pragma("unroll") for (int n = 0; n < 2; ++n) _Pragma("unroll") for (int k = 0; k < 2; ++k) dst[n][k] = *(const PG8_LAS bf16x8*)(lds + PG8_SB(b, h) + boff + n * 2048 + k * 1024); } while (0)
; #define PG8_MMA(ai, bj, At, Bt) do { __builtin_amdgcn_s_setprio(1); _Pragma("unroll") for (int m = 0; m < 4; ++m) _Pragma("unroll") for (int n = 0; n < 2; ++n) _Pragma("unroll") for (int k = 0; k < 2; ++k) \
;         acc[ai][bj][m][n] = __builtin_amdgcn_mfma_f32_16x16x32_bf16(Bt[n][k], At[m][k], acc[ai][bj][m][n], 0, 0, 0); __builtin_amdgcn_s_setprio(0); } while (0)
; #define PG8_BAR __builtin_amdgcn_s_barrier()
; template <class Epi, class Sched, bool ALIGN_EPI = false, bool SP2 = false>
; __device__ __forceinline__ void gemm_phase(PG8_LAS unsigned char* lds, const Gemm g, const Sched& S, const Epi& E) {
;     ...
;         const bool has_next = S.next(ui + 1, nxt);
;         const char* nA = has_next ? (const char*)g.A + (size_t)nxt.pm * tstep : cA; const char* nB = has_next ? (const char*)g.Bt + (size_t)nxt.pn * tstep : cB;
;         for (int t = 0; t < nt; t += 2) {
;             const bool last = (t == nt - 2);
;             const char* a1 = cA + (size_t)(t + 1) * kstep;
;             const char* a2 = last ? nA : cA + (size_t)(t + 2) * kstep; const char* b2 = last ? nB : cB + (size_t)(t + 2) * kstep;
;             const char* a3 = a2 + kstep; const char* b3 = b2 + kstep;
;             if (last && has_next) S.a_ready(nxt);
;             if constexpr (SP2) {
;             PG8_LDB(B0, 0, 0); PG8_LDB(B1, 0, 1); PG8_SCHED; PG8_LDA(At, 0, 0); PG8_STAGE(PG8_SA(1, 1), a1 + hstep, voffA);
;             PG8_WAIT_V(8); PG8_WAIT_L(0); PG8_BAR; PG8_MMA(0, 0, At, B0); PG8_MMA(0, 1, At, B1); PG8_BAR; PG8_SCHED;
;             PG8_LDA(At, 0, 1); PG8_STAGE(PG8_SB(0, 0), b2, voffB); PG8_STAGE(PG8_SB(0, 1), b2 + hstep, voffB); PG8_STAGE(PG8_SA(0, 0), a2, voffA);
.LBB0_872:
	s_ashr_i32 s49, s48, 31
	s_lshl_b64 s[50:51], s[48:49], 18
	s_add_u32 s50, s92, s50
	s_addc_u32 s51, s93, s51
	s_and_b64 s[52:53], s[10:11], exec
	s_cselect_b32 s49, s51, s59
	s_cselect_b32 s55, s50, s58
	s_ashr_i32 s45, s44, 31
	s_lshl_b64 s[52:53], s[44:45], 18
	s_add_u32 s52, s76, s52
	s_addc_u32 s53, s77, s53
	s_and_b64 s[62:63], s[10:11], exec
	s_cselect_b32 s45, s53, s61
	s_cselect_b32 s84, s52, s60
	s_add_u32 s58, s58, 0x20080
	s_addc_u32 s59, s59, 0
	s_add_u32 s85, s60, 0x100
	s_addc_u32 s86, s61, 0
	s_mov_b32 s87, -2
	s_waitcnt lgkmcnt(0)
	ds_read_b128 v[144:147], v151
	ds_read_b128 v[156:159], v151 offset:1024
	ds_read_b128 v[160:163], v151 offset:2048
	ds_read_b128 v[164:167], v151 offset:3072
	ds_read_b128 v[168:171], v152
	ds_read_b128 v[172:175], v152 offset:1024
	ds_read_b128 v[176:179], v152 offset:2048
	ds_read_b128 v[182:185], v152 offset:3072
	s_add_u32 s3, s58, 0xfffe0080
	s_addc_u32 s33, s59, -1
	s_cmp_eq_u32 s87, 4
	s_cselect_b32 s63, s49, s33
	s_cselect_b32 s62, s55, s3
	s_cselect_b32 s61, s45, s86
	s_cselect_b32 s60, s84, s85
	v_lshl_add_u64 v[202:203], s[58:59], 0, v[136:137]
	s_add_i32 m0, s15, 0xc000
	ds_read_b128 v[186:189], v153
	ds_read_b128 v[190:193], v153 offset:1024
	ds_read_b128 v[194:197], v153 offset:2048
	ds_read_b128 v[198:201], v153 offset:3072
	ds_read_b128 v[208:211], v153 offset:4096
	ds_read_b128 v[212:215], v153 offset:5120
	ds_read_b128 v[216:219], v153 offset:6144
	ds_read_b128 v[220:223], v153 offset:7168
	global_load_lds_dwordx4 v[202:203], off
	v_lshl_add_u64 v[202:203], s[58:59], 0, v[138:139]
	s_add_i32 m0, s15, 0xe000
	s_nop 0
	global_load_lds_dwordx4 v[202:203], off
	s_waitcnt vmcnt(8)
	s_waitcnt lgkmcnt(0)
	s_barrier
	s_setprio 1
	s_waitcnt lgkmcnt(0)
	v_mfma_f32_16x16x32_bf16 v[124:127], v[144:147], v[186:189], 0
	v_mfma_f32_16x16x32_bf16 v[108:111], v[144:147], v[194:197], 0
	v_mfma_f32_16x16x32_bf16 v[120:123], v[160:163], v[186:189], 0
	v_mfma_f32_16x16x32_bf16 v[104:107], v[160:163], v[194:197], 0
	v_mfma_f32_16x16x32_bf16 v[92:95], v[144:147], v[208:211], 0
	v_mfma_f32_16x16x32_bf16 v[76:79], v[144:147], v[216:219], 0
	v_mfma_f32_16x16x32_bf16 v[88:91], v[160:163], v[208:211], 0
	v_mfma_f32_16x16x32_bf16 v[72:75], v[160:163], v[216:219], 0
	v_mfma_f32_16x16x32_bf16 v[124:127], v[156:159], v[190:193], v[124:127]
	v_mfma_f32_16x16x32_bf16 v[108:111], v[156:159], v[198:201], v[108:111]
	v_mfma_f32_16x16x32_bf16 v[120:123], v[164:167], v[190:193], v[120:123]
	v_mfma_f32_16x16x32_bf16 v[104:107], v[164:167], v[198:201], v[104:107]
	v_mfma_f32_16x16x32_bf16 v[92:95], v[156:159], v[212:215], v[92:95]
	v_mfma_f32_16x16x32_bf16 v[76:79], v[156:159], v[220:223], v[76:79]
	v_mfma_f32_16x16x32_bf16 v[88:91], v[164:167], v[212:215], v[88:91]
	v_mfma_f32_16x16x32_bf16 v[72:75], v[164:167], v[220:223], v[72:75]
	s_setprio 0
	s_setprio 1
	v_mfma_f32_16x16x32_bf16 v[116:119], v[168:171], v[186:189], 0
	v_mfma_f32_16x16x32_bf16 v[100:103], v[168:171], v[194:197], 0
	v_mfma_f32_16x16x32_bf16 v[112:115], v[176:179], v[186:189], 0
	v_mfma_f32_16x16x32_bf16 v[96:99], v[176:179], v[194:197], 0
	v_mfma_f32_16x16x32_bf16 v[84:87], v[168:171], v[208:211], 0
	v_mfma_f32_16x16x32_bf16 v[68:71], v[168:171], v[216:219], 0
	v_mfma_f32_16x16x32_bf16 v[80:83], v[176:179], v[208:211], 0
	v_mfma_f32_16x16x32_bf16 v[64:67], v[176:179], v[216:219], 0
	v_mfma_f32_16x16x32_bf16 v[116:119], v[172:175], v[190:193], v[116:119]
	v_mfma_f32_16x16x32_bf16 v[100:103], v[172:175], v[198:201], v[100:103]
	v_mfma_f32_16x16x32_bf16 v[112:115], v[182:185], v[190:193], v[112:115]
	v_mfma_f32_16x16x32_bf16 v[96:99], v[182:185], v[198:201], v[96:99]
	v_mfma_f32_16x16x32_bf16 v[84:87], v[172:175], v[212:215], v[84:87]
	v_mfma_f32_16x16x32_bf16 v[68:71], v[172:175], v[220:223], v[68:71]
	v_mfma_f32_16x16x32_bf16 v[80:83], v[182:185], v[212:215], v[80:83]
	v_mfma_f32_16x16x32_bf16 v[64:67], v[182:185], v[220:223], v[64:67]
	s_setprio 0
	s_barrier
	s_add_i32 s3, s74, s14
	v_lshl_add_u64 v[202:203], s[60:61], 0, v[130:131]
	s_mov_b32 m0, s3
	ds_read_b128 v[186:189], v153 offset:16384
	ds_read_b128 v[190:193], v153 offset:17408
	ds_read_b128 v[194:197], v153 offset:18432
	ds_read_b128 v[198:201], v153 offset:19456
	ds_read_b128 v[208:211], v153 offset:20480
	ds_read_b128 v[212:215], v153 offset:21504
	ds_read_b128 v[216:219], v153 offset:22528
	ds_read_b128 v[220:223], v153 offset:23552
	global_load_lds_dwordx4 v[202:203], off
	s_add_i32 m0, s3, 0x2000
	s_add_u32 s78, s60, 0x20000
	v_lshl_add_u64 v[224:225], s[60:61], 0, v[134:135]
	s_addc_u32 s79, s61, 0
	s_add_i32 s3, s75, s14
	global_load_lds_dwordx4 v[224:225], off
	v_lshl_add_u64 v[226:227], s[78:79], 0, v[130:131]
	s_mov_b32 m0, s3
	global_load_lds_dwordx4 v[226:227], off
	v_lshl_add_u64 v[226:227], s[78:79], 0, v[134:135]
	s_add_i32 m0, s3, 0x2000
	s_nop 0
	global_load_lds_dwordx4 v[226:227], off
	s_waitcnt vmcnt(6)
	s_waitcnt lgkmcnt(0)
	s_barrier
; #define PG8_STAGE(bufoff, gbase, voff) do { _Pragma("unroll") for (int _i = 0; _i < 2; ++_i) \
;         __builtin_amdgcn_global_load_lds((const unsigned*)((const char*)(gbase) + (voff)[_i]), (PG8_LAS unsigned*)(lds + (bufoff) + ldsw + _i * 8192), 16, 0, 0); } while (0)
; #define PG8_LDA(dst, b, h) do { _Pragma("unroll") for (int m = 0; m < 4; ++m) _Pragma("unroll") for (int k = 0; k < 2; ++k) dst[m][k] = *(const PG8_LAS bf16x8*)(lds + PG8_SA(b, h) + aoff + m * 2048 + k * 1024); } while (0)
; #define PG8_LDB(dst, b, h) do { _Pragma("unroll") for (int n = 0; n < 2; ++n) _Pragma("unroll") for (int k = 0; k < 2; ++k) dst[n][k] = *(const PG8_LAS bf16x8*)(lds + PG8_SB(b, h) + boff + n * 2048 + k * 1024); } while (0)
; #define PG8_MMA(ai, bj, At, Bt) do { __builtin_amdgcn_s_setprio(1); _Pragma("unroll") for (int m = 0; m < 4; ++m) _Pragma("unroll") for (int n = 0; n < 2; ++n) _Pragma("unroll") for (int k = 0; k < 2; ++k) \
;         acc[ai][bj][m][n] = __builtin_amdgcn_mfma_f32_16x16x32_bf16(Bt[n][k], At[m][k], acc[ai][bj][m][n], 0, 0, 0); __builtin_amdgcn_s_setprio(0); } while (0)
; #define PG8_WAIT_V(n) asm volatile("s_waitcnt vmcnt(" #n ")" ::: "memory")
; #define PG8_WAIT_L(n) asm volatile("s_waitcnt lgkmcnt(" #n ")" ::: "memory")
; #define PG8_BAR __builtin_amdgcn_s_barrier()
; #define PG8_SCHED __builtin_amdgcn_sched_barrier(0)
; template <class Epi, class Sched, bool ALIGN_EPI = false, bool SP2 = false>
; __device__ __forceinline__ void gemm_phase(PG8_LAS unsigned char* lds, const Gemm g, const Sched& S, const Epi& E) {
;     ...
;             PG8_WAIT_V(8); PG8_WAIT_L(0); PG8_BAR; PG8_MMA(1, 0, At, B0); PG8_MMA(1, 1, At, B1); PG8_BAR; PG8_SCHED;
;             PG8_LDB(B0, 1, 0); PG8_LDB(B1, 1, 1); PG8_SCHED; PG8_LDA(At, 1, 0); PG8_STAGE(PG8_SA(0, 1), a2 + hstep, voffA);
;             PG8_WAIT_V(8); PG8_WAIT_L(0); PG8_BAR; PG8_MMA(0, 0, At, B0); PG8_MMA(0, 1, At, B1); PG8_BAR; PG8_SCHED;
	s_setprio 1
	s_waitcnt lgkmcnt(0)
	v_mfma_f32_16x16x32_bf16 v[60:63], v[144:147], v[186:189], 0
	v_mfma_f32_16x16x32_bf16 v[44:47], v[144:147], v[194:197], 0
	v_mfma_f32_16x16x32_bf16 v[56:59], v[160:163], v[186:189], 0
	v_mfma_f32_16x16x32_bf16 v[40:43], v[160:163], v[194:197], 0
	v_mfma_f32_16x16x32_bf16 v[28:31], v[144:147], v[208:211], 0
	v_mfma_f32_16x16x32_bf16 v[12:15], v[144:147], v[216:219], 0
	v_mfma_f32_16x16x32_bf16 v[24:27], v[160:163], v[208:211], 0
	v_mfma_f32_16x16x32_bf16 v[8:11], v[160:163], v[216:219], 0
	v_mfma_f32_16x16x32_bf16 v[60:63], v[156:159], v[190:193], v[60:63]
	v_mfma_f32_16x16x32_bf16 v[44:47], v[156:159], v[198:201], v[44:47]
	v_mfma_f32_16x16x32_bf16 v[56:59], v[164:167], v[190:193], v[56:59]
	v_mfma_f32_16x16x32_bf16 v[40:43], v[164:167], v[198:201], v[40:43]
	v_mfma_f32_16x16x32_bf16 v[28:31], v[156:159], v[212:215], v[28:31]
	v_mfma_f32_16x16x32_bf16 v[12:15], v[156:159], v[220:223], v[12:15]
	v_lshl_add_u64 v[226:227], s[62:63], 0, v[128:129]
	s_mov_b32 m0, s15
	s_nop 0
	global_load_lds_dwordx4 v[226:227], off
	v_mfma_f32_16x16x32_bf16 v[24:27], v[164:167], v[212:215], v[24:27]
	v_mfma_f32_16x16x32_bf16 v[8:11], v[164:167], v[220:223], v[8:11]
	s_setprio 0
	s_setprio 1
	v_mfma_f32_16x16x32_bf16 v[52:55], v[168:171], v[186:189], 0
	v_mfma_f32_16x16x32_bf16 v[36:39], v[168:171], v[194:197], 0
	v_mfma_f32_16x16x32_bf16 v[48:51], v[176:179], v[186:189], 0
	v_mfma_f32_16x16x32_bf16 v[32:35], v[176:179], v[194:197], 0
	v_mfma_f32_16x16x32_bf16 v[20:23], v[168:171], v[208:211], 0
	v_mfma_f32_16x16x32_bf16 v[4:7], v[168:171], v[216:219], 0
	v_mfma_f32_16x16x32_bf16 v[16:19], v[176:179], v[208:211], 0
	v_mfma_f32_16x16x32_bf16 v[0:3], v[176:179], v[216:219], 0
	v_mfma_f32_16x16x32_bf16 v[52:55], v[172:175], v[190:193], v[52:55]
	v_mfma_f32_16x16x32_bf16 v[36:39], v[172:175], v[198:201], v[36:39]
	v_mfma_f32_16x16x32_bf16 v[48:51], v[182:185], v[190:193], v[48:51]
	v_mfma_f32_16x16x32_bf16 v[32:35], v[182:185], v[198:201], v[32:35]
	v_mfma_f32_16x16x32_bf16 v[20:23], v[172:175], v[212:215], v[20:23]
	v_mfma_f32_16x16x32_bf16 v[4:7], v[172:175], v[220:223], v[4:7]
	v_lshl_add_u64 v[228:229], s[62:63], 0, v[132:133]
	s_mov_b32 m0, s34
	s_nop 0
	global_load_lds_dwordx4 v[228:229], off
	v_mfma_f32_16x16x32_bf16 v[16:19], v[182:185], v[212:215], v[16:19]
	v_mfma_f32_16x16x32_bf16 v[0:3], v[182:185], v[220:223], v[0:3]
	s_setprio 0
	s_barrier
	s_add_i32 s3, 0, 0x18000
	v_add_u32_e32 v155, s3, v149
	s_add_i32 s33, 0, 0x1c000
	ds_read_b128 v[144:147], v155
	ds_read_b128 v[156:159], v155 offset:1024
	ds_read_b128 v[160:163], v155 offset:2048
	ds_read_b128 v[164:167], v155 offset:3072
	v_add_u32_e32 v155, s33, v149
	ds_read_b128 v[168:171], v155
	ds_read_b128 v[172:175], v155 offset:1024
	ds_read_b128 v[176:179], v155 offset:2048
	ds_read_b128 v[182:185], v155 offset:3072
	s_add_u32 s62, s62, 0x20000
	s_addc_u32 s63, s63, 0
	s_mov_b32 m0, s57
	v_lshl_add_u64 v[230:231], s[62:63], 0, v[128:129]
	ds_read_b128 v[186:189], v153 offset:32768
	ds_read_b128 v[190:193], v153 offset:33792
	ds_read_b128 v[194:197], v153 offset:34816
	ds_read_b128 v[198:201], v153 offset:35840
	ds_read_b128 v[208:211], v153 offset:36864
	ds_read_b128 v[212:215], v153 offset:37888
	ds_read_b128 v[216:219], v153 offset:38912
	ds_read_b128 v[220:223], v153 offset:39936
	global_load_lds_dwordx4 v[230:231], off
	v_lshl_add_u64 v[230:231], s[62:63], 0, v[132:133]
	s_mov_b32 m0, s64
	s_nop 0
	global_load_lds_dwordx4 v[230:231], off
	s_waitcnt vmcnt(8)
	s_waitcnt lgkmcnt(0)
	s_barrier
	s_setprio 1
	s_waitcnt lgkmcnt(0)
	v_mfma_f32_16x16x32_bf16 v[124:127], v[144:147], v[186:189], v[124:127]
	v_mfma_f32_16x16x32_bf16 v[108:111], v[144:147], v[194:197], v[108:111]
	v_mfma_f32_16x16x32_bf16 v[120:123], v[160:163], v[186:189], v[120:123]
	v_mfma_f32_16x16x32_bf16 v[104:107], v[160:163], v[194:197], v[104:107]
	v_mfma_f32_16x16x32_bf16 v[92:95], v[144:147], v[208:211], v[92:95]
	v_mfma_f32_16x16x32_bf16 v[76:79], v[144:147], v[216:219], v[76:79]
	v_mfma_f32_16x16x32_bf16 v[88:91], v[160:163], v[208:211], v[88:91]
	v_mfma_f32_16x16x32_bf16 v[72:75], v[160:163], v[216:219], v[72:75]
	v_mfma_f32_16x16x32_bf16 v[124:127], v[156:159], v[190:193], v[124:127]
	v_mfma_f32_16x16x32_bf16 v[108:111], v[156:159], v[198:201], v[108:111]
	v_mfma_f32_16x16x32_bf16 v[120:123], v[164:167], v[190:193], v[120:123]
	v_mfma_f32_16x16x32_bf16 v[104:107], v[164:167], v[198:201], v[104:107]
	v_mfma_f32_16x16x32_bf16 v[92:95], v[156:159], v[212:215], v[92:95]
	v_mfma_f32_16x16x32_bf16 v[76:79], v[156:159], v[220:223], v[76:79]
	v_mfma_f32_16x16x32_bf16 v[88:91], v[164:167], v[212:215], v[88:91]
	v_mfma_f32_16x16x32_bf16 v[72:75], v[164:167], v[220:223], v[72:75]
	s_setprio 0
	s_setprio 1
	v_mfma_f32_16x16x32_bf16 v[116:119], v[168:171], v[186:189], v[116:119]
	v_mfma_f32_16x16x32_bf16 v[100:103], v[168:171], v[194:197], v[100:103]
	v_mfma_f32_16x16x32_bf16 v[112:115], v[176:179], v[186:189], v[112:115]
	v_mfma_f32_16x16x32_bf16 v[96:99], v[176:179], v[194:197], v[96:99]
	v_mfma_f32_16x16x32_bf16 v[84:87], v[168:171], v[208:211], v[84:87]
	v_mfma_f32_16x16x32_bf16 v[68:71], v[168:171], v[216:219], v[68:71]
	v_mfma_f32_16x16x32_bf16 v[80:83], v[176:179], v[208:211], v[80:83]
	v_mfma_f32_16x16x32_bf16 v[64:67], v[176:179], v[216:219], v[64:67]
	v_mfma_f32_16x16x32_bf16 v[116:119], v[172:175], v[190:193], v[116:119]
	v_mfma_f32_16x16x32_bf16 v[100:103], v[172:175], v[198:201], v[100:103]
	v_mfma_f32_16x16x32_bf16 v[112:115], v[182:185], v[190:193], v[112:115]
	v_mfma_f32_16x16x32_bf16 v[96:99], v[182:185], v[198:201], v[96:99]
	v_mfma_f32_16x16x32_bf16 v[84:87], v[172:175], v[212:215], v[84:87]
	v_mfma_f32_16x16x32_bf16 v[68:71], v[172:175], v[220:223], v[68:71]
	v_mfma_f32_16x16x32_bf16 v[80:83], v[182:185], v[212:215], v[80:83]
	v_mfma_f32_16x16x32_bf16 v[64:67], v[182:185], v[220:223], v[64:67]
	s_setprio 0
	s_barrier
; #define PG8_STAGE(bufoff, gbase, voff) do { _Pragma("unroll") for (int _i = 0; _i < 2; ++_i) \
;         __builtin_amdgcn_global_load_lds((const unsigned*)((const char*)(gbase) + (voff)[_i]), (PG8_LAS unsigned*)(lds + (bufoff) + ldsw + _i * 8192), 16, 0, 0); } while (0)
; #define PG8_LDA(dst, b, h) do { _Pragma("unroll") for (int m = 0; m < 4; ++m) _Pragma("unroll") for (int k = 0; k < 2; ++k) dst[m][k] = *(const PG8_LAS bf16x8*)(lds + PG8_SA(b, h) + aoff + m * 2048 + k * 1024); } while (0)
; #define PG8_LDB(dst, b, h) do { _Pragma("unroll") for (int n = 0; n < 2; ++n) _Pragma("unroll") for (int k = 0; k < 2; ++k) dst[n][k] = *(const PG8_LAS bf16x8*)(lds + PG8_SB(b, h) + boff + n * 2048 + k * 1024); } while (0)
; #define PG8_MMA(ai, bj, At, Bt) do { __builtin_amdgcn_s_setprio(1); _Pragma("unroll") for (int m = 0; m < 4; ++m) _Pragma("unroll") for (int n = 0; n < 2; ++n) _Pragma("unroll") for (int k = 0; k < 2; ++k) \
;         acc[ai][bj][m][n] = __builtin_amdgcn_mfma_f32_16x16x32_bf16(Bt[n][k], At[m][k], acc[ai][bj][m][n], 0, 0, 0); __builtin_amdgcn_s_setprio(0); } while (0)
; #define PG8_WAIT_V(n) asm volatile("s_waitcnt vmcnt(" #n ")" ::: "memory")
; template <class Epi, class Sched, bool ALIGN_EPI = false, bool SP2 = false>
; __device__ __forceinline__ void gemm_phase(PG8_LAS unsigned char* lds, const Gemm g, const Sched& S, const Epi& E) {
;     ...
;             PG8_LDB(B0, 0, 0); PG8_LDB(B1, 0, 1); PG8_SCHED; PG8_LDA(At, 0, 0); PG8_STAGE(PG8_SA(1, 1), a1 + hstep, voffA);
;             PG8_WAIT_V(8); PG8_WAIT_L(0); PG8_BAR; PG8_MMA(0, 0, At, B0); PG8_MMA(0, 1, At, B1); PG8_BAR; PG8_SCHED;
;             PG8_LDA(At, 0, 1); PG8_STAGE(PG8_SB(0, 0), b2, voffB); PG8_STAGE(PG8_SB(0, 1), b2 + hstep, voffB); PG8_STAGE(PG8_SA(0, 0), a2, voffA);
;             PG8_WAIT_V(8); PG8_WAIT_L(0); PG8_BAR; PG8_MMA(1, 0, At, B0); PG8_MMA(1, 1, At, B1); PG8_BAR; PG8_SCHED;
;             PG8_LDB(B0, 1, 0); PG8_LDB(B1, 1, 1); PG8_SCHED; PG8_LDA(At, 1, 0); PG8_STAGE(PG8_SA(0, 1), a2 + hstep, voffA);
;             PG8_WAIT_V(8); PG8_WAIT_L(0); PG8_BAR; PG8_MMA(0, 0, At, B0); PG8_MMA(0, 1, At, B1); PG8_BAR; PG8_SCHED;
;             PG8_LDA(At, 1, 1); PG8_STAGE(PG8_SB(1, 0), b3, voffB); PG8_STAGE(PG8_SB(1, 1), b3 + hstep, voffB); PG8_STAGE(PG8_SA(1, 0), a3, voffA);
;             PG8_WAIT_V(8); PG8_WAIT_L(0); PG8_BAR; PG8_MMA(1, 0, At, B0); PG8_MMA(1, 1, At, B1); PG8_BAR; PG8_SCHED;
	s_add_i32 s3, s3, s14
	v_lshl_add_u64 v[202:203], v[202:203], 0, s[38:39]
	s_mov_b32 m0, s3
	ds_read_b128 v[186:189], v153 offset:49152
	ds_read_b128 v[190:193], v153 offset:50176
	ds_read_b128 v[194:197], v153 offset:51200
	ds_read_b128 v[198:201], v153 offset:52224
	ds_read_b128 v[208:211], v153 offset:53248
	ds_read_b128 v[212:215], v153 offset:54272
	ds_read_b128 v[216:219], v153 offset:55296
	ds_read_b128 v[220:223], v153 offset:56320
	global_load_lds_dwordx4 v[202:203], off
	s_add_i32 m0, s3, 0x2000
	s_add_u32 s60, s60, 0x20080
	v_lshl_add_u64 v[202:203], v[224:225], 0, s[38:39]
	s_addc_u32 s61, s61, 0
	s_add_i32 s3, s33, s14
	global_load_lds_dwordx4 v[202:203], off
	v_lshl_add_u64 v[202:203], s[60:61], 0, v[130:131]
	s_mov_b32 m0, s3
	s_nop 0
	global_load_lds_dwordx4 v[202:203], off
	v_lshl_add_u64 v[202:203], s[60:61], 0, v[134:135]
	s_add_i32 m0, s3, 0x2000
	s_nop 0
	global_load_lds_dwordx4 v[202:203], off
	s_waitcnt vmcnt(6)
	s_waitcnt lgkmcnt(0)
	s_barrier
	s_setprio 1
	s_waitcnt lgkmcnt(0)
	v_mfma_f32_16x16x32_bf16 v[60:63], v[144:147], v[186:189], v[60:63]
	v_mfma_f32_16x16x32_bf16 v[44:47], v[144:147], v[194:197], v[44:47]
	v_mfma_f32_16x16x32_bf16 v[56:59], v[160:163], v[186:189], v[56:59]
	v_mfma_f32_16x16x32_bf16 v[40:43], v[160:163], v[194:197], v[40:43]
	v_mfma_f32_16x16x32_bf16 v[28:31], v[144:147], v[208:211], v[28:31]
	v_mfma_f32_16x16x32_bf16 v[12:15], v[144:147], v[216:219], v[12:15]
	v_mfma_f32_16x16x32_bf16 v[24:27], v[160:163], v[208:211], v[24:27]
	v_mfma_f32_16x16x32_bf16 v[8:11], v[160:163], v[216:219], v[8:11]
	v_mfma_f32_16x16x32_bf16 v[60:63], v[156:159], v[190:193], v[60:63]
	v_mfma_f32_16x16x32_bf16 v[44:47], v[156:159], v[198:201], v[44:47]
	v_mfma_f32_16x16x32_bf16 v[56:59], v[164:167], v[190:193], v[56:59]
	v_mfma_f32_16x16x32_bf16 v[40:43], v[164:167], v[198:201], v[40:43]
	v_mfma_f32_16x16x32_bf16 v[28:31], v[156:159], v[212:215], v[28:31]
	v_mfma_f32_16x16x32_bf16 v[12:15], v[156:159], v[220:223], v[12:15]
	v_lshl_add_u64 v[202:203], v[226:227], 0, s[38:39]
	s_mov_b32 m0, s66
	s_nop 0
	global_load_lds_dwordx4 v[202:203], off
	v_mfma_f32_16x16x32_bf16 v[24:27], v[164:167], v[212:215], v[24:27]
	v_mfma_f32_16x16x32_bf16 v[8:11], v[164:167], v[220:223], v[8:11]
	s_setprio 0
	s_setprio 1
	v_mfma_f32_16x16x32_bf16 v[52:55], v[168:171], v[186:189], v[52:55]
	v_mfma_f32_16x16x32_bf16 v[36:39], v[168:171], v[194:197], v[36:39]
	v_mfma_f32_16x16x32_bf16 v[48:51], v[176:179], v[186:189], v[48:51]
	v_mfma_f32_16x16x32_bf16 v[32:35], v[176:179], v[194:197], v[32:35]
	v_mfma_f32_16x16x32_bf16 v[20:23], v[168:171], v[208:211], v[20:23]
	v_mfma_f32_16x16x32_bf16 v[4:7], v[168:171], v[216:219], v[4:7]
	v_mfma_f32_16x16x32_bf16 v[16:19], v[176:179], v[208:211], v[16:19]
	v_mfma_f32_16x16x32_bf16 v[0:3], v[176:179], v[216:219], v[0:3]
	v_mfma_f32_16x16x32_bf16 v[52:55], v[172:175], v[190:193], v[52:55]
	v_mfma_f32_16x16x32_bf16 v[36:39], v[172:175], v[198:201], v[36:39]
	v_mfma_f32_16x16x32_bf16 v[48:51], v[182:185], v[190:193], v[48:51]
	v_mfma_f32_16x16x32_bf16 v[32:35], v[182:185], v[198:201], v[32:35]
	v_mfma_f32_16x16x32_bf16 v[20:23], v[172:175], v[212:215], v[20:23]
	v_mfma_f32_16x16x32_bf16 v[4:7], v[172:175], v[220:223], v[4:7]
	v_lshl_add_u64 v[202:203], v[228:229], 0, s[38:39]
	s_mov_b32 m0, s67
	s_nop 0
	global_load_lds_dwordx4 v[202:203], off
	v_mfma_f32_16x16x32_bf16 v[16:19], v[182:185], v[212:215], v[16:19]
	v_mfma_f32_16x16x32_bf16 v[0:3], v[182:185], v[220:223], v[0:3]
	s_setprio 0
	s_barrier
	s_add_i32 s87, s87, 2
	s_add_u32 s58, s58, 0x100
	s_addc_u32 s59, s59, 0
	s_add_u32 s85, s85, 0x100
	s_addc_u32 s86, s86, 0
.LBB0_873:
	ds_read_b128 v[144:147], v151
	ds_read_b128 v[156:159], v151 offset:1024
	ds_read_b128 v[160:163], v151 offset:2048
	ds_read_b128 v[164:167], v151 offset:3072
	ds_read_b128 v[168:171], v152
	ds_read_b128 v[172:175], v152 offset:1024
	ds_read_b128 v[176:179], v152 offset:2048
	ds_read_b128 v[182:185], v152 offset:3072
	s_add_u32 s3, s58, 0xfffe0080
	s_addc_u32 s33, s59, -1
	s_cmp_eq_u32 s87, 4
	s_cselect_b32 s63, s49, s33
	s_cselect_b32 s62, s55, s3
	s_cselect_b32 s61, s45, s86
	s_cselect_b32 s60, s84, s85
	v_lshl_add_u64 v[202:203], s[58:59], 0, v[136:137]
	s_add_i32 m0, s15, 0xc000
	ds_read_b128 v[186:189], v153
	ds_read_b128 v[190:193], v153 offset:1024
	ds_read_b128 v[194:197], v153 offset:2048
	ds_read_b128 v[198:201], v153 offset:3072
	ds_read_b128 v[208:211], v153 offset:4096
	ds_read_b128 v[212:215], v153 offset:5120
	ds_read_b128 v[216:219], v153 offset:6144
	ds_read_b128 v[220:223], v153 offset:7168
	global_load_lds_dwordx4 v[202:203], off
	v_lshl_add_u64 v[202:203], s[58:59], 0, v[138:139]
	s_add_i32 m0, s15, 0xe000
	s_nop 0
	global_load_lds_dwordx4 v[202:203], off
	s_waitcnt vmcnt(8)
	s_waitcnt lgkmcnt(0)
	s_barrier
; #define PG8_STAGE(bufoff, gbase, voff) do { _Pragma("unroll") for (int _i = 0; _i < 2; ++_i) \
;         __builtin_amdgcn_global_load_lds((const unsigned*)((const char*)(gbase) + (voff)[_i]), (PG8_LAS unsigned*)(lds + (bufoff) + ldsw + _i * 8192), 16, 0, 0); } while (0)
; #define PG8_LDA(dst, b, h) do { _Pragma("unroll") for (int m = 0; m < 4; ++m) _Pragma("unroll") for (int k = 0; k < 2; ++k) dst[m][k] = *(const PG8_LAS bf16x8*)(lds + PG8_SA(b, h) + aoff + m * 2048 + k * 1024); } while (0)
; #define PG8_MMA(ai, bj, At, Bt) do { __builtin_amdgcn_s_setprio(1); _Pragma("unroll") for (int m = 0; m < 4; ++m) _Pragma("unroll") for (int n = 0; n < 2; ++n) _Pragma("unroll") for (int k = 0; k < 2; ++k) \
;         acc[ai][bj][m][n] = __builtin_amdgcn_mfma_f32_16x16x32_bf16(Bt[n][k], At[m][k], acc[ai][bj][m][n], 0, 0, 0); __builtin_amdgcn_s_setprio(0); } while (0)
; #define PG8_WAIT_V(n) asm volatile("s_waitcnt vmcnt(" #n ")" ::: "memory")
; #define PG8_WAIT_L(n) asm volatile("s_waitcnt lgkmcnt(" #n ")" ::: "memory")
; #define PG8_BAR __builtin_amdgcn_s_barrier()
; #define PG8_SCHED __builtin_amdgcn_sched_barrier(0)
; template <class Epi, class Sched, bool ALIGN_EPI = false, bool SP2 = false>
; __device__ __forceinline__ void gemm_phase(PG8_LAS unsigned char* lds, const Gemm g, const Sched& S, const Epi& E) {
;     ...
;             PG8_WAIT_V(8); PG8_WAIT_L(0); PG8_BAR; PG8_MMA(0, 0, At, B0); PG8_MMA(0, 1, At, B1); PG8_BAR; PG8_SCHED;
;             PG8_LDA(At, 0, 1); PG8_STAGE(PG8_SB(0, 0), b2, voffB); PG8_STAGE(PG8_SB(0, 1), b2 + hstep, voffB); PG8_STAGE(PG8_SA(0, 0), a2, voffA);
;             PG8_WAIT_V(8); PG8_WAIT_L(0); PG8_BAR; PG8_MMA(1, 0, At, B0); PG8_MMA(1, 1, At, B1); PG8_BAR; PG8_SCHED;
	s_setprio 1
	s_waitcnt lgkmcnt(0)
	v_mfma_f32_16x16x32_bf16 v[124:127], v[144:147], v[186:189], v[124:127]
	v_mfma_f32_16x16x32_bf16 v[108:111], v[144:147], v[194:197], v[108:111]
	v_mfma_f32_16x16x32_bf16 v[120:123], v[160:163], v[186:189], v[120:123]
	v_mfma_f32_16x16x32_bf16 v[104:107], v[160:163], v[194:197], v[104:107]
	v_mfma_f32_16x16x32_bf16 v[92:95], v[144:147], v[208:211], v[92:95]
	v_mfma_f32_16x16x32_bf16 v[76:79], v[144:147], v[216:219], v[76:79]
	v_mfma_f32_16x16x32_bf16 v[88:91], v[160:163], v[208:211], v[88:91]
	v_mfma_f32_16x16x32_bf16 v[72:75], v[160:163], v[216:219], v[72:75]
	v_mfma_f32_16x16x32_bf16 v[124:127], v[156:159], v[190:193], v[124:127]
	v_mfma_f32_16x16x32_bf16 v[108:111], v[156:159], v[198:201], v[108:111]
	v_mfma_f32_16x16x32_bf16 v[120:123], v[164:167], v[190:193], v[120:123]
	v_mfma_f32_16x16x32_bf16 v[104:107], v[164:167], v[198:201], v[104:107]
	v_mfma_f32_16x16x32_bf16 v[92:95], v[156:159], v[212:215], v[92:95]
	v_mfma_f32_16x16x32_bf16 v[76:79], v[156:159], v[220:223], v[76:79]
	v_mfma_f32_16x16x32_bf16 v[88:91], v[164:167], v[212:215], v[88:91]
	v_mfma_f32_16x16x32_bf16 v[72:75], v[164:167], v[220:223], v[72:75]
	s_setprio 0
	s_setprio 1
	v_mfma_f32_16x16x32_bf16 v[116:119], v[168:171], v[186:189], v[116:119]
	v_mfma_f32_16x16x32_bf16 v[100:103], v[168:171], v[194:197], v[100:103]
	v_mfma_f32_16x16x32_bf16 v[112:115], v[176:179], v[186:189], v[112:115]
	v_mfma_f32_16x16x32_bf16 v[96:99], v[176:179], v[194:197], v[96:99]
	v_mfma_f32_16x16x32_bf16 v[84:87], v[168:171], v[208:211], v[84:87]
	v_mfma_f32_16x16x32_bf16 v[68:71], v[168:171], v[216:219], v[68:71]
	v_mfma_f32_16x16x32_bf16 v[80:83], v[176:179], v[208:211], v[80:83]
	v_mfma_f32_16x16x32_bf16 v[64:67], v[176:179], v[216:219], v[64:67]
	v_mfma_f32_16x16x32_bf16 v[116:119], v[172:175], v[190:193], v[116:119]
	v_mfma_f32_16x16x32_bf16 v[100:103], v[172:175], v[198:201], v[100:103]
	v_mfma_f32_16x16x32_bf16 v[112:115], v[182:185], v[190:193], v[112:115]
	v_mfma_f32_16x16x32_bf16 v[96:99], v[182:185], v[198:201], v[96:99]
	v_mfma_f32_16x16x32_bf16 v[84:87], v[172:175], v[212:215], v[84:87]
	v_mfma_f32_16x16x32_bf16 v[68:71], v[172:175], v[220:223], v[68:71]
	v_mfma_f32_16x16x32_bf16 v[80:83], v[182:185], v[212:215], v[80:83]
	v_mfma_f32_16x16x32_bf16 v[64:67], v[182:185], v[220:223], v[64:67]
	s_setprio 0
	s_barrier
	s_add_i32 s3, s74, s14
	v_lshl_add_u64 v[202:203], s[60:61], 0, v[130:131]
	s_mov_b32 m0, s3
	ds_read_b128 v[186:189], v153 offset:16384
	ds_read_b128 v[190:193], v153 offset:17408
	ds_read_b128 v[194:197], v153 offset:18432
	ds_read_b128 v[198:201], v153 offset:19456
	ds_read_b128 v[208:211], v153 offset:20480
	ds_read_b128 v[212:215], v153 offset:21504
	ds_read_b128 v[216:219], v153 offset:22528
	ds_read_b128 v[220:223], v153 offset:23552
	global_load_lds_dwordx4 v[202:203], off
	s_add_i32 m0, s3, 0x2000
	s_add_u32 s78, s60, 0x20000
	v_lshl_add_u64 v[224:225], s[60:61], 0, v[134:135]
	s_addc_u32 s79, s61, 0
	s_add_i32 s3, s75, s14
	global_load_lds_dwordx4 v[224:225], off
	v_lshl_add_u64 v[226:227], s[78:79], 0, v[130:131]
	s_mov_b32 m0, s3
	global_load_lds_dwordx4 v[226:227], off
	v_lshl_add_u64 v[226:227], s[78:79], 0, v[134:135]
	s_add_i32 m0, s3, 0x2000
	s_nop 0
	global_load_lds_dwordx4 v[226:227], off
	s_waitcnt vmcnt(6)
	s_waitcnt lgkmcnt(0)
	s_barrier
	s_setprio 1
	s_waitcnt lgkmcnt(0)
	v_mfma_f32_16x16x32_bf16 v[60:63], v[144:147], v[186:189], v[60:63]
	v_mfma_f32_16x16x32_bf16 v[44:47], v[144:147], v[194:197], v[44:47]
	v_mfma_f32_16x16x32_bf16 v[56:59], v[160:163], v[186:189], v[56:59]
	v_mfma_f32_16x16x32_bf16 v[40:43], v[160:163], v[194:197], v[40:43]
	v_mfma_f32_16x16x32_bf16 v[28:31], v[144:147], v[208:211], v[28:31]
	v_mfma_f32_16x16x32_bf16 v[12:15], v[144:147], v[216:219], v[12:15]
	v_mfma_f32_16x16x32_bf16 v[24:27], v[160:163], v[208:211], v[24:27]
	v_mfma_f32_16x16x32_bf16 v[8:11], v[160:163], v[216:219], v[8:11]
	v_mfma_f32_16x16x32_bf16 v[60:63], v[156:159], v[190:193], v[60:63]
	v_mfma_f32_16x16x32_bf16 v[44:47], v[156:159], v[198:201], v[44:47]
	v_mfma_f32_16x16x32_bf16 v[56:59], v[164:167], v[190:193], v[56:59]
	v_mfma_f32_16x16x32_bf16 v[40:43], v[164:167], v[198:201], v[40:43]
	v_mfma_f32_16x16x32_bf16 v[28:31], v[156:159], v[212:215], v[28:31]
	v_mfma_f32_16x16x32_bf16 v[12:15], v[156:159], v[220:223], v[12:15]
	v_lshl_add_u64 v[226:227], s[62:63], 0, v[128:129]
	s_mov_b32 m0, s15
	s_nop 0
	global_load_lds_dwordx4 v[226:227], off
	v_mfma_f32_16x16x32_bf16 v[24:27], v[164:167], v[212:215], v[24:27]
	v_mfma_f32_16x16x32_bf16 v[8:11], v[164:167], v[220:223], v[8:11]
	s_setprio 0
	s_setprio 1
	v_mfma_f32_16x16x32_bf16 v[52:55], v[168:171], v[186:189], v[52:55]
	v_mfma_f32_16x16x32_bf16 v[36:39], v[168:171], v[194:197], v[36:39]
	v_mfma_f32_16x16x32_bf16 v[48:51], v[176:179], v[186:189], v[48:51]
	v_mfma_f32_16x16x32_bf16 v[32:35], v[176:179], v[194:197], v[32:35]
	v_mfma_f32_16x16x32_bf16 v[20:23], v[168:171], v[208:211], v[20:23]
	v_mfma_f32_16x16x32_bf16 v[4:7], v[168:171], v[216:219], v[4:7]
	v_mfma_f32_16x16x32_bf16 v[16:19], v[176:179], v[208:211], v[16:19]
	v_mfma_f32_16x16x32_bf16 v[0:3], v[176:179], v[216:219], v[0:3]
	v_mfma_f32_16x16x32_bf16 v[52:55], v[172:175], v[190:193], v[52:55]
	v_mfma_f32_16x16x32_bf16 v[36:39], v[172:175], v[198:201], v[36:39]
	v_mfma_f32_16x16x32_bf16 v[48:51], v[182:185], v[190:193], v[48:51]
	v_mfma_f32_16x16x32_bf16 v[32:35], v[182:185], v[198:201], v[32:35]
	v_mfma_f32_16x16x32_bf16 v[20:23], v[172:175], v[212:215], v[20:23]
	v_mfma_f32_16x16x32_bf16 v[4:7], v[172:175], v[220:223], v[4:7]
	v_lshl_add_u64 v[228:229], s[62:63], 0, v[132:133]
	s_mov_b32 m0, s34
	s_nop 0
	global_load_lds_dwordx4 v[228:229], off
	v_mfma_f32_16x16x32_bf16 v[16:19], v[182:185], v[212:215], v[16:19]
	v_mfma_f32_16x16x32_bf16 v[0:3], v[182:185], v[220:223], v[0:3]
	s_setprio 0
	s_barrier
; #define PG8_STAGE(bufoff, gbase, voff) do { _Pragma("unroll") for (int _i = 0; _i < 2; ++_i) \
;         __builtin_amdgcn_global_load_lds((const unsigned*)((const char*)(gbase) + (voff)[_i]), (PG8_LAS unsigned*)(lds + (bufoff) + ldsw + _i * 8192), 16, 0, 0); } while (0)
; #define PG8_LDA(dst, b, h) do { _Pragma("unroll") for (int m = 0; m < 4; ++m) _Pragma("unroll") for (int k = 0; k < 2; ++k) dst[m][k] = *(const PG8_LAS bf16x8*)(lds + PG8_SA(b, h) + aoff + m * 2048 + k * 1024); } while (0)
; #define PG8_LDB(dst, b, h) do { _Pragma("unroll") for (int n = 0; n < 2; ++n) _Pragma("unroll") for (int k = 0; k < 2; ++k) dst[n][k] = *(const PG8_LAS bf16x8*)(lds + PG8_SB(b, h) + boff + n * 2048 + k * 1024); } while (0)
; #define PG8_MMA(ai, bj, At, Bt) do { __builtin_amdgcn_s_setprio(1); _Pragma("unroll") for (int m = 0; m < 4; ++m) _Pragma("unroll") for (int n = 0; n < 2; ++n) _Pragma("unroll") for (int k = 0; k < 2; ++k) \
;         acc[ai][bj][m][n] = __builtin_amdgcn_mfma_f32_16x16x32_bf16(Bt[n][k], At[m][k], acc[ai][bj][m][n], 0, 0, 0); __builtin_amdgcn_s_setprio(0); } while (0)
; #define PG8_WAIT_V(n) asm volatile("s_waitcnt vmcnt(" #n ")" ::: "memory")
; #define PG8_WAIT_L(n) asm volatile("s_waitcnt lgkmcnt(" #n ")" ::: "memory")
; #define PG8_BAR __builtin_amdgcn_s_barrier()
; #define PG8_SCHED __builtin_amdgcn_sched_barrier(0)
; template <class Epi, class Sched, bool ALIGN_EPI = false, bool SP2 = false>
; __device__ __forceinline__ void gemm_phase(PG8_LAS unsigned char* lds, const Gemm g, const Sched& S, const Epi& E) {
;     ...
;             PG8_LDB(B0, 1, 0); PG8_LDB(B1, 1, 1); PG8_SCHED; PG8_LDA(At, 1, 0); PG8_STAGE(PG8_SA(0, 1), a2 + hstep, voffA);
;             PG8_WAIT_V(8); PG8_WAIT_L(0); PG8_BAR; PG8_MMA(0, 0, At, B0); PG8_MMA(0, 1, At, B1); PG8_BAR; PG8_SCHED;
	s_add_i32 s3, 0, 0x18000
	v_add_u32_e32 v155, s3, v149
	s_add_i32 s33, 0, 0x1c000
	ds_read_b128 v[144:147], v155
	ds_read_b128 v[156:159], v155 offset:1024
	ds_read_b128 v[160:163], v155 offset:2048
	ds_read_b128 v[164:167], v155 offset:3072
	v_add_u32_e32 v155, s33, v149
	ds_read_b128 v[168:171], v155
	ds_read_b128 v[172:175], v155 offset:1024
	ds_read_b128 v[176:179], v155 offset:2048
	ds_read_b128 v[182:185], v155 offset:3072
	s_add_u32 s62, s62, 0x20000
	s_addc_u32 s63, s63, 0
	s_mov_b32 m0, s57
	v_lshl_add_u64 v[230:231], s[62:63], 0, v[128:129]
	ds_read_b128 v[186:189], v153 offset:32768
	ds_read_b128 v[190:193], v153 offset:33792
	ds_read_b128 v[194:197], v153 offset:34816
	ds_read_b128 v[198:201], v153 offset:35840
	ds_read_b128 v[208:211], v153 offset:36864
	ds_read_b128 v[212:215], v153 offset:37888
	ds_read_b128 v[216:219], v153 offset:38912
	ds_read_b128 v[220:223], v153 offset:39936
	global_load_lds_dwordx4 v[230:231], off
	v_lshl_add_u64 v[230:231], s[62:63], 0, v[132:133]
	s_mov_b32 m0, s64
	s_nop 0
	global_load_lds_dwordx4 v[230:231], off
	s_waitcnt vmcnt(8)
	s_waitcnt lgkmcnt(0)
	s_barrier
	s_setprio 1
	s_waitcnt lgkmcnt(0)
	v_mfma_f32_16x16x32_bf16 v[124:127], v[144:147], v[186:189], v[124:127]
	v_mfma_f32_16x16x32_bf16 v[108:111], v[144:147], v[194:197], v[108:111]
	v_mfma_f32_16x16x32_bf16 v[120:123], v[160:163], v[186:189], v[120:123]
	v_mfma_f32_16x16x32_bf16 v[104:107], v[160:163], v[194:197], v[104:107]
	v_mfma_f32_16x16x32_bf16 v[92:95], v[144:147], v[208:211], v[92:95]
	v_mfma_f32_16x16x32_bf16 v[76:79], v[144:147], v[216:219], v[76:79]
	v_mfma_f32_16x16x32_bf16 v[88:91], v[160:163], v[208:211], v[88:91]
	v_mfma_f32_16x16x32_bf16 v[72:75], v[160:163], v[216:219], v[72:75]
	v_mfma_f32_16x16x32_bf16 v[124:127], v[156:159], v[190:193], v[124:127]
	v_mfma_f32_16x16x32_bf16 v[108:111], v[156:159], v[198:201], v[108:111]
	v_mfma_f32_16x16x32_bf16 v[120:123], v[164:167], v[190:193], v[120:123]
	v_mfma_f32_16x16x32_bf16 v[104:107], v[164:167], v[198:201], v[104:107]
	v_mfma_f32_16x16x32_bf16 v[92:95], v[156:159], v[212:215], v[92:95]
	v_mfma_f32_16x16x32_bf16 v[76:79], v[156:159], v[220:223], v[76:79]
	v_mfma_f32_16x16x32_bf16 v[88:91], v[164:167], v[212:215], v[88:91]
	v_mfma_f32_16x16x32_bf16 v[72:75], v[164:167], v[220:223], v[72:75]
	s_setprio 0
	s_setprio 1
	v_mfma_f32_16x16x32_bf16 v[116:119], v[168:171], v[186:189], v[116:119]
	v_mfma_f32_16x16x32_bf16 v[100:103], v[168:171], v[194:197], v[100:103]
	v_mfma_f32_16x16x32_bf16 v[112:115], v[176:179], v[186:189], v[112:115]
	v_mfma_f32_16x16x32_bf16 v[96:99], v[176:179], v[194:197], v[96:99]
	v_mfma_f32_16x16x32_bf16 v[84:87], v[168:171], v[208:211], v[84:87]
	v_mfma_f32_16x16x32_bf16 v[68:71], v[168:171], v[216:219], v[68:71]
	v_mfma_f32_16x16x32_bf16 v[80:83], v[176:179], v[208:211], v[80:83]
	v_mfma_f32_16x16x32_bf16 v[64:67], v[176:179], v[216:219], v[64:67]
	v_mfma_f32_16x16x32_bf16 v[116:119], v[172:175], v[190:193], v[116:119]
	v_mfma_f32_16x16x32_bf16 v[100:103], v[172:175], v[198:201], v[100:103]
	v_mfma_f32_16x16x32_bf16 v[112:115], v[182:185], v[190:193], v[112:115]
	v_mfma_f32_16x16x32_bf16 v[96:99], v[182:185], v[198:201], v[96:99]
	v_mfma_f32_16x16x32_bf16 v[84:87], v[172:175], v[212:215], v[84:87]
	v_mfma_f32_16x16x32_bf16 v[68:71], v[172:175], v[220:223], v[68:71]
	v_mfma_f32_16x16x32_bf16 v[80:83], v[182:185], v[212:215], v[80:83]
	v_mfma_f32_16x16x32_bf16 v[64:67], v[182:185], v[220:223], v[64:67]
	s_setprio 0
	s_barrier
; #define PG8_STAGE(bufoff, gbase, voff) do { _Pragma("unroll") for (int _i = 0; _i < 2; ++_i) \
;         __builtin_amdgcn_global_load_lds((const unsigned*)((const char*)(gbase) + (voff)[_i]), (PG8_LAS unsigned*)(lds + (bufoff) + ldsw + _i * 8192), 16, 0, 0); } while (0)
; #define PG8_LDA(dst, b, h) do { _Pragma("unroll") for (int m = 0; m < 4; ++m) _Pragma("unroll") for (int k = 0; k < 2; ++k) dst[m][k] = *(const PG8_LAS bf16x8*)(lds + PG8_SA(b, h) + aoff + m * 2048 + k * 1024); } while (0)
; #define PG8_MMA(ai, bj, At, Bt) do { __builtin_amdgcn_s_setprio(1); _Pragma("unroll") for (int m = 0; m < 4; ++m) _Pragma("unroll") for (int n = 0; n < 2; ++n) _Pragma("unroll") for (int k = 0; k < 2; ++k) \
;         acc[ai][bj][m][n] = __builtin_amdgcn_mfma_f32_16x16x32_bf16(Bt[n][k], At[m][k], acc[ai][bj][m][n], 0, 0, 0); __builtin_amdgcn_s_setprio(0); } while (0)
; #define PG8_WAIT_V(n) asm volatile("s_waitcnt vmcnt(" #n ")" ::: "memory")
; #define PG8_WAIT_L(n) asm volatile("s_waitcnt lgkmcnt(" #n ")" ::: "memory")
; #define PG8_BAR __builtin_amdgcn_s_barrier()
; #define PG8_SCHED __builtin_amdgcn_sched_barrier(0)
; template <class Epi, class Sched, bool ALIGN_EPI = false, bool SP2 = false>
; __device__ __forceinline__ void gemm_phase(PG8_LAS unsigned char* lds, const Gemm g, const Sched& S, const Epi& E) {
;     ...
;             PG8_LDA(At, 1, 1); PG8_STAGE(PG8_SB(1, 0), b3, voffB); PG8_STAGE(PG8_SB(1, 1), b3 + hstep, voffB); PG8_STAGE(PG8_SA(1, 0), a3, voffA);
;             PG8_WAIT_V(8); PG8_WAIT_L(0); PG8_BAR; PG8_MMA(1, 0, At, B0); PG8_MMA(1, 1, At, B1); PG8_BAR; PG8_SCHED;
;     ...
;         if constexpr (ALIGN_EPI) { if (wr == 0) PG8_BAR; }
	s_add_i32 s3, s3, s14
	v_lshl_add_u64 v[202:203], v[202:203], 0, s[38:39]
	s_mov_b32 m0, s3
	ds_read_b128 v[186:189], v153 offset:49152
	ds_read_b128 v[190:193], v153 offset:50176
	ds_read_b128 v[194:197], v153 offset:51200
	ds_read_b128 v[198:201], v153 offset:52224
	ds_read_b128 v[208:211], v153 offset:53248
	ds_read_b128 v[212:215], v153 offset:54272
	ds_read_b128 v[216:219], v153 offset:55296
	ds_read_b128 v[220:223], v153 offset:56320
	global_load_lds_dwordx4 v[202:203], off
	s_add_i32 m0, s3, 0x2000
	s_add_u32 s60, s60, 0x20080
	v_lshl_add_u64 v[202:203], v[224:225], 0, s[38:39]
	s_addc_u32 s61, s61, 0
	s_add_i32 s3, s33, s14
	global_load_lds_dwordx4 v[202:203], off
	v_lshl_add_u64 v[202:203], s[60:61], 0, v[130:131]
	s_mov_b32 m0, s3
	s_nop 0
	global_load_lds_dwordx4 v[202:203], off
	v_lshl_add_u64 v[202:203], s[60:61], 0, v[134:135]
	s_add_i32 m0, s3, 0x2000
	s_nop 0
	global_load_lds_dwordx4 v[202:203], off
	s_waitcnt vmcnt(6)
	s_waitcnt lgkmcnt(0)
	s_barrier
	s_setprio 1
	s_waitcnt lgkmcnt(0)
	v_mfma_f32_16x16x32_bf16 v[60:63], v[144:147], v[186:189], v[60:63]
	v_mfma_f32_16x16x32_bf16 v[44:47], v[144:147], v[194:197], v[44:47]
	v_mfma_f32_16x16x32_bf16 v[56:59], v[160:163], v[186:189], v[56:59]
	v_mfma_f32_16x16x32_bf16 v[40:43], v[160:163], v[194:197], v[40:43]
	v_mfma_f32_16x16x32_bf16 v[28:31], v[144:147], v[208:211], v[28:31]
	v_mfma_f32_16x16x32_bf16 v[12:15], v[144:147], v[216:219], v[12:15]
	v_mfma_f32_16x16x32_bf16 v[24:27], v[160:163], v[208:211], v[24:27]
	v_mfma_f32_16x16x32_bf16 v[8:11], v[160:163], v[216:219], v[8:11]
	v_mfma_f32_16x16x32_bf16 v[60:63], v[156:159], v[190:193], v[60:63]
	v_mfma_f32_16x16x32_bf16 v[44:47], v[156:159], v[198:201], v[44:47]
	v_mfma_f32_16x16x32_bf16 v[56:59], v[164:167], v[190:193], v[56:59]
	v_mfma_f32_16x16x32_bf16 v[40:43], v[164:167], v[198:201], v[40:43]
	v_mfma_f32_16x16x32_bf16 v[28:31], v[156:159], v[212:215], v[28:31]
	v_mfma_f32_16x16x32_bf16 v[12:15], v[156:159], v[220:223], v[12:15]
	v_lshl_add_u64 v[202:203], v[226:227], 0, s[38:39]
	s_mov_b32 m0, s66
	s_nop 0
	global_load_lds_dwordx4 v[202:203], off
	v_mfma_f32_16x16x32_bf16 v[24:27], v[164:167], v[212:215], v[24:27]
	v_mfma_f32_16x16x32_bf16 v[8:11], v[164:167], v[220:223], v[8:11]
	s_setprio 0
	s_setprio 1
	v_mfma_f32_16x16x32_bf16 v[52:55], v[168:171], v[186:189], v[52:55]
	v_mfma_f32_16x16x32_bf16 v[36:39], v[168:171], v[194:197], v[36:39]
	v_mfma_f32_16x16x32_bf16 v[48:51], v[176:179], v[186:189], v[48:51]
	v_mfma_f32_16x16x32_bf16 v[32:35], v[176:179], v[194:197], v[32:35]
	v_mfma_f32_16x16x32_bf16 v[20:23], v[168:171], v[208:211], v[20:23]
	v_mfma_f32_16x16x32_bf16 v[4:7], v[168:171], v[216:219], v[4:7]
	v_mfma_f32_16x16x32_bf16 v[16:19], v[176:179], v[208:211], v[16:19]
	v_mfma_f32_16x16x32_bf16 v[0:3], v[176:179], v[216:219], v[0:3]
	v_mfma_f32_16x16x32_bf16 v[52:55], v[172:175], v[190:193], v[52:55]
	v_mfma_f32_16x16x32_bf16 v[36:39], v[172:175], v[198:201], v[36:39]
	v_mfma_f32_16x16x32_bf16 v[48:51], v[182:185], v[190:193], v[48:51]
	v_mfma_f32_16x16x32_bf16 v[32:35], v[182:185], v[198:201], v[32:35]
	v_mfma_f32_16x16x32_bf16 v[20:23], v[172:175], v[212:215], v[20:23]
	v_mfma_f32_16x16x32_bf16 v[4:7], v[172:175], v[220:223], v[4:7]
	v_lshl_add_u64 v[202:203], v[228:229], 0, s[38:39]
	s_mov_b32 m0, s67
	s_nop 0
	global_load_lds_dwordx4 v[202:203], off
	v_mfma_f32_16x16x32_bf16 v[16:19], v[182:185], v[212:215], v[16:19]
	v_mfma_f32_16x16x32_bf16 v[0:3], v[182:185], v[220:223], v[0:3]
	s_setprio 0
	s_barrier
	s_add_i32 s87, s87, 2
	s_add_u32 s58, s58, 0x100
	s_addc_u32 s59, s59, 0
	s_add_u32 s85, s85, 0x100
	s_addc_u32 s86, s86, 0
	s_cmp_gt_u32 s87, 5
	s_cbranch_scc0 .LBB0_873
	s_and_b64 vcc, exec, s[42:43]
	s_cbranch_vccz .LBB0_876
	s_barrier

; #define PG8_STAGE(bufoff, gbase, voff) do { _Pragma("unroll") for (int _i = 0; _i < 2; ++_i) \
;         __builtin_amdgcn_global_load_lds((const unsigned*)((const char*)(gbase) + (voff)[_i]), (PG8_LAS unsigned*)(lds + (bufoff) + ldsw + _i * 8192), 16, 0, 0); } while (0)
; #define PG8_LDA(dst, b, h) do { _Pragma("unroll") for (int m = 0; m < 4; ++m) _Pragma("unroll") for (int k = 0; k < 2; ++k) dst[m][k] = *(const PG8_LAS bf16x8*)(lds + PG8_SA(b, h) + aoff + m * 2048 + k * 1024); } while (0)
; #define PG8_LDB(dst, b, h) do { _Pragma("unroll") for (int n = 0; n < 2; ++n) _Pragma("unroll") for (int k = 0; k < 2; ++k) dst[n][k] = *(const PG8_LAS bf16x8*)(lds + PG8_SB(b, h) + boff + n * 2048 + k * 1024); } while (0)
; #define PG8_WAIT_V(n) asm volatile("s_waitcnt vmcnt(" #n ")" ::: "memory")
; #define PG8_WAIT_L(n) asm volatile("s_waitcnt lgkmcnt(" #n ")" ::: "memory")
; #define PG8_BAR __builtin_amdgcn_s_barrier()
; #define PG8_SCHED __builtin_amdgcn_sched_barrier(0)
; template <class Epi, class Sched, bool ALIGN_EPI = false, bool SP2 = false>
; __device__ __forceinline__ void gemm_phase(PG8_LAS unsigned char* lds, const Gemm g, const Sched& S, const Epi& E) {
;     ...
;         const bool has_next = S.next(ui + 1, nxt);
;         const char* nA = has_next ? (const char*)g.A + (size_t)nxt.pm * tstep : cA; const char* nB = has_next ? (const char*)g.Bt + (size_t)nxt.pn * tstep : cB;
;         for (int t = 0; t < nt; t += 2) {
;             const bool last = (t == nt - 2);
;             const char* a1 = cA + (size_t)(t + 1) * kstep;
;             const char* a2 = last ? nA : cA + (size_t)(t + 2) * kstep; const char* b2 = last ? nB : cB + (size_t)(t + 2) * kstep;
;             const char* a3 = a2 + kstep; const char* b3 = b2 + kstep;
;             if (last && has_next) S.a_ready(nxt);
;             if constexpr (SP2) {
;             PG8_LDB(B0, 0, 0); PG8_LDB(B1, 0, 1); PG8_SCHED; PG8_LDA(At, 0, 0); PG8_STAGE(PG8_SA(1, 1), a1 + hstep, voffA);
;             PG8_WAIT_V(8); PG8_WAIT_L(0); PG8_BAR; PG8_MMA(0, 0, At, B0); PG8_MMA(0, 1, At, B1); PG8_BAR; PG8_SCHED;
;             PG8_LDA(At, 0, 1); PG8_STAGE(PG8_SB(0, 0), b2, voffB); PG8_STAGE(PG8_SB(0, 1), b2 + hstep, voffB); PG8_STAGE(PG8_SA(0, 0), a2, voffA);
;             PG8_WAIT_V(8); PG8_WAIT_L(0); PG8_BAR; PG8_MMA(1, 0, At, B0); PG8_MMA(1, 1, At, B1); PG8_BAR; PG8_SCHED;
.LBB0_956:
	s_ashr_i32 s45, s44, 31
	s_lshl_b64 s[48:49], s[44:45], 19
	s_add_u32 s48, s22, s48
	s_addc_u32 s49, s23, s49
	s_and_b64 s[50:51], s[10:11], exec
	s_cselect_b32 s45, s49, s55
	s_cselect_b32 s75, s48, s54
	s_ashr_i32 s43, s42, 31
	s_lshl_b64 s[50:51], s[42:43], 19
	v_readlane_b32 s3, v250, 18
	s_add_u32 s50, s3, s50
	v_readlane_b32 s3, v250, 19
	s_addc_u32 s51, s3, s51
	s_and_b64 s[58:59], s[10:11], exec
	s_cselect_b32 s43, s51, s57
	s_cselect_b32 s76, s50, s56
	s_add_u32 s54, s54, 0x40080
	s_addc_u32 s55, s55, 0
	s_add_u32 s77, s56, 0x100
	s_addc_u32 s82, s57, 0
	s_mov_b32 s83, -2
	ds_read_b128 v[144:147], v155
	ds_read_b128 v[148:151], v155 offset:1024
	ds_read_b128 v[160:163], v155 offset:2048
	ds_read_b128 v[164:167], v155 offset:3072
	ds_read_b128 v[168:171], v156
	ds_read_b128 v[172:175], v156 offset:1024
	ds_read_b128 v[176:179], v156 offset:2048
	ds_read_b128 v[182:185], v156 offset:3072
	s_add_u32 s3, s54, 0xfffc0080
	s_addc_u32 s33, s55, -1
	s_cmp_eq_u32 s83, 12
	s_cselect_b32 s59, s45, s33
	s_cselect_b32 s58, s75, s3
	s_cselect_b32 s57, s43, s82
	s_cselect_b32 s56, s76, s77
	v_lshl_add_u64 v[202:203], s[54:55], 0, v[136:137]
	s_add_i32 m0, s34, 0xc000
	ds_read_b128 v[186:189], v157
	ds_read_b128 v[190:193], v157 offset:1024
	ds_read_b128 v[194:197], v157 offset:2048
	ds_read_b128 v[198:201], v157 offset:3072
	ds_read_b128 v[208:211], v157 offset:4096
	ds_read_b128 v[212:215], v157 offset:5120
	ds_read_b128 v[216:219], v157 offset:6144
	ds_read_b128 v[220:223], v157 offset:7168
	global_load_lds_dwordx4 v[202:203], off
	v_lshl_add_u64 v[202:203], s[54:55], 0, v[138:139]
	s_add_i32 m0, s34, 0xe000
	s_nop 0
	global_load_lds_dwordx4 v[202:203], off
	s_waitcnt vmcnt(8)
	s_waitcnt lgkmcnt(0)
	s_barrier
	s_setprio 1
	s_waitcnt lgkmcnt(0)
	v_mfma_f32_16x16x32_bf16 v[124:127], v[144:147], v[186:189], 0
	v_mfma_f32_16x16x32_bf16 v[108:111], v[144:147], v[194:197], 0
	v_mfma_f32_16x16x32_bf16 v[120:123], v[160:163], v[186:189], 0
	v_mfma_f32_16x16x32_bf16 v[104:107], v[160:163], v[194:197], 0
	v_mfma_f32_16x16x32_bf16 v[92:95], v[144:147], v[208:211], 0
	v_mfma_f32_16x16x32_bf16 v[76:79], v[144:147], v[216:219], 0
	v_mfma_f32_16x16x32_bf16 v[88:91], v[160:163], v[208:211], 0
	v_mfma_f32_16x16x32_bf16 v[72:75], v[160:163], v[216:219], 0
	v_mfma_f32_16x16x32_bf16 v[124:127], v[148:151], v[190:193], v[124:127]
	v_mfma_f32_16x16x32_bf16 v[108:111], v[148:151], v[198:201], v[108:111]
	v_mfma_f32_16x16x32_bf16 v[120:123], v[164:167], v[190:193], v[120:123]
	v_mfma_f32_16x16x32_bf16 v[104:107], v[164:167], v[198:201], v[104:107]
	v_mfma_f32_16x16x32_bf16 v[92:95], v[148:151], v[212:215], v[92:95]
	v_mfma_f32_16x16x32_bf16 v[76:79], v[148:151], v[220:223], v[76:79]
	v_mfma_f32_16x16x32_bf16 v[88:91], v[164:167], v[212:215], v[88:91]
	v_mfma_f32_16x16x32_bf16 v[72:75], v[164:167], v[220:223], v[72:75]
	s_setprio 0
	s_setprio 1
	v_mfma_f32_16x16x32_bf16 v[116:119], v[168:171], v[186:189], 0
	v_mfma_f32_16x16x32_bf16 v[100:103], v[168:171], v[194:197], 0
	v_mfma_f32_16x16x32_bf16 v[112:115], v[176:179], v[186:189], 0
	v_mfma_f32_16x16x32_bf16 v[96:99], v[176:179], v[194:197], 0
	v_mfma_f32_16x16x32_bf16 v[84:87], v[168:171], v[208:211], 0
	v_mfma_f32_16x16x32_bf16 v[68:71], v[168:171], v[216:219], 0
	v_mfma_f32_16x16x32_bf16 v[80:83], v[176:179], v[208:211], 0
	v_mfma_f32_16x16x32_bf16 v[64:67], v[176:179], v[216:219], 0
	v_mfma_f32_16x16x32_bf16 v[116:119], v[172:175], v[190:193], v[116:119]
	v_mfma_f32_16x16x32_bf16 v[100:103], v[172:175], v[198:201], v[100:103]
	v_mfma_f32_16x16x32_bf16 v[112:115], v[182:185], v[190:193], v[112:115]
	v_mfma_f32_16x16x32_bf16 v[96:99], v[182:185], v[198:201], v[96:99]
	v_mfma_f32_16x16x32_bf16 v[84:87], v[172:175], v[212:215], v[84:87]
	v_mfma_f32_16x16x32_bf16 v[68:71], v[172:175], v[220:223], v[68:71]
	v_mfma_f32_16x16x32_bf16 v[80:83], v[182:185], v[212:215], v[80:83]
	v_mfma_f32_16x16x32_bf16 v[64:67], v[182:185], v[220:223], v[64:67]
	s_setprio 0
	s_barrier
	s_add_i32 s3, s65, s14
	v_lshl_add_u64 v[202:203], s[56:57], 0, v[132:133]
	s_mov_b32 m0, s3
	ds_read_b128 v[186:189], v157 offset:16384
	ds_read_b128 v[190:193], v157 offset:17408
	ds_read_b128 v[194:197], v157 offset:18432
	ds_read_b128 v[198:201], v157 offset:19456
	ds_read_b128 v[208:211], v157 offset:20480
	ds_read_b128 v[212:215], v157 offset:21504
	ds_read_b128 v[216:219], v157 offset:22528
	ds_read_b128 v[220:223], v157 offset:23552
	global_load_lds_dwordx4 v[202:203], off
	s_add_i32 m0, s3, 0x2000
	s_add_u32 s78, s56, 0x40000
	v_lshl_add_u64 v[224:225], s[56:57], 0, v[128:129]
	s_addc_u32 s79, s57, 0
	s_add_i32 s3, s66, s14
	global_load_lds_dwordx4 v[224:225], off
	v_lshl_add_u64 v[226:227], s[78:79], 0, v[132:133]
	s_mov_b32 m0, s3
	global_load_lds_dwordx4 v[226:227], off
	v_lshl_add_u64 v[226:227], s[78:79], 0, v[128:129]
	s_add_i32 m0, s3, 0x2000
	s_nop 0
	global_load_lds_dwordx4 v[226:227], off
	s_waitcnt vmcnt(6)
	s_waitcnt lgkmcnt(0)
	s_barrier
; #define PG8_STAGE(bufoff, gbase, voff) do { _Pragma("unroll") for (int _i = 0; _i < 2; ++_i) \
;         __builtin_amdgcn_global_load_lds((const unsigned*)((const char*)(gbase) + (voff)[_i]), (PG8_LAS unsigned*)(lds + (bufoff) + ldsw + _i * 8192), 16, 0, 0); } while (0)
; #define PG8_LDA(dst, b, h) do { _Pragma("unroll") for (int m = 0; m < 4; ++m) _Pragma("unroll") for (int k = 0; k < 2; ++k) dst[m][k] = *(const PG8_LAS bf16x8*)(lds + PG8_SA(b, h) + aoff + m * 2048 + k * 1024); } while (0)
; #define PG8_LDB(dst, b, h) do { _Pragma("unroll") for (int n = 0; n < 2; ++n) _Pragma("unroll") for (int k = 0; k < 2; ++k) dst[n][k] = *(const PG8_LAS bf16x8*)(lds + PG8_SB(b, h) + boff + n * 2048 + k * 1024); } while (0)
; #define PG8_MMA(ai, bj, At, Bt) do { __builtin_amdgcn_s_setprio(1); _Pragma("unroll") for (int m = 0; m < 4; ++m) _Pragma("unroll") for (int n = 0; n < 2; ++n) _Pragma("unroll") for (int k = 0; k < 2; ++k) \
;         acc[ai][bj][m][n] = __builtin_amdgcn_mfma_f32_16x16x32_bf16(Bt[n][k], At[m][k], acc[ai][bj][m][n], 0, 0, 0); __builtin_amdgcn_s_setprio(0); } while (0)
; #define PG8_WAIT_V(n) asm volatile("s_waitcnt vmcnt(" #n ")" ::: "memory")
; #define PG8_WAIT_L(n) asm volatile("s_waitcnt lgkmcnt(" #n ")" ::: "memory")
; #define PG8_BAR __builtin_amdgcn_s_barrier()
; #define PG8_SCHED __builtin_amdgcn_sched_barrier(0)
; template <class Epi, class Sched, bool ALIGN_EPI = false, bool SP2 = false>
; __device__ __forceinline__ void gemm_phase(PG8_LAS unsigned char* lds, const Gemm g, const Sched& S, const Epi& E) {
;     ...
;             PG8_WAIT_V(8); PG8_WAIT_L(0); PG8_BAR; PG8_MMA(1, 0, At, B0); PG8_MMA(1, 1, At, B1); PG8_BAR; PG8_SCHED;
;             PG8_LDB(B0, 1, 0); PG8_LDB(B1, 1, 1); PG8_SCHED; PG8_LDA(At, 1, 0); PG8_STAGE(PG8_SA(0, 1), a2 + hstep, voffA);
;             PG8_WAIT_V(8); PG8_WAIT_L(0); PG8_BAR; PG8_MMA(0, 0, At, B0); PG8_MMA(0, 1, At, B1); PG8_BAR; PG8_SCHED;
	s_setprio 1
	s_waitcnt lgkmcnt(0)
	v_mfma_f32_16x16x32_bf16 v[60:63], v[144:147], v[186:189], 0
	v_mfma_f32_16x16x32_bf16 v[44:47], v[144:147], v[194:197], 0
	v_mfma_f32_16x16x32_bf16 v[56:59], v[160:163], v[186:189], 0
	v_mfma_f32_16x16x32_bf16 v[40:43], v[160:163], v[194:197], 0
	v_mfma_f32_16x16x32_bf16 v[28:31], v[144:147], v[208:211], 0
	v_mfma_f32_16x16x32_bf16 v[12:15], v[144:147], v[216:219], 0
	v_mfma_f32_16x16x32_bf16 v[24:27], v[160:163], v[208:211], 0
	v_mfma_f32_16x16x32_bf16 v[8:11], v[160:163], v[216:219], 0
	v_mfma_f32_16x16x32_bf16 v[60:63], v[148:151], v[190:193], v[60:63]
	v_mfma_f32_16x16x32_bf16 v[44:47], v[148:151], v[198:201], v[44:47]
	v_mfma_f32_16x16x32_bf16 v[56:59], v[164:167], v[190:193], v[56:59]
	v_mfma_f32_16x16x32_bf16 v[40:43], v[164:167], v[198:201], v[40:43]
	v_mfma_f32_16x16x32_bf16 v[28:31], v[148:151], v[212:215], v[28:31]
	v_mfma_f32_16x16x32_bf16 v[12:15], v[148:151], v[220:223], v[12:15]
	v_lshl_add_u64 v[226:227], s[58:59], 0, v[134:135]
	s_mov_b32 m0, s34
	s_nop 0
	global_load_lds_dwordx4 v[226:227], off
	v_mfma_f32_16x16x32_bf16 v[24:27], v[164:167], v[212:215], v[24:27]
	v_mfma_f32_16x16x32_bf16 v[8:11], v[164:167], v[220:223], v[8:11]
	s_setprio 0
	s_setprio 1
	v_mfma_f32_16x16x32_bf16 v[52:55], v[168:171], v[186:189], 0
	v_mfma_f32_16x16x32_bf16 v[36:39], v[168:171], v[194:197], 0
	v_mfma_f32_16x16x32_bf16 v[48:51], v[176:179], v[186:189], 0
	v_mfma_f32_16x16x32_bf16 v[32:35], v[176:179], v[194:197], 0
	v_mfma_f32_16x16x32_bf16 v[20:23], v[168:171], v[208:211], 0
	v_mfma_f32_16x16x32_bf16 v[4:7], v[168:171], v[216:219], 0
	v_mfma_f32_16x16x32_bf16 v[16:19], v[176:179], v[208:211], 0
	v_mfma_f32_16x16x32_bf16 v[0:3], v[176:179], v[216:219], 0
	v_mfma_f32_16x16x32_bf16 v[52:55], v[172:175], v[190:193], v[52:55]
	v_mfma_f32_16x16x32_bf16 v[36:39], v[172:175], v[198:201], v[36:39]
	v_mfma_f32_16x16x32_bf16 v[48:51], v[182:185], v[190:193], v[48:51]
	v_mfma_f32_16x16x32_bf16 v[32:35], v[182:185], v[198:201], v[32:35]
	v_mfma_f32_16x16x32_bf16 v[20:23], v[172:175], v[212:215], v[20:23]
	v_mfma_f32_16x16x32_bf16 v[4:7], v[172:175], v[220:223], v[4:7]
	v_lshl_add_u64 v[228:229], s[58:59], 0, v[130:131]
	s_mov_b32 m0, s53
	s_nop 0
	global_load_lds_dwordx4 v[228:229], off
	v_mfma_f32_16x16x32_bf16 v[16:19], v[182:185], v[212:215], v[16:19]
	v_mfma_f32_16x16x32_bf16 v[0:3], v[182:185], v[220:223], v[0:3]
	s_setprio 0
	s_barrier
	s_add_i32 s3, 0, 0x18000
	v_add_u32_e32 v159, s3, v153
	s_add_i32 s33, 0, 0x1c000
	ds_read_b128 v[144:147], v159
	ds_read_b128 v[148:151], v159 offset:1024
	ds_read_b128 v[160:163], v159 offset:2048
	ds_read_b128 v[164:167], v159 offset:3072
	v_add_u32_e32 v159, s33, v153
	ds_read_b128 v[168:171], v159
	ds_read_b128 v[172:175], v159 offset:1024
	ds_read_b128 v[176:179], v159 offset:2048
	ds_read_b128 v[182:185], v159 offset:3072
	s_add_u32 s58, s58, 0x40000
	s_addc_u32 s59, s59, 0
	s_mov_b32 m0, s60
	v_lshl_add_u64 v[230:231], s[58:59], 0, v[134:135]
	ds_read_b128 v[186:189], v157 offset:32768
	ds_read_b128 v[190:193], v157 offset:33792
	ds_read_b128 v[194:197], v157 offset:34816
	ds_read_b128 v[198:201], v157 offset:35840
	ds_read_b128 v[208:211], v157 offset:36864
	ds_read_b128 v[212:215], v157 offset:37888
	ds_read_b128 v[216:219], v157 offset:38912
	ds_read_b128 v[220:223], v157 offset:39936
	global_load_lds_dwordx4 v[230:231], off
	v_lshl_add_u64 v[230:231], s[58:59], 0, v[130:131]
	s_mov_b32 m0, s61
	s_nop 0
	global_load_lds_dwordx4 v[230:231], off
	s_waitcnt vmcnt(8)
	s_waitcnt lgkmcnt(0)
	s_barrier
	s_setprio 1
	s_waitcnt lgkmcnt(0)
	v_mfma_f32_16x16x32_bf16 v[124:127], v[144:147], v[186:189], v[124:127]
	v_mfma_f32_16x16x32_bf16 v[108:111], v[144:147], v[194:197], v[108:111]
	v_mfma_f32_16x16x32_bf16 v[120:123], v[160:163], v[186:189], v[120:123]
	v_mfma_f32_16x16x32_bf16 v[104:107], v[160:163], v[194:197], v[104:107]
	v_mfma_f32_16x16x32_bf16 v[92:95], v[144:147], v[208:211], v[92:95]
	v_mfma_f32_16x16x32_bf16 v[76:79], v[144:147], v[216:219], v[76:79]
	v_mfma_f32_16x16x32_bf16 v[88:91], v[160:163], v[208:211], v[88:91]
	v_mfma_f32_16x16x32_bf16 v[72:75], v[160:163], v[216:219], v[72:75]
	v_mfma_f32_16x16x32_bf16 v[124:127], v[148:151], v[190:193], v[124:127]
	v_mfma_f32_16x16x32_bf16 v[108:111], v[148:151], v[198:201], v[108:111]
	v_mfma_f32_16x16x32_bf16 v[120:123], v[164:167], v[190:193], v[120:123]
	v_mfma_f32_16x16x32_bf16 v[104:107], v[164:167], v[198:201], v[104:107]
	v_mfma_f32_16x16x32_bf16 v[92:95], v[148:151], v[212:215], v[92:95]
	v_mfma_f32_16x16x32_bf16 v[76:79], v[148:151], v[220:223], v[76:79]
	v_mfma_f32_16x16x32_bf16 v[88:91], v[164:167], v[212:215], v[88:91]
	v_mfma_f32_16x16x32_bf16 v[72:75], v[164:167], v[220:223], v[72:75]
	s_setprio 0
	s_setprio 1
	v_mfma_f32_16x16x32_bf16 v[116:119], v[168:171], v[186:189], v[116:119]
	v_mfma_f32_16x16x32_bf16 v[100:103], v[168:171], v[194:197], v[100:103]
	v_mfma_f32_16x16x32_bf16 v[112:115], v[176:179], v[186:189], v[112:115]
	v_mfma_f32_16x16x32_bf16 v[96:99], v[176:179], v[194:197], v[96:99]
	v_mfma_f32_16x16x32_bf16 v[84:87], v[168:171], v[208:211], v[84:87]
	v_mfma_f32_16x16x32_bf16 v[68:71], v[168:171], v[216:219], v[68:71]
	v_mfma_f32_16x16x32_bf16 v[80:83], v[176:179], v[208:211], v[80:83]
	v_mfma_f32_16x16x32_bf16 v[64:67], v[176:179], v[216:219], v[64:67]
	v_mfma_f32_16x16x32_bf16 v[116:119], v[172:175], v[190:193], v[116:119]
	v_mfma_f32_16x16x32_bf16 v[100:103], v[172:175], v[198:201], v[100:103]
	v_mfma_f32_16x16x32_bf16 v[112:115], v[182:185], v[190:193], v[112:115]
	v_mfma_f32_16x16x32_bf16 v[96:99], v[182:185], v[198:201], v[96:99]
	v_mfma_f32_16x16x32_bf16 v[84:87], v[172:175], v[212:215], v[84:87]
	v_mfma_f32_16x16x32_bf16 v[68:71], v[172:175], v[220:223], v[68:71]
	v_mfma_f32_16x16x32_bf16 v[80:83], v[182:185], v[212:215], v[80:83]
	v_mfma_f32_16x16x32_bf16 v[64:67], v[182:185], v[220:223], v[64:67]
	s_setprio 0
	s_barrier
; #define PG8_STAGE(bufoff, gbase, voff) do { _Pragma("unroll") for (int _i = 0; _i < 2; ++_i) \
;         __builtin_amdgcn_global_load_lds((const unsigned*)((const char*)(gbase) + (voff)[_i]), (PG8_LAS unsigned*)(lds + (bufoff) + ldsw + _i * 8192), 16, 0, 0); } while (0)
; #define PG8_LDA(dst, b, h) do { _Pragma("unroll") for (int m = 0; m < 4; ++m) _Pragma("unroll") for (int k = 0; k < 2; ++k) dst[m][k] = *(const PG8_LAS bf16x8*)(lds + PG8_SA(b, h) + aoff + m * 2048 + k * 1024); } while (0)
; #define PG8_LDB(dst, b, h) do { _Pragma("unroll") for (int n = 0; n < 2; ++n) _Pragma("unroll") for (int k = 0; k < 2; ++k) dst[n][k] = *(const PG8_LAS bf16x8*)(lds + PG8_SB(b, h) + boff + n * 2048 + k * 1024); } while (0)
; #define PG8_MMA(ai, bj, At, Bt) do { __builtin_amdgcn_s_setprio(1); _Pragma("unroll") for (int m = 0; m < 4; ++m) _Pragma("unroll") for (int n = 0; n < 2; ++n) _Pragma("unroll") for (int k = 0; k < 2; ++k) \
;         acc[ai][bj][m][n] = __builtin_amdgcn_mfma_f32_16x16x32_bf16(Bt[n][k], At[m][k], acc[ai][bj][m][n], 0, 0, 0); __builtin_amdgcn_s_setprio(0); } while (0)
; #define PG8_WAIT_V(n) asm volatile("s_waitcnt vmcnt(" #n ")" ::: "memory")
; template <class Epi, class Sched, bool ALIGN_EPI = false, bool SP2 = false>
; __device__ __forceinline__ void gemm_phase(PG8_LAS unsigned char* lds, const Gemm g, const Sched& S, const Epi& E) {
;     ...
;             PG8_LDB(B0, 0, 0); PG8_LDB(B1, 0, 1); PG8_SCHED; PG8_LDA(At, 0, 0); PG8_STAGE(PG8_SA(1, 1), a1 + hstep, voffA);
;             PG8_WAIT_V(8); PG8_WAIT_L(0); PG8_BAR; PG8_MMA(0, 0, At, B0); PG8_MMA(0, 1, At, B1); PG8_BAR; PG8_SCHED;
;             PG8_LDA(At, 0, 1); PG8_STAGE(PG8_SB(0, 0), b2, voffB); PG8_STAGE(PG8_SB(0, 1), b2 + hstep, voffB); PG8_STAGE(PG8_SA(0, 0), a2, voffA);
;             PG8_WAIT_V(8); PG8_WAIT_L(0); PG8_BAR; PG8_MMA(1, 0, At, B0); PG8_MMA(1, 1, At, B1); PG8_BAR; PG8_SCHED;
;             PG8_LDB(B0, 1, 0); PG8_LDB(B1, 1, 1); PG8_SCHED; PG8_LDA(At, 1, 0); PG8_STAGE(PG8_SA(0, 1), a2 + hstep, voffA);
;             PG8_WAIT_V(8); PG8_WAIT_L(0); PG8_BAR; PG8_MMA(0, 0, At, B0); PG8_MMA(0, 1, At, B1); PG8_BAR; PG8_SCHED;
;             PG8_LDA(At, 1, 1); PG8_STAGE(PG8_SB(1, 0), b3, voffB); PG8_STAGE(PG8_SB(1, 1), b3 + hstep, voffB); PG8_STAGE(PG8_SA(1, 0), a3, voffA);
;             PG8_WAIT_V(8); PG8_WAIT_L(0); PG8_BAR; PG8_MMA(1, 0, At, B0); PG8_MMA(1, 1, At, B1); PG8_BAR; PG8_SCHED;
	s_add_i32 s3, s3, s14
	v_lshl_add_u64 v[202:203], v[202:203], 0, s[36:37]
	s_mov_b32 m0, s3
	ds_read_b128 v[186:189], v157 offset:49152
	ds_read_b128 v[190:193], v157 offset:50176
	ds_read_b128 v[194:197], v157 offset:51200
	ds_read_b128 v[198:201], v157 offset:52224
	ds_read_b128 v[208:211], v157 offset:53248
	ds_read_b128 v[212:215], v157 offset:54272
	ds_read_b128 v[216:219], v157 offset:55296
	ds_read_b128 v[220:223], v157 offset:56320
	global_load_lds_dwordx4 v[202:203], off
	s_add_i32 m0, s3, 0x2000
	s_add_u32 s56, s56, 0x40080
	v_lshl_add_u64 v[202:203], v[224:225], 0, s[36:37]
	s_addc_u32 s57, s57, 0
	s_add_i32 s3, s33, s14
	global_load_lds_dwordx4 v[202:203], off
	v_lshl_add_u64 v[202:203], s[56:57], 0, v[132:133]
	s_mov_b32 m0, s3
	s_nop 0
	global_load_lds_dwordx4 v[202:203], off
	v_lshl_add_u64 v[202:203], s[56:57], 0, v[128:129]
	s_add_i32 m0, s3, 0x2000
	s_nop 0
	global_load_lds_dwordx4 v[202:203], off
	s_waitcnt vmcnt(6)
	s_waitcnt lgkmcnt(0)
	s_barrier
	s_setprio 1
	s_waitcnt lgkmcnt(0)
	v_mfma_f32_16x16x32_bf16 v[60:63], v[144:147], v[186:189], v[60:63]
	v_mfma_f32_16x16x32_bf16 v[44:47], v[144:147], v[194:197], v[44:47]
	v_mfma_f32_16x16x32_bf16 v[56:59], v[160:163], v[186:189], v[56:59]
	v_mfma_f32_16x16x32_bf16 v[40:43], v[160:163], v[194:197], v[40:43]
	v_mfma_f32_16x16x32_bf16 v[28:31], v[144:147], v[208:211], v[28:31]
	v_mfma_f32_16x16x32_bf16 v[12:15], v[144:147], v[216:219], v[12:15]
	v_mfma_f32_16x16x32_bf16 v[24:27], v[160:163], v[208:211], v[24:27]
	v_mfma_f32_16x16x32_bf16 v[8:11], v[160:163], v[216:219], v[8:11]
	v_mfma_f32_16x16x32_bf16 v[60:63], v[148:151], v[190:193], v[60:63]
	v_mfma_f32_16x16x32_bf16 v[44:47], v[148:151], v[198:201], v[44:47]
	v_mfma_f32_16x16x32_bf16 v[56:59], v[164:167], v[190:193], v[56:59]
	v_mfma_f32_16x16x32_bf16 v[40:43], v[164:167], v[198:201], v[40:43]
	v_mfma_f32_16x16x32_bf16 v[28:31], v[148:151], v[212:215], v[28:31]
	v_mfma_f32_16x16x32_bf16 v[12:15], v[148:151], v[220:223], v[12:15]
	v_lshl_add_u64 v[202:203], v[226:227], 0, s[36:37]
	s_mov_b32 m0, s63
	s_nop 0
	global_load_lds_dwordx4 v[202:203], off
	v_mfma_f32_16x16x32_bf16 v[24:27], v[164:167], v[212:215], v[24:27]
	v_mfma_f32_16x16x32_bf16 v[8:11], v[164:167], v[220:223], v[8:11]
	s_setprio 0
	s_setprio 1
	v_mfma_f32_16x16x32_bf16 v[52:55], v[168:171], v[186:189], v[52:55]
	v_mfma_f32_16x16x32_bf16 v[36:39], v[168:171], v[194:197], v[36:39]
	v_mfma_f32_16x16x32_bf16 v[48:51], v[176:179], v[186:189], v[48:51]
	v_mfma_f32_16x16x32_bf16 v[32:35], v[176:179], v[194:197], v[32:35]
	v_mfma_f32_16x16x32_bf16 v[20:23], v[168:171], v[208:211], v[20:23]
	v_mfma_f32_16x16x32_bf16 v[4:7], v[168:171], v[216:219], v[4:7]
	v_mfma_f32_16x16x32_bf16 v[16:19], v[176:179], v[208:211], v[16:19]
	v_mfma_f32_16x16x32_bf16 v[0:3], v[176:179], v[216:219], v[0:3]
	v_mfma_f32_16x16x32_bf16 v[52:55], v[172:175], v[190:193], v[52:55]
	v_mfma_f32_16x16x32_bf16 v[36:39], v[172:175], v[198:201], v[36:39]
	v_mfma_f32_16x16x32_bf16 v[48:51], v[182:185], v[190:193], v[48:51]
	v_mfma_f32_16x16x32_bf16 v[32:35], v[182:185], v[198:201], v[32:35]
	v_mfma_f32_16x16x32_bf16 v[20:23], v[172:175], v[212:215], v[20:23]
	v_mfma_f32_16x16x32_bf16 v[4:7], v[172:175], v[220:223], v[4:7]
	v_lshl_add_u64 v[202:203], v[228:229], 0, s[36:37]
	s_mov_b32 m0, s64
	s_nop 0
	global_load_lds_dwordx4 v[202:203], off
	v_mfma_f32_16x16x32_bf16 v[16:19], v[182:185], v[212:215], v[16:19]
	v_mfma_f32_16x16x32_bf16 v[0:3], v[182:185], v[220:223], v[0:3]
	s_setprio 0
	s_barrier
	s_add_i32 s83, s83, 2
	s_add_u32 s54, s54, 0x100
	s_addc_u32 s55, s55, 0
	s_add_u32 s77, s77, 0x100
	s_addc_u32 s82, s82, 0
.LBB0_957:
	ds_read_b128 v[144:147], v155
	ds_read_b128 v[148:151], v155 offset:1024
	ds_read_b128 v[160:163], v155 offset:2048
	ds_read_b128 v[164:167], v155 offset:3072
	ds_read_b128 v[168:171], v156
	ds_read_b128 v[172:175], v156 offset:1024
	ds_read_b128 v[176:179], v156 offset:2048
	ds_read_b128 v[182:185], v156 offset:3072
	s_add_u32 s3, s54, 0xfffc0080
	s_addc_u32 s33, s55, -1
	s_cmp_eq_u32 s83, 12
	s_cselect_b32 s59, s45, s33
	s_cselect_b32 s58, s75, s3
	s_cselect_b32 s57, s43, s82
	s_cselect_b32 s56, s76, s77
	v_lshl_add_u64 v[202:203], s[54:55], 0, v[136:137]
	s_add_i32 m0, s34, 0xc000
	ds_read_b128 v[186:189], v157
	ds_read_b128 v[190:193], v157 offset:1024
	ds_read_b128 v[194:197], v157 offset:2048
	ds_read_b128 v[198:201], v157 offset:3072
	ds_read_b128 v[208:211], v157 offset:4096
	ds_read_b128 v[212:215], v157 offset:5120
	ds_read_b128 v[216:219], v157 offset:6144
	ds_read_b128 v[220:223], v157 offset:7168
	global_load_lds_dwordx4 v[202:203], off
	v_lshl_add_u64 v[202:203], s[54:55], 0, v[138:139]
	s_add_i32 m0, s34, 0xe000
	s_nop 0
	global_load_lds_dwordx4 v[202:203], off
	s_waitcnt vmcnt(8)
	s_waitcnt lgkmcnt(0)
	s_barrier
; #define PG8_STAGE(bufoff, gbase, voff) do { _Pragma("unroll") for (int _i = 0; _i < 2; ++_i) \
;         __builtin_amdgcn_global_load_lds((const unsigned*)((const char*)(gbase) + (voff)[_i]), (PG8_LAS unsigned*)(lds + (bufoff) + ldsw + _i * 8192), 16, 0, 0); } while (0)
; #define PG8_LDA(dst, b, h) do { _Pragma("unroll") for (int m = 0; m < 4; ++m) _Pragma("unroll") for (int k = 0; k < 2; ++k) dst[m][k] = *(const PG8_LAS bf16x8*)(lds + PG8_SA(b, h) + aoff + m * 2048 + k * 1024); } while (0)
; #define PG8_MMA(ai, bj, At, Bt) do { __builtin_amdgcn_s_setprio(1); _Pragma("unroll") for (int m = 0; m < 4; ++m) _Pragma("unroll") for (int n = 0; n < 2; ++n) _Pragma("unroll") for (int k = 0; k < 2; ++k) \
;         acc[ai][bj][m][n] = __builtin_amdgcn_mfma_f32_16x16x32_bf16(Bt[n][k], At[m][k], acc[ai][bj][m][n], 0, 0, 0); __builtin_amdgcn_s_setprio(0); } while (0)
; #define PG8_WAIT_V(n) asm volatile("s_waitcnt vmcnt(" #n ")" ::: "memory")
; #define PG8_WAIT_L(n) asm volatile("s_waitcnt lgkmcnt(" #n ")" ::: "memory")
; #define PG8_BAR __builtin_amdgcn_s_barrier()
; #define PG8_SCHED __builtin_amdgcn_sched_barrier(0)
; template <class Epi, class Sched, bool ALIGN_EPI = false, bool SP2 = false>
; __device__ __forceinline__ void gemm_phase(PG8_LAS unsigned char* lds, const Gemm g, const Sched& S, const Epi& E) {
;     ...
;             PG8_WAIT_V(8); PG8_WAIT_L(0); PG8_BAR; PG8_MMA(0, 0, At, B0); PG8_MMA(0, 1, At, B1); PG8_BAR; PG8_SCHED;
;             PG8_LDA(At, 0, 1); PG8_STAGE(PG8_SB(0, 0), b2, voffB); PG8_STAGE(PG8_SB(0, 1), b2 + hstep, voffB); PG8_STAGE(PG8_SA(0, 0), a2, voffA);
;             PG8_WAIT_V(8); PG8_WAIT_L(0); PG8_BAR; PG8_MMA(1, 0, At, B0); PG8_MMA(1, 1, At, B1); PG8_BAR; PG8_SCHED;
	s_setprio 1
	s_waitcnt lgkmcnt(0)
	v_mfma_f32_16x16x32_bf16 v[124:127], v[144:147], v[186:189], v[124:127]
	v_mfma_f32_16x16x32_bf16 v[108:111], v[144:147], v[194:197], v[108:111]
	v_mfma_f32_16x16x32_bf16 v[120:123], v[160:163], v[186:189], v[120:123]
	v_mfma_f32_16x16x32_bf16 v[104:107], v[160:163], v[194:197], v[104:107]
	v_mfma_f32_16x16x32_bf16 v[92:95], v[144:147], v[208:211], v[92:95]
	v_mfma_f32_16x16x32_bf16 v[76:79], v[144:147], v[216:219], v[76:79]
	v_mfma_f32_16x16x32_bf16 v[88:91], v[160:163], v[208:211], v[88:91]
	v_mfma_f32_16x16x32_bf16 v[72:75], v[160:163], v[216:219], v[72:75]
	v_mfma_f32_16x16x32_bf16 v[124:127], v[148:151], v[190:193], v[124:127]
	v_mfma_f32_16x16x32_bf16 v[108:111], v[148:151], v[198:201], v[108:111]
	v_mfma_f32_16x16x32_bf16 v[120:123], v[164:167], v[190:193], v[120:123]
	v_mfma_f32_16x16x32_bf16 v[104:107], v[164:167], v[198:201], v[104:107]
	v_mfma_f32_16x16x32_bf16 v[92:95], v[148:151], v[212:215], v[92:95]
	v_mfma_f32_16x16x32_bf16 v[76:79], v[148:151], v[220:223], v[76:79]
	v_mfma_f32_16x16x32_bf16 v[88:91], v[164:167], v[212:215], v[88:91]
	v_mfma_f32_16x16x32_bf16 v[72:75], v[164:167], v[220:223], v[72:75]
	s_setprio 0
	s_setprio 1
	v_mfma_f32_16x16x32_bf16 v[116:119], v[168:171], v[186:189], v[116:119]
	v_mfma_f32_16x16x32_bf16 v[100:103], v[168:171], v[194:197], v[100:103]
	v_mfma_f32_16x16x32_bf16 v[112:115], v[176:179], v[186:189], v[112:115]
	v_mfma_f32_16x16x32_bf16 v[96:99], v[176:179], v[194:197], v[96:99]
	v_mfma_f32_16x16x32_bf16 v[84:87], v[168:171], v[208:211], v[84:87]
	v_mfma_f32_16x16x32_bf16 v[68:71], v[168:171], v[216:219], v[68:71]
	v_mfma_f32_16x16x32_bf16 v[80:83], v[176:179], v[208:211], v[80:83]
	v_mfma_f32_16x16x32_bf16 v[64:67], v[176:179], v[216:219], v[64:67]
	v_mfma_f32_16x16x32_bf16 v[116:119], v[172:175], v[190:193], v[116:119]
	v_mfma_f32_16x16x32_bf16 v[100:103], v[172:175], v[198:201], v[100:103]
	v_mfma_f32_16x16x32_bf16 v[112:115], v[182:185], v[190:193], v[112:115]
	v_mfma_f32_16x16x32_bf16 v[96:99], v[182:185], v[198:201], v[96:99]
	v_mfma_f32_16x16x32_bf16 v[84:87], v[172:175], v[212:215], v[84:87]
	v_mfma_f32_16x16x32_bf16 v[68:71], v[172:175], v[220:223], v[68:71]
	v_mfma_f32_16x16x32_bf16 v[80:83], v[182:185], v[212:215], v[80:83]
	v_mfma_f32_16x16x32_bf16 v[64:67], v[182:185], v[220:223], v[64:67]
	s_setprio 0
	s_barrier
	s_add_i32 s3, s65, s14
	v_lshl_add_u64 v[202:203], s[56:57], 0, v[132:133]
	s_mov_b32 m0, s3
	ds_read_b128 v[186:189], v157 offset:16384
	ds_read_b128 v[190:193], v157 offset:17408
	ds_read_b128 v[194:197], v157 offset:18432
	ds_read_b128 v[198:201], v157 offset:19456
	ds_read_b128 v[208:211], v157 offset:20480
	ds_read_b128 v[212:215], v157 offset:21504
	ds_read_b128 v[216:219], v157 offset:22528
	ds_read_b128 v[220:223], v157 offset:23552
	global_load_lds_dwordx4 v[202:203], off
	s_add_i32 m0, s3, 0x2000
	s_add_u32 s78, s56, 0x40000
	v_lshl_add_u64 v[224:225], s[56:57], 0, v[128:129]
	s_addc_u32 s79, s57, 0
	s_add_i32 s3, s66, s14
	global_load_lds_dwordx4 v[224:225], off
	v_lshl_add_u64 v[226:227], s[78:79], 0, v[132:133]
	s_mov_b32 m0, s3
	global_load_lds_dwordx4 v[226:227], off
	v_lshl_add_u64 v[226:227], s[78:79], 0, v[128:129]
	s_add_i32 m0, s3, 0x2000
	s_nop 0
	global_load_lds_dwordx4 v[226:227], off
	s_waitcnt vmcnt(6)
	s_waitcnt lgkmcnt(0)
	s_barrier
	s_setprio 1
	s_waitcnt lgkmcnt(0)
	v_mfma_f32_16x16x32_bf16 v[60:63], v[144:147], v[186:189], v[60:63]
	v_mfma_f32_16x16x32_bf16 v[44:47], v[144:147], v[194:197], v[44:47]
	v_mfma_f32_16x16x32_bf16 v[56:59], v[160:163], v[186:189], v[56:59]
	v_mfma_f32_16x16x32_bf16 v[40:43], v[160:163], v[194:197], v[40:43]
	v_mfma_f32_16x16x32_bf16 v[28:31], v[144:147], v[208:211], v[28:31]
	v_mfma_f32_16x16x32_bf16 v[12:15], v[144:147], v[216:219], v[12:15]
	v_mfma_f32_16x16x32_bf16 v[24:27], v[160:163], v[208:211], v[24:27]
	v_mfma_f32_16x16x32_bf16 v[8:11], v[160:163], v[216:219], v[8:11]
	v_mfma_f32_16x16x32_bf16 v[60:63], v[148:151], v[190:193], v[60:63]
	v_mfma_f32_16x16x32_bf16 v[44:47], v[148:151], v[198:201], v[44:47]
	v_mfma_f32_16x16x32_bf16 v[56:59], v[164:167], v[190:193], v[56:59]
	v_mfma_f32_16x16x32_bf16 v[40:43], v[164:167], v[198:201], v[40:43]
	v_mfma_f32_16x16x32_bf16 v[28:31], v[148:151], v[212:215], v[28:31]
	v_mfma_f32_16x16x32_bf16 v[12:15], v[148:151], v[220:223], v[12:15]
	v_lshl_add_u64 v[226:227], s[58:59], 0, v[134:135]
	s_mov_b32 m0, s34
	s_nop 0
	global_load_lds_dwordx4 v[226:227], off
	v_mfma_f32_16x16x32_bf16 v[24:27], v[164:167], v[212:215], v[24:27]
	v_mfma_f32_16x16x32_bf16 v[8:11], v[164:167], v[220:223], v[8:11]
	s_setprio 0
	s_setprio 1
	v_mfma_f32_16x16x32_bf16 v[52:55], v[168:171], v[186:189], v[52:55]
	v_mfma_f32_16x16x32_bf16 v[36:39], v[168:171], v[194:197], v[36:39]
	v_mfma_f32_16x16x32_bf16 v[48:51], v[176:179], v[186:189], v[48:51]
	v_mfma_f32_16x16x32_bf16 v[32:35], v[176:179], v[194:197], v[32:35]
	v_mfma_f32_16x16x32_bf16 v[20:23], v[168:171], v[208:211], v[20:23]
	v_mfma_f32_16x16x32_bf16 v[4:7], v[168:171], v[216:219], v[4:7]
	v_mfma_f32_16x16x32_bf16 v[16:19], v[176:179], v[208:211], v[16:19]
	v_mfma_f32_16x16x32_bf16 v[0:3], v[176:179], v[216:219], v[0:3]
	v_mfma_f32_16x16x32_bf16 v[52:55], v[172:175], v[190:193], v[52:55]
	v_mfma_f32_16x16x32_bf16 v[36:39], v[172:175], v[198:201], v[36:39]
	v_mfma_f32_16x16x32_bf16 v[48:51], v[182:185], v[190:193], v[48:51]
	v_mfma_f32_16x16x32_bf16 v[32:35], v[182:185], v[198:201], v[32:35]
	v_mfma_f32_16x16x32_bf16 v[20:23], v[172:175], v[212:215], v[20:23]
	v_mfma_f32_16x16x32_bf16 v[4:7], v[172:175], v[220:223], v[4:7]
	v_lshl_add_u64 v[228:229], s[58:59], 0, v[130:131]
	s_mov_b32 m0, s53
	s_nop 0
	global_load_lds_dwordx4 v[228:229], off
	v_mfma_f32_16x16x32_bf16 v[16:19], v[182:185], v[212:215], v[16:19]
	v_mfma_f32_16x16x32_bf16 v[0:3], v[182:185], v[220:223], v[0:3]
	s_setprio 0
	s_barrier
; #define PG8_STAGE(bufoff, gbase, voff) do { _Pragma("unroll") for (int _i = 0; _i < 2; ++_i) \
;         __builtin_amdgcn_global_load_lds((const unsigned*)((const char*)(gbase) + (voff)[_i]), (PG8_LAS unsigned*)(lds + (bufoff) + ldsw + _i * 8192), 16, 0, 0); } while (0)
; #define PG8_LDA(dst, b, h) do { _Pragma("unroll") for (int m = 0; m < 4; ++m) _Pragma("unroll") for (int k = 0; k < 2; ++k) dst[m][k] = *(const PG8_LAS bf16x8*)(lds + PG8_SA(b, h) + aoff + m * 2048 + k * 1024); } while (0)
; #define PG8_LDB(dst, b, h) do { _Pragma("unroll") for (int n = 0; n < 2; ++n) _Pragma("unroll") for (int k = 0; k < 2; ++k) dst[n][k] = *(const PG8_LAS bf16x8*)(lds + PG8_SB(b, h) + boff + n * 2048 + k * 1024); } while (0)
; #define PG8_MMA(ai, bj, At, Bt) do { __builtin_amdgcn_s_setprio(1); _Pragma("unroll") for (int m = 0; m < 4; ++m) _Pragma("unroll") for (int n = 0; n < 2; ++n) _Pragma("unroll") for (int k = 0; k < 2; ++k) \
;         acc[ai][bj][m][n] = __builtin_amdgcn_mfma_f32_16x16x32_bf16(Bt[n][k], At[m][k], acc[ai][bj][m][n], 0, 0, 0); __builtin_amdgcn_s_setprio(0); } while (0)
; #define PG8_WAIT_V(n) asm volatile("s_waitcnt vmcnt(" #n ")" ::: "memory")
; #define PG8_WAIT_L(n) asm volatile("s_waitcnt lgkmcnt(" #n ")" ::: "memory")
; #define PG8_BAR __builtin_amdgcn_s_barrier()
; #define PG8_SCHED __builtin_amdgcn_sched_barrier(0)
; template <class Epi, class Sched, bool ALIGN_EPI = false, bool SP2 = false>
; __device__ __forceinline__ void gemm_phase(PG8_LAS unsigned char* lds, const Gemm g, const Sched& S, const Epi& E) {
;     ...
;             PG8_LDB(B0, 1, 0); PG8_LDB(B1, 1, 1); PG8_SCHED; PG8_LDA(At, 1, 0); PG8_STAGE(PG8_SA(0, 1), a2 + hstep, voffA);
;             PG8_WAIT_V(8); PG8_WAIT_L(0); PG8_BAR; PG8_MMA(0, 0, At, B0); PG8_MMA(0, 1, At, B1); PG8_BAR; PG8_SCHED;
	s_add_i32 s3, 0, 0x18000
	v_add_u32_e32 v159, s3, v153
	s_add_i32 s33, 0, 0x1c000
	ds_read_b128 v[144:147], v159
	ds_read_b128 v[148:151], v159 offset:1024
	ds_read_b128 v[160:163], v159 offset:2048
	ds_read_b128 v[164:167], v159 offset:3072
	v_add_u32_e32 v159, s33, v153
	ds_read_b128 v[168:171], v159
	ds_read_b128 v[172:175], v159 offset:1024
	ds_read_b128 v[176:179], v159 offset:2048
	ds_read_b128 v[182:185], v159 offset:3072
	s_add_u32 s58, s58, 0x40000
	s_addc_u32 s59, s59, 0
	s_mov_b32 m0, s60
	v_lshl_add_u64 v[230:231], s[58:59], 0, v[134:135]
	ds_read_b128 v[186:189], v157 offset:32768
	ds_read_b128 v[190:193], v157 offset:33792
	ds_read_b128 v[194:197], v157 offset:34816
	ds_read_b128 v[198:201], v157 offset:35840
	ds_read_b128 v[208:211], v157 offset:36864
	ds_read_b128 v[212:215], v157 offset:37888
	ds_read_b128 v[216:219], v157 offset:38912
	ds_read_b128 v[220:223], v157 offset:39936
	global_load_lds_dwordx4 v[230:231], off
	v_lshl_add_u64 v[230:231], s[58:59], 0, v[130:131]
	s_mov_b32 m0, s61
	s_nop 0
	global_load_lds_dwordx4 v[230:231], off
	s_waitcnt vmcnt(8)
	s_waitcnt lgkmcnt(0)
	s_barrier
	s_setprio 1
	s_waitcnt lgkmcnt(0)
	v_mfma_f32_16x16x32_bf16 v[124:127], v[144:147], v[186:189], v[124:127]
	v_mfma_f32_16x16x32_bf16 v[108:111], v[144:147], v[194:197], v[108:111]
	v_mfma_f32_16x16x32_bf16 v[120:123], v[160:163], v[186:189], v[120:123]
	v_mfma_f32_16x16x32_bf16 v[104:107], v[160:163], v[194:197], v[104:107]
	v_mfma_f32_16x16x32_bf16 v[92:95], v[144:147], v[208:211], v[92:95]
	v_mfma_f32_16x16x32_bf16 v[76:79], v[144:147], v[216:219], v[76:79]
	v_mfma_f32_16x16x32_bf16 v[88:91], v[160:163], v[208:211], v[88:91]
	v_mfma_f32_16x16x32_bf16 v[72:75], v[160:163], v[216:219], v[72:75]
	v_mfma_f32_16x16x32_bf16 v[124:127], v[148:151], v[190:193], v[124:127]
	v_mfma_f32_16x16x32_bf16 v[108:111], v[148:151], v[198:201], v[108:111]
	v_mfma_f32_16x16x32_bf16 v[120:123], v[164:167], v[190:193], v[120:123]
	v_mfma_f32_16x16x32_bf16 v[104:107], v[164:167], v[198:201], v[104:107]
	v_mfma_f32_16x16x32_bf16 v[92:95], v[148:151], v[212:215], v[92:95]
	v_mfma_f32_16x16x32_bf16 v[76:79], v[148:151], v[220:223], v[76:79]
	v_mfma_f32_16x16x32_bf16 v[88:91], v[164:167], v[212:215], v[88:91]
	v_mfma_f32_16x16x32_bf16 v[72:75], v[164:167], v[220:223], v[72:75]
	s_setprio 0
	s_setprio 1
	v_mfma_f32_16x16x32_bf16 v[116:119], v[168:171], v[186:189], v[116:119]
	v_mfma_f32_16x16x32_bf16 v[100:103], v[168:171], v[194:197], v[100:103]
	v_mfma_f32_16x16x32_bf16 v[112:115], v[176:179], v[186:189], v[112:115]
	v_mfma_f32_16x16x32_bf16 v[96:99], v[176:179], v[194:197], v[96:99]
	v_mfma_f32_16x16x32_bf16 v[84:87], v[168:171], v[208:211], v[84:87]
	v_mfma_f32_16x16x32_bf16 v[68:71], v[168:171], v[216:219], v[68:71]
	v_mfma_f32_16x16x32_bf16 v[80:83], v[176:179], v[208:211], v[80:83]
	v_mfma_f32_16x16x32_bf16 v[64:67], v[176:179], v[216:219], v[64:67]
	v_mfma_f32_16x16x32_bf16 v[116:119], v[172:175], v[190:193], v[116:119]
	v_mfma_f32_16x16x32_bf16 v[100:103], v[172:175], v[198:201], v[100:103]
	v_mfma_f32_16x16x32_bf16 v[112:115], v[182:185], v[190:193], v[112:115]
	v_mfma_f32_16x16x32_bf16 v[96:99], v[182:185], v[198:201], v[96:99]
	v_mfma_f32_16x16x32_bf16 v[84:87], v[172:175], v[212:215], v[84:87]
	v_mfma_f32_16x16x32_bf16 v[68:71], v[172:175], v[220:223], v[68:71]
	v_mfma_f32_16x16x32_bf16 v[80:83], v[182:185], v[212:215], v[80:83]
	v_mfma_f32_16x16x32_bf16 v[64:67], v[182:185], v[220:223], v[64:67]
	s_setprio 0
	s_barrier
; #define PG8_STAGE(bufoff, gbase, voff) do { _Pragma("unroll") for (int _i = 0; _i < 2; ++_i) \
;         __builtin_amdgcn_global_load_lds((const unsigned*)((const char*)(gbase) + (voff)[_i]), (PG8_LAS unsigned*)(lds + (bufoff) + ldsw + _i * 8192), 16, 0, 0); } while (0)
; #define PG8_LDA(dst, b, h) do { _Pragma("unroll") for (int m = 0; m < 4; ++m) _Pragma("unroll") for (int k = 0; k < 2; ++k) dst[m][k] = *(const PG8_LAS bf16x8*)(lds + PG8_SA(b, h) + aoff + m * 2048 + k * 1024); } while (0)
; #define PG8_MMA(ai, bj, At, Bt) do { __builtin_amdgcn_s_setprio(1); _Pragma("unroll") for (int m = 0; m < 4; ++m) _Pragma("unroll") for (int n = 0; n < 2; ++n) _Pragma("unroll") for (int k = 0; k < 2; ++k) \
;         acc[ai][bj][m][n] = __builtin_amdgcn_mfma_f32_16x16x32_bf16(Bt[n][k], At[m][k], acc[ai][bj][m][n], 0, 0, 0); __builtin_amdgcn_s_setprio(0); } while (0)
; #define PG8_WAIT_V(n) asm volatile("s_waitcnt vmcnt(" #n ")" ::: "memory")
; #define PG8_WAIT_L(n) asm volatile("s_waitcnt lgkmcnt(" #n ")" ::: "memory")
; #define PG8_BAR __builtin_amdgcn_s_barrier()
; #define PG8_SCHED __builtin_amdgcn_sched_barrier(0)
; __device__ __forceinline__ float row_rs(const float* ssp, int row) { const unsigned long long v = ((const unsigned long long*)ssp)[row];
;     return __builtin_amdgcn_rsqf((float)v * (1.0f / 4294967296.0f) * (1.0f / 1024.0f) + RMS_EPS); }
; template <class Epi, class Sched, bool ALIGN_EPI = false, bool SP2 = false>
; __device__ __forceinline__ void gemm_phase(PG8_LAS unsigned char* lds, const Gemm g, const Sched& S, const Epi& E) {
;     ...
;             PG8_LDA(At, 1, 1); PG8_STAGE(PG8_SB(1, 0), b3, voffB); PG8_STAGE(PG8_SB(1, 1), b3 + hstep, voffB); PG8_STAGE(PG8_SA(1, 0), a3, voffA);
;             PG8_WAIT_V(8); PG8_WAIT_L(0); PG8_BAR; PG8_MMA(1, 0, At, B0); PG8_MMA(1, 1, At, B1); PG8_BAR; PG8_SCHED;
	s_add_i32 s3, s3, s14
	v_lshl_add_u64 v[202:203], v[202:203], 0, s[36:37]
	s_mov_b32 m0, s3
	ds_read_b128 v[186:189], v157 offset:49152
	ds_read_b128 v[190:193], v157 offset:50176
	ds_read_b128 v[194:197], v157 offset:51200
	ds_read_b128 v[198:201], v157 offset:52224
	ds_read_b128 v[208:211], v157 offset:53248
	ds_read_b128 v[212:215], v157 offset:54272
	ds_read_b128 v[216:219], v157 offset:55296
	ds_read_b128 v[220:223], v157 offset:56320
	global_load_lds_dwordx4 v[202:203], off
	s_add_i32 m0, s3, 0x2000
	s_add_u32 s56, s56, 0x40080
	v_lshl_add_u64 v[202:203], v[224:225], 0, s[36:37]
	s_addc_u32 s57, s57, 0
	s_add_i32 s3, s33, s14
	global_load_lds_dwordx4 v[202:203], off
	v_lshl_add_u64 v[202:203], s[56:57], 0, v[132:133]
	s_mov_b32 m0, s3
	s_nop 0
	global_load_lds_dwordx4 v[202:203], off
	v_lshl_add_u64 v[202:203], s[56:57], 0, v[128:129]
	s_add_i32 m0, s3, 0x2000
	s_nop 0
	global_load_lds_dwordx4 v[202:203], off
	s_waitcnt vmcnt(6)
	s_waitcnt lgkmcnt(0)
	s_barrier
	s_setprio 1
	s_waitcnt lgkmcnt(0)
	v_mfma_f32_16x16x32_bf16 v[60:63], v[144:147], v[186:189], v[60:63]
	v_mfma_f32_16x16x32_bf16 v[44:47], v[144:147], v[194:197], v[44:47]
	v_mfma_f32_16x16x32_bf16 v[56:59], v[160:163], v[186:189], v[56:59]
	v_mfma_f32_16x16x32_bf16 v[40:43], v[160:163], v[194:197], v[40:43]
	v_mfma_f32_16x16x32_bf16 v[28:31], v[144:147], v[208:211], v[28:31]
	v_mfma_f32_16x16x32_bf16 v[12:15], v[144:147], v[216:219], v[12:15]
	v_mfma_f32_16x16x32_bf16 v[24:27], v[160:163], v[208:211], v[24:27]
	v_mfma_f32_16x16x32_bf16 v[8:11], v[160:163], v[216:219], v[8:11]
	v_mfma_f32_16x16x32_bf16 v[60:63], v[148:151], v[190:193], v[60:63]
	v_mfma_f32_16x16x32_bf16 v[44:47], v[148:151], v[198:201], v[44:47]
	v_mfma_f32_16x16x32_bf16 v[56:59], v[164:167], v[190:193], v[56:59]
	v_mfma_f32_16x16x32_bf16 v[40:43], v[164:167], v[198:201], v[40:43]
	v_mfma_f32_16x16x32_bf16 v[28:31], v[148:151], v[212:215], v[28:31]
	v_mfma_f32_16x16x32_bf16 v[12:15], v[148:151], v[220:223], v[12:15]
	v_lshl_add_u64 v[202:203], v[226:227], 0, s[36:37]
	s_mov_b32 m0, s63
	s_nop 0
	global_load_lds_dwordx4 v[202:203], off
	v_mfma_f32_16x16x32_bf16 v[24:27], v[164:167], v[212:215], v[24:27]
	v_mfma_f32_16x16x32_bf16 v[8:11], v[164:167], v[220:223], v[8:11]
	s_setprio 0
	s_setprio 1
	v_mfma_f32_16x16x32_bf16 v[52:55], v[168:171], v[186:189], v[52:55]
	v_mfma_f32_16x16x32_bf16 v[36:39], v[168:171], v[194:197], v[36:39]
	v_mfma_f32_16x16x32_bf16 v[48:51], v[176:179], v[186:189], v[48:51]
	v_mfma_f32_16x16x32_bf16 v[32:35], v[176:179], v[194:197], v[32:35]
	v_mfma_f32_16x16x32_bf16 v[20:23], v[168:171], v[208:211], v[20:23]
	v_mfma_f32_16x16x32_bf16 v[4:7], v[168:171], v[216:219], v[4:7]
	v_mfma_f32_16x16x32_bf16 v[16:19], v[176:179], v[208:211], v[16:19]
	v_mfma_f32_16x16x32_bf16 v[0:3], v[176:179], v[216:219], v[0:3]
	v_mfma_f32_16x16x32_bf16 v[52:55], v[172:175], v[190:193], v[52:55]
	v_mfma_f32_16x16x32_bf16 v[36:39], v[172:175], v[198:201], v[36:39]
	v_mfma_f32_16x16x32_bf16 v[48:51], v[182:185], v[190:193], v[48:51]
	v_mfma_f32_16x16x32_bf16 v[32:35], v[182:185], v[198:201], v[32:35]
	v_mfma_f32_16x16x32_bf16 v[20:23], v[172:175], v[212:215], v[20:23]
	v_mfma_f32_16x16x32_bf16 v[4:7], v[172:175], v[220:223], v[4:7]
	v_lshl_add_u64 v[202:203], v[228:229], 0, s[36:37]
	s_mov_b32 m0, s64
	s_nop 0
	global_load_lds_dwordx4 v[202:203], off
	v_mfma_f32_16x16x32_bf16 v[16:19], v[182:185], v[212:215], v[16:19]
	v_mfma_f32_16x16x32_bf16 v[0:3], v[182:185], v[220:223], v[0:3]
	s_setprio 0
	s_barrier
	s_add_i32 s83, s83, 2
	s_add_u32 s54, s54, 0x100
	s_addc_u32 s55, s55, 0
	s_add_u32 s77, s77, 0x100
	s_addc_u32 s82, s82, 0
	s_cmp_gt_u32 s83, 13
	s_cbranch_scc0 .LBB0_957
	v_lshl_add_u32 v144, s52, 8, v152
	v_ashrrev_i32_e32 v145, 31, v144
	v_lshl_add_u64 v[150:151], v[144:145], 3, s[0:1]
	global_load_dwordx2 v[182:183], v[150:151], off
	global_load_dwordx2 v[184:185], v[150:151], off offset:128
	global_load_dwordx2 v[186:187], v[150:151], off offset:256
	global_load_dwordx2 v[188:189], v[150:151], off offset:384
	global_load_dwordx2 v[190:191], v[150:151], off offset:1024
	global_load_dwordx2 v[192:193], v[150:151], off offset:1152
	global_load_dwordx2 v[194:195], v[150:151], off offset:1280
	global_load_dwordx2 v[196:197], v[150:151], off offset:1408
	s_and_b64 vcc, exec, s[38:39]
	s_cbranch_vccz .LBB0_960
	s_barrier

; #define PG8_STAGE(bufoff, gbase, voff) do { _Pragma("unroll") for (int _i = 0; _i < 2; ++_i) \
;         __builtin_amdgcn_global_load_lds((const unsigned*)((const char*)(gbase) + (voff)[_i]), (PG8_LAS unsigned*)(lds + (bufoff) + ldsw + _i * 8192), 16, 0, 0); } while (0)
; #define PG8_LDA(dst, b, h) do { _Pragma("unroll") for (int m = 0; m < 4; ++m) _Pragma("unroll") for (int k = 0; k < 2; ++k) dst[m][k] = *(const PG8_LAS bf16x8*)(lds + PG8_SA(b, h) + aoff + m * 2048 + k * 1024); } while (0)
; #define PG8_LDB(dst, b, h) do { _Pragma("unroll") for (int n = 0; n < 2; ++n) _Pragma("unroll") for (int k = 0; k < 2; ++k) dst[n][k] = *(const PG8_LAS bf16x8*)(lds + PG8_SB(b, h) + boff + n * 2048 + k * 1024); } while (0)
; #define PG8_MMA(ai, bj, At, Bt) do { __builtin_amdgcn_s_setprio(1); _Pragma("unroll") for (int m = 0; m < 4; ++m) _Pragma("unroll") for (int n = 0; n < 2; ++n) _Pragma("unroll") for (int k = 0; k < 2; ++k) \
;         acc[ai][bj][m][n] = __builtin_amdgcn_mfma_f32_16x16x32_bf16(Bt[n][k], At[m][k], acc[ai][bj][m][n], 0, 0, 0); __builtin_amdgcn_s_setprio(0); } while (0)
; #define PG8_WAIT_V(n) asm volatile("s_waitcnt vmcnt(" #n ")" ::: "memory")
; #define PG8_BAR __builtin_amdgcn_s_barrier()
; template <class Epi, class Sched, bool ALIGN_EPI = false, bool SP2 = false>
; __device__ __forceinline__ void gemm_phase(PG8_LAS unsigned char* lds, const Gemm g, const Sched& S, const Epi& E) {
;     ...
;         for (int t = 0; t < nt; t += 2) {
;             const bool last = (t == nt - 2);
;             const char* a1 = cA + (size_t)(t + 1) * kstep;
;             const char* a2 = last ? nA : cA + (size_t)(t + 2) * kstep; const char* b2 = last ? nB : cB + (size_t)(t + 2) * kstep;
;             const char* a3 = a2 + kstep; const char* b3 = b2 + kstep;
;             if (last && has_next) S.a_ready(nxt);
;             if constexpr (SP2) {
;             PG8_LDB(B0, 0, 0); PG8_LDB(B1, 0, 1); PG8_SCHED; PG8_LDA(At, 0, 0); PG8_STAGE(PG8_SA(1, 1), a1 + hstep, voffA);
;             PG8_WAIT_V(8); PG8_WAIT_L(0); PG8_BAR; PG8_MMA(0, 0, At, B0); PG8_MMA(0, 1, At, B1); PG8_BAR; PG8_SCHED;
;             PG8_LDA(At, 0, 1); PG8_STAGE(PG8_SB(0, 0), b2, voffB); PG8_STAGE(PG8_SB(0, 1), b2 + hstep, voffB); PG8_STAGE(PG8_SA(0, 0), a2, voffA);
;             PG8_WAIT_V(8); PG8_WAIT_L(0); PG8_BAR; PG8_MMA(1, 0, At, B0); PG8_MMA(1, 1, At, B1); PG8_BAR; PG8_SCHED;
.LBB0_1034:
	s_add_u32 s75, s52, 0x100
	s_addc_u32 s76, s53, 0
	s_mov_b32 s77, -2
	s_waitcnt lgkmcnt(0)
	ds_read_b128 v[144:147], v151
	ds_read_b128 v[156:159], v151 offset:1024
	ds_read_b128 v[160:163], v151 offset:2048
	ds_read_b128 v[164:167], v151 offset:3072
	ds_read_b128 v[168:171], v152
	ds_read_b128 v[172:175], v152 offset:1024
	ds_read_b128 v[176:179], v152 offset:2048
	ds_read_b128 v[182:185], v152 offset:3072
	s_add_u32 s52, s50, 0x100
	s_addc_u32 s53, s51, 0
	s_cmp_eq_u32 s77, 40
	s_cselect_b32 s57, s1, s53
	s_cselect_b32 s56, s0, s52
	s_cselect_b32 s55, s49, s76
	s_cselect_b32 s54, s48, s75
	v_lshl_add_u64 v[202:203], s[50:51], 0, v[136:137]
	s_add_i32 m0, s14, 0xc000
	ds_read_b128 v[186:189], v153
	ds_read_b128 v[190:193], v153 offset:1024
	ds_read_b128 v[194:197], v153 offset:2048
	ds_read_b128 v[198:201], v153 offset:3072
	ds_read_b128 v[208:211], v153 offset:4096
	ds_read_b128 v[212:215], v153 offset:5120
	ds_read_b128 v[216:219], v153 offset:6144
	ds_read_b128 v[220:223], v153 offset:7168
	global_load_lds_dwordx4 v[202:203], off
	v_lshl_add_u64 v[202:203], s[50:51], 0, v[138:139]
	s_add_i32 m0, s14, 0xe000
	s_nop 0
	global_load_lds_dwordx4 v[202:203], off
	s_waitcnt vmcnt(8)
	s_waitcnt lgkmcnt(0)
	s_barrier
	s_setprio 1
	s_waitcnt lgkmcnt(0)
	v_mfma_f32_16x16x32_bf16 v[124:127], v[144:147], v[186:189], 0
	v_mfma_f32_16x16x32_bf16 v[108:111], v[144:147], v[194:197], 0
	v_mfma_f32_16x16x32_bf16 v[120:123], v[160:163], v[186:189], 0
	v_mfma_f32_16x16x32_bf16 v[104:107], v[160:163], v[194:197], 0
	v_mfma_f32_16x16x32_bf16 v[92:95], v[144:147], v[208:211], 0
	v_mfma_f32_16x16x32_bf16 v[76:79], v[144:147], v[216:219], 0
	v_mfma_f32_16x16x32_bf16 v[88:91], v[160:163], v[208:211], 0
	v_mfma_f32_16x16x32_bf16 v[72:75], v[160:163], v[216:219], 0
	v_mfma_f32_16x16x32_bf16 v[124:127], v[156:159], v[190:193], v[124:127]
	v_mfma_f32_16x16x32_bf16 v[108:111], v[156:159], v[198:201], v[108:111]
	v_mfma_f32_16x16x32_bf16 v[120:123], v[164:167], v[190:193], v[120:123]
	v_mfma_f32_16x16x32_bf16 v[104:107], v[164:167], v[198:201], v[104:107]
	v_mfma_f32_16x16x32_bf16 v[92:95], v[156:159], v[212:215], v[92:95]
	v_mfma_f32_16x16x32_bf16 v[76:79], v[156:159], v[220:223], v[76:79]
	v_mfma_f32_16x16x32_bf16 v[88:91], v[164:167], v[212:215], v[88:91]
	v_mfma_f32_16x16x32_bf16 v[72:75], v[164:167], v[220:223], v[72:75]
	s_setprio 0
	s_setprio 1
	v_mfma_f32_16x16x32_bf16 v[116:119], v[168:171], v[186:189], 0
	v_mfma_f32_16x16x32_bf16 v[100:103], v[168:171], v[194:197], 0
	v_mfma_f32_16x16x32_bf16 v[112:115], v[176:179], v[186:189], 0
	v_mfma_f32_16x16x32_bf16 v[96:99], v[176:179], v[194:197], 0
	v_mfma_f32_16x16x32_bf16 v[84:87], v[168:171], v[208:211], 0
	v_mfma_f32_16x16x32_bf16 v[68:71], v[168:171], v[216:219], 0
	v_mfma_f32_16x16x32_bf16 v[80:83], v[176:179], v[208:211], 0
	v_mfma_f32_16x16x32_bf16 v[64:67], v[176:179], v[216:219], 0
	v_mfma_f32_16x16x32_bf16 v[116:119], v[172:175], v[190:193], v[116:119]
	v_mfma_f32_16x16x32_bf16 v[100:103], v[172:175], v[198:201], v[100:103]
	v_mfma_f32_16x16x32_bf16 v[112:115], v[182:185], v[190:193], v[112:115]
	v_mfma_f32_16x16x32_bf16 v[96:99], v[182:185], v[198:201], v[96:99]
	v_mfma_f32_16x16x32_bf16 v[84:87], v[172:175], v[212:215], v[84:87]
	v_mfma_f32_16x16x32_bf16 v[68:71], v[172:175], v[220:223], v[68:71]
	v_mfma_f32_16x16x32_bf16 v[80:83], v[182:185], v[212:215], v[80:83]
	v_mfma_f32_16x16x32_bf16 v[64:67], v[182:185], v[220:223], v[64:67]
	s_setprio 0
	s_barrier
	s_add_i32 s50, s61, s3
	v_lshl_add_u64 v[202:203], s[54:55], 0, v[130:131]
	s_mov_b32 m0, s50
	ds_read_b128 v[186:189], v153 offset:16384
	ds_read_b128 v[190:193], v153 offset:17408
	ds_read_b128 v[194:197], v153 offset:18432
	ds_read_b128 v[198:201], v153 offset:19456
	ds_read_b128 v[208:211], v153 offset:20480
	ds_read_b128 v[212:215], v153 offset:21504
	ds_read_b128 v[216:219], v153 offset:22528
	ds_read_b128 v[220:223], v153 offset:23552
	global_load_lds_dwordx4 v[202:203], off
	s_add_i32 m0, s50, 0x2000
	s_add_u32 s50, s54, 0xb0000
	v_lshl_add_u64 v[224:225], s[54:55], 0, v[134:135]
	s_addc_u32 s51, s55, 0
	s_add_i32 s78, s62, s3
	global_load_lds_dwordx4 v[224:225], off
	v_lshl_add_u64 v[226:227], s[50:51], 0, v[130:131]
	s_mov_b32 m0, s78
	global_load_lds_dwordx4 v[226:227], off
	v_lshl_add_u64 v[226:227], s[50:51], 0, v[134:135]
	s_add_i32 m0, s78, 0x2000
	s_nop 0
	global_load_lds_dwordx4 v[226:227], off
	s_waitcnt vmcnt(6)
	s_waitcnt lgkmcnt(0)
	s_barrier
; #define PG8_STAGE(bufoff, gbase, voff) do { _Pragma("unroll") for (int _i = 0; _i < 2; ++_i) \
;         __builtin_amdgcn_global_load_lds((const unsigned*)((const char*)(gbase) + (voff)[_i]), (PG8_LAS unsigned*)(lds + (bufoff) + ldsw + _i * 8192), 16, 0, 0); } while (0)
; #define PG8_LDA(dst, b, h) do { _Pragma("unroll") for (int m = 0; m < 4; ++m) _Pragma("unroll") for (int k = 0; k < 2; ++k) dst[m][k] = *(const PG8_LAS bf16x8*)(lds + PG8_SA(b, h) + aoff + m * 2048 + k * 1024); } while (0)
; #define PG8_LDB(dst, b, h) do { _Pragma("unroll") for (int n = 0; n < 2; ++n) _Pragma("unroll") for (int k = 0; k < 2; ++k) dst[n][k] = *(const PG8_LAS bf16x8*)(lds + PG8_SB(b, h) + boff + n * 2048 + k * 1024); } while (0)
; #define PG8_MMA(ai, bj, At, Bt) do { __builtin_amdgcn_s_setprio(1); _Pragma("unroll") for (int m = 0; m < 4; ++m) _Pragma("unroll") for (int n = 0; n < 2; ++n) _Pragma("unroll") for (int k = 0; k < 2; ++k) \
;         acc[ai][bj][m][n] = __builtin_amdgcn_mfma_f32_16x16x32_bf16(Bt[n][k], At[m][k], acc[ai][bj][m][n], 0, 0, 0); __builtin_amdgcn_s_setprio(0); } while (0)
; #define PG8_WAIT_V(n) asm volatile("s_waitcnt vmcnt(" #n ")" ::: "memory")
; #define PG8_WAIT_L(n) asm volatile("s_waitcnt lgkmcnt(" #n ")" ::: "memory")
; #define PG8_BAR __builtin_amdgcn_s_barrier()
; #define PG8_SCHED __builtin_amdgcn_sched_barrier(0)
; template <class Epi, class Sched, bool ALIGN_EPI = false, bool SP2 = false>
; __device__ __forceinline__ void gemm_phase(PG8_LAS unsigned char* lds, const Gemm g, const Sched& S, const Epi& E) {
;     ...
;             PG8_WAIT_V(8); PG8_WAIT_L(0); PG8_BAR; PG8_MMA(1, 0, At, B0); PG8_MMA(1, 1, At, B1); PG8_BAR; PG8_SCHED;
;             PG8_LDB(B0, 1, 0); PG8_LDB(B1, 1, 1); PG8_SCHED; PG8_LDA(At, 1, 0); PG8_STAGE(PG8_SA(0, 1), a2 + hstep, voffA);
;             PG8_WAIT_V(8); PG8_WAIT_L(0); PG8_BAR; PG8_MMA(0, 0, At, B0); PG8_MMA(0, 1, At, B1); PG8_BAR; PG8_SCHED;
	s_setprio 1
	s_waitcnt lgkmcnt(0)
	v_mfma_f32_16x16x32_bf16 v[60:63], v[144:147], v[186:189], 0
	v_mfma_f32_16x16x32_bf16 v[44:47], v[144:147], v[194:197], 0
	v_mfma_f32_16x16x32_bf16 v[56:59], v[160:163], v[186:189], 0
	v_mfma_f32_16x16x32_bf16 v[40:43], v[160:163], v[194:197], 0
	v_mfma_f32_16x16x32_bf16 v[28:31], v[144:147], v[208:211], 0
	v_mfma_f32_16x16x32_bf16 v[12:15], v[144:147], v[216:219], 0
	v_mfma_f32_16x16x32_bf16 v[24:27], v[160:163], v[208:211], 0
	v_mfma_f32_16x16x32_bf16 v[8:11], v[160:163], v[216:219], 0
	v_mfma_f32_16x16x32_bf16 v[60:63], v[156:159], v[190:193], v[60:63]
	v_mfma_f32_16x16x32_bf16 v[44:47], v[156:159], v[198:201], v[44:47]
	v_mfma_f32_16x16x32_bf16 v[56:59], v[164:167], v[190:193], v[56:59]
	v_mfma_f32_16x16x32_bf16 v[40:43], v[164:167], v[198:201], v[40:43]
	v_mfma_f32_16x16x32_bf16 v[28:31], v[156:159], v[212:215], v[28:31]
	v_mfma_f32_16x16x32_bf16 v[12:15], v[156:159], v[220:223], v[12:15]
	v_lshl_add_u64 v[226:227], s[56:57], 0, v[128:129]
	s_mov_b32 m0, s14
	s_nop 0
	global_load_lds_dwordx4 v[226:227], off
	v_mfma_f32_16x16x32_bf16 v[24:27], v[164:167], v[212:215], v[24:27]
	v_mfma_f32_16x16x32_bf16 v[8:11], v[164:167], v[220:223], v[8:11]
	s_setprio 0
	s_setprio 1
	v_mfma_f32_16x16x32_bf16 v[52:55], v[168:171], v[186:189], 0
	v_mfma_f32_16x16x32_bf16 v[36:39], v[168:171], v[194:197], 0
	v_mfma_f32_16x16x32_bf16 v[48:51], v[176:179], v[186:189], 0
	v_mfma_f32_16x16x32_bf16 v[32:35], v[176:179], v[194:197], 0
	v_mfma_f32_16x16x32_bf16 v[20:23], v[168:171], v[208:211], 0
	v_mfma_f32_16x16x32_bf16 v[4:7], v[168:171], v[216:219], 0
	v_mfma_f32_16x16x32_bf16 v[16:19], v[176:179], v[208:211], 0
	v_mfma_f32_16x16x32_bf16 v[0:3], v[176:179], v[216:219], 0
	v_mfma_f32_16x16x32_bf16 v[52:55], v[172:175], v[190:193], v[52:55]
	v_mfma_f32_16x16x32_bf16 v[36:39], v[172:175], v[198:201], v[36:39]
	v_mfma_f32_16x16x32_bf16 v[48:51], v[182:185], v[190:193], v[48:51]
	v_mfma_f32_16x16x32_bf16 v[32:35], v[182:185], v[198:201], v[32:35]
	v_mfma_f32_16x16x32_bf16 v[20:23], v[172:175], v[212:215], v[20:23]
	v_mfma_f32_16x16x32_bf16 v[4:7], v[172:175], v[220:223], v[4:7]
	v_lshl_add_u64 v[228:229], s[56:57], 0, v[132:133]
	s_mov_b32 m0, s15
	s_nop 0
	global_load_lds_dwordx4 v[228:229], off
	v_mfma_f32_16x16x32_bf16 v[16:19], v[182:185], v[212:215], v[16:19]
	v_mfma_f32_16x16x32_bf16 v[0:3], v[182:185], v[220:223], v[0:3]
	s_setprio 0
	s_barrier
	s_add_i32 s78, 0, 0x18000
	v_add_u32_e32 v155, s78, v149
	s_add_i32 s79, 0, 0x1c000
	ds_read_b128 v[144:147], v155
	ds_read_b128 v[156:159], v155 offset:1024
	ds_read_b128 v[160:163], v155 offset:2048
	ds_read_b128 v[164:167], v155 offset:3072
	v_add_u32_e32 v155, s79, v149
	ds_read_b128 v[168:171], v155
	ds_read_b128 v[172:175], v155 offset:1024
	ds_read_b128 v[176:179], v155 offset:2048
	ds_read_b128 v[182:185], v155 offset:3072
	s_add_u32 s50, s56, 0xb0000
	s_addc_u32 s51, s57, 0
	s_mov_b32 m0, s33
	v_lshl_add_u64 v[230:231], s[50:51], 0, v[128:129]
	ds_read_b128 v[186:189], v153 offset:32768
	ds_read_b128 v[190:193], v153 offset:33792
	ds_read_b128 v[194:197], v153 offset:34816
	ds_read_b128 v[198:201], v153 offset:35840
	ds_read_b128 v[208:211], v153 offset:36864
	ds_read_b128 v[212:215], v153 offset:37888
	ds_read_b128 v[216:219], v153 offset:38912
	ds_read_b128 v[220:223], v153 offset:39936
	global_load_lds_dwordx4 v[230:231], off
	v_lshl_add_u64 v[230:231], s[50:51], 0, v[132:133]
	s_mov_b32 m0, s34
	s_nop 0
	global_load_lds_dwordx4 v[230:231], off
	s_waitcnt vmcnt(8)
	s_waitcnt lgkmcnt(0)
	s_barrier
	s_setprio 1
	s_waitcnt lgkmcnt(0)
	v_mfma_f32_16x16x32_bf16 v[124:127], v[144:147], v[186:189], v[124:127]
	v_mfma_f32_16x16x32_bf16 v[108:111], v[144:147], v[194:197], v[108:111]
	v_mfma_f32_16x16x32_bf16 v[120:123], v[160:163], v[186:189], v[120:123]
	v_mfma_f32_16x16x32_bf16 v[104:107], v[160:163], v[194:197], v[104:107]
	v_mfma_f32_16x16x32_bf16 v[92:95], v[144:147], v[208:211], v[92:95]
	v_mfma_f32_16x16x32_bf16 v[76:79], v[144:147], v[216:219], v[76:79]
	v_mfma_f32_16x16x32_bf16 v[88:91], v[160:163], v[208:211], v[88:91]
	v_mfma_f32_16x16x32_bf16 v[72:75], v[160:163], v[216:219], v[72:75]
	v_mfma_f32_16x16x32_bf16 v[124:127], v[156:159], v[190:193], v[124:127]
	v_mfma_f32_16x16x32_bf16 v[108:111], v[156:159], v[198:201], v[108:111]
	v_mfma_f32_16x16x32_bf16 v[120:123], v[164:167], v[190:193], v[120:123]
	v_mfma_f32_16x16x32_bf16 v[104:107], v[164:167], v[198:201], v[104:107]
	v_mfma_f32_16x16x32_bf16 v[92:95], v[156:159], v[212:215], v[92:95]
	v_mfma_f32_16x16x32_bf16 v[76:79], v[156:159], v[220:223], v[76:79]
	v_mfma_f32_16x16x32_bf16 v[88:91], v[164:167], v[212:215], v[88:91]
	v_mfma_f32_16x16x32_bf16 v[72:75], v[164:167], v[220:223], v[72:75]
	s_setprio 0
	s_setprio 1
	v_mfma_f32_16x16x32_bf16 v[116:119], v[168:171], v[186:189], v[116:119]
	v_mfma_f32_16x16x32_bf16 v[100:103], v[168:171], v[194:197], v[100:103]
	v_mfma_f32_16x16x32_bf16 v[112:115], v[176:179], v[186:189], v[112:115]
	v_mfma_f32_16x16x32_bf16 v[96:99], v[176:179], v[194:197], v[96:99]
	v_mfma_f32_16x16x32_bf16 v[84:87], v[168:171], v[208:211], v[84:87]
	v_mfma_f32_16x16x32_bf16 v[68:71], v[168:171], v[216:219], v[68:71]
	v_mfma_f32_16x16x32_bf16 v[80:83], v[176:179], v[208:211], v[80:83]
	v_mfma_f32_16x16x32_bf16 v[64:67], v[176:179], v[216:219], v[64:67]
	v_mfma_f32_16x16x32_bf16 v[116:119], v[172:175], v[190:193], v[116:119]
	v_mfma_f32_16x16x32_bf16 v[100:103], v[172:175], v[198:201], v[100:103]
	v_mfma_f32_16x16x32_bf16 v[112:115], v[182:185], v[190:193], v[112:115]
	v_mfma_f32_16x16x32_bf16 v[96:99], v[182:185], v[198:201], v[96:99]
	v_mfma_f32_16x16x32_bf16 v[84:87], v[172:175], v[212:215], v[84:87]
	v_mfma_f32_16x16x32_bf16 v[68:71], v[172:175], v[220:223], v[68:71]
	v_mfma_f32_16x16x32_bf16 v[80:83], v[182:185], v[212:215], v[80:83]
	v_mfma_f32_16x16x32_bf16 v[64:67], v[182:185], v[220:223], v[64:67]
	s_setprio 0
	s_barrier
; #define PG8_STAGE(bufoff, gbase, voff) do { _Pragma("unroll") for (int _i = 0; _i < 2; ++_i) \
;         __builtin_amdgcn_global_load_lds((const unsigned*)((const char*)(gbase) + (voff)[_i]), (PG8_LAS unsigned*)(lds + (bufoff) + ldsw + _i * 8192), 16, 0, 0); } while (0)
; #define PG8_LDA(dst, b, h) do { _Pragma("unroll") for (int m = 0; m < 4; ++m) _Pragma("unroll") for (int k = 0; k < 2; ++k) dst[m][k] = *(const PG8_LAS bf16x8*)(lds + PG8_SA(b, h) + aoff + m * 2048 + k * 1024); } while (0)
; #define PG8_LDB(dst, b, h) do { _Pragma("unroll") for (int n = 0; n < 2; ++n) _Pragma("unroll") for (int k = 0; k < 2; ++k) dst[n][k] = *(const PG8_LAS bf16x8*)(lds + PG8_SB(b, h) + boff + n * 2048 + k * 1024); } while (0)
; #define PG8_MMA(ai, bj, At, Bt) do { __builtin_amdgcn_s_setprio(1); _Pragma("unroll") for (int m = 0; m < 4; ++m) _Pragma("unroll") for (int n = 0; n < 2; ++n) _Pragma("unroll") for (int k = 0; k < 2; ++k) \
;         acc[ai][bj][m][n] = __builtin_amdgcn_mfma_f32_16x16x32_bf16(Bt[n][k], At[m][k], acc[ai][bj][m][n], 0, 0, 0); __builtin_amdgcn_s_setprio(0); } while (0)
; #define PG8_WAIT_V(n) asm volatile("s_waitcnt vmcnt(" #n ")" ::: "memory")
; template <class Epi, class Sched, bool ALIGN_EPI = false, bool SP2 = false>
; __device__ __forceinline__ void gemm_phase(PG8_LAS unsigned char* lds, const Gemm g, const Sched& S, const Epi& E) {
;     ...
;             PG8_LDB(B0, 0, 0); PG8_LDB(B1, 0, 1); PG8_SCHED; PG8_LDA(At, 0, 0); PG8_STAGE(PG8_SA(1, 1), a1 + hstep, voffA);
;             PG8_WAIT_V(8); PG8_WAIT_L(0); PG8_BAR; PG8_MMA(0, 0, At, B0); PG8_MMA(0, 1, At, B1); PG8_BAR; PG8_SCHED;
;             PG8_LDA(At, 0, 1); PG8_STAGE(PG8_SB(0, 0), b2, voffB); PG8_STAGE(PG8_SB(0, 1), b2 + hstep, voffB); PG8_STAGE(PG8_SA(0, 0), a2, voffA);
;             PG8_WAIT_V(8); PG8_WAIT_L(0); PG8_BAR; PG8_MMA(1, 0, At, B0); PG8_MMA(1, 1, At, B1); PG8_BAR; PG8_SCHED;
;             PG8_LDB(B0, 1, 0); PG8_LDB(B1, 1, 1); PG8_SCHED; PG8_LDA(At, 1, 0); PG8_STAGE(PG8_SA(0, 1), a2 + hstep, voffA);
;             PG8_WAIT_V(8); PG8_WAIT_L(0); PG8_BAR; PG8_MMA(0, 0, At, B0); PG8_MMA(0, 1, At, B1); PG8_BAR; PG8_SCHED;
;             PG8_LDA(At, 1, 1); PG8_STAGE(PG8_SB(1, 0), b3, voffB); PG8_STAGE(PG8_SB(1, 1), b3 + hstep, voffB); PG8_STAGE(PG8_SA(1, 0), a3, voffA);
;             PG8_WAIT_V(8); PG8_WAIT_L(0); PG8_BAR; PG8_MMA(1, 0, At, B0); PG8_MMA(1, 1, At, B1); PG8_BAR; PG8_SCHED;
	s_add_i32 s50, s78, s3
	v_lshl_add_u64 v[202:203], v[202:203], 0, s[42:43]
	s_mov_b32 m0, s50
	ds_read_b128 v[186:189], v153 offset:49152
	ds_read_b128 v[190:193], v153 offset:50176
	ds_read_b128 v[194:197], v153 offset:51200
	ds_read_b128 v[198:201], v153 offset:52224
	ds_read_b128 v[208:211], v153 offset:53248
	ds_read_b128 v[212:215], v153 offset:54272
	ds_read_b128 v[216:219], v153 offset:55296
	ds_read_b128 v[220:223], v153 offset:56320
	global_load_lds_dwordx4 v[202:203], off
	s_add_i32 m0, s50, 0x2000
	s_add_u32 s50, s54, 0xb0080
	v_lshl_add_u64 v[202:203], v[224:225], 0, s[42:43]
	s_addc_u32 s51, s55, 0
	s_add_i32 s54, s79, s3
	global_load_lds_dwordx4 v[202:203], off
	v_lshl_add_u64 v[202:203], s[50:51], 0, v[130:131]
	s_mov_b32 m0, s54
	s_nop 0
	global_load_lds_dwordx4 v[202:203], off
	v_lshl_add_u64 v[202:203], s[50:51], 0, v[134:135]
	s_add_i32 m0, s54, 0x2000
	s_nop 0
	global_load_lds_dwordx4 v[202:203], off
	s_waitcnt vmcnt(6)
	s_waitcnt lgkmcnt(0)
	s_barrier
	s_setprio 1
	s_waitcnt lgkmcnt(0)
	v_mfma_f32_16x16x32_bf16 v[60:63], v[144:147], v[186:189], v[60:63]
	v_mfma_f32_16x16x32_bf16 v[44:47], v[144:147], v[194:197], v[44:47]
	v_mfma_f32_16x16x32_bf16 v[56:59], v[160:163], v[186:189], v[56:59]
	v_mfma_f32_16x16x32_bf16 v[40:43], v[160:163], v[194:197], v[40:43]
	v_mfma_f32_16x16x32_bf16 v[28:31], v[144:147], v[208:211], v[28:31]
	v_mfma_f32_16x16x32_bf16 v[12:15], v[144:147], v[216:219], v[12:15]
	v_mfma_f32_16x16x32_bf16 v[24:27], v[160:163], v[208:211], v[24:27]
	v_mfma_f32_16x16x32_bf16 v[8:11], v[160:163], v[216:219], v[8:11]
	v_mfma_f32_16x16x32_bf16 v[60:63], v[156:159], v[190:193], v[60:63]
	v_mfma_f32_16x16x32_bf16 v[44:47], v[156:159], v[198:201], v[44:47]
	v_mfma_f32_16x16x32_bf16 v[56:59], v[164:167], v[190:193], v[56:59]
	v_mfma_f32_16x16x32_bf16 v[40:43], v[164:167], v[198:201], v[40:43]
	v_mfma_f32_16x16x32_bf16 v[28:31], v[156:159], v[212:215], v[28:31]
	v_mfma_f32_16x16x32_bf16 v[12:15], v[156:159], v[220:223], v[12:15]
	v_lshl_add_u64 v[202:203], v[226:227], 0, s[42:43]
	s_mov_b32 m0, s59
	s_nop 0
	global_load_lds_dwordx4 v[202:203], off
	v_mfma_f32_16x16x32_bf16 v[24:27], v[164:167], v[212:215], v[24:27]
	v_mfma_f32_16x16x32_bf16 v[8:11], v[164:167], v[220:223], v[8:11]
	s_setprio 0
	s_setprio 1
	v_mfma_f32_16x16x32_bf16 v[52:55], v[168:171], v[186:189], v[52:55]
	v_mfma_f32_16x16x32_bf16 v[36:39], v[168:171], v[194:197], v[36:39]
	v_mfma_f32_16x16x32_bf16 v[48:51], v[176:179], v[186:189], v[48:51]
	v_mfma_f32_16x16x32_bf16 v[32:35], v[176:179], v[194:197], v[32:35]
	v_mfma_f32_16x16x32_bf16 v[20:23], v[168:171], v[208:211], v[20:23]
	v_mfma_f32_16x16x32_bf16 v[4:7], v[168:171], v[216:219], v[4:7]
	v_mfma_f32_16x16x32_bf16 v[16:19], v[176:179], v[208:211], v[16:19]
	v_mfma_f32_16x16x32_bf16 v[0:3], v[176:179], v[216:219], v[0:3]
	v_mfma_f32_16x16x32_bf16 v[52:55], v[172:175], v[190:193], v[52:55]
	v_mfma_f32_16x16x32_bf16 v[36:39], v[172:175], v[198:201], v[36:39]
	v_mfma_f32_16x16x32_bf16 v[48:51], v[182:185], v[190:193], v[48:51]
	v_mfma_f32_16x16x32_bf16 v[32:35], v[182:185], v[198:201], v[32:35]
	v_mfma_f32_16x16x32_bf16 v[20:23], v[172:175], v[212:215], v[20:23]
	v_mfma_f32_16x16x32_bf16 v[4:7], v[172:175], v[220:223], v[4:7]
	v_lshl_add_u64 v[202:203], v[228:229], 0, s[42:43]
	s_mov_b32 m0, s60
	s_nop 0
	global_load_lds_dwordx4 v[202:203], off
	v_mfma_f32_16x16x32_bf16 v[16:19], v[182:185], v[212:215], v[16:19]
	v_mfma_f32_16x16x32_bf16 v[0:3], v[182:185], v[220:223], v[0:3]
	s_setprio 0
	s_barrier
	s_add_i32 s77, s77, 2
	s_add_u32 s75, s75, 0x100
	s_addc_u32 s76, s76, 0
	s_mov_b64 s[50:51], s[52:53]
.LBB0_1035:
	ds_read_b128 v[144:147], v151
	ds_read_b128 v[156:159], v151 offset:1024
	ds_read_b128 v[160:163], v151 offset:2048
	ds_read_b128 v[164:167], v151 offset:3072
	ds_read_b128 v[168:171], v152
	ds_read_b128 v[172:175], v152 offset:1024
	ds_read_b128 v[176:179], v152 offset:2048
	ds_read_b128 v[182:185], v152 offset:3072
	s_add_u32 s52, s50, 0x100
	s_addc_u32 s53, s51, 0
	s_cmp_eq_u32 s77, 40
	s_cselect_b32 s57, s1, s53
	s_cselect_b32 s56, s0, s52
	s_cselect_b32 s55, s49, s76
	s_cselect_b32 s54, s48, s75
	v_lshl_add_u64 v[202:203], s[50:51], 0, v[136:137]
	s_add_i32 m0, s14, 0xc000
	ds_read_b128 v[186:189], v153
	ds_read_b128 v[190:193], v153 offset:1024
	ds_read_b128 v[194:197], v153 offset:2048
	ds_read_b128 v[198:201], v153 offset:3072
	ds_read_b128 v[208:211], v153 offset:4096
	ds_read_b128 v[212:215], v153 offset:5120
	ds_read_b128 v[216:219], v153 offset:6144
	ds_read_b128 v[220:223], v153 offset:7168
	global_load_lds_dwordx4 v[202:203], off
	v_lshl_add_u64 v[202:203], s[50:51], 0, v[138:139]
	s_add_i32 m0, s14, 0xe000
	s_nop 0
	global_load_lds_dwordx4 v[202:203], off
	s_waitcnt vmcnt(8)
	s_waitcnt lgkmcnt(0)
	s_barrier
; #define PG8_STAGE(bufoff, gbase, voff) do { _Pragma("unroll") for (int _i = 0; _i < 2; ++_i) \
;         __builtin_amdgcn_global_load_lds((const unsigned*)((const char*)(gbase) + (voff)[_i]), (PG8_LAS unsigned*)(lds + (bufoff) + ldsw + _i * 8192), 16, 0, 0); } while (0)
; #define PG8_LDA(dst, b, h) do { _Pragma("unroll") for (int m = 0; m < 4; ++m) _Pragma("unroll") for (int k = 0; k < 2; ++k) dst[m][k] = *(const PG8_LAS bf16x8*)(lds + PG8_SA(b, h) + aoff + m * 2048 + k * 1024); } while (0)
; #define PG8_MMA(ai, bj, At, Bt) do { __builtin_amdgcn_s_setprio(1); _Pragma("unroll") for (int m = 0; m < 4; ++m) _Pragma("unroll") for (int n = 0; n < 2; ++n) _Pragma("unroll") for (int k = 0; k < 2; ++k) \
;         acc[ai][bj][m][n] = __builtin_amdgcn_mfma_f32_16x16x32_bf16(Bt[n][k], At[m][k], acc[ai][bj][m][n], 0, 0, 0); __builtin_amdgcn_s_setprio(0); } while (0)
; #define PG8_WAIT_V(n) asm volatile("s_waitcnt vmcnt(" #n ")" ::: "memory")
; #define PG8_WAIT_L(n) asm volatile("s_waitcnt lgkmcnt(" #n ")" ::: "memory")
; #define PG8_BAR __builtin_amdgcn_s_barrier()
; #define PG8_SCHED __builtin_amdgcn_sched_barrier(0)
; template <class Epi, class Sched, bool ALIGN_EPI = false, bool SP2 = false>
; __device__ __forceinline__ void gemm_phase(PG8_LAS unsigned char* lds, const Gemm g, const Sched& S, const Epi& E) {
;     ...
;             PG8_WAIT_V(8); PG8_WAIT_L(0); PG8_BAR; PG8_MMA(0, 0, At, B0); PG8_MMA(0, 1, At, B1); PG8_BAR; PG8_SCHED;
;             PG8_LDA(At, 0, 1); PG8_STAGE(PG8_SB(0, 0), b2, voffB); PG8_STAGE(PG8_SB(0, 1), b2 + hstep, voffB); PG8_STAGE(PG8_SA(0, 0), a2, voffA);
;             PG8_WAIT_V(8); PG8_WAIT_L(0); PG8_BAR; PG8_MMA(1, 0, At, B0); PG8_MMA(1, 1, At, B1); PG8_BAR; PG8_SCHED;
	s_setprio 1
	s_waitcnt lgkmcnt(0)
	v_mfma_f32_16x16x32_bf16 v[124:127], v[144:147], v[186:189], v[124:127]
	v_mfma_f32_16x16x32_bf16 v[108:111], v[144:147], v[194:197], v[108:111]
	v_mfma_f32_16x16x32_bf16 v[120:123], v[160:163], v[186:189], v[120:123]
	v_mfma_f32_16x16x32_bf16 v[104:107], v[160:163], v[194:197], v[104:107]
	v_mfma_f32_16x16x32_bf16 v[92:95], v[144:147], v[208:211], v[92:95]
	v_mfma_f32_16x16x32_bf16 v[76:79], v[144:147], v[216:219], v[76:79]
	v_mfma_f32_16x16x32_bf16 v[88:91], v[160:163], v[208:211], v[88:91]
	v_mfma_f32_16x16x32_bf16 v[72:75], v[160:163], v[216:219], v[72:75]
	v_mfma_f32_16x16x32_bf16 v[124:127], v[156:159], v[190:193], v[124:127]
	v_mfma_f32_16x16x32_bf16 v[108:111], v[156:159], v[198:201], v[108:111]
	v_mfma_f32_16x16x32_bf16 v[120:123], v[164:167], v[190:193], v[120:123]
	v_mfma_f32_16x16x32_bf16 v[104:107], v[164:167], v[198:201], v[104:107]
	v_mfma_f32_16x16x32_bf16 v[92:95], v[156:159], v[212:215], v[92:95]
	v_mfma_f32_16x16x32_bf16 v[76:79], v[156:159], v[220:223], v[76:79]
	v_mfma_f32_16x16x32_bf16 v[88:91], v[164:167], v[212:215], v[88:91]
	v_mfma_f32_16x16x32_bf16 v[72:75], v[164:167], v[220:223], v[72:75]
	s_setprio 0
	s_setprio 1
	v_mfma_f32_16x16x32_bf16 v[116:119], v[168:171], v[186:189], v[116:119]
	v_mfma_f32_16x16x32_bf16 v[100:103], v[168:171], v[194:197], v[100:103]
	v_mfma_f32_16x16x32_bf16 v[112:115], v[176:179], v[186:189], v[112:115]
	v_mfma_f32_16x16x32_bf16 v[96:99], v[176:179], v[194:197], v[96:99]
	v_mfma_f32_16x16x32_bf16 v[84:87], v[168:171], v[208:211], v[84:87]
	v_mfma_f32_16x16x32_bf16 v[68:71], v[168:171], v[216:219], v[68:71]
	v_mfma_f32_16x16x32_bf16 v[80:83], v[176:179], v[208:211], v[80:83]
	v_mfma_f32_16x16x32_bf16 v[64:67], v[176:179], v[216:219], v[64:67]
	v_mfma_f32_16x16x32_bf16 v[116:119], v[172:175], v[190:193], v[116:119]
	v_mfma_f32_16x16x32_bf16 v[100:103], v[172:175], v[198:201], v[100:103]
	v_mfma_f32_16x16x32_bf16 v[112:115], v[182:185], v[190:193], v[112:115]
	v_mfma_f32_16x16x32_bf16 v[96:99], v[182:185], v[198:201], v[96:99]
	v_mfma_f32_16x16x32_bf16 v[84:87], v[172:175], v[212:215], v[84:87]
	v_mfma_f32_16x16x32_bf16 v[68:71], v[172:175], v[220:223], v[68:71]
	v_mfma_f32_16x16x32_bf16 v[80:83], v[182:185], v[212:215], v[80:83]
	v_mfma_f32_16x16x32_bf16 v[64:67], v[182:185], v[220:223], v[64:67]
	s_setprio 0
	s_barrier
	s_add_i32 s50, s61, s3
	v_lshl_add_u64 v[202:203], s[54:55], 0, v[130:131]
	s_mov_b32 m0, s50
	ds_read_b128 v[186:189], v153 offset:16384
	ds_read_b128 v[190:193], v153 offset:17408
	ds_read_b128 v[194:197], v153 offset:18432
	ds_read_b128 v[198:201], v153 offset:19456
	ds_read_b128 v[208:211], v153 offset:20480
	ds_read_b128 v[212:215], v153 offset:21504
	ds_read_b128 v[216:219], v153 offset:22528
	ds_read_b128 v[220:223], v153 offset:23552
	global_load_lds_dwordx4 v[202:203], off
	s_add_i32 m0, s50, 0x2000
	s_add_u32 s50, s54, 0xb0000
	v_lshl_add_u64 v[224:225], s[54:55], 0, v[134:135]
	s_addc_u32 s51, s55, 0
	s_add_i32 s78, s62, s3
	global_load_lds_dwordx4 v[224:225], off
	v_lshl_add_u64 v[226:227], s[50:51], 0, v[130:131]
	s_mov_b32 m0, s78
	global_load_lds_dwordx4 v[226:227], off
	v_lshl_add_u64 v[226:227], s[50:51], 0, v[134:135]
	s_add_i32 m0, s78, 0x2000
	s_nop 0
	global_load_lds_dwordx4 v[226:227], off
	s_waitcnt vmcnt(6)
	s_waitcnt lgkmcnt(0)
	s_barrier
	s_setprio 1
	s_waitcnt lgkmcnt(0)
	v_mfma_f32_16x16x32_bf16 v[60:63], v[144:147], v[186:189], v[60:63]
	v_mfma_f32_16x16x32_bf16 v[44:47], v[144:147], v[194:197], v[44:47]
	v_mfma_f32_16x16x32_bf16 v[56:59], v[160:163], v[186:189], v[56:59]
	v_mfma_f32_16x16x32_bf16 v[40:43], v[160:163], v[194:197], v[40:43]
	v_mfma_f32_16x16x32_bf16 v[28:31], v[144:147], v[208:211], v[28:31]
	v_mfma_f32_16x16x32_bf16 v[12:15], v[144:147], v[216:219], v[12:15]
	v_mfma_f32_16x16x32_bf16 v[24:27], v[160:163], v[208:211], v[24:27]
	v_mfma_f32_16x16x32_bf16 v[8:11], v[160:163], v[216:219], v[8:11]
	v_mfma_f32_16x16x32_bf16 v[60:63], v[156:159], v[190:193], v[60:63]
	v_mfma_f32_16x16x32_bf16 v[44:47], v[156:159], v[198:201], v[44:47]
	v_mfma_f32_16x16x32_bf16 v[56:59], v[164:167], v[190:193], v[56:59]
	v_mfma_f32_16x16x32_bf16 v[40:43], v[164:167], v[198:201], v[40:43]
	v_mfma_f32_16x16x32_bf16 v[28:31], v[156:159], v[212:215], v[28:31]
	v_mfma_f32_16x16x32_bf16 v[12:15], v[156:159], v[220:223], v[12:15]
	v_lshl_add_u64 v[226:227], s[56:57], 0, v[128:129]
	s_mov_b32 m0, s14
	s_nop 0
	global_load_lds_dwordx4 v[226:227], off
	v_mfma_f32_16x16x32_bf16 v[24:27], v[164:167], v[212:215], v[24:27]
	v_mfma_f32_16x16x32_bf16 v[8:11], v[164:167], v[220:223], v[8:11]
	s_setprio 0
	s_setprio 1
	v_mfma_f32_16x16x32_bf16 v[52:55], v[168:171], v[186:189], v[52:55]
	v_mfma_f32_16x16x32_bf16 v[36:39], v[168:171], v[194:197], v[36:39]
	v_mfma_f32_16x16x32_bf16 v[48:51], v[176:179], v[186:189], v[48:51]
	v_mfma_f32_16x16x32_bf16 v[32:35], v[176:179], v[194:197], v[32:35]
	v_mfma_f32_16x16x32_bf16 v[20:23], v[168:171], v[208:211], v[20:23]
	v_mfma_f32_16x16x32_bf16 v[4:7], v[168:171], v[216:219], v[4:7]
	v_mfma_f32_16x16x32_bf16 v[16:19], v[176:179], v[208:211], v[16:19]
	v_mfma_f32_16x16x32_bf16 v[0:3], v[176:179], v[216:219], v[0:3]
	v_mfma_f32_16x16x32_bf16 v[52:55], v[172:175], v[190:193], v[52:55]
	v_mfma_f32_16x16x32_bf16 v[36:39], v[172:175], v[198:201], v[36:39]
	v_mfma_f32_16x16x32_bf16 v[48:51], v[182:185], v[190:193], v[48:51]
	v_mfma_f32_16x16x32_bf16 v[32:35], v[182:185], v[198:201], v[32:35]
	v_mfma_f32_16x16x32_bf16 v[20:23], v[172:175], v[212:215], v[20:23]
	v_mfma_f32_16x16x32_bf16 v[4:7], v[172:175], v[220:223], v[4:7]
	v_lshl_add_u64 v[228:229], s[56:57], 0, v[132:133]
	s_mov_b32 m0, s15
	s_nop 0
	global_load_lds_dwordx4 v[228:229], off
	v_mfma_f32_16x16x32_bf16 v[16:19], v[182:185], v[212:215], v[16:19]
	v_mfma_f32_16x16x32_bf16 v[0:3], v[182:185], v[220:223], v[0:3]
	s_setprio 0
	s_barrier
; #define PG8_STAGE(bufoff, gbase, voff) do { _Pragma("unroll") for (int _i = 0; _i < 2; ++_i) \
;         __builtin_amdgcn_global_load_lds((const unsigned*)((const char*)(gbase) + (voff)[_i]), (PG8_LAS unsigned*)(lds + (bufoff) + ldsw + _i * 8192), 16, 0, 0); } while (0)
; #define PG8_LDA(dst, b, h) do { _Pragma("unroll") for (int m = 0; m < 4; ++m) _Pragma("unroll") for (int k = 0; k < 2; ++k) dst[m][k] = *(const PG8_LAS bf16x8*)(lds + PG8_SA(b, h) + aoff + m * 2048 + k * 1024); } while (0)
; #define PG8_LDB(dst, b, h) do { _Pragma("unroll") for (int n = 0; n < 2; ++n) _Pragma("unroll") for (int k = 0; k < 2; ++k) dst[n][k] = *(const PG8_LAS bf16x8*)(lds + PG8_SB(b, h) + boff + n * 2048 + k * 1024); } while (0)
; #define PG8_MMA(ai, bj, At, Bt) do { __builtin_amdgcn_s_setprio(1); _Pragma("unroll") for (int m = 0; m < 4; ++m) _Pragma("unroll") for (int n = 0; n < 2; ++n) _Pragma("unroll") for (int k = 0; k < 2; ++k) \
;         acc[ai][bj][m][n] = __builtin_amdgcn_mfma_f32_16x16x32_bf16(Bt[n][k], At[m][k], acc[ai][bj][m][n], 0, 0, 0); __builtin_amdgcn_s_setprio(0); } while (0)
; #define PG8_WAIT_V(n) asm volatile("s_waitcnt vmcnt(" #n ")" ::: "memory")
; #define PG8_WAIT_L(n) asm volatile("s_waitcnt lgkmcnt(" #n ")" ::: "memory")
; #define PG8_BAR __builtin_amdgcn_s_barrier()
; #define PG8_SCHED __builtin_amdgcn_sched_barrier(0)
; template <class Epi, class Sched, bool ALIGN_EPI = false, bool SP2 = false>
; __device__ __forceinline__ void gemm_phase(PG8_LAS unsigned char* lds, const Gemm g, const Sched& S, const Epi& E) {
;     ...
;             PG8_LDB(B0, 1, 0); PG8_LDB(B1, 1, 1); PG8_SCHED; PG8_LDA(At, 1, 0); PG8_STAGE(PG8_SA(0, 1), a2 + hstep, voffA);
;             PG8_WAIT_V(8); PG8_WAIT_L(0); PG8_BAR; PG8_MMA(0, 0, At, B0); PG8_MMA(0, 1, At, B1); PG8_BAR; PG8_SCHED;
	s_add_i32 s78, 0, 0x18000
	v_add_u32_e32 v155, s78, v149
	s_add_i32 s79, 0, 0x1c000
	ds_read_b128 v[144:147], v155
	ds_read_b128 v[156:159], v155 offset:1024
	ds_read_b128 v[160:163], v155 offset:2048
	ds_read_b128 v[164:167], v155 offset:3072
	v_add_u32_e32 v155, s79, v149
	ds_read_b128 v[168:171], v155
	ds_read_b128 v[172:175], v155 offset:1024
	ds_read_b128 v[176:179], v155 offset:2048
	ds_read_b128 v[182:185], v155 offset:3072
	s_add_u32 s50, s56, 0xb0000
	s_addc_u32 s51, s57, 0
	s_mov_b32 m0, s33
	v_lshl_add_u64 v[230:231], s[50:51], 0, v[128:129]
	ds_read_b128 v[186:189], v153 offset:32768
	ds_read_b128 v[190:193], v153 offset:33792
	ds_read_b128 v[194:197], v153 offset:34816
	ds_read_b128 v[198:201], v153 offset:35840
	ds_read_b128 v[208:211], v153 offset:36864
	ds_read_b128 v[212:215], v153 offset:37888
	ds_read_b128 v[216:219], v153 offset:38912
	ds_read_b128 v[220:223], v153 offset:39936
	global_load_lds_dwordx4 v[230:231], off
	v_lshl_add_u64 v[230:231], s[50:51], 0, v[132:133]
	s_mov_b32 m0, s34
	s_nop 0
	global_load_lds_dwordx4 v[230:231], off
	s_waitcnt vmcnt(8)
	s_waitcnt lgkmcnt(0)
	s_barrier
	s_setprio 1
	s_waitcnt lgkmcnt(0)
	v_mfma_f32_16x16x32_bf16 v[124:127], v[144:147], v[186:189], v[124:127]
	v_mfma_f32_16x16x32_bf16 v[108:111], v[144:147], v[194:197], v[108:111]
	v_mfma_f32_16x16x32_bf16 v[120:123], v[160:163], v[186:189], v[120:123]
	v_mfma_f32_16x16x32_bf16 v[104:107], v[160:163], v[194:197], v[104:107]
	v_mfma_f32_16x16x32_bf16 v[92:95], v[144:147], v[208:211], v[92:95]
	v_mfma_f32_16x16x32_bf16 v[76:79], v[144:147], v[216:219], v[76:79]
	v_mfma_f32_16x16x32_bf16 v[88:91], v[160:163], v[208:211], v[88:91]
	v_mfma_f32_16x16x32_bf16 v[72:75], v[160:163], v[216:219], v[72:75]
	v_mfma_f32_16x16x32_bf16 v[124:127], v[156:159], v[190:193], v[124:127]
	v_mfma_f32_16x16x32_bf16 v[108:111], v[156:159], v[198:201], v[108:111]
	v_mfma_f32_16x16x32_bf16 v[120:123], v[164:167], v[190:193], v[120:123]
	v_mfma_f32_16x16x32_bf16 v[104:107], v[164:167], v[198:201], v[104:107]
	v_mfma_f32_16x16x32_bf16 v[92:95], v[156:159], v[212:215], v[92:95]
	v_mfma_f32_16x16x32_bf16 v[76:79], v[156:159], v[220:223], v[76:79]
	v_mfma_f32_16x16x32_bf16 v[88:91], v[164:167], v[212:215], v[88:91]
	v_mfma_f32_16x16x32_bf16 v[72:75], v[164:167], v[220:223], v[72:75]
	s_setprio 0
	s_setprio 1
	v_mfma_f32_16x16x32_bf16 v[116:119], v[168:171], v[186:189], v[116:119]
	v_mfma_f32_16x16x32_bf16 v[100:103], v[168:171], v[194:197], v[100:103]
	v_mfma_f32_16x16x32_bf16 v[112:115], v[176:179], v[186:189], v[112:115]
	v_mfma_f32_16x16x32_bf16 v[96:99], v[176:179], v[194:197], v[96:99]
	v_mfma_f32_16x16x32_bf16 v[84:87], v[168:171], v[208:211], v[84:87]
	v_mfma_f32_16x16x32_bf16 v[68:71], v[168:171], v[216:219], v[68:71]
	v_mfma_f32_16x16x32_bf16 v[80:83], v[176:179], v[208:211], v[80:83]
	v_mfma_f32_16x16x32_bf16 v[64:67], v[176:179], v[216:219], v[64:67]
	v_mfma_f32_16x16x32_bf16 v[116:119], v[172:175], v[190:193], v[116:119]
	v_mfma_f32_16x16x32_bf16 v[100:103], v[172:175], v[198:201], v[100:103]
	v_mfma_f32_16x16x32_bf16 v[112:115], v[182:185], v[190:193], v[112:115]
	v_mfma_f32_16x16x32_bf16 v[96:99], v[182:185], v[198:201], v[96:99]
	v_mfma_f32_16x16x32_bf16 v[84:87], v[172:175], v[212:215], v[84:87]
	v_mfma_f32_16x16x32_bf16 v[68:71], v[172:175], v[220:223], v[68:71]
	v_mfma_f32_16x16x32_bf16 v[80:83], v[182:185], v[212:215], v[80:83]
	v_mfma_f32_16x16x32_bf16 v[64:67], v[182:185], v[220:223], v[64:67]
	s_setprio 0
	s_barrier
; #define PG8_STAGE(bufoff, gbase, voff) do { _Pragma("unroll") for (int _i = 0; _i < 2; ++_i) \
;         __builtin_amdgcn_global_load_lds((const unsigned*)((const char*)(gbase) + (voff)[_i]), (PG8_LAS unsigned*)(lds + (bufoff) + ldsw + _i * 8192), 16, 0, 0); } while (0)
; #define PG8_LDA(dst, b, h) do { _Pragma("unroll") for (int m = 0; m < 4; ++m) _Pragma("unroll") for (int k = 0; k < 2; ++k) dst[m][k] = *(const PG8_LAS bf16x8*)(lds + PG8_SA(b, h) + aoff + m * 2048 + k * 1024); } while (0)
; #define PG8_MMA(ai, bj, At, Bt) do { __builtin_amdgcn_s_setprio(1); _Pragma("unroll") for (int m = 0; m < 4; ++m) _Pragma("unroll") for (int n = 0; n < 2; ++n) _Pragma("unroll") for (int k = 0; k < 2; ++k) \
;         acc[ai][bj][m][n] = __builtin_amdgcn_mfma_f32_16x16x32_bf16(Bt[n][k], At[m][k], acc[ai][bj][m][n], 0, 0, 0); __builtin_amdgcn_s_setprio(0); } while (0)
; #define PG8_WAIT_V(n) asm volatile("s_waitcnt vmcnt(" #n ")" ::: "memory")
; #define PG8_WAIT_L(n) asm volatile("s_waitcnt lgkmcnt(" #n ")" ::: "memory")
; #define PG8_BAR __builtin_amdgcn_s_barrier()
; #define PG8_SCHED __builtin_amdgcn_sched_barrier(0)
; template <class Epi, class Sched, bool ALIGN_EPI = false, bool SP2 = false>
; __device__ __forceinline__ void gemm_phase(PG8_LAS unsigned char* lds, const Gemm g, const Sched& S, const Epi& E) {
;     ...
;             PG8_LDA(At, 1, 1); PG8_STAGE(PG8_SB(1, 0), b3, voffB); PG8_STAGE(PG8_SB(1, 1), b3 + hstep, voffB); PG8_STAGE(PG8_SA(1, 0), a3, voffA);
;             PG8_WAIT_V(8); PG8_WAIT_L(0); PG8_BAR; PG8_MMA(1, 0, At, B0); PG8_MMA(1, 1, At, B1); PG8_BAR; PG8_SCHED;
;     ...
;         if constexpr (ALIGN_EPI) { if (wr == 0) PG8_BAR; }
	s_add_i32 s50, s78, s3
	v_lshl_add_u64 v[202:203], v[202:203], 0, s[42:43]
	s_mov_b32 m0, s50
	ds_read_b128 v[186:189], v153 offset:49152
	ds_read_b128 v[190:193], v153 offset:50176
	ds_read_b128 v[194:197], v153 offset:51200
	ds_read_b128 v[198:201], v153 offset:52224
	ds_read_b128 v[208:211], v153 offset:53248
	ds_read_b128 v[212:215], v153 offset:54272
	ds_read_b128 v[216:219], v153 offset:55296
	ds_read_b128 v[220:223], v153 offset:56320
	global_load_lds_dwordx4 v[202:203], off
	s_add_i32 m0, s50, 0x2000
	s_add_u32 s50, s54, 0xb0080
	v_lshl_add_u64 v[202:203], v[224:225], 0, s[42:43]
	s_addc_u32 s51, s55, 0
	s_add_i32 s54, s79, s3
	global_load_lds_dwordx4 v[202:203], off
	v_lshl_add_u64 v[202:203], s[50:51], 0, v[130:131]
	s_mov_b32 m0, s54
	s_nop 0
	global_load_lds_dwordx4 v[202:203], off
	v_lshl_add_u64 v[202:203], s[50:51], 0, v[134:135]
	s_add_i32 m0, s54, 0x2000
	s_nop 0
	global_load_lds_dwordx4 v[202:203], off
	s_waitcnt vmcnt(6)
	s_waitcnt lgkmcnt(0)
	s_barrier
	s_setprio 1
	s_waitcnt lgkmcnt(0)
	v_mfma_f32_16x16x32_bf16 v[60:63], v[144:147], v[186:189], v[60:63]
	v_mfma_f32_16x16x32_bf16 v[44:47], v[144:147], v[194:197], v[44:47]
	v_mfma_f32_16x16x32_bf16 v[56:59], v[160:163], v[186:189], v[56:59]
	v_mfma_f32_16x16x32_bf16 v[40:43], v[160:163], v[194:197], v[40:43]
	v_mfma_f32_16x16x32_bf16 v[28:31], v[144:147], v[208:211], v[28:31]
	v_mfma_f32_16x16x32_bf16 v[12:15], v[144:147], v[216:219], v[12:15]
	v_mfma_f32_16x16x32_bf16 v[24:27], v[160:163], v[208:211], v[24:27]
	v_mfma_f32_16x16x32_bf16 v[8:11], v[160:163], v[216:219], v[8:11]
	v_mfma_f32_16x16x32_bf16 v[60:63], v[156:159], v[190:193], v[60:63]
	v_mfma_f32_16x16x32_bf16 v[44:47], v[156:159], v[198:201], v[44:47]
	v_mfma_f32_16x16x32_bf16 v[56:59], v[164:167], v[190:193], v[56:59]
	v_mfma_f32_16x16x32_bf16 v[40:43], v[164:167], v[198:201], v[40:43]
	v_mfma_f32_16x16x32_bf16 v[28:31], v[156:159], v[212:215], v[28:31]
	v_mfma_f32_16x16x32_bf16 v[12:15], v[156:159], v[220:223], v[12:15]
	v_lshl_add_u64 v[202:203], v[226:227], 0, s[42:43]
	s_mov_b32 m0, s59
	s_nop 0
	global_load_lds_dwordx4 v[202:203], off
	v_mfma_f32_16x16x32_bf16 v[24:27], v[164:167], v[212:215], v[24:27]
	v_mfma_f32_16x16x32_bf16 v[8:11], v[164:167], v[220:223], v[8:11]
	s_setprio 0
	s_setprio 1
	v_mfma_f32_16x16x32_bf16 v[52:55], v[168:171], v[186:189], v[52:55]
	v_mfma_f32_16x16x32_bf16 v[36:39], v[168:171], v[194:197], v[36:39]
	v_mfma_f32_16x16x32_bf16 v[48:51], v[176:179], v[186:189], v[48:51]
	v_mfma_f32_16x16x32_bf16 v[32:35], v[176:179], v[194:197], v[32:35]
	v_mfma_f32_16x16x32_bf16 v[20:23], v[168:171], v[208:211], v[20:23]
	v_mfma_f32_16x16x32_bf16 v[4:7], v[168:171], v[216:219], v[4:7]
	v_mfma_f32_16x16x32_bf16 v[16:19], v[176:179], v[208:211], v[16:19]
	v_mfma_f32_16x16x32_bf16 v[0:3], v[176:179], v[216:219], v[0:3]
	v_mfma_f32_16x16x32_bf16 v[52:55], v[172:175], v[190:193], v[52:55]
	v_mfma_f32_16x16x32_bf16 v[36:39], v[172:175], v[198:201], v[36:39]
	v_mfma_f32_16x16x32_bf16 v[48:51], v[182:185], v[190:193], v[48:51]
	v_mfma_f32_16x16x32_bf16 v[32:35], v[182:185], v[198:201], v[32:35]
	v_mfma_f32_16x16x32_bf16 v[20:23], v[172:175], v[212:215], v[20:23]
	v_mfma_f32_16x16x32_bf16 v[4:7], v[172:175], v[220:223], v[4:7]
	v_lshl_add_u64 v[202:203], v[228:229], 0, s[42:43]
	s_mov_b32 m0, s60
	s_nop 0
	global_load_lds_dwordx4 v[202:203], off
	v_mfma_f32_16x16x32_bf16 v[16:19], v[182:185], v[212:215], v[16:19]
	v_mfma_f32_16x16x32_bf16 v[0:3], v[182:185], v[220:223], v[0:3]
	s_setprio 0
	s_barrier
	s_add_i32 s77, s77, 2
	s_add_u32 s75, s75, 0x100
	s_addc_u32 s76, s76, 0
	s_cmp_gt_u32 s77, 41
	s_mov_b64 s[50:51], s[52:53]
	s_cbranch_scc0 .LBB0_1035
	s_and_b64 vcc, exec, s[44:45]
	s_cbranch_vccz .LBB0_1038
	s_barrier

; #define PG8_STAGE(bufoff, gbase, voff) do { _Pragma("unroll") for (int _i = 0; _i < 2; ++_i) \
;         __builtin_amdgcn_global_load_lds((const unsigned*)((const char*)(gbase) + (voff)[_i]), (PG8_LAS unsigned*)(lds + (bufoff) + ldsw + _i * 8192), 16, 0, 0); } while (0)
; #define PG8_LDA(dst, b, h) do { _Pragma("unroll") for (int m = 0; m < 4; ++m) _Pragma("unroll") for (int k = 0; k < 2; ++k) dst[m][k] = *(const PG8_LAS bf16x8*)(lds + PG8_SA(b, h) + aoff + m * 2048 + k * 1024); } while (0)
; #define PG8_LDB(dst, b, h) do { _Pragma("unroll") for (int n = 0; n < 2; ++n) _Pragma("unroll") for (int k = 0; k < 2; ++k) dst[n][k] = *(const PG8_LAS bf16x8*)(lds + PG8_SB(b, h) + boff + n * 2048 + k * 1024); } while (0)
; #define PG8_WAIT_V(n) asm volatile("s_waitcnt vmcnt(" #n ")" ::: "memory")
; #define PG8_WAIT_L(n) asm volatile("s_waitcnt lgkmcnt(" #n ")" ::: "memory")
; #define PG8_BAR __builtin_amdgcn_s_barrier()
; #define PG8_SCHED __builtin_amdgcn_sched_barrier(0)
; template <class Epi, class Sched, bool ALIGN_EPI = false, bool SP2 = false>
; __device__ __forceinline__ void gemm_phase(PG8_LAS unsigned char* lds, const Gemm g, const Sched& S, const Epi& E) {
;     ...
;         const bool has_next = S.next(ui + 1, nxt);
;         const char* nA = has_next ? (const char*)g.A + (size_t)nxt.pm * tstep : cA; const char* nB = has_next ? (const char*)g.Bt + (size_t)nxt.pn * tstep : cB;
;         for (int t = 0; t < nt; t += 2) {
;             const bool last = (t == nt - 2);
;             const char* a1 = cA + (size_t)(t + 1) * kstep;
;             const char* a2 = last ? nA : cA + (size_t)(t + 2) * kstep; const char* b2 = last ? nB : cB + (size_t)(t + 2) * kstep;
;             const char* a3 = a2 + kstep; const char* b3 = b2 + kstep;
;             if (last && has_next) S.a_ready(nxt);
;             if constexpr (SP2) {
;             PG8_LDB(B0, 0, 0); PG8_LDB(B1, 0, 1); PG8_SCHED; PG8_LDA(At, 0, 0); PG8_STAGE(PG8_SA(1, 1), a1 + hstep, voffA);
;             PG8_WAIT_V(8); PG8_WAIT_L(0); PG8_BAR; PG8_MMA(0, 0, At, B0); PG8_MMA(0, 1, At, B1); PG8_BAR; PG8_SCHED;
;             PG8_LDA(At, 0, 1); PG8_STAGE(PG8_SB(0, 0), b2, voffB); PG8_STAGE(PG8_SB(0, 1), b2 + hstep, voffB); PG8_STAGE(PG8_SA(0, 0), a2, voffA);
;             PG8_WAIT_V(8); PG8_WAIT_L(0); PG8_BAR; PG8_MMA(1, 0, At, B0); PG8_MMA(1, 1, At, B1); PG8_BAR; PG8_SCHED;
.LBB0_1118:
	s_ashr_i32 s45, s44, 31
	s_lshl_b64 s[48:49], s[44:45], 19
	s_add_u32 s48, s22, s48
	s_addc_u32 s49, s23, s49
	s_and_b64 s[50:51], s[10:11], exec
	s_cselect_b32 s45, s49, s55
	s_cselect_b32 s76, s48, s54
	s_ashr_i32 s43, s42, 31
	s_lshl_b64 s[50:51], s[42:43], 19
	s_add_u32 s50, s14, s50
	s_addc_u32 s51, s15, s51
	s_and_b64 s[58:59], s[10:11], exec
	s_cselect_b32 s43, s51, s57
	s_cselect_b32 s77, s50, s56
	s_add_u32 s54, s54, 0x40080
	s_addc_u32 s55, s55, 0
	s_add_u32 s82, s56, 0x100
	s_addc_u32 s83, s57, 0
	s_mov_b32 s84, -2
	ds_read_b128 v[144:147], v155
	ds_read_b128 v[148:151], v155 offset:1024
	ds_read_b128 v[160:163], v155 offset:2048
	ds_read_b128 v[164:167], v155 offset:3072
	ds_read_b128 v[168:171], v156
	ds_read_b128 v[172:175], v156 offset:1024
	ds_read_b128 v[176:179], v156 offset:2048
	ds_read_b128 v[182:185], v156 offset:3072
	s_add_u32 s56, s54, 0xfffc0080
	s_addc_u32 s57, s55, -1
	s_cmp_eq_u32 s84, 12
	s_cselect_b32 s59, s45, s57
	s_cselect_b32 s58, s76, s56
	s_cselect_b32 s57, s43, s83
	s_cselect_b32 s56, s77, s82
	v_lshl_add_u64 v[224:225], s[54:55], 0, v[136:137]
	s_add_i32 m0, s53, 0xc000
	ds_read_b128 v[186:189], v157
	ds_read_b128 v[190:193], v157 offset:1024
	ds_read_b128 v[194:197], v157 offset:2048
	ds_read_b128 v[198:201], v157 offset:3072
	ds_read_b128 v[208:211], v157 offset:4096
	ds_read_b128 v[212:215], v157 offset:5120
	ds_read_b128 v[216:219], v157 offset:6144
	ds_read_b128 v[220:223], v157 offset:7168
	global_load_lds_dwordx4 v[224:225], off
	v_lshl_add_u64 v[224:225], s[54:55], 0, v[138:139]
	s_add_i32 m0, s53, 0xe000
	s_nop 0
	global_load_lds_dwordx4 v[224:225], off
	s_waitcnt vmcnt(8)
	s_waitcnt lgkmcnt(0)
	s_barrier
	s_setprio 1
	s_waitcnt lgkmcnt(0)
	v_mfma_f32_16x16x32_bf16 v[124:127], v[144:147], v[186:189], 0
	v_mfma_f32_16x16x32_bf16 v[108:111], v[144:147], v[194:197], 0
	v_mfma_f32_16x16x32_bf16 v[120:123], v[160:163], v[186:189], 0
	v_mfma_f32_16x16x32_bf16 v[104:107], v[160:163], v[194:197], 0
	v_mfma_f32_16x16x32_bf16 v[92:95], v[144:147], v[208:211], 0
	v_mfma_f32_16x16x32_bf16 v[76:79], v[144:147], v[216:219], 0
	v_mfma_f32_16x16x32_bf16 v[88:91], v[160:163], v[208:211], 0
	v_mfma_f32_16x16x32_bf16 v[72:75], v[160:163], v[216:219], 0
	v_mfma_f32_16x16x32_bf16 v[124:127], v[148:151], v[190:193], v[124:127]
	v_mfma_f32_16x16x32_bf16 v[108:111], v[148:151], v[198:201], v[108:111]
	v_mfma_f32_16x16x32_bf16 v[120:123], v[164:167], v[190:193], v[120:123]
	v_mfma_f32_16x16x32_bf16 v[104:107], v[164:167], v[198:201], v[104:107]
	v_mfma_f32_16x16x32_bf16 v[92:95], v[148:151], v[212:215], v[92:95]
	v_mfma_f32_16x16x32_bf16 v[76:79], v[148:151], v[220:223], v[76:79]
	v_mfma_f32_16x16x32_bf16 v[88:91], v[164:167], v[212:215], v[88:91]
	v_mfma_f32_16x16x32_bf16 v[72:75], v[164:167], v[220:223], v[72:75]
	s_setprio 0
	s_setprio 1
	v_mfma_f32_16x16x32_bf16 v[116:119], v[168:171], v[186:189], 0
	v_mfma_f32_16x16x32_bf16 v[100:103], v[168:171], v[194:197], 0
	v_mfma_f32_16x16x32_bf16 v[112:115], v[176:179], v[186:189], 0
	v_mfma_f32_16x16x32_bf16 v[96:99], v[176:179], v[194:197], 0
	v_mfma_f32_16x16x32_bf16 v[84:87], v[168:171], v[208:211], 0
	v_mfma_f32_16x16x32_bf16 v[68:71], v[168:171], v[216:219], 0
	v_mfma_f32_16x16x32_bf16 v[80:83], v[176:179], v[208:211], 0
	v_mfma_f32_16x16x32_bf16 v[64:67], v[176:179], v[216:219], 0
	v_mfma_f32_16x16x32_bf16 v[116:119], v[172:175], v[190:193], v[116:119]
	v_mfma_f32_16x16x32_bf16 v[100:103], v[172:175], v[198:201], v[100:103]
	v_mfma_f32_16x16x32_bf16 v[112:115], v[182:185], v[190:193], v[112:115]
	v_mfma_f32_16x16x32_bf16 v[96:99], v[182:185], v[198:201], v[96:99]
	v_mfma_f32_16x16x32_bf16 v[84:87], v[172:175], v[212:215], v[84:87]
	v_mfma_f32_16x16x32_bf16 v[68:71], v[172:175], v[220:223], v[68:71]
	v_mfma_f32_16x16x32_bf16 v[80:83], v[182:185], v[212:215], v[80:83]
	v_mfma_f32_16x16x32_bf16 v[64:67], v[182:185], v[220:223], v[64:67]
	s_setprio 0
	s_barrier
	s_add_i32 s78, s66, s33
	v_lshl_add_u64 v[224:225], s[56:57], 0, v[132:133]
	s_mov_b32 m0, s78
	ds_read_b128 v[186:189], v157 offset:16384
	ds_read_b128 v[190:193], v157 offset:17408
	ds_read_b128 v[194:197], v157 offset:18432
	ds_read_b128 v[198:201], v157 offset:19456
	ds_read_b128 v[208:211], v157 offset:20480
	ds_read_b128 v[212:215], v157 offset:21504
	ds_read_b128 v[216:219], v157 offset:22528
	ds_read_b128 v[220:223], v157 offset:23552
	global_load_lds_dwordx4 v[224:225], off
	s_add_i32 m0, s78, 0x2000
	s_add_u32 s78, s56, 0x40000
	v_lshl_add_u64 v[226:227], s[56:57], 0, v[128:129]
	s_addc_u32 s79, s57, 0
	s_add_i32 s85, s67, s33
	global_load_lds_dwordx4 v[226:227], off
	v_lshl_add_u64 v[228:229], s[78:79], 0, v[132:133]
	s_mov_b32 m0, s85
	global_load_lds_dwordx4 v[228:229], off
	v_lshl_add_u64 v[228:229], s[78:79], 0, v[128:129]
	s_add_i32 m0, s85, 0x2000
	s_nop 0
	global_load_lds_dwordx4 v[228:229], off
	s_waitcnt vmcnt(6)
	s_waitcnt lgkmcnt(0)
	s_barrier
; #define PG8_STAGE(bufoff, gbase, voff) do { _Pragma("unroll") for (int _i = 0; _i < 2; ++_i) \
;         __builtin_amdgcn_global_load_lds((const unsigned*)((const char*)(gbase) + (voff)[_i]), (PG8_LAS unsigned*)(lds + (bufoff) + ldsw + _i * 8192), 16, 0, 0); } while (0)
; #define PG8_LDA(dst, b, h) do { _Pragma("unroll") for (int m = 0; m < 4; ++m) _Pragma("unroll") for (int k = 0; k < 2; ++k) dst[m][k] = *(const PG8_LAS bf16x8*)(lds + PG8_SA(b, h) + aoff + m * 2048 + k * 1024); } while (0)
; #define PG8_LDB(dst, b, h) do { _Pragma("unroll") for (int n = 0; n < 2; ++n) _Pragma("unroll") for (int k = 0; k < 2; ++k) dst[n][k] = *(const PG8_LAS bf16x8*)(lds + PG8_SB(b, h) + boff + n * 2048 + k * 1024); } while (0)
; #define PG8_MMA(ai, bj, At, Bt) do { __builtin_amdgcn_s_setprio(1); _Pragma("unroll") for (int m = 0; m < 4; ++m) _Pragma("unroll") for (int n = 0; n < 2; ++n) _Pragma("unroll") for (int k = 0; k < 2; ++k) \
;         acc[ai][bj][m][n] = __builtin_amdgcn_mfma_f32_16x16x32_bf16(Bt[n][k], At[m][k], acc[ai][bj][m][n], 0, 0, 0); __builtin_amdgcn_s_setprio(0); } while (0)
; #define PG8_WAIT_V(n) asm volatile("s_waitcnt vmcnt(" #n ")" ::: "memory")
; #define PG8_WAIT_L(n) asm volatile("s_waitcnt lgkmcnt(" #n ")" ::: "memory")
; #define PG8_BAR __builtin_amdgcn_s_barrier()
; #define PG8_SCHED __builtin_amdgcn_sched_barrier(0)
; template <class Epi, class Sched, bool ALIGN_EPI = false, bool SP2 = false>
; __device__ __forceinline__ void gemm_phase(PG8_LAS unsigned char* lds, const Gemm g, const Sched& S, const Epi& E) {
;     ...
;             PG8_WAIT_V(8); PG8_WAIT_L(0); PG8_BAR; PG8_MMA(1, 0, At, B0); PG8_MMA(1, 1, At, B1); PG8_BAR; PG8_SCHED;
;             PG8_LDB(B0, 1, 0); PG8_LDB(B1, 1, 1); PG8_SCHED; PG8_LDA(At, 1, 0); PG8_STAGE(PG8_SA(0, 1), a2 + hstep, voffA);
;             PG8_WAIT_V(8); PG8_WAIT_L(0); PG8_BAR; PG8_MMA(0, 0, At, B0); PG8_MMA(0, 1, At, B1); PG8_BAR; PG8_SCHED;
	s_setprio 1
	s_waitcnt lgkmcnt(0)
	v_mfma_f32_16x16x32_bf16 v[60:63], v[144:147], v[186:189], 0
	v_mfma_f32_16x16x32_bf16 v[44:47], v[144:147], v[194:197], 0
	v_mfma_f32_16x16x32_bf16 v[56:59], v[160:163], v[186:189], 0
	v_mfma_f32_16x16x32_bf16 v[40:43], v[160:163], v[194:197], 0
	v_mfma_f32_16x16x32_bf16 v[28:31], v[144:147], v[208:211], 0
	v_mfma_f32_16x16x32_bf16 v[12:15], v[144:147], v[216:219], 0
	v_mfma_f32_16x16x32_bf16 v[24:27], v[160:163], v[208:211], 0
	v_mfma_f32_16x16x32_bf16 v[8:11], v[160:163], v[216:219], 0
	v_mfma_f32_16x16x32_bf16 v[60:63], v[148:151], v[190:193], v[60:63]
	v_mfma_f32_16x16x32_bf16 v[44:47], v[148:151], v[198:201], v[44:47]
	v_mfma_f32_16x16x32_bf16 v[56:59], v[164:167], v[190:193], v[56:59]
	v_mfma_f32_16x16x32_bf16 v[40:43], v[164:167], v[198:201], v[40:43]
	v_mfma_f32_16x16x32_bf16 v[28:31], v[148:151], v[212:215], v[28:31]
	v_mfma_f32_16x16x32_bf16 v[12:15], v[148:151], v[220:223], v[12:15]
	v_lshl_add_u64 v[228:229], s[58:59], 0, v[134:135]
	s_mov_b32 m0, s53
	s_nop 0
	global_load_lds_dwordx4 v[228:229], off
	v_mfma_f32_16x16x32_bf16 v[24:27], v[164:167], v[212:215], v[24:27]
	v_mfma_f32_16x16x32_bf16 v[8:11], v[164:167], v[220:223], v[8:11]
	s_setprio 0
	s_setprio 1
	v_mfma_f32_16x16x32_bf16 v[52:55], v[168:171], v[186:189], 0
	v_mfma_f32_16x16x32_bf16 v[36:39], v[168:171], v[194:197], 0
	v_mfma_f32_16x16x32_bf16 v[48:51], v[176:179], v[186:189], 0
	v_mfma_f32_16x16x32_bf16 v[32:35], v[176:179], v[194:197], 0
	v_mfma_f32_16x16x32_bf16 v[20:23], v[168:171], v[208:211], 0
	v_mfma_f32_16x16x32_bf16 v[4:7], v[168:171], v[216:219], 0
	v_mfma_f32_16x16x32_bf16 v[16:19], v[176:179], v[208:211], 0
	v_mfma_f32_16x16x32_bf16 v[0:3], v[176:179], v[216:219], 0
	v_mfma_f32_16x16x32_bf16 v[52:55], v[172:175], v[190:193], v[52:55]
	v_mfma_f32_16x16x32_bf16 v[36:39], v[172:175], v[198:201], v[36:39]
	v_mfma_f32_16x16x32_bf16 v[48:51], v[182:185], v[190:193], v[48:51]
	v_mfma_f32_16x16x32_bf16 v[32:35], v[182:185], v[198:201], v[32:35]
	v_mfma_f32_16x16x32_bf16 v[20:23], v[172:175], v[212:215], v[20:23]
	v_mfma_f32_16x16x32_bf16 v[4:7], v[172:175], v[220:223], v[4:7]
	v_lshl_add_u64 v[230:231], s[58:59], 0, v[130:131]
	s_mov_b32 m0, s60
	s_nop 0
	global_load_lds_dwordx4 v[230:231], off
	v_mfma_f32_16x16x32_bf16 v[16:19], v[182:185], v[212:215], v[16:19]
	v_mfma_f32_16x16x32_bf16 v[0:3], v[182:185], v[220:223], v[0:3]
	s_setprio 0
	s_barrier
	s_add_i32 s78, 0, 0x18000
	v_add_u32_e32 v159, s78, v153
	s_add_i32 s79, 0, 0x1c000
	ds_read_b128 v[144:147], v159
	ds_read_b128 v[148:151], v159 offset:1024
	ds_read_b128 v[160:163], v159 offset:2048
	ds_read_b128 v[164:167], v159 offset:3072
	v_add_u32_e32 v159, s79, v153
	ds_read_b128 v[168:171], v159
	ds_read_b128 v[172:175], v159 offset:1024
	ds_read_b128 v[176:179], v159 offset:2048
	ds_read_b128 v[182:185], v159 offset:3072
	s_add_u32 s58, s58, 0x40000
	s_addc_u32 s59, s59, 0
	s_mov_b32 m0, s61
	v_lshl_add_u64 v[232:233], s[58:59], 0, v[134:135]
	ds_read_b128 v[186:189], v157 offset:32768
	ds_read_b128 v[190:193], v157 offset:33792
	ds_read_b128 v[194:197], v157 offset:34816
	ds_read_b128 v[198:201], v157 offset:35840
	ds_read_b128 v[208:211], v157 offset:36864
	ds_read_b128 v[212:215], v157 offset:37888
	ds_read_b128 v[216:219], v157 offset:38912
	ds_read_b128 v[220:223], v157 offset:39936
	global_load_lds_dwordx4 v[232:233], off
	v_lshl_add_u64 v[232:233], s[58:59], 0, v[130:131]
	s_mov_b32 m0, s62
	s_nop 0
	global_load_lds_dwordx4 v[232:233], off
	s_waitcnt vmcnt(8)
	s_waitcnt lgkmcnt(0)
	s_barrier
	s_setprio 1
	s_waitcnt lgkmcnt(0)
	v_mfma_f32_16x16x32_bf16 v[124:127], v[144:147], v[186:189], v[124:127]
	v_mfma_f32_16x16x32_bf16 v[108:111], v[144:147], v[194:197], v[108:111]
	v_mfma_f32_16x16x32_bf16 v[120:123], v[160:163], v[186:189], v[120:123]
	v_mfma_f32_16x16x32_bf16 v[104:107], v[160:163], v[194:197], v[104:107]
	v_mfma_f32_16x16x32_bf16 v[92:95], v[144:147], v[208:211], v[92:95]
	v_mfma_f32_16x16x32_bf16 v[76:79], v[144:147], v[216:219], v[76:79]
	v_mfma_f32_16x16x32_bf16 v[88:91], v[160:163], v[208:211], v[88:91]
	v_mfma_f32_16x16x32_bf16 v[72:75], v[160:163], v[216:219], v[72:75]
	v_mfma_f32_16x16x32_bf16 v[124:127], v[148:151], v[190:193], v[124:127]
	v_mfma_f32_16x16x32_bf16 v[108:111], v[148:151], v[198:201], v[108:111]
	v_mfma_f32_16x16x32_bf16 v[120:123], v[164:167], v[190:193], v[120:123]
	v_mfma_f32_16x16x32_bf16 v[104:107], v[164:167], v[198:201], v[104:107]
	v_mfma_f32_16x16x32_bf16 v[92:95], v[148:151], v[212:215], v[92:95]
	v_mfma_f32_16x16x32_bf16 v[76:79], v[148:151], v[220:223], v[76:79]
	v_mfma_f32_16x16x32_bf16 v[88:91], v[164:167], v[212:215], v[88:91]
	v_mfma_f32_16x16x32_bf16 v[72:75], v[164:167], v[220:223], v[72:75]
	s_setprio 0
	s_setprio 1
	v_mfma_f32_16x16x32_bf16 v[116:119], v[168:171], v[186:189], v[116:119]
	v_mfma_f32_16x16x32_bf16 v[100:103], v[168:171], v[194:197], v[100:103]
	v_mfma_f32_16x16x32_bf16 v[112:115], v[176:179], v[186:189], v[112:115]
	v_mfma_f32_16x16x32_bf16 v[96:99], v[176:179], v[194:197], v[96:99]
	v_mfma_f32_16x16x32_bf16 v[84:87], v[168:171], v[208:211], v[84:87]
	v_mfma_f32_16x16x32_bf16 v[68:71], v[168:171], v[216:219], v[68:71]
	v_mfma_f32_16x16x32_bf16 v[80:83], v[176:179], v[208:211], v[80:83]
	v_mfma_f32_16x16x32_bf16 v[64:67], v[176:179], v[216:219], v[64:67]
	v_mfma_f32_16x16x32_bf16 v[116:119], v[172:175], v[190:193], v[116:119]
	v_mfma_f32_16x16x32_bf16 v[100:103], v[172:175], v[198:201], v[100:103]
	v_mfma_f32_16x16x32_bf16 v[112:115], v[182:185], v[190:193], v[112:115]
	v_mfma_f32_16x16x32_bf16 v[96:99], v[182:185], v[198:201], v[96:99]
	v_mfma_f32_16x16x32_bf16 v[84:87], v[172:175], v[212:215], v[84:87]
	v_mfma_f32_16x16x32_bf16 v[68:71], v[172:175], v[220:223], v[68:71]
	v_mfma_f32_16x16x32_bf16 v[80:83], v[182:185], v[212:215], v[80:83]
	v_mfma_f32_16x16x32_bf16 v[64:67], v[182:185], v[220:223], v[64:67]
	s_setprio 0
	s_barrier
; #define PG8_STAGE(bufoff, gbase, voff) do { _Pragma("unroll") for (int _i = 0; _i < 2; ++_i) \
;         __builtin_amdgcn_global_load_lds((const unsigned*)((const char*)(gbase) + (voff)[_i]), (PG8_LAS unsigned*)(lds + (bufoff) + ldsw + _i * 8192), 16, 0, 0); } while (0)
; #define PG8_LDA(dst, b, h) do { _Pragma("unroll") for (int m = 0; m < 4; ++m) _Pragma("unroll") for (int k = 0; k < 2; ++k) dst[m][k] = *(const PG8_LAS bf16x8*)(lds + PG8_SA(b, h) + aoff + m * 2048 + k * 1024); } while (0)
; #define PG8_LDB(dst, b, h) do { _Pragma("unroll") for (int n = 0; n < 2; ++n) _Pragma("unroll") for (int k = 0; k < 2; ++k) dst[n][k] = *(const PG8_LAS bf16x8*)(lds + PG8_SB(b, h) + boff + n * 2048 + k * 1024); } while (0)
; #define PG8_MMA(ai, bj, At, Bt) do { __builtin_amdgcn_s_setprio(1); _Pragma("unroll") for (int m = 0; m < 4; ++m) _Pragma("unroll") for (int n = 0; n < 2; ++n) _Pragma("unroll") for (int k = 0; k < 2; ++k) \
;         acc[ai][bj][m][n] = __builtin_amdgcn_mfma_f32_16x16x32_bf16(Bt[n][k], At[m][k], acc[ai][bj][m][n], 0, 0, 0); __builtin_amdgcn_s_setprio(0); } while (0)
; #define PG8_WAIT_V(n) asm volatile("s_waitcnt vmcnt(" #n ")" ::: "memory")
; template <class Epi, class Sched, bool ALIGN_EPI = false, bool SP2 = false>
; __device__ __forceinline__ void gemm_phase(PG8_LAS unsigned char* lds, const Gemm g, const Sched& S, const Epi& E) {
;     ...
;             PG8_LDB(B0, 0, 0); PG8_LDB(B1, 0, 1); PG8_SCHED; PG8_LDA(At, 0, 0); PG8_STAGE(PG8_SA(1, 1), a1 + hstep, voffA);
;             PG8_WAIT_V(8); PG8_WAIT_L(0); PG8_BAR; PG8_MMA(0, 0, At, B0); PG8_MMA(0, 1, At, B1); PG8_BAR; PG8_SCHED;
;             PG8_LDA(At, 0, 1); PG8_STAGE(PG8_SB(0, 0), b2, voffB); PG8_STAGE(PG8_SB(0, 1), b2 + hstep, voffB); PG8_STAGE(PG8_SA(0, 0), a2, voffA);
;             PG8_WAIT_V(8); PG8_WAIT_L(0); PG8_BAR; PG8_MMA(1, 0, At, B0); PG8_MMA(1, 1, At, B1); PG8_BAR; PG8_SCHED;
;             PG8_LDB(B0, 1, 0); PG8_LDB(B1, 1, 1); PG8_SCHED; PG8_LDA(At, 1, 0); PG8_STAGE(PG8_SA(0, 1), a2 + hstep, voffA);
;             PG8_WAIT_V(8); PG8_WAIT_L(0); PG8_BAR; PG8_MMA(0, 0, At, B0); PG8_MMA(0, 1, At, B1); PG8_BAR; PG8_SCHED;
;             PG8_LDA(At, 1, 1); PG8_STAGE(PG8_SB(1, 0), b3, voffB); PG8_STAGE(PG8_SB(1, 1), b3 + hstep, voffB); PG8_STAGE(PG8_SA(1, 0), a3, voffA);
;             PG8_WAIT_V(8); PG8_WAIT_L(0); PG8_BAR; PG8_MMA(1, 0, At, B0); PG8_MMA(1, 1, At, B1); PG8_BAR; PG8_SCHED;
	s_add_i32 s58, s78, s33
	v_lshl_add_u64 v[224:225], v[224:225], 0, s[12:13]
	s_mov_b32 m0, s58
	ds_read_b128 v[186:189], v157 offset:49152
	ds_read_b128 v[190:193], v157 offset:50176
	ds_read_b128 v[194:197], v157 offset:51200
	ds_read_b128 v[198:201], v157 offset:52224
	ds_read_b128 v[208:211], v157 offset:53248
	ds_read_b128 v[212:215], v157 offset:54272
	ds_read_b128 v[216:219], v157 offset:55296
	ds_read_b128 v[220:223], v157 offset:56320
	global_load_lds_dwordx4 v[224:225], off
	s_add_i32 m0, s58, 0x2000
	s_add_u32 s56, s56, 0x40080
	v_lshl_add_u64 v[224:225], v[226:227], 0, s[12:13]
	s_addc_u32 s57, s57, 0
	s_add_i32 s58, s79, s33
	global_load_lds_dwordx4 v[224:225], off
	v_lshl_add_u64 v[224:225], s[56:57], 0, v[132:133]
	s_mov_b32 m0, s58
	s_nop 0
	global_load_lds_dwordx4 v[224:225], off
	v_lshl_add_u64 v[224:225], s[56:57], 0, v[128:129]
	s_add_i32 m0, s58, 0x2000
	s_nop 0
	global_load_lds_dwordx4 v[224:225], off
	s_waitcnt vmcnt(6)
	s_waitcnt lgkmcnt(0)
	s_barrier
	s_setprio 1
	s_waitcnt lgkmcnt(0)
	v_mfma_f32_16x16x32_bf16 v[60:63], v[144:147], v[186:189], v[60:63]
	v_mfma_f32_16x16x32_bf16 v[44:47], v[144:147], v[194:197], v[44:47]
	v_mfma_f32_16x16x32_bf16 v[56:59], v[160:163], v[186:189], v[56:59]
	v_mfma_f32_16x16x32_bf16 v[40:43], v[160:163], v[194:197], v[40:43]
	v_mfma_f32_16x16x32_bf16 v[28:31], v[144:147], v[208:211], v[28:31]
	v_mfma_f32_16x16x32_bf16 v[12:15], v[144:147], v[216:219], v[12:15]
	v_mfma_f32_16x16x32_bf16 v[24:27], v[160:163], v[208:211], v[24:27]
	v_mfma_f32_16x16x32_bf16 v[8:11], v[160:163], v[216:219], v[8:11]
	v_mfma_f32_16x16x32_bf16 v[60:63], v[148:151], v[190:193], v[60:63]
	v_mfma_f32_16x16x32_bf16 v[44:47], v[148:151], v[198:201], v[44:47]
	v_mfma_f32_16x16x32_bf16 v[56:59], v[164:167], v[190:193], v[56:59]
	v_mfma_f32_16x16x32_bf16 v[40:43], v[164:167], v[198:201], v[40:43]
	v_mfma_f32_16x16x32_bf16 v[28:31], v[148:151], v[212:215], v[28:31]
	v_mfma_f32_16x16x32_bf16 v[12:15], v[148:151], v[220:223], v[12:15]
	v_lshl_add_u64 v[224:225], v[228:229], 0, s[12:13]
	s_mov_b32 m0, s64
	s_nop 0
	global_load_lds_dwordx4 v[224:225], off
	v_mfma_f32_16x16x32_bf16 v[24:27], v[164:167], v[212:215], v[24:27]
	v_mfma_f32_16x16x32_bf16 v[8:11], v[164:167], v[220:223], v[8:11]
	s_setprio 0
	s_setprio 1
	v_mfma_f32_16x16x32_bf16 v[52:55], v[168:171], v[186:189], v[52:55]
	v_mfma_f32_16x16x32_bf16 v[36:39], v[168:171], v[194:197], v[36:39]
	v_mfma_f32_16x16x32_bf16 v[48:51], v[176:179], v[186:189], v[48:51]
	v_mfma_f32_16x16x32_bf16 v[32:35], v[176:179], v[194:197], v[32:35]
	v_mfma_f32_16x16x32_bf16 v[20:23], v[168:171], v[208:211], v[20:23]
	v_mfma_f32_16x16x32_bf16 v[4:7], v[168:171], v[216:219], v[4:7]
	v_mfma_f32_16x16x32_bf16 v[16:19], v[176:179], v[208:211], v[16:19]
	v_mfma_f32_16x16x32_bf16 v[0:3], v[176:179], v[216:219], v[0:3]
	v_mfma_f32_16x16x32_bf16 v[52:55], v[172:175], v[190:193], v[52:55]
	v_mfma_f32_16x16x32_bf16 v[36:39], v[172:175], v[198:201], v[36:39]
	v_mfma_f32_16x16x32_bf16 v[48:51], v[182:185], v[190:193], v[48:51]
	v_mfma_f32_16x16x32_bf16 v[32:35], v[182:185], v[198:201], v[32:35]
	v_mfma_f32_16x16x32_bf16 v[20:23], v[172:175], v[212:215], v[20:23]
	v_mfma_f32_16x16x32_bf16 v[4:7], v[172:175], v[220:223], v[4:7]
	v_lshl_add_u64 v[224:225], v[230:231], 0, s[12:13]
	s_mov_b32 m0, s65
	s_nop 0
	global_load_lds_dwordx4 v[224:225], off
	v_mfma_f32_16x16x32_bf16 v[16:19], v[182:185], v[212:215], v[16:19]
	v_mfma_f32_16x16x32_bf16 v[0:3], v[182:185], v[220:223], v[0:3]
	s_setprio 0
	s_barrier
	s_add_i32 s84, s84, 2
	s_add_u32 s54, s54, 0x100
	s_addc_u32 s55, s55, 0
	s_add_u32 s82, s82, 0x100
	s_addc_u32 s83, s83, 0
.LBB0_1119:
	ds_read_b128 v[144:147], v155
	ds_read_b128 v[148:151], v155 offset:1024
	ds_read_b128 v[160:163], v155 offset:2048
	ds_read_b128 v[164:167], v155 offset:3072
	ds_read_b128 v[168:171], v156
	ds_read_b128 v[172:175], v156 offset:1024
	ds_read_b128 v[176:179], v156 offset:2048
	ds_read_b128 v[182:185], v156 offset:3072
	s_add_u32 s56, s54, 0xfffc0080
	s_addc_u32 s57, s55, -1
	s_cmp_eq_u32 s84, 12
	s_cselect_b32 s59, s45, s57
	s_cselect_b32 s58, s76, s56
	s_cselect_b32 s57, s43, s83
	s_cselect_b32 s56, s77, s82
	v_lshl_add_u64 v[224:225], s[54:55], 0, v[136:137]
	s_add_i32 m0, s53, 0xc000
	ds_read_b128 v[186:189], v157
	ds_read_b128 v[190:193], v157 offset:1024
	ds_read_b128 v[194:197], v157 offset:2048
	ds_read_b128 v[198:201], v157 offset:3072
	ds_read_b128 v[208:211], v157 offset:4096
	ds_read_b128 v[212:215], v157 offset:5120
	ds_read_b128 v[216:219], v157 offset:6144
	ds_read_b128 v[220:223], v157 offset:7168
	global_load_lds_dwordx4 v[224:225], off
	v_lshl_add_u64 v[224:225], s[54:55], 0, v[138:139]
	s_add_i32 m0, s53, 0xe000
	s_nop 0
	global_load_lds_dwordx4 v[224:225], off
	s_waitcnt vmcnt(8)
	s_waitcnt lgkmcnt(0)
	s_barrier
; #define PG8_STAGE(bufoff, gbase, voff) do { _Pragma("unroll") for (int _i = 0; _i < 2; ++_i) \
;         __builtin_amdgcn_global_load_lds((const unsigned*)((const char*)(gbase) + (voff)[_i]), (PG8_LAS unsigned*)(lds + (bufoff) + ldsw + _i * 8192), 16, 0, 0); } while (0)
; #define PG8_LDA(dst, b, h) do { _Pragma("unroll") for (int m = 0; m < 4; ++m) _Pragma("unroll") for (int k = 0; k < 2; ++k) dst[m][k] = *(const PG8_LAS bf16x8*)(lds + PG8_SA(b, h) + aoff + m * 2048 + k * 1024); } while (0)
; #define PG8_MMA(ai, bj, At, Bt) do { __builtin_amdgcn_s_setprio(1); _Pragma("unroll") for (int m = 0; m < 4; ++m) _Pragma("unroll") for (int n = 0; n < 2; ++n) _Pragma("unroll") for (int k = 0; k < 2; ++k) \
;         acc[ai][bj][m][n] = __builtin_amdgcn_mfma_f32_16x16x32_bf16(Bt[n][k], At[m][k], acc[ai][bj][m][n], 0, 0, 0); __builtin_amdgcn_s_setprio(0); } while (0)
; #define PG8_WAIT_V(n) asm volatile("s_waitcnt vmcnt(" #n ")" ::: "memory")
; #define PG8_WAIT_L(n) asm volatile("s_waitcnt lgkmcnt(" #n ")" ::: "memory")
; #define PG8_BAR __builtin_amdgcn_s_barrier()
; #define PG8_SCHED __builtin_amdgcn_sched_barrier(0)
; template <class Epi, class Sched, bool ALIGN_EPI = false, bool SP2 = false>
; __device__ __forceinline__ void gemm_phase(PG8_LAS unsigned char* lds, const Gemm g, const Sched& S, const Epi& E) {
;     ...
;             PG8_WAIT_V(8); PG8_WAIT_L(0); PG8_BAR; PG8_MMA(0, 0, At, B0); PG8_MMA(0, 1, At, B1); PG8_BAR; PG8_SCHED;
;             PG8_LDA(At, 0, 1); PG8_STAGE(PG8_SB(0, 0), b2, voffB); PG8_STAGE(PG8_SB(0, 1), b2 + hstep, voffB); PG8_STAGE(PG8_SA(0, 0), a2, voffA);
;             PG8_WAIT_V(8); PG8_WAIT_L(0); PG8_BAR; PG8_MMA(1, 0, At, B0); PG8_MMA(1, 1, At, B1); PG8_BAR; PG8_SCHED;
	s_setprio 1
	s_waitcnt lgkmcnt(0)
	v_mfma_f32_16x16x32_bf16 v[124:127], v[144:147], v[186:189], v[124:127]
	v_mfma_f32_16x16x32_bf16 v[108:111], v[144:147], v[194:197], v[108:111]
	v_mfma_f32_16x16x32_bf16 v[120:123], v[160:163], v[186:189], v[120:123]
	v_mfma_f32_16x16x32_bf16 v[104:107], v[160:163], v[194:197], v[104:107]
	v_mfma_f32_16x16x32_bf16 v[92:95], v[144:147], v[208:211], v[92:95]
	v_mfma_f32_16x16x32_bf16 v[76:79], v[144:147], v[216:219], v[76:79]
	v_mfma_f32_16x16x32_bf16 v[88:91], v[160:163], v[208:211], v[88:91]
	v_mfma_f32_16x16x32_bf16 v[72:75], v[160:163], v[216:219], v[72:75]
	v_mfma_f32_16x16x32_bf16 v[124:127], v[148:151], v[190:193], v[124:127]
	v_mfma_f32_16x16x32_bf16 v[108:111], v[148:151], v[198:201], v[108:111]
	v_mfma_f32_16x16x32_bf16 v[120:123], v[164:167], v[190:193], v[120:123]
	v_mfma_f32_16x16x32_bf16 v[104:107], v[164:167], v[198:201], v[104:107]
	v_mfma_f32_16x16x32_bf16 v[92:95], v[148:151], v[212:215], v[92:95]
	v_mfma_f32_16x16x32_bf16 v[76:79], v[148:151], v[220:223], v[76:79]
	v_mfma_f32_16x16x32_bf16 v[88:91], v[164:167], v[212:215], v[88:91]
	v_mfma_f32_16x16x32_bf16 v[72:75], v[164:167], v[220:223], v[72:75]
	s_setprio 0
	s_setprio 1
	v_mfma_f32_16x16x32_bf16 v[116:119], v[168:171], v[186:189], v[116:119]
	v_mfma_f32_16x16x32_bf16 v[100:103], v[168:171], v[194:197], v[100:103]
	v_mfma_f32_16x16x32_bf16 v[112:115], v[176:179], v[186:189], v[112:115]
	v_mfma_f32_16x16x32_bf16 v[96:99], v[176:179], v[194:197], v[96:99]
	v_mfma_f32_16x16x32_bf16 v[84:87], v[168:171], v[208:211], v[84:87]
	v_mfma_f32_16x16x32_bf16 v[68:71], v[168:171], v[216:219], v[68:71]
	v_mfma_f32_16x16x32_bf16 v[80:83], v[176:179], v[208:211], v[80:83]
	v_mfma_f32_16x16x32_bf16 v[64:67], v[176:179], v[216:219], v[64:67]
	v_mfma_f32_16x16x32_bf16 v[116:119], v[172:175], v[190:193], v[116:119]
	v_mfma_f32_16x16x32_bf16 v[100:103], v[172:175], v[198:201], v[100:103]
	v_mfma_f32_16x16x32_bf16 v[112:115], v[182:185], v[190:193], v[112:115]
	v_mfma_f32_16x16x32_bf16 v[96:99], v[182:185], v[198:201], v[96:99]
	v_mfma_f32_16x16x32_bf16 v[84:87], v[172:175], v[212:215], v[84:87]
	v_mfma_f32_16x16x32_bf16 v[68:71], v[172:175], v[220:223], v[68:71]
	v_mfma_f32_16x16x32_bf16 v[80:83], v[182:185], v[212:215], v[80:83]
	v_mfma_f32_16x16x32_bf16 v[64:67], v[182:185], v[220:223], v[64:67]
	s_setprio 0
	s_barrier
	s_add_i32 s78, s66, s33
	v_lshl_add_u64 v[224:225], s[56:57], 0, v[132:133]
	s_mov_b32 m0, s78
	ds_read_b128 v[186:189], v157 offset:16384
	ds_read_b128 v[190:193], v157 offset:17408
	ds_read_b128 v[194:197], v157 offset:18432
	ds_read_b128 v[198:201], v157 offset:19456
	ds_read_b128 v[208:211], v157 offset:20480
	ds_read_b128 v[212:215], v157 offset:21504
	ds_read_b128 v[216:219], v157 offset:22528
	ds_read_b128 v[220:223], v157 offset:23552
	global_load_lds_dwordx4 v[224:225], off
	s_add_i32 m0, s78, 0x2000
	s_add_u32 s78, s56, 0x40000
	v_lshl_add_u64 v[226:227], s[56:57], 0, v[128:129]
	s_addc_u32 s79, s57, 0
	s_add_i32 s85, s67, s33
	global_load_lds_dwordx4 v[226:227], off
	v_lshl_add_u64 v[228:229], s[78:79], 0, v[132:133]
	s_mov_b32 m0, s85
	global_load_lds_dwordx4 v[228:229], off
	v_lshl_add_u64 v[228:229], s[78:79], 0, v[128:129]
	s_add_i32 m0, s85, 0x2000
	s_nop 0
	global_load_lds_dwordx4 v[228:229], off
	s_waitcnt vmcnt(6)
	s_waitcnt lgkmcnt(0)
	s_barrier
	s_setprio 1
	s_waitcnt lgkmcnt(0)
	v_mfma_f32_16x16x32_bf16 v[60:63], v[144:147], v[186:189], v[60:63]
	v_mfma_f32_16x16x32_bf16 v[44:47], v[144:147], v[194:197], v[44:47]
	v_mfma_f32_16x16x32_bf16 v[56:59], v[160:163], v[186:189], v[56:59]
	v_mfma_f32_16x16x32_bf16 v[40:43], v[160:163], v[194:197], v[40:43]
	v_mfma_f32_16x16x32_bf16 v[28:31], v[144:147], v[208:211], v[28:31]
	v_mfma_f32_16x16x32_bf16 v[12:15], v[144:147], v[216:219], v[12:15]
	v_mfma_f32_16x16x32_bf16 v[24:27], v[160:163], v[208:211], v[24:27]
	v_mfma_f32_16x16x32_bf16 v[8:11], v[160:163], v[216:219], v[8:11]
	v_mfma_f32_16x16x32_bf16 v[60:63], v[148:151], v[190:193], v[60:63]
	v_mfma_f32_16x16x32_bf16 v[44:47], v[148:151], v[198:201], v[44:47]
	v_mfma_f32_16x16x32_bf16 v[56:59], v[164:167], v[190:193], v[56:59]
	v_mfma_f32_16x16x32_bf16 v[40:43], v[164:167], v[198:201], v[40:43]
	v_mfma_f32_16x16x32_bf16 v[28:31], v[148:151], v[212:215], v[28:31]
	v_mfma_f32_16x16x32_bf16 v[12:15], v[148:151], v[220:223], v[12:15]
	v_lshl_add_u64 v[228:229], s[58:59], 0, v[134:135]
	s_mov_b32 m0, s53
	s_nop 0
	global_load_lds_dwordx4 v[228:229], off
	v_mfma_f32_16x16x32_bf16 v[24:27], v[164:167], v[212:215], v[24:27]
	v_mfma_f32_16x16x32_bf16 v[8:11], v[164:167], v[220:223], v[8:11]
	s_setprio 0
	s_setprio 1
	v_mfma_f32_16x16x32_bf16 v[52:55], v[168:171], v[186:189], v[52:55]
	v_mfma_f32_16x16x32_bf16 v[36:39], v[168:171], v[194:197], v[36:39]
	v_mfma_f32_16x16x32_bf16 v[48:51], v[176:179], v[186:189], v[48:51]
	v_mfma_f32_16x16x32_bf16 v[32:35], v[176:179], v[194:197], v[32:35]
	v_mfma_f32_16x16x32_bf16 v[20:23], v[168:171], v[208:211], v[20:23]
	v_mfma_f32_16x16x32_bf16 v[4:7], v[168:171], v[216:219], v[4:7]
	v_mfma_f32_16x16x32_bf16 v[16:19], v[176:179], v[208:211], v[16:19]
	v_mfma_f32_16x16x32_bf16 v[0:3], v[176:179], v[216:219], v[0:3]
	v_mfma_f32_16x16x32_bf16 v[52:55], v[172:175], v[190:193], v[52:55]
	v_mfma_f32_16x16x32_bf16 v[36:39], v[172:175], v[198:201], v[36:39]
	v_mfma_f32_16x16x32_bf16 v[48:51], v[182:185], v[190:193], v[48:51]
	v_mfma_f32_16x16x32_bf16 v[32:35], v[182:185], v[198:201], v[32:35]
	v_mfma_f32_16x16x32_bf16 v[20:23], v[172:175], v[212:215], v[20:23]
	v_mfma_f32_16x16x32_bf16 v[4:7], v[172:175], v[220:223], v[4:7]
	v_lshl_add_u64 v[230:231], s[58:59], 0, v[130:131]
	s_mov_b32 m0, s60
	s_nop 0
	global_load_lds_dwordx4 v[230:231], off
	v_mfma_f32_16x16x32_bf16 v[16:19], v[182:185], v[212:215], v[16:19]
	v_mfma_f32_16x16x32_bf16 v[0:3], v[182:185], v[220:223], v[0:3]
	s_setprio 0
	s_barrier
; #define PG8_STAGE(bufoff, gbase, voff) do { _Pragma("unroll") for (int _i = 0; _i < 2; ++_i) \
;         __builtin_amdgcn_global_load_lds((const unsigned*)((const char*)(gbase) + (voff)[_i]), (PG8_LAS unsigned*)(lds + (bufoff) + ldsw + _i * 8192), 16, 0, 0); } while (0)
; #define PG8_LDA(dst, b, h) do { _Pragma("unroll") for (int m = 0; m < 4; ++m) _Pragma("unroll") for (int k = 0; k < 2; ++k) dst[m][k] = *(const PG8_LAS bf16x8*)(lds + PG8_SA(b, h) + aoff + m * 2048 + k * 1024); } while (0)
; #define PG8_LDB(dst, b, h) do { _Pragma("unroll") for (int n = 0; n < 2; ++n) _Pragma("unroll") for (int k = 0; k < 2; ++k) dst[n][k] = *(const PG8_LAS bf16x8*)(lds + PG8_SB(b, h) + boff + n * 2048 + k * 1024); } while (0)
; #define PG8_MMA(ai, bj, At, Bt) do { __builtin_amdgcn_s_setprio(1); _Pragma("unroll") for (int m = 0; m < 4; ++m) _Pragma("unroll") for (int n = 0; n < 2; ++n) _Pragma("unroll") for (int k = 0; k < 2; ++k) \
;         acc[ai][bj][m][n] = __builtin_amdgcn_mfma_f32_16x16x32_bf16(Bt[n][k], At[m][k], acc[ai][bj][m][n], 0, 0, 0); __builtin_amdgcn_s_setprio(0); } while (0)
; #define PG8_WAIT_V(n) asm volatile("s_waitcnt vmcnt(" #n ")" ::: "memory")
; #define PG8_WAIT_L(n) asm volatile("s_waitcnt lgkmcnt(" #n ")" ::: "memory")
; #define PG8_BAR __builtin_amdgcn_s_barrier()
; #define PG8_SCHED __builtin_amdgcn_sched_barrier(0)
; template <class Epi, class Sched, bool ALIGN_EPI = false, bool SP2 = false>
; __device__ __forceinline__ void gemm_phase(PG8_LAS unsigned char* lds, const Gemm g, const Sched& S, const Epi& E) {
;     ...
;             PG8_LDB(B0, 1, 0); PG8_LDB(B1, 1, 1); PG8_SCHED; PG8_LDA(At, 1, 0); PG8_STAGE(PG8_SA(0, 1), a2 + hstep, voffA);
;             PG8_WAIT_V(8); PG8_WAIT_L(0); PG8_BAR; PG8_MMA(0, 0, At, B0); PG8_MMA(0, 1, At, B1); PG8_BAR; PG8_SCHED;
	s_add_i32 s78, 0, 0x18000
	v_add_u32_e32 v159, s78, v153
	s_add_i32 s79, 0, 0x1c000
	ds_read_b128 v[144:147], v159
	ds_read_b128 v[148:151], v159 offset:1024
	ds_read_b128 v[160:163], v159 offset:2048
	ds_read_b128 v[164:167], v159 offset:3072
	v_add_u32_e32 v159, s79, v153
	ds_read_b128 v[168:171], v159
	ds_read_b128 v[172:175], v159 offset:1024
	ds_read_b128 v[176:179], v159 offset:2048
	ds_read_b128 v[182:185], v159 offset:3072
	s_add_u32 s58, s58, 0x40000
	s_addc_u32 s59, s59, 0
	s_mov_b32 m0, s61
	v_lshl_add_u64 v[232:233], s[58:59], 0, v[134:135]
	ds_read_b128 v[186:189], v157 offset:32768
	ds_read_b128 v[190:193], v157 offset:33792
	ds_read_b128 v[194:197], v157 offset:34816
	ds_read_b128 v[198:201], v157 offset:35840
	ds_read_b128 v[208:211], v157 offset:36864
	ds_read_b128 v[212:215], v157 offset:37888
	ds_read_b128 v[216:219], v157 offset:38912
	ds_read_b128 v[220:223], v157 offset:39936
	global_load_lds_dwordx4 v[232:233], off
	v_lshl_add_u64 v[232:233], s[58:59], 0, v[130:131]
	s_mov_b32 m0, s62
	s_nop 0
	global_load_lds_dwordx4 v[232:233], off
	s_waitcnt vmcnt(8)
	s_waitcnt lgkmcnt(0)
	s_barrier
	s_setprio 1
	s_waitcnt lgkmcnt(0)
	v_mfma_f32_16x16x32_bf16 v[124:127], v[144:147], v[186:189], v[124:127]
	v_mfma_f32_16x16x32_bf16 v[108:111], v[144:147], v[194:197], v[108:111]
	v_mfma_f32_16x16x32_bf16 v[120:123], v[160:163], v[186:189], v[120:123]
	v_mfma_f32_16x16x32_bf16 v[104:107], v[160:163], v[194:197], v[104:107]
	v_mfma_f32_16x16x32_bf16 v[92:95], v[144:147], v[208:211], v[92:95]
	v_mfma_f32_16x16x32_bf16 v[76:79], v[144:147], v[216:219], v[76:79]
	v_mfma_f32_16x16x32_bf16 v[88:91], v[160:163], v[208:211], v[88:91]
	v_mfma_f32_16x16x32_bf16 v[72:75], v[160:163], v[216:219], v[72:75]
	v_mfma_f32_16x16x32_bf16 v[124:127], v[148:151], v[190:193], v[124:127]
	v_mfma_f32_16x16x32_bf16 v[108:111], v[148:151], v[198:201], v[108:111]
	v_mfma_f32_16x16x32_bf16 v[120:123], v[164:167], v[190:193], v[120:123]
	v_mfma_f32_16x16x32_bf16 v[104:107], v[164:167], v[198:201], v[104:107]
	v_mfma_f32_16x16x32_bf16 v[92:95], v[148:151], v[212:215], v[92:95]
	v_mfma_f32_16x16x32_bf16 v[76:79], v[148:151], v[220:223], v[76:79]
	v_mfma_f32_16x16x32_bf16 v[88:91], v[164:167], v[212:215], v[88:91]
	v_mfma_f32_16x16x32_bf16 v[72:75], v[164:167], v[220:223], v[72:75]
	s_setprio 0
	s_setprio 1
	v_mfma_f32_16x16x32_bf16 v[116:119], v[168:171], v[186:189], v[116:119]
	v_mfma_f32_16x16x32_bf16 v[100:103], v[168:171], v[194:197], v[100:103]
	v_mfma_f32_16x16x32_bf16 v[112:115], v[176:179], v[186:189], v[112:115]
	v_mfma_f32_16x16x32_bf16 v[96:99], v[176:179], v[194:197], v[96:99]
	v_mfma_f32_16x16x32_bf16 v[84:87], v[168:171], v[208:211], v[84:87]
	v_mfma_f32_16x16x32_bf16 v[68:71], v[168:171], v[216:219], v[68:71]
	v_mfma_f32_16x16x32_bf16 v[80:83], v[176:179], v[208:211], v[80:83]
	v_mfma_f32_16x16x32_bf16 v[64:67], v[176:179], v[216:219], v[64:67]
	v_mfma_f32_16x16x32_bf16 v[116:119], v[172:175], v[190:193], v[116:119]
	v_mfma_f32_16x16x32_bf16 v[100:103], v[172:175], v[198:201], v[100:103]
	v_mfma_f32_16x16x32_bf16 v[112:115], v[182:185], v[190:193], v[112:115]
	v_mfma_f32_16x16x32_bf16 v[96:99], v[182:185], v[198:201], v[96:99]
	v_mfma_f32_16x16x32_bf16 v[84:87], v[172:175], v[212:215], v[84:87]
	v_mfma_f32_16x16x32_bf16 v[68:71], v[172:175], v[220:223], v[68:71]
	v_mfma_f32_16x16x32_bf16 v[80:83], v[182:185], v[212:215], v[80:83]
	v_mfma_f32_16x16x32_bf16 v[64:67], v[182:185], v[220:223], v[64:67]
	s_setprio 0
	s_barrier
; #define PG8_STAGE(bufoff, gbase, voff) do { _Pragma("unroll") for (int _i = 0; _i < 2; ++_i) \
;         __builtin_amdgcn_global_load_lds((const unsigned*)((const char*)(gbase) + (voff)[_i]), (PG8_LAS unsigned*)(lds + (bufoff) + ldsw + _i * 8192), 16, 0, 0); } while (0)
; #define PG8_LDA(dst, b, h) do { _Pragma("unroll") for (int m = 0; m < 4; ++m) _Pragma("unroll") for (int k = 0; k < 2; ++k) dst[m][k] = *(const PG8_LAS bf16x8*)(lds + PG8_SA(b, h) + aoff + m * 2048 + k * 1024); } while (0)
; #define PG8_MMA(ai, bj, At, Bt) do { __builtin_amdgcn_s_setprio(1); _Pragma("unroll") for (int m = 0; m < 4; ++m) _Pragma("unroll") for (int n = 0; n < 2; ++n) _Pragma("unroll") for (int k = 0; k < 2; ++k) \
;         acc[ai][bj][m][n] = __builtin_amdgcn_mfma_f32_16x16x32_bf16(Bt[n][k], At[m][k], acc[ai][bj][m][n], 0, 0, 0); __builtin_amdgcn_s_setprio(0); } while (0)
; #define PG8_WAIT_V(n) asm volatile("s_waitcnt vmcnt(" #n ")" ::: "memory")
; #define PG8_WAIT_L(n) asm volatile("s_waitcnt lgkmcnt(" #n ")" ::: "memory")
; #define PG8_BAR __builtin_amdgcn_s_barrier()
; #define PG8_SCHED __builtin_amdgcn_sched_barrier(0)
; __device__ __forceinline__ float row_rs(const float* ssp, int row) { const unsigned long long v = ((const unsigned long long*)ssp)[row];
;     return __builtin_amdgcn_rsqf((float)v * (1.0f / 4294967296.0f) * (1.0f / 1024.0f) + RMS_EPS); }
; template <class Epi, class Sched, bool ALIGN_EPI = false, bool SP2 = false>
; __device__ __forceinline__ void gemm_phase(PG8_LAS unsigned char* lds, const Gemm g, const Sched& S, const Epi& E) {
;     ...
;             PG8_LDA(At, 1, 1); PG8_STAGE(PG8_SB(1, 0), b3, voffB); PG8_STAGE(PG8_SB(1, 1), b3 + hstep, voffB); PG8_STAGE(PG8_SA(1, 0), a3, voffA);
;             PG8_WAIT_V(8); PG8_WAIT_L(0); PG8_BAR; PG8_MMA(1, 0, At, B0); PG8_MMA(1, 1, At, B1); PG8_BAR; PG8_SCHED;
	s_add_i32 s58, s78, s33
	v_lshl_add_u64 v[224:225], v[224:225], 0, s[12:13]
	s_mov_b32 m0, s58
	ds_read_b128 v[186:189], v157 offset:49152
	ds_read_b128 v[190:193], v157 offset:50176
	ds_read_b128 v[194:197], v157 offset:51200
	ds_read_b128 v[198:201], v157 offset:52224
	ds_read_b128 v[208:211], v157 offset:53248
	ds_read_b128 v[212:215], v157 offset:54272
	ds_read_b128 v[216:219], v157 offset:55296
	ds_read_b128 v[220:223], v157 offset:56320
	global_load_lds_dwordx4 v[224:225], off
	s_add_i32 m0, s58, 0x2000
	s_add_u32 s56, s56, 0x40080
	v_lshl_add_u64 v[224:225], v[226:227], 0, s[12:13]
	s_addc_u32 s57, s57, 0
	s_add_i32 s58, s79, s33
	global_load_lds_dwordx4 v[224:225], off
	v_lshl_add_u64 v[224:225], s[56:57], 0, v[132:133]
	s_mov_b32 m0, s58
	s_nop 0
	global_load_lds_dwordx4 v[224:225], off
	v_lshl_add_u64 v[224:225], s[56:57], 0, v[128:129]
	s_add_i32 m0, s58, 0x2000
	s_nop 0
	global_load_lds_dwordx4 v[224:225], off
	s_waitcnt vmcnt(6)
	s_waitcnt lgkmcnt(0)
	s_barrier
	s_setprio 1
	s_waitcnt lgkmcnt(0)
	v_mfma_f32_16x16x32_bf16 v[60:63], v[144:147], v[186:189], v[60:63]
	v_mfma_f32_16x16x32_bf16 v[44:47], v[144:147], v[194:197], v[44:47]
	v_mfma_f32_16x16x32_bf16 v[56:59], v[160:163], v[186:189], v[56:59]
	v_mfma_f32_16x16x32_bf16 v[40:43], v[160:163], v[194:197], v[40:43]
	v_mfma_f32_16x16x32_bf16 v[28:31], v[144:147], v[208:211], v[28:31]
	v_mfma_f32_16x16x32_bf16 v[12:15], v[144:147], v[216:219], v[12:15]
	v_mfma_f32_16x16x32_bf16 v[24:27], v[160:163], v[208:211], v[24:27]
	v_mfma_f32_16x16x32_bf16 v[8:11], v[160:163], v[216:219], v[8:11]
	v_mfma_f32_16x16x32_bf16 v[60:63], v[148:151], v[190:193], v[60:63]
	v_mfma_f32_16x16x32_bf16 v[44:47], v[148:151], v[198:201], v[44:47]
	v_mfma_f32_16x16x32_bf16 v[56:59], v[164:167], v[190:193], v[56:59]
	v_mfma_f32_16x16x32_bf16 v[40:43], v[164:167], v[198:201], v[40:43]
	v_mfma_f32_16x16x32_bf16 v[28:31], v[148:151], v[212:215], v[28:31]
	v_mfma_f32_16x16x32_bf16 v[12:15], v[148:151], v[220:223], v[12:15]
	v_lshl_add_u64 v[224:225], v[228:229], 0, s[12:13]
	s_mov_b32 m0, s64
	s_nop 0
	global_load_lds_dwordx4 v[224:225], off
	v_mfma_f32_16x16x32_bf16 v[24:27], v[164:167], v[212:215], v[24:27]
	v_mfma_f32_16x16x32_bf16 v[8:11], v[164:167], v[220:223], v[8:11]
	s_setprio 0
	s_setprio 1
	v_mfma_f32_16x16x32_bf16 v[52:55], v[168:171], v[186:189], v[52:55]
	v_mfma_f32_16x16x32_bf16 v[36:39], v[168:171], v[194:197], v[36:39]
	v_mfma_f32_16x16x32_bf16 v[48:51], v[176:179], v[186:189], v[48:51]
	v_mfma_f32_16x16x32_bf16 v[32:35], v[176:179], v[194:197], v[32:35]
	v_mfma_f32_16x16x32_bf16 v[20:23], v[168:171], v[208:211], v[20:23]
	v_mfma_f32_16x16x32_bf16 v[4:7], v[168:171], v[216:219], v[4:7]
	v_mfma_f32_16x16x32_bf16 v[16:19], v[176:179], v[208:211], v[16:19]
	v_mfma_f32_16x16x32_bf16 v[0:3], v[176:179], v[216:219], v[0:3]
	v_mfma_f32_16x16x32_bf16 v[52:55], v[172:175], v[190:193], v[52:55]
	v_mfma_f32_16x16x32_bf16 v[36:39], v[172:175], v[198:201], v[36:39]
	v_mfma_f32_16x16x32_bf16 v[48:51], v[182:185], v[190:193], v[48:51]
	v_mfma_f32_16x16x32_bf16 v[32:35], v[182:185], v[198:201], v[32:35]
	v_mfma_f32_16x16x32_bf16 v[20:23], v[172:175], v[212:215], v[20:23]
	v_mfma_f32_16x16x32_bf16 v[4:7], v[172:175], v[220:223], v[4:7]
	v_lshl_add_u64 v[224:225], v[230:231], 0, s[12:13]
	s_mov_b32 m0, s65
	s_nop 0
	global_load_lds_dwordx4 v[224:225], off
	v_mfma_f32_16x16x32_bf16 v[16:19], v[182:185], v[212:215], v[16:19]
	v_mfma_f32_16x16x32_bf16 v[0:3], v[182:185], v[220:223], v[0:3]
	s_setprio 0
	s_barrier
	s_add_i32 s84, s84, 2
	s_add_u32 s54, s54, 0x100
	s_addc_u32 s55, s55, 0
	s_add_u32 s82, s82, 0x100
	s_addc_u32 s83, s83, 0
	s_cmp_gt_u32 s84, 13
	s_cbranch_scc0 .LBB0_1119
	v_lshl_add_u32 v144, s52, 8, v152
	v_ashrrev_i32_e32 v145, 31, v144
	v_lshl_add_u64 v[150:151], v[144:145], 3, s[36:37]
	global_load_dwordx2 v[182:183], v[150:151], off
	global_load_dwordx2 v[184:185], v[150:151], off offset:128
	global_load_dwordx2 v[186:187], v[150:151], off offset:256
	global_load_dwordx2 v[188:189], v[150:151], off offset:384
	global_load_dwordx2 v[190:191], v[150:151], off offset:1024
	global_load_dwordx2 v[192:193], v[150:151], off offset:1152
	global_load_dwordx2 v[194:195], v[150:151], off offset:1280
	global_load_dwordx2 v[196:197], v[150:151], off offset:1408
	s_and_b64 vcc, exec, s[38:39]
	s_cbranch_vccz .LBB0_1122
	s_barrier

; #define PG8_STAGE(bufoff, gbase, voff) do { _Pragma("unroll") for (int _i = 0; _i < 2; ++_i) \
;         __builtin_amdgcn_global_load_lds((const unsigned*)((const char*)(gbase) + (voff)[_i]), (PG8_LAS unsigned*)(lds + (bufoff) + ldsw + _i * 8192), 16, 0, 0); } while (0)
; #define PG8_LDA(dst, b, h) do { _Pragma("unroll") for (int m = 0; m < 4; ++m) _Pragma("unroll") for (int k = 0; k < 2; ++k) dst[m][k] = *(const PG8_LAS bf16x8*)(lds + PG8_SA(b, h) + aoff + m * 2048 + k * 1024); } while (0)
; #define PG8_LDB(dst, b, h) do { _Pragma("unroll") for (int n = 0; n < 2; ++n) _Pragma("unroll") for (int k = 0; k < 2; ++k) dst[n][k] = *(const PG8_LAS bf16x8*)(lds + PG8_SB(b, h) + boff + n * 2048 + k * 1024); } while (0)
; #define PG8_MMA(ai, bj, At, Bt) do { __builtin_amdgcn_s_setprio(1); _Pragma("unroll") for (int m = 0; m < 4; ++m) _Pragma("unroll") for (int n = 0; n < 2; ++n) _Pragma("unroll") for (int k = 0; k < 2; ++k) \
;         acc[ai][bj][m][n] = __builtin_amdgcn_mfma_f32_16x16x32_bf16(Bt[n][k], At[m][k], acc[ai][bj][m][n], 0, 0, 0); __builtin_amdgcn_s_setprio(0); } while (0)
; #define PG8_WAIT_V(n) asm volatile("s_waitcnt vmcnt(" #n ")" ::: "memory")
; #define PG8_BAR __builtin_amdgcn_s_barrier()
; template <class Epi, class Sched, bool ALIGN_EPI = false, bool SP2 = false>
; __device__ __forceinline__ void gemm_phase(PG8_LAS unsigned char* lds, const Gemm g, const Sched& S, const Epi& E) {
;     ...
;         for (int t = 0; t < nt; t += 2) {
;             const bool last = (t == nt - 2);
;             const char* a1 = cA + (size_t)(t + 1) * kstep;
;             const char* a2 = last ? nA : cA + (size_t)(t + 2) * kstep; const char* b2 = last ? nB : cB + (size_t)(t + 2) * kstep;
;             const char* a3 = a2 + kstep; const char* b3 = b2 + kstep;
;             if (last && has_next) S.a_ready(nxt);
;             if constexpr (SP2) {
;             PG8_LDB(B0, 0, 0); PG8_LDB(B1, 0, 1); PG8_SCHED; PG8_LDA(At, 0, 0); PG8_STAGE(PG8_SA(1, 1), a1 + hstep, voffA);
;             PG8_WAIT_V(8); PG8_WAIT_L(0); PG8_BAR; PG8_MMA(0, 0, At, B0); PG8_MMA(0, 1, At, B1); PG8_BAR; PG8_SCHED;
;             PG8_LDA(At, 0, 1); PG8_STAGE(PG8_SB(0, 0), b2, voffB); PG8_STAGE(PG8_SB(0, 1), b2 + hstep, voffB); PG8_STAGE(PG8_SA(0, 0), a2, voffA);
;             PG8_WAIT_V(8); PG8_WAIT_L(0); PG8_BAR; PG8_MMA(1, 0, At, B0); PG8_MMA(1, 1, At, B1); PG8_BAR; PG8_SCHED;
.LBB0_1196:
	s_add_u32 s82, s52, 0x100
	s_addc_u32 s83, s53, 0
	s_mov_b32 s84, -2
	s_waitcnt lgkmcnt(0)
	ds_read_b128 v[144:147], v151
	ds_read_b128 v[156:159], v151 offset:1024
	ds_read_b128 v[160:163], v151 offset:2048
	ds_read_b128 v[164:167], v151 offset:3072
	ds_read_b128 v[168:171], v152
	ds_read_b128 v[172:175], v152 offset:1024
	ds_read_b128 v[176:179], v152 offset:2048
	ds_read_b128 v[182:185], v152 offset:3072
	s_add_u32 s52, s50, 0x100
	s_addc_u32 s53, s51, 0
	s_cmp_eq_u32 s84, 40
	s_cselect_b32 s57, s1, s53
	s_cselect_b32 s56, s0, s52
	s_cselect_b32 s55, s49, s83
	s_cselect_b32 s54, s48, s82
	v_lshl_add_u64 v[224:225], s[50:51], 0, v[136:137]
	s_add_i32 m0, s34, 0xc000
	ds_read_b128 v[186:189], v153
	ds_read_b128 v[190:193], v153 offset:1024
	ds_read_b128 v[194:197], v153 offset:2048
	ds_read_b128 v[198:201], v153 offset:3072
	ds_read_b128 v[208:211], v153 offset:4096
	ds_read_b128 v[212:215], v153 offset:5120
	ds_read_b128 v[216:219], v153 offset:6144
	ds_read_b128 v[220:223], v153 offset:7168
	global_load_lds_dwordx4 v[224:225], off
	v_lshl_add_u64 v[224:225], s[50:51], 0, v[138:139]
	s_add_i32 m0, s34, 0xe000
	s_nop 0
	global_load_lds_dwordx4 v[224:225], off
	s_waitcnt vmcnt(8)
	s_waitcnt lgkmcnt(0)
	s_barrier
	s_setprio 1
	s_waitcnt lgkmcnt(0)
	v_mfma_f32_16x16x32_bf16 v[124:127], v[144:147], v[186:189], 0
	v_mfma_f32_16x16x32_bf16 v[108:111], v[144:147], v[194:197], 0
	v_mfma_f32_16x16x32_bf16 v[120:123], v[160:163], v[186:189], 0
	v_mfma_f32_16x16x32_bf16 v[104:107], v[160:163], v[194:197], 0
	v_mfma_f32_16x16x32_bf16 v[92:95], v[144:147], v[208:211], 0
	v_mfma_f32_16x16x32_bf16 v[76:79], v[144:147], v[216:219], 0
	v_mfma_f32_16x16x32_bf16 v[88:91], v[160:163], v[208:211], 0
	v_mfma_f32_16x16x32_bf16 v[72:75], v[160:163], v[216:219], 0
	v_mfma_f32_16x16x32_bf16 v[124:127], v[156:159], v[190:193], v[124:127]
	v_mfma_f32_16x16x32_bf16 v[108:111], v[156:159], v[198:201], v[108:111]
	v_mfma_f32_16x16x32_bf16 v[120:123], v[164:167], v[190:193], v[120:123]
	v_mfma_f32_16x16x32_bf16 v[104:107], v[164:167], v[198:201], v[104:107]
	v_mfma_f32_16x16x32_bf16 v[92:95], v[156:159], v[212:215], v[92:95]
	v_mfma_f32_16x16x32_bf16 v[76:79], v[156:159], v[220:223], v[76:79]
	v_mfma_f32_16x16x32_bf16 v[88:91], v[164:167], v[212:215], v[88:91]
	v_mfma_f32_16x16x32_bf16 v[72:75], v[164:167], v[220:223], v[72:75]
	s_setprio 0
	s_setprio 1
	v_mfma_f32_16x16x32_bf16 v[116:119], v[168:171], v[186:189], 0
	v_mfma_f32_16x16x32_bf16 v[100:103], v[168:171], v[194:197], 0
	v_mfma_f32_16x16x32_bf16 v[112:115], v[176:179], v[186:189], 0
	v_mfma_f32_16x16x32_bf16 v[96:99], v[176:179], v[194:197], 0
	v_mfma_f32_16x16x32_bf16 v[84:87], v[168:171], v[208:211], 0
	v_mfma_f32_16x16x32_bf16 v[68:71], v[168:171], v[216:219], 0
	v_mfma_f32_16x16x32_bf16 v[80:83], v[176:179], v[208:211], 0
	v_mfma_f32_16x16x32_bf16 v[64:67], v[176:179], v[216:219], 0
	v_mfma_f32_16x16x32_bf16 v[116:119], v[172:175], v[190:193], v[116:119]
	v_mfma_f32_16x16x32_bf16 v[100:103], v[172:175], v[198:201], v[100:103]
	v_mfma_f32_16x16x32_bf16 v[112:115], v[182:185], v[190:193], v[112:115]
	v_mfma_f32_16x16x32_bf16 v[96:99], v[182:185], v[198:201], v[96:99]
	v_mfma_f32_16x16x32_bf16 v[84:87], v[172:175], v[212:215], v[84:87]
	v_mfma_f32_16x16x32_bf16 v[68:71], v[172:175], v[220:223], v[68:71]
	v_mfma_f32_16x16x32_bf16 v[80:83], v[182:185], v[212:215], v[80:83]
	v_mfma_f32_16x16x32_bf16 v[64:67], v[182:185], v[220:223], v[64:67]
	s_setprio 0
	s_barrier
	s_add_i32 s50, s64, s33
	v_lshl_add_u64 v[224:225], s[54:55], 0, v[130:131]
	s_mov_b32 m0, s50
	ds_read_b128 v[186:189], v153 offset:16384
	ds_read_b128 v[190:193], v153 offset:17408
	ds_read_b128 v[194:197], v153 offset:18432
	ds_read_b128 v[198:201], v153 offset:19456
	ds_read_b128 v[208:211], v153 offset:20480
	ds_read_b128 v[212:215], v153 offset:21504
	ds_read_b128 v[216:219], v153 offset:22528
	ds_read_b128 v[220:223], v153 offset:23552
	global_load_lds_dwordx4 v[224:225], off
	s_add_i32 m0, s50, 0x2000
	s_add_u32 s50, s54, 0xb0000
	v_lshl_add_u64 v[226:227], s[54:55], 0, v[134:135]
	s_addc_u32 s51, s55, 0
	s_add_i32 s78, s65, s33
	global_load_lds_dwordx4 v[226:227], off
	v_lshl_add_u64 v[228:229], s[50:51], 0, v[130:131]
	s_mov_b32 m0, s78
	global_load_lds_dwordx4 v[228:229], off
	v_lshl_add_u64 v[228:229], s[50:51], 0, v[134:135]
	s_add_i32 m0, s78, 0x2000
	s_nop 0
	global_load_lds_dwordx4 v[228:229], off
	s_waitcnt vmcnt(6)
	s_waitcnt lgkmcnt(0)
	s_barrier
; #define PG8_STAGE(bufoff, gbase, voff) do { _Pragma("unroll") for (int _i = 0; _i < 2; ++_i) \
;         __builtin_amdgcn_global_load_lds((const unsigned*)((const char*)(gbase) + (voff)[_i]), (PG8_LAS unsigned*)(lds + (bufoff) + ldsw + _i * 8192), 16, 0, 0); } while (0)
; #define PG8_LDA(dst, b, h) do { _Pragma("unroll") for (int m = 0; m < 4; ++m) _Pragma("unroll") for (int k = 0; k < 2; ++k) dst[m][k] = *(const PG8_LAS bf16x8*)(lds + PG8_SA(b, h) + aoff + m * 2048 + k * 1024); } while (0)
; #define PG8_LDB(dst, b, h) do { _Pragma("unroll") for (int n = 0; n < 2; ++n) _Pragma("unroll") for (int k = 0; k < 2; ++k) dst[n][k] = *(const PG8_LAS bf16x8*)(lds + PG8_SB(b, h) + boff + n * 2048 + k * 1024); } while (0)
; #define PG8_MMA(ai, bj, At, Bt) do { __builtin_amdgcn_s_setprio(1); _Pragma("unroll") for (int m = 0; m < 4; ++m) _Pragma("unroll") for (int n = 0; n < 2; ++n) _Pragma("unroll") for (int k = 0; k < 2; ++k) \
;         acc[ai][bj][m][n] = __builtin_amdgcn_mfma_f32_16x16x32_bf16(Bt[n][k], At[m][k], acc[ai][bj][m][n], 0, 0, 0); __builtin_amdgcn_s_setprio(0); } while (0)
; #define PG8_WAIT_V(n) asm volatile("s_waitcnt vmcnt(" #n ")" ::: "memory")
; #define PG8_WAIT_L(n) asm volatile("s_waitcnt lgkmcnt(" #n ")" ::: "memory")
; #define PG8_BAR __builtin_amdgcn_s_barrier()
; #define PG8_SCHED __builtin_amdgcn_sched_barrier(0)
; template <class Epi, class Sched, bool ALIGN_EPI = false, bool SP2 = false>
; __device__ __forceinline__ void gemm_phase(PG8_LAS unsigned char* lds, const Gemm g, const Sched& S, const Epi& E) {
;     ...
;             PG8_WAIT_V(8); PG8_WAIT_L(0); PG8_BAR; PG8_MMA(0, 0, At, B0); PG8_MMA(0, 1, At, B1); PG8_BAR; PG8_SCHED;
;             PG8_LDA(At, 0, 1); PG8_STAGE(PG8_SB(0, 0), b2, voffB); PG8_STAGE(PG8_SB(0, 1), b2 + hstep, voffB); PG8_STAGE(PG8_SA(0, 0), a2, voffA);
;             PG8_WAIT_V(8); PG8_WAIT_L(0); PG8_BAR; PG8_MMA(1, 0, At, B0); PG8_MMA(1, 1, At, B1); PG8_BAR; PG8_SCHED;
;             PG8_LDB(B0, 1, 0); PG8_LDB(B1, 1, 1); PG8_SCHED; PG8_LDA(At, 1, 0); PG8_STAGE(PG8_SA(0, 1), a2 + hstep, voffA);
;             PG8_WAIT_V(8); PG8_WAIT_L(0); PG8_BAR; PG8_MMA(0, 0, At, B0); PG8_MMA(0, 1, At, B1); PG8_BAR; PG8_SCHED;
	s_setprio 1
	s_waitcnt lgkmcnt(0)
	v_mfma_f32_16x16x32_bf16 v[60:63], v[144:147], v[186:189], 0
	v_mfma_f32_16x16x32_bf16 v[44:47], v[144:147], v[194:197], 0
	v_mfma_f32_16x16x32_bf16 v[56:59], v[160:163], v[186:189], 0
	v_mfma_f32_16x16x32_bf16 v[40:43], v[160:163], v[194:197], 0
	v_mfma_f32_16x16x32_bf16 v[28:31], v[144:147], v[208:211], 0
	v_mfma_f32_16x16x32_bf16 v[12:15], v[144:147], v[216:219], 0
	v_mfma_f32_16x16x32_bf16 v[24:27], v[160:163], v[208:211], 0
	v_mfma_f32_16x16x32_bf16 v[8:11], v[160:163], v[216:219], 0
	v_mfma_f32_16x16x32_bf16 v[60:63], v[156:159], v[190:193], v[60:63]
	v_mfma_f32_16x16x32_bf16 v[44:47], v[156:159], v[198:201], v[44:47]
	v_mfma_f32_16x16x32_bf16 v[56:59], v[164:167], v[190:193], v[56:59]
	v_mfma_f32_16x16x32_bf16 v[40:43], v[164:167], v[198:201], v[40:43]
	v_mfma_f32_16x16x32_bf16 v[28:31], v[156:159], v[212:215], v[28:31]
	v_mfma_f32_16x16x32_bf16 v[12:15], v[156:159], v[220:223], v[12:15]
	v_lshl_add_u64 v[228:229], s[56:57], 0, v[128:129]
	s_mov_b32 m0, s34
	s_nop 0
	global_load_lds_dwordx4 v[228:229], off
	v_mfma_f32_16x16x32_bf16 v[24:27], v[164:167], v[212:215], v[24:27]
	v_mfma_f32_16x16x32_bf16 v[8:11], v[164:167], v[220:223], v[8:11]
	s_setprio 0
	s_setprio 1
	v_mfma_f32_16x16x32_bf16 v[52:55], v[168:171], v[186:189], 0
	v_mfma_f32_16x16x32_bf16 v[36:39], v[168:171], v[194:197], 0
	v_mfma_f32_16x16x32_bf16 v[48:51], v[176:179], v[186:189], 0
	v_mfma_f32_16x16x32_bf16 v[32:35], v[176:179], v[194:197], 0
	v_mfma_f32_16x16x32_bf16 v[20:23], v[168:171], v[208:211], 0
	v_mfma_f32_16x16x32_bf16 v[4:7], v[168:171], v[216:219], 0
	v_mfma_f32_16x16x32_bf16 v[16:19], v[176:179], v[208:211], 0
	v_mfma_f32_16x16x32_bf16 v[0:3], v[176:179], v[216:219], 0
	v_mfma_f32_16x16x32_bf16 v[52:55], v[172:175], v[190:193], v[52:55]
	v_mfma_f32_16x16x32_bf16 v[36:39], v[172:175], v[198:201], v[36:39]
	v_mfma_f32_16x16x32_bf16 v[48:51], v[182:185], v[190:193], v[48:51]
	v_mfma_f32_16x16x32_bf16 v[32:35], v[182:185], v[198:201], v[32:35]
	v_mfma_f32_16x16x32_bf16 v[20:23], v[172:175], v[212:215], v[20:23]
	v_mfma_f32_16x16x32_bf16 v[4:7], v[172:175], v[220:223], v[4:7]
	v_lshl_add_u64 v[230:231], s[56:57], 0, v[132:133]
	s_mov_b32 m0, s58
	s_nop 0
	global_load_lds_dwordx4 v[230:231], off
	v_mfma_f32_16x16x32_bf16 v[16:19], v[182:185], v[212:215], v[16:19]
	v_mfma_f32_16x16x32_bf16 v[0:3], v[182:185], v[220:223], v[0:3]
	s_setprio 0
	s_barrier
	s_add_i32 s78, 0, 0x18000
	v_add_u32_e32 v155, s78, v149
	s_add_i32 s79, 0, 0x1c000
	ds_read_b128 v[144:147], v155
	ds_read_b128 v[156:159], v155 offset:1024
	ds_read_b128 v[160:163], v155 offset:2048
	ds_read_b128 v[164:167], v155 offset:3072
	v_add_u32_e32 v155, s79, v149
	ds_read_b128 v[168:171], v155
	ds_read_b128 v[172:175], v155 offset:1024
	ds_read_b128 v[176:179], v155 offset:2048
	ds_read_b128 v[182:185], v155 offset:3072
	s_add_u32 s50, s56, 0xb0000
	s_addc_u32 s51, s57, 0
	s_mov_b32 m0, s59
	v_lshl_add_u64 v[232:233], s[50:51], 0, v[128:129]
	ds_read_b128 v[186:189], v153 offset:32768
	ds_read_b128 v[190:193], v153 offset:33792
	ds_read_b128 v[194:197], v153 offset:34816
	ds_read_b128 v[198:201], v153 offset:35840
	ds_read_b128 v[208:211], v153 offset:36864
	ds_read_b128 v[212:215], v153 offset:37888
	ds_read_b128 v[216:219], v153 offset:38912
	ds_read_b128 v[220:223], v153 offset:39936
	global_load_lds_dwordx4 v[232:233], off
	v_lshl_add_u64 v[232:233], s[50:51], 0, v[132:133]
	s_mov_b32 m0, s60
	s_nop 0
	global_load_lds_dwordx4 v[232:233], off
	s_waitcnt vmcnt(8)
	s_waitcnt lgkmcnt(0)
	s_barrier
	s_setprio 1
	s_waitcnt lgkmcnt(0)
	v_mfma_f32_16x16x32_bf16 v[124:127], v[144:147], v[186:189], v[124:127]
	v_mfma_f32_16x16x32_bf16 v[108:111], v[144:147], v[194:197], v[108:111]
	v_mfma_f32_16x16x32_bf16 v[120:123], v[160:163], v[186:189], v[120:123]
	v_mfma_f32_16x16x32_bf16 v[104:107], v[160:163], v[194:197], v[104:107]
	v_mfma_f32_16x16x32_bf16 v[92:95], v[144:147], v[208:211], v[92:95]
	v_mfma_f32_16x16x32_bf16 v[76:79], v[144:147], v[216:219], v[76:79]
	v_mfma_f32_16x16x32_bf16 v[88:91], v[160:163], v[208:211], v[88:91]
	v_mfma_f32_16x16x32_bf16 v[72:75], v[160:163], v[216:219], v[72:75]
	v_mfma_f32_16x16x32_bf16 v[124:127], v[156:159], v[190:193], v[124:127]
	v_mfma_f32_16x16x32_bf16 v[108:111], v[156:159], v[198:201], v[108:111]
	v_mfma_f32_16x16x32_bf16 v[120:123], v[164:167], v[190:193], v[120:123]
	v_mfma_f32_16x16x32_bf16 v[104:107], v[164:167], v[198:201], v[104:107]
	v_mfma_f32_16x16x32_bf16 v[92:95], v[156:159], v[212:215], v[92:95]
	v_mfma_f32_16x16x32_bf16 v[76:79], v[156:159], v[220:223], v[76:79]
	v_mfma_f32_16x16x32_bf16 v[88:91], v[164:167], v[212:215], v[88:91]
	v_mfma_f32_16x16x32_bf16 v[72:75], v[164:167], v[220:223], v[72:75]
	s_setprio 0
	s_setprio 1
	v_mfma_f32_16x16x32_bf16 v[116:119], v[168:171], v[186:189], v[116:119]
	v_mfma_f32_16x16x32_bf16 v[100:103], v[168:171], v[194:197], v[100:103]
	v_mfma_f32_16x16x32_bf16 v[112:115], v[176:179], v[186:189], v[112:115]
	v_mfma_f32_16x16x32_bf16 v[96:99], v[176:179], v[194:197], v[96:99]
	v_mfma_f32_16x16x32_bf16 v[84:87], v[168:171], v[208:211], v[84:87]
	v_mfma_f32_16x16x32_bf16 v[68:71], v[168:171], v[216:219], v[68:71]
	v_mfma_f32_16x16x32_bf16 v[80:83], v[176:179], v[208:211], v[80:83]
	v_mfma_f32_16x16x32_bf16 v[64:67], v[176:179], v[216:219], v[64:67]
	v_mfma_f32_16x16x32_bf16 v[116:119], v[172:175], v[190:193], v[116:119]
	v_mfma_f32_16x16x32_bf16 v[100:103], v[172:175], v[198:201], v[100:103]
	v_mfma_f32_16x16x32_bf16 v[112:115], v[182:185], v[190:193], v[112:115]
	v_mfma_f32_16x16x32_bf16 v[96:99], v[182:185], v[198:201], v[96:99]
	v_mfma_f32_16x16x32_bf16 v[84:87], v[172:175], v[212:215], v[84:87]
	v_mfma_f32_16x16x32_bf16 v[68:71], v[172:175], v[220:223], v[68:71]
	v_mfma_f32_16x16x32_bf16 v[80:83], v[182:185], v[212:215], v[80:83]
	v_mfma_f32_16x16x32_bf16 v[64:67], v[182:185], v[220:223], v[64:67]
	s_setprio 0
	s_barrier
; #define PG8_STAGE(bufoff, gbase, voff) do { _Pragma("unroll") for (int _i = 0; _i < 2; ++_i) \
;         __builtin_amdgcn_global_load_lds((const unsigned*)((const char*)(gbase) + (voff)[_i]), (PG8_LAS unsigned*)(lds + (bufoff) + ldsw + _i * 8192), 16, 0, 0); } while (0)
; #define PG8_LDA(dst, b, h) do { _Pragma("unroll") for (int m = 0; m < 4; ++m) _Pragma("unroll") for (int k = 0; k < 2; ++k) dst[m][k] = *(const PG8_LAS bf16x8*)(lds + PG8_SA(b, h) + aoff + m * 2048 + k * 1024); } while (0)
; #define PG8_LDB(dst, b, h) do { _Pragma("unroll") for (int n = 0; n < 2; ++n) _Pragma("unroll") for (int k = 0; k < 2; ++k) dst[n][k] = *(const PG8_LAS bf16x8*)(lds + PG8_SB(b, h) + boff + n * 2048 + k * 1024); } while (0)
; template <class Epi, class Sched, bool ALIGN_EPI = false, bool SP2 = false>
; __device__ __forceinline__ void gemm_phase(PG8_LAS unsigned char* lds, const Gemm g, const Sched& S, const Epi& E) {
;     ...
;         for (int t = 0; t < nt; t += 2) {
;             const bool last = (t == nt - 2);
;             const char* a1 = cA + (size_t)(t + 1) * kstep;
;             const char* a2 = last ? nA : cA + (size_t)(t + 2) * kstep; const char* b2 = last ? nB : cB + (size_t)(t + 2) * kstep;
;             const char* a3 = a2 + kstep; const char* b3 = b2 + kstep;
;             if (last && has_next) S.a_ready(nxt);
;             if constexpr (SP2) {
;             PG8_LDB(B0, 0, 0); PG8_LDB(B1, 0, 1); PG8_SCHED; PG8_LDA(At, 0, 0); PG8_STAGE(PG8_SA(1, 1), a1 + hstep, voffA);
;             PG8_WAIT_V(8); PG8_WAIT_L(0); PG8_BAR; PG8_MMA(0, 0, At, B0); PG8_MMA(0, 1, At, B1); PG8_BAR; PG8_SCHED;
;             PG8_LDA(At, 0, 1); PG8_STAGE(PG8_SB(0, 0), b2, voffB); PG8_STAGE(PG8_SB(0, 1), b2 + hstep, voffB); PG8_STAGE(PG8_SA(0, 0), a2, voffA);
;             PG8_WAIT_V(8); PG8_WAIT_L(0); PG8_BAR; PG8_MMA(1, 0, At, B0); PG8_MMA(1, 1, At, B1); PG8_BAR; PG8_SCHED;
;             PG8_LDB(B0, 1, 0); PG8_LDB(B1, 1, 1); PG8_SCHED; PG8_LDA(At, 1, 0); PG8_STAGE(PG8_SA(0, 1), a2 + hstep, voffA);
;             PG8_WAIT_V(8); PG8_WAIT_L(0); PG8_BAR; PG8_MMA(0, 0, At, B0); PG8_MMA(0, 1, At, B1); PG8_BAR; PG8_SCHED;
;             PG8_LDA(At, 1, 1); PG8_STAGE(PG8_SB(1, 0), b3, voffB); PG8_STAGE(PG8_SB(1, 1), b3 + hstep, voffB); PG8_STAGE(PG8_SA(1, 0), a3, voffA);
;             PG8_WAIT_V(8); PG8_WAIT_L(0); PG8_BAR; PG8_MMA(1, 0, At, B0); PG8_MMA(1, 1, At, B1); PG8_BAR; PG8_SCHED;
	s_add_i32 s50, s78, s33
	v_lshl_add_u64 v[224:225], v[224:225], 0, s[42:43]
	s_mov_b32 m0, s50
	ds_read_b128 v[186:189], v153 offset:49152
	ds_read_b128 v[190:193], v153 offset:50176
	ds_read_b128 v[194:197], v153 offset:51200
	ds_read_b128 v[198:201], v153 offset:52224
	ds_read_b128 v[208:211], v153 offset:53248
	ds_read_b128 v[212:215], v153 offset:54272
	ds_read_b128 v[216:219], v153 offset:55296
	ds_read_b128 v[220:223], v153 offset:56320
	global_load_lds_dwordx4 v[224:225], off
	s_add_i32 m0, s50, 0x2000
	s_add_u32 s50, s54, 0xb0080
	v_lshl_add_u64 v[224:225], v[226:227], 0, s[42:43]
	s_addc_u32 s51, s55, 0
	s_add_i32 s54, s79, s33
	global_load_lds_dwordx4 v[224:225], off
	v_lshl_add_u64 v[224:225], s[50:51], 0, v[130:131]
	s_mov_b32 m0, s54
	s_nop 0
	global_load_lds_dwordx4 v[224:225], off
	v_lshl_add_u64 v[224:225], s[50:51], 0, v[134:135]
	s_add_i32 m0, s54, 0x2000
	s_nop 0
	global_load_lds_dwordx4 v[224:225], off
	s_waitcnt vmcnt(6)
	s_waitcnt lgkmcnt(0)
	s_barrier
	s_setprio 1
	s_waitcnt lgkmcnt(0)
	v_mfma_f32_16x16x32_bf16 v[60:63], v[144:147], v[186:189], v[60:63]
	v_mfma_f32_16x16x32_bf16 v[44:47], v[144:147], v[194:197], v[44:47]
	v_mfma_f32_16x16x32_bf16 v[56:59], v[160:163], v[186:189], v[56:59]
	v_mfma_f32_16x16x32_bf16 v[40:43], v[160:163], v[194:197], v[40:43]
	v_mfma_f32_16x16x32_bf16 v[28:31], v[144:147], v[208:211], v[28:31]
	v_mfma_f32_16x16x32_bf16 v[12:15], v[144:147], v[216:219], v[12:15]
	v_mfma_f32_16x16x32_bf16 v[24:27], v[160:163], v[208:211], v[24:27]
	v_mfma_f32_16x16x32_bf16 v[8:11], v[160:163], v[216:219], v[8:11]
	v_mfma_f32_16x16x32_bf16 v[60:63], v[156:159], v[190:193], v[60:63]
	v_mfma_f32_16x16x32_bf16 v[44:47], v[156:159], v[198:201], v[44:47]
	v_mfma_f32_16x16x32_bf16 v[56:59], v[164:167], v[190:193], v[56:59]
	v_mfma_f32_16x16x32_bf16 v[40:43], v[164:167], v[198:201], v[40:43]
	v_mfma_f32_16x16x32_bf16 v[28:31], v[156:159], v[212:215], v[28:31]
	v_mfma_f32_16x16x32_bf16 v[12:15], v[156:159], v[220:223], v[12:15]
	v_lshl_add_u64 v[224:225], v[228:229], 0, s[42:43]
	s_mov_b32 m0, s62
	s_nop 0
	global_load_lds_dwordx4 v[224:225], off
	v_mfma_f32_16x16x32_bf16 v[24:27], v[164:167], v[212:215], v[24:27]
	v_mfma_f32_16x16x32_bf16 v[8:11], v[164:167], v[220:223], v[8:11]
	s_setprio 0
	s_setprio 1
	v_mfma_f32_16x16x32_bf16 v[52:55], v[168:171], v[186:189], v[52:55]
	v_mfma_f32_16x16x32_bf16 v[36:39], v[168:171], v[194:197], v[36:39]
	v_mfma_f32_16x16x32_bf16 v[48:51], v[176:179], v[186:189], v[48:51]
	v_mfma_f32_16x16x32_bf16 v[32:35], v[176:179], v[194:197], v[32:35]
	v_mfma_f32_16x16x32_bf16 v[20:23], v[168:171], v[208:211], v[20:23]
	v_mfma_f32_16x16x32_bf16 v[4:7], v[168:171], v[216:219], v[4:7]
	v_mfma_f32_16x16x32_bf16 v[16:19], v[176:179], v[208:211], v[16:19]
	v_mfma_f32_16x16x32_bf16 v[0:3], v[176:179], v[216:219], v[0:3]
	v_mfma_f32_16x16x32_bf16 v[52:55], v[172:175], v[190:193], v[52:55]
	v_mfma_f32_16x16x32_bf16 v[36:39], v[172:175], v[198:201], v[36:39]
	v_mfma_f32_16x16x32_bf16 v[48:51], v[182:185], v[190:193], v[48:51]
	v_mfma_f32_16x16x32_bf16 v[32:35], v[182:185], v[198:201], v[32:35]
	v_mfma_f32_16x16x32_bf16 v[20:23], v[172:175], v[212:215], v[20:23]
	v_mfma_f32_16x16x32_bf16 v[4:7], v[172:175], v[220:223], v[4:7]
	v_lshl_add_u64 v[224:225], v[230:231], 0, s[42:43]
	s_mov_b32 m0, s63
	s_nop 0
	global_load_lds_dwordx4 v[224:225], off
	v_mfma_f32_16x16x32_bf16 v[16:19], v[182:185], v[212:215], v[16:19]
	v_mfma_f32_16x16x32_bf16 v[0:3], v[182:185], v[220:223], v[0:3]
	s_setprio 0
	s_barrier
	s_add_i32 s84, s84, 2
	s_add_u32 s82, s82, 0x100
	s_addc_u32 s83, s83, 0
	s_mov_b64 s[50:51], s[52:53]
.LBB0_1197:
	ds_read_b128 v[144:147], v151
	ds_read_b128 v[156:159], v151 offset:1024
	ds_read_b128 v[160:163], v151 offset:2048
	ds_read_b128 v[164:167], v151 offset:3072
	ds_read_b128 v[168:171], v152
	ds_read_b128 v[172:175], v152 offset:1024
	ds_read_b128 v[176:179], v152 offset:2048
	ds_read_b128 v[182:185], v152 offset:3072
	s_add_u32 s52, s50, 0x100
	s_addc_u32 s53, s51, 0
	s_cmp_eq_u32 s84, 40
	s_cselect_b32 s57, s1, s53
	s_cselect_b32 s56, s0, s52
	s_cselect_b32 s55, s49, s83
	s_cselect_b32 s54, s48, s82
	v_lshl_add_u64 v[224:225], s[50:51], 0, v[136:137]
	s_add_i32 m0, s34, 0xc000
	ds_read_b128 v[186:189], v153
	ds_read_b128 v[190:193], v153 offset:1024
	ds_read_b128 v[194:197], v153 offset:2048
	ds_read_b128 v[198:201], v153 offset:3072
	ds_read_b128 v[208:211], v153 offset:4096
	ds_read_b128 v[212:215], v153 offset:5120
	ds_read_b128 v[216:219], v153 offset:6144
	ds_read_b128 v[220:223], v153 offset:7168
	global_load_lds_dwordx4 v[224:225], off
	v_lshl_add_u64 v[224:225], s[50:51], 0, v[138:139]
	s_add_i32 m0, s34, 0xe000
	s_nop 0
	global_load_lds_dwordx4 v[224:225], off
	s_waitcnt vmcnt(8)
	s_waitcnt lgkmcnt(0)
	s_barrier
; #define PG8_STAGE(bufoff, gbase, voff) do { _Pragma("unroll") for (int _i = 0; _i < 2; ++_i) \
;         __builtin_amdgcn_global_load_lds((const unsigned*)((const char*)(gbase) + (voff)[_i]), (PG8_LAS unsigned*)(lds + (bufoff) + ldsw + _i * 8192), 16, 0, 0); } while (0)
; #define PG8_LDA(dst, b, h) do { _Pragma("unroll") for (int m = 0; m < 4; ++m) _Pragma("unroll") for (int k = 0; k < 2; ++k) dst[m][k] = *(const PG8_LAS bf16x8*)(lds + PG8_SA(b, h) + aoff + m * 2048 + k * 1024); } while (0)
; #define PG8_MMA(ai, bj, At, Bt) do { __builtin_amdgcn_s_setprio(1); _Pragma("unroll") for (int m = 0; m < 4; ++m) _Pragma("unroll") for (int n = 0; n < 2; ++n) _Pragma("unroll") for (int k = 0; k < 2; ++k) \
;         acc[ai][bj][m][n] = __builtin_amdgcn_mfma_f32_16x16x32_bf16(Bt[n][k], At[m][k], acc[ai][bj][m][n], 0, 0, 0); __builtin_amdgcn_s_setprio(0); } while (0)
; #define PG8_WAIT_V(n) asm volatile("s_waitcnt vmcnt(" #n ")" ::: "memory")
; #define PG8_WAIT_L(n) asm volatile("s_waitcnt lgkmcnt(" #n ")" ::: "memory")
; #define PG8_BAR __builtin_amdgcn_s_barrier()
; #define PG8_SCHED __builtin_amdgcn_sched_barrier(0)
; template <class Epi, class Sched, bool ALIGN_EPI = false, bool SP2 = false>
; __device__ __forceinline__ void gemm_phase(PG8_LAS unsigned char* lds, const Gemm g, const Sched& S, const Epi& E) {
;     ...
;             PG8_WAIT_V(8); PG8_WAIT_L(0); PG8_BAR; PG8_MMA(0, 0, At, B0); PG8_MMA(0, 1, At, B1); PG8_BAR; PG8_SCHED;
;             PG8_LDA(At, 0, 1); PG8_STAGE(PG8_SB(0, 0), b2, voffB); PG8_STAGE(PG8_SB(0, 1), b2 + hstep, voffB); PG8_STAGE(PG8_SA(0, 0), a2, voffA);
;             PG8_WAIT_V(8); PG8_WAIT_L(0); PG8_BAR; PG8_MMA(1, 0, At, B0); PG8_MMA(1, 1, At, B1); PG8_BAR; PG8_SCHED;
	s_setprio 1
	s_waitcnt lgkmcnt(0)
	v_mfma_f32_16x16x32_bf16 v[124:127], v[144:147], v[186:189], v[124:127]
	v_mfma_f32_16x16x32_bf16 v[108:111], v[144:147], v[194:197], v[108:111]
	v_mfma_f32_16x16x32_bf16 v[120:123], v[160:163], v[186:189], v[120:123]
	v_mfma_f32_16x16x32_bf16 v[104:107], v[160:163], v[194:197], v[104:107]
	v_mfma_f32_16x16x32_bf16 v[92:95], v[144:147], v[208:211], v[92:95]
	v_mfma_f32_16x16x32_bf16 v[76:79], v[144:147], v[216:219], v[76:79]
	v_mfma_f32_16x16x32_bf16 v[88:91], v[160:163], v[208:211], v[88:91]
	v_mfma_f32_16x16x32_bf16 v[72:75], v[160:163], v[216:219], v[72:75]
	v_mfma_f32_16x16x32_bf16 v[124:127], v[156:159], v[190:193], v[124:127]
	v_mfma_f32_16x16x32_bf16 v[108:111], v[156:159], v[198:201], v[108:111]
	v_mfma_f32_16x16x32_bf16 v[120:123], v[164:167], v[190:193], v[120:123]
	v_mfma_f32_16x16x32_bf16 v[104:107], v[164:167], v[198:201], v[104:107]
	v_mfma_f32_16x16x32_bf16 v[92:95], v[156:159], v[212:215], v[92:95]
	v_mfma_f32_16x16x32_bf16 v[76:79], v[156:159], v[220:223], v[76:79]
	v_mfma_f32_16x16x32_bf16 v[88:91], v[164:167], v[212:215], v[88:91]
	v_mfma_f32_16x16x32_bf16 v[72:75], v[164:167], v[220:223], v[72:75]
	s_setprio 0
	s_setprio 1
	v_mfma_f32_16x16x32_bf16 v[116:119], v[168:171], v[186:189], v[116:119]
	v_mfma_f32_16x16x32_bf16 v[100:103], v[168:171], v[194:197], v[100:103]
	v_mfma_f32_16x16x32_bf16 v[112:115], v[176:179], v[186:189], v[112:115]
	v_mfma_f32_16x16x32_bf16 v[96:99], v[176:179], v[194:197], v[96:99]
	v_mfma_f32_16x16x32_bf16 v[84:87], v[168:171], v[208:211], v[84:87]
	v_mfma_f32_16x16x32_bf16 v[68:71], v[168:171], v[216:219], v[68:71]
	v_mfma_f32_16x16x32_bf16 v[80:83], v[176:179], v[208:211], v[80:83]
	v_mfma_f32_16x16x32_bf16 v[64:67], v[176:179], v[216:219], v[64:67]
	v_mfma_f32_16x16x32_bf16 v[116:119], v[172:175], v[190:193], v[116:119]
	v_mfma_f32_16x16x32_bf16 v[100:103], v[172:175], v[198:201], v[100:103]
	v_mfma_f32_16x16x32_bf16 v[112:115], v[182:185], v[190:193], v[112:115]
	v_mfma_f32_16x16x32_bf16 v[96:99], v[182:185], v[198:201], v[96:99]
	v_mfma_f32_16x16x32_bf16 v[84:87], v[172:175], v[212:215], v[84:87]
	v_mfma_f32_16x16x32_bf16 v[68:71], v[172:175], v[220:223], v[68:71]
	v_mfma_f32_16x16x32_bf16 v[80:83], v[182:185], v[212:215], v[80:83]
	v_mfma_f32_16x16x32_bf16 v[64:67], v[182:185], v[220:223], v[64:67]
	s_setprio 0
	s_barrier
	s_add_i32 s50, s64, s33
	v_lshl_add_u64 v[224:225], s[54:55], 0, v[130:131]
	s_mov_b32 m0, s50
	ds_read_b128 v[186:189], v153 offset:16384
	ds_read_b128 v[190:193], v153 offset:17408
	ds_read_b128 v[194:197], v153 offset:18432
	ds_read_b128 v[198:201], v153 offset:19456
	ds_read_b128 v[208:211], v153 offset:20480
	ds_read_b128 v[212:215], v153 offset:21504
	ds_read_b128 v[216:219], v153 offset:22528
	ds_read_b128 v[220:223], v153 offset:23552
	global_load_lds_dwordx4 v[224:225], off
	s_add_i32 m0, s50, 0x2000
	s_add_u32 s50, s54, 0xb0000
	v_lshl_add_u64 v[226:227], s[54:55], 0, v[134:135]
	s_addc_u32 s51, s55, 0
	s_add_i32 s78, s65, s33
	global_load_lds_dwordx4 v[226:227], off
	v_lshl_add_u64 v[228:229], s[50:51], 0, v[130:131]
	s_mov_b32 m0, s78
	global_load_lds_dwordx4 v[228:229], off
	v_lshl_add_u64 v[228:229], s[50:51], 0, v[134:135]
	s_add_i32 m0, s78, 0x2000
	s_nop 0
	global_load_lds_dwordx4 v[228:229], off
	s_waitcnt vmcnt(6)
	s_waitcnt lgkmcnt(0)
	s_barrier
	s_setprio 1
	s_waitcnt lgkmcnt(0)
	v_mfma_f32_16x16x32_bf16 v[60:63], v[144:147], v[186:189], v[60:63]
	v_mfma_f32_16x16x32_bf16 v[44:47], v[144:147], v[194:197], v[44:47]
	v_mfma_f32_16x16x32_bf16 v[56:59], v[160:163], v[186:189], v[56:59]
	v_mfma_f32_16x16x32_bf16 v[40:43], v[160:163], v[194:197], v[40:43]
	v_mfma_f32_16x16x32_bf16 v[28:31], v[144:147], v[208:211], v[28:31]
	v_mfma_f32_16x16x32_bf16 v[12:15], v[144:147], v[216:219], v[12:15]
	v_mfma_f32_16x16x32_bf16 v[24:27], v[160:163], v[208:211], v[24:27]
	v_mfma_f32_16x16x32_bf16 v[8:11], v[160:163], v[216:219], v[8:11]
	v_mfma_f32_16x16x32_bf16 v[60:63], v[156:159], v[190:193], v[60:63]
	v_mfma_f32_16x16x32_bf16 v[44:47], v[156:159], v[198:201], v[44:47]
	v_mfma_f32_16x16x32_bf16 v[56:59], v[164:167], v[190:193], v[56:59]
	v_mfma_f32_16x16x32_bf16 v[40:43], v[164:167], v[198:201], v[40:43]
	v_mfma_f32_16x16x32_bf16 v[28:31], v[156:159], v[212:215], v[28:31]
	v_mfma_f32_16x16x32_bf16 v[12:15], v[156:159], v[220:223], v[12:15]
	v_lshl_add_u64 v[228:229], s[56:57], 0, v[128:129]
	s_mov_b32 m0, s34
	s_nop 0
	global_load_lds_dwordx4 v[228:229], off
	v_mfma_f32_16x16x32_bf16 v[24:27], v[164:167], v[212:215], v[24:27]
	v_mfma_f32_16x16x32_bf16 v[8:11], v[164:167], v[220:223], v[8:11]
	s_setprio 0
	s_setprio 1
	v_mfma_f32_16x16x32_bf16 v[52:55], v[168:171], v[186:189], v[52:55]
	v_mfma_f32_16x16x32_bf16 v[36:39], v[168:171], v[194:197], v[36:39]
	v_mfma_f32_16x16x32_bf16 v[48:51], v[176:179], v[186:189], v[48:51]
	v_mfma_f32_16x16x32_bf16 v[32:35], v[176:179], v[194:197], v[32:35]
	v_mfma_f32_16x16x32_bf16 v[20:23], v[168:171], v[208:211], v[20:23]
	v_mfma_f32_16x16x32_bf16 v[4:7], v[168:171], v[216:219], v[4:7]
	v_mfma_f32_16x16x32_bf16 v[16:19], v[176:179], v[208:211], v[16:19]
	v_mfma_f32_16x16x32_bf16 v[0:3], v[176:179], v[216:219], v[0:3]
	v_mfma_f32_16x16x32_bf16 v[52:55], v[172:175], v[190:193], v[52:55]
	v_mfma_f32_16x16x32_bf16 v[36:39], v[172:175], v[198:201], v[36:39]
	v_mfma_f32_16x16x32_bf16 v[48:51], v[182:185], v[190:193], v[48:51]
	v_mfma_f32_16x16x32_bf16 v[32:35], v[182:185], v[198:201], v[32:35]
	v_mfma_f32_16x16x32_bf16 v[20:23], v[172:175], v[212:215], v[20:23]
	v_mfma_f32_16x16x32_bf16 v[4:7], v[172:175], v[220:223], v[4:7]
	v_lshl_add_u64 v[230:231], s[56:57], 0, v[132:133]
	s_mov_b32 m0, s58
	s_nop 0
	global_load_lds_dwordx4 v[230:231], off
	v_mfma_f32_16x16x32_bf16 v[16:19], v[182:185], v[212:215], v[16:19]
	v_mfma_f32_16x16x32_bf16 v[0:3], v[182:185], v[220:223], v[0:3]
	s_setprio 0
	s_barrier
; #define PG8_STAGE(bufoff, gbase, voff) do { _Pragma("unroll") for (int _i = 0; _i < 2; ++_i) \
;         __builtin_amdgcn_global_load_lds((const unsigned*)((const char*)(gbase) + (voff)[_i]), (PG8_LAS unsigned*)(lds + (bufoff) + ldsw + _i * 8192), 16, 0, 0); } while (0)
; #define PG8_LDA(dst, b, h) do { _Pragma("unroll") for (int m = 0; m < 4; ++m) _Pragma("unroll") for (int k = 0; k < 2; ++k) dst[m][k] = *(const PG8_LAS bf16x8*)(lds + PG8_SA(b, h) + aoff + m * 2048 + k * 1024); } while (0)
; #define PG8_LDB(dst, b, h) do { _Pragma("unroll") for (int n = 0; n < 2; ++n) _Pragma("unroll") for (int k = 0; k < 2; ++k) dst[n][k] = *(const PG8_LAS bf16x8*)(lds + PG8_SB(b, h) + boff + n * 2048 + k * 1024); } while (0)
; #define PG8_MMA(ai, bj, At, Bt) do { __builtin_amdgcn_s_setprio(1); _Pragma("unroll") for (int m = 0; m < 4; ++m) _Pragma("unroll") for (int n = 0; n < 2; ++n) _Pragma("unroll") for (int k = 0; k < 2; ++k) \
;         acc[ai][bj][m][n] = __builtin_amdgcn_mfma_f32_16x16x32_bf16(Bt[n][k], At[m][k], acc[ai][bj][m][n], 0, 0, 0); __builtin_amdgcn_s_setprio(0); } while (0)
; #define PG8_WAIT_V(n) asm volatile("s_waitcnt vmcnt(" #n ")" ::: "memory")
; #define PG8_WAIT_L(n) asm volatile("s_waitcnt lgkmcnt(" #n ")" ::: "memory")
; #define PG8_BAR __builtin_amdgcn_s_barrier()
; #define PG8_SCHED __builtin_amdgcn_sched_barrier(0)
; template <class Epi, class Sched, bool ALIGN_EPI = false, bool SP2 = false>
; __device__ __forceinline__ void gemm_phase(PG8_LAS unsigned char* lds, const Gemm g, const Sched& S, const Epi& E) {
;     ...
;             PG8_LDB(B0, 1, 0); PG8_LDB(B1, 1, 1); PG8_SCHED; PG8_LDA(At, 1, 0); PG8_STAGE(PG8_SA(0, 1), a2 + hstep, voffA);
;             PG8_WAIT_V(8); PG8_WAIT_L(0); PG8_BAR; PG8_MMA(0, 0, At, B0); PG8_MMA(0, 1, At, B1); PG8_BAR; PG8_SCHED;
	s_add_i32 s78, 0, 0x18000
	v_add_u32_e32 v155, s78, v149
	s_add_i32 s79, 0, 0x1c000
	ds_read_b128 v[144:147], v155
	ds_read_b128 v[156:159], v155 offset:1024
	ds_read_b128 v[160:163], v155 offset:2048
	ds_read_b128 v[164:167], v155 offset:3072
	v_add_u32_e32 v155, s79, v149
	ds_read_b128 v[168:171], v155
	ds_read_b128 v[172:175], v155 offset:1024
	ds_read_b128 v[176:179], v155 offset:2048
	ds_read_b128 v[182:185], v155 offset:3072
	s_add_u32 s50, s56, 0xb0000
	s_addc_u32 s51, s57, 0
	s_mov_b32 m0, s59
	v_lshl_add_u64 v[232:233], s[50:51], 0, v[128:129]
	ds_read_b128 v[186:189], v153 offset:32768
	ds_read_b128 v[190:193], v153 offset:33792
	ds_read_b128 v[194:197], v153 offset:34816
	ds_read_b128 v[198:201], v153 offset:35840
	ds_read_b128 v[208:211], v153 offset:36864
	ds_read_b128 v[212:215], v153 offset:37888
	ds_read_b128 v[216:219], v153 offset:38912
	ds_read_b128 v[220:223], v153 offset:39936
	global_load_lds_dwordx4 v[232:233], off
	v_lshl_add_u64 v[232:233], s[50:51], 0, v[132:133]
	s_mov_b32 m0, s60
	s_nop 0
	global_load_lds_dwordx4 v[232:233], off
	s_waitcnt vmcnt(8)
	s_waitcnt lgkmcnt(0)
	s_barrier
	s_setprio 1
	s_waitcnt lgkmcnt(0)
	v_mfma_f32_16x16x32_bf16 v[124:127], v[144:147], v[186:189], v[124:127]
	v_mfma_f32_16x16x32_bf16 v[108:111], v[144:147], v[194:197], v[108:111]
	v_mfma_f32_16x16x32_bf16 v[120:123], v[160:163], v[186:189], v[120:123]
	v_mfma_f32_16x16x32_bf16 v[104:107], v[160:163], v[194:197], v[104:107]
	v_mfma_f32_16x16x32_bf16 v[92:95], v[144:147], v[208:211], v[92:95]
	v_mfma_f32_16x16x32_bf16 v[76:79], v[144:147], v[216:219], v[76:79]
	v_mfma_f32_16x16x32_bf16 v[88:91], v[160:163], v[208:211], v[88:91]
	v_mfma_f32_16x16x32_bf16 v[72:75], v[160:163], v[216:219], v[72:75]
	v_mfma_f32_16x16x32_bf16 v[124:127], v[156:159], v[190:193], v[124:127]
	v_mfma_f32_16x16x32_bf16 v[108:111], v[156:159], v[198:201], v[108:111]
	v_mfma_f32_16x16x32_bf16 v[120:123], v[164:167], v[190:193], v[120:123]
	v_mfma_f32_16x16x32_bf16 v[104:107], v[164:167], v[198:201], v[104:107]
	v_mfma_f32_16x16x32_bf16 v[92:95], v[156:159], v[212:215], v[92:95]
	v_mfma_f32_16x16x32_bf16 v[76:79], v[156:159], v[220:223], v[76:79]
	v_mfma_f32_16x16x32_bf16 v[88:91], v[164:167], v[212:215], v[88:91]
	v_mfma_f32_16x16x32_bf16 v[72:75], v[164:167], v[220:223], v[72:75]
	s_setprio 0
	s_setprio 1
	v_mfma_f32_16x16x32_bf16 v[116:119], v[168:171], v[186:189], v[116:119]
	v_mfma_f32_16x16x32_bf16 v[100:103], v[168:171], v[194:197], v[100:103]
	v_mfma_f32_16x16x32_bf16 v[112:115], v[176:179], v[186:189], v[112:115]
	v_mfma_f32_16x16x32_bf16 v[96:99], v[176:179], v[194:197], v[96:99]
	v_mfma_f32_16x16x32_bf16 v[84:87], v[168:171], v[208:211], v[84:87]
	v_mfma_f32_16x16x32_bf16 v[68:71], v[168:171], v[216:219], v[68:71]
	v_mfma_f32_16x16x32_bf16 v[80:83], v[176:179], v[208:211], v[80:83]
	v_mfma_f32_16x16x32_bf16 v[64:67], v[176:179], v[216:219], v[64:67]
	v_mfma_f32_16x16x32_bf16 v[116:119], v[172:175], v[190:193], v[116:119]
	v_mfma_f32_16x16x32_bf16 v[100:103], v[172:175], v[198:201], v[100:103]
	v_mfma_f32_16x16x32_bf16 v[112:115], v[182:185], v[190:193], v[112:115]
	v_mfma_f32_16x16x32_bf16 v[96:99], v[182:185], v[198:201], v[96:99]
	v_mfma_f32_16x16x32_bf16 v[84:87], v[172:175], v[212:215], v[84:87]
	v_mfma_f32_16x16x32_bf16 v[68:71], v[172:175], v[220:223], v[68:71]
	v_mfma_f32_16x16x32_bf16 v[80:83], v[182:185], v[212:215], v[80:83]
	v_mfma_f32_16x16x32_bf16 v[64:67], v[182:185], v[220:223], v[64:67]
	s_setprio 0
	s_barrier
; #define PG8_STAGE(bufoff, gbase, voff) do { _Pragma("unroll") for (int _i = 0; _i < 2; ++_i) \
;         __builtin_amdgcn_global_load_lds((const unsigned*)((const char*)(gbase) + (voff)[_i]), (PG8_LAS unsigned*)(lds + (bufoff) + ldsw + _i * 8192), 16, 0, 0); } while (0)
; #define PG8_LDA(dst, b, h) do { _Pragma("unroll") for (int m = 0; m < 4; ++m) _Pragma("unroll") for (int k = 0; k < 2; ++k) dst[m][k] = *(const PG8_LAS bf16x8*)(lds + PG8_SA(b, h) + aoff + m * 2048 + k * 1024); } while (0)
; #define PG8_MMA(ai, bj, At, Bt) do { __builtin_amdgcn_s_setprio(1); _Pragma("unroll") for (int m = 0; m < 4; ++m) _Pragma("unroll") for (int n = 0; n < 2; ++n) _Pragma("unroll") for (int k = 0; k < 2; ++k) \
;         acc[ai][bj][m][n] = __builtin_amdgcn_mfma_f32_16x16x32_bf16(Bt[n][k], At[m][k], acc[ai][bj][m][n], 0, 0, 0); __builtin_amdgcn_s_setprio(0); } while (0)
; #define PG8_WAIT_V(n) asm volatile("s_waitcnt vmcnt(" #n ")" ::: "memory")
; #define PG8_WAIT_L(n) asm volatile("s_waitcnt lgkmcnt(" #n ")" ::: "memory")
; #define PG8_BAR __builtin_amdgcn_s_barrier()
; #define PG8_SCHED __builtin_amdgcn_sched_barrier(0)
; template <class Epi, class Sched, bool ALIGN_EPI = false, bool SP2 = false>
; __device__ __forceinline__ void gemm_phase(PG8_LAS unsigned char* lds, const Gemm g, const Sched& S, const Epi& E) {
;     ...
;         for (int t = 0; t < nt; t += 2) {
;             const bool last = (t == nt - 2);
;     ...
;             PG8_LDA(At, 1, 1); PG8_STAGE(PG8_SB(1, 0), b3, voffB); PG8_STAGE(PG8_SB(1, 1), b3 + hstep, voffB); PG8_STAGE(PG8_SA(1, 0), a3, voffA);
;             PG8_WAIT_V(8); PG8_WAIT_L(0); PG8_BAR; PG8_MMA(1, 0, At, B0); PG8_MMA(1, 1, At, B1); PG8_BAR; PG8_SCHED;
	s_add_i32 s50, s78, s33
	v_lshl_add_u64 v[224:225], v[224:225], 0, s[42:43]
	s_mov_b32 m0, s50
	ds_read_b128 v[186:189], v153 offset:49152
	ds_read_b128 v[190:193], v153 offset:50176
	ds_read_b128 v[194:197], v153 offset:51200
	ds_read_b128 v[198:201], v153 offset:52224
	ds_read_b128 v[208:211], v153 offset:53248
	ds_read_b128 v[212:215], v153 offset:54272
	ds_read_b128 v[216:219], v153 offset:55296
	ds_read_b128 v[220:223], v153 offset:56320
	global_load_lds_dwordx4 v[224:225], off
	s_add_i32 m0, s50, 0x2000
	s_add_u32 s50, s54, 0xb0080
	v_lshl_add_u64 v[224:225], v[226:227], 0, s[42:43]
	s_addc_u32 s51, s55, 0
	s_add_i32 s54, s79, s33
	global_load_lds_dwordx4 v[224:225], off
	v_lshl_add_u64 v[224:225], s[50:51], 0, v[130:131]
	s_mov_b32 m0, s54
	s_nop 0
	global_load_lds_dwordx4 v[224:225], off
	v_lshl_add_u64 v[224:225], s[50:51], 0, v[134:135]
	s_add_i32 m0, s54, 0x2000
	s_nop 0
	global_load_lds_dwordx4 v[224:225], off
	s_waitcnt vmcnt(6)
	s_waitcnt lgkmcnt(0)
	s_barrier
	s_setprio 1
	s_waitcnt lgkmcnt(0)
	v_mfma_f32_16x16x32_bf16 v[60:63], v[144:147], v[186:189], v[60:63]
	v_mfma_f32_16x16x32_bf16 v[44:47], v[144:147], v[194:197], v[44:47]
	v_mfma_f32_16x16x32_bf16 v[56:59], v[160:163], v[186:189], v[56:59]
	v_mfma_f32_16x16x32_bf16 v[40:43], v[160:163], v[194:197], v[40:43]
	v_mfma_f32_16x16x32_bf16 v[28:31], v[144:147], v[208:211], v[28:31]
	v_mfma_f32_16x16x32_bf16 v[12:15], v[144:147], v[216:219], v[12:15]
	v_mfma_f32_16x16x32_bf16 v[24:27], v[160:163], v[208:211], v[24:27]
	v_mfma_f32_16x16x32_bf16 v[8:11], v[160:163], v[216:219], v[8:11]
	v_mfma_f32_16x16x32_bf16 v[60:63], v[156:159], v[190:193], v[60:63]
	v_mfma_f32_16x16x32_bf16 v[44:47], v[156:159], v[198:201], v[44:47]
	v_mfma_f32_16x16x32_bf16 v[56:59], v[164:167], v[190:193], v[56:59]
	v_mfma_f32_16x16x32_bf16 v[40:43], v[164:167], v[198:201], v[40:43]
	v_mfma_f32_16x16x32_bf16 v[28:31], v[156:159], v[212:215], v[28:31]
	v_mfma_f32_16x16x32_bf16 v[12:15], v[156:159], v[220:223], v[12:15]
	v_lshl_add_u64 v[224:225], v[228:229], 0, s[42:43]
	s_mov_b32 m0, s62
	s_nop 0
	global_load_lds_dwordx4 v[224:225], off
	v_mfma_f32_16x16x32_bf16 v[24:27], v[164:167], v[212:215], v[24:27]
	v_mfma_f32_16x16x32_bf16 v[8:11], v[164:167], v[220:223], v[8:11]
	s_setprio 0
	s_setprio 1
	v_mfma_f32_16x16x32_bf16 v[52:55], v[168:171], v[186:189], v[52:55]
	v_mfma_f32_16x16x32_bf16 v[36:39], v[168:171], v[194:197], v[36:39]
	v_mfma_f32_16x16x32_bf16 v[48:51], v[176:179], v[186:189], v[48:51]
	v_mfma_f32_16x16x32_bf16 v[32:35], v[176:179], v[194:197], v[32:35]
	v_mfma_f32_16x16x32_bf16 v[20:23], v[168:171], v[208:211], v[20:23]
	v_mfma_f32_16x16x32_bf16 v[4:7], v[168:171], v[216:219], v[4:7]
	v_mfma_f32_16x16x32_bf16 v[16:19], v[176:179], v[208:211], v[16:19]
	v_mfma_f32_16x16x32_bf16 v[0:3], v[176:179], v[216:219], v[0:3]
	v_mfma_f32_16x16x32_bf16 v[52:55], v[172:175], v[190:193], v[52:55]
	v_mfma_f32_16x16x32_bf16 v[36:39], v[172:175], v[198:201], v[36:39]
	v_mfma_f32_16x16x32_bf16 v[48:51], v[182:185], v[190:193], v[48:51]
	v_mfma_f32_16x16x32_bf16 v[32:35], v[182:185], v[198:201], v[32:35]
	v_mfma_f32_16x16x32_bf16 v[20:23], v[172:175], v[212:215], v[20:23]
	v_mfma_f32_16x16x32_bf16 v[4:7], v[172:175], v[220:223], v[4:7]
	v_lshl_add_u64 v[224:225], v[230:231], 0, s[42:43]
	s_mov_b32 m0, s63
	s_nop 0
	global_load_lds_dwordx4 v[224:225], off
	v_mfma_f32_16x16x32_bf16 v[16:19], v[182:185], v[212:215], v[16:19]
	v_mfma_f32_16x16x32_bf16 v[0:3], v[182:185], v[220:223], v[0:3]
	s_setprio 0
	s_barrier
	s_add_i32 s84, s84, 2
	s_add_u32 s82, s82, 0x100
	s_addc_u32 s83, s83, 0
	s_cmp_gt_u32 s84, 41
	s_mov_b64 s[50:51], s[52:53]
	s_cbranch_scc0 .LBB0_1197
	s_and_b64 vcc, exec, s[44:45]
	s_cbranch_vccz .LBB0_1200
	s_barrier

; #define PG8_STAGE(bufoff, gbase, voff) do { _Pragma("unroll") for (int _i = 0; _i < 2; ++_i) \
;         __builtin_amdgcn_global_load_lds((const unsigned*)((const char*)(gbase) + (voff)[_i]), (PG8_LAS unsigned*)(lds + (bufoff) + ldsw + _i * 8192), 16, 0, 0); } while (0)
; #define PG8_LDA(dst, b, h) do { _Pragma("unroll") for (int m = 0; m < 4; ++m) _Pragma("unroll") for (int k = 0; k < 2; ++k) dst[m][k] = *(const PG8_LAS bf16x8*)(lds + PG8_SA(b, h) + aoff + m * 2048 + k * 1024); } while (0)
; #define PG8_LDB(dst, b, h) do { _Pragma("unroll") for (int n = 0; n < 2; ++n) _Pragma("unroll") for (int k = 0; k < 2; ++k) dst[n][k] = *(const PG8_LAS bf16x8*)(lds + PG8_SB(b, h) + boff + n * 2048 + k * 1024); } while (0)
; #define PG8_WAIT_V(n) asm volatile("s_waitcnt vmcnt(" #n ")" ::: "memory")
; #define PG8_WAIT_L(n) asm volatile("s_waitcnt lgkmcnt(" #n ")" ::: "memory")
; #define PG8_BAR __builtin_amdgcn_s_barrier()
; #define PG8_SCHED __builtin_amdgcn_sched_barrier(0)
; template <class Epi, class Sched, bool ALIGN_EPI = false, bool SP2 = false>
; __device__ __forceinline__ void gemm_phase(PG8_LAS unsigned char* lds, const Gemm g, const Sched& S, const Epi& E) {
;     ...
;         const bool has_next = S.next(ui + 1, nxt);
;         const char* nA = has_next ? (const char*)g.A + (size_t)nxt.pm * tstep : cA; const char* nB = has_next ? (const char*)g.Bt + (size_t)nxt.pn * tstep : cB;
;         for (int t = 0; t < nt; t += 2) {
;             const bool last = (t == nt - 2);
;             const char* a1 = cA + (size_t)(t + 1) * kstep;
;             const char* a2 = last ? nA : cA + (size_t)(t + 2) * kstep; const char* b2 = last ? nB : cB + (size_t)(t + 2) * kstep;
;             const char* a3 = a2 + kstep; const char* b3 = b2 + kstep;
;             if (last && has_next) S.a_ready(nxt);
;             if constexpr (SP2) {
;             PG8_LDB(B0, 0, 0); PG8_LDB(B1, 0, 1); PG8_SCHED; PG8_LDA(At, 0, 0); PG8_STAGE(PG8_SA(1, 1), a1 + hstep, voffA);
;             PG8_WAIT_V(8); PG8_WAIT_L(0); PG8_BAR; PG8_MMA(0, 0, At, B0); PG8_MMA(0, 1, At, B1); PG8_BAR; PG8_SCHED;
;             PG8_LDA(At, 0, 1); PG8_STAGE(PG8_SB(0, 0), b2, voffB); PG8_STAGE(PG8_SB(0, 1), b2 + hstep, voffB); PG8_STAGE(PG8_SA(0, 0), a2, voffA);
;             PG8_WAIT_V(8); PG8_WAIT_L(0); PG8_BAR; PG8_MMA(1, 0, At, B0); PG8_MMA(1, 1, At, B1); PG8_BAR; PG8_SCHED;
.LBB0_1286:
	s_ashr_i32 s51, s50, 31
	s_lshl_b64 s[52:53], s[50:51], 19
	s_add_u32 s52, s22, s52
	s_addc_u32 s53, s23, s53
	s_and_b64 s[54:55], s[12:13], exec
	s_cselect_b32 s51, s53, s59
	s_cselect_b32 s61, s52, s58
	s_ashr_i32 s49, s48, 31
	s_lshl_b64 s[54:55], s[48:49], 19
	v_readlane_b32 s64, v250, 9
	v_readlane_b32 s65, v250, 10
	s_add_u32 s54, s64, s54
	s_addc_u32 s55, s65, s55
	s_and_b64 s[64:65], s[12:13], exec
	s_cselect_b32 s49, s55, s63
	s_cselect_b32 s87, s54, s62
	s_add_u32 s58, s58, 0x40080
	s_addc_u32 s59, s59, 0
	s_add_u32 s88, s62, 0x100
	s_addc_u32 s89, s63, 0
	s_mov_b32 s90, -2
	s_waitcnt lgkmcnt(0)
	ds_read_b128 v[128:131], v181
	ds_read_b128 v[160:163], v181 offset:1024
	ds_read_b128 v[164:167], v181 offset:2048
	ds_read_b128 v[168:171], v181 offset:3072
	ds_read_b128 v[172:175], v203
	ds_read_b128 v[176:179], v203 offset:1024
	ds_read_b128 v[182:185], v203 offset:2048
	ds_read_b128 v[186:189], v203 offset:3072
	s_add_u32 s62, s58, 0xfffc0080
	s_addc_u32 s63, s59, -1
	s_cmp_eq_u32 s90, 12
	s_cselect_b32 s65, s51, s63
	s_cselect_b32 s64, s61, s62
	s_cselect_b32 s63, s49, s89
	s_cselect_b32 s62, s87, s88
	v_lshl_add_u64 v[232:233], s[58:59], 0, v[152:153]
	s_add_i32 m0, s15, 0xc000
	ds_read_b128 v[190:193], v208
	ds_read_b128 v[194:197], v208 offset:1024
	ds_read_b128 v[198:201], v208 offset:2048
	ds_read_b128 v[212:215], v208 offset:3072
	ds_read_b128 v[216:219], v208 offset:4096
	ds_read_b128 v[220:223], v208 offset:5120
	ds_read_b128 v[224:227], v208 offset:6144
	ds_read_b128 v[228:231], v208 offset:7168
	global_load_lds_dwordx4 v[232:233], off
	v_lshl_add_u64 v[232:233], s[58:59], 0, v[154:155]
	s_add_i32 m0, s15, 0xe000
	s_nop 0
	global_load_lds_dwordx4 v[232:233], off
	s_waitcnt vmcnt(8)
	s_waitcnt lgkmcnt(0)
	s_barrier
	s_setprio 1
	s_waitcnt lgkmcnt(0)
	v_mfma_f32_16x16x32_bf16 v[124:127], v[128:131], v[190:193], 0
	v_mfma_f32_16x16x32_bf16 v[116:119], v[128:131], v[198:201], 0
	v_mfma_f32_16x16x32_bf16 v[120:123], v[164:167], v[190:193], 0
	v_mfma_f32_16x16x32_bf16 v[112:115], v[164:167], v[198:201], 0
	v_mfma_f32_16x16x32_bf16 v[108:111], v[128:131], v[216:219], 0
	v_mfma_f32_16x16x32_bf16 v[100:103], v[128:131], v[224:227], 0
	v_mfma_f32_16x16x32_bf16 v[104:107], v[164:167], v[216:219], 0
	v_mfma_f32_16x16x32_bf16 v[96:99], v[164:167], v[224:227], 0
	v_mfma_f32_16x16x32_bf16 v[124:127], v[160:163], v[194:197], v[124:127]
	v_mfma_f32_16x16x32_bf16 v[116:119], v[160:163], v[212:215], v[116:119]
	v_mfma_f32_16x16x32_bf16 v[120:123], v[168:171], v[194:197], v[120:123]
	v_mfma_f32_16x16x32_bf16 v[112:115], v[168:171], v[212:215], v[112:115]
	v_mfma_f32_16x16x32_bf16 v[108:111], v[160:163], v[220:223], v[108:111]
	v_mfma_f32_16x16x32_bf16 v[100:103], v[160:163], v[228:231], v[100:103]
	v_mfma_f32_16x16x32_bf16 v[104:107], v[168:171], v[220:223], v[104:107]
	v_mfma_f32_16x16x32_bf16 v[96:99], v[168:171], v[228:231], v[96:99]
	s_setprio 0
	s_setprio 1
	v_mfma_f32_16x16x32_bf16 v[60:63], v[172:175], v[190:193], 0
	v_mfma_f32_16x16x32_bf16 v[52:55], v[172:175], v[198:201], 0
	v_mfma_f32_16x16x32_bf16 v[56:59], v[182:185], v[190:193], 0
	v_mfma_f32_16x16x32_bf16 v[48:51], v[182:185], v[198:201], 0
	v_mfma_f32_16x16x32_bf16 v[44:47], v[172:175], v[216:219], 0
	v_mfma_f32_16x16x32_bf16 v[36:39], v[172:175], v[224:227], 0
	v_mfma_f32_16x16x32_bf16 v[40:43], v[182:185], v[216:219], 0
	v_mfma_f32_16x16x32_bf16 v[32:35], v[182:185], v[224:227], 0
	v_mfma_f32_16x16x32_bf16 v[60:63], v[176:179], v[194:197], v[60:63]
	v_mfma_f32_16x16x32_bf16 v[52:55], v[176:179], v[212:215], v[52:55]
	v_mfma_f32_16x16x32_bf16 v[56:59], v[186:189], v[194:197], v[56:59]
	v_mfma_f32_16x16x32_bf16 v[48:51], v[186:189], v[212:215], v[48:51]
	v_mfma_f32_16x16x32_bf16 v[44:47], v[176:179], v[220:223], v[44:47]
	v_mfma_f32_16x16x32_bf16 v[36:39], v[176:179], v[228:231], v[36:39]
	v_mfma_f32_16x16x32_bf16 v[40:43], v[186:189], v[220:223], v[40:43]
	v_mfma_f32_16x16x32_bf16 v[32:35], v[186:189], v[228:231], v[32:35]
	s_setprio 0
	s_barrier
	s_add_i32 s78, s75, s14
	v_lshl_add_u64 v[232:233], s[62:63], 0, v[134:135]
	s_mov_b32 m0, s78
	ds_read_b128 v[190:193], v208 offset:16384
	ds_read_b128 v[194:197], v208 offset:17408
	ds_read_b128 v[198:201], v208 offset:18432
	ds_read_b128 v[212:215], v208 offset:19456
	ds_read_b128 v[216:219], v208 offset:20480
	ds_read_b128 v[220:223], v208 offset:21504
	ds_read_b128 v[224:227], v208 offset:22528
	ds_read_b128 v[228:231], v208 offset:23552
	global_load_lds_dwordx4 v[232:233], off
	s_add_i32 m0, s78, 0x2000
	s_add_u32 s78, s62, 0x40000
	v_lshl_add_u64 v[234:235], s[62:63], 0, v[138:139]
	s_addc_u32 s79, s63, 0
	s_add_i32 s91, s76, s14
	global_load_lds_dwordx4 v[234:235], off
	v_lshl_add_u64 v[236:237], s[78:79], 0, v[134:135]
	s_mov_b32 m0, s91
	global_load_lds_dwordx4 v[236:237], off
	v_lshl_add_u64 v[236:237], s[78:79], 0, v[138:139]
	s_add_i32 m0, s91, 0x2000
	s_nop 0
	global_load_lds_dwordx4 v[236:237], off
	s_waitcnt vmcnt(6)
	s_waitcnt lgkmcnt(0)
	s_barrier
; #define PG8_STAGE(bufoff, gbase, voff) do { _Pragma("unroll") for (int _i = 0; _i < 2; ++_i) \
;         __builtin_amdgcn_global_load_lds((const unsigned*)((const char*)(gbase) + (voff)[_i]), (PG8_LAS unsigned*)(lds + (bufoff) + ldsw + _i * 8192), 16, 0, 0); } while (0)
; #define PG8_LDA(dst, b, h) do { _Pragma("unroll") for (int m = 0; m < 4; ++m) _Pragma("unroll") for (int k = 0; k < 2; ++k) dst[m][k] = *(const PG8_LAS bf16x8*)(lds + PG8_SA(b, h) + aoff + m * 2048 + k * 1024); } while (0)
; #define PG8_LDB(dst, b, h) do { _Pragma("unroll") for (int n = 0; n < 2; ++n) _Pragma("unroll") for (int k = 0; k < 2; ++k) dst[n][k] = *(const PG8_LAS bf16x8*)(lds + PG8_SB(b, h) + boff + n * 2048 + k * 1024); } while (0)
; #define PG8_MMA(ai, bj, At, Bt) do { __builtin_amdgcn_s_setprio(1); _Pragma("unroll") for (int m = 0; m < 4; ++m) _Pragma("unroll") for (int n = 0; n < 2; ++n) _Pragma("unroll") for (int k = 0; k < 2; ++k) \
;         acc[ai][bj][m][n] = __builtin_amdgcn_mfma_f32_16x16x32_bf16(Bt[n][k], At[m][k], acc[ai][bj][m][n], 0, 0, 0); __builtin_amdgcn_s_setprio(0); } while (0)
; #define PG8_WAIT_V(n) asm volatile("s_waitcnt vmcnt(" #n ")" ::: "memory")
; #define PG8_WAIT_L(n) asm volatile("s_waitcnt lgkmcnt(" #n ")" ::: "memory")
; #define PG8_BAR __builtin_amdgcn_s_barrier()
; #define PG8_SCHED __builtin_amdgcn_sched_barrier(0)
; template <class Epi, class Sched, bool ALIGN_EPI = false, bool SP2 = false>
; __device__ __forceinline__ void gemm_phase(PG8_LAS unsigned char* lds, const Gemm g, const Sched& S, const Epi& E) {
;     ...
;             PG8_WAIT_V(8); PG8_WAIT_L(0); PG8_BAR; PG8_MMA(1, 0, At, B0); PG8_MMA(1, 1, At, B1); PG8_BAR; PG8_SCHED;
;             PG8_LDB(B0, 1, 0); PG8_LDB(B1, 1, 1); PG8_SCHED; PG8_LDA(At, 1, 0); PG8_STAGE(PG8_SA(0, 1), a2 + hstep, voffA);
;             PG8_WAIT_V(8); PG8_WAIT_L(0); PG8_BAR; PG8_MMA(0, 0, At, B0); PG8_MMA(0, 1, At, B1); PG8_BAR; PG8_SCHED;
	s_setprio 1
	s_waitcnt lgkmcnt(0)
	v_mfma_f32_16x16x32_bf16 v[92:95], v[128:131], v[190:193], 0
	v_mfma_f32_16x16x32_bf16 v[84:87], v[128:131], v[198:201], 0
	v_mfma_f32_16x16x32_bf16 v[88:91], v[164:167], v[190:193], 0
	v_mfma_f32_16x16x32_bf16 v[80:83], v[164:167], v[198:201], 0
	v_mfma_f32_16x16x32_bf16 v[76:79], v[128:131], v[216:219], 0
	v_mfma_f32_16x16x32_bf16 v[68:71], v[128:131], v[224:227], 0
	v_mfma_f32_16x16x32_bf16 v[72:75], v[164:167], v[216:219], 0
	v_mfma_f32_16x16x32_bf16 v[64:67], v[164:167], v[224:227], 0
	v_mfma_f32_16x16x32_bf16 v[92:95], v[160:163], v[194:197], v[92:95]
	v_mfma_f32_16x16x32_bf16 v[84:87], v[160:163], v[212:215], v[84:87]
	v_mfma_f32_16x16x32_bf16 v[88:91], v[168:171], v[194:197], v[88:91]
	v_mfma_f32_16x16x32_bf16 v[80:83], v[168:171], v[212:215], v[80:83]
	v_mfma_f32_16x16x32_bf16 v[76:79], v[160:163], v[220:223], v[76:79]
	v_mfma_f32_16x16x32_bf16 v[68:71], v[160:163], v[228:231], v[68:71]
	v_lshl_add_u64 v[236:237], s[64:65], 0, v[132:133]
	s_mov_b32 m0, s15
	s_nop 0
	global_load_lds_dwordx4 v[236:237], off
	v_mfma_f32_16x16x32_bf16 v[72:75], v[168:171], v[220:223], v[72:75]
	v_mfma_f32_16x16x32_bf16 v[64:67], v[168:171], v[228:231], v[64:67]
	s_setprio 0
	s_setprio 1
	v_mfma_f32_16x16x32_bf16 v[28:31], v[172:175], v[190:193], 0
	v_mfma_f32_16x16x32_bf16 v[20:23], v[172:175], v[198:201], 0
	v_mfma_f32_16x16x32_bf16 v[24:27], v[182:185], v[190:193], 0
	v_mfma_f32_16x16x32_bf16 v[16:19], v[182:185], v[198:201], 0
	v_mfma_f32_16x16x32_bf16 v[12:15], v[172:175], v[216:219], 0
	v_mfma_f32_16x16x32_bf16 v[4:7], v[172:175], v[224:227], 0
	v_mfma_f32_16x16x32_bf16 v[8:11], v[182:185], v[216:219], 0
	v_mfma_f32_16x16x32_bf16 v[0:3], v[182:185], v[224:227], 0
	v_mfma_f32_16x16x32_bf16 v[28:31], v[176:179], v[194:197], v[28:31]
	v_mfma_f32_16x16x32_bf16 v[20:23], v[176:179], v[212:215], v[20:23]
	v_mfma_f32_16x16x32_bf16 v[24:27], v[186:189], v[194:197], v[24:27]
	v_mfma_f32_16x16x32_bf16 v[16:19], v[186:189], v[212:215], v[16:19]
	v_mfma_f32_16x16x32_bf16 v[12:15], v[176:179], v[220:223], v[12:15]
	v_mfma_f32_16x16x32_bf16 v[4:7], v[176:179], v[228:231], v[4:7]
	v_lshl_add_u64 v[238:239], s[64:65], 0, v[136:137]
	s_mov_b32 m0, s33
	s_nop 0
	global_load_lds_dwordx4 v[238:239], off
	v_mfma_f32_16x16x32_bf16 v[8:11], v[186:189], v[220:223], v[8:11]
	v_mfma_f32_16x16x32_bf16 v[0:3], v[186:189], v[228:231], v[0:3]
	s_setprio 0
	s_barrier
	s_add_i32 s78, 0, 0x18000
	v_add_u32_e32 v140, s78, v147
	s_add_i32 s79, 0, 0x1c000
	ds_read_b128 v[128:131], v140
	ds_read_b128 v[160:163], v140 offset:1024
	ds_read_b128 v[164:167], v140 offset:2048
	ds_read_b128 v[168:171], v140 offset:3072
	v_add_u32_e32 v140, s79, v147
	ds_read_b128 v[172:175], v140
	ds_read_b128 v[176:179], v140 offset:1024
	ds_read_b128 v[182:185], v140 offset:2048
	ds_read_b128 v[186:189], v140 offset:3072
	s_add_u32 s64, s64, 0x40000
	s_addc_u32 s65, s65, 0
	s_mov_b32 m0, s34
	v_lshl_add_u64 v[240:241], s[64:65], 0, v[132:133]
	ds_read_b128 v[190:193], v208 offset:32768
	ds_read_b128 v[194:197], v208 offset:33792
	ds_read_b128 v[198:201], v208 offset:34816
	ds_read_b128 v[212:215], v208 offset:35840
	ds_read_b128 v[216:219], v208 offset:36864
	ds_read_b128 v[220:223], v208 offset:37888
	ds_read_b128 v[224:227], v208 offset:38912
	ds_read_b128 v[228:231], v208 offset:39936
	global_load_lds_dwordx4 v[240:241], off
	v_lshl_add_u64 v[240:241], s[64:65], 0, v[136:137]
	s_mov_b32 m0, s57
	s_nop 0
	global_load_lds_dwordx4 v[240:241], off
	s_waitcnt vmcnt(8)
	s_waitcnt lgkmcnt(0)
	s_barrier
	s_setprio 1
	s_waitcnt lgkmcnt(0)
	v_mfma_f32_16x16x32_bf16 v[124:127], v[128:131], v[190:193], v[124:127]
	v_mfma_f32_16x16x32_bf16 v[116:119], v[128:131], v[198:201], v[116:119]
	v_mfma_f32_16x16x32_bf16 v[120:123], v[164:167], v[190:193], v[120:123]
	v_mfma_f32_16x16x32_bf16 v[112:115], v[164:167], v[198:201], v[112:115]
	v_mfma_f32_16x16x32_bf16 v[108:111], v[128:131], v[216:219], v[108:111]
	v_mfma_f32_16x16x32_bf16 v[100:103], v[128:131], v[224:227], v[100:103]
	v_mfma_f32_16x16x32_bf16 v[104:107], v[164:167], v[216:219], v[104:107]
	v_mfma_f32_16x16x32_bf16 v[96:99], v[164:167], v[224:227], v[96:99]
	v_mfma_f32_16x16x32_bf16 v[124:127], v[160:163], v[194:197], v[124:127]
	v_mfma_f32_16x16x32_bf16 v[116:119], v[160:163], v[212:215], v[116:119]
	v_mfma_f32_16x16x32_bf16 v[120:123], v[168:171], v[194:197], v[120:123]
	v_mfma_f32_16x16x32_bf16 v[112:115], v[168:171], v[212:215], v[112:115]
	v_mfma_f32_16x16x32_bf16 v[108:111], v[160:163], v[220:223], v[108:111]
	v_mfma_f32_16x16x32_bf16 v[100:103], v[160:163], v[228:231], v[100:103]
	v_mfma_f32_16x16x32_bf16 v[104:107], v[168:171], v[220:223], v[104:107]
	v_mfma_f32_16x16x32_bf16 v[96:99], v[168:171], v[228:231], v[96:99]
	s_setprio 0
	s_setprio 1
	v_mfma_f32_16x16x32_bf16 v[60:63], v[172:175], v[190:193], v[60:63]
	v_mfma_f32_16x16x32_bf16 v[52:55], v[172:175], v[198:201], v[52:55]
	v_mfma_f32_16x16x32_bf16 v[56:59], v[182:185], v[190:193], v[56:59]
	v_mfma_f32_16x16x32_bf16 v[48:51], v[182:185], v[198:201], v[48:51]
	v_mfma_f32_16x16x32_bf16 v[44:47], v[172:175], v[216:219], v[44:47]
	v_mfma_f32_16x16x32_bf16 v[36:39], v[172:175], v[224:227], v[36:39]
	v_mfma_f32_16x16x32_bf16 v[40:43], v[182:185], v[216:219], v[40:43]
	v_mfma_f32_16x16x32_bf16 v[32:35], v[182:185], v[224:227], v[32:35]
	v_mfma_f32_16x16x32_bf16 v[60:63], v[176:179], v[194:197], v[60:63]
	v_mfma_f32_16x16x32_bf16 v[52:55], v[176:179], v[212:215], v[52:55]
	v_mfma_f32_16x16x32_bf16 v[56:59], v[186:189], v[194:197], v[56:59]
	v_mfma_f32_16x16x32_bf16 v[48:51], v[186:189], v[212:215], v[48:51]
	v_mfma_f32_16x16x32_bf16 v[44:47], v[176:179], v[220:223], v[44:47]
	v_mfma_f32_16x16x32_bf16 v[36:39], v[176:179], v[228:231], v[36:39]
	v_mfma_f32_16x16x32_bf16 v[40:43], v[186:189], v[220:223], v[40:43]
	v_mfma_f32_16x16x32_bf16 v[32:35], v[186:189], v[228:231], v[32:35]
	s_setprio 0
	s_barrier
; #define PG8_STAGE(bufoff, gbase, voff) do { _Pragma("unroll") for (int _i = 0; _i < 2; ++_i) \
;         __builtin_amdgcn_global_load_lds((const unsigned*)((const char*)(gbase) + (voff)[_i]), (PG8_LAS unsigned*)(lds + (bufoff) + ldsw + _i * 8192), 16, 0, 0); } while (0)
; #define PG8_LDA(dst, b, h) do { _Pragma("unroll") for (int m = 0; m < 4; ++m) _Pragma("unroll") for (int k = 0; k < 2; ++k) dst[m][k] = *(const PG8_LAS bf16x8*)(lds + PG8_SA(b, h) + aoff + m * 2048 + k * 1024); } while (0)
; #define PG8_LDB(dst, b, h) do { _Pragma("unroll") for (int n = 0; n < 2; ++n) _Pragma("unroll") for (int k = 0; k < 2; ++k) dst[n][k] = *(const PG8_LAS bf16x8*)(lds + PG8_SB(b, h) + boff + n * 2048 + k * 1024); } while (0)
; template <class Epi, class Sched, bool ALIGN_EPI = false, bool SP2 = false>
; __device__ __forceinline__ void gemm_phase(PG8_LAS unsigned char* lds, const Gemm g, const Sched& S, const Epi& E) {
;     ...
;         for (int t = 0; t < nt; t += 2) {
;             const bool last = (t == nt - 2);
;             const char* a1 = cA + (size_t)(t + 1) * kstep;
;             const char* a2 = last ? nA : cA + (size_t)(t + 2) * kstep; const char* b2 = last ? nB : cB + (size_t)(t + 2) * kstep;
;             const char* a3 = a2 + kstep; const char* b3 = b2 + kstep;
;             if (last && has_next) S.a_ready(nxt);
;             if constexpr (SP2) {
;             PG8_LDB(B0, 0, 0); PG8_LDB(B1, 0, 1); PG8_SCHED; PG8_LDA(At, 0, 0); PG8_STAGE(PG8_SA(1, 1), a1 + hstep, voffA);
;             PG8_WAIT_V(8); PG8_WAIT_L(0); PG8_BAR; PG8_MMA(0, 0, At, B0); PG8_MMA(0, 1, At, B1); PG8_BAR; PG8_SCHED;
;             PG8_LDA(At, 0, 1); PG8_STAGE(PG8_SB(0, 0), b2, voffB); PG8_STAGE(PG8_SB(0, 1), b2 + hstep, voffB); PG8_STAGE(PG8_SA(0, 0), a2, voffA);
;             PG8_WAIT_V(8); PG8_WAIT_L(0); PG8_BAR; PG8_MMA(1, 0, At, B0); PG8_MMA(1, 1, At, B1); PG8_BAR; PG8_SCHED;
;             PG8_LDB(B0, 1, 0); PG8_LDB(B1, 1, 1); PG8_SCHED; PG8_LDA(At, 1, 0); PG8_STAGE(PG8_SA(0, 1), a2 + hstep, voffA);
;             PG8_WAIT_V(8); PG8_WAIT_L(0); PG8_BAR; PG8_MMA(0, 0, At, B0); PG8_MMA(0, 1, At, B1); PG8_BAR; PG8_SCHED;
;             PG8_LDA(At, 1, 1); PG8_STAGE(PG8_SB(1, 0), b3, voffB); PG8_STAGE(PG8_SB(1, 1), b3 + hstep, voffB); PG8_STAGE(PG8_SA(1, 0), a3, voffA);
;             PG8_WAIT_V(8); PG8_WAIT_L(0); PG8_BAR; PG8_MMA(1, 0, At, B0); PG8_MMA(1, 1, At, B1); PG8_BAR; PG8_SCHED;
	s_add_i32 s64, s78, s14
	v_lshl_add_u64 v[232:233], v[232:233], 0, s[42:43]
	s_mov_b32 m0, s64
	ds_read_b128 v[190:193], v208 offset:49152
	ds_read_b128 v[194:197], v208 offset:50176
	ds_read_b128 v[198:201], v208 offset:51200
	ds_read_b128 v[212:215], v208 offset:52224
	ds_read_b128 v[216:219], v208 offset:53248
	ds_read_b128 v[220:223], v208 offset:54272
	ds_read_b128 v[224:227], v208 offset:55296
	ds_read_b128 v[228:231], v208 offset:56320
	global_load_lds_dwordx4 v[232:233], off
	s_add_i32 m0, s64, 0x2000
	s_add_u32 s62, s62, 0x40080
	v_lshl_add_u64 v[232:233], v[234:235], 0, s[42:43]
	s_addc_u32 s63, s63, 0
	s_add_i32 s64, s79, s14
	global_load_lds_dwordx4 v[232:233], off
	v_lshl_add_u64 v[232:233], s[62:63], 0, v[134:135]
	s_mov_b32 m0, s64
	s_nop 0
	global_load_lds_dwordx4 v[232:233], off
	v_lshl_add_u64 v[232:233], s[62:63], 0, v[138:139]
	s_add_i32 m0, s64, 0x2000
	s_nop 0
	global_load_lds_dwordx4 v[232:233], off
	s_waitcnt vmcnt(6)
	s_waitcnt lgkmcnt(0)
	s_barrier
	s_setprio 1
	s_waitcnt lgkmcnt(0)
	v_mfma_f32_16x16x32_bf16 v[92:95], v[128:131], v[190:193], v[92:95]
	v_mfma_f32_16x16x32_bf16 v[84:87], v[128:131], v[198:201], v[84:87]
	v_mfma_f32_16x16x32_bf16 v[88:91], v[164:167], v[190:193], v[88:91]
	v_mfma_f32_16x16x32_bf16 v[80:83], v[164:167], v[198:201], v[80:83]
	v_mfma_f32_16x16x32_bf16 v[76:79], v[128:131], v[216:219], v[76:79]
	v_mfma_f32_16x16x32_bf16 v[68:71], v[128:131], v[224:227], v[68:71]
	v_mfma_f32_16x16x32_bf16 v[72:75], v[164:167], v[216:219], v[72:75]
	v_mfma_f32_16x16x32_bf16 v[64:67], v[164:167], v[224:227], v[64:67]
	v_mfma_f32_16x16x32_bf16 v[92:95], v[160:163], v[194:197], v[92:95]
	v_mfma_f32_16x16x32_bf16 v[84:87], v[160:163], v[212:215], v[84:87]
	v_mfma_f32_16x16x32_bf16 v[88:91], v[168:171], v[194:197], v[88:91]
	v_mfma_f32_16x16x32_bf16 v[80:83], v[168:171], v[212:215], v[80:83]
	v_mfma_f32_16x16x32_bf16 v[76:79], v[160:163], v[220:223], v[76:79]
	v_mfma_f32_16x16x32_bf16 v[68:71], v[160:163], v[228:231], v[68:71]
	v_lshl_add_u64 v[232:233], v[236:237], 0, s[42:43]
	s_mov_b32 m0, s67
	s_nop 0
	global_load_lds_dwordx4 v[232:233], off
	v_mfma_f32_16x16x32_bf16 v[72:75], v[168:171], v[220:223], v[72:75]
	v_mfma_f32_16x16x32_bf16 v[64:67], v[168:171], v[228:231], v[64:67]
	s_setprio 0
	s_setprio 1
	v_mfma_f32_16x16x32_bf16 v[28:31], v[172:175], v[190:193], v[28:31]
	v_mfma_f32_16x16x32_bf16 v[20:23], v[172:175], v[198:201], v[20:23]
	v_mfma_f32_16x16x32_bf16 v[24:27], v[182:185], v[190:193], v[24:27]
	v_mfma_f32_16x16x32_bf16 v[16:19], v[182:185], v[198:201], v[16:19]
	v_mfma_f32_16x16x32_bf16 v[12:15], v[172:175], v[216:219], v[12:15]
	v_mfma_f32_16x16x32_bf16 v[4:7], v[172:175], v[224:227], v[4:7]
	v_mfma_f32_16x16x32_bf16 v[8:11], v[182:185], v[216:219], v[8:11]
	v_mfma_f32_16x16x32_bf16 v[0:3], v[182:185], v[224:227], v[0:3]
	v_mfma_f32_16x16x32_bf16 v[28:31], v[176:179], v[194:197], v[28:31]
	v_mfma_f32_16x16x32_bf16 v[20:23], v[176:179], v[212:215], v[20:23]
	v_mfma_f32_16x16x32_bf16 v[24:27], v[186:189], v[194:197], v[24:27]
	v_mfma_f32_16x16x32_bf16 v[16:19], v[186:189], v[212:215], v[16:19]
	v_mfma_f32_16x16x32_bf16 v[12:15], v[176:179], v[220:223], v[12:15]
	v_mfma_f32_16x16x32_bf16 v[4:7], v[176:179], v[228:231], v[4:7]
	v_lshl_add_u64 v[232:233], v[238:239], 0, s[42:43]
	s_mov_b32 m0, s74
	s_nop 0
	global_load_lds_dwordx4 v[232:233], off
	v_mfma_f32_16x16x32_bf16 v[8:11], v[186:189], v[220:223], v[8:11]
	v_mfma_f32_16x16x32_bf16 v[0:3], v[186:189], v[228:231], v[0:3]
	s_setprio 0
	s_barrier
	s_add_i32 s90, s90, 2
	s_add_u32 s58, s58, 0x100
	s_addc_u32 s59, s59, 0
	s_add_u32 s88, s88, 0x100
	s_addc_u32 s89, s89, 0
.LBB0_1287:
	ds_read_b128 v[128:131], v181
	ds_read_b128 v[160:163], v181 offset:1024
	ds_read_b128 v[164:167], v181 offset:2048
	ds_read_b128 v[168:171], v181 offset:3072
	ds_read_b128 v[172:175], v203
	ds_read_b128 v[176:179], v203 offset:1024
	ds_read_b128 v[182:185], v203 offset:2048
	ds_read_b128 v[186:189], v203 offset:3072
	s_add_u32 s62, s58, 0xfffc0080
	s_addc_u32 s63, s59, -1
	s_cmp_eq_u32 s90, 12
	s_cselect_b32 s65, s51, s63
	s_cselect_b32 s64, s61, s62
	s_cselect_b32 s63, s49, s89
	s_cselect_b32 s62, s87, s88
	v_lshl_add_u64 v[232:233], s[58:59], 0, v[152:153]
	s_add_i32 m0, s15, 0xc000
	ds_read_b128 v[190:193], v208
	ds_read_b128 v[194:197], v208 offset:1024
	ds_read_b128 v[198:201], v208 offset:2048
	ds_read_b128 v[212:215], v208 offset:3072
	ds_read_b128 v[216:219], v208 offset:4096
	ds_read_b128 v[220:223], v208 offset:5120
	ds_read_b128 v[224:227], v208 offset:6144
	ds_read_b128 v[228:231], v208 offset:7168
	global_load_lds_dwordx4 v[232:233], off
	v_lshl_add_u64 v[232:233], s[58:59], 0, v[154:155]
	s_add_i32 m0, s15, 0xe000
	s_nop 0
	global_load_lds_dwordx4 v[232:233], off
	s_waitcnt vmcnt(8)
	s_waitcnt lgkmcnt(0)
	s_barrier
; #define PG8_STAGE(bufoff, gbase, voff) do { _Pragma("unroll") for (int _i = 0; _i < 2; ++_i) \
;         __builtin_amdgcn_global_load_lds((const unsigned*)((const char*)(gbase) + (voff)[_i]), (PG8_LAS unsigned*)(lds + (bufoff) + ldsw + _i * 8192), 16, 0, 0); } while (0)
; #define PG8_LDA(dst, b, h) do { _Pragma("unroll") for (int m = 0; m < 4; ++m) _Pragma("unroll") for (int k = 0; k < 2; ++k) dst[m][k] = *(const PG8_LAS bf16x8*)(lds + PG8_SA(b, h) + aoff + m * 2048 + k * 1024); } while (0)
; #define PG8_MMA(ai, bj, At, Bt) do { __builtin_amdgcn_s_setprio(1); _Pragma("unroll") for (int m = 0; m < 4; ++m) _Pragma("unroll") for (int n = 0; n < 2; ++n) _Pragma("unroll") for (int k = 0; k < 2; ++k) \
;         acc[ai][bj][m][n] = __builtin_amdgcn_mfma_f32_16x16x32_bf16(Bt[n][k], At[m][k], acc[ai][bj][m][n], 0, 0, 0); __builtin_amdgcn_s_setprio(0); } while (0)
; #define PG8_WAIT_V(n) asm volatile("s_waitcnt vmcnt(" #n ")" ::: "memory")
; #define PG8_WAIT_L(n) asm volatile("s_waitcnt lgkmcnt(" #n ")" ::: "memory")
; #define PG8_BAR __builtin_amdgcn_s_barrier()
; #define PG8_SCHED __builtin_amdgcn_sched_barrier(0)
; template <class Epi, class Sched, bool ALIGN_EPI = false, bool SP2 = false>
; __device__ __forceinline__ void gemm_phase(PG8_LAS unsigned char* lds, const Gemm g, const Sched& S, const Epi& E) {
;     ...
;             PG8_WAIT_V(8); PG8_WAIT_L(0); PG8_BAR; PG8_MMA(0, 0, At, B0); PG8_MMA(0, 1, At, B1); PG8_BAR; PG8_SCHED;
;             PG8_LDA(At, 0, 1); PG8_STAGE(PG8_SB(0, 0), b2, voffB); PG8_STAGE(PG8_SB(0, 1), b2 + hstep, voffB); PG8_STAGE(PG8_SA(0, 0), a2, voffA);
;             PG8_WAIT_V(8); PG8_WAIT_L(0); PG8_BAR; PG8_MMA(1, 0, At, B0); PG8_MMA(1, 1, At, B1); PG8_BAR; PG8_SCHED;
	s_setprio 1
	s_waitcnt lgkmcnt(0)
	v_mfma_f32_16x16x32_bf16 v[124:127], v[128:131], v[190:193], v[124:127]
	v_mfma_f32_16x16x32_bf16 v[116:119], v[128:131], v[198:201], v[116:119]
	v_mfma_f32_16x16x32_bf16 v[120:123], v[164:167], v[190:193], v[120:123]
	v_mfma_f32_16x16x32_bf16 v[112:115], v[164:167], v[198:201], v[112:115]
	v_mfma_f32_16x16x32_bf16 v[108:111], v[128:131], v[216:219], v[108:111]
	v_mfma_f32_16x16x32_bf16 v[100:103], v[128:131], v[224:227], v[100:103]
	v_mfma_f32_16x16x32_bf16 v[104:107], v[164:167], v[216:219], v[104:107]
	v_mfma_f32_16x16x32_bf16 v[96:99], v[164:167], v[224:227], v[96:99]
	v_mfma_f32_16x16x32_bf16 v[124:127], v[160:163], v[194:197], v[124:127]
	v_mfma_f32_16x16x32_bf16 v[116:119], v[160:163], v[212:215], v[116:119]
	v_mfma_f32_16x16x32_bf16 v[120:123], v[168:171], v[194:197], v[120:123]
	v_mfma_f32_16x16x32_bf16 v[112:115], v[168:171], v[212:215], v[112:115]
	v_mfma_f32_16x16x32_bf16 v[108:111], v[160:163], v[220:223], v[108:111]
	v_mfma_f32_16x16x32_bf16 v[100:103], v[160:163], v[228:231], v[100:103]
	v_mfma_f32_16x16x32_bf16 v[104:107], v[168:171], v[220:223], v[104:107]
	v_mfma_f32_16x16x32_bf16 v[96:99], v[168:171], v[228:231], v[96:99]
	s_setprio 0
	s_setprio 1
	v_mfma_f32_16x16x32_bf16 v[60:63], v[172:175], v[190:193], v[60:63]
	v_mfma_f32_16x16x32_bf16 v[52:55], v[172:175], v[198:201], v[52:55]
	v_mfma_f32_16x16x32_bf16 v[56:59], v[182:185], v[190:193], v[56:59]
	v_mfma_f32_16x16x32_bf16 v[48:51], v[182:185], v[198:201], v[48:51]
	v_mfma_f32_16x16x32_bf16 v[44:47], v[172:175], v[216:219], v[44:47]
	v_mfma_f32_16x16x32_bf16 v[36:39], v[172:175], v[224:227], v[36:39]
	v_mfma_f32_16x16x32_bf16 v[40:43], v[182:185], v[216:219], v[40:43]
	v_mfma_f32_16x16x32_bf16 v[32:35], v[182:185], v[224:227], v[32:35]
	v_mfma_f32_16x16x32_bf16 v[60:63], v[176:179], v[194:197], v[60:63]
	v_mfma_f32_16x16x32_bf16 v[52:55], v[176:179], v[212:215], v[52:55]
	v_mfma_f32_16x16x32_bf16 v[56:59], v[186:189], v[194:197], v[56:59]
	v_mfma_f32_16x16x32_bf16 v[48:51], v[186:189], v[212:215], v[48:51]
	v_mfma_f32_16x16x32_bf16 v[44:47], v[176:179], v[220:223], v[44:47]
	v_mfma_f32_16x16x32_bf16 v[36:39], v[176:179], v[228:231], v[36:39]
	v_mfma_f32_16x16x32_bf16 v[40:43], v[186:189], v[220:223], v[40:43]
	v_mfma_f32_16x16x32_bf16 v[32:35], v[186:189], v[228:231], v[32:35]
	s_setprio 0
	s_barrier
	s_add_i32 s78, s75, s14
	v_lshl_add_u64 v[232:233], s[62:63], 0, v[134:135]
	s_mov_b32 m0, s78
	ds_read_b128 v[190:193], v208 offset:16384
	ds_read_b128 v[194:197], v208 offset:17408
	ds_read_b128 v[198:201], v208 offset:18432
	ds_read_b128 v[212:215], v208 offset:19456
	ds_read_b128 v[216:219], v208 offset:20480
	ds_read_b128 v[220:223], v208 offset:21504
	ds_read_b128 v[224:227], v208 offset:22528
	ds_read_b128 v[228:231], v208 offset:23552
	global_load_lds_dwordx4 v[232:233], off
	s_add_i32 m0, s78, 0x2000
	s_add_u32 s78, s62, 0x40000
	v_lshl_add_u64 v[234:235], s[62:63], 0, v[138:139]
	s_addc_u32 s79, s63, 0
	s_add_i32 s91, s76, s14
	global_load_lds_dwordx4 v[234:235], off
	v_lshl_add_u64 v[236:237], s[78:79], 0, v[134:135]
	s_mov_b32 m0, s91
	global_load_lds_dwordx4 v[236:237], off
	v_lshl_add_u64 v[236:237], s[78:79], 0, v[138:139]
	s_add_i32 m0, s91, 0x2000
	s_nop 0
	global_load_lds_dwordx4 v[236:237], off
	s_waitcnt vmcnt(6)
	s_waitcnt lgkmcnt(0)
	s_barrier
	s_setprio 1
	s_waitcnt lgkmcnt(0)
	v_mfma_f32_16x16x32_bf16 v[92:95], v[128:131], v[190:193], v[92:95]
	v_mfma_f32_16x16x32_bf16 v[84:87], v[128:131], v[198:201], v[84:87]
	v_mfma_f32_16x16x32_bf16 v[88:91], v[164:167], v[190:193], v[88:91]
	v_mfma_f32_16x16x32_bf16 v[80:83], v[164:167], v[198:201], v[80:83]
	v_mfma_f32_16x16x32_bf16 v[76:79], v[128:131], v[216:219], v[76:79]
	v_mfma_f32_16x16x32_bf16 v[68:71], v[128:131], v[224:227], v[68:71]
	v_mfma_f32_16x16x32_bf16 v[72:75], v[164:167], v[216:219], v[72:75]
	v_mfma_f32_16x16x32_bf16 v[64:67], v[164:167], v[224:227], v[64:67]
	v_mfma_f32_16x16x32_bf16 v[92:95], v[160:163], v[194:197], v[92:95]
	v_mfma_f32_16x16x32_bf16 v[84:87], v[160:163], v[212:215], v[84:87]
	v_mfma_f32_16x16x32_bf16 v[88:91], v[168:171], v[194:197], v[88:91]
	v_mfma_f32_16x16x32_bf16 v[80:83], v[168:171], v[212:215], v[80:83]
	v_mfma_f32_16x16x32_bf16 v[76:79], v[160:163], v[220:223], v[76:79]
	v_mfma_f32_16x16x32_bf16 v[68:71], v[160:163], v[228:231], v[68:71]
	v_lshl_add_u64 v[236:237], s[64:65], 0, v[132:133]
	s_mov_b32 m0, s15
	s_nop 0
	global_load_lds_dwordx4 v[236:237], off
	v_mfma_f32_16x16x32_bf16 v[72:75], v[168:171], v[220:223], v[72:75]
	v_mfma_f32_16x16x32_bf16 v[64:67], v[168:171], v[228:231], v[64:67]
	s_setprio 0
	s_setprio 1
	v_mfma_f32_16x16x32_bf16 v[28:31], v[172:175], v[190:193], v[28:31]
	v_mfma_f32_16x16x32_bf16 v[20:23], v[172:175], v[198:201], v[20:23]
	v_mfma_f32_16x16x32_bf16 v[24:27], v[182:185], v[190:193], v[24:27]
	v_mfma_f32_16x16x32_bf16 v[16:19], v[182:185], v[198:201], v[16:19]
	v_mfma_f32_16x16x32_bf16 v[12:15], v[172:175], v[216:219], v[12:15]
	v_mfma_f32_16x16x32_bf16 v[4:7], v[172:175], v[224:227], v[4:7]
	v_mfma_f32_16x16x32_bf16 v[8:11], v[182:185], v[216:219], v[8:11]
	v_mfma_f32_16x16x32_bf16 v[0:3], v[182:185], v[224:227], v[0:3]
	v_mfma_f32_16x16x32_bf16 v[28:31], v[176:179], v[194:197], v[28:31]
	v_mfma_f32_16x16x32_bf16 v[20:23], v[176:179], v[212:215], v[20:23]
	v_mfma_f32_16x16x32_bf16 v[24:27], v[186:189], v[194:197], v[24:27]
	v_mfma_f32_16x16x32_bf16 v[16:19], v[186:189], v[212:215], v[16:19]
	v_mfma_f32_16x16x32_bf16 v[12:15], v[176:179], v[220:223], v[12:15]
	v_mfma_f32_16x16x32_bf16 v[4:7], v[176:179], v[228:231], v[4:7]
	v_lshl_add_u64 v[238:239], s[64:65], 0, v[136:137]
	s_mov_b32 m0, s33
	s_nop 0
	global_load_lds_dwordx4 v[238:239], off
	v_mfma_f32_16x16x32_bf16 v[8:11], v[186:189], v[220:223], v[8:11]
	v_mfma_f32_16x16x32_bf16 v[0:3], v[186:189], v[228:231], v[0:3]
	s_setprio 0
	s_barrier
; #define PG8_STAGE(bufoff, gbase, voff) do { _Pragma("unroll") for (int _i = 0; _i < 2; ++_i) \
;         __builtin_amdgcn_global_load_lds((const unsigned*)((const char*)(gbase) + (voff)[_i]), (PG8_LAS unsigned*)(lds + (bufoff) + ldsw + _i * 8192), 16, 0, 0); } while (0)
; #define PG8_LDA(dst, b, h) do { _Pragma("unroll") for (int m = 0; m < 4; ++m) _Pragma("unroll") for (int k = 0; k < 2; ++k) dst[m][k] = *(const PG8_LAS bf16x8*)(lds + PG8_SA(b, h) + aoff + m * 2048 + k * 1024); } while (0)
; #define PG8_LDB(dst, b, h) do { _Pragma("unroll") for (int n = 0; n < 2; ++n) _Pragma("unroll") for (int k = 0; k < 2; ++k) dst[n][k] = *(const PG8_LAS bf16x8*)(lds + PG8_SB(b, h) + boff + n * 2048 + k * 1024); } while (0)
; #define PG8_MMA(ai, bj, At, Bt) do { __builtin_amdgcn_s_setprio(1); _Pragma("unroll") for (int m = 0; m < 4; ++m) _Pragma("unroll") for (int n = 0; n < 2; ++n) _Pragma("unroll") for (int k = 0; k < 2; ++k) \
;         acc[ai][bj][m][n] = __builtin_amdgcn_mfma_f32_16x16x32_bf16(Bt[n][k], At[m][k], acc[ai][bj][m][n], 0, 0, 0); __builtin_amdgcn_s_setprio(0); } while (0)
; #define PG8_WAIT_V(n) asm volatile("s_waitcnt vmcnt(" #n ")" ::: "memory")
; #define PG8_WAIT_L(n) asm volatile("s_waitcnt lgkmcnt(" #n ")" ::: "memory")
; #define PG8_BAR __builtin_amdgcn_s_barrier()
; #define PG8_SCHED __builtin_amdgcn_sched_barrier(0)
; template <class Epi, class Sched, bool ALIGN_EPI = false, bool SP2 = false>
; __device__ __forceinline__ void gemm_phase(PG8_LAS unsigned char* lds, const Gemm g, const Sched& S, const Epi& E) {
;     ...
;             PG8_LDB(B0, 1, 0); PG8_LDB(B1, 1, 1); PG8_SCHED; PG8_LDA(At, 1, 0); PG8_STAGE(PG8_SA(0, 1), a2 + hstep, voffA);
;             PG8_WAIT_V(8); PG8_WAIT_L(0); PG8_BAR; PG8_MMA(0, 0, At, B0); PG8_MMA(0, 1, At, B1); PG8_BAR; PG8_SCHED;
	s_add_i32 s78, 0, 0x18000
	v_add_u32_e32 v140, s78, v147
	s_add_i32 s79, 0, 0x1c000
	ds_read_b128 v[128:131], v140
	ds_read_b128 v[160:163], v140 offset:1024
	ds_read_b128 v[164:167], v140 offset:2048
	ds_read_b128 v[168:171], v140 offset:3072
	v_add_u32_e32 v140, s79, v147
	ds_read_b128 v[172:175], v140
	ds_read_b128 v[176:179], v140 offset:1024
	ds_read_b128 v[182:185], v140 offset:2048
	ds_read_b128 v[186:189], v140 offset:3072
	s_add_u32 s64, s64, 0x40000
	s_addc_u32 s65, s65, 0
	s_mov_b32 m0, s34
	v_lshl_add_u64 v[240:241], s[64:65], 0, v[132:133]
	ds_read_b128 v[190:193], v208 offset:32768
	ds_read_b128 v[194:197], v208 offset:33792
	ds_read_b128 v[198:201], v208 offset:34816
	ds_read_b128 v[212:215], v208 offset:35840
	ds_read_b128 v[216:219], v208 offset:36864
	ds_read_b128 v[220:223], v208 offset:37888
	ds_read_b128 v[224:227], v208 offset:38912
	ds_read_b128 v[228:231], v208 offset:39936
	global_load_lds_dwordx4 v[240:241], off
	v_lshl_add_u64 v[240:241], s[64:65], 0, v[136:137]
	s_mov_b32 m0, s57
	s_nop 0
	global_load_lds_dwordx4 v[240:241], off
	s_waitcnt vmcnt(8)
	s_waitcnt lgkmcnt(0)
	s_barrier
	s_setprio 1
	s_waitcnt lgkmcnt(0)
	v_mfma_f32_16x16x32_bf16 v[124:127], v[128:131], v[190:193], v[124:127]
	v_mfma_f32_16x16x32_bf16 v[116:119], v[128:131], v[198:201], v[116:119]
	v_mfma_f32_16x16x32_bf16 v[120:123], v[164:167], v[190:193], v[120:123]
	v_mfma_f32_16x16x32_bf16 v[112:115], v[164:167], v[198:201], v[112:115]
	v_mfma_f32_16x16x32_bf16 v[108:111], v[128:131], v[216:219], v[108:111]
	v_mfma_f32_16x16x32_bf16 v[100:103], v[128:131], v[224:227], v[100:103]
	v_mfma_f32_16x16x32_bf16 v[104:107], v[164:167], v[216:219], v[104:107]
	v_mfma_f32_16x16x32_bf16 v[96:99], v[164:167], v[224:227], v[96:99]
	v_mfma_f32_16x16x32_bf16 v[124:127], v[160:163], v[194:197], v[124:127]
	v_mfma_f32_16x16x32_bf16 v[116:119], v[160:163], v[212:215], v[116:119]
	v_mfma_f32_16x16x32_bf16 v[120:123], v[168:171], v[194:197], v[120:123]
	v_mfma_f32_16x16x32_bf16 v[112:115], v[168:171], v[212:215], v[112:115]
	v_mfma_f32_16x16x32_bf16 v[108:111], v[160:163], v[220:223], v[108:111]
	v_mfma_f32_16x16x32_bf16 v[100:103], v[160:163], v[228:231], v[100:103]
	v_mfma_f32_16x16x32_bf16 v[104:107], v[168:171], v[220:223], v[104:107]
	v_mfma_f32_16x16x32_bf16 v[96:99], v[168:171], v[228:231], v[96:99]
	s_setprio 0
	s_setprio 1
	v_mfma_f32_16x16x32_bf16 v[60:63], v[172:175], v[190:193], v[60:63]
	v_mfma_f32_16x16x32_bf16 v[52:55], v[172:175], v[198:201], v[52:55]
	v_mfma_f32_16x16x32_bf16 v[56:59], v[182:185], v[190:193], v[56:59]
	v_mfma_f32_16x16x32_bf16 v[48:51], v[182:185], v[198:201], v[48:51]
	v_mfma_f32_16x16x32_bf16 v[44:47], v[172:175], v[216:219], v[44:47]
	v_mfma_f32_16x16x32_bf16 v[36:39], v[172:175], v[224:227], v[36:39]
	v_mfma_f32_16x16x32_bf16 v[40:43], v[182:185], v[216:219], v[40:43]
	v_mfma_f32_16x16x32_bf16 v[32:35], v[182:185], v[224:227], v[32:35]
	v_mfma_f32_16x16x32_bf16 v[60:63], v[176:179], v[194:197], v[60:63]
	v_mfma_f32_16x16x32_bf16 v[52:55], v[176:179], v[212:215], v[52:55]
	v_mfma_f32_16x16x32_bf16 v[56:59], v[186:189], v[194:197], v[56:59]
	v_mfma_f32_16x16x32_bf16 v[48:51], v[186:189], v[212:215], v[48:51]
	v_mfma_f32_16x16x32_bf16 v[44:47], v[176:179], v[220:223], v[44:47]
	v_mfma_f32_16x16x32_bf16 v[36:39], v[176:179], v[228:231], v[36:39]
	v_mfma_f32_16x16x32_bf16 v[40:43], v[186:189], v[220:223], v[40:43]
	v_mfma_f32_16x16x32_bf16 v[32:35], v[186:189], v[228:231], v[32:35]
	s_setprio 0
	s_barrier
; #define PG8_STAGE(bufoff, gbase, voff) do { _Pragma("unroll") for (int _i = 0; _i < 2; ++_i) \
;         __builtin_amdgcn_global_load_lds((const unsigned*)((const char*)(gbase) + (voff)[_i]), (PG8_LAS unsigned*)(lds + (bufoff) + ldsw + _i * 8192), 16, 0, 0); } while (0)
; #define PG8_LDA(dst, b, h) do { _Pragma("unroll") for (int m = 0; m < 4; ++m) _Pragma("unroll") for (int k = 0; k < 2; ++k) dst[m][k] = *(const PG8_LAS bf16x8*)(lds + PG8_SA(b, h) + aoff + m * 2048 + k * 1024); } while (0)
; #define PG8_MMA(ai, bj, At, Bt) do { __builtin_amdgcn_s_setprio(1); _Pragma("unroll") for (int m = 0; m < 4; ++m) _Pragma("unroll") for (int n = 0; n < 2; ++n) _Pragma("unroll") for (int k = 0; k < 2; ++k) \
;         acc[ai][bj][m][n] = __builtin_amdgcn_mfma_f32_16x16x32_bf16(Bt[n][k], At[m][k], acc[ai][bj][m][n], 0, 0, 0); __builtin_amdgcn_s_setprio(0); } while (0)
; #define PG8_WAIT_V(n) asm volatile("s_waitcnt vmcnt(" #n ")" ::: "memory")
; #define PG8_WAIT_L(n) asm volatile("s_waitcnt lgkmcnt(" #n ")" ::: "memory")
; #define PG8_BAR __builtin_amdgcn_s_barrier()
; #define PG8_SCHED __builtin_amdgcn_sched_barrier(0)
; template <class Epi, class Sched, bool ALIGN_EPI = false, bool SP2 = false>
; __device__ __forceinline__ void gemm_phase(PG8_LAS unsigned char* lds, const Gemm g, const Sched& S, const Epi& E) {
;     ...
;             PG8_LDA(At, 1, 1); PG8_STAGE(PG8_SB(1, 0), b3, voffB); PG8_STAGE(PG8_SB(1, 1), b3 + hstep, voffB); PG8_STAGE(PG8_SA(1, 0), a3, voffA);
;             PG8_WAIT_V(8); PG8_WAIT_L(0); PG8_BAR; PG8_MMA(1, 0, At, B0); PG8_MMA(1, 1, At, B1); PG8_BAR; PG8_SCHED;
	s_add_i32 s64, s78, s14
	v_lshl_add_u64 v[232:233], v[232:233], 0, s[42:43]
	s_mov_b32 m0, s64
	ds_read_b128 v[190:193], v208 offset:49152
	ds_read_b128 v[194:197], v208 offset:50176
	ds_read_b128 v[198:201], v208 offset:51200
	ds_read_b128 v[212:215], v208 offset:52224
	ds_read_b128 v[216:219], v208 offset:53248
	ds_read_b128 v[220:223], v208 offset:54272
	ds_read_b128 v[224:227], v208 offset:55296
	ds_read_b128 v[228:231], v208 offset:56320
	global_load_lds_dwordx4 v[232:233], off
	s_add_i32 m0, s64, 0x2000
	s_add_u32 s62, s62, 0x40080
	v_lshl_add_u64 v[232:233], v[234:235], 0, s[42:43]
	s_addc_u32 s63, s63, 0
	s_add_i32 s64, s79, s14
	global_load_lds_dwordx4 v[232:233], off
	v_lshl_add_u64 v[232:233], s[62:63], 0, v[134:135]
	s_mov_b32 m0, s64
	s_nop 0
	global_load_lds_dwordx4 v[232:233], off
	v_lshl_add_u64 v[232:233], s[62:63], 0, v[138:139]
	s_add_i32 m0, s64, 0x2000
	s_nop 0
	global_load_lds_dwordx4 v[232:233], off
	s_waitcnt vmcnt(6)
	s_waitcnt lgkmcnt(0)
	s_barrier
	s_setprio 1
	s_waitcnt lgkmcnt(0)
	v_mfma_f32_16x16x32_bf16 v[92:95], v[128:131], v[190:193], v[92:95]
	v_mfma_f32_16x16x32_bf16 v[84:87], v[128:131], v[198:201], v[84:87]
	v_mfma_f32_16x16x32_bf16 v[88:91], v[164:167], v[190:193], v[88:91]
	v_mfma_f32_16x16x32_bf16 v[80:83], v[164:167], v[198:201], v[80:83]
	v_mfma_f32_16x16x32_bf16 v[76:79], v[128:131], v[216:219], v[76:79]
	v_mfma_f32_16x16x32_bf16 v[68:71], v[128:131], v[224:227], v[68:71]
	v_mfma_f32_16x16x32_bf16 v[72:75], v[164:167], v[216:219], v[72:75]
	v_mfma_f32_16x16x32_bf16 v[64:67], v[164:167], v[224:227], v[64:67]
	v_mfma_f32_16x16x32_bf16 v[92:95], v[160:163], v[194:197], v[92:95]
	v_mfma_f32_16x16x32_bf16 v[84:87], v[160:163], v[212:215], v[84:87]
	v_mfma_f32_16x16x32_bf16 v[88:91], v[168:171], v[194:197], v[88:91]
	v_mfma_f32_16x16x32_bf16 v[80:83], v[168:171], v[212:215], v[80:83]
	v_mfma_f32_16x16x32_bf16 v[76:79], v[160:163], v[220:223], v[76:79]
	v_mfma_f32_16x16x32_bf16 v[68:71], v[160:163], v[228:231], v[68:71]
	v_lshl_add_u64 v[232:233], v[236:237], 0, s[42:43]
	s_mov_b32 m0, s67
	s_nop 0
	global_load_lds_dwordx4 v[232:233], off
	v_mfma_f32_16x16x32_bf16 v[72:75], v[168:171], v[220:223], v[72:75]
	v_mfma_f32_16x16x32_bf16 v[64:67], v[168:171], v[228:231], v[64:67]
	s_setprio 0
	s_setprio 1
	v_mfma_f32_16x16x32_bf16 v[28:31], v[172:175], v[190:193], v[28:31]
	v_mfma_f32_16x16x32_bf16 v[20:23], v[172:175], v[198:201], v[20:23]
	v_mfma_f32_16x16x32_bf16 v[24:27], v[182:185], v[190:193], v[24:27]
	v_mfma_f32_16x16x32_bf16 v[16:19], v[182:185], v[198:201], v[16:19]
	v_mfma_f32_16x16x32_bf16 v[12:15], v[172:175], v[216:219], v[12:15]
	v_mfma_f32_16x16x32_bf16 v[4:7], v[172:175], v[224:227], v[4:7]
	v_mfma_f32_16x16x32_bf16 v[8:11], v[182:185], v[216:219], v[8:11]
	v_mfma_f32_16x16x32_bf16 v[0:3], v[182:185], v[224:227], v[0:3]
	v_mfma_f32_16x16x32_bf16 v[28:31], v[176:179], v[194:197], v[28:31]
	v_mfma_f32_16x16x32_bf16 v[20:23], v[176:179], v[212:215], v[20:23]
	v_mfma_f32_16x16x32_bf16 v[24:27], v[186:189], v[194:197], v[24:27]
	v_mfma_f32_16x16x32_bf16 v[16:19], v[186:189], v[212:215], v[16:19]
	v_mfma_f32_16x16x32_bf16 v[12:15], v[176:179], v[220:223], v[12:15]
	v_mfma_f32_16x16x32_bf16 v[4:7], v[176:179], v[228:231], v[4:7]
	v_lshl_add_u64 v[232:233], v[238:239], 0, s[42:43]
	s_mov_b32 m0, s74
	s_nop 0
	global_load_lds_dwordx4 v[232:233], off
	v_mfma_f32_16x16x32_bf16 v[8:11], v[186:189], v[220:223], v[8:11]
	v_mfma_f32_16x16x32_bf16 v[0:3], v[186:189], v[228:231], v[0:3]
	s_setprio 0
	s_barrier
	s_add_i32 s90, s90, 2
	s_add_u32 s58, s58, 0x100
	s_addc_u32 s59, s59, 0
	s_add_u32 s88, s88, 0x100
	s_addc_u32 s89, s89, 0
	s_cmp_gt_u32 s90, 13
	s_cbranch_scc0 .LBB0_1287
	s_and_b64 vcc, exec, s[44:45]
	s_cbranch_vccz .LBB0_1290
	s_barrier

; #define PG8_STAGE(bufoff, gbase, voff) do { _Pragma("unroll") for (int _i = 0; _i < 2; ++_i) \
;         __builtin_amdgcn_global_load_lds((const unsigned*)((const char*)(gbase) + (voff)[_i]), (PG8_LAS unsigned*)(lds + (bufoff) + ldsw + _i * 8192), 16, 0, 0); } while (0)
; #define PG8_LDA(dst, b, h) do { _Pragma("unroll") for (int m = 0; m < 4; ++m) _Pragma("unroll") for (int k = 0; k < 2; ++k) dst[m][k] = *(const PG8_LAS bf16x8*)(lds + PG8_SA(b, h) + aoff + m * 2048 + k * 1024); } while (0)
; #define PG8_LDB(dst, b, h) do { _Pragma("unroll") for (int n = 0; n < 2; ++n) _Pragma("unroll") for (int k = 0; k < 2; ++k) dst[n][k] = *(const PG8_LAS bf16x8*)(lds + PG8_SB(b, h) + boff + n * 2048 + k * 1024); } while (0)
; #define PG8_WAIT_V(n) asm volatile("s_waitcnt vmcnt(" #n ")" ::: "memory")
; #define PG8_WAIT_L(n) asm volatile("s_waitcnt lgkmcnt(" #n ")" ::: "memory")
; #define PG8_BAR __builtin_amdgcn_s_barrier()
; #define PG8_SCHED __builtin_amdgcn_sched_barrier(0)
; template <class Epi, class Sched, bool ALIGN_EPI = false, bool SP2 = false>
; __device__ __forceinline__ void gemm_phase(PG8_LAS unsigned char* lds, const Gemm g, const Sched& S, const Epi& E) {
;     ...
;         const bool has_next = S.next(ui + 1, nxt);
;         const char* nA = has_next ? (const char*)g.A + (size_t)nxt.pm * tstep : cA; const char* nB = has_next ? (const char*)g.Bt + (size_t)nxt.pn * tstep : cB;
;         for (int t = 0; t < nt; t += 2) {
;             const bool last = (t == nt - 2);
;             const char* a1 = cA + (size_t)(t + 1) * kstep;
;             const char* a2 = last ? nA : cA + (size_t)(t + 2) * kstep; const char* b2 = last ? nB : cB + (size_t)(t + 2) * kstep;
;             const char* a3 = a2 + kstep; const char* b3 = b2 + kstep;
;             if (last && has_next) S.a_ready(nxt);
;             if constexpr (SP2) {
;             PG8_LDB(B0, 0, 0); PG8_LDB(B1, 0, 1); PG8_SCHED; PG8_LDA(At, 0, 0); PG8_STAGE(PG8_SA(1, 1), a1 + hstep, voffA);
;             PG8_WAIT_V(8); PG8_WAIT_L(0); PG8_BAR; PG8_MMA(0, 0, At, B0); PG8_MMA(0, 1, At, B1); PG8_BAR; PG8_SCHED;
;             PG8_LDA(At, 0, 1); PG8_STAGE(PG8_SB(0, 0), b2, voffB); PG8_STAGE(PG8_SB(0, 1), b2 + hstep, voffB); PG8_STAGE(PG8_SA(0, 0), a2, voffA);
;             PG8_WAIT_V(8); PG8_WAIT_L(0); PG8_BAR; PG8_MMA(1, 0, At, B0); PG8_MMA(1, 1, At, B1); PG8_BAR; PG8_SCHED;
.LBB0_1592:
	s_ashr_i32 s39, s38, 31
	s_lshl_b64 s[42:43], s[38:39], 19
	s_add_u32 s42, s40, s42
	s_addc_u32 s43, s41, s43
	s_and_b64 s[44:45], s[10:11], exec
	s_cselect_b32 s39, s43, s51
	s_cselect_b32 s47, s42, s50
	s_ashr_i32 s37, s36, 31
	s_lshl_b64 s[44:45], s[36:37], 19
	v_readlane_b32 s54, v250, 11
	v_readlane_b32 s55, v250, 12
	s_add_u32 s44, s54, s44
	s_addc_u32 s45, s55, s45
	s_and_b64 s[54:55], s[10:11], exec
	s_cselect_b32 s37, s45, s53
	s_cselect_b32 s64, s44, s52
	s_add_u32 s50, s50, 0x40080
	s_addc_u32 s51, s51, 0
	s_add_u32 s65, s52, 0x100
	s_addc_u32 s66, s53, 0
	s_mov_b32 s67, -2
	s_waitcnt lgkmcnt(0)
	ds_read_b128 v[146:149], v152
	ds_read_b128 v[156:159], v152 offset:1024
	ds_read_b128 v[160:163], v152 offset:2048
	ds_read_b128 v[164:167], v152 offset:3072
	ds_read_b128 v[168:171], v153
	ds_read_b128 v[172:175], v153 offset:1024
	ds_read_b128 v[180:183], v153 offset:2048
	ds_read_b128 v[184:187], v153 offset:3072
	s_add_u32 s52, s50, 0xfffc0080
	s_addc_u32 s53, s51, -1
	s_cmp_eq_u32 s67, 12
	s_cselect_b32 s55, s39, s53
	s_cselect_b32 s54, s47, s52
	s_cselect_b32 s53, s37, s66
	s_cselect_b32 s52, s64, s65
	v_lshl_add_u64 v[200:201], s[50:51], 0, v[136:137]
	s_add_i32 m0, s33, 0xc000
	ds_read_b128 v[188:191], v154
	ds_read_b128 v[192:195], v154 offset:1024
	ds_read_b128 v[196:199], v154 offset:2048
	ds_read_b128 v[206:209], v154 offset:3072
	ds_read_b128 v[210:213], v154 offset:4096
	ds_read_b128 v[214:217], v154 offset:5120
	ds_read_b128 v[218:221], v154 offset:6144
	ds_read_b128 v[222:225], v154 offset:7168
	global_load_lds_dwordx4 v[200:201], off
	v_lshl_add_u64 v[200:201], s[50:51], 0, v[138:139]
	s_add_i32 m0, s33, 0xe000
	s_nop 0
	global_load_lds_dwordx4 v[200:201], off
	s_waitcnt vmcnt(8)
	s_waitcnt lgkmcnt(0)
	s_barrier
	s_setprio 1
	s_waitcnt lgkmcnt(0)
	v_mfma_f32_16x16x32_bf16 v[124:127], v[146:149], v[188:191], 0
	v_mfma_f32_16x16x32_bf16 v[108:111], v[146:149], v[196:199], 0
	v_mfma_f32_16x16x32_bf16 v[120:123], v[160:163], v[188:191], 0
	v_mfma_f32_16x16x32_bf16 v[104:107], v[160:163], v[196:199], 0
	v_mfma_f32_16x16x32_bf16 v[92:95], v[146:149], v[210:213], 0
	v_mfma_f32_16x16x32_bf16 v[76:79], v[146:149], v[218:221], 0
	v_mfma_f32_16x16x32_bf16 v[88:91], v[160:163], v[210:213], 0
	v_mfma_f32_16x16x32_bf16 v[72:75], v[160:163], v[218:221], 0
	v_mfma_f32_16x16x32_bf16 v[124:127], v[156:159], v[192:195], v[124:127]
	v_mfma_f32_16x16x32_bf16 v[108:111], v[156:159], v[206:209], v[108:111]
	v_mfma_f32_16x16x32_bf16 v[120:123], v[164:167], v[192:195], v[120:123]
	v_mfma_f32_16x16x32_bf16 v[104:107], v[164:167], v[206:209], v[104:107]
	v_mfma_f32_16x16x32_bf16 v[92:95], v[156:159], v[214:217], v[92:95]
	v_mfma_f32_16x16x32_bf16 v[76:79], v[156:159], v[222:225], v[76:79]
	v_mfma_f32_16x16x32_bf16 v[88:91], v[164:167], v[214:217], v[88:91]
	v_mfma_f32_16x16x32_bf16 v[72:75], v[164:167], v[222:225], v[72:75]
	s_setprio 0
	s_setprio 1
	v_mfma_f32_16x16x32_bf16 v[116:119], v[168:171], v[188:191], 0
	v_mfma_f32_16x16x32_bf16 v[100:103], v[168:171], v[196:199], 0
	v_mfma_f32_16x16x32_bf16 v[112:115], v[180:183], v[188:191], 0
	v_mfma_f32_16x16x32_bf16 v[96:99], v[180:183], v[196:199], 0
	v_mfma_f32_16x16x32_bf16 v[84:87], v[168:171], v[210:213], 0
	v_mfma_f32_16x16x32_bf16 v[68:71], v[168:171], v[218:221], 0
	v_mfma_f32_16x16x32_bf16 v[80:83], v[180:183], v[210:213], 0
	v_mfma_f32_16x16x32_bf16 v[64:67], v[180:183], v[218:221], 0
	v_mfma_f32_16x16x32_bf16 v[116:119], v[172:175], v[192:195], v[116:119]
	v_mfma_f32_16x16x32_bf16 v[100:103], v[172:175], v[206:209], v[100:103]
	v_mfma_f32_16x16x32_bf16 v[112:115], v[184:187], v[192:195], v[112:115]
	v_mfma_f32_16x16x32_bf16 v[96:99], v[184:187], v[206:209], v[96:99]
	v_mfma_f32_16x16x32_bf16 v[84:87], v[172:175], v[214:217], v[84:87]
	v_mfma_f32_16x16x32_bf16 v[68:71], v[172:175], v[222:225], v[68:71]
	v_mfma_f32_16x16x32_bf16 v[80:83], v[184:187], v[214:217], v[80:83]
	v_mfma_f32_16x16x32_bf16 v[64:67], v[184:187], v[222:225], v[64:67]
	s_setprio 0
	s_barrier
	s_add_i32 s74, s60, s15
	v_lshl_add_u64 v[200:201], s[52:53], 0, v[130:131]
	s_mov_b32 m0, s74
	ds_read_b128 v[188:191], v154 offset:16384
	ds_read_b128 v[192:195], v154 offset:17408
	ds_read_b128 v[196:199], v154 offset:18432
	ds_read_b128 v[206:209], v154 offset:19456
	ds_read_b128 v[210:213], v154 offset:20480
	ds_read_b128 v[214:217], v154 offset:21504
	ds_read_b128 v[218:221], v154 offset:22528
	ds_read_b128 v[222:225], v154 offset:23552
	global_load_lds_dwordx4 v[200:201], off
	s_add_i32 m0, s74, 0x2000
	s_add_u32 s74, s52, 0x40000
	v_lshl_add_u64 v[226:227], s[52:53], 0, v[134:135]
	s_addc_u32 s75, s53, 0
	s_add_i32 s76, s61, s15
	global_load_lds_dwordx4 v[226:227], off
	v_lshl_add_u64 v[228:229], s[74:75], 0, v[130:131]
	s_mov_b32 m0, s76
	global_load_lds_dwordx4 v[228:229], off
	v_lshl_add_u64 v[228:229], s[74:75], 0, v[134:135]
	s_add_i32 m0, s76, 0x2000
	s_nop 0
	global_load_lds_dwordx4 v[228:229], off
	s_waitcnt vmcnt(6)
	s_waitcnt lgkmcnt(0)
	s_barrier
; #define PG8_STAGE(bufoff, gbase, voff) do { _Pragma("unroll") for (int _i = 0; _i < 2; ++_i) \
;         __builtin_amdgcn_global_load_lds((const unsigned*)((const char*)(gbase) + (voff)[_i]), (PG8_LAS unsigned*)(lds + (bufoff) + ldsw + _i * 8192), 16, 0, 0); } while (0)
; #define PG8_LDA(dst, b, h) do { _Pragma("unroll") for (int m = 0; m < 4; ++m) _Pragma("unroll") for (int k = 0; k < 2; ++k) dst[m][k] = *(const PG8_LAS bf16x8*)(lds + PG8_SA(b, h) + aoff + m * 2048 + k * 1024); } while (0)
; #define PG8_LDB(dst, b, h) do { _Pragma("unroll") for (int n = 0; n < 2; ++n) _Pragma("unroll") for (int k = 0; k < 2; ++k) dst[n][k] = *(const PG8_LAS bf16x8*)(lds + PG8_SB(b, h) + boff + n * 2048 + k * 1024); } while (0)
; #define PG8_MMA(ai, bj, At, Bt) do { __builtin_amdgcn_s_setprio(1); _Pragma("unroll") for (int m = 0; m < 4; ++m) _Pragma("unroll") for (int n = 0; n < 2; ++n) _Pragma("unroll") for (int k = 0; k < 2; ++k) \
;         acc[ai][bj][m][n] = __builtin_amdgcn_mfma_f32_16x16x32_bf16(Bt[n][k], At[m][k], acc[ai][bj][m][n], 0, 0, 0); __builtin_amdgcn_s_setprio(0); } while (0)
; #define PG8_WAIT_V(n) asm volatile("s_waitcnt vmcnt(" #n ")" ::: "memory")
; #define PG8_WAIT_L(n) asm volatile("s_waitcnt lgkmcnt(" #n ")" ::: "memory")
; #define PG8_BAR __builtin_amdgcn_s_barrier()
; #define PG8_SCHED __builtin_amdgcn_sched_barrier(0)
; template <class Epi, class Sched, bool ALIGN_EPI = false, bool SP2 = false>
; __device__ __forceinline__ void gemm_phase(PG8_LAS unsigned char* lds, const Gemm g, const Sched& S, const Epi& E) {
;     ...
;             PG8_WAIT_V(8); PG8_WAIT_L(0); PG8_BAR; PG8_MMA(1, 0, At, B0); PG8_MMA(1, 1, At, B1); PG8_BAR; PG8_SCHED;
;             PG8_LDB(B0, 1, 0); PG8_LDB(B1, 1, 1); PG8_SCHED; PG8_LDA(At, 1, 0); PG8_STAGE(PG8_SA(0, 1), a2 + hstep, voffA);
;             PG8_WAIT_V(8); PG8_WAIT_L(0); PG8_BAR; PG8_MMA(0, 0, At, B0); PG8_MMA(0, 1, At, B1); PG8_BAR; PG8_SCHED;
	s_setprio 1
	s_waitcnt lgkmcnt(0)
	v_mfma_f32_16x16x32_bf16 v[60:63], v[146:149], v[188:191], 0
	v_mfma_f32_16x16x32_bf16 v[44:47], v[146:149], v[196:199], 0
	v_mfma_f32_16x16x32_bf16 v[56:59], v[160:163], v[188:191], 0
	v_mfma_f32_16x16x32_bf16 v[40:43], v[160:163], v[196:199], 0
	v_mfma_f32_16x16x32_bf16 v[28:31], v[146:149], v[210:213], 0
	v_mfma_f32_16x16x32_bf16 v[12:15], v[146:149], v[218:221], 0
	v_mfma_f32_16x16x32_bf16 v[24:27], v[160:163], v[210:213], 0
	v_mfma_f32_16x16x32_bf16 v[8:11], v[160:163], v[218:221], 0
	v_mfma_f32_16x16x32_bf16 v[60:63], v[156:159], v[192:195], v[60:63]
	v_mfma_f32_16x16x32_bf16 v[44:47], v[156:159], v[206:209], v[44:47]
	v_mfma_f32_16x16x32_bf16 v[56:59], v[164:167], v[192:195], v[56:59]
	v_mfma_f32_16x16x32_bf16 v[40:43], v[164:167], v[206:209], v[40:43]
	v_mfma_f32_16x16x32_bf16 v[28:31], v[156:159], v[214:217], v[28:31]
	v_mfma_f32_16x16x32_bf16 v[12:15], v[156:159], v[222:225], v[12:15]
	v_lshl_add_u64 v[228:229], s[54:55], 0, v[128:129]
	s_mov_b32 m0, s33
	s_nop 0
	global_load_lds_dwordx4 v[228:229], off
	v_mfma_f32_16x16x32_bf16 v[24:27], v[164:167], v[214:217], v[24:27]
	v_mfma_f32_16x16x32_bf16 v[8:11], v[164:167], v[222:225], v[8:11]
	s_setprio 0
	s_setprio 1
	v_mfma_f32_16x16x32_bf16 v[52:55], v[168:171], v[188:191], 0
	v_mfma_f32_16x16x32_bf16 v[36:39], v[168:171], v[196:199], 0
	v_mfma_f32_16x16x32_bf16 v[48:51], v[180:183], v[188:191], 0
	v_mfma_f32_16x16x32_bf16 v[32:35], v[180:183], v[196:199], 0
	v_mfma_f32_16x16x32_bf16 v[20:23], v[168:171], v[210:213], 0
	v_mfma_f32_16x16x32_bf16 v[4:7], v[168:171], v[218:221], 0
	v_mfma_f32_16x16x32_bf16 v[16:19], v[180:183], v[210:213], 0
	v_mfma_f32_16x16x32_bf16 v[0:3], v[180:183], v[218:221], 0
	v_mfma_f32_16x16x32_bf16 v[52:55], v[172:175], v[192:195], v[52:55]
	v_mfma_f32_16x16x32_bf16 v[36:39], v[172:175], v[206:209], v[36:39]
	v_mfma_f32_16x16x32_bf16 v[48:51], v[184:187], v[192:195], v[48:51]
	v_mfma_f32_16x16x32_bf16 v[32:35], v[184:187], v[206:209], v[32:35]
	v_mfma_f32_16x16x32_bf16 v[20:23], v[172:175], v[214:217], v[20:23]
	v_mfma_f32_16x16x32_bf16 v[4:7], v[172:175], v[222:225], v[4:7]
	v_lshl_add_u64 v[230:231], s[54:55], 0, v[132:133]
	s_mov_b32 m0, s34
	s_nop 0
	global_load_lds_dwordx4 v[230:231], off
	v_mfma_f32_16x16x32_bf16 v[16:19], v[184:187], v[214:217], v[16:19]
	v_mfma_f32_16x16x32_bf16 v[0:3], v[184:187], v[222:225], v[0:3]
	s_setprio 0
	s_barrier
	s_add_i32 s74, 0, 0x18000
	s_add_i32 s75, 0, 0x1c000
	v_add_u32_e32 v164, s74, v150
	v_add_u32_e32 v179, s75, v150
	ds_read_b128 v[146:149], v164
	ds_read_b128 v[156:159], v164 offset:1024
	ds_read_b128 v[160:163], v164 offset:2048
	ds_read_b128 v[164:167], v164 offset:3072
	ds_read_b128 v[168:171], v179
	ds_read_b128 v[172:175], v179 offset:1024
	ds_read_b128 v[180:183], v179 offset:2048
	ds_read_b128 v[184:187], v179 offset:3072
	s_add_u32 s54, s54, 0x40000
	s_addc_u32 s55, s55, 0
	s_mov_b32 m0, s49
	v_lshl_add_u64 v[232:233], s[54:55], 0, v[128:129]
	ds_read_b128 v[188:191], v154 offset:32768
	ds_read_b128 v[192:195], v154 offset:33792
	ds_read_b128 v[196:199], v154 offset:34816
	ds_read_b128 v[206:209], v154 offset:35840
	ds_read_b128 v[210:213], v154 offset:36864
	ds_read_b128 v[214:217], v154 offset:37888
	ds_read_b128 v[218:221], v154 offset:38912
	ds_read_b128 v[222:225], v154 offset:39936
	global_load_lds_dwordx4 v[232:233], off
	v_lshl_add_u64 v[232:233], s[54:55], 0, v[132:133]
	s_mov_b32 m0, s56
	s_nop 0
	global_load_lds_dwordx4 v[232:233], off
	s_waitcnt vmcnt(8)
	s_waitcnt lgkmcnt(0)
	s_barrier
	s_setprio 1
	s_waitcnt lgkmcnt(0)
	v_mfma_f32_16x16x32_bf16 v[124:127], v[146:149], v[188:191], v[124:127]
	v_mfma_f32_16x16x32_bf16 v[108:111], v[146:149], v[196:199], v[108:111]
	v_mfma_f32_16x16x32_bf16 v[120:123], v[160:163], v[188:191], v[120:123]
	v_mfma_f32_16x16x32_bf16 v[104:107], v[160:163], v[196:199], v[104:107]
	v_mfma_f32_16x16x32_bf16 v[92:95], v[146:149], v[210:213], v[92:95]
	v_mfma_f32_16x16x32_bf16 v[76:79], v[146:149], v[218:221], v[76:79]
	v_mfma_f32_16x16x32_bf16 v[88:91], v[160:163], v[210:213], v[88:91]
	v_mfma_f32_16x16x32_bf16 v[72:75], v[160:163], v[218:221], v[72:75]
	v_mfma_f32_16x16x32_bf16 v[124:127], v[156:159], v[192:195], v[124:127]
	v_mfma_f32_16x16x32_bf16 v[108:111], v[156:159], v[206:209], v[108:111]
	v_mfma_f32_16x16x32_bf16 v[120:123], v[164:167], v[192:195], v[120:123]
	v_mfma_f32_16x16x32_bf16 v[104:107], v[164:167], v[206:209], v[104:107]
	v_mfma_f32_16x16x32_bf16 v[92:95], v[156:159], v[214:217], v[92:95]
	v_mfma_f32_16x16x32_bf16 v[76:79], v[156:159], v[222:225], v[76:79]
	v_mfma_f32_16x16x32_bf16 v[88:91], v[164:167], v[214:217], v[88:91]
	v_mfma_f32_16x16x32_bf16 v[72:75], v[164:167], v[222:225], v[72:75]
	s_setprio 0
	s_setprio 1
	v_mfma_f32_16x16x32_bf16 v[116:119], v[168:171], v[188:191], v[116:119]
	v_mfma_f32_16x16x32_bf16 v[100:103], v[168:171], v[196:199], v[100:103]
	v_mfma_f32_16x16x32_bf16 v[112:115], v[180:183], v[188:191], v[112:115]
	v_mfma_f32_16x16x32_bf16 v[96:99], v[180:183], v[196:199], v[96:99]
	v_mfma_f32_16x16x32_bf16 v[84:87], v[168:171], v[210:213], v[84:87]
	v_mfma_f32_16x16x32_bf16 v[68:71], v[168:171], v[218:221], v[68:71]
	v_mfma_f32_16x16x32_bf16 v[80:83], v[180:183], v[210:213], v[80:83]
	v_mfma_f32_16x16x32_bf16 v[64:67], v[180:183], v[218:221], v[64:67]
	v_mfma_f32_16x16x32_bf16 v[116:119], v[172:175], v[192:195], v[116:119]
	v_mfma_f32_16x16x32_bf16 v[100:103], v[172:175], v[206:209], v[100:103]
	v_mfma_f32_16x16x32_bf16 v[112:115], v[184:187], v[192:195], v[112:115]
	v_mfma_f32_16x16x32_bf16 v[96:99], v[184:187], v[206:209], v[96:99]
	v_mfma_f32_16x16x32_bf16 v[84:87], v[172:175], v[214:217], v[84:87]
	v_mfma_f32_16x16x32_bf16 v[68:71], v[172:175], v[222:225], v[68:71]
	v_mfma_f32_16x16x32_bf16 v[80:83], v[184:187], v[214:217], v[80:83]
	v_mfma_f32_16x16x32_bf16 v[64:67], v[184:187], v[222:225], v[64:67]
	s_setprio 0
	s_barrier
; #define PG8_STAGE(bufoff, gbase, voff) do { _Pragma("unroll") for (int _i = 0; _i < 2; ++_i) \
;         __builtin_amdgcn_global_load_lds((const unsigned*)((const char*)(gbase) + (voff)[_i]), (PG8_LAS unsigned*)(lds + (bufoff) + ldsw + _i * 8192), 16, 0, 0); } while (0)
; #define PG8_LDA(dst, b, h) do { _Pragma("unroll") for (int m = 0; m < 4; ++m) _Pragma("unroll") for (int k = 0; k < 2; ++k) dst[m][k] = *(const PG8_LAS bf16x8*)(lds + PG8_SA(b, h) + aoff + m * 2048 + k * 1024); } while (0)
; #define PG8_LDB(dst, b, h) do { _Pragma("unroll") for (int n = 0; n < 2; ++n) _Pragma("unroll") for (int k = 0; k < 2; ++k) dst[n][k] = *(const PG8_LAS bf16x8*)(lds + PG8_SB(b, h) + boff + n * 2048 + k * 1024); } while (0)
; template <class Epi, class Sched, bool ALIGN_EPI = false, bool SP2 = false>
; __device__ __forceinline__ void gemm_phase(PG8_LAS unsigned char* lds, const Gemm g, const Sched& S, const Epi& E) {
;     ...
;         for (int t = 0; t < nt; t += 2) {
;             const bool last = (t == nt - 2);
;             const char* a1 = cA + (size_t)(t + 1) * kstep;
;             const char* a2 = last ? nA : cA + (size_t)(t + 2) * kstep; const char* b2 = last ? nB : cB + (size_t)(t + 2) * kstep;
;             const char* a3 = a2 + kstep; const char* b3 = b2 + kstep;
;             if (last && has_next) S.a_ready(nxt);
;             if constexpr (SP2) {
;             PG8_LDB(B0, 0, 0); PG8_LDB(B1, 0, 1); PG8_SCHED; PG8_LDA(At, 0, 0); PG8_STAGE(PG8_SA(1, 1), a1 + hstep, voffA);
;             PG8_WAIT_V(8); PG8_WAIT_L(0); PG8_BAR; PG8_MMA(0, 0, At, B0); PG8_MMA(0, 1, At, B1); PG8_BAR; PG8_SCHED;
;             PG8_LDA(At, 0, 1); PG8_STAGE(PG8_SB(0, 0), b2, voffB); PG8_STAGE(PG8_SB(0, 1), b2 + hstep, voffB); PG8_STAGE(PG8_SA(0, 0), a2, voffA);
;             PG8_WAIT_V(8); PG8_WAIT_L(0); PG8_BAR; PG8_MMA(1, 0, At, B0); PG8_MMA(1, 1, At, B1); PG8_BAR; PG8_SCHED;
;             PG8_LDB(B0, 1, 0); PG8_LDB(B1, 1, 1); PG8_SCHED; PG8_LDA(At, 1, 0); PG8_STAGE(PG8_SA(0, 1), a2 + hstep, voffA);
;             PG8_WAIT_V(8); PG8_WAIT_L(0); PG8_BAR; PG8_MMA(0, 0, At, B0); PG8_MMA(0, 1, At, B1); PG8_BAR; PG8_SCHED;
;             PG8_LDA(At, 1, 1); PG8_STAGE(PG8_SB(1, 0), b3, voffB); PG8_STAGE(PG8_SB(1, 1), b3 + hstep, voffB); PG8_STAGE(PG8_SA(1, 0), a3, voffA);
;             PG8_WAIT_V(8); PG8_WAIT_L(0); PG8_BAR; PG8_MMA(1, 0, At, B0); PG8_MMA(1, 1, At, B1); PG8_BAR; PG8_SCHED;
	s_add_i32 s54, s74, s15
	v_lshl_add_u64 v[200:201], v[200:201], 0, s[26:27]
	s_mov_b32 m0, s54
	ds_read_b128 v[188:191], v154 offset:49152
	ds_read_b128 v[192:195], v154 offset:50176
	ds_read_b128 v[196:199], v154 offset:51200
	ds_read_b128 v[206:209], v154 offset:52224
	ds_read_b128 v[210:213], v154 offset:53248
	ds_read_b128 v[214:217], v154 offset:54272
	ds_read_b128 v[218:221], v154 offset:55296
	ds_read_b128 v[222:225], v154 offset:56320
	global_load_lds_dwordx4 v[200:201], off
	s_add_i32 m0, s54, 0x2000
	s_add_u32 s52, s52, 0x40080
	v_lshl_add_u64 v[200:201], v[226:227], 0, s[26:27]
	s_addc_u32 s53, s53, 0
	s_add_i32 s54, s75, s15
	global_load_lds_dwordx4 v[200:201], off
	v_lshl_add_u64 v[200:201], s[52:53], 0, v[130:131]
	s_mov_b32 m0, s54
	s_nop 0
	global_load_lds_dwordx4 v[200:201], off
	v_lshl_add_u64 v[200:201], s[52:53], 0, v[134:135]
	s_add_i32 m0, s54, 0x2000
	s_nop 0
	global_load_lds_dwordx4 v[200:201], off
	s_waitcnt vmcnt(6)
	s_waitcnt lgkmcnt(0)
	s_barrier
	s_setprio 1
	s_waitcnt lgkmcnt(0)
	v_mfma_f32_16x16x32_bf16 v[60:63], v[146:149], v[188:191], v[60:63]
	v_mfma_f32_16x16x32_bf16 v[44:47], v[146:149], v[196:199], v[44:47]
	v_mfma_f32_16x16x32_bf16 v[56:59], v[160:163], v[188:191], v[56:59]
	v_mfma_f32_16x16x32_bf16 v[40:43], v[160:163], v[196:199], v[40:43]
	v_mfma_f32_16x16x32_bf16 v[28:31], v[146:149], v[210:213], v[28:31]
	v_mfma_f32_16x16x32_bf16 v[12:15], v[146:149], v[218:221], v[12:15]
	v_mfma_f32_16x16x32_bf16 v[24:27], v[160:163], v[210:213], v[24:27]
	v_mfma_f32_16x16x32_bf16 v[8:11], v[160:163], v[218:221], v[8:11]
	v_mfma_f32_16x16x32_bf16 v[60:63], v[156:159], v[192:195], v[60:63]
	v_mfma_f32_16x16x32_bf16 v[44:47], v[156:159], v[206:209], v[44:47]
	v_mfma_f32_16x16x32_bf16 v[56:59], v[164:167], v[192:195], v[56:59]
	v_mfma_f32_16x16x32_bf16 v[40:43], v[164:167], v[206:209], v[40:43]
	v_mfma_f32_16x16x32_bf16 v[28:31], v[156:159], v[214:217], v[28:31]
	v_mfma_f32_16x16x32_bf16 v[12:15], v[156:159], v[222:225], v[12:15]
	v_lshl_add_u64 v[200:201], v[228:229], 0, s[26:27]
	s_mov_b32 m0, s58
	s_nop 0
	global_load_lds_dwordx4 v[200:201], off
	v_mfma_f32_16x16x32_bf16 v[24:27], v[164:167], v[214:217], v[24:27]
	v_mfma_f32_16x16x32_bf16 v[8:11], v[164:167], v[222:225], v[8:11]
	s_setprio 0
	s_setprio 1
	v_mfma_f32_16x16x32_bf16 v[52:55], v[168:171], v[188:191], v[52:55]
	v_mfma_f32_16x16x32_bf16 v[36:39], v[168:171], v[196:199], v[36:39]
	v_mfma_f32_16x16x32_bf16 v[48:51], v[180:183], v[188:191], v[48:51]
	v_mfma_f32_16x16x32_bf16 v[32:35], v[180:183], v[196:199], v[32:35]
	v_mfma_f32_16x16x32_bf16 v[20:23], v[168:171], v[210:213], v[20:23]
	v_mfma_f32_16x16x32_bf16 v[4:7], v[168:171], v[218:221], v[4:7]
	v_mfma_f32_16x16x32_bf16 v[16:19], v[180:183], v[210:213], v[16:19]
	v_mfma_f32_16x16x32_bf16 v[0:3], v[180:183], v[218:221], v[0:3]
	v_mfma_f32_16x16x32_bf16 v[52:55], v[172:175], v[192:195], v[52:55]
	v_mfma_f32_16x16x32_bf16 v[36:39], v[172:175], v[206:209], v[36:39]
	v_mfma_f32_16x16x32_bf16 v[48:51], v[184:187], v[192:195], v[48:51]
	v_mfma_f32_16x16x32_bf16 v[32:35], v[184:187], v[206:209], v[32:35]
	v_mfma_f32_16x16x32_bf16 v[20:23], v[172:175], v[214:217], v[20:23]
	v_mfma_f32_16x16x32_bf16 v[4:7], v[172:175], v[222:225], v[4:7]
	v_lshl_add_u64 v[200:201], v[230:231], 0, s[26:27]
	s_mov_b32 m0, s59
	s_nop 0
	global_load_lds_dwordx4 v[200:201], off
	v_mfma_f32_16x16x32_bf16 v[16:19], v[184:187], v[214:217], v[16:19]
	v_mfma_f32_16x16x32_bf16 v[0:3], v[184:187], v[222:225], v[0:3]
	s_setprio 0
	s_barrier
	s_add_i32 s67, s67, 2
	s_add_u32 s50, s50, 0x100
	s_addc_u32 s51, s51, 0
	s_add_u32 s65, s65, 0x100
	s_addc_u32 s66, s66, 0
.LBB0_1593:
	ds_read_b128 v[146:149], v152
	ds_read_b128 v[156:159], v152 offset:1024
	ds_read_b128 v[160:163], v152 offset:2048
	ds_read_b128 v[164:167], v152 offset:3072
	ds_read_b128 v[168:171], v153
	ds_read_b128 v[172:175], v153 offset:1024
	ds_read_b128 v[180:183], v153 offset:2048
	ds_read_b128 v[184:187], v153 offset:3072
	s_add_u32 s52, s50, 0xfffc0080
	s_addc_u32 s53, s51, -1
	s_cmp_eq_u32 s67, 12
	s_cselect_b32 s55, s39, s53
	s_cselect_b32 s54, s47, s52
	s_cselect_b32 s53, s37, s66
	s_cselect_b32 s52, s64, s65
	v_lshl_add_u64 v[200:201], s[50:51], 0, v[136:137]
	s_add_i32 m0, s33, 0xc000
	ds_read_b128 v[188:191], v154
	ds_read_b128 v[192:195], v154 offset:1024
	ds_read_b128 v[196:199], v154 offset:2048
	ds_read_b128 v[206:209], v154 offset:3072
	ds_read_b128 v[210:213], v154 offset:4096
	ds_read_b128 v[214:217], v154 offset:5120
	ds_read_b128 v[218:221], v154 offset:6144
	ds_read_b128 v[222:225], v154 offset:7168
	global_load_lds_dwordx4 v[200:201], off
	v_lshl_add_u64 v[200:201], s[50:51], 0, v[138:139]
	s_add_i32 m0, s33, 0xe000
	s_nop 0
	global_load_lds_dwordx4 v[200:201], off
	s_waitcnt vmcnt(8)
	s_waitcnt lgkmcnt(0)
	s_barrier
; #define PG8_STAGE(bufoff, gbase, voff) do { _Pragma("unroll") for (int _i = 0; _i < 2; ++_i) \
;         __builtin_amdgcn_global_load_lds((const unsigned*)((const char*)(gbase) + (voff)[_i]), (PG8_LAS unsigned*)(lds + (bufoff) + ldsw + _i * 8192), 16, 0, 0); } while (0)
; #define PG8_LDA(dst, b, h) do { _Pragma("unroll") for (int m = 0; m < 4; ++m) _Pragma("unroll") for (int k = 0; k < 2; ++k) dst[m][k] = *(const PG8_LAS bf16x8*)(lds + PG8_SA(b, h) + aoff + m * 2048 + k * 1024); } while (0)
; #define PG8_MMA(ai, bj, At, Bt) do { __builtin_amdgcn_s_setprio(1); _Pragma("unroll") for (int m = 0; m < 4; ++m) _Pragma("unroll") for (int n = 0; n < 2; ++n) _Pragma("unroll") for (int k = 0; k < 2; ++k) \
;         acc[ai][bj][m][n] = __builtin_amdgcn_mfma_f32_16x16x32_bf16(Bt[n][k], At[m][k], acc[ai][bj][m][n], 0, 0, 0); __builtin_amdgcn_s_setprio(0); } while (0)
; #define PG8_WAIT_V(n) asm volatile("s_waitcnt vmcnt(" #n ")" ::: "memory")
; #define PG8_WAIT_L(n) asm volatile("s_waitcnt lgkmcnt(" #n ")" ::: "memory")
; #define PG8_BAR __builtin_amdgcn_s_barrier()
; #define PG8_SCHED __builtin_amdgcn_sched_barrier(0)
; template <class Epi, class Sched, bool ALIGN_EPI = false, bool SP2 = false>
; __device__ __forceinline__ void gemm_phase(PG8_LAS unsigned char* lds, const Gemm g, const Sched& S, const Epi& E) {
;     ...
;             PG8_WAIT_V(8); PG8_WAIT_L(0); PG8_BAR; PG8_MMA(0, 0, At, B0); PG8_MMA(0, 1, At, B1); PG8_BAR; PG8_SCHED;
;             PG8_LDA(At, 0, 1); PG8_STAGE(PG8_SB(0, 0), b2, voffB); PG8_STAGE(PG8_SB(0, 1), b2 + hstep, voffB); PG8_STAGE(PG8_SA(0, 0), a2, voffA);
;             PG8_WAIT_V(8); PG8_WAIT_L(0); PG8_BAR; PG8_MMA(1, 0, At, B0); PG8_MMA(1, 1, At, B1); PG8_BAR; PG8_SCHED;
	s_setprio 1
	s_waitcnt lgkmcnt(0)
	v_mfma_f32_16x16x32_bf16 v[124:127], v[146:149], v[188:191], v[124:127]
	v_mfma_f32_16x16x32_bf16 v[108:111], v[146:149], v[196:199], v[108:111]
	v_mfma_f32_16x16x32_bf16 v[120:123], v[160:163], v[188:191], v[120:123]
	v_mfma_f32_16x16x32_bf16 v[104:107], v[160:163], v[196:199], v[104:107]
	v_mfma_f32_16x16x32_bf16 v[92:95], v[146:149], v[210:213], v[92:95]
	v_mfma_f32_16x16x32_bf16 v[76:79], v[146:149], v[218:221], v[76:79]
	v_mfma_f32_16x16x32_bf16 v[88:91], v[160:163], v[210:213], v[88:91]
	v_mfma_f32_16x16x32_bf16 v[72:75], v[160:163], v[218:221], v[72:75]
	v_mfma_f32_16x16x32_bf16 v[124:127], v[156:159], v[192:195], v[124:127]
	v_mfma_f32_16x16x32_bf16 v[108:111], v[156:159], v[206:209], v[108:111]
	v_mfma_f32_16x16x32_bf16 v[120:123], v[164:167], v[192:195], v[120:123]
	v_mfma_f32_16x16x32_bf16 v[104:107], v[164:167], v[206:209], v[104:107]
	v_mfma_f32_16x16x32_bf16 v[92:95], v[156:159], v[214:217], v[92:95]
	v_mfma_f32_16x16x32_bf16 v[76:79], v[156:159], v[222:225], v[76:79]
	v_mfma_f32_16x16x32_bf16 v[88:91], v[164:167], v[214:217], v[88:91]
	v_mfma_f32_16x16x32_bf16 v[72:75], v[164:167], v[222:225], v[72:75]
	s_setprio 0
	s_setprio 1
	v_mfma_f32_16x16x32_bf16 v[116:119], v[168:171], v[188:191], v[116:119]
	v_mfma_f32_16x16x32_bf16 v[100:103], v[168:171], v[196:199], v[100:103]
	v_mfma_f32_16x16x32_bf16 v[112:115], v[180:183], v[188:191], v[112:115]
	v_mfma_f32_16x16x32_bf16 v[96:99], v[180:183], v[196:199], v[96:99]
	v_mfma_f32_16x16x32_bf16 v[84:87], v[168:171], v[210:213], v[84:87]
	v_mfma_f32_16x16x32_bf16 v[68:71], v[168:171], v[218:221], v[68:71]
	v_mfma_f32_16x16x32_bf16 v[80:83], v[180:183], v[210:213], v[80:83]
	v_mfma_f32_16x16x32_bf16 v[64:67], v[180:183], v[218:221], v[64:67]
	v_mfma_f32_16x16x32_bf16 v[116:119], v[172:175], v[192:195], v[116:119]
	v_mfma_f32_16x16x32_bf16 v[100:103], v[172:175], v[206:209], v[100:103]
	v_mfma_f32_16x16x32_bf16 v[112:115], v[184:187], v[192:195], v[112:115]
	v_mfma_f32_16x16x32_bf16 v[96:99], v[184:187], v[206:209], v[96:99]
	v_mfma_f32_16x16x32_bf16 v[84:87], v[172:175], v[214:217], v[84:87]
	v_mfma_f32_16x16x32_bf16 v[68:71], v[172:175], v[222:225], v[68:71]
	v_mfma_f32_16x16x32_bf16 v[80:83], v[184:187], v[214:217], v[80:83]
	v_mfma_f32_16x16x32_bf16 v[64:67], v[184:187], v[222:225], v[64:67]
	s_setprio 0
	s_barrier
	s_add_i32 s74, s60, s15
	v_lshl_add_u64 v[200:201], s[52:53], 0, v[130:131]
	s_mov_b32 m0, s74
	ds_read_b128 v[188:191], v154 offset:16384
	ds_read_b128 v[192:195], v154 offset:17408
	ds_read_b128 v[196:199], v154 offset:18432
	ds_read_b128 v[206:209], v154 offset:19456
	ds_read_b128 v[210:213], v154 offset:20480
	ds_read_b128 v[214:217], v154 offset:21504
	ds_read_b128 v[218:221], v154 offset:22528
	ds_read_b128 v[222:225], v154 offset:23552
	global_load_lds_dwordx4 v[200:201], off
	s_add_i32 m0, s74, 0x2000
	s_add_u32 s74, s52, 0x40000
	v_lshl_add_u64 v[226:227], s[52:53], 0, v[134:135]
	s_addc_u32 s75, s53, 0
	s_add_i32 s76, s61, s15
	global_load_lds_dwordx4 v[226:227], off
	v_lshl_add_u64 v[228:229], s[74:75], 0, v[130:131]
	s_mov_b32 m0, s76
	global_load_lds_dwordx4 v[228:229], off
	v_lshl_add_u64 v[228:229], s[74:75], 0, v[134:135]
	s_add_i32 m0, s76, 0x2000
	s_nop 0
	global_load_lds_dwordx4 v[228:229], off
	s_waitcnt vmcnt(6)
	s_waitcnt lgkmcnt(0)
	s_barrier
	s_setprio 1
	s_waitcnt lgkmcnt(0)
	v_mfma_f32_16x16x32_bf16 v[60:63], v[146:149], v[188:191], v[60:63]
	v_mfma_f32_16x16x32_bf16 v[44:47], v[146:149], v[196:199], v[44:47]
	v_mfma_f32_16x16x32_bf16 v[56:59], v[160:163], v[188:191], v[56:59]
	v_mfma_f32_16x16x32_bf16 v[40:43], v[160:163], v[196:199], v[40:43]
	v_mfma_f32_16x16x32_bf16 v[28:31], v[146:149], v[210:213], v[28:31]
	v_mfma_f32_16x16x32_bf16 v[12:15], v[146:149], v[218:221], v[12:15]
	v_mfma_f32_16x16x32_bf16 v[24:27], v[160:163], v[210:213], v[24:27]
	v_mfma_f32_16x16x32_bf16 v[8:11], v[160:163], v[218:221], v[8:11]
	v_mfma_f32_16x16x32_bf16 v[60:63], v[156:159], v[192:195], v[60:63]
	v_mfma_f32_16x16x32_bf16 v[44:47], v[156:159], v[206:209], v[44:47]
	v_mfma_f32_16x16x32_bf16 v[56:59], v[164:167], v[192:195], v[56:59]
	v_mfma_f32_16x16x32_bf16 v[40:43], v[164:167], v[206:209], v[40:43]
	v_mfma_f32_16x16x32_bf16 v[28:31], v[156:159], v[214:217], v[28:31]
	v_mfma_f32_16x16x32_bf16 v[12:15], v[156:159], v[222:225], v[12:15]
	v_lshl_add_u64 v[228:229], s[54:55], 0, v[128:129]
	s_mov_b32 m0, s33
	s_nop 0
	global_load_lds_dwordx4 v[228:229], off
	v_mfma_f32_16x16x32_bf16 v[24:27], v[164:167], v[214:217], v[24:27]
	v_mfma_f32_16x16x32_bf16 v[8:11], v[164:167], v[222:225], v[8:11]
	s_setprio 0
	s_setprio 1
	v_mfma_f32_16x16x32_bf16 v[52:55], v[168:171], v[188:191], v[52:55]
	v_mfma_f32_16x16x32_bf16 v[36:39], v[168:171], v[196:199], v[36:39]
	v_mfma_f32_16x16x32_bf16 v[48:51], v[180:183], v[188:191], v[48:51]
	v_mfma_f32_16x16x32_bf16 v[32:35], v[180:183], v[196:199], v[32:35]
	v_mfma_f32_16x16x32_bf16 v[20:23], v[168:171], v[210:213], v[20:23]
	v_mfma_f32_16x16x32_bf16 v[4:7], v[168:171], v[218:221], v[4:7]
	v_mfma_f32_16x16x32_bf16 v[16:19], v[180:183], v[210:213], v[16:19]
	v_mfma_f32_16x16x32_bf16 v[0:3], v[180:183], v[218:221], v[0:3]
	v_mfma_f32_16x16x32_bf16 v[52:55], v[172:175], v[192:195], v[52:55]
	v_mfma_f32_16x16x32_bf16 v[36:39], v[172:175], v[206:209], v[36:39]
	v_mfma_f32_16x16x32_bf16 v[48:51], v[184:187], v[192:195], v[48:51]
	v_mfma_f32_16x16x32_bf16 v[32:35], v[184:187], v[206:209], v[32:35]
	v_mfma_f32_16x16x32_bf16 v[20:23], v[172:175], v[214:217], v[20:23]
	v_mfma_f32_16x16x32_bf16 v[4:7], v[172:175], v[222:225], v[4:7]
	v_lshl_add_u64 v[230:231], s[54:55], 0, v[132:133]
	s_mov_b32 m0, s34
	s_nop 0
	global_load_lds_dwordx4 v[230:231], off
	v_mfma_f32_16x16x32_bf16 v[16:19], v[184:187], v[214:217], v[16:19]
	v_mfma_f32_16x16x32_bf16 v[0:3], v[184:187], v[222:225], v[0:3]
	s_setprio 0
	s_barrier
; #define PG8_STAGE(bufoff, gbase, voff) do { _Pragma("unroll") for (int _i = 0; _i < 2; ++_i) \
;         __builtin_amdgcn_global_load_lds((const unsigned*)((const char*)(gbase) + (voff)[_i]), (PG8_LAS unsigned*)(lds + (bufoff) + ldsw + _i * 8192), 16, 0, 0); } while (0)
; #define PG8_LDA(dst, b, h) do { _Pragma("unroll") for (int m = 0; m < 4; ++m) _Pragma("unroll") for (int k = 0; k < 2; ++k) dst[m][k] = *(const PG8_LAS bf16x8*)(lds + PG8_SA(b, h) + aoff + m * 2048 + k * 1024); } while (0)
; #define PG8_LDB(dst, b, h) do { _Pragma("unroll") for (int n = 0; n < 2; ++n) _Pragma("unroll") for (int k = 0; k < 2; ++k) dst[n][k] = *(const PG8_LAS bf16x8*)(lds + PG8_SB(b, h) + boff + n * 2048 + k * 1024); } while (0)
; #define PG8_MMA(ai, bj, At, Bt) do { __builtin_amdgcn_s_setprio(1); _Pragma("unroll") for (int m = 0; m < 4; ++m) _Pragma("unroll") for (int n = 0; n < 2; ++n) _Pragma("unroll") for (int k = 0; k < 2; ++k) \
;         acc[ai][bj][m][n] = __builtin_amdgcn_mfma_f32_16x16x32_bf16(Bt[n][k], At[m][k], acc[ai][bj][m][n], 0, 0, 0); __builtin_amdgcn_s_setprio(0); } while (0)
; #define PG8_WAIT_V(n) asm volatile("s_waitcnt vmcnt(" #n ")" ::: "memory")
; #define PG8_WAIT_L(n) asm volatile("s_waitcnt lgkmcnt(" #n ")" ::: "memory")
; #define PG8_BAR __builtin_amdgcn_s_barrier()
; #define PG8_SCHED __builtin_amdgcn_sched_barrier(0)
; template <class Epi, class Sched, bool ALIGN_EPI = false, bool SP2 = false>
; __device__ __forceinline__ void gemm_phase(PG8_LAS unsigned char* lds, const Gemm g, const Sched& S, const Epi& E) {
;     ...
;             PG8_LDB(B0, 1, 0); PG8_LDB(B1, 1, 1); PG8_SCHED; PG8_LDA(At, 1, 0); PG8_STAGE(PG8_SA(0, 1), a2 + hstep, voffA);
;             PG8_WAIT_V(8); PG8_WAIT_L(0); PG8_BAR; PG8_MMA(0, 0, At, B0); PG8_MMA(0, 1, At, B1); PG8_BAR; PG8_SCHED;
	s_add_i32 s74, 0, 0x18000
	s_add_i32 s75, 0, 0x1c000
	v_add_u32_e32 v164, s74, v150
	v_add_u32_e32 v179, s75, v150
	ds_read_b128 v[146:149], v164
	ds_read_b128 v[156:159], v164 offset:1024
	ds_read_b128 v[160:163], v164 offset:2048
	ds_read_b128 v[164:167], v164 offset:3072
	ds_read_b128 v[168:171], v179
	ds_read_b128 v[172:175], v179 offset:1024
	ds_read_b128 v[180:183], v179 offset:2048
	ds_read_b128 v[184:187], v179 offset:3072
	s_add_u32 s54, s54, 0x40000
	s_addc_u32 s55, s55, 0
	s_mov_b32 m0, s49
	v_lshl_add_u64 v[232:233], s[54:55], 0, v[128:129]
	ds_read_b128 v[188:191], v154 offset:32768
	ds_read_b128 v[192:195], v154 offset:33792
	ds_read_b128 v[196:199], v154 offset:34816
	ds_read_b128 v[206:209], v154 offset:35840
	ds_read_b128 v[210:213], v154 offset:36864
	ds_read_b128 v[214:217], v154 offset:37888
	ds_read_b128 v[218:221], v154 offset:38912
	ds_read_b128 v[222:225], v154 offset:39936
	global_load_lds_dwordx4 v[232:233], off
	v_lshl_add_u64 v[232:233], s[54:55], 0, v[132:133]
	s_mov_b32 m0, s56
	s_nop 0
	global_load_lds_dwordx4 v[232:233], off
	s_waitcnt vmcnt(8)
	s_waitcnt lgkmcnt(0)
	s_barrier
	s_setprio 1
	s_waitcnt lgkmcnt(0)
	v_mfma_f32_16x16x32_bf16 v[124:127], v[146:149], v[188:191], v[124:127]
	v_mfma_f32_16x16x32_bf16 v[108:111], v[146:149], v[196:199], v[108:111]
	v_mfma_f32_16x16x32_bf16 v[120:123], v[160:163], v[188:191], v[120:123]
	v_mfma_f32_16x16x32_bf16 v[104:107], v[160:163], v[196:199], v[104:107]
	v_mfma_f32_16x16x32_bf16 v[92:95], v[146:149], v[210:213], v[92:95]
	v_mfma_f32_16x16x32_bf16 v[76:79], v[146:149], v[218:221], v[76:79]
	v_mfma_f32_16x16x32_bf16 v[88:91], v[160:163], v[210:213], v[88:91]
	v_mfma_f32_16x16x32_bf16 v[72:75], v[160:163], v[218:221], v[72:75]
	v_mfma_f32_16x16x32_bf16 v[124:127], v[156:159], v[192:195], v[124:127]
	v_mfma_f32_16x16x32_bf16 v[108:111], v[156:159], v[206:209], v[108:111]
	v_mfma_f32_16x16x32_bf16 v[120:123], v[164:167], v[192:195], v[120:123]
	v_mfma_f32_16x16x32_bf16 v[104:107], v[164:167], v[206:209], v[104:107]
	v_mfma_f32_16x16x32_bf16 v[92:95], v[156:159], v[214:217], v[92:95]
	v_mfma_f32_16x16x32_bf16 v[76:79], v[156:159], v[222:225], v[76:79]
	v_mfma_f32_16x16x32_bf16 v[88:91], v[164:167], v[214:217], v[88:91]
	v_mfma_f32_16x16x32_bf16 v[72:75], v[164:167], v[222:225], v[72:75]
	s_setprio 0
	s_setprio 1
	v_mfma_f32_16x16x32_bf16 v[116:119], v[168:171], v[188:191], v[116:119]
	v_mfma_f32_16x16x32_bf16 v[100:103], v[168:171], v[196:199], v[100:103]
	v_mfma_f32_16x16x32_bf16 v[112:115], v[180:183], v[188:191], v[112:115]
	v_mfma_f32_16x16x32_bf16 v[96:99], v[180:183], v[196:199], v[96:99]
	v_mfma_f32_16x16x32_bf16 v[84:87], v[168:171], v[210:213], v[84:87]
	v_mfma_f32_16x16x32_bf16 v[68:71], v[168:171], v[218:221], v[68:71]
	v_mfma_f32_16x16x32_bf16 v[80:83], v[180:183], v[210:213], v[80:83]
	v_mfma_f32_16x16x32_bf16 v[64:67], v[180:183], v[218:221], v[64:67]
	v_mfma_f32_16x16x32_bf16 v[116:119], v[172:175], v[192:195], v[116:119]
	v_mfma_f32_16x16x32_bf16 v[100:103], v[172:175], v[206:209], v[100:103]
	v_mfma_f32_16x16x32_bf16 v[112:115], v[184:187], v[192:195], v[112:115]
	v_mfma_f32_16x16x32_bf16 v[96:99], v[184:187], v[206:209], v[96:99]
	v_mfma_f32_16x16x32_bf16 v[84:87], v[172:175], v[214:217], v[84:87]
	v_mfma_f32_16x16x32_bf16 v[68:71], v[172:175], v[222:225], v[68:71]
	v_mfma_f32_16x16x32_bf16 v[80:83], v[184:187], v[214:217], v[80:83]
	v_mfma_f32_16x16x32_bf16 v[64:67], v[184:187], v[222:225], v[64:67]
	s_setprio 0
	s_barrier
; #define PG8_STAGE(bufoff, gbase, voff) do { _Pragma("unroll") for (int _i = 0; _i < 2; ++_i) \
;         __builtin_amdgcn_global_load_lds((const unsigned*)((const char*)(gbase) + (voff)[_i]), (PG8_LAS unsigned*)(lds + (bufoff) + ldsw + _i * 8192), 16, 0, 0); } while (0)
; #define PG8_LDA(dst, b, h) do { _Pragma("unroll") for (int m = 0; m < 4; ++m) _Pragma("unroll") for (int k = 0; k < 2; ++k) dst[m][k] = *(const PG8_LAS bf16x8*)(lds + PG8_SA(b, h) + aoff + m * 2048 + k * 1024); } while (0)
; #define PG8_MMA(ai, bj, At, Bt) do { __builtin_amdgcn_s_setprio(1); _Pragma("unroll") for (int m = 0; m < 4; ++m) _Pragma("unroll") for (int n = 0; n < 2; ++n) _Pragma("unroll") for (int k = 0; k < 2; ++k) \
;         acc[ai][bj][m][n] = __builtin_amdgcn_mfma_f32_16x16x32_bf16(Bt[n][k], At[m][k], acc[ai][bj][m][n], 0, 0, 0); __builtin_amdgcn_s_setprio(0); } while (0)
; #define PG8_WAIT_V(n) asm volatile("s_waitcnt vmcnt(" #n ")" ::: "memory")
; #define PG8_WAIT_L(n) asm volatile("s_waitcnt lgkmcnt(" #n ")" ::: "memory")
; #define PG8_BAR __builtin_amdgcn_s_barrier()
; #define PG8_SCHED __builtin_amdgcn_sched_barrier(0)
; template <class Epi, class Sched, bool ALIGN_EPI = false, bool SP2 = false>
; __device__ __forceinline__ void gemm_phase(PG8_LAS unsigned char* lds, const Gemm g, const Sched& S, const Epi& E) {
;     ...
;             PG8_LDA(At, 1, 1); PG8_STAGE(PG8_SB(1, 0), b3, voffB); PG8_STAGE(PG8_SB(1, 1), b3 + hstep, voffB); PG8_STAGE(PG8_SA(1, 0), a3, voffA);
;             PG8_WAIT_V(8); PG8_WAIT_L(0); PG8_BAR; PG8_MMA(1, 0, At, B0); PG8_MMA(1, 1, At, B1); PG8_BAR; PG8_SCHED;
	s_add_i32 s54, s74, s15
	v_lshl_add_u64 v[200:201], v[200:201], 0, s[26:27]
	s_mov_b32 m0, s54
	ds_read_b128 v[188:191], v154 offset:49152
	ds_read_b128 v[192:195], v154 offset:50176
	ds_read_b128 v[196:199], v154 offset:51200
	ds_read_b128 v[206:209], v154 offset:52224
	ds_read_b128 v[210:213], v154 offset:53248
	ds_read_b128 v[214:217], v154 offset:54272
	ds_read_b128 v[218:221], v154 offset:55296
	ds_read_b128 v[222:225], v154 offset:56320
	global_load_lds_dwordx4 v[200:201], off
	s_add_i32 m0, s54, 0x2000
	s_add_u32 s52, s52, 0x40080
	v_lshl_add_u64 v[200:201], v[226:227], 0, s[26:27]
	s_addc_u32 s53, s53, 0
	s_add_i32 s54, s75, s15
	global_load_lds_dwordx4 v[200:201], off
	v_lshl_add_u64 v[200:201], s[52:53], 0, v[130:131]
	s_mov_b32 m0, s54
	s_nop 0
	global_load_lds_dwordx4 v[200:201], off
	v_lshl_add_u64 v[200:201], s[52:53], 0, v[134:135]
	s_add_i32 m0, s54, 0x2000
	s_nop 0
	global_load_lds_dwordx4 v[200:201], off
	s_waitcnt vmcnt(6)
	s_waitcnt lgkmcnt(0)
	s_barrier
	s_setprio 1
	s_waitcnt lgkmcnt(0)
	v_mfma_f32_16x16x32_bf16 v[60:63], v[146:149], v[188:191], v[60:63]
	v_mfma_f32_16x16x32_bf16 v[44:47], v[146:149], v[196:199], v[44:47]
	v_mfma_f32_16x16x32_bf16 v[56:59], v[160:163], v[188:191], v[56:59]
	v_mfma_f32_16x16x32_bf16 v[40:43], v[160:163], v[196:199], v[40:43]
	v_mfma_f32_16x16x32_bf16 v[28:31], v[146:149], v[210:213], v[28:31]
	v_mfma_f32_16x16x32_bf16 v[12:15], v[146:149], v[218:221], v[12:15]
	v_mfma_f32_16x16x32_bf16 v[24:27], v[160:163], v[210:213], v[24:27]
	v_mfma_f32_16x16x32_bf16 v[8:11], v[160:163], v[218:221], v[8:11]
	v_mfma_f32_16x16x32_bf16 v[60:63], v[156:159], v[192:195], v[60:63]
	v_mfma_f32_16x16x32_bf16 v[44:47], v[156:159], v[206:209], v[44:47]
	v_mfma_f32_16x16x32_bf16 v[56:59], v[164:167], v[192:195], v[56:59]
	v_mfma_f32_16x16x32_bf16 v[40:43], v[164:167], v[206:209], v[40:43]
	v_mfma_f32_16x16x32_bf16 v[28:31], v[156:159], v[214:217], v[28:31]
	v_mfma_f32_16x16x32_bf16 v[12:15], v[156:159], v[222:225], v[12:15]
	v_lshl_add_u64 v[200:201], v[228:229], 0, s[26:27]
	s_mov_b32 m0, s58
	s_nop 0
	global_load_lds_dwordx4 v[200:201], off
	v_mfma_f32_16x16x32_bf16 v[24:27], v[164:167], v[214:217], v[24:27]
	v_mfma_f32_16x16x32_bf16 v[8:11], v[164:167], v[222:225], v[8:11]
	s_setprio 0
	s_setprio 1
	v_mfma_f32_16x16x32_bf16 v[52:55], v[168:171], v[188:191], v[52:55]
	v_mfma_f32_16x16x32_bf16 v[36:39], v[168:171], v[196:199], v[36:39]
	v_mfma_f32_16x16x32_bf16 v[48:51], v[180:183], v[188:191], v[48:51]
	v_mfma_f32_16x16x32_bf16 v[32:35], v[180:183], v[196:199], v[32:35]
	v_mfma_f32_16x16x32_bf16 v[20:23], v[168:171], v[210:213], v[20:23]
	v_mfma_f32_16x16x32_bf16 v[4:7], v[168:171], v[218:221], v[4:7]
	v_mfma_f32_16x16x32_bf16 v[16:19], v[180:183], v[210:213], v[16:19]
	v_mfma_f32_16x16x32_bf16 v[0:3], v[180:183], v[218:221], v[0:3]
	v_mfma_f32_16x16x32_bf16 v[52:55], v[172:175], v[192:195], v[52:55]
	v_mfma_f32_16x16x32_bf16 v[36:39], v[172:175], v[206:209], v[36:39]
	v_mfma_f32_16x16x32_bf16 v[48:51], v[184:187], v[192:195], v[48:51]
	v_mfma_f32_16x16x32_bf16 v[32:35], v[184:187], v[206:209], v[32:35]
	v_mfma_f32_16x16x32_bf16 v[20:23], v[172:175], v[214:217], v[20:23]
	v_mfma_f32_16x16x32_bf16 v[4:7], v[172:175], v[222:225], v[4:7]
	v_lshl_add_u64 v[200:201], v[230:231], 0, s[26:27]
	s_mov_b32 m0, s59
	s_nop 0
	global_load_lds_dwordx4 v[200:201], off
	v_mfma_f32_16x16x32_bf16 v[16:19], v[184:187], v[214:217], v[16:19]
	v_mfma_f32_16x16x32_bf16 v[0:3], v[184:187], v[222:225], v[0:3]
	s_setprio 0
	s_barrier
	s_add_i32 s67, s67, 2
	s_add_u32 s50, s50, 0x100
	s_addc_u32 s51, s51, 0
	s_add_u32 s65, s65, 0x100
	s_addc_u32 s66, s66, 0
	s_cmp_gt_u32 s67, 13
	s_cbranch_scc0 .LBB0_1593
	s_and_b64 vcc, exec, s[28:29]
	s_cbranch_vccz .LBB0_1596
	s_barrier

; #define PG8_STAGE(bufoff, gbase, voff) do { _Pragma("unroll") for (int _i = 0; _i < 2; ++_i) \
;         __builtin_amdgcn_global_load_lds((const unsigned*)((const char*)(gbase) + (voff)[_i]), (PG8_LAS unsigned*)(lds + (bufoff) + ldsw + _i * 8192), 16, 0, 0); } while (0)
; #define PG8_LDA(dst, b, h) do { _Pragma("unroll") for (int m = 0; m < 4; ++m) _Pragma("unroll") for (int k = 0; k < 2; ++k) dst[m][k] = *(const PG8_LAS bf16x8*)(lds + PG8_SA(b, h) + aoff + m * 2048 + k * 1024); } while (0)
; #define PG8_LDB(dst, b, h) do { _Pragma("unroll") for (int n = 0; n < 2; ++n) _Pragma("unroll") for (int k = 0; k < 2; ++k) dst[n][k] = *(const PG8_LAS bf16x8*)(lds + PG8_SB(b, h) + boff + n * 2048 + k * 1024); } while (0)
; #define PG8_WAIT_V(n) asm volatile("s_waitcnt vmcnt(" #n ")" ::: "memory")
; #define PG8_WAIT_L(n) asm volatile("s_waitcnt lgkmcnt(" #n ")" ::: "memory")
; #define PG8_BAR __builtin_amdgcn_s_barrier()
; #define PG8_SCHED __builtin_amdgcn_sched_barrier(0)
; template <class Epi, class Sched, bool ALIGN_EPI = false, bool SP2 = false>
; __device__ __forceinline__ void gemm_phase(PG8_LAS unsigned char* lds, const Gemm g, const Sched& S, const Epi& E) {
;     ...
;         const bool has_next = S.next(ui + 1, nxt);
;         const char* nA = has_next ? (const char*)g.A + (size_t)nxt.pm * tstep : cA; const char* nB = has_next ? (const char*)g.Bt + (size_t)nxt.pn * tstep : cB;
;         for (int t = 0; t < nt; t += 2) {
;             const bool last = (t == nt - 2);
;             const char* a1 = cA + (size_t)(t + 1) * kstep;
;             const char* a2 = last ? nA : cA + (size_t)(t + 2) * kstep; const char* b2 = last ? nB : cB + (size_t)(t + 2) * kstep;
;             const char* a3 = a2 + kstep; const char* b3 = b2 + kstep;
;             if (last && has_next) S.a_ready(nxt);
;             if constexpr (SP2) {
;             PG8_LDB(B0, 0, 0); PG8_LDB(B1, 0, 1); PG8_SCHED; PG8_LDA(At, 0, 0); PG8_STAGE(PG8_SA(1, 1), a1 + hstep, voffA);
;             PG8_WAIT_V(8); PG8_WAIT_L(0); PG8_BAR; PG8_MMA(0, 0, At, B0); PG8_MMA(0, 1, At, B1); PG8_BAR; PG8_SCHED;
;             PG8_LDA(At, 0, 1); PG8_STAGE(PG8_SB(0, 0), b2, voffB); PG8_STAGE(PG8_SB(0, 1), b2 + hstep, voffB); PG8_STAGE(PG8_SA(0, 0), a2, voffA);
;             PG8_WAIT_V(8); PG8_WAIT_L(0); PG8_BAR; PG8_MMA(1, 0, At, B0); PG8_MMA(1, 1, At, B1); PG8_BAR; PG8_SCHED;
.LBB0_1680:
	s_ashr_i32 s47, s46, 31
	s_lshl_b64 s[48:49], s[46:47], 19
	s_add_u32 s48, s22, s48
	s_addc_u32 s49, s23, s49
	s_and_b64 s[50:51], s[4:5], exec
	s_cselect_b32 s47, s49, s53
	s_cselect_b32 s77, s48, s52
	s_ashr_i32 s45, s44, 31
	s_lshl_b64 s[50:51], s[44:45], 19
	s_add_u32 s50, s15, s50
	s_addc_u32 s51, s33, s51
	s_and_b64 s[56:57], s[4:5], exec
	s_cselect_b32 s45, s51, s55
	s_cselect_b32 s78, s50, s54
	s_add_u32 s52, s52, 0x40080
	s_addc_u32 s53, s53, 0
	s_add_u32 s79, s54, 0x100
	s_addc_u32 s80, s55, 0
	s_mov_b32 s81, -2
	ds_read_b128 v[146:149], v152
	ds_read_b128 v[156:159], v152 offset:1024
	ds_read_b128 v[160:163], v152 offset:2048
	ds_read_b128 v[164:167], v152 offset:3072
	ds_read_b128 v[168:171], v153
	ds_read_b128 v[172:175], v153 offset:1024
	ds_read_b128 v[180:183], v153 offset:2048
	ds_read_b128 v[184:187], v153 offset:3072
	s_add_u32 s54, s52, 0xfffc0080
	s_addc_u32 s55, s53, -1
	s_cmp_eq_u32 s81, 12
	s_cselect_b32 s57, s47, s55
	s_cselect_b32 s56, s77, s54
	s_cselect_b32 s55, s45, s80
	s_cselect_b32 s54, s78, s79
	v_lshl_add_u64 v[200:201], s[52:53], 0, v[136:137]
	s_add_i32 m0, s58, 0xc000
	ds_read_b128 v[188:191], v154
	ds_read_b128 v[192:195], v154 offset:1024
	ds_read_b128 v[196:199], v154 offset:2048
	ds_read_b128 v[206:209], v154 offset:3072
	ds_read_b128 v[210:213], v154 offset:4096
	ds_read_b128 v[214:217], v154 offset:5120
	ds_read_b128 v[218:221], v154 offset:6144
	ds_read_b128 v[222:225], v154 offset:7168
	global_load_lds_dwordx4 v[200:201], off
	v_lshl_add_u64 v[200:201], s[52:53], 0, v[138:139]
	s_add_i32 m0, s58, 0xe000
	s_nop 0
	global_load_lds_dwordx4 v[200:201], off
	s_waitcnt vmcnt(8)
	s_waitcnt lgkmcnt(0)
	s_barrier
	s_setprio 1
	s_waitcnt lgkmcnt(0)
	v_mfma_f32_16x16x32_bf16 v[124:127], v[146:149], v[188:191], 0
	v_mfma_f32_16x16x32_bf16 v[108:111], v[146:149], v[196:199], 0
	v_mfma_f32_16x16x32_bf16 v[120:123], v[160:163], v[188:191], 0
	v_mfma_f32_16x16x32_bf16 v[104:107], v[160:163], v[196:199], 0
	v_mfma_f32_16x16x32_bf16 v[92:95], v[146:149], v[210:213], 0
	v_mfma_f32_16x16x32_bf16 v[76:79], v[146:149], v[218:221], 0
	v_mfma_f32_16x16x32_bf16 v[88:91], v[160:163], v[210:213], 0
	v_mfma_f32_16x16x32_bf16 v[72:75], v[160:163], v[218:221], 0
	v_mfma_f32_16x16x32_bf16 v[124:127], v[156:159], v[192:195], v[124:127]
	v_mfma_f32_16x16x32_bf16 v[108:111], v[156:159], v[206:209], v[108:111]
	v_mfma_f32_16x16x32_bf16 v[120:123], v[164:167], v[192:195], v[120:123]
	v_mfma_f32_16x16x32_bf16 v[104:107], v[164:167], v[206:209], v[104:107]
	v_mfma_f32_16x16x32_bf16 v[92:95], v[156:159], v[214:217], v[92:95]
	v_mfma_f32_16x16x32_bf16 v[76:79], v[156:159], v[222:225], v[76:79]
	v_mfma_f32_16x16x32_bf16 v[88:91], v[164:167], v[214:217], v[88:91]
	v_mfma_f32_16x16x32_bf16 v[72:75], v[164:167], v[222:225], v[72:75]
	s_setprio 0
	s_setprio 1
	v_mfma_f32_16x16x32_bf16 v[116:119], v[168:171], v[188:191], 0
	v_mfma_f32_16x16x32_bf16 v[100:103], v[168:171], v[196:199], 0
	v_mfma_f32_16x16x32_bf16 v[112:115], v[180:183], v[188:191], 0
	v_mfma_f32_16x16x32_bf16 v[96:99], v[180:183], v[196:199], 0
	v_mfma_f32_16x16x32_bf16 v[84:87], v[168:171], v[210:213], 0
	v_mfma_f32_16x16x32_bf16 v[68:71], v[168:171], v[218:221], 0
	v_mfma_f32_16x16x32_bf16 v[80:83], v[180:183], v[210:213], 0
	v_mfma_f32_16x16x32_bf16 v[64:67], v[180:183], v[218:221], 0
	v_mfma_f32_16x16x32_bf16 v[116:119], v[172:175], v[192:195], v[116:119]
	v_mfma_f32_16x16x32_bf16 v[100:103], v[172:175], v[206:209], v[100:103]
	v_mfma_f32_16x16x32_bf16 v[112:115], v[184:187], v[192:195], v[112:115]
	v_mfma_f32_16x16x32_bf16 v[96:99], v[184:187], v[206:209], v[96:99]
	v_mfma_f32_16x16x32_bf16 v[84:87], v[172:175], v[214:217], v[84:87]
	v_mfma_f32_16x16x32_bf16 v[68:71], v[172:175], v[222:225], v[68:71]
	v_mfma_f32_16x16x32_bf16 v[80:83], v[184:187], v[214:217], v[80:83]
	v_mfma_f32_16x16x32_bf16 v[64:67], v[184:187], v[222:225], v[64:67]
	s_setprio 0
	s_barrier
	s_add_i32 s82, s65, s34
	v_lshl_add_u64 v[200:201], s[54:55], 0, v[132:133]
	s_mov_b32 m0, s82
	ds_read_b128 v[188:191], v154 offset:16384
	ds_read_b128 v[192:195], v154 offset:17408
	ds_read_b128 v[196:199], v154 offset:18432
	ds_read_b128 v[206:209], v154 offset:19456
	ds_read_b128 v[210:213], v154 offset:20480
	ds_read_b128 v[214:217], v154 offset:21504
	ds_read_b128 v[218:221], v154 offset:22528
	ds_read_b128 v[222:225], v154 offset:23552
	global_load_lds_dwordx4 v[200:201], off
	s_add_i32 m0, s82, 0x2000
	s_add_u32 s82, s54, 0x40000
	v_lshl_add_u64 v[226:227], s[54:55], 0, v[128:129]
	s_addc_u32 s83, s55, 0
	s_add_i32 s84, s66, s34
	global_load_lds_dwordx4 v[226:227], off
	v_lshl_add_u64 v[228:229], s[82:83], 0, v[132:133]
	s_mov_b32 m0, s84
	global_load_lds_dwordx4 v[228:229], off
	v_lshl_add_u64 v[228:229], s[82:83], 0, v[128:129]
	s_add_i32 m0, s84, 0x2000
	s_nop 0
	global_load_lds_dwordx4 v[228:229], off
	s_waitcnt vmcnt(6)
	s_waitcnt lgkmcnt(0)
	s_barrier
; #define PG8_STAGE(bufoff, gbase, voff) do { _Pragma("unroll") for (int _i = 0; _i < 2; ++_i) \
;         __builtin_amdgcn_global_load_lds((const unsigned*)((const char*)(gbase) + (voff)[_i]), (PG8_LAS unsigned*)(lds + (bufoff) + ldsw + _i * 8192), 16, 0, 0); } while (0)
; #define PG8_LDA(dst, b, h) do { _Pragma("unroll") for (int m = 0; m < 4; ++m) _Pragma("unroll") for (int k = 0; k < 2; ++k) dst[m][k] = *(const PG8_LAS bf16x8*)(lds + PG8_SA(b, h) + aoff + m * 2048 + k * 1024); } while (0)
; #define PG8_LDB(dst, b, h) do { _Pragma("unroll") for (int n = 0; n < 2; ++n) _Pragma("unroll") for (int k = 0; k < 2; ++k) dst[n][k] = *(const PG8_LAS bf16x8*)(lds + PG8_SB(b, h) + boff + n * 2048 + k * 1024); } while (0)
; #define PG8_MMA(ai, bj, At, Bt) do { __builtin_amdgcn_s_setprio(1); _Pragma("unroll") for (int m = 0; m < 4; ++m) _Pragma("unroll") for (int n = 0; n < 2; ++n) _Pragma("unroll") for (int k = 0; k < 2; ++k) \
;         acc[ai][bj][m][n] = __builtin_amdgcn_mfma_f32_16x16x32_bf16(Bt[n][k], At[m][k], acc[ai][bj][m][n], 0, 0, 0); __builtin_amdgcn_s_setprio(0); } while (0)
; #define PG8_WAIT_V(n) asm volatile("s_waitcnt vmcnt(" #n ")" ::: "memory")
; #define PG8_WAIT_L(n) asm volatile("s_waitcnt lgkmcnt(" #n ")" ::: "memory")
; #define PG8_BAR __builtin_amdgcn_s_barrier()
; #define PG8_SCHED __builtin_amdgcn_sched_barrier(0)
; template <class Epi, class Sched, bool ALIGN_EPI = false, bool SP2 = false>
; __device__ __forceinline__ void gemm_phase(PG8_LAS unsigned char* lds, const Gemm g, const Sched& S, const Epi& E) {
;     ...
;             PG8_WAIT_V(8); PG8_WAIT_L(0); PG8_BAR; PG8_MMA(1, 0, At, B0); PG8_MMA(1, 1, At, B1); PG8_BAR; PG8_SCHED;
;             PG8_LDB(B0, 1, 0); PG8_LDB(B1, 1, 1); PG8_SCHED; PG8_LDA(At, 1, 0); PG8_STAGE(PG8_SA(0, 1), a2 + hstep, voffA);
;             PG8_WAIT_V(8); PG8_WAIT_L(0); PG8_BAR; PG8_MMA(0, 0, At, B0); PG8_MMA(0, 1, At, B1); PG8_BAR; PG8_SCHED;
	s_setprio 1
	s_waitcnt lgkmcnt(0)
	v_mfma_f32_16x16x32_bf16 v[60:63], v[146:149], v[188:191], 0
	v_mfma_f32_16x16x32_bf16 v[44:47], v[146:149], v[196:199], 0
	v_mfma_f32_16x16x32_bf16 v[56:59], v[160:163], v[188:191], 0
	v_mfma_f32_16x16x32_bf16 v[40:43], v[160:163], v[196:199], 0
	v_mfma_f32_16x16x32_bf16 v[28:31], v[146:149], v[210:213], 0
	v_mfma_f32_16x16x32_bf16 v[12:15], v[146:149], v[218:221], 0
	v_mfma_f32_16x16x32_bf16 v[24:27], v[160:163], v[210:213], 0
	v_mfma_f32_16x16x32_bf16 v[8:11], v[160:163], v[218:221], 0
	v_mfma_f32_16x16x32_bf16 v[60:63], v[156:159], v[192:195], v[60:63]
	v_mfma_f32_16x16x32_bf16 v[44:47], v[156:159], v[206:209], v[44:47]
	v_mfma_f32_16x16x32_bf16 v[56:59], v[164:167], v[192:195], v[56:59]
	v_mfma_f32_16x16x32_bf16 v[40:43], v[164:167], v[206:209], v[40:43]
	v_mfma_f32_16x16x32_bf16 v[28:31], v[156:159], v[214:217], v[28:31]
	v_mfma_f32_16x16x32_bf16 v[12:15], v[156:159], v[222:225], v[12:15]
	v_lshl_add_u64 v[228:229], s[56:57], 0, v[134:135]
	s_mov_b32 m0, s58
	s_nop 0
	global_load_lds_dwordx4 v[228:229], off
	v_mfma_f32_16x16x32_bf16 v[24:27], v[164:167], v[214:217], v[24:27]
	v_mfma_f32_16x16x32_bf16 v[8:11], v[164:167], v[222:225], v[8:11]
	s_setprio 0
	s_setprio 1
	v_mfma_f32_16x16x32_bf16 v[52:55], v[168:171], v[188:191], 0
	v_mfma_f32_16x16x32_bf16 v[36:39], v[168:171], v[196:199], 0
	v_mfma_f32_16x16x32_bf16 v[48:51], v[180:183], v[188:191], 0
	v_mfma_f32_16x16x32_bf16 v[32:35], v[180:183], v[196:199], 0
	v_mfma_f32_16x16x32_bf16 v[20:23], v[168:171], v[210:213], 0
	v_mfma_f32_16x16x32_bf16 v[4:7], v[168:171], v[218:221], 0
	v_mfma_f32_16x16x32_bf16 v[16:19], v[180:183], v[210:213], 0
	v_mfma_f32_16x16x32_bf16 v[0:3], v[180:183], v[218:221], 0
	v_mfma_f32_16x16x32_bf16 v[52:55], v[172:175], v[192:195], v[52:55]
	v_mfma_f32_16x16x32_bf16 v[36:39], v[172:175], v[206:209], v[36:39]
	v_mfma_f32_16x16x32_bf16 v[48:51], v[184:187], v[192:195], v[48:51]
	v_mfma_f32_16x16x32_bf16 v[32:35], v[184:187], v[206:209], v[32:35]
	v_mfma_f32_16x16x32_bf16 v[20:23], v[172:175], v[214:217], v[20:23]
	v_mfma_f32_16x16x32_bf16 v[4:7], v[172:175], v[222:225], v[4:7]
	v_lshl_add_u64 v[230:231], s[56:57], 0, v[130:131]
	s_mov_b32 m0, s59
	s_nop 0
	global_load_lds_dwordx4 v[230:231], off
	v_mfma_f32_16x16x32_bf16 v[16:19], v[184:187], v[214:217], v[16:19]
	v_mfma_f32_16x16x32_bf16 v[0:3], v[184:187], v[222:225], v[0:3]
	s_setprio 0
	s_barrier
	s_add_i32 s82, 0, 0x18000
	s_add_i32 s83, 0, 0x1c000
	v_add_u32_e32 v164, s82, v150
	v_add_u32_e32 v179, s83, v150
	ds_read_b128 v[146:149], v164
	ds_read_b128 v[156:159], v164 offset:1024
	ds_read_b128 v[160:163], v164 offset:2048
	ds_read_b128 v[164:167], v164 offset:3072
	ds_read_b128 v[168:171], v179
	ds_read_b128 v[172:175], v179 offset:1024
	ds_read_b128 v[180:183], v179 offset:2048
	ds_read_b128 v[184:187], v179 offset:3072
	s_add_u32 s56, s56, 0x40000
	s_addc_u32 s57, s57, 0
	s_mov_b32 m0, s60
	v_lshl_add_u64 v[232:233], s[56:57], 0, v[134:135]
	ds_read_b128 v[188:191], v154 offset:32768
	ds_read_b128 v[192:195], v154 offset:33792
	ds_read_b128 v[196:199], v154 offset:34816
	ds_read_b128 v[206:209], v154 offset:35840
	ds_read_b128 v[210:213], v154 offset:36864
	ds_read_b128 v[214:217], v154 offset:37888
	ds_read_b128 v[218:221], v154 offset:38912
	ds_read_b128 v[222:225], v154 offset:39936
	global_load_lds_dwordx4 v[232:233], off
	v_lshl_add_u64 v[232:233], s[56:57], 0, v[130:131]
	s_mov_b32 m0, s61
	s_nop 0
	global_load_lds_dwordx4 v[232:233], off
	s_waitcnt vmcnt(8)
	s_waitcnt lgkmcnt(0)
	s_barrier
	s_setprio 1
	s_waitcnt lgkmcnt(0)
	v_mfma_f32_16x16x32_bf16 v[124:127], v[146:149], v[188:191], v[124:127]
	v_mfma_f32_16x16x32_bf16 v[108:111], v[146:149], v[196:199], v[108:111]
	v_mfma_f32_16x16x32_bf16 v[120:123], v[160:163], v[188:191], v[120:123]
	v_mfma_f32_16x16x32_bf16 v[104:107], v[160:163], v[196:199], v[104:107]
	v_mfma_f32_16x16x32_bf16 v[92:95], v[146:149], v[210:213], v[92:95]
	v_mfma_f32_16x16x32_bf16 v[76:79], v[146:149], v[218:221], v[76:79]
	v_mfma_f32_16x16x32_bf16 v[88:91], v[160:163], v[210:213], v[88:91]
	v_mfma_f32_16x16x32_bf16 v[72:75], v[160:163], v[218:221], v[72:75]
	v_mfma_f32_16x16x32_bf16 v[124:127], v[156:159], v[192:195], v[124:127]
	v_mfma_f32_16x16x32_bf16 v[108:111], v[156:159], v[206:209], v[108:111]
	v_mfma_f32_16x16x32_bf16 v[120:123], v[164:167], v[192:195], v[120:123]
	v_mfma_f32_16x16x32_bf16 v[104:107], v[164:167], v[206:209], v[104:107]
	v_mfma_f32_16x16x32_bf16 v[92:95], v[156:159], v[214:217], v[92:95]
	v_mfma_f32_16x16x32_bf16 v[76:79], v[156:159], v[222:225], v[76:79]
	v_mfma_f32_16x16x32_bf16 v[88:91], v[164:167], v[214:217], v[88:91]
	v_mfma_f32_16x16x32_bf16 v[72:75], v[164:167], v[222:225], v[72:75]
	s_setprio 0
	s_setprio 1
	v_mfma_f32_16x16x32_bf16 v[116:119], v[168:171], v[188:191], v[116:119]
	v_mfma_f32_16x16x32_bf16 v[100:103], v[168:171], v[196:199], v[100:103]
	v_mfma_f32_16x16x32_bf16 v[112:115], v[180:183], v[188:191], v[112:115]
	v_mfma_f32_16x16x32_bf16 v[96:99], v[180:183], v[196:199], v[96:99]
	v_mfma_f32_16x16x32_bf16 v[84:87], v[168:171], v[210:213], v[84:87]
	v_mfma_f32_16x16x32_bf16 v[68:71], v[168:171], v[218:221], v[68:71]
	v_mfma_f32_16x16x32_bf16 v[80:83], v[180:183], v[210:213], v[80:83]
	v_mfma_f32_16x16x32_bf16 v[64:67], v[180:183], v[218:221], v[64:67]
	v_mfma_f32_16x16x32_bf16 v[116:119], v[172:175], v[192:195], v[116:119]
	v_mfma_f32_16x16x32_bf16 v[100:103], v[172:175], v[206:209], v[100:103]
	v_mfma_f32_16x16x32_bf16 v[112:115], v[184:187], v[192:195], v[112:115]
	v_mfma_f32_16x16x32_bf16 v[96:99], v[184:187], v[206:209], v[96:99]
	v_mfma_f32_16x16x32_bf16 v[84:87], v[172:175], v[214:217], v[84:87]
	v_mfma_f32_16x16x32_bf16 v[68:71], v[172:175], v[222:225], v[68:71]
	v_mfma_f32_16x16x32_bf16 v[80:83], v[184:187], v[214:217], v[80:83]
	v_mfma_f32_16x16x32_bf16 v[64:67], v[184:187], v[222:225], v[64:67]
	s_setprio 0
	s_barrier
; #define PG8_STAGE(bufoff, gbase, voff) do { _Pragma("unroll") for (int _i = 0; _i < 2; ++_i) \
;         __builtin_amdgcn_global_load_lds((const unsigned*)((const char*)(gbase) + (voff)[_i]), (PG8_LAS unsigned*)(lds + (bufoff) + ldsw + _i * 8192), 16, 0, 0); } while (0)
; #define PG8_LDA(dst, b, h) do { _Pragma("unroll") for (int m = 0; m < 4; ++m) _Pragma("unroll") for (int k = 0; k < 2; ++k) dst[m][k] = *(const PG8_LAS bf16x8*)(lds + PG8_SA(b, h) + aoff + m * 2048 + k * 1024); } while (0)
; #define PG8_LDB(dst, b, h) do { _Pragma("unroll") for (int n = 0; n < 2; ++n) _Pragma("unroll") for (int k = 0; k < 2; ++k) dst[n][k] = *(const PG8_LAS bf16x8*)(lds + PG8_SB(b, h) + boff + n * 2048 + k * 1024); } while (0)
; template <class Epi, class Sched, bool ALIGN_EPI = false, bool SP2 = false>
; __device__ __forceinline__ void gemm_phase(PG8_LAS unsigned char* lds, const Gemm g, const Sched& S, const Epi& E) {
;     ...
;         for (int t = 0; t < nt; t += 2) {
;             const bool last = (t == nt - 2);
;             const char* a1 = cA + (size_t)(t + 1) * kstep;
;             const char* a2 = last ? nA : cA + (size_t)(t + 2) * kstep; const char* b2 = last ? nB : cB + (size_t)(t + 2) * kstep;
;             const char* a3 = a2 + kstep; const char* b3 = b2 + kstep;
;             if (last && has_next) S.a_ready(nxt);
;             if constexpr (SP2) {
;             PG8_LDB(B0, 0, 0); PG8_LDB(B1, 0, 1); PG8_SCHED; PG8_LDA(At, 0, 0); PG8_STAGE(PG8_SA(1, 1), a1 + hstep, voffA);
;             PG8_WAIT_V(8); PG8_WAIT_L(0); PG8_BAR; PG8_MMA(0, 0, At, B0); PG8_MMA(0, 1, At, B1); PG8_BAR; PG8_SCHED;
;             PG8_LDA(At, 0, 1); PG8_STAGE(PG8_SB(0, 0), b2, voffB); PG8_STAGE(PG8_SB(0, 1), b2 + hstep, voffB); PG8_STAGE(PG8_SA(0, 0), a2, voffA);
;             PG8_WAIT_V(8); PG8_WAIT_L(0); PG8_BAR; PG8_MMA(1, 0, At, B0); PG8_MMA(1, 1, At, B1); PG8_BAR; PG8_SCHED;
;             PG8_LDB(B0, 1, 0); PG8_LDB(B1, 1, 1); PG8_SCHED; PG8_LDA(At, 1, 0); PG8_STAGE(PG8_SA(0, 1), a2 + hstep, voffA);
;             PG8_WAIT_V(8); PG8_WAIT_L(0); PG8_BAR; PG8_MMA(0, 0, At, B0); PG8_MMA(0, 1, At, B1); PG8_BAR; PG8_SCHED;
;             PG8_LDA(At, 1, 1); PG8_STAGE(PG8_SB(1, 0), b3, voffB); PG8_STAGE(PG8_SB(1, 1), b3 + hstep, voffB); PG8_STAGE(PG8_SA(1, 0), a3, voffA);
;             PG8_WAIT_V(8); PG8_WAIT_L(0); PG8_BAR; PG8_MMA(1, 0, At, B0); PG8_MMA(1, 1, At, B1); PG8_BAR; PG8_SCHED;
	s_add_i32 s56, s82, s34
	v_lshl_add_u64 v[200:201], v[200:201], 0, s[26:27]
	s_mov_b32 m0, s56
	ds_read_b128 v[188:191], v154 offset:49152
	ds_read_b128 v[192:195], v154 offset:50176
	ds_read_b128 v[196:199], v154 offset:51200
	ds_read_b128 v[206:209], v154 offset:52224
	ds_read_b128 v[210:213], v154 offset:53248
	ds_read_b128 v[214:217], v154 offset:54272
	ds_read_b128 v[218:221], v154 offset:55296
	ds_read_b128 v[222:225], v154 offset:56320
	global_load_lds_dwordx4 v[200:201], off
	s_add_i32 m0, s56, 0x2000
	s_add_u32 s54, s54, 0x40080
	v_lshl_add_u64 v[200:201], v[226:227], 0, s[26:27]
	s_addc_u32 s55, s55, 0
	s_add_i32 s56, s83, s34
	global_load_lds_dwordx4 v[200:201], off
	v_lshl_add_u64 v[200:201], s[54:55], 0, v[132:133]
	s_mov_b32 m0, s56
	s_nop 0
	global_load_lds_dwordx4 v[200:201], off
	v_lshl_add_u64 v[200:201], s[54:55], 0, v[128:129]
	s_add_i32 m0, s56, 0x2000
	s_nop 0
	global_load_lds_dwordx4 v[200:201], off
	s_waitcnt vmcnt(6)
	s_waitcnt lgkmcnt(0)
	s_barrier
	s_setprio 1
	s_waitcnt lgkmcnt(0)
	v_mfma_f32_16x16x32_bf16 v[60:63], v[146:149], v[188:191], v[60:63]
	v_mfma_f32_16x16x32_bf16 v[44:47], v[146:149], v[196:199], v[44:47]
	v_mfma_f32_16x16x32_bf16 v[56:59], v[160:163], v[188:191], v[56:59]
	v_mfma_f32_16x16x32_bf16 v[40:43], v[160:163], v[196:199], v[40:43]
	v_mfma_f32_16x16x32_bf16 v[28:31], v[146:149], v[210:213], v[28:31]
	v_mfma_f32_16x16x32_bf16 v[12:15], v[146:149], v[218:221], v[12:15]
	v_mfma_f32_16x16x32_bf16 v[24:27], v[160:163], v[210:213], v[24:27]
	v_mfma_f32_16x16x32_bf16 v[8:11], v[160:163], v[218:221], v[8:11]
	v_mfma_f32_16x16x32_bf16 v[60:63], v[156:159], v[192:195], v[60:63]
	v_mfma_f32_16x16x32_bf16 v[44:47], v[156:159], v[206:209], v[44:47]
	v_mfma_f32_16x16x32_bf16 v[56:59], v[164:167], v[192:195], v[56:59]
	v_mfma_f32_16x16x32_bf16 v[40:43], v[164:167], v[206:209], v[40:43]
	v_mfma_f32_16x16x32_bf16 v[28:31], v[156:159], v[214:217], v[28:31]
	v_mfma_f32_16x16x32_bf16 v[12:15], v[156:159], v[222:225], v[12:15]
	v_lshl_add_u64 v[200:201], v[228:229], 0, s[26:27]
	s_mov_b32 m0, s63
	s_nop 0
	global_load_lds_dwordx4 v[200:201], off
	v_mfma_f32_16x16x32_bf16 v[24:27], v[164:167], v[214:217], v[24:27]
	v_mfma_f32_16x16x32_bf16 v[8:11], v[164:167], v[222:225], v[8:11]
	s_setprio 0
	s_setprio 1
	v_mfma_f32_16x16x32_bf16 v[52:55], v[168:171], v[188:191], v[52:55]
	v_mfma_f32_16x16x32_bf16 v[36:39], v[168:171], v[196:199], v[36:39]
	v_mfma_f32_16x16x32_bf16 v[48:51], v[180:183], v[188:191], v[48:51]
	v_mfma_f32_16x16x32_bf16 v[32:35], v[180:183], v[196:199], v[32:35]
	v_mfma_f32_16x16x32_bf16 v[20:23], v[168:171], v[210:213], v[20:23]
	v_mfma_f32_16x16x32_bf16 v[4:7], v[168:171], v[218:221], v[4:7]
	v_mfma_f32_16x16x32_bf16 v[16:19], v[180:183], v[210:213], v[16:19]
	v_mfma_f32_16x16x32_bf16 v[0:3], v[180:183], v[218:221], v[0:3]
	v_mfma_f32_16x16x32_bf16 v[52:55], v[172:175], v[192:195], v[52:55]
	v_mfma_f32_16x16x32_bf16 v[36:39], v[172:175], v[206:209], v[36:39]
	v_mfma_f32_16x16x32_bf16 v[48:51], v[184:187], v[192:195], v[48:51]
	v_mfma_f32_16x16x32_bf16 v[32:35], v[184:187], v[206:209], v[32:35]
	v_mfma_f32_16x16x32_bf16 v[20:23], v[172:175], v[214:217], v[20:23]
	v_mfma_f32_16x16x32_bf16 v[4:7], v[172:175], v[222:225], v[4:7]
	v_lshl_add_u64 v[200:201], v[230:231], 0, s[26:27]
	s_mov_b32 m0, s64
	s_nop 0
	global_load_lds_dwordx4 v[200:201], off
	v_mfma_f32_16x16x32_bf16 v[16:19], v[184:187], v[214:217], v[16:19]
	v_mfma_f32_16x16x32_bf16 v[0:3], v[184:187], v[222:225], v[0:3]
	s_setprio 0
	s_barrier
	s_add_i32 s81, s81, 2
	s_add_u32 s52, s52, 0x100
	s_addc_u32 s53, s53, 0
	s_add_u32 s79, s79, 0x100
	s_addc_u32 s80, s80, 0
.LBB0_1681:
	ds_read_b128 v[146:149], v152
	ds_read_b128 v[156:159], v152 offset:1024
	ds_read_b128 v[160:163], v152 offset:2048
	ds_read_b128 v[164:167], v152 offset:3072
	ds_read_b128 v[168:171], v153
	ds_read_b128 v[172:175], v153 offset:1024
	ds_read_b128 v[180:183], v153 offset:2048
	ds_read_b128 v[184:187], v153 offset:3072
	s_add_u32 s54, s52, 0xfffc0080
	s_addc_u32 s55, s53, -1
	s_cmp_eq_u32 s81, 12
	s_cselect_b32 s57, s47, s55
	s_cselect_b32 s56, s77, s54
	s_cselect_b32 s55, s45, s80
	s_cselect_b32 s54, s78, s79
	v_lshl_add_u64 v[200:201], s[52:53], 0, v[136:137]
	s_add_i32 m0, s58, 0xc000
	ds_read_b128 v[188:191], v154
	ds_read_b128 v[192:195], v154 offset:1024
	ds_read_b128 v[196:199], v154 offset:2048
	ds_read_b128 v[206:209], v154 offset:3072
	ds_read_b128 v[210:213], v154 offset:4096
	ds_read_b128 v[214:217], v154 offset:5120
	ds_read_b128 v[218:221], v154 offset:6144
	ds_read_b128 v[222:225], v154 offset:7168
	global_load_lds_dwordx4 v[200:201], off
	v_lshl_add_u64 v[200:201], s[52:53], 0, v[138:139]
	s_add_i32 m0, s58, 0xe000
	s_nop 0
	global_load_lds_dwordx4 v[200:201], off
	s_waitcnt vmcnt(8)
	s_waitcnt lgkmcnt(0)
	s_barrier
; #define PG8_STAGE(bufoff, gbase, voff) do { _Pragma("unroll") for (int _i = 0; _i < 2; ++_i) \
;         __builtin_amdgcn_global_load_lds((const unsigned*)((const char*)(gbase) + (voff)[_i]), (PG8_LAS unsigned*)(lds + (bufoff) + ldsw + _i * 8192), 16, 0, 0); } while (0)
; #define PG8_LDA(dst, b, h) do { _Pragma("unroll") for (int m = 0; m < 4; ++m) _Pragma("unroll") for (int k = 0; k < 2; ++k) dst[m][k] = *(const PG8_LAS bf16x8*)(lds + PG8_SA(b, h) + aoff + m * 2048 + k * 1024); } while (0)
; #define PG8_LDB(dst, b, h) do { _Pragma("unroll") for (int n = 0; n < 2; ++n) _Pragma("unroll") for (int k = 0; k < 2; ++k) dst[n][k] = *(const PG8_LAS bf16x8*)(lds + PG8_SB(b, h) + boff + n * 2048 + k * 1024); } while (0)
; #define PG8_MMA(ai, bj, At, Bt) do { __builtin_amdgcn_s_setprio(1); _Pragma("unroll") for (int m = 0; m < 4; ++m) _Pragma("unroll") for (int n = 0; n < 2; ++n) _Pragma("unroll") for (int k = 0; k < 2; ++k) \
;         acc[ai][bj][m][n] = __builtin_amdgcn_mfma_f32_16x16x32_bf16(Bt[n][k], At[m][k], acc[ai][bj][m][n], 0, 0, 0); __builtin_amdgcn_s_setprio(0); } while (0)
; #define PG8_WAIT_V(n) asm volatile("s_waitcnt vmcnt(" #n ")" ::: "memory")
; #define PG8_WAIT_L(n) asm volatile("s_waitcnt lgkmcnt(" #n ")" ::: "memory")
; #define PG8_BAR __builtin_amdgcn_s_barrier()
; #define PG8_SCHED __builtin_amdgcn_sched_barrier(0)
; template <class Epi, class Sched, bool ALIGN_EPI = false, bool SP2 = false>
; __device__ __forceinline__ void gemm_phase(PG8_LAS unsigned char* lds, const Gemm g, const Sched& S, const Epi& E) {
;     ...
;             PG8_LDB(B0, 0, 0); PG8_LDB(B1, 0, 1); PG8_SCHED; PG8_LDA(At, 0, 0); PG8_STAGE(PG8_SA(1, 1), a1 + hstep, voffA);
;             PG8_WAIT_V(8); PG8_WAIT_L(0); PG8_BAR; PG8_MMA(0, 0, At, B0); PG8_MMA(0, 1, At, B1); PG8_BAR; PG8_SCHED;
;             PG8_LDA(At, 0, 1); PG8_STAGE(PG8_SB(0, 0), b2, voffB); PG8_STAGE(PG8_SB(0, 1), b2 + hstep, voffB); PG8_STAGE(PG8_SA(0, 0), a2, voffA);
;             PG8_WAIT_V(8); PG8_WAIT_L(0); PG8_BAR; PG8_MMA(1, 0, At, B0); PG8_MMA(1, 1, At, B1); PG8_BAR; PG8_SCHED;
	s_setprio 1
	s_waitcnt lgkmcnt(0)
	v_mfma_f32_16x16x32_bf16 v[124:127], v[146:149], v[188:191], v[124:127]
	v_mfma_f32_16x16x32_bf16 v[108:111], v[146:149], v[196:199], v[108:111]
	v_mfma_f32_16x16x32_bf16 v[120:123], v[160:163], v[188:191], v[120:123]
	v_mfma_f32_16x16x32_bf16 v[104:107], v[160:163], v[196:199], v[104:107]
	v_mfma_f32_16x16x32_bf16 v[92:95], v[146:149], v[210:213], v[92:95]
	v_mfma_f32_16x16x32_bf16 v[76:79], v[146:149], v[218:221], v[76:79]
	v_mfma_f32_16x16x32_bf16 v[88:91], v[160:163], v[210:213], v[88:91]
	v_mfma_f32_16x16x32_bf16 v[72:75], v[160:163], v[218:221], v[72:75]
	v_mfma_f32_16x16x32_bf16 v[124:127], v[156:159], v[192:195], v[124:127]
	v_mfma_f32_16x16x32_bf16 v[108:111], v[156:159], v[206:209], v[108:111]
	v_mfma_f32_16x16x32_bf16 v[120:123], v[164:167], v[192:195], v[120:123]
	v_mfma_f32_16x16x32_bf16 v[104:107], v[164:167], v[206:209], v[104:107]
	v_mfma_f32_16x16x32_bf16 v[92:95], v[156:159], v[214:217], v[92:95]
	v_mfma_f32_16x16x32_bf16 v[76:79], v[156:159], v[222:225], v[76:79]
	v_mfma_f32_16x16x32_bf16 v[88:91], v[164:167], v[214:217], v[88:91]
	v_mfma_f32_16x16x32_bf16 v[72:75], v[164:167], v[222:225], v[72:75]
	s_setprio 0
	s_setprio 1
	v_mfma_f32_16x16x32_bf16 v[116:119], v[168:171], v[188:191], v[116:119]
	v_mfma_f32_16x16x32_bf16 v[100:103], v[168:171], v[196:199], v[100:103]
	v_mfma_f32_16x16x32_bf16 v[112:115], v[180:183], v[188:191], v[112:115]
	v_mfma_f32_16x16x32_bf16 v[96:99], v[180:183], v[196:199], v[96:99]
	v_mfma_f32_16x16x32_bf16 v[84:87], v[168:171], v[210:213], v[84:87]
	v_mfma_f32_16x16x32_bf16 v[68:71], v[168:171], v[218:221], v[68:71]
	v_mfma_f32_16x16x32_bf16 v[80:83], v[180:183], v[210:213], v[80:83]
	v_mfma_f32_16x16x32_bf16 v[64:67], v[180:183], v[218:221], v[64:67]
	v_mfma_f32_16x16x32_bf16 v[116:119], v[172:175], v[192:195], v[116:119]
	v_mfma_f32_16x16x32_bf16 v[100:103], v[172:175], v[206:209], v[100:103]
	v_mfma_f32_16x16x32_bf16 v[112:115], v[184:187], v[192:195], v[112:115]
	v_mfma_f32_16x16x32_bf16 v[96:99], v[184:187], v[206:209], v[96:99]
	v_mfma_f32_16x16x32_bf16 v[84:87], v[172:175], v[214:217], v[84:87]
	v_mfma_f32_16x16x32_bf16 v[68:71], v[172:175], v[222:225], v[68:71]
	v_mfma_f32_16x16x32_bf16 v[80:83], v[184:187], v[214:217], v[80:83]
	v_mfma_f32_16x16x32_bf16 v[64:67], v[184:187], v[222:225], v[64:67]
	s_setprio 0
	s_barrier
	s_add_i32 s82, s65, s34
	v_lshl_add_u64 v[200:201], s[54:55], 0, v[132:133]
	s_mov_b32 m0, s82
	ds_read_b128 v[188:191], v154 offset:16384
	ds_read_b128 v[192:195], v154 offset:17408
	ds_read_b128 v[196:199], v154 offset:18432
	ds_read_b128 v[206:209], v154 offset:19456
	ds_read_b128 v[210:213], v154 offset:20480
	ds_read_b128 v[214:217], v154 offset:21504
	ds_read_b128 v[218:221], v154 offset:22528
	ds_read_b128 v[222:225], v154 offset:23552
	global_load_lds_dwordx4 v[200:201], off
	s_add_i32 m0, s82, 0x2000
	s_add_u32 s82, s54, 0x40000
	v_lshl_add_u64 v[226:227], s[54:55], 0, v[128:129]
	s_addc_u32 s83, s55, 0
	s_add_i32 s84, s66, s34
	global_load_lds_dwordx4 v[226:227], off
	v_lshl_add_u64 v[228:229], s[82:83], 0, v[132:133]
	s_mov_b32 m0, s84
	global_load_lds_dwordx4 v[228:229], off
	v_lshl_add_u64 v[228:229], s[82:83], 0, v[128:129]
	s_add_i32 m0, s84, 0x2000
	s_nop 0
	global_load_lds_dwordx4 v[228:229], off
	s_waitcnt vmcnt(6)
	s_waitcnt lgkmcnt(0)
	s_barrier
	s_setprio 1
	s_waitcnt lgkmcnt(0)
	v_mfma_f32_16x16x32_bf16 v[60:63], v[146:149], v[188:191], v[60:63]
	v_mfma_f32_16x16x32_bf16 v[44:47], v[146:149], v[196:199], v[44:47]
	v_mfma_f32_16x16x32_bf16 v[56:59], v[160:163], v[188:191], v[56:59]
	v_mfma_f32_16x16x32_bf16 v[40:43], v[160:163], v[196:199], v[40:43]
	v_mfma_f32_16x16x32_bf16 v[28:31], v[146:149], v[210:213], v[28:31]
	v_mfma_f32_16x16x32_bf16 v[12:15], v[146:149], v[218:221], v[12:15]
	v_mfma_f32_16x16x32_bf16 v[24:27], v[160:163], v[210:213], v[24:27]
	v_mfma_f32_16x16x32_bf16 v[8:11], v[160:163], v[218:221], v[8:11]
	v_mfma_f32_16x16x32_bf16 v[60:63], v[156:159], v[192:195], v[60:63]
	v_mfma_f32_16x16x32_bf16 v[44:47], v[156:159], v[206:209], v[44:47]
	v_mfma_f32_16x16x32_bf16 v[56:59], v[164:167], v[192:195], v[56:59]
	v_mfma_f32_16x16x32_bf16 v[40:43], v[164:167], v[206:209], v[40:43]
	v_mfma_f32_16x16x32_bf16 v[28:31], v[156:159], v[214:217], v[28:31]
	v_mfma_f32_16x16x32_bf16 v[12:15], v[156:159], v[222:225], v[12:15]
	v_lshl_add_u64 v[228:229], s[56:57], 0, v[134:135]
	s_mov_b32 m0, s58
	s_nop 0
	global_load_lds_dwordx4 v[228:229], off
	v_mfma_f32_16x16x32_bf16 v[24:27], v[164:167], v[214:217], v[24:27]
	v_mfma_f32_16x16x32_bf16 v[8:11], v[164:167], v[222:225], v[8:11]
	s_setprio 0
	s_setprio 1
	v_mfma_f32_16x16x32_bf16 v[52:55], v[168:171], v[188:191], v[52:55]
	v_mfma_f32_16x16x32_bf16 v[36:39], v[168:171], v[196:199], v[36:39]
	v_mfma_f32_16x16x32_bf16 v[48:51], v[180:183], v[188:191], v[48:51]
	v_mfma_f32_16x16x32_bf16 v[32:35], v[180:183], v[196:199], v[32:35]
	v_mfma_f32_16x16x32_bf16 v[20:23], v[168:171], v[210:213], v[20:23]
	v_mfma_f32_16x16x32_bf16 v[4:7], v[168:171], v[218:221], v[4:7]
	v_mfma_f32_16x16x32_bf16 v[16:19], v[180:183], v[210:213], v[16:19]
	v_mfma_f32_16x16x32_bf16 v[0:3], v[180:183], v[218:221], v[0:3]
	v_mfma_f32_16x16x32_bf16 v[52:55], v[172:175], v[192:195], v[52:55]
	v_mfma_f32_16x16x32_bf16 v[36:39], v[172:175], v[206:209], v[36:39]
	v_mfma_f32_16x16x32_bf16 v[48:51], v[184:187], v[192:195], v[48:51]
	v_mfma_f32_16x16x32_bf16 v[32:35], v[184:187], v[206:209], v[32:35]
	v_mfma_f32_16x16x32_bf16 v[20:23], v[172:175], v[214:217], v[20:23]
	v_mfma_f32_16x16x32_bf16 v[4:7], v[172:175], v[222:225], v[4:7]
	v_lshl_add_u64 v[230:231], s[56:57], 0, v[130:131]
	s_mov_b32 m0, s59
	s_nop 0
	global_load_lds_dwordx4 v[230:231], off
	v_mfma_f32_16x16x32_bf16 v[16:19], v[184:187], v[214:217], v[16:19]
	v_mfma_f32_16x16x32_bf16 v[0:3], v[184:187], v[222:225], v[0:3]
	s_setprio 0
	s_barrier
; #define PG8_STAGE(bufoff, gbase, voff) do { _Pragma("unroll") for (int _i = 0; _i < 2; ++_i) \
;         __builtin_amdgcn_global_load_lds((const unsigned*)((const char*)(gbase) + (voff)[_i]), (PG8_LAS unsigned*)(lds + (bufoff) + ldsw + _i * 8192), 16, 0, 0); } while (0)
; #define PG8_LDA(dst, b, h) do { _Pragma("unroll") for (int m = 0; m < 4; ++m) _Pragma("unroll") for (int k = 0; k < 2; ++k) dst[m][k] = *(const PG8_LAS bf16x8*)(lds + PG8_SA(b, h) + aoff + m * 2048 + k * 1024); } while (0)
; #define PG8_LDB(dst, b, h) do { _Pragma("unroll") for (int n = 0; n < 2; ++n) _Pragma("unroll") for (int k = 0; k < 2; ++k) dst[n][k] = *(const PG8_LAS bf16x8*)(lds + PG8_SB(b, h) + boff + n * 2048 + k * 1024); } while (0)
; #define PG8_MMA(ai, bj, At, Bt) do { __builtin_amdgcn_s_setprio(1); _Pragma("unroll") for (int m = 0; m < 4; ++m) _Pragma("unroll") for (int n = 0; n < 2; ++n) _Pragma("unroll") for (int k = 0; k < 2; ++k) \
;         acc[ai][bj][m][n] = __builtin_amdgcn_mfma_f32_16x16x32_bf16(Bt[n][k], At[m][k], acc[ai][bj][m][n], 0, 0, 0); __builtin_amdgcn_s_setprio(0); } while (0)
; #define PG8_WAIT_V(n) asm volatile("s_waitcnt vmcnt(" #n ")" ::: "memory")
; #define PG8_WAIT_L(n) asm volatile("s_waitcnt lgkmcnt(" #n ")" ::: "memory")
; #define PG8_BAR __builtin_amdgcn_s_barrier()
; #define PG8_SCHED __builtin_amdgcn_sched_barrier(0)
; template <class Epi, class Sched, bool ALIGN_EPI = false, bool SP2 = false>
; __device__ __forceinline__ void gemm_phase(PG8_LAS unsigned char* lds, const Gemm g, const Sched& S, const Epi& E) {
;     ...
;             PG8_LDB(B0, 1, 0); PG8_LDB(B1, 1, 1); PG8_SCHED; PG8_LDA(At, 1, 0); PG8_STAGE(PG8_SA(0, 1), a2 + hstep, voffA);
;             PG8_WAIT_V(8); PG8_WAIT_L(0); PG8_BAR; PG8_MMA(0, 0, At, B0); PG8_MMA(0, 1, At, B1); PG8_BAR; PG8_SCHED;
	s_add_i32 s82, 0, 0x18000
	s_add_i32 s83, 0, 0x1c000
	v_add_u32_e32 v164, s82, v150
	v_add_u32_e32 v179, s83, v150
	ds_read_b128 v[146:149], v164
	ds_read_b128 v[156:159], v164 offset:1024
	ds_read_b128 v[160:163], v164 offset:2048
	ds_read_b128 v[164:167], v164 offset:3072
	ds_read_b128 v[168:171], v179
	ds_read_b128 v[172:175], v179 offset:1024
	ds_read_b128 v[180:183], v179 offset:2048
	ds_read_b128 v[184:187], v179 offset:3072
	s_add_u32 s56, s56, 0x40000
	s_addc_u32 s57, s57, 0
	s_mov_b32 m0, s60
	v_lshl_add_u64 v[232:233], s[56:57], 0, v[134:135]
	ds_read_b128 v[188:191], v154 offset:32768
	ds_read_b128 v[192:195], v154 offset:33792
	ds_read_b128 v[196:199], v154 offset:34816
	ds_read_b128 v[206:209], v154 offset:35840
	ds_read_b128 v[210:213], v154 offset:36864
	ds_read_b128 v[214:217], v154 offset:37888
	ds_read_b128 v[218:221], v154 offset:38912
	ds_read_b128 v[222:225], v154 offset:39936
	global_load_lds_dwordx4 v[232:233], off
	v_lshl_add_u64 v[232:233], s[56:57], 0, v[130:131]
	s_mov_b32 m0, s61
	s_nop 0
	global_load_lds_dwordx4 v[232:233], off
	s_waitcnt vmcnt(8)
	s_waitcnt lgkmcnt(0)
	s_barrier
	s_setprio 1
	s_waitcnt lgkmcnt(0)
	v_mfma_f32_16x16x32_bf16 v[124:127], v[146:149], v[188:191], v[124:127]
	v_mfma_f32_16x16x32_bf16 v[108:111], v[146:149], v[196:199], v[108:111]
	v_mfma_f32_16x16x32_bf16 v[120:123], v[160:163], v[188:191], v[120:123]
	v_mfma_f32_16x16x32_bf16 v[104:107], v[160:163], v[196:199], v[104:107]
	v_mfma_f32_16x16x32_bf16 v[92:95], v[146:149], v[210:213], v[92:95]
	v_mfma_f32_16x16x32_bf16 v[76:79], v[146:149], v[218:221], v[76:79]
	v_mfma_f32_16x16x32_bf16 v[88:91], v[160:163], v[210:213], v[88:91]
	v_mfma_f32_16x16x32_bf16 v[72:75], v[160:163], v[218:221], v[72:75]
	v_mfma_f32_16x16x32_bf16 v[124:127], v[156:159], v[192:195], v[124:127]
	v_mfma_f32_16x16x32_bf16 v[108:111], v[156:159], v[206:209], v[108:111]
	v_mfma_f32_16x16x32_bf16 v[120:123], v[164:167], v[192:195], v[120:123]
	v_mfma_f32_16x16x32_bf16 v[104:107], v[164:167], v[206:209], v[104:107]
	v_mfma_f32_16x16x32_bf16 v[92:95], v[156:159], v[214:217], v[92:95]
	v_mfma_f32_16x16x32_bf16 v[76:79], v[156:159], v[222:225], v[76:79]
	v_mfma_f32_16x16x32_bf16 v[88:91], v[164:167], v[214:217], v[88:91]
	v_mfma_f32_16x16x32_bf16 v[72:75], v[164:167], v[222:225], v[72:75]
	s_setprio 0
	s_setprio 1
	v_mfma_f32_16x16x32_bf16 v[116:119], v[168:171], v[188:191], v[116:119]
	v_mfma_f32_16x16x32_bf16 v[100:103], v[168:171], v[196:199], v[100:103]
	v_mfma_f32_16x16x32_bf16 v[112:115], v[180:183], v[188:191], v[112:115]
	v_mfma_f32_16x16x32_bf16 v[96:99], v[180:183], v[196:199], v[96:99]
	v_mfma_f32_16x16x32_bf16 v[84:87], v[168:171], v[210:213], v[84:87]
	v_mfma_f32_16x16x32_bf16 v[68:71], v[168:171], v[218:221], v[68:71]
	v_mfma_f32_16x16x32_bf16 v[80:83], v[180:183], v[210:213], v[80:83]
	v_mfma_f32_16x16x32_bf16 v[64:67], v[180:183], v[218:221], v[64:67]
	v_mfma_f32_16x16x32_bf16 v[116:119], v[172:175], v[192:195], v[116:119]
	v_mfma_f32_16x16x32_bf16 v[100:103], v[172:175], v[206:209], v[100:103]
	v_mfma_f32_16x16x32_bf16 v[112:115], v[184:187], v[192:195], v[112:115]
	v_mfma_f32_16x16x32_bf16 v[96:99], v[184:187], v[206:209], v[96:99]
	v_mfma_f32_16x16x32_bf16 v[84:87], v[172:175], v[214:217], v[84:87]
	v_mfma_f32_16x16x32_bf16 v[68:71], v[172:175], v[222:225], v[68:71]
	v_mfma_f32_16x16x32_bf16 v[80:83], v[184:187], v[214:217], v[80:83]
	v_mfma_f32_16x16x32_bf16 v[64:67], v[184:187], v[222:225], v[64:67]
	s_setprio 0
	s_barrier
; #define PG8_STAGE(bufoff, gbase, voff) do { _Pragma("unroll") for (int _i = 0; _i < 2; ++_i) \
;         __builtin_amdgcn_global_load_lds((const unsigned*)((const char*)(gbase) + (voff)[_i]), (PG8_LAS unsigned*)(lds + (bufoff) + ldsw + _i * 8192), 16, 0, 0); } while (0)
; #define PG8_LDA(dst, b, h) do { _Pragma("unroll") for (int m = 0; m < 4; ++m) _Pragma("unroll") for (int k = 0; k < 2; ++k) dst[m][k] = *(const PG8_LAS bf16x8*)(lds + PG8_SA(b, h) + aoff + m * 2048 + k * 1024); } while (0)
; #define PG8_MMA(ai, bj, At, Bt) do { __builtin_amdgcn_s_setprio(1); _Pragma("unroll") for (int m = 0; m < 4; ++m) _Pragma("unroll") for (int n = 0; n < 2; ++n) _Pragma("unroll") for (int k = 0; k < 2; ++k) \
;         acc[ai][bj][m][n] = __builtin_amdgcn_mfma_f32_16x16x32_bf16(Bt[n][k], At[m][k], acc[ai][bj][m][n], 0, 0, 0); __builtin_amdgcn_s_setprio(0); } while (0)
; #define PG8_WAIT_V(n) asm volatile("s_waitcnt vmcnt(" #n ")" ::: "memory")
; #define PG8_WAIT_L(n) asm volatile("s_waitcnt lgkmcnt(" #n ")" ::: "memory")
; #define PG8_BAR __builtin_amdgcn_s_barrier()
; #define PG8_SCHED __builtin_amdgcn_sched_barrier(0)
; template <class Epi, class Sched, bool ALIGN_EPI = false, bool SP2 = false>
; __device__ __forceinline__ void gemm_phase(PG8_LAS unsigned char* lds, const Gemm g, const Sched& S, const Epi& E) {
;     ...
;         for (int t = 0; t < nt; t += 2) {
;             const bool last = (t == nt - 2);
;     ...
;             PG8_LDA(At, 1, 1); PG8_STAGE(PG8_SB(1, 0), b3, voffB); PG8_STAGE(PG8_SB(1, 1), b3 + hstep, voffB); PG8_STAGE(PG8_SA(1, 0), a3, voffA);
;             PG8_WAIT_V(8); PG8_WAIT_L(0); PG8_BAR; PG8_MMA(1, 0, At, B0); PG8_MMA(1, 1, At, B1); PG8_BAR; PG8_SCHED;
	s_add_i32 s56, s82, s34
	v_lshl_add_u64 v[200:201], v[200:201], 0, s[26:27]
	s_mov_b32 m0, s56
	ds_read_b128 v[188:191], v154 offset:49152
	ds_read_b128 v[192:195], v154 offset:50176
	ds_read_b128 v[196:199], v154 offset:51200
	ds_read_b128 v[206:209], v154 offset:52224
	ds_read_b128 v[210:213], v154 offset:53248
	ds_read_b128 v[214:217], v154 offset:54272
	ds_read_b128 v[218:221], v154 offset:55296
	ds_read_b128 v[222:225], v154 offset:56320
	global_load_lds_dwordx4 v[200:201], off
	s_add_i32 m0, s56, 0x2000
	s_add_u32 s54, s54, 0x40080
	v_lshl_add_u64 v[200:201], v[226:227], 0, s[26:27]
	s_addc_u32 s55, s55, 0
	s_add_i32 s56, s83, s34
	global_load_lds_dwordx4 v[200:201], off
	v_lshl_add_u64 v[200:201], s[54:55], 0, v[132:133]
	s_mov_b32 m0, s56
	s_nop 0
	global_load_lds_dwordx4 v[200:201], off
	v_lshl_add_u64 v[200:201], s[54:55], 0, v[128:129]
	s_add_i32 m0, s56, 0x2000
	s_nop 0
	global_load_lds_dwordx4 v[200:201], off
	s_waitcnt vmcnt(6)
	s_waitcnt lgkmcnt(0)
	s_barrier
	s_setprio 1
	s_waitcnt lgkmcnt(0)
	v_mfma_f32_16x16x32_bf16 v[60:63], v[146:149], v[188:191], v[60:63]
	v_mfma_f32_16x16x32_bf16 v[44:47], v[146:149], v[196:199], v[44:47]
	v_mfma_f32_16x16x32_bf16 v[56:59], v[160:163], v[188:191], v[56:59]
	v_mfma_f32_16x16x32_bf16 v[40:43], v[160:163], v[196:199], v[40:43]
	v_mfma_f32_16x16x32_bf16 v[28:31], v[146:149], v[210:213], v[28:31]
	v_mfma_f32_16x16x32_bf16 v[12:15], v[146:149], v[218:221], v[12:15]
	v_mfma_f32_16x16x32_bf16 v[24:27], v[160:163], v[210:213], v[24:27]
	v_mfma_f32_16x16x32_bf16 v[8:11], v[160:163], v[218:221], v[8:11]
	v_mfma_f32_16x16x32_bf16 v[60:63], v[156:159], v[192:195], v[60:63]
	v_mfma_f32_16x16x32_bf16 v[44:47], v[156:159], v[206:209], v[44:47]
	v_mfma_f32_16x16x32_bf16 v[56:59], v[164:167], v[192:195], v[56:59]
	v_mfma_f32_16x16x32_bf16 v[40:43], v[164:167], v[206:209], v[40:43]
	v_mfma_f32_16x16x32_bf16 v[28:31], v[156:159], v[214:217], v[28:31]
	v_mfma_f32_16x16x32_bf16 v[12:15], v[156:159], v[222:225], v[12:15]
	v_lshl_add_u64 v[200:201], v[228:229], 0, s[26:27]
	s_mov_b32 m0, s63
	s_nop 0
	global_load_lds_dwordx4 v[200:201], off
	v_mfma_f32_16x16x32_bf16 v[24:27], v[164:167], v[214:217], v[24:27]
	v_mfma_f32_16x16x32_bf16 v[8:11], v[164:167], v[222:225], v[8:11]
	s_setprio 0
	s_setprio 1
	v_mfma_f32_16x16x32_bf16 v[52:55], v[168:171], v[188:191], v[52:55]
	v_mfma_f32_16x16x32_bf16 v[36:39], v[168:171], v[196:199], v[36:39]
	v_mfma_f32_16x16x32_bf16 v[48:51], v[180:183], v[188:191], v[48:51]
	v_mfma_f32_16x16x32_bf16 v[32:35], v[180:183], v[196:199], v[32:35]
	v_mfma_f32_16x16x32_bf16 v[20:23], v[168:171], v[210:213], v[20:23]
	v_mfma_f32_16x16x32_bf16 v[4:7], v[168:171], v[218:221], v[4:7]
	v_mfma_f32_16x16x32_bf16 v[16:19], v[180:183], v[210:213], v[16:19]
	v_mfma_f32_16x16x32_bf16 v[0:3], v[180:183], v[218:221], v[0:3]
	v_mfma_f32_16x16x32_bf16 v[52:55], v[172:175], v[192:195], v[52:55]
	v_mfma_f32_16x16x32_bf16 v[36:39], v[172:175], v[206:209], v[36:39]
	v_mfma_f32_16x16x32_bf16 v[48:51], v[184:187], v[192:195], v[48:51]
	v_mfma_f32_16x16x32_bf16 v[32:35], v[184:187], v[206:209], v[32:35]
	v_mfma_f32_16x16x32_bf16 v[20:23], v[172:175], v[214:217], v[20:23]
	v_mfma_f32_16x16x32_bf16 v[4:7], v[172:175], v[222:225], v[4:7]
	v_lshl_add_u64 v[200:201], v[230:231], 0, s[26:27]
	s_mov_b32 m0, s64
	s_nop 0
	global_load_lds_dwordx4 v[200:201], off
	v_mfma_f32_16x16x32_bf16 v[16:19], v[184:187], v[214:217], v[16:19]
	v_mfma_f32_16x16x32_bf16 v[0:3], v[184:187], v[222:225], v[0:3]
	s_setprio 0
	s_barrier
	s_add_i32 s81, s81, 2
	s_add_u32 s52, s52, 0x100
	s_addc_u32 s53, s53, 0
	s_add_u32 s79, s79, 0x100
	s_addc_u32 s80, s80, 0
	s_cmp_gt_u32 s81, 13
	s_cbranch_scc0 .LBB0_1681
	s_and_b64 vcc, exec, s[28:29]
	s_cbranch_vccz .LBB0_1684
	s_barrier

; #define PG8_STAGE(bufoff, gbase, voff) do { _Pragma("unroll") for (int _i = 0; _i < 2; ++_i) \
;         __builtin_amdgcn_global_load_lds((const unsigned*)((const char*)(gbase) + (voff)[_i]), (PG8_LAS unsigned*)(lds + (bufoff) + ldsw + _i * 8192), 16, 0, 0); } while (0)
; #define PG8_LDA(dst, b, h) do { _Pragma("unroll") for (int m = 0; m < 4; ++m) _Pragma("unroll") for (int k = 0; k < 2; ++k) dst[m][k] = *(const PG8_LAS bf16x8*)(lds + PG8_SA(b, h) + aoff + m * 2048 + k * 1024); } while (0)
; #define PG8_LDB(dst, b, h) do { _Pragma("unroll") for (int n = 0; n < 2; ++n) _Pragma("unroll") for (int k = 0; k < 2; ++k) dst[n][k] = *(const PG8_LAS bf16x8*)(lds + PG8_SB(b, h) + boff + n * 2048 + k * 1024); } while (0)
; #define PG8_MMA(ai, bj, At, Bt) do { __builtin_amdgcn_s_setprio(1); _Pragma("unroll") for (int m = 0; m < 4; ++m) _Pragma("unroll") for (int n = 0; n < 2; ++n) _Pragma("unroll") for (int k = 0; k < 2; ++k) \
;         acc[ai][bj][m][n] = __builtin_amdgcn_mfma_f32_16x16x32_bf16(Bt[n][k], At[m][k], acc[ai][bj][m][n], 0, 0, 0); __builtin_amdgcn_s_setprio(0); } while (0)
; #define PG8_BAR __builtin_amdgcn_s_barrier()
; template <class Epi, class Sched, bool ALIGN_EPI = false, bool SP2 = false>
; __device__ __forceinline__ void gemm_phase(PG8_LAS unsigned char* lds, const Gemm g, const Sched& S, const Epi& E) {
;     ...
;         const bool has_next = S.next(ui + 1, nxt);
;         const char* nA = has_next ? (const char*)g.A + (size_t)nxt.pm * tstep : cA; const char* nB = has_next ? (const char*)g.Bt + (size_t)nxt.pn * tstep : cB;
;         for (int t = 0; t < nt; t += 2) {
;             const bool last = (t == nt - 2);
;             const char* a1 = cA + (size_t)(t + 1) * kstep;
;             const char* a2 = last ? nA : cA + (size_t)(t + 2) * kstep; const char* b2 = last ? nB : cB + (size_t)(t + 2) * kstep;
;             const char* a3 = a2 + kstep; const char* b3 = b2 + kstep;
;             if (last && has_next) S.a_ready(nxt);
;             if constexpr (SP2) {
;             PG8_LDB(B0, 0, 0); PG8_LDB(B1, 0, 1); PG8_SCHED; PG8_LDA(At, 0, 0); PG8_STAGE(PG8_SA(1, 1), a1 + hstep, voffA);
;             PG8_WAIT_V(8); PG8_WAIT_L(0); PG8_BAR; PG8_MMA(0, 0, At, B0); PG8_MMA(0, 1, At, B1); PG8_BAR; PG8_SCHED;
;             PG8_LDA(At, 0, 1); PG8_STAGE(PG8_SB(0, 0), b2, voffB); PG8_STAGE(PG8_SB(0, 1), b2 + hstep, voffB); PG8_STAGE(PG8_SA(0, 0), a2, voffA);
.LBB0_1815:
	s_ashr_i32 s29, s28, 31
	s_lshl_b64 s[36:37], s[28:29], 18
	s_add_u32 s36, s92, s36
	s_addc_u32 s37, s93, s37
	s_and_b64 s[38:39], s[6:7], exec
	s_cselect_b32 s29, s37, s45
	s_cselect_b32 s41, s36, s44
	s_ashr_i32 s27, s26, 31
	s_lshl_b64 s[38:39], s[26:27], 18
	s_add_u32 s38, s3, s38
	s_addc_u32 s39, s14, s39
	s_and_b64 s[48:49], s[6:7], exec
	s_cselect_b32 s27, s39, s47
	s_cselect_b32 s58, s38, s46
	s_add_u32 s44, s44, 0x20080
	s_addc_u32 s45, s45, 0
	s_add_u32 s59, s46, 0x100
	s_addc_u32 s60, s47, 0
	s_mov_b32 s61, -2
	s_waitcnt lgkmcnt(0)
	ds_read_b128 v[144:147], v151
	ds_read_b128 v[156:159], v151 offset:1024
	ds_read_b128 v[160:163], v151 offset:2048
	ds_read_b128 v[164:167], v151 offset:3072
	ds_read_b128 v[168:171], v152
	ds_read_b128 v[172:175], v152 offset:1024
	ds_read_b128 v[176:179], v152 offset:2048
	ds_read_b128 v[180:183], v152 offset:3072
	s_add_u32 s46, s44, 0xfffe0080
	s_addc_u32 s47, s45, -1
	s_cmp_eq_u32 s61, 4
	s_cselect_b32 s49, s29, s47
	s_cselect_b32 s48, s41, s46
	s_cselect_b32 s47, s27, s60
	s_cselect_b32 s46, s58, s59
	v_lshl_add_u64 v[218:219], s[44:45], 0, v[136:137]
	s_add_i32 m0, s33, 0xc000
	ds_read_b128 v[184:187], v153
	ds_read_b128 v[188:191], v153 offset:1024
	ds_read_b128 v[192:195], v153 offset:2048
	ds_read_b128 v[196:199], v153 offset:3072
	ds_read_b128 v[200:203], v153 offset:4096
	ds_read_b128 v[206:209], v153 offset:5120
	ds_read_b128 v[210:213], v153 offset:6144
	ds_read_b128 v[214:217], v153 offset:7168
	global_load_lds_dwordx4 v[218:219], off
	v_lshl_add_u64 v[218:219], s[44:45], 0, v[138:139]
	s_add_i32 m0, s33, 0xe000
	s_nop 0
	global_load_lds_dwordx4 v[218:219], off
	s_waitcnt vmcnt(8)
	s_waitcnt lgkmcnt(0)
	s_barrier
	s_setprio 1
	s_waitcnt lgkmcnt(0)
	v_mfma_f32_16x16x32_bf16 v[124:127], v[144:147], v[184:187], 0
	v_mfma_f32_16x16x32_bf16 v[108:111], v[144:147], v[192:195], 0
	v_mfma_f32_16x16x32_bf16 v[120:123], v[160:163], v[184:187], 0
	v_mfma_f32_16x16x32_bf16 v[104:107], v[160:163], v[192:195], 0
	v_mfma_f32_16x16x32_bf16 v[92:95], v[144:147], v[200:203], 0
	v_mfma_f32_16x16x32_bf16 v[76:79], v[144:147], v[210:213], 0
	v_mfma_f32_16x16x32_bf16 v[88:91], v[160:163], v[200:203], 0
	v_mfma_f32_16x16x32_bf16 v[72:75], v[160:163], v[210:213], 0
	v_mfma_f32_16x16x32_bf16 v[124:127], v[156:159], v[188:191], v[124:127]
	v_mfma_f32_16x16x32_bf16 v[108:111], v[156:159], v[196:199], v[108:111]
	v_mfma_f32_16x16x32_bf16 v[120:123], v[164:167], v[188:191], v[120:123]
	v_mfma_f32_16x16x32_bf16 v[104:107], v[164:167], v[196:199], v[104:107]
	v_mfma_f32_16x16x32_bf16 v[92:95], v[156:159], v[206:209], v[92:95]
	v_mfma_f32_16x16x32_bf16 v[76:79], v[156:159], v[214:217], v[76:79]
	v_mfma_f32_16x16x32_bf16 v[88:91], v[164:167], v[206:209], v[88:91]
	v_mfma_f32_16x16x32_bf16 v[72:75], v[164:167], v[214:217], v[72:75]
	s_setprio 0
	s_setprio 1
	v_mfma_f32_16x16x32_bf16 v[116:119], v[168:171], v[184:187], 0
	v_mfma_f32_16x16x32_bf16 v[100:103], v[168:171], v[192:195], 0
	v_mfma_f32_16x16x32_bf16 v[112:115], v[176:179], v[184:187], 0
	v_mfma_f32_16x16x32_bf16 v[96:99], v[176:179], v[192:195], 0
	v_mfma_f32_16x16x32_bf16 v[84:87], v[168:171], v[200:203], 0
	v_mfma_f32_16x16x32_bf16 v[68:71], v[168:171], v[210:213], 0
	v_mfma_f32_16x16x32_bf16 v[80:83], v[176:179], v[200:203], 0
	v_mfma_f32_16x16x32_bf16 v[64:67], v[176:179], v[210:213], 0
	v_mfma_f32_16x16x32_bf16 v[116:119], v[172:175], v[188:191], v[116:119]
	v_mfma_f32_16x16x32_bf16 v[100:103], v[172:175], v[196:199], v[100:103]
	v_mfma_f32_16x16x32_bf16 v[112:115], v[180:183], v[188:191], v[112:115]
	v_mfma_f32_16x16x32_bf16 v[96:99], v[180:183], v[196:199], v[96:99]
	v_mfma_f32_16x16x32_bf16 v[84:87], v[172:175], v[206:209], v[84:87]
	v_mfma_f32_16x16x32_bf16 v[68:71], v[172:175], v[214:217], v[68:71]
	v_mfma_f32_16x16x32_bf16 v[80:83], v[180:183], v[206:209], v[80:83]
	v_mfma_f32_16x16x32_bf16 v[64:67], v[180:183], v[214:217], v[64:67]
	s_setprio 0
	s_barrier
	s_add_i32 s62, s54, s15
	v_lshl_add_u64 v[218:219], s[46:47], 0, v[130:131]
	s_mov_b32 m0, s62
	ds_read_b128 v[184:187], v153 offset:16384
	ds_read_b128 v[188:191], v153 offset:17408
	ds_read_b128 v[192:195], v153 offset:18432
	ds_read_b128 v[196:199], v153 offset:19456
	ds_read_b128 v[200:203], v153 offset:20480
	ds_read_b128 v[206:209], v153 offset:21504
	ds_read_b128 v[210:213], v153 offset:22528
	ds_read_b128 v[214:217], v153 offset:23552
	global_load_lds_dwordx4 v[218:219], off
	s_add_i32 m0, s62, 0x2000
	s_add_u32 s62, s46, 0x20000
	v_lshl_add_u64 v[220:221], s[46:47], 0, v[134:135]
	s_addc_u32 s63, s47, 0
	s_add_i32 s64, s55, s15
	global_load_lds_dwordx4 v[220:221], off
	v_lshl_add_u64 v[222:223], s[62:63], 0, v[130:131]
	s_mov_b32 m0, s64
	global_load_lds_dwordx4 v[222:223], off
	v_lshl_add_u64 v[222:223], s[62:63], 0, v[134:135]
	s_add_i32 m0, s64, 0x2000
	s_nop 0
	global_load_lds_dwordx4 v[222:223], off
	s_waitcnt vmcnt(6)
	s_waitcnt lgkmcnt(0)
	s_barrier
; #define PG8_STAGE(bufoff, gbase, voff) do { _Pragma("unroll") for (int _i = 0; _i < 2; ++_i) \
;         __builtin_amdgcn_global_load_lds((const unsigned*)((const char*)(gbase) + (voff)[_i]), (PG8_LAS unsigned*)(lds + (bufoff) + ldsw + _i * 8192), 16, 0, 0); } while (0)
; #define PG8_LDA(dst, b, h) do { _Pragma("unroll") for (int m = 0; m < 4; ++m) _Pragma("unroll") for (int k = 0; k < 2; ++k) dst[m][k] = *(const PG8_LAS bf16x8*)(lds + PG8_SA(b, h) + aoff + m * 2048 + k * 1024); } while (0)
; #define PG8_LDB(dst, b, h) do { _Pragma("unroll") for (int n = 0; n < 2; ++n) _Pragma("unroll") for (int k = 0; k < 2; ++k) dst[n][k] = *(const PG8_LAS bf16x8*)(lds + PG8_SB(b, h) + boff + n * 2048 + k * 1024); } while (0)
; #define PG8_MMA(ai, bj, At, Bt) do { __builtin_amdgcn_s_setprio(1); _Pragma("unroll") for (int m = 0; m < 4; ++m) _Pragma("unroll") for (int n = 0; n < 2; ++n) _Pragma("unroll") for (int k = 0; k < 2; ++k) \
;         acc[ai][bj][m][n] = __builtin_amdgcn_mfma_f32_16x16x32_bf16(Bt[n][k], At[m][k], acc[ai][bj][m][n], 0, 0, 0); __builtin_amdgcn_s_setprio(0); } while (0)
; #define PG8_WAIT_V(n) asm volatile("s_waitcnt vmcnt(" #n ")" ::: "memory")
; #define PG8_WAIT_L(n) asm volatile("s_waitcnt lgkmcnt(" #n ")" ::: "memory")
; #define PG8_BAR __builtin_amdgcn_s_barrier()
; #define PG8_SCHED __builtin_amdgcn_sched_barrier(0)
; template <class Epi, class Sched, bool ALIGN_EPI = false, bool SP2 = false>
; __device__ __forceinline__ void gemm_phase(PG8_LAS unsigned char* lds, const Gemm g, const Sched& S, const Epi& E) {
;     ...
;             PG8_WAIT_V(8); PG8_WAIT_L(0); PG8_BAR; PG8_MMA(1, 0, At, B0); PG8_MMA(1, 1, At, B1); PG8_BAR; PG8_SCHED;
;             PG8_LDB(B0, 1, 0); PG8_LDB(B1, 1, 1); PG8_SCHED; PG8_LDA(At, 1, 0); PG8_STAGE(PG8_SA(0, 1), a2 + hstep, voffA);
;             PG8_WAIT_V(8); PG8_WAIT_L(0); PG8_BAR; PG8_MMA(0, 0, At, B0); PG8_MMA(0, 1, At, B1); PG8_BAR; PG8_SCHED;
	s_setprio 1
	s_waitcnt lgkmcnt(0)
	v_mfma_f32_16x16x32_bf16 v[60:63], v[144:147], v[184:187], 0
	v_mfma_f32_16x16x32_bf16 v[44:47], v[144:147], v[192:195], 0
	v_mfma_f32_16x16x32_bf16 v[56:59], v[160:163], v[184:187], 0
	v_mfma_f32_16x16x32_bf16 v[40:43], v[160:163], v[192:195], 0
	v_mfma_f32_16x16x32_bf16 v[28:31], v[144:147], v[200:203], 0
	v_mfma_f32_16x16x32_bf16 v[12:15], v[144:147], v[210:213], 0
	v_mfma_f32_16x16x32_bf16 v[24:27], v[160:163], v[200:203], 0
	v_mfma_f32_16x16x32_bf16 v[8:11], v[160:163], v[210:213], 0
	v_mfma_f32_16x16x32_bf16 v[60:63], v[156:159], v[188:191], v[60:63]
	v_mfma_f32_16x16x32_bf16 v[44:47], v[156:159], v[196:199], v[44:47]
	v_mfma_f32_16x16x32_bf16 v[56:59], v[164:167], v[188:191], v[56:59]
	v_mfma_f32_16x16x32_bf16 v[40:43], v[164:167], v[196:199], v[40:43]
	v_mfma_f32_16x16x32_bf16 v[28:31], v[156:159], v[206:209], v[28:31]
	v_mfma_f32_16x16x32_bf16 v[12:15], v[156:159], v[214:217], v[12:15]
	v_lshl_add_u64 v[222:223], s[48:49], 0, v[128:129]
	s_mov_b32 m0, s33
	s_nop 0
	global_load_lds_dwordx4 v[222:223], off
	v_mfma_f32_16x16x32_bf16 v[24:27], v[164:167], v[206:209], v[24:27]
	v_mfma_f32_16x16x32_bf16 v[8:11], v[164:167], v[214:217], v[8:11]
	s_setprio 0
	s_setprio 1
	v_mfma_f32_16x16x32_bf16 v[52:55], v[168:171], v[184:187], 0
	v_mfma_f32_16x16x32_bf16 v[36:39], v[168:171], v[192:195], 0
	v_mfma_f32_16x16x32_bf16 v[48:51], v[176:179], v[184:187], 0
	v_mfma_f32_16x16x32_bf16 v[32:35], v[176:179], v[192:195], 0
	v_mfma_f32_16x16x32_bf16 v[20:23], v[168:171], v[200:203], 0
	v_mfma_f32_16x16x32_bf16 v[4:7], v[168:171], v[210:213], 0
	v_mfma_f32_16x16x32_bf16 v[16:19], v[176:179], v[200:203], 0
	v_mfma_f32_16x16x32_bf16 v[0:3], v[176:179], v[210:213], 0
	v_mfma_f32_16x16x32_bf16 v[52:55], v[172:175], v[188:191], v[52:55]
	v_mfma_f32_16x16x32_bf16 v[36:39], v[172:175], v[196:199], v[36:39]
	v_mfma_f32_16x16x32_bf16 v[48:51], v[180:183], v[188:191], v[48:51]
	v_mfma_f32_16x16x32_bf16 v[32:35], v[180:183], v[196:199], v[32:35]
	v_mfma_f32_16x16x32_bf16 v[20:23], v[172:175], v[206:209], v[20:23]
	v_mfma_f32_16x16x32_bf16 v[4:7], v[172:175], v[214:217], v[4:7]
	v_lshl_add_u64 v[224:225], s[48:49], 0, v[132:133]
	s_mov_b32 m0, s34
	s_nop 0
	global_load_lds_dwordx4 v[224:225], off
	v_mfma_f32_16x16x32_bf16 v[16:19], v[180:183], v[206:209], v[16:19]
	v_mfma_f32_16x16x32_bf16 v[0:3], v[180:183], v[214:217], v[0:3]
	s_setprio 0
	s_barrier
	s_add_i32 s62, 0, 0x18000
	v_add_u32_e32 v155, s62, v149
	s_add_i32 s63, 0, 0x1c000
	ds_read_b128 v[144:147], v155
	ds_read_b128 v[156:159], v155 offset:1024
	ds_read_b128 v[160:163], v155 offset:2048
	ds_read_b128 v[164:167], v155 offset:3072
	v_add_u32_e32 v155, s63, v149
	ds_read_b128 v[168:171], v155
	ds_read_b128 v[172:175], v155 offset:1024
	ds_read_b128 v[176:179], v155 offset:2048
	ds_read_b128 v[180:183], v155 offset:3072
	s_add_u32 s48, s48, 0x20000
	s_addc_u32 s49, s49, 0
	s_mov_b32 m0, s43
	v_lshl_add_u64 v[226:227], s[48:49], 0, v[128:129]
	ds_read_b128 v[184:187], v153 offset:32768
	ds_read_b128 v[188:191], v153 offset:33792
	ds_read_b128 v[192:195], v153 offset:34816
	ds_read_b128 v[196:199], v153 offset:35840
	ds_read_b128 v[200:203], v153 offset:36864
	ds_read_b128 v[206:209], v153 offset:37888
	ds_read_b128 v[210:213], v153 offset:38912
	ds_read_b128 v[214:217], v153 offset:39936
	global_load_lds_dwordx4 v[226:227], off
	v_lshl_add_u64 v[226:227], s[48:49], 0, v[132:133]
	s_mov_b32 m0, s50
	s_nop 0
	global_load_lds_dwordx4 v[226:227], off
	s_waitcnt vmcnt(8)
	s_waitcnt lgkmcnt(0)
	s_barrier
	s_setprio 1
	s_waitcnt lgkmcnt(0)
	v_mfma_f32_16x16x32_bf16 v[124:127], v[144:147], v[184:187], v[124:127]
	v_mfma_f32_16x16x32_bf16 v[108:111], v[144:147], v[192:195], v[108:111]
	v_mfma_f32_16x16x32_bf16 v[120:123], v[160:163], v[184:187], v[120:123]
	v_mfma_f32_16x16x32_bf16 v[104:107], v[160:163], v[192:195], v[104:107]
	v_mfma_f32_16x16x32_bf16 v[92:95], v[144:147], v[200:203], v[92:95]
	v_mfma_f32_16x16x32_bf16 v[76:79], v[144:147], v[210:213], v[76:79]
	v_mfma_f32_16x16x32_bf16 v[88:91], v[160:163], v[200:203], v[88:91]
	v_mfma_f32_16x16x32_bf16 v[72:75], v[160:163], v[210:213], v[72:75]
	v_mfma_f32_16x16x32_bf16 v[124:127], v[156:159], v[188:191], v[124:127]
	v_mfma_f32_16x16x32_bf16 v[108:111], v[156:159], v[196:199], v[108:111]
	v_mfma_f32_16x16x32_bf16 v[120:123], v[164:167], v[188:191], v[120:123]
	v_mfma_f32_16x16x32_bf16 v[104:107], v[164:167], v[196:199], v[104:107]
	v_mfma_f32_16x16x32_bf16 v[92:95], v[156:159], v[206:209], v[92:95]
	v_mfma_f32_16x16x32_bf16 v[76:79], v[156:159], v[214:217], v[76:79]
	v_mfma_f32_16x16x32_bf16 v[88:91], v[164:167], v[206:209], v[88:91]
	v_mfma_f32_16x16x32_bf16 v[72:75], v[164:167], v[214:217], v[72:75]
	s_setprio 0
	s_setprio 1
	v_mfma_f32_16x16x32_bf16 v[116:119], v[168:171], v[184:187], v[116:119]
	v_mfma_f32_16x16x32_bf16 v[100:103], v[168:171], v[192:195], v[100:103]
	v_mfma_f32_16x16x32_bf16 v[112:115], v[176:179], v[184:187], v[112:115]
	v_mfma_f32_16x16x32_bf16 v[96:99], v[176:179], v[192:195], v[96:99]
	v_mfma_f32_16x16x32_bf16 v[84:87], v[168:171], v[200:203], v[84:87]
	v_mfma_f32_16x16x32_bf16 v[68:71], v[168:171], v[210:213], v[68:71]
	v_mfma_f32_16x16x32_bf16 v[80:83], v[176:179], v[200:203], v[80:83]
	v_mfma_f32_16x16x32_bf16 v[64:67], v[176:179], v[210:213], v[64:67]
	v_mfma_f32_16x16x32_bf16 v[116:119], v[172:175], v[188:191], v[116:119]
	v_mfma_f32_16x16x32_bf16 v[100:103], v[172:175], v[196:199], v[100:103]
	v_mfma_f32_16x16x32_bf16 v[112:115], v[180:183], v[188:191], v[112:115]
	v_mfma_f32_16x16x32_bf16 v[96:99], v[180:183], v[196:199], v[96:99]
	v_mfma_f32_16x16x32_bf16 v[84:87], v[172:175], v[206:209], v[84:87]
	v_mfma_f32_16x16x32_bf16 v[68:71], v[172:175], v[214:217], v[68:71]
	v_mfma_f32_16x16x32_bf16 v[80:83], v[180:183], v[206:209], v[80:83]
	v_mfma_f32_16x16x32_bf16 v[64:67], v[180:183], v[214:217], v[64:67]
	s_setprio 0
	s_barrier
; #define PG8_STAGE(bufoff, gbase, voff) do { _Pragma("unroll") for (int _i = 0; _i < 2; ++_i) \
;         __builtin_amdgcn_global_load_lds((const unsigned*)((const char*)(gbase) + (voff)[_i]), (PG8_LAS unsigned*)(lds + (bufoff) + ldsw + _i * 8192), 16, 0, 0); } while (0)
; #define PG8_LDA(dst, b, h) do { _Pragma("unroll") for (int m = 0; m < 4; ++m) _Pragma("unroll") for (int k = 0; k < 2; ++k) dst[m][k] = *(const PG8_LAS bf16x8*)(lds + PG8_SA(b, h) + aoff + m * 2048 + k * 1024); } while (0)
; #define PG8_LDB(dst, b, h) do { _Pragma("unroll") for (int n = 0; n < 2; ++n) _Pragma("unroll") for (int k = 0; k < 2; ++k) dst[n][k] = *(const PG8_LAS bf16x8*)(lds + PG8_SB(b, h) + boff + n * 2048 + k * 1024); } while (0)
; #define PG8_MMA(ai, bj, At, Bt) do { __builtin_amdgcn_s_setprio(1); _Pragma("unroll") for (int m = 0; m < 4; ++m) _Pragma("unroll") for (int n = 0; n < 2; ++n) _Pragma("unroll") for (int k = 0; k < 2; ++k) \
;         acc[ai][bj][m][n] = __builtin_amdgcn_mfma_f32_16x16x32_bf16(Bt[n][k], At[m][k], acc[ai][bj][m][n], 0, 0, 0); __builtin_amdgcn_s_setprio(0); } while (0)
; #define PG8_WAIT_V(n) asm volatile("s_waitcnt vmcnt(" #n ")" ::: "memory")
; template <class Epi, class Sched, bool ALIGN_EPI = false, bool SP2 = false>
; __device__ __forceinline__ void gemm_phase(PG8_LAS unsigned char* lds, const Gemm g, const Sched& S, const Epi& E) {
;     ...
;             PG8_LDB(B0, 0, 0); PG8_LDB(B1, 0, 1); PG8_SCHED; PG8_LDA(At, 0, 0); PG8_STAGE(PG8_SA(1, 1), a1 + hstep, voffA);
;             PG8_WAIT_V(8); PG8_WAIT_L(0); PG8_BAR; PG8_MMA(0, 0, At, B0); PG8_MMA(0, 1, At, B1); PG8_BAR; PG8_SCHED;
;             PG8_LDA(At, 0, 1); PG8_STAGE(PG8_SB(0, 0), b2, voffB); PG8_STAGE(PG8_SB(0, 1), b2 + hstep, voffB); PG8_STAGE(PG8_SA(0, 0), a2, voffA);
;             PG8_WAIT_V(8); PG8_WAIT_L(0); PG8_BAR; PG8_MMA(1, 0, At, B0); PG8_MMA(1, 1, At, B1); PG8_BAR; PG8_SCHED;
;             PG8_LDB(B0, 1, 0); PG8_LDB(B1, 1, 1); PG8_SCHED; PG8_LDA(At, 1, 0); PG8_STAGE(PG8_SA(0, 1), a2 + hstep, voffA);
;             PG8_WAIT_V(8); PG8_WAIT_L(0); PG8_BAR; PG8_MMA(0, 0, At, B0); PG8_MMA(0, 1, At, B1); PG8_BAR; PG8_SCHED;
;             PG8_LDA(At, 1, 1); PG8_STAGE(PG8_SB(1, 0), b3, voffB); PG8_STAGE(PG8_SB(1, 1), b3 + hstep, voffB); PG8_STAGE(PG8_SA(1, 0), a3, voffA);
;             PG8_WAIT_V(8); PG8_WAIT_L(0); PG8_BAR; PG8_MMA(1, 0, At, B0); PG8_MMA(1, 1, At, B1); PG8_BAR; PG8_SCHED;
	s_add_i32 s48, s62, s15
	v_lshl_add_u64 v[218:219], v[218:219], 0, s[12:13]
	s_mov_b32 m0, s48
	ds_read_b128 v[184:187], v153 offset:49152
	ds_read_b128 v[188:191], v153 offset:50176
	ds_read_b128 v[192:195], v153 offset:51200
	ds_read_b128 v[196:199], v153 offset:52224
	ds_read_b128 v[200:203], v153 offset:53248
	ds_read_b128 v[206:209], v153 offset:54272
	ds_read_b128 v[210:213], v153 offset:55296
	ds_read_b128 v[214:217], v153 offset:56320
	global_load_lds_dwordx4 v[218:219], off
	s_add_i32 m0, s48, 0x2000
	s_add_u32 s46, s46, 0x20080
	v_lshl_add_u64 v[218:219], v[220:221], 0, s[12:13]
	s_addc_u32 s47, s47, 0
	s_add_i32 s48, s63, s15
	global_load_lds_dwordx4 v[218:219], off
	v_lshl_add_u64 v[218:219], s[46:47], 0, v[130:131]
	s_mov_b32 m0, s48
	s_nop 0
	global_load_lds_dwordx4 v[218:219], off
	v_lshl_add_u64 v[218:219], s[46:47], 0, v[134:135]
	s_add_i32 m0, s48, 0x2000
	s_nop 0
	global_load_lds_dwordx4 v[218:219], off
	s_waitcnt vmcnt(6)
	s_waitcnt lgkmcnt(0)
	s_barrier
	s_setprio 1
	s_waitcnt lgkmcnt(0)
	v_mfma_f32_16x16x32_bf16 v[60:63], v[144:147], v[184:187], v[60:63]
	v_mfma_f32_16x16x32_bf16 v[44:47], v[144:147], v[192:195], v[44:47]
	v_mfma_f32_16x16x32_bf16 v[56:59], v[160:163], v[184:187], v[56:59]
	v_mfma_f32_16x16x32_bf16 v[40:43], v[160:163], v[192:195], v[40:43]
	v_mfma_f32_16x16x32_bf16 v[28:31], v[144:147], v[200:203], v[28:31]
	v_mfma_f32_16x16x32_bf16 v[12:15], v[144:147], v[210:213], v[12:15]
	v_mfma_f32_16x16x32_bf16 v[24:27], v[160:163], v[200:203], v[24:27]
	v_mfma_f32_16x16x32_bf16 v[8:11], v[160:163], v[210:213], v[8:11]
	v_mfma_f32_16x16x32_bf16 v[60:63], v[156:159], v[188:191], v[60:63]
	v_mfma_f32_16x16x32_bf16 v[44:47], v[156:159], v[196:199], v[44:47]
	v_mfma_f32_16x16x32_bf16 v[56:59], v[164:167], v[188:191], v[56:59]
	v_mfma_f32_16x16x32_bf16 v[40:43], v[164:167], v[196:199], v[40:43]
	v_mfma_f32_16x16x32_bf16 v[28:31], v[156:159], v[206:209], v[28:31]
	v_mfma_f32_16x16x32_bf16 v[12:15], v[156:159], v[214:217], v[12:15]
	v_lshl_add_u64 v[218:219], v[222:223], 0, s[12:13]
	s_mov_b32 m0, s52
	s_nop 0
	global_load_lds_dwordx4 v[218:219], off
	v_mfma_f32_16x16x32_bf16 v[24:27], v[164:167], v[206:209], v[24:27]
	v_mfma_f32_16x16x32_bf16 v[8:11], v[164:167], v[214:217], v[8:11]
	s_setprio 0
	s_setprio 1
	v_mfma_f32_16x16x32_bf16 v[52:55], v[168:171], v[184:187], v[52:55]
	v_mfma_f32_16x16x32_bf16 v[36:39], v[168:171], v[192:195], v[36:39]
	v_mfma_f32_16x16x32_bf16 v[48:51], v[176:179], v[184:187], v[48:51]
	v_mfma_f32_16x16x32_bf16 v[32:35], v[176:179], v[192:195], v[32:35]
	v_mfma_f32_16x16x32_bf16 v[20:23], v[168:171], v[200:203], v[20:23]
	v_mfma_f32_16x16x32_bf16 v[4:7], v[168:171], v[210:213], v[4:7]
	v_mfma_f32_16x16x32_bf16 v[16:19], v[176:179], v[200:203], v[16:19]
	v_mfma_f32_16x16x32_bf16 v[0:3], v[176:179], v[210:213], v[0:3]
	v_mfma_f32_16x16x32_bf16 v[52:55], v[172:175], v[188:191], v[52:55]
	v_mfma_f32_16x16x32_bf16 v[36:39], v[172:175], v[196:199], v[36:39]
	v_mfma_f32_16x16x32_bf16 v[48:51], v[180:183], v[188:191], v[48:51]
	v_mfma_f32_16x16x32_bf16 v[32:35], v[180:183], v[196:199], v[32:35]
	v_mfma_f32_16x16x32_bf16 v[20:23], v[172:175], v[206:209], v[20:23]
	v_mfma_f32_16x16x32_bf16 v[4:7], v[172:175], v[214:217], v[4:7]
	v_lshl_add_u64 v[218:219], v[224:225], 0, s[12:13]
	s_mov_b32 m0, s53
	s_nop 0
	global_load_lds_dwordx4 v[218:219], off
	v_mfma_f32_16x16x32_bf16 v[16:19], v[180:183], v[206:209], v[16:19]
	v_mfma_f32_16x16x32_bf16 v[0:3], v[180:183], v[214:217], v[0:3]
	s_setprio 0
	s_barrier
	s_add_i32 s61, s61, 2
	s_add_u32 s44, s44, 0x100
	s_addc_u32 s45, s45, 0
	s_add_u32 s59, s59, 0x100
	s_addc_u32 s60, s60, 0
.LBB0_1816:
	ds_read_b128 v[144:147], v151
	ds_read_b128 v[156:159], v151 offset:1024
	ds_read_b128 v[160:163], v151 offset:2048
	ds_read_b128 v[164:167], v151 offset:3072
	ds_read_b128 v[168:171], v152
	ds_read_b128 v[172:175], v152 offset:1024
	ds_read_b128 v[176:179], v152 offset:2048
	ds_read_b128 v[180:183], v152 offset:3072
	s_add_u32 s46, s44, 0xfffe0080
	s_addc_u32 s47, s45, -1
	s_cmp_eq_u32 s61, 4
	s_cselect_b32 s49, s29, s47
	s_cselect_b32 s48, s41, s46
	s_cselect_b32 s47, s27, s60
	s_cselect_b32 s46, s58, s59
	v_lshl_add_u64 v[218:219], s[44:45], 0, v[136:137]
	s_add_i32 m0, s33, 0xc000
	ds_read_b128 v[184:187], v153
	ds_read_b128 v[188:191], v153 offset:1024
	ds_read_b128 v[192:195], v153 offset:2048
	ds_read_b128 v[196:199], v153 offset:3072
	ds_read_b128 v[200:203], v153 offset:4096
	ds_read_b128 v[206:209], v153 offset:5120
	ds_read_b128 v[210:213], v153 offset:6144
	ds_read_b128 v[214:217], v153 offset:7168
	global_load_lds_dwordx4 v[218:219], off
	v_lshl_add_u64 v[218:219], s[44:45], 0, v[138:139]
	s_add_i32 m0, s33, 0xe000
	s_nop 0
	global_load_lds_dwordx4 v[218:219], off
	s_waitcnt vmcnt(8)
	s_waitcnt lgkmcnt(0)
	s_barrier
; #define PG8_STAGE(bufoff, gbase, voff) do { _Pragma("unroll") for (int _i = 0; _i < 2; ++_i) \
;         __builtin_amdgcn_global_load_lds((const unsigned*)((const char*)(gbase) + (voff)[_i]), (PG8_LAS unsigned*)(lds + (bufoff) + ldsw + _i * 8192), 16, 0, 0); } while (0)
; #define PG8_LDA(dst, b, h) do { _Pragma("unroll") for (int m = 0; m < 4; ++m) _Pragma("unroll") for (int k = 0; k < 2; ++k) dst[m][k] = *(const PG8_LAS bf16x8*)(lds + PG8_SA(b, h) + aoff + m * 2048 + k * 1024); } while (0)
; #define PG8_MMA(ai, bj, At, Bt) do { __builtin_amdgcn_s_setprio(1); _Pragma("unroll") for (int m = 0; m < 4; ++m) _Pragma("unroll") for (int n = 0; n < 2; ++n) _Pragma("unroll") for (int k = 0; k < 2; ++k) \
;         acc[ai][bj][m][n] = __builtin_amdgcn_mfma_f32_16x16x32_bf16(Bt[n][k], At[m][k], acc[ai][bj][m][n], 0, 0, 0); __builtin_amdgcn_s_setprio(0); } while (0)
; #define PG8_WAIT_V(n) asm volatile("s_waitcnt vmcnt(" #n ")" ::: "memory")
; #define PG8_WAIT_L(n) asm volatile("s_waitcnt lgkmcnt(" #n ")" ::: "memory")
; #define PG8_BAR __builtin_amdgcn_s_barrier()
; #define PG8_SCHED __builtin_amdgcn_sched_barrier(0)
; template <class Epi, class Sched, bool ALIGN_EPI = false, bool SP2 = false>
; __device__ __forceinline__ void gemm_phase(PG8_LAS unsigned char* lds, const Gemm g, const Sched& S, const Epi& E) {
;     ...
;             PG8_WAIT_V(8); PG8_WAIT_L(0); PG8_BAR; PG8_MMA(0, 0, At, B0); PG8_MMA(0, 1, At, B1); PG8_BAR; PG8_SCHED;
;             PG8_LDA(At, 0, 1); PG8_STAGE(PG8_SB(0, 0), b2, voffB); PG8_STAGE(PG8_SB(0, 1), b2 + hstep, voffB); PG8_STAGE(PG8_SA(0, 0), a2, voffA);
;             PG8_WAIT_V(8); PG8_WAIT_L(0); PG8_BAR; PG8_MMA(1, 0, At, B0); PG8_MMA(1, 1, At, B1); PG8_BAR; PG8_SCHED;
	s_setprio 1
	s_waitcnt lgkmcnt(0)
	v_mfma_f32_16x16x32_bf16 v[124:127], v[144:147], v[184:187], v[124:127]
	v_mfma_f32_16x16x32_bf16 v[108:111], v[144:147], v[192:195], v[108:111]
	v_mfma_f32_16x16x32_bf16 v[120:123], v[160:163], v[184:187], v[120:123]
	v_mfma_f32_16x16x32_bf16 v[104:107], v[160:163], v[192:195], v[104:107]
	v_mfma_f32_16x16x32_bf16 v[92:95], v[144:147], v[200:203], v[92:95]
	v_mfma_f32_16x16x32_bf16 v[76:79], v[144:147], v[210:213], v[76:79]
	v_mfma_f32_16x16x32_bf16 v[88:91], v[160:163], v[200:203], v[88:91]
	v_mfma_f32_16x16x32_bf16 v[72:75], v[160:163], v[210:213], v[72:75]
	v_mfma_f32_16x16x32_bf16 v[124:127], v[156:159], v[188:191], v[124:127]
	v_mfma_f32_16x16x32_bf16 v[108:111], v[156:159], v[196:199], v[108:111]
	v_mfma_f32_16x16x32_bf16 v[120:123], v[164:167], v[188:191], v[120:123]
	v_mfma_f32_16x16x32_bf16 v[104:107], v[164:167], v[196:199], v[104:107]
	v_mfma_f32_16x16x32_bf16 v[92:95], v[156:159], v[206:209], v[92:95]
	v_mfma_f32_16x16x32_bf16 v[76:79], v[156:159], v[214:217], v[76:79]
	v_mfma_f32_16x16x32_bf16 v[88:91], v[164:167], v[206:209], v[88:91]
	v_mfma_f32_16x16x32_bf16 v[72:75], v[164:167], v[214:217], v[72:75]
	s_setprio 0
	s_setprio 1
	v_mfma_f32_16x16x32_bf16 v[116:119], v[168:171], v[184:187], v[116:119]
	v_mfma_f32_16x16x32_bf16 v[100:103], v[168:171], v[192:195], v[100:103]
	v_mfma_f32_16x16x32_bf16 v[112:115], v[176:179], v[184:187], v[112:115]
	v_mfma_f32_16x16x32_bf16 v[96:99], v[176:179], v[192:195], v[96:99]
	v_mfma_f32_16x16x32_bf16 v[84:87], v[168:171], v[200:203], v[84:87]
	v_mfma_f32_16x16x32_bf16 v[68:71], v[168:171], v[210:213], v[68:71]
	v_mfma_f32_16x16x32_bf16 v[80:83], v[176:179], v[200:203], v[80:83]
	v_mfma_f32_16x16x32_bf16 v[64:67], v[176:179], v[210:213], v[64:67]
	v_mfma_f32_16x16x32_bf16 v[116:119], v[172:175], v[188:191], v[116:119]
	v_mfma_f32_16x16x32_bf16 v[100:103], v[172:175], v[196:199], v[100:103]
	v_mfma_f32_16x16x32_bf16 v[112:115], v[180:183], v[188:191], v[112:115]
	v_mfma_f32_16x16x32_bf16 v[96:99], v[180:183], v[196:199], v[96:99]
	v_mfma_f32_16x16x32_bf16 v[84:87], v[172:175], v[206:209], v[84:87]
	v_mfma_f32_16x16x32_bf16 v[68:71], v[172:175], v[214:217], v[68:71]
	v_mfma_f32_16x16x32_bf16 v[80:83], v[180:183], v[206:209], v[80:83]
	v_mfma_f32_16x16x32_bf16 v[64:67], v[180:183], v[214:217], v[64:67]
	s_setprio 0
	s_barrier
	s_add_i32 s62, s54, s15
	v_lshl_add_u64 v[218:219], s[46:47], 0, v[130:131]
	s_mov_b32 m0, s62
	ds_read_b128 v[184:187], v153 offset:16384
	ds_read_b128 v[188:191], v153 offset:17408
	ds_read_b128 v[192:195], v153 offset:18432
	ds_read_b128 v[196:199], v153 offset:19456
	ds_read_b128 v[200:203], v153 offset:20480
	ds_read_b128 v[206:209], v153 offset:21504
	ds_read_b128 v[210:213], v153 offset:22528
	ds_read_b128 v[214:217], v153 offset:23552
	global_load_lds_dwordx4 v[218:219], off
	s_add_i32 m0, s62, 0x2000
	s_add_u32 s62, s46, 0x20000
	v_lshl_add_u64 v[220:221], s[46:47], 0, v[134:135]
	s_addc_u32 s63, s47, 0
	s_add_i32 s64, s55, s15
	global_load_lds_dwordx4 v[220:221], off
	v_lshl_add_u64 v[222:223], s[62:63], 0, v[130:131]
	s_mov_b32 m0, s64
	global_load_lds_dwordx4 v[222:223], off
	v_lshl_add_u64 v[222:223], s[62:63], 0, v[134:135]
	s_add_i32 m0, s64, 0x2000
	s_nop 0
	global_load_lds_dwordx4 v[222:223], off
	s_waitcnt vmcnt(6)
	s_waitcnt lgkmcnt(0)
	s_barrier
	s_setprio 1
	s_waitcnt lgkmcnt(0)
	v_mfma_f32_16x16x32_bf16 v[60:63], v[144:147], v[184:187], v[60:63]
	v_mfma_f32_16x16x32_bf16 v[44:47], v[144:147], v[192:195], v[44:47]
	v_mfma_f32_16x16x32_bf16 v[56:59], v[160:163], v[184:187], v[56:59]
	v_mfma_f32_16x16x32_bf16 v[40:43], v[160:163], v[192:195], v[40:43]
	v_mfma_f32_16x16x32_bf16 v[28:31], v[144:147], v[200:203], v[28:31]
	v_mfma_f32_16x16x32_bf16 v[12:15], v[144:147], v[210:213], v[12:15]
	v_mfma_f32_16x16x32_bf16 v[24:27], v[160:163], v[200:203], v[24:27]
	v_mfma_f32_16x16x32_bf16 v[8:11], v[160:163], v[210:213], v[8:11]
	v_mfma_f32_16x16x32_bf16 v[60:63], v[156:159], v[188:191], v[60:63]
	v_mfma_f32_16x16x32_bf16 v[44:47], v[156:159], v[196:199], v[44:47]
	v_mfma_f32_16x16x32_bf16 v[56:59], v[164:167], v[188:191], v[56:59]
	v_mfma_f32_16x16x32_bf16 v[40:43], v[164:167], v[196:199], v[40:43]
	v_mfma_f32_16x16x32_bf16 v[28:31], v[156:159], v[206:209], v[28:31]
	v_mfma_f32_16x16x32_bf16 v[12:15], v[156:159], v[214:217], v[12:15]
	v_lshl_add_u64 v[222:223], s[48:49], 0, v[128:129]
	s_mov_b32 m0, s33
	s_nop 0
	global_load_lds_dwordx4 v[222:223], off
	v_mfma_f32_16x16x32_bf16 v[24:27], v[164:167], v[206:209], v[24:27]
	v_mfma_f32_16x16x32_bf16 v[8:11], v[164:167], v[214:217], v[8:11]
	s_setprio 0
	s_setprio 1
	v_mfma_f32_16x16x32_bf16 v[52:55], v[168:171], v[184:187], v[52:55]
	v_mfma_f32_16x16x32_bf16 v[36:39], v[168:171], v[192:195], v[36:39]
	v_mfma_f32_16x16x32_bf16 v[48:51], v[176:179], v[184:187], v[48:51]
	v_mfma_f32_16x16x32_bf16 v[32:35], v[176:179], v[192:195], v[32:35]
	v_mfma_f32_16x16x32_bf16 v[20:23], v[168:171], v[200:203], v[20:23]
	v_mfma_f32_16x16x32_bf16 v[4:7], v[168:171], v[210:213], v[4:7]
	v_mfma_f32_16x16x32_bf16 v[16:19], v[176:179], v[200:203], v[16:19]
	v_mfma_f32_16x16x32_bf16 v[0:3], v[176:179], v[210:213], v[0:3]
	v_mfma_f32_16x16x32_bf16 v[52:55], v[172:175], v[188:191], v[52:55]
	v_mfma_f32_16x16x32_bf16 v[36:39], v[172:175], v[196:199], v[36:39]
	v_mfma_f32_16x16x32_bf16 v[48:51], v[180:183], v[188:191], v[48:51]
	v_mfma_f32_16x16x32_bf16 v[32:35], v[180:183], v[196:199], v[32:35]
	v_mfma_f32_16x16x32_bf16 v[20:23], v[172:175], v[206:209], v[20:23]
	v_mfma_f32_16x16x32_bf16 v[4:7], v[172:175], v[214:217], v[4:7]
	v_lshl_add_u64 v[224:225], s[48:49], 0, v[132:133]
	s_mov_b32 m0, s34
	s_nop 0
	global_load_lds_dwordx4 v[224:225], off
	v_mfma_f32_16x16x32_bf16 v[16:19], v[180:183], v[206:209], v[16:19]
	v_mfma_f32_16x16x32_bf16 v[0:3], v[180:183], v[214:217], v[0:3]
	s_setprio 0
	s_barrier
; #define PG8_STAGE(bufoff, gbase, voff) do { _Pragma("unroll") for (int _i = 0; _i < 2; ++_i) \
;         __builtin_amdgcn_global_load_lds((const unsigned*)((const char*)(gbase) + (voff)[_i]), (PG8_LAS unsigned*)(lds + (bufoff) + ldsw + _i * 8192), 16, 0, 0); } while (0)
; #define PG8_LDA(dst, b, h) do { _Pragma("unroll") for (int m = 0; m < 4; ++m) _Pragma("unroll") for (int k = 0; k < 2; ++k) dst[m][k] = *(const PG8_LAS bf16x8*)(lds + PG8_SA(b, h) + aoff + m * 2048 + k * 1024); } while (0)
; #define PG8_LDB(dst, b, h) do { _Pragma("unroll") for (int n = 0; n < 2; ++n) _Pragma("unroll") for (int k = 0; k < 2; ++k) dst[n][k] = *(const PG8_LAS bf16x8*)(lds + PG8_SB(b, h) + boff + n * 2048 + k * 1024); } while (0)
; #define PG8_MMA(ai, bj, At, Bt) do { __builtin_amdgcn_s_setprio(1); _Pragma("unroll") for (int m = 0; m < 4; ++m) _Pragma("unroll") for (int n = 0; n < 2; ++n) _Pragma("unroll") for (int k = 0; k < 2; ++k) \
;         acc[ai][bj][m][n] = __builtin_amdgcn_mfma_f32_16x16x32_bf16(Bt[n][k], At[m][k], acc[ai][bj][m][n], 0, 0, 0); __builtin_amdgcn_s_setprio(0); } while (0)
; #define PG8_WAIT_V(n) asm volatile("s_waitcnt vmcnt(" #n ")" ::: "memory")
; #define PG8_WAIT_L(n) asm volatile("s_waitcnt lgkmcnt(" #n ")" ::: "memory")
; #define PG8_BAR __builtin_amdgcn_s_barrier()
; #define PG8_SCHED __builtin_amdgcn_sched_barrier(0)
; template <class Epi, class Sched, bool ALIGN_EPI = false, bool SP2 = false>
; __device__ __forceinline__ void gemm_phase(PG8_LAS unsigned char* lds, const Gemm g, const Sched& S, const Epi& E) {
;     ...
;             PG8_LDB(B0, 1, 0); PG8_LDB(B1, 1, 1); PG8_SCHED; PG8_LDA(At, 1, 0); PG8_STAGE(PG8_SA(0, 1), a2 + hstep, voffA);
;             PG8_WAIT_V(8); PG8_WAIT_L(0); PG8_BAR; PG8_MMA(0, 0, At, B0); PG8_MMA(0, 1, At, B1); PG8_BAR; PG8_SCHED;
	s_add_i32 s62, 0, 0x18000
	v_add_u32_e32 v155, s62, v149
	s_add_i32 s63, 0, 0x1c000
	ds_read_b128 v[144:147], v155
	ds_read_b128 v[156:159], v155 offset:1024
	ds_read_b128 v[160:163], v155 offset:2048
	ds_read_b128 v[164:167], v155 offset:3072
	v_add_u32_e32 v155, s63, v149
	ds_read_b128 v[168:171], v155
	ds_read_b128 v[172:175], v155 offset:1024
	ds_read_b128 v[176:179], v155 offset:2048
	ds_read_b128 v[180:183], v155 offset:3072
	s_add_u32 s48, s48, 0x20000
	s_addc_u32 s49, s49, 0
	s_mov_b32 m0, s43
	v_lshl_add_u64 v[226:227], s[48:49], 0, v[128:129]
	ds_read_b128 v[184:187], v153 offset:32768
	ds_read_b128 v[188:191], v153 offset:33792
	ds_read_b128 v[192:195], v153 offset:34816
	ds_read_b128 v[196:199], v153 offset:35840
	ds_read_b128 v[200:203], v153 offset:36864
	ds_read_b128 v[206:209], v153 offset:37888
	ds_read_b128 v[210:213], v153 offset:38912
	ds_read_b128 v[214:217], v153 offset:39936
	global_load_lds_dwordx4 v[226:227], off
	v_lshl_add_u64 v[226:227], s[48:49], 0, v[132:133]
	s_mov_b32 m0, s50
	s_nop 0
	global_load_lds_dwordx4 v[226:227], off
	s_waitcnt vmcnt(8)
	s_waitcnt lgkmcnt(0)
	s_barrier
	s_setprio 1
	s_waitcnt lgkmcnt(0)
	v_mfma_f32_16x16x32_bf16 v[124:127], v[144:147], v[184:187], v[124:127]
	v_mfma_f32_16x16x32_bf16 v[108:111], v[144:147], v[192:195], v[108:111]
	v_mfma_f32_16x16x32_bf16 v[120:123], v[160:163], v[184:187], v[120:123]
	v_mfma_f32_16x16x32_bf16 v[104:107], v[160:163], v[192:195], v[104:107]
	v_mfma_f32_16x16x32_bf16 v[92:95], v[144:147], v[200:203], v[92:95]
	v_mfma_f32_16x16x32_bf16 v[76:79], v[144:147], v[210:213], v[76:79]
	v_mfma_f32_16x16x32_bf16 v[88:91], v[160:163], v[200:203], v[88:91]
	v_mfma_f32_16x16x32_bf16 v[72:75], v[160:163], v[210:213], v[72:75]
	v_mfma_f32_16x16x32_bf16 v[124:127], v[156:159], v[188:191], v[124:127]
	v_mfma_f32_16x16x32_bf16 v[108:111], v[156:159], v[196:199], v[108:111]
	v_mfma_f32_16x16x32_bf16 v[120:123], v[164:167], v[188:191], v[120:123]
	v_mfma_f32_16x16x32_bf16 v[104:107], v[164:167], v[196:199], v[104:107]
	v_mfma_f32_16x16x32_bf16 v[92:95], v[156:159], v[206:209], v[92:95]
	v_mfma_f32_16x16x32_bf16 v[76:79], v[156:159], v[214:217], v[76:79]
	v_mfma_f32_16x16x32_bf16 v[88:91], v[164:167], v[206:209], v[88:91]
	v_mfma_f32_16x16x32_bf16 v[72:75], v[164:167], v[214:217], v[72:75]
	s_setprio 0
	s_setprio 1
	v_mfma_f32_16x16x32_bf16 v[116:119], v[168:171], v[184:187], v[116:119]
	v_mfma_f32_16x16x32_bf16 v[100:103], v[168:171], v[192:195], v[100:103]
	v_mfma_f32_16x16x32_bf16 v[112:115], v[176:179], v[184:187], v[112:115]
	v_mfma_f32_16x16x32_bf16 v[96:99], v[176:179], v[192:195], v[96:99]
	v_mfma_f32_16x16x32_bf16 v[84:87], v[168:171], v[200:203], v[84:87]
	v_mfma_f32_16x16x32_bf16 v[68:71], v[168:171], v[210:213], v[68:71]
	v_mfma_f32_16x16x32_bf16 v[80:83], v[176:179], v[200:203], v[80:83]
	v_mfma_f32_16x16x32_bf16 v[64:67], v[176:179], v[210:213], v[64:67]
	v_mfma_f32_16x16x32_bf16 v[116:119], v[172:175], v[188:191], v[116:119]
	v_mfma_f32_16x16x32_bf16 v[100:103], v[172:175], v[196:199], v[100:103]
	v_mfma_f32_16x16x32_bf16 v[112:115], v[180:183], v[188:191], v[112:115]
	v_mfma_f32_16x16x32_bf16 v[96:99], v[180:183], v[196:199], v[96:99]
	v_mfma_f32_16x16x32_bf16 v[84:87], v[172:175], v[206:209], v[84:87]
	v_mfma_f32_16x16x32_bf16 v[68:71], v[172:175], v[214:217], v[68:71]
	v_mfma_f32_16x16x32_bf16 v[80:83], v[180:183], v[206:209], v[80:83]
	v_mfma_f32_16x16x32_bf16 v[64:67], v[180:183], v[214:217], v[64:67]
	s_setprio 0
	s_barrier
; #define PG8_STAGE(bufoff, gbase, voff) do { _Pragma("unroll") for (int _i = 0; _i < 2; ++_i) \
;         __builtin_amdgcn_global_load_lds((const unsigned*)((const char*)(gbase) + (voff)[_i]), (PG8_LAS unsigned*)(lds + (bufoff) + ldsw + _i * 8192), 16, 0, 0); } while (0)
; #define PG8_LDA(dst, b, h) do { _Pragma("unroll") for (int m = 0; m < 4; ++m) _Pragma("unroll") for (int k = 0; k < 2; ++k) dst[m][k] = *(const PG8_LAS bf16x8*)(lds + PG8_SA(b, h) + aoff + m * 2048 + k * 1024); } while (0)
; #define PG8_MMA(ai, bj, At, Bt) do { __builtin_amdgcn_s_setprio(1); _Pragma("unroll") for (int m = 0; m < 4; ++m) _Pragma("unroll") for (int n = 0; n < 2; ++n) _Pragma("unroll") for (int k = 0; k < 2; ++k) \
;         acc[ai][bj][m][n] = __builtin_amdgcn_mfma_f32_16x16x32_bf16(Bt[n][k], At[m][k], acc[ai][bj][m][n], 0, 0, 0); __builtin_amdgcn_s_setprio(0); } while (0)
; #define PG8_WAIT_V(n) asm volatile("s_waitcnt vmcnt(" #n ")" ::: "memory")
; #define PG8_WAIT_L(n) asm volatile("s_waitcnt lgkmcnt(" #n ")" ::: "memory")
; #define PG8_BAR __builtin_amdgcn_s_barrier()
; #define PG8_SCHED __builtin_amdgcn_sched_barrier(0)
; template <class Epi, class Sched, bool ALIGN_EPI = false, bool SP2 = false>
; __device__ __forceinline__ void gemm_phase(PG8_LAS unsigned char* lds, const Gemm g, const Sched& S, const Epi& E) {
;     ...
;         for (int t = 0; t < nt; t += 2) {
;             const bool last = (t == nt - 2);
;     ...
;             PG8_LDA(At, 1, 1); PG8_STAGE(PG8_SB(1, 0), b3, voffB); PG8_STAGE(PG8_SB(1, 1), b3 + hstep, voffB); PG8_STAGE(PG8_SA(1, 0), a3, voffA);
;             PG8_WAIT_V(8); PG8_WAIT_L(0); PG8_BAR; PG8_MMA(1, 0, At, B0); PG8_MMA(1, 1, At, B1); PG8_BAR; PG8_SCHED;
	s_add_i32 s48, s62, s15
	v_lshl_add_u64 v[218:219], v[218:219], 0, s[12:13]
	s_mov_b32 m0, s48
	ds_read_b128 v[184:187], v153 offset:49152
	ds_read_b128 v[188:191], v153 offset:50176
	ds_read_b128 v[192:195], v153 offset:51200
	ds_read_b128 v[196:199], v153 offset:52224
	ds_read_b128 v[200:203], v153 offset:53248
	ds_read_b128 v[206:209], v153 offset:54272
	ds_read_b128 v[210:213], v153 offset:55296
	ds_read_b128 v[214:217], v153 offset:56320
	global_load_lds_dwordx4 v[218:219], off
	s_add_i32 m0, s48, 0x2000
	s_add_u32 s46, s46, 0x20080
	v_lshl_add_u64 v[218:219], v[220:221], 0, s[12:13]
	s_addc_u32 s47, s47, 0
	s_add_i32 s48, s63, s15
	global_load_lds_dwordx4 v[218:219], off
	v_lshl_add_u64 v[218:219], s[46:47], 0, v[130:131]
	s_mov_b32 m0, s48
	s_nop 0
	global_load_lds_dwordx4 v[218:219], off
	v_lshl_add_u64 v[218:219], s[46:47], 0, v[134:135]
	s_add_i32 m0, s48, 0x2000
	s_nop 0
	global_load_lds_dwordx4 v[218:219], off
	s_waitcnt vmcnt(6)
	s_waitcnt lgkmcnt(0)
	s_barrier
	s_setprio 1
	s_waitcnt lgkmcnt(0)
	v_mfma_f32_16x16x32_bf16 v[60:63], v[144:147], v[184:187], v[60:63]
	v_mfma_f32_16x16x32_bf16 v[44:47], v[144:147], v[192:195], v[44:47]
	v_mfma_f32_16x16x32_bf16 v[56:59], v[160:163], v[184:187], v[56:59]
	v_mfma_f32_16x16x32_bf16 v[40:43], v[160:163], v[192:195], v[40:43]
	v_mfma_f32_16x16x32_bf16 v[28:31], v[144:147], v[200:203], v[28:31]
	v_mfma_f32_16x16x32_bf16 v[12:15], v[144:147], v[210:213], v[12:15]
	v_mfma_f32_16x16x32_bf16 v[24:27], v[160:163], v[200:203], v[24:27]
	v_mfma_f32_16x16x32_bf16 v[8:11], v[160:163], v[210:213], v[8:11]
	v_mfma_f32_16x16x32_bf16 v[60:63], v[156:159], v[188:191], v[60:63]
	v_mfma_f32_16x16x32_bf16 v[44:47], v[156:159], v[196:199], v[44:47]
	v_mfma_f32_16x16x32_bf16 v[56:59], v[164:167], v[188:191], v[56:59]
	v_mfma_f32_16x16x32_bf16 v[40:43], v[164:167], v[196:199], v[40:43]
	v_mfma_f32_16x16x32_bf16 v[28:31], v[156:159], v[206:209], v[28:31]
	v_mfma_f32_16x16x32_bf16 v[12:15], v[156:159], v[214:217], v[12:15]
	v_lshl_add_u64 v[218:219], v[222:223], 0, s[12:13]
	s_mov_b32 m0, s52
	s_nop 0
	global_load_lds_dwordx4 v[218:219], off
	v_mfma_f32_16x16x32_bf16 v[24:27], v[164:167], v[206:209], v[24:27]
	v_mfma_f32_16x16x32_bf16 v[8:11], v[164:167], v[214:217], v[8:11]
	s_setprio 0
	s_setprio 1
	v_mfma_f32_16x16x32_bf16 v[52:55], v[168:171], v[184:187], v[52:55]
	v_mfma_f32_16x16x32_bf16 v[36:39], v[168:171], v[192:195], v[36:39]
	v_mfma_f32_16x16x32_bf16 v[48:51], v[176:179], v[184:187], v[48:51]
	v_mfma_f32_16x16x32_bf16 v[32:35], v[176:179], v[192:195], v[32:35]
	v_mfma_f32_16x16x32_bf16 v[20:23], v[168:171], v[200:203], v[20:23]
	v_mfma_f32_16x16x32_bf16 v[4:7], v[168:171], v[210:213], v[4:7]
	v_mfma_f32_16x16x32_bf16 v[16:19], v[176:179], v[200:203], v[16:19]
	v_mfma_f32_16x16x32_bf16 v[0:3], v[176:179], v[210:213], v[0:3]
	v_mfma_f32_16x16x32_bf16 v[52:55], v[172:175], v[188:191], v[52:55]
	v_mfma_f32_16x16x32_bf16 v[36:39], v[172:175], v[196:199], v[36:39]
	v_mfma_f32_16x16x32_bf16 v[48:51], v[180:183], v[188:191], v[48:51]
	v_mfma_f32_16x16x32_bf16 v[32:35], v[180:183], v[196:199], v[32:35]
	v_mfma_f32_16x16x32_bf16 v[20:23], v[172:175], v[206:209], v[20:23]
	v_mfma_f32_16x16x32_bf16 v[4:7], v[172:175], v[214:217], v[4:7]
	v_lshl_add_u64 v[218:219], v[224:225], 0, s[12:13]
	s_mov_b32 m0, s53
	s_nop 0
	global_load_lds_dwordx4 v[218:219], off
	v_mfma_f32_16x16x32_bf16 v[16:19], v[180:183], v[206:209], v[16:19]
	v_mfma_f32_16x16x32_bf16 v[0:3], v[180:183], v[214:217], v[0:3]
	s_setprio 0
	s_barrier
	s_add_i32 s61, s61, 2
	s_add_u32 s44, s44, 0x100
	s_addc_u32 s45, s45, 0
	s_add_u32 s59, s59, 0x100
	s_addc_u32 s60, s60, 0
	s_cmp_gt_u32 s61, 5
	s_cbranch_scc0 .LBB0_1816
	s_and_b64 vcc, exec, s[24:25]
	s_cbranch_vccz .LBB0_1819
	s_barrier

; #define PG8_STAGE(bufoff, gbase, voff) do { _Pragma("unroll") for (int _i = 0; _i < 2; ++_i) \
;         __builtin_amdgcn_global_load_lds((const unsigned*)((const char*)(gbase) + (voff)[_i]), (PG8_LAS unsigned*)(lds + (bufoff) + ldsw + _i * 8192), 16, 0, 0); } while (0)
; #define PG8_LDA(dst, b, h) do { _Pragma("unroll") for (int m = 0; m < 4; ++m) _Pragma("unroll") for (int k = 0; k < 2; ++k) dst[m][k] = *(const PG8_LAS bf16x8*)(lds + PG8_SA(b, h) + aoff + m * 2048 + k * 1024); } while (0)
; #define PG8_LDB(dst, b, h) do { _Pragma("unroll") for (int n = 0; n < 2; ++n) _Pragma("unroll") for (int k = 0; k < 2; ++k) dst[n][k] = *(const PG8_LAS bf16x8*)(lds + PG8_SB(b, h) + boff + n * 2048 + k * 1024); } while (0)
; #define PG8_MMA(ai, bj, At, Bt) do { __builtin_amdgcn_s_setprio(1); _Pragma("unroll") for (int m = 0; m < 4; ++m) _Pragma("unroll") for (int n = 0; n < 2; ++n) _Pragma("unroll") for (int k = 0; k < 2; ++k) \
;         acc[ai][bj][m][n] = __builtin_amdgcn_mfma_f32_16x16x32_bf16(Bt[n][k], At[m][k], acc[ai][bj][m][n], 0, 0, 0); __builtin_amdgcn_s_setprio(0); } while (0)
; #define PG8_BAR __builtin_amdgcn_s_barrier()
; template <class Epi, class Sched, bool ALIGN_EPI = false, bool SP2 = false>
; __device__ __forceinline__ void gemm_phase(PG8_LAS unsigned char* lds, const Gemm g, const Sched& S, const Epi& E) {
;     ...
;         const bool has_next = S.next(ui + 1, nxt);
;         const char* nA = has_next ? (const char*)g.A + (size_t)nxt.pm * tstep : cA; const char* nB = has_next ? (const char*)g.Bt + (size_t)nxt.pn * tstep : cB;
;         for (int t = 0; t < nt; t += 2) {
;             const bool last = (t == nt - 2);
;             const char* a1 = cA + (size_t)(t + 1) * kstep;
;             const char* a2 = last ? nA : cA + (size_t)(t + 2) * kstep; const char* b2 = last ? nB : cB + (size_t)(t + 2) * kstep;
;             const char* a3 = a2 + kstep; const char* b3 = b2 + kstep;
;             if (last && has_next) S.a_ready(nxt);
;             if constexpr (SP2) {
;             PG8_LDB(B0, 0, 0); PG8_LDB(B1, 0, 1); PG8_SCHED; PG8_LDA(At, 0, 0); PG8_STAGE(PG8_SA(1, 1), a1 + hstep, voffA);
;             PG8_WAIT_V(8); PG8_WAIT_L(0); PG8_BAR; PG8_MMA(0, 0, At, B0); PG8_MMA(0, 1, At, B1); PG8_BAR; PG8_SCHED;
;             PG8_LDA(At, 0, 1); PG8_STAGE(PG8_SB(0, 0), b2, voffB); PG8_STAGE(PG8_SB(0, 1), b2 + hstep, voffB); PG8_STAGE(PG8_SA(0, 0), a2, voffA);
.LBB0_1899:
	s_ashr_i32 s25, s24, 31
	s_lshl_b64 s[26:27], s[24:25], 19
	s_add_u32 s26, s22, s26
	s_addc_u32 s27, s23, s27
	s_and_b64 s[28:29], s[4:5], exec
	s_cselect_b32 s25, s27, s39
	s_cselect_b32 s53, s26, s38
	s_ashr_i32 s13, s12, 31
	s_lshl_b64 s[28:29], s[12:13], 19
	s_add_u32 s28, s3, s28
	s_addc_u32 s29, s14, s29
	s_and_b64 s[42:43], s[4:5], exec
	s_cselect_b32 s13, s29, s41
	s_cselect_b32 s54, s28, s40
	s_add_u32 s38, s38, 0x40080
	s_addc_u32 s39, s39, 0
	s_add_u32 s55, s40, 0x100
	s_addc_u32 s56, s41, 0
	s_mov_b32 s57, -2
	ds_read_b128 v[144:147], v155
	ds_read_b128 v[148:151], v155 offset:1024
	ds_read_b128 v[160:163], v155 offset:2048
	ds_read_b128 v[164:167], v155 offset:3072
	ds_read_b128 v[168:171], v156
	ds_read_b128 v[172:175], v156 offset:1024
	ds_read_b128 v[176:179], v156 offset:2048
	ds_read_b128 v[180:183], v156 offset:3072
	s_add_u32 s40, s38, 0xfffc0080
	s_addc_u32 s41, s39, -1
	s_cmp_eq_u32 s57, 12
	s_cselect_b32 s43, s25, s41
	s_cselect_b32 s42, s53, s40
	s_cselect_b32 s41, s13, s56
	s_cselect_b32 s40, s54, s55
	v_lshl_add_u64 v[218:219], s[38:39], 0, v[136:137]
	s_add_i32 m0, s34, 0xc000
	ds_read_b128 v[184:187], v157
	ds_read_b128 v[188:191], v157 offset:1024
	ds_read_b128 v[192:195], v157 offset:2048
	ds_read_b128 v[196:199], v157 offset:3072
	ds_read_b128 v[200:203], v157 offset:4096
	ds_read_b128 v[206:209], v157 offset:5120
	ds_read_b128 v[210:213], v157 offset:6144
	ds_read_b128 v[214:217], v157 offset:7168
	global_load_lds_dwordx4 v[218:219], off
	v_lshl_add_u64 v[218:219], s[38:39], 0, v[138:139]
	s_add_i32 m0, s34, 0xe000
	s_nop 0
	global_load_lds_dwordx4 v[218:219], off
	s_waitcnt vmcnt(8)
	s_waitcnt lgkmcnt(0)
	s_barrier
	s_setprio 1
	s_waitcnt lgkmcnt(0)
	v_mfma_f32_16x16x32_bf16 v[124:127], v[144:147], v[184:187], 0
	v_mfma_f32_16x16x32_bf16 v[108:111], v[144:147], v[192:195], 0
	v_mfma_f32_16x16x32_bf16 v[120:123], v[160:163], v[184:187], 0
	v_mfma_f32_16x16x32_bf16 v[104:107], v[160:163], v[192:195], 0
	v_mfma_f32_16x16x32_bf16 v[92:95], v[144:147], v[200:203], 0
	v_mfma_f32_16x16x32_bf16 v[76:79], v[144:147], v[210:213], 0
	v_mfma_f32_16x16x32_bf16 v[88:91], v[160:163], v[200:203], 0
	v_mfma_f32_16x16x32_bf16 v[72:75], v[160:163], v[210:213], 0
	v_mfma_f32_16x16x32_bf16 v[124:127], v[148:151], v[188:191], v[124:127]
	v_mfma_f32_16x16x32_bf16 v[108:111], v[148:151], v[196:199], v[108:111]
	v_mfma_f32_16x16x32_bf16 v[120:123], v[164:167], v[188:191], v[120:123]
	v_mfma_f32_16x16x32_bf16 v[104:107], v[164:167], v[196:199], v[104:107]
	v_mfma_f32_16x16x32_bf16 v[92:95], v[148:151], v[206:209], v[92:95]
	v_mfma_f32_16x16x32_bf16 v[76:79], v[148:151], v[214:217], v[76:79]
	v_mfma_f32_16x16x32_bf16 v[88:91], v[164:167], v[206:209], v[88:91]
	v_mfma_f32_16x16x32_bf16 v[72:75], v[164:167], v[214:217], v[72:75]
	s_setprio 0
	s_setprio 1
	v_mfma_f32_16x16x32_bf16 v[116:119], v[168:171], v[184:187], 0
	v_mfma_f32_16x16x32_bf16 v[100:103], v[168:171], v[192:195], 0
	v_mfma_f32_16x16x32_bf16 v[112:115], v[176:179], v[184:187], 0
	v_mfma_f32_16x16x32_bf16 v[96:99], v[176:179], v[192:195], 0
	v_mfma_f32_16x16x32_bf16 v[84:87], v[168:171], v[200:203], 0
	v_mfma_f32_16x16x32_bf16 v[68:71], v[168:171], v[210:213], 0
	v_mfma_f32_16x16x32_bf16 v[80:83], v[176:179], v[200:203], 0
	v_mfma_f32_16x16x32_bf16 v[64:67], v[176:179], v[210:213], 0
	v_mfma_f32_16x16x32_bf16 v[116:119], v[172:175], v[188:191], v[116:119]
	v_mfma_f32_16x16x32_bf16 v[100:103], v[172:175], v[196:199], v[100:103]
	v_mfma_f32_16x16x32_bf16 v[112:115], v[180:183], v[188:191], v[112:115]
	v_mfma_f32_16x16x32_bf16 v[96:99], v[180:183], v[196:199], v[96:99]
	v_mfma_f32_16x16x32_bf16 v[84:87], v[172:175], v[206:209], v[84:87]
	v_mfma_f32_16x16x32_bf16 v[68:71], v[172:175], v[214:217], v[68:71]
	v_mfma_f32_16x16x32_bf16 v[80:83], v[180:183], v[206:209], v[80:83]
	v_mfma_f32_16x16x32_bf16 v[64:67], v[180:183], v[214:217], v[64:67]
	s_setprio 0
	s_barrier
	s_add_i32 s58, s49, s15
	v_lshl_add_u64 v[218:219], s[40:41], 0, v[132:133]
	s_mov_b32 m0, s58
	ds_read_b128 v[184:187], v157 offset:16384
	ds_read_b128 v[188:191], v157 offset:17408
	ds_read_b128 v[192:195], v157 offset:18432
	ds_read_b128 v[196:199], v157 offset:19456
	ds_read_b128 v[200:203], v157 offset:20480
	ds_read_b128 v[206:209], v157 offset:21504
	ds_read_b128 v[210:213], v157 offset:22528
	ds_read_b128 v[214:217], v157 offset:23552
	global_load_lds_dwordx4 v[218:219], off
	s_add_i32 m0, s58, 0x2000
	s_add_u32 s58, s40, 0x40000
	v_lshl_add_u64 v[220:221], s[40:41], 0, v[128:129]
	s_addc_u32 s59, s41, 0
	s_add_i32 s60, s50, s15
	global_load_lds_dwordx4 v[220:221], off
	v_lshl_add_u64 v[222:223], s[58:59], 0, v[132:133]
	s_mov_b32 m0, s60
	global_load_lds_dwordx4 v[222:223], off
	v_lshl_add_u64 v[222:223], s[58:59], 0, v[128:129]
	s_add_i32 m0, s60, 0x2000
	s_nop 0
	global_load_lds_dwordx4 v[222:223], off
	s_waitcnt vmcnt(6)
	s_waitcnt lgkmcnt(0)
	s_barrier
; #define PG8_STAGE(bufoff, gbase, voff) do { _Pragma("unroll") for (int _i = 0; _i < 2; ++_i) \
;         __builtin_amdgcn_global_load_lds((const unsigned*)((const char*)(gbase) + (voff)[_i]), (PG8_LAS unsigned*)(lds + (bufoff) + ldsw + _i * 8192), 16, 0, 0); } while (0)
; #define PG8_LDA(dst, b, h) do { _Pragma("unroll") for (int m = 0; m < 4; ++m) _Pragma("unroll") for (int k = 0; k < 2; ++k) dst[m][k] = *(const PG8_LAS bf16x8*)(lds + PG8_SA(b, h) + aoff + m * 2048 + k * 1024); } while (0)
; #define PG8_LDB(dst, b, h) do { _Pragma("unroll") for (int n = 0; n < 2; ++n) _Pragma("unroll") for (int k = 0; k < 2; ++k) dst[n][k] = *(const PG8_LAS bf16x8*)(lds + PG8_SB(b, h) + boff + n * 2048 + k * 1024); } while (0)
; #define PG8_MMA(ai, bj, At, Bt) do { __builtin_amdgcn_s_setprio(1); _Pragma("unroll") for (int m = 0; m < 4; ++m) _Pragma("unroll") for (int n = 0; n < 2; ++n) _Pragma("unroll") for (int k = 0; k < 2; ++k) \
;         acc[ai][bj][m][n] = __builtin_amdgcn_mfma_f32_16x16x32_bf16(Bt[n][k], At[m][k], acc[ai][bj][m][n], 0, 0, 0); __builtin_amdgcn_s_setprio(0); } while (0)
; #define PG8_WAIT_V(n) asm volatile("s_waitcnt vmcnt(" #n ")" ::: "memory")
; #define PG8_WAIT_L(n) asm volatile("s_waitcnt lgkmcnt(" #n ")" ::: "memory")
; #define PG8_BAR __builtin_amdgcn_s_barrier()
; #define PG8_SCHED __builtin_amdgcn_sched_barrier(0)
; template <class Epi, class Sched, bool ALIGN_EPI = false, bool SP2 = false>
; __device__ __forceinline__ void gemm_phase(PG8_LAS unsigned char* lds, const Gemm g, const Sched& S, const Epi& E) {
;     ...
;             PG8_WAIT_V(8); PG8_WAIT_L(0); PG8_BAR; PG8_MMA(1, 0, At, B0); PG8_MMA(1, 1, At, B1); PG8_BAR; PG8_SCHED;
;             PG8_LDB(B0, 1, 0); PG8_LDB(B1, 1, 1); PG8_SCHED; PG8_LDA(At, 1, 0); PG8_STAGE(PG8_SA(0, 1), a2 + hstep, voffA);
;             PG8_WAIT_V(8); PG8_WAIT_L(0); PG8_BAR; PG8_MMA(0, 0, At, B0); PG8_MMA(0, 1, At, B1); PG8_BAR; PG8_SCHED;
	s_setprio 1
	s_waitcnt lgkmcnt(0)
	v_mfma_f32_16x16x32_bf16 v[60:63], v[144:147], v[184:187], 0
	v_mfma_f32_16x16x32_bf16 v[44:47], v[144:147], v[192:195], 0
	v_mfma_f32_16x16x32_bf16 v[56:59], v[160:163], v[184:187], 0
	v_mfma_f32_16x16x32_bf16 v[40:43], v[160:163], v[192:195], 0
	v_mfma_f32_16x16x32_bf16 v[28:31], v[144:147], v[200:203], 0
	v_mfma_f32_16x16x32_bf16 v[12:15], v[144:147], v[210:213], 0
	v_mfma_f32_16x16x32_bf16 v[24:27], v[160:163], v[200:203], 0
	v_mfma_f32_16x16x32_bf16 v[8:11], v[160:163], v[210:213], 0
	v_mfma_f32_16x16x32_bf16 v[60:63], v[148:151], v[188:191], v[60:63]
	v_mfma_f32_16x16x32_bf16 v[44:47], v[148:151], v[196:199], v[44:47]
	v_mfma_f32_16x16x32_bf16 v[56:59], v[164:167], v[188:191], v[56:59]
	v_mfma_f32_16x16x32_bf16 v[40:43], v[164:167], v[196:199], v[40:43]
	v_mfma_f32_16x16x32_bf16 v[28:31], v[148:151], v[206:209], v[28:31]
	v_mfma_f32_16x16x32_bf16 v[12:15], v[148:151], v[214:217], v[12:15]
	v_lshl_add_u64 v[222:223], s[42:43], 0, v[134:135]
	s_mov_b32 m0, s34
	s_nop 0
	global_load_lds_dwordx4 v[222:223], off
	v_mfma_f32_16x16x32_bf16 v[24:27], v[164:167], v[206:209], v[24:27]
	v_mfma_f32_16x16x32_bf16 v[8:11], v[164:167], v[214:217], v[8:11]
	s_setprio 0
	s_setprio 1
	v_mfma_f32_16x16x32_bf16 v[52:55], v[168:171], v[184:187], 0
	v_mfma_f32_16x16x32_bf16 v[36:39], v[168:171], v[192:195], 0
	v_mfma_f32_16x16x32_bf16 v[48:51], v[176:179], v[184:187], 0
	v_mfma_f32_16x16x32_bf16 v[32:35], v[176:179], v[192:195], 0
	v_mfma_f32_16x16x32_bf16 v[20:23], v[168:171], v[200:203], 0
	v_mfma_f32_16x16x32_bf16 v[4:7], v[168:171], v[210:213], 0
	v_mfma_f32_16x16x32_bf16 v[16:19], v[176:179], v[200:203], 0
	v_mfma_f32_16x16x32_bf16 v[0:3], v[176:179], v[210:213], 0
	v_mfma_f32_16x16x32_bf16 v[52:55], v[172:175], v[188:191], v[52:55]
	v_mfma_f32_16x16x32_bf16 v[36:39], v[172:175], v[196:199], v[36:39]
	v_mfma_f32_16x16x32_bf16 v[48:51], v[180:183], v[188:191], v[48:51]
	v_mfma_f32_16x16x32_bf16 v[32:35], v[180:183], v[196:199], v[32:35]
	v_mfma_f32_16x16x32_bf16 v[20:23], v[172:175], v[206:209], v[20:23]
	v_mfma_f32_16x16x32_bf16 v[4:7], v[172:175], v[214:217], v[4:7]
	v_lshl_add_u64 v[224:225], s[42:43], 0, v[130:131]
	s_mov_b32 m0, s37
	s_nop 0
	global_load_lds_dwordx4 v[224:225], off
	v_mfma_f32_16x16x32_bf16 v[16:19], v[180:183], v[206:209], v[16:19]
	v_mfma_f32_16x16x32_bf16 v[0:3], v[180:183], v[214:217], v[0:3]
	s_setprio 0
	s_barrier
	s_add_i32 s58, 0, 0x18000
	v_add_u32_e32 v159, s58, v153
	s_add_i32 s59, 0, 0x1c000
	ds_read_b128 v[144:147], v159
	ds_read_b128 v[148:151], v159 offset:1024
	ds_read_b128 v[160:163], v159 offset:2048
	ds_read_b128 v[164:167], v159 offset:3072
	v_add_u32_e32 v159, s59, v153
	ds_read_b128 v[168:171], v159
	ds_read_b128 v[172:175], v159 offset:1024
	ds_read_b128 v[176:179], v159 offset:2048
	ds_read_b128 v[180:183], v159 offset:3072
	s_add_u32 s42, s42, 0x40000
	s_addc_u32 s43, s43, 0
	s_mov_b32 m0, s44
	v_lshl_add_u64 v[226:227], s[42:43], 0, v[134:135]
	ds_read_b128 v[184:187], v157 offset:32768
	ds_read_b128 v[188:191], v157 offset:33792
	ds_read_b128 v[192:195], v157 offset:34816
	ds_read_b128 v[196:199], v157 offset:35840
	ds_read_b128 v[200:203], v157 offset:36864
	ds_read_b128 v[206:209], v157 offset:37888
	ds_read_b128 v[210:213], v157 offset:38912
	ds_read_b128 v[214:217], v157 offset:39936
	global_load_lds_dwordx4 v[226:227], off
	v_lshl_add_u64 v[226:227], s[42:43], 0, v[130:131]
	s_mov_b32 m0, s45
	s_nop 0
	global_load_lds_dwordx4 v[226:227], off
	s_waitcnt vmcnt(8)
	s_waitcnt lgkmcnt(0)
	s_barrier
	s_setprio 1
	s_waitcnt lgkmcnt(0)
	v_mfma_f32_16x16x32_bf16 v[124:127], v[144:147], v[184:187], v[124:127]
	v_mfma_f32_16x16x32_bf16 v[108:111], v[144:147], v[192:195], v[108:111]
	v_mfma_f32_16x16x32_bf16 v[120:123], v[160:163], v[184:187], v[120:123]
	v_mfma_f32_16x16x32_bf16 v[104:107], v[160:163], v[192:195], v[104:107]
	v_mfma_f32_16x16x32_bf16 v[92:95], v[144:147], v[200:203], v[92:95]
	v_mfma_f32_16x16x32_bf16 v[76:79], v[144:147], v[210:213], v[76:79]
	v_mfma_f32_16x16x32_bf16 v[88:91], v[160:163], v[200:203], v[88:91]
	v_mfma_f32_16x16x32_bf16 v[72:75], v[160:163], v[210:213], v[72:75]
	v_mfma_f32_16x16x32_bf16 v[124:127], v[148:151], v[188:191], v[124:127]
	v_mfma_f32_16x16x32_bf16 v[108:111], v[148:151], v[196:199], v[108:111]
	v_mfma_f32_16x16x32_bf16 v[120:123], v[164:167], v[188:191], v[120:123]
	v_mfma_f32_16x16x32_bf16 v[104:107], v[164:167], v[196:199], v[104:107]
	v_mfma_f32_16x16x32_bf16 v[92:95], v[148:151], v[206:209], v[92:95]
	v_mfma_f32_16x16x32_bf16 v[76:79], v[148:151], v[214:217], v[76:79]
	v_mfma_f32_16x16x32_bf16 v[88:91], v[164:167], v[206:209], v[88:91]
	v_mfma_f32_16x16x32_bf16 v[72:75], v[164:167], v[214:217], v[72:75]
	s_setprio 0
	s_setprio 1
	v_mfma_f32_16x16x32_bf16 v[116:119], v[168:171], v[184:187], v[116:119]
	v_mfma_f32_16x16x32_bf16 v[100:103], v[168:171], v[192:195], v[100:103]
	v_mfma_f32_16x16x32_bf16 v[112:115], v[176:179], v[184:187], v[112:115]
	v_mfma_f32_16x16x32_bf16 v[96:99], v[176:179], v[192:195], v[96:99]
	v_mfma_f32_16x16x32_bf16 v[84:87], v[168:171], v[200:203], v[84:87]
	v_mfma_f32_16x16x32_bf16 v[68:71], v[168:171], v[210:213], v[68:71]
	v_mfma_f32_16x16x32_bf16 v[80:83], v[176:179], v[200:203], v[80:83]
	v_mfma_f32_16x16x32_bf16 v[64:67], v[176:179], v[210:213], v[64:67]
	v_mfma_f32_16x16x32_bf16 v[116:119], v[172:175], v[188:191], v[116:119]
	v_mfma_f32_16x16x32_bf16 v[100:103], v[172:175], v[196:199], v[100:103]
	v_mfma_f32_16x16x32_bf16 v[112:115], v[180:183], v[188:191], v[112:115]
	v_mfma_f32_16x16x32_bf16 v[96:99], v[180:183], v[196:199], v[96:99]
	v_mfma_f32_16x16x32_bf16 v[84:87], v[172:175], v[206:209], v[84:87]
	v_mfma_f32_16x16x32_bf16 v[68:71], v[172:175], v[214:217], v[68:71]
	v_mfma_f32_16x16x32_bf16 v[80:83], v[180:183], v[206:209], v[80:83]
	v_mfma_f32_16x16x32_bf16 v[64:67], v[180:183], v[214:217], v[64:67]
	s_setprio 0
	s_barrier
; #define PG8_STAGE(bufoff, gbase, voff) do { _Pragma("unroll") for (int _i = 0; _i < 2; ++_i) \
;         __builtin_amdgcn_global_load_lds((const unsigned*)((const char*)(gbase) + (voff)[_i]), (PG8_LAS unsigned*)(lds + (bufoff) + ldsw + _i * 8192), 16, 0, 0); } while (0)
; #define PG8_LDA(dst, b, h) do { _Pragma("unroll") for (int m = 0; m < 4; ++m) _Pragma("unroll") for (int k = 0; k < 2; ++k) dst[m][k] = *(const PG8_LAS bf16x8*)(lds + PG8_SA(b, h) + aoff + m * 2048 + k * 1024); } while (0)
; #define PG8_LDB(dst, b, h) do { _Pragma("unroll") for (int n = 0; n < 2; ++n) _Pragma("unroll") for (int k = 0; k < 2; ++k) dst[n][k] = *(const PG8_LAS bf16x8*)(lds + PG8_SB(b, h) + boff + n * 2048 + k * 1024); } while (0)
; #define PG8_MMA(ai, bj, At, Bt) do { __builtin_amdgcn_s_setprio(1); _Pragma("unroll") for (int m = 0; m < 4; ++m) _Pragma("unroll") for (int n = 0; n < 2; ++n) _Pragma("unroll") for (int k = 0; k < 2; ++k) \
;         acc[ai][bj][m][n] = __builtin_amdgcn_mfma_f32_16x16x32_bf16(Bt[n][k], At[m][k], acc[ai][bj][m][n], 0, 0, 0); __builtin_amdgcn_s_setprio(0); } while (0)
; #define PG8_WAIT_V(n) asm volatile("s_waitcnt vmcnt(" #n ")" ::: "memory")
; template <class Epi, class Sched, bool ALIGN_EPI = false, bool SP2 = false>
; __device__ __forceinline__ void gemm_phase(PG8_LAS unsigned char* lds, const Gemm g, const Sched& S, const Epi& E) {
;     ...
;             PG8_LDB(B0, 0, 0); PG8_LDB(B1, 0, 1); PG8_SCHED; PG8_LDA(At, 0, 0); PG8_STAGE(PG8_SA(1, 1), a1 + hstep, voffA);
;             PG8_WAIT_V(8); PG8_WAIT_L(0); PG8_BAR; PG8_MMA(0, 0, At, B0); PG8_MMA(0, 1, At, B1); PG8_BAR; PG8_SCHED;
;             PG8_LDA(At, 0, 1); PG8_STAGE(PG8_SB(0, 0), b2, voffB); PG8_STAGE(PG8_SB(0, 1), b2 + hstep, voffB); PG8_STAGE(PG8_SA(0, 0), a2, voffA);
;             PG8_WAIT_V(8); PG8_WAIT_L(0); PG8_BAR; PG8_MMA(1, 0, At, B0); PG8_MMA(1, 1, At, B1); PG8_BAR; PG8_SCHED;
;             PG8_LDB(B0, 1, 0); PG8_LDB(B1, 1, 1); PG8_SCHED; PG8_LDA(At, 1, 0); PG8_STAGE(PG8_SA(0, 1), a2 + hstep, voffA);
;             PG8_WAIT_V(8); PG8_WAIT_L(0); PG8_BAR; PG8_MMA(0, 0, At, B0); PG8_MMA(0, 1, At, B1); PG8_BAR; PG8_SCHED;
;             PG8_LDA(At, 1, 1); PG8_STAGE(PG8_SB(1, 0), b3, voffB); PG8_STAGE(PG8_SB(1, 1), b3 + hstep, voffB); PG8_STAGE(PG8_SA(1, 0), a3, voffA);
;             PG8_WAIT_V(8); PG8_WAIT_L(0); PG8_BAR; PG8_MMA(1, 0, At, B0); PG8_MMA(1, 1, At, B1); PG8_BAR; PG8_SCHED;
	s_add_i32 s42, s58, s15
	v_lshl_add_u64 v[218:219], v[218:219], 0, s[8:9]
	s_mov_b32 m0, s42
	ds_read_b128 v[184:187], v157 offset:49152
	ds_read_b128 v[188:191], v157 offset:50176
	ds_read_b128 v[192:195], v157 offset:51200
	ds_read_b128 v[196:199], v157 offset:52224
	ds_read_b128 v[200:203], v157 offset:53248
	ds_read_b128 v[206:209], v157 offset:54272
	ds_read_b128 v[210:213], v157 offset:55296
	ds_read_b128 v[214:217], v157 offset:56320
	global_load_lds_dwordx4 v[218:219], off
	s_add_i32 m0, s42, 0x2000
	s_add_u32 s40, s40, 0x40080
	v_lshl_add_u64 v[218:219], v[220:221], 0, s[8:9]
	s_addc_u32 s41, s41, 0
	s_add_i32 s42, s59, s15
	global_load_lds_dwordx4 v[218:219], off
	v_lshl_add_u64 v[218:219], s[40:41], 0, v[132:133]
	s_mov_b32 m0, s42
	s_nop 0
	global_load_lds_dwordx4 v[218:219], off
	v_lshl_add_u64 v[218:219], s[40:41], 0, v[128:129]
	s_add_i32 m0, s42, 0x2000
	s_nop 0
	global_load_lds_dwordx4 v[218:219], off
	s_waitcnt vmcnt(6)
	s_waitcnt lgkmcnt(0)
	s_barrier
	s_setprio 1
	s_waitcnt lgkmcnt(0)
	v_mfma_f32_16x16x32_bf16 v[60:63], v[144:147], v[184:187], v[60:63]
	v_mfma_f32_16x16x32_bf16 v[44:47], v[144:147], v[192:195], v[44:47]
	v_mfma_f32_16x16x32_bf16 v[56:59], v[160:163], v[184:187], v[56:59]
	v_mfma_f32_16x16x32_bf16 v[40:43], v[160:163], v[192:195], v[40:43]
	v_mfma_f32_16x16x32_bf16 v[28:31], v[144:147], v[200:203], v[28:31]
	v_mfma_f32_16x16x32_bf16 v[12:15], v[144:147], v[210:213], v[12:15]
	v_mfma_f32_16x16x32_bf16 v[24:27], v[160:163], v[200:203], v[24:27]
	v_mfma_f32_16x16x32_bf16 v[8:11], v[160:163], v[210:213], v[8:11]
	v_mfma_f32_16x16x32_bf16 v[60:63], v[148:151], v[188:191], v[60:63]
	v_mfma_f32_16x16x32_bf16 v[44:47], v[148:151], v[196:199], v[44:47]
	v_mfma_f32_16x16x32_bf16 v[56:59], v[164:167], v[188:191], v[56:59]
	v_mfma_f32_16x16x32_bf16 v[40:43], v[164:167], v[196:199], v[40:43]
	v_mfma_f32_16x16x32_bf16 v[28:31], v[148:151], v[206:209], v[28:31]
	v_mfma_f32_16x16x32_bf16 v[12:15], v[148:151], v[214:217], v[12:15]
	v_lshl_add_u64 v[218:219], v[222:223], 0, s[8:9]
	s_mov_b32 m0, s47
	s_nop 0
	global_load_lds_dwordx4 v[218:219], off
	v_mfma_f32_16x16x32_bf16 v[24:27], v[164:167], v[206:209], v[24:27]
	v_mfma_f32_16x16x32_bf16 v[8:11], v[164:167], v[214:217], v[8:11]
	s_setprio 0
	s_setprio 1
	v_mfma_f32_16x16x32_bf16 v[52:55], v[168:171], v[184:187], v[52:55]
	v_mfma_f32_16x16x32_bf16 v[36:39], v[168:171], v[192:195], v[36:39]
	v_mfma_f32_16x16x32_bf16 v[48:51], v[176:179], v[184:187], v[48:51]
	v_mfma_f32_16x16x32_bf16 v[32:35], v[176:179], v[192:195], v[32:35]
	v_mfma_f32_16x16x32_bf16 v[20:23], v[168:171], v[200:203], v[20:23]
	v_mfma_f32_16x16x32_bf16 v[4:7], v[168:171], v[210:213], v[4:7]
	v_mfma_f32_16x16x32_bf16 v[16:19], v[176:179], v[200:203], v[16:19]
	v_mfma_f32_16x16x32_bf16 v[0:3], v[176:179], v[210:213], v[0:3]
	v_mfma_f32_16x16x32_bf16 v[52:55], v[172:175], v[188:191], v[52:55]
	v_mfma_f32_16x16x32_bf16 v[36:39], v[172:175], v[196:199], v[36:39]
	v_mfma_f32_16x16x32_bf16 v[48:51], v[180:183], v[188:191], v[48:51]
	v_mfma_f32_16x16x32_bf16 v[32:35], v[180:183], v[196:199], v[32:35]
	v_mfma_f32_16x16x32_bf16 v[20:23], v[172:175], v[206:209], v[20:23]
	v_mfma_f32_16x16x32_bf16 v[4:7], v[172:175], v[214:217], v[4:7]
	v_lshl_add_u64 v[218:219], v[224:225], 0, s[8:9]
	s_mov_b32 m0, s48
	s_nop 0
	global_load_lds_dwordx4 v[218:219], off
	v_mfma_f32_16x16x32_bf16 v[16:19], v[180:183], v[206:209], v[16:19]
	v_mfma_f32_16x16x32_bf16 v[0:3], v[180:183], v[214:217], v[0:3]
	s_setprio 0
	s_barrier
	s_add_i32 s57, s57, 2
	s_add_u32 s38, s38, 0x100
	s_addc_u32 s39, s39, 0
	s_add_u32 s55, s55, 0x100
	s_addc_u32 s56, s56, 0
.LBB0_1900:
	ds_read_b128 v[144:147], v155
	ds_read_b128 v[148:151], v155 offset:1024
	ds_read_b128 v[160:163], v155 offset:2048
	ds_read_b128 v[164:167], v155 offset:3072
	ds_read_b128 v[168:171], v156
	ds_read_b128 v[172:175], v156 offset:1024
	ds_read_b128 v[176:179], v156 offset:2048
	ds_read_b128 v[180:183], v156 offset:3072
	s_add_u32 s40, s38, 0xfffc0080
	s_addc_u32 s41, s39, -1
	s_cmp_eq_u32 s57, 12
	s_cselect_b32 s43, s25, s41
	s_cselect_b32 s42, s53, s40
	s_cselect_b32 s41, s13, s56
	s_cselect_b32 s40, s54, s55
	v_lshl_add_u64 v[218:219], s[38:39], 0, v[136:137]
	s_add_i32 m0, s34, 0xc000
	ds_read_b128 v[184:187], v157
	ds_read_b128 v[188:191], v157 offset:1024
	ds_read_b128 v[192:195], v157 offset:2048
	ds_read_b128 v[196:199], v157 offset:3072
	ds_read_b128 v[200:203], v157 offset:4096
	ds_read_b128 v[206:209], v157 offset:5120
	ds_read_b128 v[210:213], v157 offset:6144
	ds_read_b128 v[214:217], v157 offset:7168
	global_load_lds_dwordx4 v[218:219], off
	v_lshl_add_u64 v[218:219], s[38:39], 0, v[138:139]
	s_add_i32 m0, s34, 0xe000
	s_nop 0
	global_load_lds_dwordx4 v[218:219], off
	s_waitcnt vmcnt(8)
	s_waitcnt lgkmcnt(0)
	s_barrier
; #define PG8_STAGE(bufoff, gbase, voff) do { _Pragma("unroll") for (int _i = 0; _i < 2; ++_i) \
;         __builtin_amdgcn_global_load_lds((const unsigned*)((const char*)(gbase) + (voff)[_i]), (PG8_LAS unsigned*)(lds + (bufoff) + ldsw + _i * 8192), 16, 0, 0); } while (0)
; #define PG8_LDA(dst, b, h) do { _Pragma("unroll") for (int m = 0; m < 4; ++m) _Pragma("unroll") for (int k = 0; k < 2; ++k) dst[m][k] = *(const PG8_LAS bf16x8*)(lds + PG8_SA(b, h) + aoff + m * 2048 + k * 1024); } while (0)
; #define PG8_MMA(ai, bj, At, Bt) do { __builtin_amdgcn_s_setprio(1); _Pragma("unroll") for (int m = 0; m < 4; ++m) _Pragma("unroll") for (int n = 0; n < 2; ++n) _Pragma("unroll") for (int k = 0; k < 2; ++k) \
;         acc[ai][bj][m][n] = __builtin_amdgcn_mfma_f32_16x16x32_bf16(Bt[n][k], At[m][k], acc[ai][bj][m][n], 0, 0, 0); __builtin_amdgcn_s_setprio(0); } while (0)
; #define PG8_WAIT_V(n) asm volatile("s_waitcnt vmcnt(" #n ")" ::: "memory")
; #define PG8_WAIT_L(n) asm volatile("s_waitcnt lgkmcnt(" #n ")" ::: "memory")
; #define PG8_BAR __builtin_amdgcn_s_barrier()
; #define PG8_SCHED __builtin_amdgcn_sched_barrier(0)
; template <class Epi, class Sched, bool ALIGN_EPI = false, bool SP2 = false>
; __device__ __forceinline__ void gemm_phase(PG8_LAS unsigned char* lds, const Gemm g, const Sched& S, const Epi& E) {
;     ...
;             PG8_WAIT_V(8); PG8_WAIT_L(0); PG8_BAR; PG8_MMA(0, 0, At, B0); PG8_MMA(0, 1, At, B1); PG8_BAR; PG8_SCHED;
;             PG8_LDA(At, 0, 1); PG8_STAGE(PG8_SB(0, 0), b2, voffB); PG8_STAGE(PG8_SB(0, 1), b2 + hstep, voffB); PG8_STAGE(PG8_SA(0, 0), a2, voffA);
;             PG8_WAIT_V(8); PG8_WAIT_L(0); PG8_BAR; PG8_MMA(1, 0, At, B0); PG8_MMA(1, 1, At, B1); PG8_BAR; PG8_SCHED;
	s_setprio 1
	s_waitcnt lgkmcnt(0)
	v_mfma_f32_16x16x32_bf16 v[124:127], v[144:147], v[184:187], v[124:127]
	v_mfma_f32_16x16x32_bf16 v[108:111], v[144:147], v[192:195], v[108:111]
	v_mfma_f32_16x16x32_bf16 v[120:123], v[160:163], v[184:187], v[120:123]
	v_mfma_f32_16x16x32_bf16 v[104:107], v[160:163], v[192:195], v[104:107]
	v_mfma_f32_16x16x32_bf16 v[92:95], v[144:147], v[200:203], v[92:95]
	v_mfma_f32_16x16x32_bf16 v[76:79], v[144:147], v[210:213], v[76:79]
	v_mfma_f32_16x16x32_bf16 v[88:91], v[160:163], v[200:203], v[88:91]
	v_mfma_f32_16x16x32_bf16 v[72:75], v[160:163], v[210:213], v[72:75]
	v_mfma_f32_16x16x32_bf16 v[124:127], v[148:151], v[188:191], v[124:127]
	v_mfma_f32_16x16x32_bf16 v[108:111], v[148:151], v[196:199], v[108:111]
	v_mfma_f32_16x16x32_bf16 v[120:123], v[164:167], v[188:191], v[120:123]
	v_mfma_f32_16x16x32_bf16 v[104:107], v[164:167], v[196:199], v[104:107]
	v_mfma_f32_16x16x32_bf16 v[92:95], v[148:151], v[206:209], v[92:95]
	v_mfma_f32_16x16x32_bf16 v[76:79], v[148:151], v[214:217], v[76:79]
	v_mfma_f32_16x16x32_bf16 v[88:91], v[164:167], v[206:209], v[88:91]
	v_mfma_f32_16x16x32_bf16 v[72:75], v[164:167], v[214:217], v[72:75]
	s_setprio 0
	s_setprio 1
	v_mfma_f32_16x16x32_bf16 v[116:119], v[168:171], v[184:187], v[116:119]
	v_mfma_f32_16x16x32_bf16 v[100:103], v[168:171], v[192:195], v[100:103]
	v_mfma_f32_16x16x32_bf16 v[112:115], v[176:179], v[184:187], v[112:115]
	v_mfma_f32_16x16x32_bf16 v[96:99], v[176:179], v[192:195], v[96:99]
	v_mfma_f32_16x16x32_bf16 v[84:87], v[168:171], v[200:203], v[84:87]
	v_mfma_f32_16x16x32_bf16 v[68:71], v[168:171], v[210:213], v[68:71]
	v_mfma_f32_16x16x32_bf16 v[80:83], v[176:179], v[200:203], v[80:83]
	v_mfma_f32_16x16x32_bf16 v[64:67], v[176:179], v[210:213], v[64:67]
	v_mfma_f32_16x16x32_bf16 v[116:119], v[172:175], v[188:191], v[116:119]
	v_mfma_f32_16x16x32_bf16 v[100:103], v[172:175], v[196:199], v[100:103]
	v_mfma_f32_16x16x32_bf16 v[112:115], v[180:183], v[188:191], v[112:115]
	v_mfma_f32_16x16x32_bf16 v[96:99], v[180:183], v[196:199], v[96:99]
	v_mfma_f32_16x16x32_bf16 v[84:87], v[172:175], v[206:209], v[84:87]
	v_mfma_f32_16x16x32_bf16 v[68:71], v[172:175], v[214:217], v[68:71]
	v_mfma_f32_16x16x32_bf16 v[80:83], v[180:183], v[206:209], v[80:83]
	v_mfma_f32_16x16x32_bf16 v[64:67], v[180:183], v[214:217], v[64:67]
	s_setprio 0
	s_barrier
	s_add_i32 s58, s49, s15
	v_lshl_add_u64 v[218:219], s[40:41], 0, v[132:133]
	s_mov_b32 m0, s58
	ds_read_b128 v[184:187], v157 offset:16384
	ds_read_b128 v[188:191], v157 offset:17408
	ds_read_b128 v[192:195], v157 offset:18432
	ds_read_b128 v[196:199], v157 offset:19456
	ds_read_b128 v[200:203], v157 offset:20480
	ds_read_b128 v[206:209], v157 offset:21504
	ds_read_b128 v[210:213], v157 offset:22528
	ds_read_b128 v[214:217], v157 offset:23552
	global_load_lds_dwordx4 v[218:219], off
	s_add_i32 m0, s58, 0x2000
	s_add_u32 s58, s40, 0x40000
	v_lshl_add_u64 v[220:221], s[40:41], 0, v[128:129]
	s_addc_u32 s59, s41, 0
	s_add_i32 s60, s50, s15
	global_load_lds_dwordx4 v[220:221], off
	v_lshl_add_u64 v[222:223], s[58:59], 0, v[132:133]
	s_mov_b32 m0, s60
	global_load_lds_dwordx4 v[222:223], off
	v_lshl_add_u64 v[222:223], s[58:59], 0, v[128:129]
	s_add_i32 m0, s60, 0x2000
	s_nop 0
	global_load_lds_dwordx4 v[222:223], off
	s_waitcnt vmcnt(6)
	s_waitcnt lgkmcnt(0)
	s_barrier
	s_setprio 1
	s_waitcnt lgkmcnt(0)
	v_mfma_f32_16x16x32_bf16 v[60:63], v[144:147], v[184:187], v[60:63]
	v_mfma_f32_16x16x32_bf16 v[44:47], v[144:147], v[192:195], v[44:47]
	v_mfma_f32_16x16x32_bf16 v[56:59], v[160:163], v[184:187], v[56:59]
	v_mfma_f32_16x16x32_bf16 v[40:43], v[160:163], v[192:195], v[40:43]
	v_mfma_f32_16x16x32_bf16 v[28:31], v[144:147], v[200:203], v[28:31]
	v_mfma_f32_16x16x32_bf16 v[12:15], v[144:147], v[210:213], v[12:15]
	v_mfma_f32_16x16x32_bf16 v[24:27], v[160:163], v[200:203], v[24:27]
	v_mfma_f32_16x16x32_bf16 v[8:11], v[160:163], v[210:213], v[8:11]
	v_mfma_f32_16x16x32_bf16 v[60:63], v[148:151], v[188:191], v[60:63]
	v_mfma_f32_16x16x32_bf16 v[44:47], v[148:151], v[196:199], v[44:47]
	v_mfma_f32_16x16x32_bf16 v[56:59], v[164:167], v[188:191], v[56:59]
	v_mfma_f32_16x16x32_bf16 v[40:43], v[164:167], v[196:199], v[40:43]
	v_mfma_f32_16x16x32_bf16 v[28:31], v[148:151], v[206:209], v[28:31]
	v_mfma_f32_16x16x32_bf16 v[12:15], v[148:151], v[214:217], v[12:15]
	v_lshl_add_u64 v[222:223], s[42:43], 0, v[134:135]
	s_mov_b32 m0, s34
	s_nop 0
	global_load_lds_dwordx4 v[222:223], off
	v_mfma_f32_16x16x32_bf16 v[24:27], v[164:167], v[206:209], v[24:27]
	v_mfma_f32_16x16x32_bf16 v[8:11], v[164:167], v[214:217], v[8:11]
	s_setprio 0
	s_setprio 1
	v_mfma_f32_16x16x32_bf16 v[52:55], v[168:171], v[184:187], v[52:55]
	v_mfma_f32_16x16x32_bf16 v[36:39], v[168:171], v[192:195], v[36:39]
	v_mfma_f32_16x16x32_bf16 v[48:51], v[176:179], v[184:187], v[48:51]
	v_mfma_f32_16x16x32_bf16 v[32:35], v[176:179], v[192:195], v[32:35]
	v_mfma_f32_16x16x32_bf16 v[20:23], v[168:171], v[200:203], v[20:23]
	v_mfma_f32_16x16x32_bf16 v[4:7], v[168:171], v[210:213], v[4:7]
	v_mfma_f32_16x16x32_bf16 v[16:19], v[176:179], v[200:203], v[16:19]
	v_mfma_f32_16x16x32_bf16 v[0:3], v[176:179], v[210:213], v[0:3]
	v_mfma_f32_16x16x32_bf16 v[52:55], v[172:175], v[188:191], v[52:55]
	v_mfma_f32_16x16x32_bf16 v[36:39], v[172:175], v[196:199], v[36:39]
	v_mfma_f32_16x16x32_bf16 v[48:51], v[180:183], v[188:191], v[48:51]
	v_mfma_f32_16x16x32_bf16 v[32:35], v[180:183], v[196:199], v[32:35]
	v_mfma_f32_16x16x32_bf16 v[20:23], v[172:175], v[206:209], v[20:23]
	v_mfma_f32_16x16x32_bf16 v[4:7], v[172:175], v[214:217], v[4:7]
	v_lshl_add_u64 v[224:225], s[42:43], 0, v[130:131]
	s_mov_b32 m0, s37
	s_nop 0
	global_load_lds_dwordx4 v[224:225], off
	v_mfma_f32_16x16x32_bf16 v[16:19], v[180:183], v[206:209], v[16:19]
	v_mfma_f32_16x16x32_bf16 v[0:3], v[180:183], v[214:217], v[0:3]
	s_setprio 0
	s_barrier
; #define PG8_STAGE(bufoff, gbase, voff) do { _Pragma("unroll") for (int _i = 0; _i < 2; ++_i) \
;         __builtin_amdgcn_global_load_lds((const unsigned*)((const char*)(gbase) + (voff)[_i]), (PG8_LAS unsigned*)(lds + (bufoff) + ldsw + _i * 8192), 16, 0, 0); } while (0)
; #define PG8_LDA(dst, b, h) do { _Pragma("unroll") for (int m = 0; m < 4; ++m) _Pragma("unroll") for (int k = 0; k < 2; ++k) dst[m][k] = *(const PG8_LAS bf16x8*)(lds + PG8_SA(b, h) + aoff + m * 2048 + k * 1024); } while (0)
; #define PG8_LDB(dst, b, h) do { _Pragma("unroll") for (int n = 0; n < 2; ++n) _Pragma("unroll") for (int k = 0; k < 2; ++k) dst[n][k] = *(const PG8_LAS bf16x8*)(lds + PG8_SB(b, h) + boff + n * 2048 + k * 1024); } while (0)
; #define PG8_MMA(ai, bj, At, Bt) do { __builtin_amdgcn_s_setprio(1); _Pragma("unroll") for (int m = 0; m < 4; ++m) _Pragma("unroll") for (int n = 0; n < 2; ++n) _Pragma("unroll") for (int k = 0; k < 2; ++k) \
;         acc[ai][bj][m][n] = __builtin_amdgcn_mfma_f32_16x16x32_bf16(Bt[n][k], At[m][k], acc[ai][bj][m][n], 0, 0, 0); __builtin_amdgcn_s_setprio(0); } while (0)
; #define PG8_WAIT_V(n) asm volatile("s_waitcnt vmcnt(" #n ")" ::: "memory")
; #define PG8_WAIT_L(n) asm volatile("s_waitcnt lgkmcnt(" #n ")" ::: "memory")
; #define PG8_BAR __builtin_amdgcn_s_barrier()
; #define PG8_SCHED __builtin_amdgcn_sched_barrier(0)
; template <class Epi, class Sched, bool ALIGN_EPI = false, bool SP2 = false>
; __device__ __forceinline__ void gemm_phase(PG8_LAS unsigned char* lds, const Gemm g, const Sched& S, const Epi& E) {
;     ...
;             PG8_LDB(B0, 1, 0); PG8_LDB(B1, 1, 1); PG8_SCHED; PG8_LDA(At, 1, 0); PG8_STAGE(PG8_SA(0, 1), a2 + hstep, voffA);
;             PG8_WAIT_V(8); PG8_WAIT_L(0); PG8_BAR; PG8_MMA(0, 0, At, B0); PG8_MMA(0, 1, At, B1); PG8_BAR; PG8_SCHED;
	s_add_i32 s58, 0, 0x18000
	v_add_u32_e32 v159, s58, v153
	s_add_i32 s59, 0, 0x1c000
	ds_read_b128 v[144:147], v159
	ds_read_b128 v[148:151], v159 offset:1024
	ds_read_b128 v[160:163], v159 offset:2048
	ds_read_b128 v[164:167], v159 offset:3072
	v_add_u32_e32 v159, s59, v153
	ds_read_b128 v[168:171], v159
	ds_read_b128 v[172:175], v159 offset:1024
	ds_read_b128 v[176:179], v159 offset:2048
	ds_read_b128 v[180:183], v159 offset:3072
	s_add_u32 s42, s42, 0x40000
	s_addc_u32 s43, s43, 0
	s_mov_b32 m0, s44
	v_lshl_add_u64 v[226:227], s[42:43], 0, v[134:135]
	ds_read_b128 v[184:187], v157 offset:32768
	ds_read_b128 v[188:191], v157 offset:33792
	ds_read_b128 v[192:195], v157 offset:34816
	ds_read_b128 v[196:199], v157 offset:35840
	ds_read_b128 v[200:203], v157 offset:36864
	ds_read_b128 v[206:209], v157 offset:37888
	ds_read_b128 v[210:213], v157 offset:38912
	ds_read_b128 v[214:217], v157 offset:39936
	global_load_lds_dwordx4 v[226:227], off
	v_lshl_add_u64 v[226:227], s[42:43], 0, v[130:131]
	s_mov_b32 m0, s45
	s_nop 0
	global_load_lds_dwordx4 v[226:227], off
	s_waitcnt vmcnt(8)
	s_waitcnt lgkmcnt(0)
	s_barrier
	s_setprio 1
	s_waitcnt lgkmcnt(0)
	v_mfma_f32_16x16x32_bf16 v[124:127], v[144:147], v[184:187], v[124:127]
	v_mfma_f32_16x16x32_bf16 v[108:111], v[144:147], v[192:195], v[108:111]
	v_mfma_f32_16x16x32_bf16 v[120:123], v[160:163], v[184:187], v[120:123]
	v_mfma_f32_16x16x32_bf16 v[104:107], v[160:163], v[192:195], v[104:107]
	v_mfma_f32_16x16x32_bf16 v[92:95], v[144:147], v[200:203], v[92:95]
	v_mfma_f32_16x16x32_bf16 v[76:79], v[144:147], v[210:213], v[76:79]
	v_mfma_f32_16x16x32_bf16 v[88:91], v[160:163], v[200:203], v[88:91]
	v_mfma_f32_16x16x32_bf16 v[72:75], v[160:163], v[210:213], v[72:75]
	v_mfma_f32_16x16x32_bf16 v[124:127], v[148:151], v[188:191], v[124:127]
	v_mfma_f32_16x16x32_bf16 v[108:111], v[148:151], v[196:199], v[108:111]
	v_mfma_f32_16x16x32_bf16 v[120:123], v[164:167], v[188:191], v[120:123]
	v_mfma_f32_16x16x32_bf16 v[104:107], v[164:167], v[196:199], v[104:107]
	v_mfma_f32_16x16x32_bf16 v[92:95], v[148:151], v[206:209], v[92:95]
	v_mfma_f32_16x16x32_bf16 v[76:79], v[148:151], v[214:217], v[76:79]
	v_mfma_f32_16x16x32_bf16 v[88:91], v[164:167], v[206:209], v[88:91]
	v_mfma_f32_16x16x32_bf16 v[72:75], v[164:167], v[214:217], v[72:75]
	s_setprio 0
	s_setprio 1
	v_mfma_f32_16x16x32_bf16 v[116:119], v[168:171], v[184:187], v[116:119]
	v_mfma_f32_16x16x32_bf16 v[100:103], v[168:171], v[192:195], v[100:103]
	v_mfma_f32_16x16x32_bf16 v[112:115], v[176:179], v[184:187], v[112:115]
	v_mfma_f32_16x16x32_bf16 v[96:99], v[176:179], v[192:195], v[96:99]
	v_mfma_f32_16x16x32_bf16 v[84:87], v[168:171], v[200:203], v[84:87]
	v_mfma_f32_16x16x32_bf16 v[68:71], v[168:171], v[210:213], v[68:71]
	v_mfma_f32_16x16x32_bf16 v[80:83], v[176:179], v[200:203], v[80:83]
	v_mfma_f32_16x16x32_bf16 v[64:67], v[176:179], v[210:213], v[64:67]
	v_mfma_f32_16x16x32_bf16 v[116:119], v[172:175], v[188:191], v[116:119]
	v_mfma_f32_16x16x32_bf16 v[100:103], v[172:175], v[196:199], v[100:103]
	v_mfma_f32_16x16x32_bf16 v[112:115], v[180:183], v[188:191], v[112:115]
	v_mfma_f32_16x16x32_bf16 v[96:99], v[180:183], v[196:199], v[96:99]
	v_mfma_f32_16x16x32_bf16 v[84:87], v[172:175], v[206:209], v[84:87]
	v_mfma_f32_16x16x32_bf16 v[68:71], v[172:175], v[214:217], v[68:71]
	v_mfma_f32_16x16x32_bf16 v[80:83], v[180:183], v[206:209], v[80:83]
	v_mfma_f32_16x16x32_bf16 v[64:67], v[180:183], v[214:217], v[64:67]
	s_setprio 0
	s_barrier
; #define PG8_STAGE(bufoff, gbase, voff) do { _Pragma("unroll") for (int _i = 0; _i < 2; ++_i) \
;         __builtin_amdgcn_global_load_lds((const unsigned*)((const char*)(gbase) + (voff)[_i]), (PG8_LAS unsigned*)(lds + (bufoff) + ldsw + _i * 8192), 16, 0, 0); } while (0)
; #define PG8_LDA(dst, b, h) do { _Pragma("unroll") for (int m = 0; m < 4; ++m) _Pragma("unroll") for (int k = 0; k < 2; ++k) dst[m][k] = *(const PG8_LAS bf16x8*)(lds + PG8_SA(b, h) + aoff + m * 2048 + k * 1024); } while (0)
; #define PG8_MMA(ai, bj, At, Bt) do { __builtin_amdgcn_s_setprio(1); _Pragma("unroll") for (int m = 0; m < 4; ++m) _Pragma("unroll") for (int n = 0; n < 2; ++n) _Pragma("unroll") for (int k = 0; k < 2; ++k) \
;         acc[ai][bj][m][n] = __builtin_amdgcn_mfma_f32_16x16x32_bf16(Bt[n][k], At[m][k], acc[ai][bj][m][n], 0, 0, 0); __builtin_amdgcn_s_setprio(0); } while (0)
; #define PG8_WAIT_V(n) asm volatile("s_waitcnt vmcnt(" #n ")" ::: "memory")
; #define PG8_WAIT_L(n) asm volatile("s_waitcnt lgkmcnt(" #n ")" ::: "memory")
; #define PG8_BAR __builtin_amdgcn_s_barrier()
; #define PG8_SCHED __builtin_amdgcn_sched_barrier(0)
; __device__ __forceinline__ float row_rs(const float* ssp, int row) { const unsigned long long v = ((const unsigned long long*)ssp)[row];
;     return __builtin_amdgcn_rsqf((float)v * (1.0f / 4294967296.0f) * (1.0f / 1024.0f) + RMS_EPS); }
; template <class Epi, class Sched, bool ALIGN_EPI = false, bool SP2 = false>
; __device__ __forceinline__ void gemm_phase(PG8_LAS unsigned char* lds, const Gemm g, const Sched& S, const Epi& E) {
;     ...
;             PG8_LDA(At, 1, 1); PG8_STAGE(PG8_SB(1, 0), b3, voffB); PG8_STAGE(PG8_SB(1, 1), b3 + hstep, voffB); PG8_STAGE(PG8_SA(1, 0), a3, voffA);
;             PG8_WAIT_V(8); PG8_WAIT_L(0); PG8_BAR; PG8_MMA(1, 0, At, B0); PG8_MMA(1, 1, At, B1); PG8_BAR; PG8_SCHED;
	s_add_i32 s42, s58, s15
	v_lshl_add_u64 v[218:219], v[218:219], 0, s[8:9]
	s_mov_b32 m0, s42
	ds_read_b128 v[184:187], v157 offset:49152
	ds_read_b128 v[188:191], v157 offset:50176
	ds_read_b128 v[192:195], v157 offset:51200
	ds_read_b128 v[196:199], v157 offset:52224
	ds_read_b128 v[200:203], v157 offset:53248
	ds_read_b128 v[206:209], v157 offset:54272
	ds_read_b128 v[210:213], v157 offset:55296
	ds_read_b128 v[214:217], v157 offset:56320
	global_load_lds_dwordx4 v[218:219], off
	s_add_i32 m0, s42, 0x2000
	s_add_u32 s40, s40, 0x40080
	v_lshl_add_u64 v[218:219], v[220:221], 0, s[8:9]
	s_addc_u32 s41, s41, 0
	s_add_i32 s42, s59, s15
	global_load_lds_dwordx4 v[218:219], off
	v_lshl_add_u64 v[218:219], s[40:41], 0, v[132:133]
	s_mov_b32 m0, s42
	s_nop 0
	global_load_lds_dwordx4 v[218:219], off
	v_lshl_add_u64 v[218:219], s[40:41], 0, v[128:129]
	s_add_i32 m0, s42, 0x2000
	s_nop 0
	global_load_lds_dwordx4 v[218:219], off
	s_waitcnt vmcnt(6)
	s_waitcnt lgkmcnt(0)
	s_barrier
	s_setprio 1
	s_waitcnt lgkmcnt(0)
	v_mfma_f32_16x16x32_bf16 v[60:63], v[144:147], v[184:187], v[60:63]
	v_mfma_f32_16x16x32_bf16 v[44:47], v[144:147], v[192:195], v[44:47]
	v_mfma_f32_16x16x32_bf16 v[56:59], v[160:163], v[184:187], v[56:59]
	v_mfma_f32_16x16x32_bf16 v[40:43], v[160:163], v[192:195], v[40:43]
	v_mfma_f32_16x16x32_bf16 v[28:31], v[144:147], v[200:203], v[28:31]
	v_mfma_f32_16x16x32_bf16 v[12:15], v[144:147], v[210:213], v[12:15]
	v_mfma_f32_16x16x32_bf16 v[24:27], v[160:163], v[200:203], v[24:27]
	v_mfma_f32_16x16x32_bf16 v[8:11], v[160:163], v[210:213], v[8:11]
	v_mfma_f32_16x16x32_bf16 v[60:63], v[148:151], v[188:191], v[60:63]
	v_mfma_f32_16x16x32_bf16 v[44:47], v[148:151], v[196:199], v[44:47]
	v_mfma_f32_16x16x32_bf16 v[56:59], v[164:167], v[188:191], v[56:59]
	v_mfma_f32_16x16x32_bf16 v[40:43], v[164:167], v[196:199], v[40:43]
	v_mfma_f32_16x16x32_bf16 v[28:31], v[148:151], v[206:209], v[28:31]
	v_mfma_f32_16x16x32_bf16 v[12:15], v[148:151], v[214:217], v[12:15]
	v_lshl_add_u64 v[218:219], v[222:223], 0, s[8:9]
	s_mov_b32 m0, s47
	s_nop 0
	global_load_lds_dwordx4 v[218:219], off
	v_mfma_f32_16x16x32_bf16 v[24:27], v[164:167], v[206:209], v[24:27]
	v_mfma_f32_16x16x32_bf16 v[8:11], v[164:167], v[214:217], v[8:11]
	s_setprio 0
	s_setprio 1
	v_mfma_f32_16x16x32_bf16 v[52:55], v[168:171], v[184:187], v[52:55]
	v_mfma_f32_16x16x32_bf16 v[36:39], v[168:171], v[192:195], v[36:39]
	v_mfma_f32_16x16x32_bf16 v[48:51], v[176:179], v[184:187], v[48:51]
	v_mfma_f32_16x16x32_bf16 v[32:35], v[176:179], v[192:195], v[32:35]
	v_mfma_f32_16x16x32_bf16 v[20:23], v[168:171], v[200:203], v[20:23]
	v_mfma_f32_16x16x32_bf16 v[4:7], v[168:171], v[210:213], v[4:7]
	v_mfma_f32_16x16x32_bf16 v[16:19], v[176:179], v[200:203], v[16:19]
	v_mfma_f32_16x16x32_bf16 v[0:3], v[176:179], v[210:213], v[0:3]
	v_mfma_f32_16x16x32_bf16 v[52:55], v[172:175], v[188:191], v[52:55]
	v_mfma_f32_16x16x32_bf16 v[36:39], v[172:175], v[196:199], v[36:39]
	v_mfma_f32_16x16x32_bf16 v[48:51], v[180:183], v[188:191], v[48:51]
	v_mfma_f32_16x16x32_bf16 v[32:35], v[180:183], v[196:199], v[32:35]
	v_mfma_f32_16x16x32_bf16 v[20:23], v[172:175], v[206:209], v[20:23]
	v_mfma_f32_16x16x32_bf16 v[4:7], v[172:175], v[214:217], v[4:7]
	v_lshl_add_u64 v[218:219], v[224:225], 0, s[8:9]
	s_mov_b32 m0, s48
	s_nop 0
	global_load_lds_dwordx4 v[218:219], off
	v_mfma_f32_16x16x32_bf16 v[16:19], v[180:183], v[206:209], v[16:19]
	v_mfma_f32_16x16x32_bf16 v[0:3], v[180:183], v[214:217], v[0:3]
	s_setprio 0
	s_barrier
	s_add_i32 s57, s57, 2
	s_add_u32 s38, s38, 0x100
	s_addc_u32 s39, s39, 0
	s_add_u32 s55, s55, 0x100
	s_addc_u32 s56, s56, 0
	s_cmp_gt_u32 s57, 13
	s_cbranch_scc0 .LBB0_1900
	v_lshl_add_u32 v144, s36, 8, v152
	v_ashrrev_i32_e32 v145, 31, v144
	v_lshl_add_u64 v[150:151], v[144:145], 3, s[0:1]
	global_load_dwordx2 v[182:183], v[150:151], off
	global_load_dwordx2 v[184:185], v[150:151], off offset:128
	global_load_dwordx2 v[186:187], v[150:151], off offset:256
	global_load_dwordx2 v[188:189], v[150:151], off offset:384
	global_load_dwordx2 v[190:191], v[150:151], off offset:1024
	global_load_dwordx2 v[192:193], v[150:151], off offset:1152
	global_load_dwordx2 v[194:195], v[150:151], off offset:1280
	global_load_dwordx2 v[196:197], v[150:151], off offset:1408
	s_and_b64 vcc, exec, s[10:11]
	s_cbranch_vccz .LBB0_1903
	s_barrier

; #define PG8_STAGE(bufoff, gbase, voff) do { _Pragma("unroll") for (int _i = 0; _i < 2; ++_i) \
;         __builtin_amdgcn_global_load_lds((const unsigned*)((const char*)(gbase) + (voff)[_i]), (PG8_LAS unsigned*)(lds + (bufoff) + ldsw + _i * 8192), 16, 0, 0); } while (0)
; #define PG8_LDA(dst, b, h) do { _Pragma("unroll") for (int m = 0; m < 4; ++m) _Pragma("unroll") for (int k = 0; k < 2; ++k) dst[m][k] = *(const PG8_LAS bf16x8*)(lds + PG8_SA(b, h) + aoff + m * 2048 + k * 1024); } while (0)
; #define PG8_LDB(dst, b, h) do { _Pragma("unroll") for (int n = 0; n < 2; ++n) _Pragma("unroll") for (int k = 0; k < 2; ++k) dst[n][k] = *(const PG8_LAS bf16x8*)(lds + PG8_SB(b, h) + boff + n * 2048 + k * 1024); } while (0)
; #define PG8_MMA(ai, bj, At, Bt) do { __builtin_amdgcn_s_setprio(1); _Pragma("unroll") for (int m = 0; m < 4; ++m) _Pragma("unroll") for (int n = 0; n < 2; ++n) _Pragma("unroll") for (int k = 0; k < 2; ++k) \
;         acc[ai][bj][m][n] = __builtin_amdgcn_mfma_f32_16x16x32_bf16(Bt[n][k], At[m][k], acc[ai][bj][m][n], 0, 0, 0); __builtin_amdgcn_s_setprio(0); } while (0)
; #define PG8_WAIT_V(n) asm volatile("s_waitcnt vmcnt(" #n ")" ::: "memory")
; #define PG8_WAIT_L(n) asm volatile("s_waitcnt lgkmcnt(" #n ")" ::: "memory")
; #define PG8_BAR __builtin_amdgcn_s_barrier()
; #define PG8_SCHED __builtin_amdgcn_sched_barrier(0)
; template <class Epi, class Sched, bool ALIGN_EPI = false, bool SP2 = false>
; __device__ __forceinline__ void gemm_phase(PG8_LAS unsigned char* lds, const Gemm g, const Sched& S, const Epi& E) {
;     ...
;         for (int t = 0; t < nt; t += 2) {
;             const bool last = (t == nt - 2);
;             const char* a1 = cA + (size_t)(t + 1) * kstep;
;             const char* a2 = last ? nA : cA + (size_t)(t + 2) * kstep; const char* b2 = last ? nB : cB + (size_t)(t + 2) * kstep;
;             const char* a3 = a2 + kstep; const char* b3 = b2 + kstep;
;             if (last && has_next) S.a_ready(nxt);
;             if constexpr (SP2) {
;             PG8_LDB(B0, 0, 0); PG8_LDB(B1, 0, 1); PG8_SCHED; PG8_LDA(At, 0, 0); PG8_STAGE(PG8_SA(1, 1), a1 + hstep, voffA);
;             PG8_WAIT_V(8); PG8_WAIT_L(0); PG8_BAR; PG8_MMA(0, 0, At, B0); PG8_MMA(0, 1, At, B1); PG8_BAR; PG8_SCHED;
;             PG8_LDA(At, 0, 1); PG8_STAGE(PG8_SB(0, 0), b2, voffB); PG8_STAGE(PG8_SB(0, 1), b2 + hstep, voffB); PG8_STAGE(PG8_SA(0, 0), a2, voffA);
.LBB0_1977:
	s_add_u32 s53, s28, 0x100
	s_addc_u32 s54, s29, 0
	s_mov_b32 s55, -2
	s_waitcnt lgkmcnt(0)
	ds_read_b128 v[144:147], v151
	ds_read_b128 v[156:159], v151 offset:1024
	ds_read_b128 v[160:163], v151 offset:2048
	ds_read_b128 v[164:167], v151 offset:3072
	ds_read_b128 v[168:171], v152
	ds_read_b128 v[172:175], v152 offset:1024
	ds_read_b128 v[176:179], v152 offset:2048
	ds_read_b128 v[180:183], v152 offset:3072
	s_add_u32 s28, s26, 0x100
	s_addc_u32 s29, s27, 0
	s_cmp_eq_u32 s55, 40
	s_cselect_b32 s39, s1, s29
	s_cselect_b32 s38, s0, s28
	s_cselect_b32 s37, s25, s54
	s_cselect_b32 s36, s24, s53
	v_lshl_add_u64 v[218:219], s[26:27], 0, v[136:137]
	s_add_i32 m0, s33, 0xc000
	ds_read_b128 v[184:187], v153
	ds_read_b128 v[188:191], v153 offset:1024
	ds_read_b128 v[192:195], v153 offset:2048
	ds_read_b128 v[196:199], v153 offset:3072
	ds_read_b128 v[200:203], v153 offset:4096
	ds_read_b128 v[206:209], v153 offset:5120
	ds_read_b128 v[210:213], v153 offset:6144
	ds_read_b128 v[214:217], v153 offset:7168
	global_load_lds_dwordx4 v[218:219], off
	v_lshl_add_u64 v[218:219], s[26:27], 0, v[138:139]
	s_add_i32 m0, s33, 0xe000
	s_nop 0
	global_load_lds_dwordx4 v[218:219], off
	s_waitcnt vmcnt(8)
	s_waitcnt lgkmcnt(0)
	s_barrier
	s_setprio 1
	s_waitcnt lgkmcnt(0)
	v_mfma_f32_16x16x32_bf16 v[124:127], v[144:147], v[184:187], 0
	v_mfma_f32_16x16x32_bf16 v[108:111], v[144:147], v[192:195], 0
	v_mfma_f32_16x16x32_bf16 v[120:123], v[160:163], v[184:187], 0
	v_mfma_f32_16x16x32_bf16 v[104:107], v[160:163], v[192:195], 0
	v_mfma_f32_16x16x32_bf16 v[92:95], v[144:147], v[200:203], 0
	v_mfma_f32_16x16x32_bf16 v[76:79], v[144:147], v[210:213], 0
	v_mfma_f32_16x16x32_bf16 v[88:91], v[160:163], v[200:203], 0
	v_mfma_f32_16x16x32_bf16 v[72:75], v[160:163], v[210:213], 0
	v_mfma_f32_16x16x32_bf16 v[124:127], v[156:159], v[188:191], v[124:127]
	v_mfma_f32_16x16x32_bf16 v[108:111], v[156:159], v[196:199], v[108:111]
	v_mfma_f32_16x16x32_bf16 v[120:123], v[164:167], v[188:191], v[120:123]
	v_mfma_f32_16x16x32_bf16 v[104:107], v[164:167], v[196:199], v[104:107]
	v_mfma_f32_16x16x32_bf16 v[92:95], v[156:159], v[206:209], v[92:95]
	v_mfma_f32_16x16x32_bf16 v[76:79], v[156:159], v[214:217], v[76:79]
	v_mfma_f32_16x16x32_bf16 v[88:91], v[164:167], v[206:209], v[88:91]
	v_mfma_f32_16x16x32_bf16 v[72:75], v[164:167], v[214:217], v[72:75]
	s_setprio 0
	s_setprio 1
	v_mfma_f32_16x16x32_bf16 v[116:119], v[168:171], v[184:187], 0
	v_mfma_f32_16x16x32_bf16 v[100:103], v[168:171], v[192:195], 0
	v_mfma_f32_16x16x32_bf16 v[112:115], v[176:179], v[184:187], 0
	v_mfma_f32_16x16x32_bf16 v[96:99], v[176:179], v[192:195], 0
	v_mfma_f32_16x16x32_bf16 v[84:87], v[168:171], v[200:203], 0
	v_mfma_f32_16x16x32_bf16 v[68:71], v[168:171], v[210:213], 0
	v_mfma_f32_16x16x32_bf16 v[80:83], v[176:179], v[200:203], 0
	v_mfma_f32_16x16x32_bf16 v[64:67], v[176:179], v[210:213], 0
	v_mfma_f32_16x16x32_bf16 v[116:119], v[172:175], v[188:191], v[116:119]
	v_mfma_f32_16x16x32_bf16 v[100:103], v[172:175], v[196:199], v[100:103]
	v_mfma_f32_16x16x32_bf16 v[112:115], v[180:183], v[188:191], v[112:115]
	v_mfma_f32_16x16x32_bf16 v[96:99], v[180:183], v[196:199], v[96:99]
	v_mfma_f32_16x16x32_bf16 v[84:87], v[172:175], v[206:209], v[84:87]
	v_mfma_f32_16x16x32_bf16 v[68:71], v[172:175], v[214:217], v[68:71]
	v_mfma_f32_16x16x32_bf16 v[80:83], v[180:183], v[206:209], v[80:83]
	v_mfma_f32_16x16x32_bf16 v[64:67], v[180:183], v[214:217], v[64:67]
	s_setprio 0
	s_barrier
	s_add_i32 s26, s45, s15
	v_lshl_add_u64 v[218:219], s[36:37], 0, v[130:131]
	s_mov_b32 m0, s26
	ds_read_b128 v[184:187], v153 offset:16384
	ds_read_b128 v[188:191], v153 offset:17408
	ds_read_b128 v[192:195], v153 offset:18432
	ds_read_b128 v[196:199], v153 offset:19456
	ds_read_b128 v[200:203], v153 offset:20480
	ds_read_b128 v[206:209], v153 offset:21504
	ds_read_b128 v[210:213], v153 offset:22528
	ds_read_b128 v[214:217], v153 offset:23552
	global_load_lds_dwordx4 v[218:219], off
	s_add_i32 m0, s26, 0x2000
	s_add_u32 s26, s36, 0xb0000
	v_lshl_add_u64 v[220:221], s[36:37], 0, v[134:135]
	s_addc_u32 s27, s37, 0
	s_add_i32 s56, s46, s15
	global_load_lds_dwordx4 v[220:221], off
	v_lshl_add_u64 v[222:223], s[26:27], 0, v[130:131]
	s_mov_b32 m0, s56
	global_load_lds_dwordx4 v[222:223], off
	v_lshl_add_u64 v[222:223], s[26:27], 0, v[134:135]
	s_add_i32 m0, s56, 0x2000
	s_nop 0
	global_load_lds_dwordx4 v[222:223], off
	s_waitcnt vmcnt(6)
	s_waitcnt lgkmcnt(0)
	s_barrier
; #define PG8_STAGE(bufoff, gbase, voff) do { _Pragma("unroll") for (int _i = 0; _i < 2; ++_i) \
;         __builtin_amdgcn_global_load_lds((const unsigned*)((const char*)(gbase) + (voff)[_i]), (PG8_LAS unsigned*)(lds + (bufoff) + ldsw + _i * 8192), 16, 0, 0); } while (0)
; #define PG8_LDA(dst, b, h) do { _Pragma("unroll") for (int m = 0; m < 4; ++m) _Pragma("unroll") for (int k = 0; k < 2; ++k) dst[m][k] = *(const PG8_LAS bf16x8*)(lds + PG8_SA(b, h) + aoff + m * 2048 + k * 1024); } while (0)
; #define PG8_LDB(dst, b, h) do { _Pragma("unroll") for (int n = 0; n < 2; ++n) _Pragma("unroll") for (int k = 0; k < 2; ++k) dst[n][k] = *(const PG8_LAS bf16x8*)(lds + PG8_SB(b, h) + boff + n * 2048 + k * 1024); } while (0)
; #define PG8_MMA(ai, bj, At, Bt) do { __builtin_amdgcn_s_setprio(1); _Pragma("unroll") for (int m = 0; m < 4; ++m) _Pragma("unroll") for (int n = 0; n < 2; ++n) _Pragma("unroll") for (int k = 0; k < 2; ++k) \
;         acc[ai][bj][m][n] = __builtin_amdgcn_mfma_f32_16x16x32_bf16(Bt[n][k], At[m][k], acc[ai][bj][m][n], 0, 0, 0); __builtin_amdgcn_s_setprio(0); } while (0)
; #define PG8_WAIT_V(n) asm volatile("s_waitcnt vmcnt(" #n ")" ::: "memory")
; #define PG8_WAIT_L(n) asm volatile("s_waitcnt lgkmcnt(" #n ")" ::: "memory")
; #define PG8_BAR __builtin_amdgcn_s_barrier()
; #define PG8_SCHED __builtin_amdgcn_sched_barrier(0)
; template <class Epi, class Sched, bool ALIGN_EPI = false, bool SP2 = false>
; __device__ __forceinline__ void gemm_phase(PG8_LAS unsigned char* lds, const Gemm g, const Sched& S, const Epi& E) {
;     ...
;             PG8_WAIT_V(8); PG8_WAIT_L(0); PG8_BAR; PG8_MMA(1, 0, At, B0); PG8_MMA(1, 1, At, B1); PG8_BAR; PG8_SCHED;
;             PG8_LDB(B0, 1, 0); PG8_LDB(B1, 1, 1); PG8_SCHED; PG8_LDA(At, 1, 0); PG8_STAGE(PG8_SA(0, 1), a2 + hstep, voffA);
;             PG8_WAIT_V(8); PG8_WAIT_L(0); PG8_BAR; PG8_MMA(0, 0, At, B0); PG8_MMA(0, 1, At, B1); PG8_BAR; PG8_SCHED;
	s_setprio 1
	s_waitcnt lgkmcnt(0)
	v_mfma_f32_16x16x32_bf16 v[60:63], v[144:147], v[184:187], 0
	v_mfma_f32_16x16x32_bf16 v[44:47], v[144:147], v[192:195], 0
	v_mfma_f32_16x16x32_bf16 v[56:59], v[160:163], v[184:187], 0
	v_mfma_f32_16x16x32_bf16 v[40:43], v[160:163], v[192:195], 0
	v_mfma_f32_16x16x32_bf16 v[28:31], v[144:147], v[200:203], 0
	v_mfma_f32_16x16x32_bf16 v[12:15], v[144:147], v[210:213], 0
	v_mfma_f32_16x16x32_bf16 v[24:27], v[160:163], v[200:203], 0
	v_mfma_f32_16x16x32_bf16 v[8:11], v[160:163], v[210:213], 0
	v_mfma_f32_16x16x32_bf16 v[60:63], v[156:159], v[188:191], v[60:63]
	v_mfma_f32_16x16x32_bf16 v[44:47], v[156:159], v[196:199], v[44:47]
	v_mfma_f32_16x16x32_bf16 v[56:59], v[164:167], v[188:191], v[56:59]
	v_mfma_f32_16x16x32_bf16 v[40:43], v[164:167], v[196:199], v[40:43]
	v_mfma_f32_16x16x32_bf16 v[28:31], v[156:159], v[206:209], v[28:31]
	v_mfma_f32_16x16x32_bf16 v[12:15], v[156:159], v[214:217], v[12:15]
	v_lshl_add_u64 v[222:223], s[38:39], 0, v[128:129]
	s_mov_b32 m0, s33
	s_nop 0
	global_load_lds_dwordx4 v[222:223], off
	v_mfma_f32_16x16x32_bf16 v[24:27], v[164:167], v[206:209], v[24:27]
	v_mfma_f32_16x16x32_bf16 v[8:11], v[164:167], v[214:217], v[8:11]
	s_setprio 0
	s_setprio 1
	v_mfma_f32_16x16x32_bf16 v[52:55], v[168:171], v[184:187], 0
	v_mfma_f32_16x16x32_bf16 v[36:39], v[168:171], v[192:195], 0
	v_mfma_f32_16x16x32_bf16 v[48:51], v[176:179], v[184:187], 0
	v_mfma_f32_16x16x32_bf16 v[32:35], v[176:179], v[192:195], 0
	v_mfma_f32_16x16x32_bf16 v[20:23], v[168:171], v[200:203], 0
	v_mfma_f32_16x16x32_bf16 v[4:7], v[168:171], v[210:213], 0
	v_mfma_f32_16x16x32_bf16 v[16:19], v[176:179], v[200:203], 0
	v_mfma_f32_16x16x32_bf16 v[0:3], v[176:179], v[210:213], 0
	v_mfma_f32_16x16x32_bf16 v[52:55], v[172:175], v[188:191], v[52:55]
	v_mfma_f32_16x16x32_bf16 v[36:39], v[172:175], v[196:199], v[36:39]
	v_mfma_f32_16x16x32_bf16 v[48:51], v[180:183], v[188:191], v[48:51]
	v_mfma_f32_16x16x32_bf16 v[32:35], v[180:183], v[196:199], v[32:35]
	v_mfma_f32_16x16x32_bf16 v[20:23], v[172:175], v[206:209], v[20:23]
	v_mfma_f32_16x16x32_bf16 v[4:7], v[172:175], v[214:217], v[4:7]
	v_lshl_add_u64 v[224:225], s[38:39], 0, v[132:133]
	s_mov_b32 m0, s34
	s_nop 0
	global_load_lds_dwordx4 v[224:225], off
	v_mfma_f32_16x16x32_bf16 v[16:19], v[180:183], v[206:209], v[16:19]
	v_mfma_f32_16x16x32_bf16 v[0:3], v[180:183], v[214:217], v[0:3]
	s_setprio 0
	s_barrier
	s_add_i32 s56, 0, 0x18000
	v_add_u32_e32 v155, s56, v149
	s_add_i32 s57, 0, 0x1c000
	ds_read_b128 v[144:147], v155
	ds_read_b128 v[156:159], v155 offset:1024
	ds_read_b128 v[160:163], v155 offset:2048
	ds_read_b128 v[164:167], v155 offset:3072
	v_add_u32_e32 v155, s57, v149
	ds_read_b128 v[168:171], v155
	ds_read_b128 v[172:175], v155 offset:1024
	ds_read_b128 v[176:179], v155 offset:2048
	ds_read_b128 v[180:183], v155 offset:3072
	s_add_u32 s26, s38, 0xb0000
	s_addc_u32 s27, s39, 0
	s_mov_b32 m0, s40
	v_lshl_add_u64 v[226:227], s[26:27], 0, v[128:129]
	ds_read_b128 v[184:187], v153 offset:32768
	ds_read_b128 v[188:191], v153 offset:33792
	ds_read_b128 v[192:195], v153 offset:34816
	ds_read_b128 v[196:199], v153 offset:35840
	ds_read_b128 v[200:203], v153 offset:36864
	ds_read_b128 v[206:209], v153 offset:37888
	ds_read_b128 v[210:213], v153 offset:38912
	ds_read_b128 v[214:217], v153 offset:39936
	global_load_lds_dwordx4 v[226:227], off
	v_lshl_add_u64 v[226:227], s[26:27], 0, v[132:133]
	s_mov_b32 m0, s41
	s_nop 0
	global_load_lds_dwordx4 v[226:227], off
	s_waitcnt vmcnt(8)
	s_waitcnt lgkmcnt(0)
	s_barrier
	s_setprio 1
	s_waitcnt lgkmcnt(0)
	v_mfma_f32_16x16x32_bf16 v[124:127], v[144:147], v[184:187], v[124:127]
	v_mfma_f32_16x16x32_bf16 v[108:111], v[144:147], v[192:195], v[108:111]
	v_mfma_f32_16x16x32_bf16 v[120:123], v[160:163], v[184:187], v[120:123]
	v_mfma_f32_16x16x32_bf16 v[104:107], v[160:163], v[192:195], v[104:107]
	v_mfma_f32_16x16x32_bf16 v[92:95], v[144:147], v[200:203], v[92:95]
	v_mfma_f32_16x16x32_bf16 v[76:79], v[144:147], v[210:213], v[76:79]
	v_mfma_f32_16x16x32_bf16 v[88:91], v[160:163], v[200:203], v[88:91]
	v_mfma_f32_16x16x32_bf16 v[72:75], v[160:163], v[210:213], v[72:75]
	v_mfma_f32_16x16x32_bf16 v[124:127], v[156:159], v[188:191], v[124:127]
	v_mfma_f32_16x16x32_bf16 v[108:111], v[156:159], v[196:199], v[108:111]
	v_mfma_f32_16x16x32_bf16 v[120:123], v[164:167], v[188:191], v[120:123]
	v_mfma_f32_16x16x32_bf16 v[104:107], v[164:167], v[196:199], v[104:107]
	v_mfma_f32_16x16x32_bf16 v[92:95], v[156:159], v[206:209], v[92:95]
	v_mfma_f32_16x16x32_bf16 v[76:79], v[156:159], v[214:217], v[76:79]
	v_mfma_f32_16x16x32_bf16 v[88:91], v[164:167], v[206:209], v[88:91]
	v_mfma_f32_16x16x32_bf16 v[72:75], v[164:167], v[214:217], v[72:75]
	s_setprio 0
	s_setprio 1
	v_mfma_f32_16x16x32_bf16 v[116:119], v[168:171], v[184:187], v[116:119]
	v_mfma_f32_16x16x32_bf16 v[100:103], v[168:171], v[192:195], v[100:103]
	v_mfma_f32_16x16x32_bf16 v[112:115], v[176:179], v[184:187], v[112:115]
	v_mfma_f32_16x16x32_bf16 v[96:99], v[176:179], v[192:195], v[96:99]
	v_mfma_f32_16x16x32_bf16 v[84:87], v[168:171], v[200:203], v[84:87]
	v_mfma_f32_16x16x32_bf16 v[68:71], v[168:171], v[210:213], v[68:71]
	v_mfma_f32_16x16x32_bf16 v[80:83], v[176:179], v[200:203], v[80:83]
	v_mfma_f32_16x16x32_bf16 v[64:67], v[176:179], v[210:213], v[64:67]
	v_mfma_f32_16x16x32_bf16 v[116:119], v[172:175], v[188:191], v[116:119]
	v_mfma_f32_16x16x32_bf16 v[100:103], v[172:175], v[196:199], v[100:103]
	v_mfma_f32_16x16x32_bf16 v[112:115], v[180:183], v[188:191], v[112:115]
	v_mfma_f32_16x16x32_bf16 v[96:99], v[180:183], v[196:199], v[96:99]
	v_mfma_f32_16x16x32_bf16 v[84:87], v[172:175], v[206:209], v[84:87]
	v_mfma_f32_16x16x32_bf16 v[68:71], v[172:175], v[214:217], v[68:71]
	v_mfma_f32_16x16x32_bf16 v[80:83], v[180:183], v[206:209], v[80:83]
	v_mfma_f32_16x16x32_bf16 v[64:67], v[180:183], v[214:217], v[64:67]
	s_setprio 0
	s_barrier
; #define PG8_STAGE(bufoff, gbase, voff) do { _Pragma("unroll") for (int _i = 0; _i < 2; ++_i) \
;         __builtin_amdgcn_global_load_lds((const unsigned*)((const char*)(gbase) + (voff)[_i]), (PG8_LAS unsigned*)(lds + (bufoff) + ldsw + _i * 8192), 16, 0, 0); } while (0)
; #define PG8_LDA(dst, b, h) do { _Pragma("unroll") for (int m = 0; m < 4; ++m) _Pragma("unroll") for (int k = 0; k < 2; ++k) dst[m][k] = *(const PG8_LAS bf16x8*)(lds + PG8_SA(b, h) + aoff + m * 2048 + k * 1024); } while (0)
; #define PG8_LDB(dst, b, h) do { _Pragma("unroll") for (int n = 0; n < 2; ++n) _Pragma("unroll") for (int k = 0; k < 2; ++k) dst[n][k] = *(const PG8_LAS bf16x8*)(lds + PG8_SB(b, h) + boff + n * 2048 + k * 1024); } while (0)
; #define PG8_MMA(ai, bj, At, Bt) do { __builtin_amdgcn_s_setprio(1); _Pragma("unroll") for (int m = 0; m < 4; ++m) _Pragma("unroll") for (int n = 0; n < 2; ++n) _Pragma("unroll") for (int k = 0; k < 2; ++k) \
;         acc[ai][bj][m][n] = __builtin_amdgcn_mfma_f32_16x16x32_bf16(Bt[n][k], At[m][k], acc[ai][bj][m][n], 0, 0, 0); __builtin_amdgcn_s_setprio(0); } while (0)
; #define PG8_WAIT_V(n) asm volatile("s_waitcnt vmcnt(" #n ")" ::: "memory")
; template <class Epi, class Sched, bool ALIGN_EPI = false, bool SP2 = false>
; __device__ __forceinline__ void gemm_phase(PG8_LAS unsigned char* lds, const Gemm g, const Sched& S, const Epi& E) {
;     ...
;             PG8_LDB(B0, 0, 0); PG8_LDB(B1, 0, 1); PG8_SCHED; PG8_LDA(At, 0, 0); PG8_STAGE(PG8_SA(1, 1), a1 + hstep, voffA);
;             PG8_WAIT_V(8); PG8_WAIT_L(0); PG8_BAR; PG8_MMA(0, 0, At, B0); PG8_MMA(0, 1, At, B1); PG8_BAR; PG8_SCHED;
;             PG8_LDA(At, 0, 1); PG8_STAGE(PG8_SB(0, 0), b2, voffB); PG8_STAGE(PG8_SB(0, 1), b2 + hstep, voffB); PG8_STAGE(PG8_SA(0, 0), a2, voffA);
;             PG8_WAIT_V(8); PG8_WAIT_L(0); PG8_BAR; PG8_MMA(1, 0, At, B0); PG8_MMA(1, 1, At, B1); PG8_BAR; PG8_SCHED;
;             PG8_LDB(B0, 1, 0); PG8_LDB(B1, 1, 1); PG8_SCHED; PG8_LDA(At, 1, 0); PG8_STAGE(PG8_SA(0, 1), a2 + hstep, voffA);
;             PG8_WAIT_V(8); PG8_WAIT_L(0); PG8_BAR; PG8_MMA(0, 0, At, B0); PG8_MMA(0, 1, At, B1); PG8_BAR; PG8_SCHED;
;             PG8_LDA(At, 1, 1); PG8_STAGE(PG8_SB(1, 0), b3, voffB); PG8_STAGE(PG8_SB(1, 1), b3 + hstep, voffB); PG8_STAGE(PG8_SA(1, 0), a3, voffA);
;             PG8_WAIT_V(8); PG8_WAIT_L(0); PG8_BAR; PG8_MMA(1, 0, At, B0); PG8_MMA(1, 1, At, B1); PG8_BAR; PG8_SCHED;
	s_add_i32 s26, s56, s15
	v_lshl_add_u64 v[218:219], v[218:219], 0, s[12:13]
	s_mov_b32 m0, s26
	ds_read_b128 v[184:187], v153 offset:49152
	ds_read_b128 v[188:191], v153 offset:50176
	ds_read_b128 v[192:195], v153 offset:51200
	ds_read_b128 v[196:199], v153 offset:52224
	ds_read_b128 v[200:203], v153 offset:53248
	ds_read_b128 v[206:209], v153 offset:54272
	ds_read_b128 v[210:213], v153 offset:55296
	ds_read_b128 v[214:217], v153 offset:56320
	global_load_lds_dwordx4 v[218:219], off
	s_add_i32 m0, s26, 0x2000
	s_add_u32 s26, s36, 0xb0080
	v_lshl_add_u64 v[218:219], v[220:221], 0, s[12:13]
	s_addc_u32 s27, s37, 0
	s_add_i32 s36, s57, s15
	global_load_lds_dwordx4 v[218:219], off
	v_lshl_add_u64 v[218:219], s[26:27], 0, v[130:131]
	s_mov_b32 m0, s36
	s_nop 0
	global_load_lds_dwordx4 v[218:219], off
	v_lshl_add_u64 v[218:219], s[26:27], 0, v[134:135]
	s_add_i32 m0, s36, 0x2000
	s_nop 0
	global_load_lds_dwordx4 v[218:219], off
	s_waitcnt vmcnt(6)
	s_waitcnt lgkmcnt(0)
	s_barrier
	s_setprio 1
	s_waitcnt lgkmcnt(0)
	v_mfma_f32_16x16x32_bf16 v[60:63], v[144:147], v[184:187], v[60:63]
	v_mfma_f32_16x16x32_bf16 v[44:47], v[144:147], v[192:195], v[44:47]
	v_mfma_f32_16x16x32_bf16 v[56:59], v[160:163], v[184:187], v[56:59]
	v_mfma_f32_16x16x32_bf16 v[40:43], v[160:163], v[192:195], v[40:43]
	v_mfma_f32_16x16x32_bf16 v[28:31], v[144:147], v[200:203], v[28:31]
	v_mfma_f32_16x16x32_bf16 v[12:15], v[144:147], v[210:213], v[12:15]
	v_mfma_f32_16x16x32_bf16 v[24:27], v[160:163], v[200:203], v[24:27]
	v_mfma_f32_16x16x32_bf16 v[8:11], v[160:163], v[210:213], v[8:11]
	v_mfma_f32_16x16x32_bf16 v[60:63], v[156:159], v[188:191], v[60:63]
	v_mfma_f32_16x16x32_bf16 v[44:47], v[156:159], v[196:199], v[44:47]
	v_mfma_f32_16x16x32_bf16 v[56:59], v[164:167], v[188:191], v[56:59]
	v_mfma_f32_16x16x32_bf16 v[40:43], v[164:167], v[196:199], v[40:43]
	v_mfma_f32_16x16x32_bf16 v[28:31], v[156:159], v[206:209], v[28:31]
	v_mfma_f32_16x16x32_bf16 v[12:15], v[156:159], v[214:217], v[12:15]
	v_lshl_add_u64 v[218:219], v[222:223], 0, s[12:13]
	s_mov_b32 m0, s43
	s_nop 0
	global_load_lds_dwordx4 v[218:219], off
	v_mfma_f32_16x16x32_bf16 v[24:27], v[164:167], v[206:209], v[24:27]
	v_mfma_f32_16x16x32_bf16 v[8:11], v[164:167], v[214:217], v[8:11]
	s_setprio 0
	s_setprio 1
	v_mfma_f32_16x16x32_bf16 v[52:55], v[168:171], v[184:187], v[52:55]
	v_mfma_f32_16x16x32_bf16 v[36:39], v[168:171], v[192:195], v[36:39]
	v_mfma_f32_16x16x32_bf16 v[48:51], v[176:179], v[184:187], v[48:51]
	v_mfma_f32_16x16x32_bf16 v[32:35], v[176:179], v[192:195], v[32:35]
	v_mfma_f32_16x16x32_bf16 v[20:23], v[168:171], v[200:203], v[20:23]
	v_mfma_f32_16x16x32_bf16 v[4:7], v[168:171], v[210:213], v[4:7]
	v_mfma_f32_16x16x32_bf16 v[16:19], v[176:179], v[200:203], v[16:19]
	v_mfma_f32_16x16x32_bf16 v[0:3], v[176:179], v[210:213], v[0:3]
	v_mfma_f32_16x16x32_bf16 v[52:55], v[172:175], v[188:191], v[52:55]
	v_mfma_f32_16x16x32_bf16 v[36:39], v[172:175], v[196:199], v[36:39]
	v_mfma_f32_16x16x32_bf16 v[48:51], v[180:183], v[188:191], v[48:51]
	v_mfma_f32_16x16x32_bf16 v[32:35], v[180:183], v[196:199], v[32:35]
	v_mfma_f32_16x16x32_bf16 v[20:23], v[172:175], v[206:209], v[20:23]
	v_mfma_f32_16x16x32_bf16 v[4:7], v[172:175], v[214:217], v[4:7]
	v_lshl_add_u64 v[218:219], v[224:225], 0, s[12:13]
	s_mov_b32 m0, s44
	s_nop 0
	global_load_lds_dwordx4 v[218:219], off
	v_mfma_f32_16x16x32_bf16 v[16:19], v[180:183], v[206:209], v[16:19]
	v_mfma_f32_16x16x32_bf16 v[0:3], v[180:183], v[214:217], v[0:3]
	s_setprio 0
	s_barrier
	s_add_i32 s55, s55, 2
	s_add_u32 s53, s53, 0x100
	s_addc_u32 s54, s54, 0
	s_mov_b64 s[26:27], s[28:29]
.LBB0_1978:
	ds_read_b128 v[144:147], v151
	ds_read_b128 v[156:159], v151 offset:1024
	ds_read_b128 v[160:163], v151 offset:2048
	ds_read_b128 v[164:167], v151 offset:3072
	ds_read_b128 v[168:171], v152
	ds_read_b128 v[172:175], v152 offset:1024
	ds_read_b128 v[176:179], v152 offset:2048
	ds_read_b128 v[180:183], v152 offset:3072
	s_add_u32 s28, s26, 0x100
	s_addc_u32 s29, s27, 0
	s_cmp_eq_u32 s55, 40
	s_cselect_b32 s39, s1, s29
	s_cselect_b32 s38, s0, s28
	s_cselect_b32 s37, s25, s54
	s_cselect_b32 s36, s24, s53
	v_lshl_add_u64 v[218:219], s[26:27], 0, v[136:137]
	s_add_i32 m0, s33, 0xc000
	ds_read_b128 v[184:187], v153
	ds_read_b128 v[188:191], v153 offset:1024
	ds_read_b128 v[192:195], v153 offset:2048
	ds_read_b128 v[196:199], v153 offset:3072
	ds_read_b128 v[200:203], v153 offset:4096
	ds_read_b128 v[206:209], v153 offset:5120
	ds_read_b128 v[210:213], v153 offset:6144
	ds_read_b128 v[214:217], v153 offset:7168
	global_load_lds_dwordx4 v[218:219], off
	v_lshl_add_u64 v[218:219], s[26:27], 0, v[138:139]
	s_add_i32 m0, s33, 0xe000
	s_nop 0
	global_load_lds_dwordx4 v[218:219], off
	s_waitcnt vmcnt(8)
	s_waitcnt lgkmcnt(0)
	s_barrier
; #define PG8_STAGE(bufoff, gbase, voff) do { _Pragma("unroll") for (int _i = 0; _i < 2; ++_i) \
;         __builtin_amdgcn_global_load_lds((const unsigned*)((const char*)(gbase) + (voff)[_i]), (PG8_LAS unsigned*)(lds + (bufoff) + ldsw + _i * 8192), 16, 0, 0); } while (0)
; #define PG8_LDA(dst, b, h) do { _Pragma("unroll") for (int m = 0; m < 4; ++m) _Pragma("unroll") for (int k = 0; k < 2; ++k) dst[m][k] = *(const PG8_LAS bf16x8*)(lds + PG8_SA(b, h) + aoff + m * 2048 + k * 1024); } while (0)
; #define PG8_MMA(ai, bj, At, Bt) do { __builtin_amdgcn_s_setprio(1); _Pragma("unroll") for (int m = 0; m < 4; ++m) _Pragma("unroll") for (int n = 0; n < 2; ++n) _Pragma("unroll") for (int k = 0; k < 2; ++k) \
;         acc[ai][bj][m][n] = __builtin_amdgcn_mfma_f32_16x16x32_bf16(Bt[n][k], At[m][k], acc[ai][bj][m][n], 0, 0, 0); __builtin_amdgcn_s_setprio(0); } while (0)
; #define PG8_WAIT_V(n) asm volatile("s_waitcnt vmcnt(" #n ")" ::: "memory")
; #define PG8_WAIT_L(n) asm volatile("s_waitcnt lgkmcnt(" #n ")" ::: "memory")
; #define PG8_BAR __builtin_amdgcn_s_barrier()
; #define PG8_SCHED __builtin_amdgcn_sched_barrier(0)
; template <class Epi, class Sched, bool ALIGN_EPI = false, bool SP2 = false>
; __device__ __forceinline__ void gemm_phase(PG8_LAS unsigned char* lds, const Gemm g, const Sched& S, const Epi& E) {
;     ...
;             PG8_WAIT_V(8); PG8_WAIT_L(0); PG8_BAR; PG8_MMA(0, 0, At, B0); PG8_MMA(0, 1, At, B1); PG8_BAR; PG8_SCHED;
;             PG8_LDA(At, 0, 1); PG8_STAGE(PG8_SB(0, 0), b2, voffB); PG8_STAGE(PG8_SB(0, 1), b2 + hstep, voffB); PG8_STAGE(PG8_SA(0, 0), a2, voffA);
;             PG8_WAIT_V(8); PG8_WAIT_L(0); PG8_BAR; PG8_MMA(1, 0, At, B0); PG8_MMA(1, 1, At, B1); PG8_BAR; PG8_SCHED;
	s_setprio 1
	s_waitcnt lgkmcnt(0)
	v_mfma_f32_16x16x32_bf16 v[124:127], v[144:147], v[184:187], v[124:127]
	v_mfma_f32_16x16x32_bf16 v[108:111], v[144:147], v[192:195], v[108:111]
	v_mfma_f32_16x16x32_bf16 v[120:123], v[160:163], v[184:187], v[120:123]
	v_mfma_f32_16x16x32_bf16 v[104:107], v[160:163], v[192:195], v[104:107]
	v_mfma_f32_16x16x32_bf16 v[92:95], v[144:147], v[200:203], v[92:95]
	v_mfma_f32_16x16x32_bf16 v[76:79], v[144:147], v[210:213], v[76:79]
	v_mfma_f32_16x16x32_bf16 v[88:91], v[160:163], v[200:203], v[88:91]
	v_mfma_f32_16x16x32_bf16 v[72:75], v[160:163], v[210:213], v[72:75]
	v_mfma_f32_16x16x32_bf16 v[124:127], v[156:159], v[188:191], v[124:127]
	v_mfma_f32_16x16x32_bf16 v[108:111], v[156:159], v[196:199], v[108:111]
	v_mfma_f32_16x16x32_bf16 v[120:123], v[164:167], v[188:191], v[120:123]
	v_mfma_f32_16x16x32_bf16 v[104:107], v[164:167], v[196:199], v[104:107]
	v_mfma_f32_16x16x32_bf16 v[92:95], v[156:159], v[206:209], v[92:95]
	v_mfma_f32_16x16x32_bf16 v[76:79], v[156:159], v[214:217], v[76:79]
	v_mfma_f32_16x16x32_bf16 v[88:91], v[164:167], v[206:209], v[88:91]
	v_mfma_f32_16x16x32_bf16 v[72:75], v[164:167], v[214:217], v[72:75]
	s_setprio 0
	s_setprio 1
	v_mfma_f32_16x16x32_bf16 v[116:119], v[168:171], v[184:187], v[116:119]
	v_mfma_f32_16x16x32_bf16 v[100:103], v[168:171], v[192:195], v[100:103]
	v_mfma_f32_16x16x32_bf16 v[112:115], v[176:179], v[184:187], v[112:115]
	v_mfma_f32_16x16x32_bf16 v[96:99], v[176:179], v[192:195], v[96:99]
	v_mfma_f32_16x16x32_bf16 v[84:87], v[168:171], v[200:203], v[84:87]
	v_mfma_f32_16x16x32_bf16 v[68:71], v[168:171], v[210:213], v[68:71]
	v_mfma_f32_16x16x32_bf16 v[80:83], v[176:179], v[200:203], v[80:83]
	v_mfma_f32_16x16x32_bf16 v[64:67], v[176:179], v[210:213], v[64:67]
	v_mfma_f32_16x16x32_bf16 v[116:119], v[172:175], v[188:191], v[116:119]
	v_mfma_f32_16x16x32_bf16 v[100:103], v[172:175], v[196:199], v[100:103]
	v_mfma_f32_16x16x32_bf16 v[112:115], v[180:183], v[188:191], v[112:115]
	v_mfma_f32_16x16x32_bf16 v[96:99], v[180:183], v[196:199], v[96:99]
	v_mfma_f32_16x16x32_bf16 v[84:87], v[172:175], v[206:209], v[84:87]
	v_mfma_f32_16x16x32_bf16 v[68:71], v[172:175], v[214:217], v[68:71]
	v_mfma_f32_16x16x32_bf16 v[80:83], v[180:183], v[206:209], v[80:83]
	v_mfma_f32_16x16x32_bf16 v[64:67], v[180:183], v[214:217], v[64:67]
	s_setprio 0
	s_barrier
	s_add_i32 s26, s45, s15
	v_lshl_add_u64 v[218:219], s[36:37], 0, v[130:131]
	s_mov_b32 m0, s26
	ds_read_b128 v[184:187], v153 offset:16384
	ds_read_b128 v[188:191], v153 offset:17408
	ds_read_b128 v[192:195], v153 offset:18432
	ds_read_b128 v[196:199], v153 offset:19456
	ds_read_b128 v[200:203], v153 offset:20480
	ds_read_b128 v[206:209], v153 offset:21504
	ds_read_b128 v[210:213], v153 offset:22528
	ds_read_b128 v[214:217], v153 offset:23552
	global_load_lds_dwordx4 v[218:219], off
	s_add_i32 m0, s26, 0x2000
	s_add_u32 s26, s36, 0xb0000
	v_lshl_add_u64 v[220:221], s[36:37], 0, v[134:135]
	s_addc_u32 s27, s37, 0
	s_add_i32 s56, s46, s15
	global_load_lds_dwordx4 v[220:221], off
	v_lshl_add_u64 v[222:223], s[26:27], 0, v[130:131]
	s_mov_b32 m0, s56
	global_load_lds_dwordx4 v[222:223], off
	v_lshl_add_u64 v[222:223], s[26:27], 0, v[134:135]
	s_add_i32 m0, s56, 0x2000
	s_nop 0
	global_load_lds_dwordx4 v[222:223], off
	s_waitcnt vmcnt(6)
	s_waitcnt lgkmcnt(0)
	s_barrier
	s_setprio 1
	s_waitcnt lgkmcnt(0)
	v_mfma_f32_16x16x32_bf16 v[60:63], v[144:147], v[184:187], v[60:63]
	v_mfma_f32_16x16x32_bf16 v[44:47], v[144:147], v[192:195], v[44:47]
	v_mfma_f32_16x16x32_bf16 v[56:59], v[160:163], v[184:187], v[56:59]
	v_mfma_f32_16x16x32_bf16 v[40:43], v[160:163], v[192:195], v[40:43]
	v_mfma_f32_16x16x32_bf16 v[28:31], v[144:147], v[200:203], v[28:31]
	v_mfma_f32_16x16x32_bf16 v[12:15], v[144:147], v[210:213], v[12:15]
	v_mfma_f32_16x16x32_bf16 v[24:27], v[160:163], v[200:203], v[24:27]
	v_mfma_f32_16x16x32_bf16 v[8:11], v[160:163], v[210:213], v[8:11]
	v_mfma_f32_16x16x32_bf16 v[60:63], v[156:159], v[188:191], v[60:63]
	v_mfma_f32_16x16x32_bf16 v[44:47], v[156:159], v[196:199], v[44:47]
	v_mfma_f32_16x16x32_bf16 v[56:59], v[164:167], v[188:191], v[56:59]
	v_mfma_f32_16x16x32_bf16 v[40:43], v[164:167], v[196:199], v[40:43]
	v_mfma_f32_16x16x32_bf16 v[28:31], v[156:159], v[206:209], v[28:31]
	v_mfma_f32_16x16x32_bf16 v[12:15], v[156:159], v[214:217], v[12:15]
	v_lshl_add_u64 v[222:223], s[38:39], 0, v[128:129]
	s_mov_b32 m0, s33
	s_nop 0
	global_load_lds_dwordx4 v[222:223], off
	v_mfma_f32_16x16x32_bf16 v[24:27], v[164:167], v[206:209], v[24:27]
	v_mfma_f32_16x16x32_bf16 v[8:11], v[164:167], v[214:217], v[8:11]
	s_setprio 0
	s_setprio 1
	v_mfma_f32_16x16x32_bf16 v[52:55], v[168:171], v[184:187], v[52:55]
	v_mfma_f32_16x16x32_bf16 v[36:39], v[168:171], v[192:195], v[36:39]
	v_mfma_f32_16x16x32_bf16 v[48:51], v[176:179], v[184:187], v[48:51]
	v_mfma_f32_16x16x32_bf16 v[32:35], v[176:179], v[192:195], v[32:35]
	v_mfma_f32_16x16x32_bf16 v[20:23], v[168:171], v[200:203], v[20:23]
	v_mfma_f32_16x16x32_bf16 v[4:7], v[168:171], v[210:213], v[4:7]
	v_mfma_f32_16x16x32_bf16 v[16:19], v[176:179], v[200:203], v[16:19]
	v_mfma_f32_16x16x32_bf16 v[0:3], v[176:179], v[210:213], v[0:3]
	v_mfma_f32_16x16x32_bf16 v[52:55], v[172:175], v[188:191], v[52:55]
	v_mfma_f32_16x16x32_bf16 v[36:39], v[172:175], v[196:199], v[36:39]
	v_mfma_f32_16x16x32_bf16 v[48:51], v[180:183], v[188:191], v[48:51]
	v_mfma_f32_16x16x32_bf16 v[32:35], v[180:183], v[196:199], v[32:35]
	v_mfma_f32_16x16x32_bf16 v[20:23], v[172:175], v[206:209], v[20:23]
	v_mfma_f32_16x16x32_bf16 v[4:7], v[172:175], v[214:217], v[4:7]
	v_lshl_add_u64 v[224:225], s[38:39], 0, v[132:133]
	s_mov_b32 m0, s34
	s_nop 0
	global_load_lds_dwordx4 v[224:225], off
	v_mfma_f32_16x16x32_bf16 v[16:19], v[180:183], v[206:209], v[16:19]
	v_mfma_f32_16x16x32_bf16 v[0:3], v[180:183], v[214:217], v[0:3]
	s_setprio 0
	s_barrier
; #define PG8_STAGE(bufoff, gbase, voff) do { _Pragma("unroll") for (int _i = 0; _i < 2; ++_i) \
;         __builtin_amdgcn_global_load_lds((const unsigned*)((const char*)(gbase) + (voff)[_i]), (PG8_LAS unsigned*)(lds + (bufoff) + ldsw + _i * 8192), 16, 0, 0); } while (0)
; #define PG8_LDA(dst, b, h) do { _Pragma("unroll") for (int m = 0; m < 4; ++m) _Pragma("unroll") for (int k = 0; k < 2; ++k) dst[m][k] = *(const PG8_LAS bf16x8*)(lds + PG8_SA(b, h) + aoff + m * 2048 + k * 1024); } while (0)
; #define PG8_LDB(dst, b, h) do { _Pragma("unroll") for (int n = 0; n < 2; ++n) _Pragma("unroll") for (int k = 0; k < 2; ++k) dst[n][k] = *(const PG8_LAS bf16x8*)(lds + PG8_SB(b, h) + boff + n * 2048 + k * 1024); } while (0)
; #define PG8_MMA(ai, bj, At, Bt) do { __builtin_amdgcn_s_setprio(1); _Pragma("unroll") for (int m = 0; m < 4; ++m) _Pragma("unroll") for (int n = 0; n < 2; ++n) _Pragma("unroll") for (int k = 0; k < 2; ++k) \
;         acc[ai][bj][m][n] = __builtin_amdgcn_mfma_f32_16x16x32_bf16(Bt[n][k], At[m][k], acc[ai][bj][m][n], 0, 0, 0); __builtin_amdgcn_s_setprio(0); } while (0)
; #define PG8_WAIT_V(n) asm volatile("s_waitcnt vmcnt(" #n ")" ::: "memory")
; #define PG8_WAIT_L(n) asm volatile("s_waitcnt lgkmcnt(" #n ")" ::: "memory")
; #define PG8_BAR __builtin_amdgcn_s_barrier()
; #define PG8_SCHED __builtin_amdgcn_sched_barrier(0)
; template <class Epi, class Sched, bool ALIGN_EPI = false, bool SP2 = false>
; __device__ __forceinline__ void gemm_phase(PG8_LAS unsigned char* lds, const Gemm g, const Sched& S, const Epi& E) {
;     ...
;             PG8_LDB(B0, 1, 0); PG8_LDB(B1, 1, 1); PG8_SCHED; PG8_LDA(At, 1, 0); PG8_STAGE(PG8_SA(0, 1), a2 + hstep, voffA);
;             PG8_WAIT_V(8); PG8_WAIT_L(0); PG8_BAR; PG8_MMA(0, 0, At, B0); PG8_MMA(0, 1, At, B1); PG8_BAR; PG8_SCHED;
	s_add_i32 s56, 0, 0x18000
	v_add_u32_e32 v155, s56, v149
	s_add_i32 s57, 0, 0x1c000
	ds_read_b128 v[144:147], v155
	ds_read_b128 v[156:159], v155 offset:1024
	ds_read_b128 v[160:163], v155 offset:2048
	ds_read_b128 v[164:167], v155 offset:3072
	v_add_u32_e32 v155, s57, v149
	ds_read_b128 v[168:171], v155
	ds_read_b128 v[172:175], v155 offset:1024
	ds_read_b128 v[176:179], v155 offset:2048
	ds_read_b128 v[180:183], v155 offset:3072
	s_add_u32 s26, s38, 0xb0000
	s_addc_u32 s27, s39, 0
	s_mov_b32 m0, s40
	v_lshl_add_u64 v[226:227], s[26:27], 0, v[128:129]
	ds_read_b128 v[184:187], v153 offset:32768
	ds_read_b128 v[188:191], v153 offset:33792
	ds_read_b128 v[192:195], v153 offset:34816
	ds_read_b128 v[196:199], v153 offset:35840
	ds_read_b128 v[200:203], v153 offset:36864
	ds_read_b128 v[206:209], v153 offset:37888
	ds_read_b128 v[210:213], v153 offset:38912
	ds_read_b128 v[214:217], v153 offset:39936
	global_load_lds_dwordx4 v[226:227], off
	v_lshl_add_u64 v[226:227], s[26:27], 0, v[132:133]
	s_mov_b32 m0, s41
	s_nop 0
	global_load_lds_dwordx4 v[226:227], off
	s_waitcnt vmcnt(8)
	s_waitcnt lgkmcnt(0)
	s_barrier
	s_setprio 1
	s_waitcnt lgkmcnt(0)
	v_mfma_f32_16x16x32_bf16 v[124:127], v[144:147], v[184:187], v[124:127]
	v_mfma_f32_16x16x32_bf16 v[108:111], v[144:147], v[192:195], v[108:111]
	v_mfma_f32_16x16x32_bf16 v[120:123], v[160:163], v[184:187], v[120:123]
	v_mfma_f32_16x16x32_bf16 v[104:107], v[160:163], v[192:195], v[104:107]
	v_mfma_f32_16x16x32_bf16 v[92:95], v[144:147], v[200:203], v[92:95]
	v_mfma_f32_16x16x32_bf16 v[76:79], v[144:147], v[210:213], v[76:79]
	v_mfma_f32_16x16x32_bf16 v[88:91], v[160:163], v[200:203], v[88:91]
	v_mfma_f32_16x16x32_bf16 v[72:75], v[160:163], v[210:213], v[72:75]
	v_mfma_f32_16x16x32_bf16 v[124:127], v[156:159], v[188:191], v[124:127]
	v_mfma_f32_16x16x32_bf16 v[108:111], v[156:159], v[196:199], v[108:111]
	v_mfma_f32_16x16x32_bf16 v[120:123], v[164:167], v[188:191], v[120:123]
	v_mfma_f32_16x16x32_bf16 v[104:107], v[164:167], v[196:199], v[104:107]
	v_mfma_f32_16x16x32_bf16 v[92:95], v[156:159], v[206:209], v[92:95]
	v_mfma_f32_16x16x32_bf16 v[76:79], v[156:159], v[214:217], v[76:79]
	v_mfma_f32_16x16x32_bf16 v[88:91], v[164:167], v[206:209], v[88:91]
	v_mfma_f32_16x16x32_bf16 v[72:75], v[164:167], v[214:217], v[72:75]
	s_setprio 0
	s_setprio 1
	v_mfma_f32_16x16x32_bf16 v[116:119], v[168:171], v[184:187], v[116:119]
	v_mfma_f32_16x16x32_bf16 v[100:103], v[168:171], v[192:195], v[100:103]
	v_mfma_f32_16x16x32_bf16 v[112:115], v[176:179], v[184:187], v[112:115]
	v_mfma_f32_16x16x32_bf16 v[96:99], v[176:179], v[192:195], v[96:99]
	v_mfma_f32_16x16x32_bf16 v[84:87], v[168:171], v[200:203], v[84:87]
	v_mfma_f32_16x16x32_bf16 v[68:71], v[168:171], v[210:213], v[68:71]
	v_mfma_f32_16x16x32_bf16 v[80:83], v[176:179], v[200:203], v[80:83]
	v_mfma_f32_16x16x32_bf16 v[64:67], v[176:179], v[210:213], v[64:67]
	v_mfma_f32_16x16x32_bf16 v[116:119], v[172:175], v[188:191], v[116:119]
	v_mfma_f32_16x16x32_bf16 v[100:103], v[172:175], v[196:199], v[100:103]
	v_mfma_f32_16x16x32_bf16 v[112:115], v[180:183], v[188:191], v[112:115]
	v_mfma_f32_16x16x32_bf16 v[96:99], v[180:183], v[196:199], v[96:99]
	v_mfma_f32_16x16x32_bf16 v[84:87], v[172:175], v[206:209], v[84:87]
	v_mfma_f32_16x16x32_bf16 v[68:71], v[172:175], v[214:217], v[68:71]
	v_mfma_f32_16x16x32_bf16 v[80:83], v[180:183], v[206:209], v[80:83]
	v_mfma_f32_16x16x32_bf16 v[64:67], v[180:183], v[214:217], v[64:67]
	s_setprio 0
	s_barrier
; #define PG8_STAGE(bufoff, gbase, voff) do { _Pragma("unroll") for (int _i = 0; _i < 2; ++_i) \
;         __builtin_amdgcn_global_load_lds((const unsigned*)((const char*)(gbase) + (voff)[_i]), (PG8_LAS unsigned*)(lds + (bufoff) + ldsw + _i * 8192), 16, 0, 0); } while (0)
; #define PG8_LDA(dst, b, h) do { _Pragma("unroll") for (int m = 0; m < 4; ++m) _Pragma("unroll") for (int k = 0; k < 2; ++k) dst[m][k] = *(const PG8_LAS bf16x8*)(lds + PG8_SA(b, h) + aoff + m * 2048 + k * 1024); } while (0)
; #define PG8_MMA(ai, bj, At, Bt) do { __builtin_amdgcn_s_setprio(1); _Pragma("unroll") for (int m = 0; m < 4; ++m) _Pragma("unroll") for (int n = 0; n < 2; ++n) _Pragma("unroll") for (int k = 0; k < 2; ++k) \
;         acc[ai][bj][m][n] = __builtin_amdgcn_mfma_f32_16x16x32_bf16(Bt[n][k], At[m][k], acc[ai][bj][m][n], 0, 0, 0); __builtin_amdgcn_s_setprio(0); } while (0)
; #define PG8_WAIT_V(n) asm volatile("s_waitcnt vmcnt(" #n ")" ::: "memory")
; #define PG8_WAIT_L(n) asm volatile("s_waitcnt lgkmcnt(" #n ")" ::: "memory")
; #define PG8_BAR __builtin_amdgcn_s_barrier()
; #define PG8_SCHED __builtin_amdgcn_sched_barrier(0)
; template <class Epi, class Sched, bool ALIGN_EPI = false, bool SP2 = false>
; __device__ __forceinline__ void gemm_phase(PG8_LAS unsigned char* lds, const Gemm g, const Sched& S, const Epi& E) {
;     ...
;             PG8_LDA(At, 1, 1); PG8_STAGE(PG8_SB(1, 0), b3, voffB); PG8_STAGE(PG8_SB(1, 1), b3 + hstep, voffB); PG8_STAGE(PG8_SA(1, 0), a3, voffA);
;             PG8_WAIT_V(8); PG8_WAIT_L(0); PG8_BAR; PG8_MMA(1, 0, At, B0); PG8_MMA(1, 1, At, B1); PG8_BAR; PG8_SCHED;
	s_add_i32 s26, s56, s15
	v_lshl_add_u64 v[218:219], v[218:219], 0, s[12:13]
	s_mov_b32 m0, s26
	ds_read_b128 v[184:187], v153 offset:49152
	ds_read_b128 v[188:191], v153 offset:50176
	ds_read_b128 v[192:195], v153 offset:51200
	ds_read_b128 v[196:199], v153 offset:52224
	ds_read_b128 v[200:203], v153 offset:53248
	ds_read_b128 v[206:209], v153 offset:54272
	ds_read_b128 v[210:213], v153 offset:55296
	ds_read_b128 v[214:217], v153 offset:56320
	global_load_lds_dwordx4 v[218:219], off
	s_add_i32 m0, s26, 0x2000
	s_add_u32 s26, s36, 0xb0080
	v_lshl_add_u64 v[218:219], v[220:221], 0, s[12:13]
	s_addc_u32 s27, s37, 0
	s_add_i32 s36, s57, s15
	global_load_lds_dwordx4 v[218:219], off
	v_lshl_add_u64 v[218:219], s[26:27], 0, v[130:131]
	s_mov_b32 m0, s36
	s_nop 0
	global_load_lds_dwordx4 v[218:219], off
	v_lshl_add_u64 v[218:219], s[26:27], 0, v[134:135]
	s_add_i32 m0, s36, 0x2000
	s_nop 0
	global_load_lds_dwordx4 v[218:219], off
	s_waitcnt vmcnt(6)
	s_waitcnt lgkmcnt(0)
	s_barrier
	s_setprio 1
	s_waitcnt lgkmcnt(0)
	v_mfma_f32_16x16x32_bf16 v[60:63], v[144:147], v[184:187], v[60:63]
	v_mfma_f32_16x16x32_bf16 v[44:47], v[144:147], v[192:195], v[44:47]
	v_mfma_f32_16x16x32_bf16 v[56:59], v[160:163], v[184:187], v[56:59]
	v_mfma_f32_16x16x32_bf16 v[40:43], v[160:163], v[192:195], v[40:43]
	v_mfma_f32_16x16x32_bf16 v[28:31], v[144:147], v[200:203], v[28:31]
	v_mfma_f32_16x16x32_bf16 v[12:15], v[144:147], v[210:213], v[12:15]
	v_mfma_f32_16x16x32_bf16 v[24:27], v[160:163], v[200:203], v[24:27]
	v_mfma_f32_16x16x32_bf16 v[8:11], v[160:163], v[210:213], v[8:11]
	v_mfma_f32_16x16x32_bf16 v[60:63], v[156:159], v[188:191], v[60:63]
	v_mfma_f32_16x16x32_bf16 v[44:47], v[156:159], v[196:199], v[44:47]
	v_mfma_f32_16x16x32_bf16 v[56:59], v[164:167], v[188:191], v[56:59]
	v_mfma_f32_16x16x32_bf16 v[40:43], v[164:167], v[196:199], v[40:43]
	v_mfma_f32_16x16x32_bf16 v[28:31], v[156:159], v[206:209], v[28:31]
	v_mfma_f32_16x16x32_bf16 v[12:15], v[156:159], v[214:217], v[12:15]
	v_lshl_add_u64 v[218:219], v[222:223], 0, s[12:13]
	s_mov_b32 m0, s43
	s_nop 0
	global_load_lds_dwordx4 v[218:219], off
	v_mfma_f32_16x16x32_bf16 v[24:27], v[164:167], v[206:209], v[24:27]
	v_mfma_f32_16x16x32_bf16 v[8:11], v[164:167], v[214:217], v[8:11]
	s_setprio 0
	s_setprio 1
	v_mfma_f32_16x16x32_bf16 v[52:55], v[168:171], v[184:187], v[52:55]
	v_mfma_f32_16x16x32_bf16 v[36:39], v[168:171], v[192:195], v[36:39]
	v_mfma_f32_16x16x32_bf16 v[48:51], v[176:179], v[184:187], v[48:51]
	v_mfma_f32_16x16x32_bf16 v[32:35], v[176:179], v[192:195], v[32:35]
	v_mfma_f32_16x16x32_bf16 v[20:23], v[168:171], v[200:203], v[20:23]
	v_mfma_f32_16x16x32_bf16 v[4:7], v[168:171], v[210:213], v[4:7]
	v_mfma_f32_16x16x32_bf16 v[16:19], v[176:179], v[200:203], v[16:19]
	v_mfma_f32_16x16x32_bf16 v[0:3], v[176:179], v[210:213], v[0:3]
	v_mfma_f32_16x16x32_bf16 v[52:55], v[172:175], v[188:191], v[52:55]
	v_mfma_f32_16x16x32_bf16 v[36:39], v[172:175], v[196:199], v[36:39]
	v_mfma_f32_16x16x32_bf16 v[48:51], v[180:183], v[188:191], v[48:51]
	v_mfma_f32_16x16x32_bf16 v[32:35], v[180:183], v[196:199], v[32:35]
	v_mfma_f32_16x16x32_bf16 v[20:23], v[172:175], v[206:209], v[20:23]
	v_mfma_f32_16x16x32_bf16 v[4:7], v[172:175], v[214:217], v[4:7]
	v_lshl_add_u64 v[218:219], v[224:225], 0, s[12:13]
	s_mov_b32 m0, s44
	s_nop 0
	global_load_lds_dwordx4 v[218:219], off
	v_mfma_f32_16x16x32_bf16 v[16:19], v[180:183], v[206:209], v[16:19]
	v_mfma_f32_16x16x32_bf16 v[0:3], v[180:183], v[214:217], v[0:3]
	s_setprio 0
	s_barrier
	s_add_i32 s55, s55, 2
	s_add_u32 s53, s53, 0x100
	s_addc_u32 s54, s54, 0
	s_cmp_gt_u32 s55, 41
	s_mov_b64 s[26:27], s[28:29]
	s_cbranch_scc0 .LBB0_1978
	s_and_b64 vcc, exec, s[16:17]
	s_cbranch_vccz .LBB0_1981
	s_barrier
